# nt hint on the weight-conversion stores (both layers)
# speedup vs baseline: 1.0047x; 1.0047x over previous
.LBB0_246:
	s_or_b64 exec, exec, s[16:17]
	s_waitcnt lgkmcnt(0)
	v_max_f32_e32 v130, v130, v130
	v_max_f32_e32 v130, 0xda24260, v130
	v_div_scale_f32 v134, s[16:17], v130, v130, s33
	v_rcp_f32_e32 v135, v134
	v_div_scale_f32 v136, vcc, s33, v130, s33
	v_max_f32_e32 v131, v131, v131
	v_fma_f32 v138, -v134, v135, 1.0
	v_fmac_f32_e32 v135, v138, v135
	v_mul_f32_e32 v138, v136, v135
	v_fma_f32 v139, -v134, v138, v136
	v_fmac_f32_e32 v138, v139, v135
	v_max_f32_e32 v131, 0xda24260, v131
	v_fma_f32 v134, -v134, v138, v136
	v_div_scale_f32 v136, s[16:17], v131, v131, s33
	v_rcp_f32_e32 v139, v136
	v_div_fmas_f32 v134, v134, v135, v138
	v_div_fixup_f32 v130, v134, v130, s33
	v_max_f32_e32 v132, v132, v132
	v_fma_f32 v134, -v136, v139, 1.0
	v_fmac_f32_e32 v139, v134, v139
	v_div_scale_f32 v134, vcc, s33, v131, s33
	v_mul_f32_e32 v135, v134, v139
	v_fma_f32 v138, -v136, v135, v134
	v_fmac_f32_e32 v135, v138, v139
	v_max_f32_e32 v132, 0xda24260, v132
	v_fma_f32 v134, -v136, v135, v134
	v_div_scale_f32 v136, s[16:17], v132, v132, s33
	v_rcp_f32_e32 v138, v136
	v_div_fmas_f32 v134, v134, v139, v135
	v_div_fixup_f32 v131, v134, v131, s33
	v_max_f32_e32 v133, v133, v133
	v_fma_f32 v134, -v136, v138, 1.0
	v_fmac_f32_e32 v138, v134, v138
	v_div_scale_f32 v134, vcc, s33, v132, s33
	v_mul_f32_e32 v135, v134, v138
	v_fma_f32 v139, -v136, v135, v134
	v_fmac_f32_e32 v135, v139, v138
	v_max_f32_e32 v133, 0xda24260, v133
	v_fma_f32 v134, -v136, v135, v134
	v_div_scale_f32 v136, s[16:17], v133, v133, s33
	v_rcp_f32_e32 v139, v136
	v_div_fmas_f32 v134, v134, v138, v135
	v_div_fixup_f32 v132, v134, v132, s33
	v_bfe_u32 v175, v124, 16, 1
	v_fma_f32 v134, -v136, v139, 1.0
	v_fmac_f32_e32 v139, v134, v139
	v_div_scale_f32 v134, vcc, s33, v133, s33
	v_mul_f32_e32 v135, v134, v139
	v_fma_f32 v138, -v136, v135, v134
	v_fmac_f32_e32 v135, v138, v139
	v_fma_f32 v134, -v136, v135, v134
	v_div_fmas_f32 v134, v134, v139, v135
	v_bfe_u32 v135, v77, 16, 1
	v_add3_u32 v168, v77, v135, s30
	v_bfe_u32 v77, v70, 16, 1
	v_add3_u32 v135, v70, v77, s30
	v_add3_u32 v77, v124, v175, s30
	v_bfe_u32 v124, v10, 16, 1
	v_add3_u32 v10, v10, v124, s30
	v_bfe_u32 v124, v11, 16, 1
	v_add3_u32 v11, v11, v124, s30
	v_bfe_u32 v124, v12, 16, 1
	v_add3_u32 v12, v12, v124, s30
	v_bfe_u32 v124, v13, 16, 1
	v_add3_u32 v13, v13, v124, s30
	v_bfe_u32 v124, v6, 16, 1
	v_add3_u32 v6, v6, v124, s30
	v_bfe_u32 v124, v7, 16, 1
	v_bfe_u32 v146, v89, 16, 1
	v_add3_u32 v7, v7, v124, s30
	v_bfe_u32 v159, v123, 16, 1
	v_add3_u32 v146, v89, v146, s30
	v_bfe_u32 v89, v94, 16, 1
	v_bfe_u32 v178, v126, 16, 1
	v_and_b32_e32 v124, 0xffff0000, v7
	v_bfe_u32 v7, v8, 16, 1
	v_div_fixup_f32 v133, v134, v133, s33
	v_bfe_u32 v134, v75, 16, 1
	v_bfe_u32 v138, v73, 16, 1
	v_add3_u32 v159, v123, v159, s30
	v_add3_u32 v123, v94, v89, s30
	v_add3_u32 v89, v126, v178, s30
	v_add3_u32 v126, v8, v7, s30
	v_bfe_u32 v7, v9, 16, 1
	v_bfe_u32 v161, v119, 16, 1
	v_add3_u32 v75, v75, v134, s30
	v_bfe_u32 v134, v76, 16, 1
	v_add3_u32 v138, v73, v138, s30
	v_bfe_u32 v73, v78, 16, 1
	v_bfe_u32 v179, v128, 16, 1
	v_add3_u32 v7, v9, v7, s30
	v_add3_u32 v161, v119, v161, s30
	v_add3_u32 v119, v76, v134, s30
	v_add3_u32 v134, v78, v73, s30
	v_add3_u32 v73, v128, v179, s30
	v_and_b32_e32 v128, 0xffff0000, v7
	v_bfe_u32 v7, v18, 16, 1
	v_bfe_u32 v9, v20, 16, 1
	v_add3_u32 v7, v18, v7, s30
	v_add3_u32 v18, v20, v9, s30
	v_bfe_u32 v9, v21, 16, 1
	v_bfe_u32 v8, v19, 16, 1
	v_add3_u32 v9, v21, v9, s30
	v_add3_u32 v8, v19, v8, s30
	v_and_b32_e32 v19, 0xffff0000, v9
	v_bfe_u32 v9, v2, 16, 1
	v_add3_u32 v9, v2, v9, s30
	v_bfe_u32 v2, v3, 16, 1
	v_add3_u32 v2, v3, v2, s30
	v_and_b32_e32 v20, 0xffff0000, v2
	v_bfe_u32 v2, v4, 16, 1
	v_bfe_u32 v148, v97, 16, 1
	v_bfe_u32 v150, v85, 16, 1
	v_add3_u32 v21, v4, v2, s30
	v_bfe_u32 v2, v5, 16, 1
	v_bfe_u32 v162, v121, 16, 1
	v_add3_u32 v148, v97, v148, s30
	v_bfe_u32 v97, v82, 16, 1
	v_add3_u32 v85, v85, v150, s30
	v_bfe_u32 v150, v106, 16, 1
	v_add3_u32 v2, v5, v2, s30
	v_add3_u32 v162, v121, v162, s30
	v_add3_u32 v121, v82, v97, s30
	v_add3_u32 v97, v106, v150, s30
	v_and_b32_e32 v106, 0xffff0000, v138
	v_and_b32_e32 v138, 0xffff0000, v2
	v_bfe_u32 v2, v26, 16, 1
	v_add3_u32 v26, v26, v2, s30
	v_bfe_u32 v2, v27, 16, 1
	v_add3_u32 v2, v27, v2, s30
	v_and_b32_e32 v27, 0xffff0000, v2
	v_bfe_u32 v2, v28, 16, 1
	v_add3_u32 v28, v28, v2, s30
	v_bfe_u32 v2, v29, 16, 1
	v_add3_u32 v2, v29, v2, s30
	v_and_b32_e32 v29, 0xffff0000, v2
	v_bfe_u32 v2, v22, 16, 1
	v_add3_u32 v22, v22, v2, s30
	v_bfe_u32 v2, v23, 16, 1
	v_add3_u32 v2, v23, v2, s30
	v_and_b32_e32 v23, 0xffff0000, v2
	v_bfe_u32 v2, v24, 16, 1
	v_add3_u32 v24, v24, v2, s30
	v_bfe_u32 v2, v25, 16, 1
	v_and_b32_e32 v6, 0xffff0000, v6
	v_add3_u32 v2, v25, v2, s30
	v_and_b32_e32 v10, 0xffff0000, v10
	v_mul_f32_e32 v6, v130, v6
	v_and_b32_e32 v7, 0xffff0000, v7
	v_and_b32_e32 v9, 0xffff0000, v9
	v_and_b32_e32 v25, 0xffff0000, v2
	v_bfe_u32 v2, v30, 16, 1
	v_mul_f32_e32 v10, v130, v10
	v_rndne_f32_e32 v6, v6
	v_mul_f32_e32 v7, v130, v7
	v_mul_f32_e32 v9, v130, v9
	v_add3_u32 v30, v30, v2, s30
	v_bfe_u32 v2, v31, 16, 1
	v_rndne_f32_e32 v10, v10
	v_cvt_i32_f32_e32 v6, v6
	v_rndne_f32_e32 v7, v7
	v_rndne_f32_e32 v9, v9
	v_add3_u32 v2, v31, v2, s30
	v_cvt_i32_f32_e32 v10, v10
	v_cvt_i32_f32_sdwa v7, v7 dst_sel:WORD_1 dst_unused:UNUSED_PAD src0_sel:DWORD
	v_cvt_i32_f32_e32 v9, v9
	v_and_b32_e32 v31, 0xffff0000, v2
	v_bfe_u32 v2, v32, 16, 1
	v_add3_u32 v32, v32, v2, s30
	v_bfe_u32 v2, v33, 16, 1
	v_add3_u32 v2, v33, v2, s30
	v_lshlrev_b32_e32 v6, 8, v6
	v_and_b32_e32 v33, 0xffff0000, v2
	v_bfe_u32 v2, v14, 16, 1
	v_and_b32_e32 v6, 0xff00, v6
	v_and_b32_e32 v7, 0xff0000, v7
	v_perm_b32 v9, v9, v10, s34
	v_add3_u32 v14, v14, v2, s30
	v_or3_b32 v6, v9, v6, v7
	v_and_b32_e32 v9, 0xffff0000, v22
	v_and_b32_e32 v7, 0xffff0000, v26
	v_mul_f32_e32 v9, v130, v9
	v_and_b32_e32 v10, 0xffff0000, v30
	v_and_b32_e32 v14, 0xffff0000, v14
	v_mul_f32_e32 v7, v130, v7
	v_rndne_f32_e32 v9, v9
	v_mul_f32_e32 v10, v130, v10
	v_mul_f32_e32 v14, v130, v14
	v_rndne_f32_e32 v7, v7
	v_cvt_i32_f32_e32 v9, v9
	v_rndne_f32_e32 v10, v10
	v_rndne_f32_e32 v14, v14
	v_cvt_i32_f32_e32 v7, v7
	v_cvt_i32_f32_sdwa v10, v10 dst_sel:WORD_1 dst_unused:UNUSED_PAD src0_sel:DWORD
	v_cvt_i32_f32_e32 v14, v14
	v_or_b32_e32 v4, v137, v211
	v_ashrrev_i32_e32 v5, 31, v4
	v_lshlrev_b32_e32 v9, 8, v9
	v_lshlrev_b64 v[4:5], 12, v[4:5]
	v_and_b32_e32 v9, 0xff00, v9
	v_and_b32_e32 v10, 0xff0000, v10
	v_perm_b32 v7, v14, v7, s34
	v_lshl_add_u64 v[4:5], v[198:199], 0, v[4:5]
	v_or3_b32 v7, v7, v9, v10
	v_and_b32_e32 v11, 0xffff0000, v11
	v_and_b32_e32 v8, 0xffff0000, v8
	global_store_dwordx2 v[4:5], v[6:7], off nt
	v_mul_f32_e32 v7, v131, v124
	v_mul_f32_e32 v6, v131, v11
	v_rndne_f32_e32 v7, v7
	v_mul_f32_e32 v8, v131, v8
	v_mul_f32_e32 v9, v131, v20
	v_rndne_f32_e32 v6, v6
	v_cvt_i32_f32_e32 v7, v7
	v_rndne_f32_e32 v8, v8
	v_rndne_f32_e32 v9, v9
	v_cvt_i32_f32_e32 v6, v6
	v_cvt_i32_f32_sdwa v8, v8 dst_sel:WORD_1 dst_unused:UNUSED_PAD src0_sel:DWORD
	v_cvt_i32_f32_e32 v9, v9
	v_bfe_u32 v2, v15, 16, 1
	v_lshlrev_b32_e32 v7, 8, v7
	v_add3_u32 v2, v15, v2, s30
	v_and_b32_e32 v7, 0xff00, v7
	v_and_b32_e32 v8, 0xff0000, v8
	v_perm_b32 v6, v9, v6, s34
	v_and_b32_e32 v15, 0xffff0000, v2
	v_or3_b32 v10, v6, v7, v8
	v_mul_f32_e32 v7, v131, v23
	v_mul_f32_e32 v6, v131, v27
	v_rndne_f32_e32 v7, v7
	v_mul_f32_e32 v8, v131, v31
	v_mul_f32_e32 v9, v131, v15
	v_rndne_f32_e32 v6, v6
	v_cvt_i32_f32_e32 v7, v7
	v_rndne_f32_e32 v8, v8
	v_rndne_f32_e32 v9, v9
	v_cvt_i32_f32_e32 v6, v6
	v_cvt_i32_f32_sdwa v8, v8 dst_sel:WORD_1 dst_unused:UNUSED_PAD src0_sel:DWORD
	v_cvt_i32_f32_e32 v9, v9
	v_lshlrev_b32_e32 v7, 8, v7
	v_and_b32_e32 v7, 0xff00, v7
	v_and_b32_e32 v8, 0xff0000, v8
	v_perm_b32 v6, v9, v6, s34
	v_or3_b32 v11, v6, v7, v8
	v_add_co_u32_e32 v8, vcc, s35, v4
	v_bfe_u32 v2, v16, 16, 1
	s_nop 0
	v_addc_co_u32_e32 v9, vcc, 0, v5, vcc
	v_add_co_u32_e32 v6, vcc, s36, v4
	v_add3_u32 v16, v16, v2, s30
	s_nop 0
	v_addc_co_u32_e32 v7, vcc, 0, v5, vcc
	global_store_dwordx2 v[6:7], v[10:11], off offset:-4096 nt
	v_and_b32_e32 v11, 0xffff0000, v126
	v_bfe_u32 v2, v17, 16, 1
	v_and_b32_e32 v10, 0xffff0000, v12
	v_mul_f32_e32 v11, v132, v11
	v_and_b32_e32 v12, 0xffff0000, v18
	v_and_b32_e32 v14, 0xffff0000, v21
	v_add3_u32 v2, v17, v2, s30
	v_mul_f32_e32 v10, v132, v10
	v_rndne_f32_e32 v11, v11
	v_mul_f32_e32 v12, v132, v12
	v_mul_f32_e32 v14, v132, v14
	v_and_b32_e32 v17, 0xffff0000, v2
	v_bfe_u32 v2, v42, 16, 1
	v_rndne_f32_e32 v10, v10
	v_cvt_i32_f32_e32 v11, v11
	v_rndne_f32_e32 v12, v12
	v_rndne_f32_e32 v14, v14
	v_add3_u32 v42, v42, v2, s30
	v_bfe_u32 v2, v43, 16, 1
	v_cvt_i32_f32_e32 v10, v10
	v_cvt_i32_f32_sdwa v12, v12 dst_sel:WORD_1 dst_unused:UNUSED_PAD src0_sel:DWORD
	v_cvt_i32_f32_e32 v14, v14
	v_add3_u32 v2, v43, v2, s30
	v_and_b32_e32 v43, 0xffff0000, v2
	v_bfe_u32 v2, v44, 16, 1
	v_add3_u32 v44, v44, v2, s30
	v_bfe_u32 v2, v45, 16, 1
	v_lshlrev_b32_e32 v11, 8, v11
	v_add3_u32 v2, v45, v2, s30
	v_and_b32_e32 v11, 0xff00, v11
	v_and_b32_e32 v12, 0xff0000, v12
	v_perm_b32 v10, v14, v10, s34
	v_and_b32_e32 v45, 0xffff0000, v2
	v_bfe_u32 v2, v38, 16, 1
	v_or3_b32 v10, v10, v11, v12
	v_and_b32_e32 v12, 0xffff0000, v24
	v_add3_u32 v38, v38, v2, s30
	v_bfe_u32 v2, v39, 16, 1
	v_and_b32_e32 v11, 0xffff0000, v28
	v_mul_f32_e32 v12, v132, v12
	v_and_b32_e32 v14, 0xffff0000, v32
	v_and_b32_e32 v15, 0xffff0000, v16
	v_add3_u32 v2, v39, v2, s30
	v_mul_f32_e32 v11, v132, v11
	v_rndne_f32_e32 v12, v12
	v_mul_f32_e32 v14, v132, v14
	v_mul_f32_e32 v15, v132, v15
	v_and_b32_e32 v39, 0xffff0000, v2
	v_bfe_u32 v2, v40, 16, 1
	v_rndne_f32_e32 v11, v11
	v_cvt_i32_f32_e32 v12, v12
	v_rndne_f32_e32 v14, v14
	v_rndne_f32_e32 v15, v15
	v_add3_u32 v40, v40, v2, s30
	v_bfe_u32 v2, v41, 16, 1
	v_cvt_i32_f32_e32 v11, v11
	v_cvt_i32_f32_sdwa v14, v14 dst_sel:WORD_1 dst_unused:UNUSED_PAD src0_sel:DWORD
	v_cvt_i32_f32_e32 v15, v15
	v_add3_u32 v2, v41, v2, s30
	v_and_b32_e32 v41, 0xffff0000, v2
	v_bfe_u32 v2, v50, 16, 1
	v_add3_u32 v50, v50, v2, s30
	v_bfe_u32 v2, v51, 16, 1
	v_lshlrev_b32_e32 v12, 8, v12
	v_add3_u32 v2, v51, v2, s30
	v_and_b32_e32 v12, 0xff00, v12
	v_and_b32_e32 v14, 0xff0000, v14
	v_perm_b32 v11, v15, v11, s34
	v_and_b32_e32 v51, 0xffff0000, v2
	v_bfe_u32 v2, v52, 16, 1
	v_or3_b32 v11, v11, v12, v14
	v_and_b32_e32 v13, 0xffff0000, v13
	v_add3_u32 v52, v52, v2, s30
	v_bfe_u32 v2, v53, 16, 1
	global_store_dwordx2 v[6:7], v[10:11], off nt
	v_mul_f32_e32 v11, v133, v128
	v_add3_u32 v2, v53, v2, s30
	v_mul_f32_e32 v10, v133, v13
	v_rndne_f32_e32 v11, v11
	v_mul_f32_e32 v12, v133, v19
	v_mul_f32_e32 v13, v133, v138
	v_and_b32_e32 v53, 0xffff0000, v2
	v_bfe_u32 v2, v34, 16, 1
	v_rndne_f32_e32 v10, v10
	v_cvt_i32_f32_e32 v11, v11
	v_rndne_f32_e32 v12, v12
	v_rndne_f32_e32 v13, v13
	v_add3_u32 v34, v34, v2, s30
	v_bfe_u32 v2, v35, 16, 1
	v_cvt_i32_f32_e32 v10, v10
	v_cvt_i32_f32_sdwa v12, v12 dst_sel:WORD_1 dst_unused:UNUSED_PAD src0_sel:DWORD
	v_cvt_i32_f32_e32 v13, v13
	v_add3_u32 v2, v35, v2, s30
	v_and_b32_e32 v35, 0xffff0000, v2
	v_bfe_u32 v2, v36, 16, 1
	v_add3_u32 v36, v36, v2, s30
	v_bfe_u32 v2, v37, 16, 1
	v_lshlrev_b32_e32 v11, 8, v11
	v_add3_u32 v2, v37, v2, s30
	v_and_b32_e32 v11, 0xff00, v11
	v_and_b32_e32 v12, 0xff0000, v12
	v_perm_b32 v10, v13, v10, s34
	v_and_b32_e32 v37, 0xffff0000, v2
	v_bfe_u32 v2, v58, 16, 1
	v_or3_b32 v12, v10, v11, v12
	v_mul_f32_e32 v11, v133, v25
	v_add3_u32 v58, v58, v2, s30
	v_bfe_u32 v2, v59, 16, 1
	v_mul_f32_e32 v10, v133, v29
	v_rndne_f32_e32 v11, v11
	v_mul_f32_e32 v13, v133, v33
	v_mul_f32_e32 v14, v133, v17
	v_add3_u32 v2, v59, v2, s30
	v_rndne_f32_e32 v10, v10
	v_cvt_i32_f32_e32 v11, v11
	v_rndne_f32_e32 v13, v13
	v_rndne_f32_e32 v14, v14
	v_and_b32_e32 v59, 0xffff0000, v2
	v_bfe_u32 v2, v60, 16, 1
	v_cvt_i32_f32_e32 v10, v10
	v_cvt_i32_f32_sdwa v13, v13 dst_sel:WORD_1 dst_unused:UNUSED_PAD src0_sel:DWORD
	v_cvt_i32_f32_e32 v14, v14
	v_add3_u32 v60, v60, v2, s30
	v_bfe_u32 v2, v61, 16, 1
	v_add3_u32 v2, v61, v2, s30
	v_and_b32_e32 v61, 0xffff0000, v2
	v_bfe_u32 v2, v54, 16, 1
	v_lshlrev_b32_e32 v11, 8, v11
	v_add3_u32 v54, v54, v2, s30
	v_bfe_u32 v2, v55, 16, 1
	v_and_b32_e32 v11, 0xff00, v11
	v_and_b32_e32 v13, 0xff0000, v13
	v_perm_b32 v10, v14, v10, s34
	v_add3_u32 v2, v55, v2, s30
	v_or3_b32 v13, v10, v11, v13
	v_add_co_u32_e32 v10, vcc, s37, v4
	v_and_b32_e32 v55, 0xffff0000, v2
	v_bfe_u32 v2, v56, 16, 1
	v_addc_co_u32_e32 v11, vcc, 0, v5, vcc
	v_add3_u32 v56, v56, v2, s30
	v_bfe_u32 v2, v57, 16, 1
	global_store_dwordx2 v[10:11], v[12:13], off nt
	v_and_b32_e32 v13, 0xffff0000, v38
	v_add3_u32 v2, v57, v2, s30
	v_and_b32_e32 v12, 0xffff0000, v42
	v_mul_f32_e32 v13, v130, v13
	v_and_b32_e32 v14, 0xffff0000, v50
	v_and_b32_e32 v15, 0xffff0000, v34
	v_and_b32_e32 v57, 0xffff0000, v2
	v_bfe_u32 v2, v62, 16, 1
	v_mul_f32_e32 v12, v130, v12
	v_rndne_f32_e32 v13, v13
	v_mul_f32_e32 v14, v130, v14
	v_mul_f32_e32 v15, v130, v15
	v_add3_u32 v62, v62, v2, s30
	v_bfe_u32 v2, v63, 16, 1
	v_rndne_f32_e32 v12, v12
	v_cvt_i32_f32_e32 v13, v13
	v_rndne_f32_e32 v14, v14
	v_rndne_f32_e32 v15, v15
	v_add3_u32 v2, v63, v2, s30
	v_cvt_i32_f32_e32 v12, v12
	v_cvt_i32_f32_sdwa v14, v14 dst_sel:WORD_1 dst_unused:UNUSED_PAD src0_sel:DWORD
	v_cvt_i32_f32_e32 v15, v15
	v_and_b32_e32 v63, 0xffff0000, v2
	v_bfe_u32 v2, v64, 16, 1
	v_add3_u32 v64, v64, v2, s30
	v_bfe_u32 v2, v65, 16, 1
	v_add3_u32 v2, v65, v2, s30
	v_lshlrev_b32_e32 v13, 8, v13
	v_and_b32_e32 v65, 0xffff0000, v2
	v_bfe_u32 v2, v46, 16, 1
	v_and_b32_e32 v13, 0xff00, v13
	v_and_b32_e32 v14, 0xff0000, v14
	v_perm_b32 v12, v15, v12, s34
	v_add3_u32 v46, v46, v2, s30
	v_or3_b32 v12, v12, v13, v14
	v_and_b32_e32 v14, 0xffff0000, v54
	v_and_b32_e32 v13, 0xffff0000, v58
	v_mul_f32_e32 v14, v130, v14
	v_and_b32_e32 v15, 0xffff0000, v62
	v_and_b32_e32 v16, 0xffff0000, v46
	v_mul_f32_e32 v13, v130, v13
	v_rndne_f32_e32 v14, v14
	v_mul_f32_e32 v15, v130, v15
	v_mul_f32_e32 v16, v130, v16
	v_rndne_f32_e32 v13, v13
	v_cvt_i32_f32_e32 v14, v14
	v_rndne_f32_e32 v15, v15
	v_rndne_f32_e32 v16, v16
	v_cvt_i32_f32_e32 v13, v13
	v_cvt_i32_f32_sdwa v15, v15 dst_sel:WORD_1 dst_unused:UNUSED_PAD src0_sel:DWORD
	v_cvt_i32_f32_e32 v16, v16
	v_lshlrev_b32_e32 v14, 8, v14
	v_and_b32_e32 v14, 0xff00, v14
	v_and_b32_e32 v15, 0xff0000, v15
	v_perm_b32 v13, v16, v13, s34
	v_or3_b32 v13, v13, v14, v15
	global_store_dwordx2 v[4:5], v[12:13], off offset:512 nt
	v_mul_f32_e32 v13, v131, v39
	v_mul_f32_e32 v12, v131, v43
	v_rndne_f32_e32 v13, v13
	v_mul_f32_e32 v14, v131, v51
	v_mul_f32_e32 v15, v131, v35
	v_rndne_f32_e32 v12, v12
	v_cvt_i32_f32_e32 v13, v13
	v_rndne_f32_e32 v14, v14
	v_rndne_f32_e32 v15, v15
	v_cvt_i32_f32_e32 v12, v12
	v_cvt_i32_f32_sdwa v14, v14 dst_sel:WORD_1 dst_unused:UNUSED_PAD src0_sel:DWORD
	v_cvt_i32_f32_e32 v15, v15
	v_bfe_u32 v2, v47, 16, 1
	v_lshlrev_b32_e32 v13, 8, v13
	v_add3_u32 v2, v47, v2, s30
	v_and_b32_e32 v13, 0xff00, v13
	v_and_b32_e32 v14, 0xff0000, v14
	v_perm_b32 v12, v15, v12, s34
	v_and_b32_e32 v47, 0xffff0000, v2
	v_or3_b32 v12, v12, v13, v14
	v_mul_f32_e32 v14, v131, v55
	v_mul_f32_e32 v13, v131, v59
	v_rndne_f32_e32 v14, v14
	v_mul_f32_e32 v15, v131, v63
	v_mul_f32_e32 v16, v131, v47
	v_rndne_f32_e32 v13, v13
	v_cvt_i32_f32_e32 v14, v14
	v_rndne_f32_e32 v15, v15
	v_rndne_f32_e32 v16, v16
	v_cvt_i32_f32_e32 v13, v13
	v_cvt_i32_f32_sdwa v15, v15 dst_sel:WORD_1 dst_unused:UNUSED_PAD src0_sel:DWORD
	v_cvt_i32_f32_e32 v16, v16
	v_lshlrev_b32_e32 v14, 8, v14
	v_and_b32_e32 v14, 0xff00, v14
	v_and_b32_e32 v15, 0xff0000, v15
	v_perm_b32 v13, v16, v13, s34
	v_or3_b32 v13, v13, v14, v15
	global_store_dwordx2 v[8:9], v[12:13], off offset:512 nt
	v_and_b32_e32 v13, 0xffff0000, v40
	v_and_b32_e32 v12, 0xffff0000, v44
	v_mul_f32_e32 v13, v132, v13
	v_and_b32_e32 v14, 0xffff0000, v52
	v_and_b32_e32 v15, 0xffff0000, v36
	v_mul_f32_e32 v12, v132, v12
	v_rndne_f32_e32 v13, v13
	v_mul_f32_e32 v14, v132, v14
	v_mul_f32_e32 v15, v132, v15
	v_rndne_f32_e32 v12, v12
	v_cvt_i32_f32_e32 v13, v13
	v_rndne_f32_e32 v14, v14
	v_rndne_f32_e32 v15, v15
	v_cvt_i32_f32_e32 v12, v12
	v_cvt_i32_f32_sdwa v14, v14 dst_sel:WORD_1 dst_unused:UNUSED_PAD src0_sel:DWORD
	v_cvt_i32_f32_e32 v15, v15
	v_lshlrev_b32_e32 v13, 8, v13
	v_bfe_u32 v2, v48, 16, 1
	v_and_b32_e32 v13, 0xff00, v13
	v_and_b32_e32 v14, 0xff0000, v14
	v_perm_b32 v12, v15, v12, s34
	v_add3_u32 v48, v48, v2, s30
	v_or3_b32 v12, v12, v13, v14
	v_and_b32_e32 v14, 0xffff0000, v56
	v_and_b32_e32 v13, 0xffff0000, v60
	v_mul_f32_e32 v14, v132, v14
	v_and_b32_e32 v15, 0xffff0000, v64
	v_and_b32_e32 v16, 0xffff0000, v48
	v_mul_f32_e32 v13, v132, v13
	v_rndne_f32_e32 v14, v14
	v_mul_f32_e32 v15, v132, v15
	v_mul_f32_e32 v16, v132, v16
	v_rndne_f32_e32 v13, v13
	v_cvt_i32_f32_e32 v14, v14
	v_rndne_f32_e32 v15, v15
	v_rndne_f32_e32 v16, v16
	v_cvt_i32_f32_e32 v13, v13
	v_cvt_i32_f32_sdwa v15, v15 dst_sel:WORD_1 dst_unused:UNUSED_PAD src0_sel:DWORD
	v_cvt_i32_f32_e32 v16, v16
	v_lshlrev_b32_e32 v14, 8, v14
	v_and_b32_e32 v14, 0xff00, v14
	v_and_b32_e32 v15, 0xff0000, v15
	v_perm_b32 v13, v16, v13, s34
	v_or3_b32 v13, v13, v14, v15
	global_store_dwordx2 v[6:7], v[12:13], off offset:512 nt
	v_mul_f32_e32 v13, v133, v41
	v_mul_f32_e32 v12, v133, v45
	v_rndne_f32_e32 v13, v13
	v_mul_f32_e32 v14, v133, v53
	v_mul_f32_e32 v15, v133, v37
	v_rndne_f32_e32 v12, v12
	v_cvt_i32_f32_e32 v13, v13
	v_rndne_f32_e32 v14, v14
	v_rndne_f32_e32 v15, v15
	v_cvt_i32_f32_e32 v12, v12
	v_cvt_i32_f32_sdwa v14, v14 dst_sel:WORD_1 dst_unused:UNUSED_PAD src0_sel:DWORD
	v_cvt_i32_f32_e32 v15, v15
	v_bfe_u32 v2, v49, 16, 1
	v_lshlrev_b32_e32 v13, 8, v13
	v_add3_u32 v2, v49, v2, s30
	v_and_b32_e32 v13, 0xff00, v13
	v_and_b32_e32 v14, 0xff0000, v14
	v_perm_b32 v12, v15, v12, s34
	v_and_b32_e32 v49, 0xffff0000, v2
	v_or3_b32 v12, v12, v13, v14
	v_mul_f32_e32 v14, v133, v57
	v_mul_f32_e32 v13, v133, v61
	v_rndne_f32_e32 v14, v14
	v_mul_f32_e32 v15, v133, v65
	v_mul_f32_e32 v16, v133, v49
	v_rndne_f32_e32 v13, v13
	v_cvt_i32_f32_e32 v14, v14
	v_rndne_f32_e32 v15, v15
	v_rndne_f32_e32 v16, v16
	v_cvt_i32_f32_e32 v13, v13
	v_cvt_i32_f32_sdwa v15, v15 dst_sel:WORD_1 dst_unused:UNUSED_PAD src0_sel:DWORD
	v_cvt_i32_f32_e32 v16, v16
	v_lshlrev_b32_e32 v14, 8, v14
	v_bfe_u32 v140, v81, 16, 1
	v_and_b32_e32 v14, 0xff00, v14
	v_and_b32_e32 v15, 0xff0000, v15
	v_perm_b32 v13, v16, v13, s34
	v_bfe_u32 v136, v71, 16, 1
	v_bfe_u32 v164, v129, 16, 1
	v_bfe_u32 v167, v74, 16, 1
	v_add3_u32 v140, v81, v140, s30
	v_bfe_u32 v81, v66, 16, 1
	v_or3_b32 v13, v13, v14, v15
	v_add3_u32 v71, v71, v136, s30
	v_add3_u32 v164, v129, v164, s30
	v_add3_u32 v136, v74, v167, s30
	v_add3_u32 v129, v66, v81, s30
	global_store_dwordx2 v[10:11], v[12:13], off offset:512 nt
	v_and_b32_e32 v13, 0xffff0000, v135
	v_and_b32_e32 v12, 0xffff0000, v136
	v_mul_f32_e32 v13, v130, v13
	v_and_b32_e32 v14, 0xffff0000, v134
	v_and_b32_e32 v15, 0xffff0000, v129
	v_mul_f32_e32 v12, v130, v12
	v_rndne_f32_e32 v13, v13
	v_mul_f32_e32 v14, v130, v14
	v_mul_f32_e32 v15, v130, v15
	v_rndne_f32_e32 v12, v12
	v_cvt_i32_f32_e32 v13, v13
	v_rndne_f32_e32 v14, v14
	v_rndne_f32_e32 v15, v15
	v_cvt_i32_f32_e32 v12, v12
	v_cvt_i32_f32_sdwa v14, v14 dst_sel:WORD_1 dst_unused:UNUSED_PAD src0_sel:DWORD
	v_cvt_i32_f32_e32 v15, v15
	v_bfe_u32 v144, v93, 16, 1
	v_bfe_u32 v142, v69, 16, 1
	v_bfe_u32 v160, v125, 16, 1
	v_add3_u32 v144, v93, v144, s30
	v_bfe_u32 v93, v86, 16, 1
	v_lshlrev_b32_e32 v13, 8, v13
	v_bfe_u32 v163, v127, 16, 1
	v_add3_u32 v69, v69, v142, s30
	v_bfe_u32 v142, v90, 16, 1
	v_add3_u32 v160, v125, v160, s30
	v_add3_u32 v125, v86, v93, s30
	v_and_b32_e32 v13, 0xff00, v13
	v_and_b32_e32 v14, 0xff0000, v14
	v_perm_b32 v12, v15, v12, s34
	v_add3_u32 v163, v127, v163, s30
	v_add3_u32 v127, v90, v142, s30
	v_or3_b32 v12, v12, v13, v14
	v_and_b32_e32 v14, 0xffff0000, v125
	v_and_b32_e32 v13, 0xffff0000, v127
	v_mul_f32_e32 v14, v130, v14
	v_and_b32_e32 v15, 0xffff0000, v123
	v_and_b32_e32 v16, 0xffff0000, v121
	v_mul_f32_e32 v13, v130, v13
	v_rndne_f32_e32 v14, v14
	v_mul_f32_e32 v15, v130, v15
	v_mul_f32_e32 v16, v130, v16
	v_rndne_f32_e32 v13, v13
	v_cvt_i32_f32_e32 v14, v14
	v_rndne_f32_e32 v15, v15
	v_rndne_f32_e32 v16, v16
	v_cvt_i32_f32_e32 v13, v13
	v_cvt_i32_f32_sdwa v15, v15 dst_sel:WORD_1 dst_unused:UNUSED_PAD src0_sel:DWORD
	v_cvt_i32_f32_e32 v16, v16
	v_lshlrev_b32_e32 v14, 8, v14
	v_bfe_u32 v139, v79, 16, 1
	v_bfe_u32 v141, v67, 16, 1
	v_bfe_u32 v143, v91, 16, 1
	v_bfe_u32 v158, v101, 16, 1
	v_bfe_u32 v177, v120, 16, 1
	v_and_b32_e32 v14, 0xff00, v14
	v_and_b32_e32 v15, 0xff0000, v15
	v_perm_b32 v13, v16, v13, s34
	v_bfe_u32 v155, v111, 16, 1
	v_add3_u32 v139, v79, v139, s30
	v_add3_u32 v67, v67, v141, s30
	v_add3_u32 v91, v91, v143, s30
	v_bfe_u32 v143, v92, 16, 1
	v_add3_u32 v158, v101, v158, s30
	v_bfe_u32 v101, v122, 16, 1
	v_bfe_u32 v176, v118, 16, 1
	v_bfe_u32 v181, v116, 16, 1
	v_add3_u32 v76, v120, v177, s30
	v_and_b32_e32 v120, 0xffff0000, v71
	v_or3_b32 v13, v13, v14, v15
	v_add3_u32 v155, v111, v155, s30
	v_add3_u32 v111, v92, v143, s30
	v_add3_u32 v93, v122, v101, s30
	v_add3_u32 v92, v118, v176, s30
	v_add3_u32 v70, v116, v181, s30
	v_and_b32_e32 v122, 0xffff0000, v75
	v_and_b32_e32 v118, 0xffff0000, v139
	v_and_b32_e32 v116, 0xffff0000, v67
	global_store_dwordx2 v[4:5], v[12:13], off offset:1024 nt
	v_mul_f32_e32 v13, v131, v120
	v_mul_f32_e32 v12, v131, v122
	v_rndne_f32_e32 v13, v13
	v_mul_f32_e32 v14, v131, v118
	v_mul_f32_e32 v15, v131, v116
	v_rndne_f32_e32 v12, v12
	v_cvt_i32_f32_e32 v13, v13
	v_rndne_f32_e32 v14, v14
	v_rndne_f32_e32 v15, v15
	v_cvt_i32_f32_e32 v12, v12
	v_cvt_i32_f32_sdwa v14, v14 dst_sel:WORD_1 dst_unused:UNUSED_PAD src0_sel:DWORD
	v_cvt_i32_f32_e32 v15, v15
	v_bfe_u32 v145, v87, 16, 1
	v_bfe_u32 v147, v95, 16, 1
	v_bfe_u32 v149, v83, 16, 1
	v_bfe_u32 v151, v107, 16, 1
	v_bfe_u32 v165, v115, 16, 1
	v_bfe_u32 v79, v80, 16, 1
	v_add3_u32 v87, v87, v145, s30
	v_bfe_u32 v173, v112, 16, 1
	v_lshlrev_b32_e32 v13, 8, v13
	v_bfe_u32 v154, v105, 16, 1
	v_add3_u32 v147, v95, v147, s30
	v_bfe_u32 v95, v96, 16, 1
	v_add3_u32 v83, v83, v149, s30
	v_add3_u32 v151, v107, v151, s30
	v_bfe_u32 v107, v108, 16, 1
	v_bfe_u32 v172, v110, 16, 1
	v_bfe_u32 v180, v114, 16, 1
	v_add3_u32 v165, v115, v165, s30
	v_add3_u32 v115, v80, v79, s30
	v_add3_u32 v79, v112, v173, s30
	v_and_b32_e32 v112, 0xffff0000, v87
	v_and_b32_e32 v13, 0xff00, v13
	v_and_b32_e32 v14, 0xff0000, v14
	v_perm_b32 v12, v15, v12, s34
	v_add3_u32 v154, v105, v154, s30
	v_add3_u32 v105, v96, v95, s30
	v_add3_u32 v81, v108, v107, s30
	v_add3_u32 v95, v110, v172, s30
	v_add3_u32 v86, v114, v180, s30
	v_and_b32_e32 v114, 0xffff0000, v91
	v_and_b32_e32 v110, 0xffff0000, v147
	v_and_b32_e32 v108, 0xffff0000, v83
	v_or3_b32 v12, v12, v13, v14
	v_mul_f32_e32 v14, v131, v112
	v_mul_f32_e32 v13, v131, v114
	v_rndne_f32_e32 v14, v14
	v_mul_f32_e32 v15, v131, v110
	v_mul_f32_e32 v16, v131, v108
	v_rndne_f32_e32 v13, v13
	v_cvt_i32_f32_e32 v14, v14
	v_rndne_f32_e32 v15, v15
	v_rndne_f32_e32 v16, v16
	v_cvt_i32_f32_e32 v13, v13
	v_cvt_i32_f32_sdwa v15, v15 dst_sel:WORD_1 dst_unused:UNUSED_PAD src0_sel:DWORD
	v_cvt_i32_f32_e32 v16, v16
	v_lshlrev_b32_e32 v14, 8, v14
	v_bfe_u32 v166, v117, 16, 1
	v_bfe_u32 v169, v72, 16, 1
	v_and_b32_e32 v14, 0xff00, v14
	v_and_b32_e32 v15, 0xff0000, v15
	v_perm_b32 v13, v16, v13, s34
	v_bfe_u32 v156, v113, 16, 1
	v_bfe_u32 v141, v68, 16, 1
	v_add3_u32 v166, v117, v166, s30
	v_add3_u32 v117, v72, v169, s30
	v_or3_b32 v13, v13, v14, v15
	v_add3_u32 v156, v113, v156, s30
	v_add3_u32 v113, v68, v141, s30
	global_store_dwordx2 v[8:9], v[12:13], off offset:1024 nt
	v_and_b32_e32 v13, 0xffff0000, v117
	v_and_b32_e32 v12, 0xffff0000, v119
	v_mul_f32_e32 v13, v132, v13
	v_and_b32_e32 v14, 0xffff0000, v115
	v_and_b32_e32 v15, 0xffff0000, v113
	v_mul_f32_e32 v12, v132, v12
	v_rndne_f32_e32 v13, v13
	v_mul_f32_e32 v14, v132, v14
	v_mul_f32_e32 v15, v132, v15
	v_rndne_f32_e32 v12, v12
	v_cvt_i32_f32_e32 v13, v13
	v_rndne_f32_e32 v14, v14
	v_rndne_f32_e32 v15, v15
	v_cvt_i32_f32_e32 v12, v12
	v_cvt_i32_f32_sdwa v14, v14 dst_sel:WORD_1 dst_unused:UNUSED_PAD src0_sel:DWORD
	v_cvt_i32_f32_e32 v15, v15
	v_bfe_u32 v152, v109, 16, 1
	v_bfe_u32 v145, v88, 16, 1
	v_lshlrev_b32_e32 v13, 8, v13
	v_bfe_u32 v153, v103, 16, 1
	v_bfe_u32 v149, v84, 16, 1
	v_add3_u32 v152, v109, v152, s30
	v_add3_u32 v109, v88, v145, s30
	v_and_b32_e32 v13, 0xff00, v13
	v_and_b32_e32 v14, 0xff0000, v14
	v_perm_b32 v12, v15, v12, s34
	v_add3_u32 v153, v103, v153, s30
	v_add3_u32 v103, v84, v149, s30
	v_or3_b32 v12, v12, v13, v14
	v_and_b32_e32 v14, 0xffff0000, v109
	v_and_b32_e32 v13, 0xffff0000, v111
	v_mul_f32_e32 v14, v132, v14
	v_and_b32_e32 v15, 0xffff0000, v105
	v_and_b32_e32 v16, 0xffff0000, v103
	v_mul_f32_e32 v13, v132, v13
	v_rndne_f32_e32 v14, v14
	v_mul_f32_e32 v15, v132, v15
	v_mul_f32_e32 v16, v132, v16
	v_rndne_f32_e32 v13, v13
	v_cvt_i32_f32_e32 v14, v14
	v_rndne_f32_e32 v15, v15
	v_rndne_f32_e32 v16, v16
	v_cvt_i32_f32_e32 v13, v13
	v_cvt_i32_f32_sdwa v15, v15 dst_sel:WORD_1 dst_unused:UNUSED_PAD src0_sel:DWORD
	v_cvt_i32_f32_e32 v16, v16
	v_lshlrev_b32_e32 v14, 8, v14
	v_and_b32_e32 v14, 0xff00, v14
	v_and_b32_e32 v15, 0xff0000, v15
	v_perm_b32 v13, v16, v13, s34
	v_bfe_u32 v170, v102, 16, 1
	v_bfe_u32 v171, v104, 16, 1
	v_or3_b32 v13, v13, v14, v15
	v_add3_u32 v96, v102, v170, s30
	v_add3_u32 v80, v104, v171, s30
	v_and_b32_e32 v107, 0xffff0000, v168
	v_and_b32_e32 v104, 0xffff0000, v140
	v_and_b32_e32 v102, 0xffff0000, v69
	global_store_dwordx2 v[6:7], v[12:13], off offset:1024 nt
	v_mul_f32_e32 v13, v133, v106
	v_mul_f32_e32 v12, v133, v107
	v_rndne_f32_e32 v13, v13
	v_mul_f32_e32 v14, v133, v104
	v_mul_f32_e32 v15, v133, v102
	v_rndne_f32_e32 v12, v12
	v_cvt_i32_f32_e32 v13, v13
	v_rndne_f32_e32 v14, v14
	v_rndne_f32_e32 v15, v15
	v_cvt_i32_f32_e32 v12, v12
	v_cvt_i32_f32_sdwa v14, v14 dst_sel:WORD_1 dst_unused:UNUSED_PAD src0_sel:DWORD
	v_cvt_i32_f32_e32 v15, v15
	v_bfe_u32 v157, v99, 16, 1
	v_add3_u32 v157, v99, v157, s30
	v_bfe_u32 v99, v100, 16, 1
	v_lshlrev_b32_e32 v13, 8, v13
	v_bfe_u32 v174, v98, 16, 1
	v_add3_u32 v78, v100, v99, s30
	v_and_b32_e32 v100, 0xffff0000, v146
	v_and_b32_e32 v13, 0xff00, v13
	v_and_b32_e32 v14, 0xff0000, v14
	v_perm_b32 v12, v15, v12, s34
	v_add3_u32 v94, v98, v174, s30
	v_and_b32_e32 v101, 0xffff0000, v144
	v_and_b32_e32 v99, 0xffff0000, v148
	v_and_b32_e32 v98, 0xffff0000, v85
	v_or3_b32 v12, v12, v13, v14
	v_mul_f32_e32 v14, v133, v100
	v_mul_f32_e32 v13, v133, v101
	v_rndne_f32_e32 v14, v14
	v_mul_f32_e32 v15, v133, v99
	v_mul_f32_e32 v16, v133, v98
	v_rndne_f32_e32 v13, v13
	v_cvt_i32_f32_e32 v14, v14
	v_rndne_f32_e32 v15, v15
	v_rndne_f32_e32 v16, v16
	v_cvt_i32_f32_e32 v13, v13
	v_cvt_i32_f32_sdwa v15, v15 dst_sel:WORD_1 dst_unused:UNUSED_PAD src0_sel:DWORD
	v_cvt_i32_f32_e32 v16, v16
	v_lshlrev_b32_e32 v14, 8, v14
	v_and_b32_e32 v14, 0xff00, v14
	v_and_b32_e32 v15, 0xff0000, v15
	v_perm_b32 v13, v16, v13, s34
	v_or3_b32 v13, v13, v14, v15
	global_store_dwordx2 v[10:11], v[12:13], off offset:1024 nt
	v_and_b32_e32 v13, 0xffff0000, v96
	v_and_b32_e32 v12, 0xffff0000, v97
	v_mul_f32_e32 v13, v130, v13
	v_and_b32_e32 v14, 0xffff0000, v95
	v_and_b32_e32 v15, 0xffff0000, v94
	v_mul_f32_e32 v12, v130, v12
	v_rndne_f32_e32 v13, v13
	v_mul_f32_e32 v14, v130, v14
	v_mul_f32_e32 v15, v130, v15
	v_rndne_f32_e32 v12, v12
	v_cvt_i32_f32_e32 v13, v13
	v_rndne_f32_e32 v14, v14
	v_rndne_f32_e32 v15, v15
	v_cvt_i32_f32_e32 v12, v12
	v_cvt_i32_f32_sdwa v14, v14 dst_sel:WORD_1 dst_unused:UNUSED_PAD src0_sel:DWORD
	v_cvt_i32_f32_e32 v15, v15
	v_lshlrev_b32_e32 v13, 8, v13
	v_and_b32_e32 v13, 0xff00, v13
	v_and_b32_e32 v14, 0xff0000, v14
	v_perm_b32 v12, v15, v12, s34
	v_or3_b32 v12, v12, v13, v14
	v_and_b32_e32 v14, 0xffff0000, v92
	v_and_b32_e32 v13, 0xffff0000, v93
	v_mul_f32_e32 v14, v130, v14
	v_and_b32_e32 v15, 0xffff0000, v89
	v_and_b32_e32 v16, 0xffff0000, v86
	v_mul_f32_e32 v13, v130, v13
	v_rndne_f32_e32 v14, v14
	v_mul_f32_e32 v15, v130, v15
	v_mul_f32_e32 v16, v130, v16
	v_rndne_f32_e32 v13, v13
	v_cvt_i32_f32_e32 v14, v14
	v_rndne_f32_e32 v15, v15
	v_rndne_f32_e32 v16, v16
	v_cvt_i32_f32_e32 v13, v13
	v_cvt_i32_f32_sdwa v15, v15 dst_sel:WORD_1 dst_unused:UNUSED_PAD src0_sel:DWORD
	v_cvt_i32_f32_e32 v16, v16
	v_lshlrev_b32_e32 v14, 8, v14
	v_and_b32_e32 v14, 0xff00, v14
	v_and_b32_e32 v15, 0xff0000, v15
	v_perm_b32 v13, v16, v13, s34
	v_and_b32_e32 v90, 0xffff0000, v153
	v_or3_b32 v13, v13, v14, v15
	v_and_b32_e32 v91, 0xffff0000, v151
	v_and_b32_e32 v88, 0xffff0000, v155
	v_and_b32_e32 v87, 0xffff0000, v157
	global_store_dwordx2 v[4:5], v[12:13], off offset:1536 nt
	v_mul_f32_e32 v5, v131, v90
	v_mul_f32_e32 v4, v131, v91
	v_rndne_f32_e32 v5, v5
	v_mul_f32_e32 v12, v131, v88
	v_mul_f32_e32 v13, v131, v87
	v_rndne_f32_e32 v4, v4
	v_cvt_i32_f32_e32 v5, v5
	v_rndne_f32_e32 v12, v12
	v_rndne_f32_e32 v13, v13
	v_cvt_i32_f32_e32 v4, v4
	v_cvt_i32_f32_sdwa v12, v12 dst_sel:WORD_1 dst_unused:UNUSED_PAD src0_sel:DWORD
	v_cvt_i32_f32_e32 v13, v13
	v_lshlrev_b32_e32 v5, 8, v5
	v_and_b32_e32 v84, 0xffff0000, v161
	v_and_b32_e32 v5, 0xff00, v5
	v_and_b32_e32 v12, 0xff0000, v12
	v_perm_b32 v4, v13, v4, s34
	v_and_b32_e32 v85, 0xffff0000, v159
	v_and_b32_e32 v83, 0xffff0000, v163
	v_and_b32_e32 v82, 0xffff0000, v165
	v_or3_b32 v4, v4, v5, v12
	v_mul_f32_e32 v12, v131, v84
	v_mul_f32_e32 v5, v131, v85
	v_rndne_f32_e32 v12, v12
	v_mul_f32_e32 v13, v131, v83
	v_mul_f32_e32 v14, v131, v82
	v_rndne_f32_e32 v5, v5
	v_cvt_i32_f32_e32 v12, v12
	v_rndne_f32_e32 v13, v13
	v_rndne_f32_e32 v14, v14
	v_cvt_i32_f32_e32 v5, v5
	v_cvt_i32_f32_sdwa v13, v13 dst_sel:WORD_1 dst_unused:UNUSED_PAD src0_sel:DWORD
	v_cvt_i32_f32_e32 v14, v14
	v_lshlrev_b32_e32 v12, 8, v12
	v_and_b32_e32 v12, 0xff00, v12
	v_and_b32_e32 v13, 0xff0000, v13
	v_perm_b32 v5, v14, v5, s34
	v_or3_b32 v5, v5, v12, v13
	global_store_dwordx2 v[8:9], v[4:5], off offset:1536 nt
	v_and_b32_e32 v5, 0xffff0000, v80
	v_and_b32_e32 v4, 0xffff0000, v81
	v_mul_f32_e32 v5, v132, v5
	v_and_b32_e32 v8, 0xffff0000, v79
	v_and_b32_e32 v9, 0xffff0000, v78
	v_mul_f32_e32 v4, v132, v4
	v_rndne_f32_e32 v5, v5
	v_mul_f32_e32 v8, v132, v8
	v_mul_f32_e32 v9, v132, v9
	v_rndne_f32_e32 v4, v4
	v_cvt_i32_f32_e32 v5, v5
	v_rndne_f32_e32 v8, v8
	v_rndne_f32_e32 v9, v9
	v_cvt_i32_f32_e32 v4, v4
	v_cvt_i32_f32_sdwa v8, v8 dst_sel:WORD_1 dst_unused:UNUSED_PAD src0_sel:DWORD
	v_cvt_i32_f32_e32 v9, v9
	v_lshlrev_b32_e32 v5, 8, v5
	v_and_b32_e32 v5, 0xff00, v5
	v_and_b32_e32 v8, 0xff0000, v8
	v_perm_b32 v4, v9, v4, s34
	v_or3_b32 v4, v4, v5, v8
	v_and_b32_e32 v8, 0xffff0000, v76
	v_and_b32_e32 v5, 0xffff0000, v77
	v_mul_f32_e32 v8, v132, v8
	v_and_b32_e32 v9, 0xffff0000, v73
	v_and_b32_e32 v12, 0xffff0000, v70
	v_mul_f32_e32 v5, v132, v5
	v_rndne_f32_e32 v8, v8
	v_mul_f32_e32 v9, v132, v9
	v_mul_f32_e32 v12, v132, v12
	v_rndne_f32_e32 v5, v5
	v_cvt_i32_f32_e32 v8, v8
	v_rndne_f32_e32 v9, v9
	v_rndne_f32_e32 v12, v12
	v_cvt_i32_f32_e32 v5, v5
	v_cvt_i32_f32_sdwa v9, v9 dst_sel:WORD_1 dst_unused:UNUSED_PAD src0_sel:DWORD
	v_cvt_i32_f32_e32 v12, v12
	v_lshlrev_b32_e32 v8, 8, v8
	v_and_b32_e32 v8, 0xff00, v8
	v_and_b32_e32 v9, 0xff0000, v9
	v_perm_b32 v5, v12, v5, s34
	v_and_b32_e32 v74, 0xffff0000, v154
	v_or3_b32 v5, v5, v8, v9
	v_and_b32_e32 v75, 0xffff0000, v152
	v_and_b32_e32 v72, 0xffff0000, v156
	v_and_b32_e32 v71, 0xffff0000, v158
	global_store_dwordx2 v[6:7], v[4:5], off offset:1536 nt
	v_mul_f32_e32 v5, v133, v74
	v_mul_f32_e32 v4, v133, v75
	v_rndne_f32_e32 v5, v5
	v_mul_f32_e32 v6, v133, v72
	v_mul_f32_e32 v7, v133, v71
	v_rndne_f32_e32 v4, v4
	v_cvt_i32_f32_e32 v5, v5
	v_rndne_f32_e32 v6, v6
	v_rndne_f32_e32 v7, v7
	v_cvt_i32_f32_e32 v4, v4
	v_cvt_i32_f32_sdwa v6, v6 dst_sel:WORD_1 dst_unused:UNUSED_PAD src0_sel:DWORD
	v_cvt_i32_f32_e32 v7, v7
	v_lshlrev_b32_e32 v5, 8, v5
	v_and_b32_e32 v68, 0xffff0000, v162
	v_and_b32_e32 v5, 0xff00, v5
	v_and_b32_e32 v6, 0xff0000, v6
	v_perm_b32 v4, v7, v4, s34
	v_and_b32_e32 v69, 0xffff0000, v160
	v_and_b32_e32 v67, 0xffff0000, v164
	v_and_b32_e32 v66, 0xffff0000, v166
	v_or3_b32 v4, v4, v5, v6
	v_mul_f32_e32 v6, v133, v68
	v_mul_f32_e32 v5, v133, v69
	v_rndne_f32_e32 v6, v6
	v_mul_f32_e32 v7, v133, v67
	v_mul_f32_e32 v8, v133, v66
	v_rndne_f32_e32 v5, v5
	v_cvt_i32_f32_e32 v6, v6
	v_rndne_f32_e32 v7, v7
	v_rndne_f32_e32 v8, v8
	v_cvt_i32_f32_e32 v5, v5
	v_cvt_i32_f32_sdwa v7, v7 dst_sel:WORD_1 dst_unused:UNUSED_PAD src0_sel:DWORD
	v_cvt_i32_f32_e32 v8, v8
	v_lshlrev_b32_e32 v6, 8, v6
	v_ashrrev_i32_e32 v201, 31, v200
	v_and_b32_e32 v6, 0xff00, v6
	v_and_b32_e32 v7, 0xff0000, v7
	v_perm_b32 v5, v8, v5, s34
	v_lshlrev_b64 v[2:3], 12, v[200:201]
	v_or3_b32 v5, v5, v6, v7
	v_lshl_add_u64 v[2:3], v[196:197], 0, v[2:3]
	global_store_dwordx2 v[10:11], v[4:5], off offset:1536 nt
	s_mov_b64 s[16:17], 0
	v_mov_b32_e32 v4, v212
.LBB0_247:
	ds_read_b128 v[6:9], v4
	ds_read_b128 v[10:13], v4 offset:8192
	ds_read_b128 v[14:17], v4 offset:16384
	ds_read_b128 v[18:21], v4 offset:24576
	v_lshl_add_u64 v[22:23], v[2:3], 0, s[16:17]
	s_waitcnt lgkmcnt(3)
	v_lshlrev_b32_e32 v30, 16, v8
	v_lshlrev_b32_e32 v5, 16, v6
	s_waitcnt lgkmcnt(1)
	v_lshlrev_b32_e32 v34, 16, v16
	v_lshlrev_b32_e32 v31, 16, v10
	v_lshlrev_b32_e32 v33, 16, v14
	s_waitcnt lgkmcnt(0)
	v_lshlrev_b32_e32 v35, 16, v18
	v_and_b32_e32 v8, 0xffff0000, v8
	v_and_b32_e32 v16, 0xffff0000, v16
	v_lshlrev_b32_e32 v38, 16, v9
	v_lshlrev_b32_e32 v39, 16, v11
	v_lshlrev_b32_e32 v42, 16, v17
	v_lshlrev_b32_e32 v43, 16, v19
	v_and_b32_e32 v9, 0xffff0000, v9
	v_and_b32_e32 v11, 0xffff0000, v11
	v_and_b32_e32 v17, 0xffff0000, v17
	v_and_b32_e32 v19, 0xffff0000, v19
	v_mul_f32_e32 v30, v130, v30
	v_mul_f32_e32 v34, v130, v34
	v_lshlrev_b32_e32 v32, 16, v12
	v_lshlrev_b32_e32 v36, 16, v20
	v_and_b32_e32 v6, 0xffff0000, v6
	v_and_b32_e32 v10, 0xffff0000, v10
	v_and_b32_e32 v14, 0xffff0000, v14
	v_and_b32_e32 v18, 0xffff0000, v18
	v_lshlrev_b32_e32 v37, 16, v7
	v_lshlrev_b32_e32 v41, 16, v15
	v_and_b32_e32 v7, 0xffff0000, v7
	v_and_b32_e32 v15, 0xffff0000, v15
	v_mul_f32_e32 v5, v130, v5
	v_mul_f32_e32 v31, v130, v31
	v_mul_f32_e32 v33, v130, v33
	v_mul_f32_e32 v35, v130, v35
	v_mul_f32_e32 v8, v131, v8
	v_mul_f32_e32 v16, v131, v16
	v_mul_f32_e32 v38, v132, v38
	v_mul_f32_e32 v42, v132, v42
	v_mul_f32_e32 v9, v133, v9
	v_mul_f32_e32 v11, v133, v11
	v_mul_f32_e32 v17, v133, v17
	v_mul_f32_e32 v19, v133, v19
	v_rndne_f32_e32 v30, v30
	v_rndne_f32_e32 v34, v34
	v_add_co_u32_e32 v24, vcc, s39, v22
	v_and_b32_e32 v12, 0xffff0000, v12
	v_and_b32_e32 v20, 0xffff0000, v20
	v_lshlrev_b32_e32 v40, 16, v13
	v_lshlrev_b32_e32 v44, 16, v21
	v_and_b32_e32 v13, 0xffff0000, v13
	v_and_b32_e32 v21, 0xffff0000, v21
	v_mul_f32_e32 v32, v130, v32
	v_mul_f32_e32 v36, v130, v36
	v_mul_f32_e32 v6, v131, v6
	v_mul_f32_e32 v10, v131, v10
	v_mul_f32_e32 v14, v131, v14
	v_mul_f32_e32 v18, v131, v18
	v_mul_f32_e32 v37, v132, v37
	v_mul_f32_e32 v39, v132, v39
	v_mul_f32_e32 v41, v132, v41
	v_mul_f32_e32 v43, v132, v43
	v_mul_f32_e32 v7, v133, v7
	v_mul_f32_e32 v15, v133, v15
	v_rndne_f32_e32 v5, v5
	v_rndne_f32_e32 v31, v31
	v_rndne_f32_e32 v33, v33
	v_rndne_f32_e32 v35, v35
	v_rndne_f32_e32 v8, v8
	v_rndne_f32_e32 v16, v16
	v_rndne_f32_e32 v38, v38
	v_rndne_f32_e32 v42, v42
	v_rndne_f32_e32 v9, v9
	v_rndne_f32_e32 v11, v11
	v_rndne_f32_e32 v17, v17
	v_rndne_f32_e32 v19, v19
	v_cvt_i32_f32_e32 v30, v30
	v_cvt_i32_f32_e32 v34, v34
	v_addc_co_u32_e32 v25, vcc, 0, v23, vcc
	v_mul_f32_e32 v12, v131, v12
	v_mul_f32_e32 v20, v131, v20
	v_mul_f32_e32 v40, v132, v40
	v_mul_f32_e32 v44, v132, v44
	v_mul_f32_e32 v13, v133, v13
	v_mul_f32_e32 v21, v133, v21
	v_rndne_f32_e32 v32, v32
	v_rndne_f32_e32 v36, v36
	v_rndne_f32_e32 v6, v6
	v_rndne_f32_e32 v10, v10
	v_rndne_f32_e32 v14, v14
	v_rndne_f32_e32 v18, v18
	v_rndne_f32_e32 v37, v37
	v_rndne_f32_e32 v39, v39
	v_rndne_f32_e32 v41, v41
	v_rndne_f32_e32 v43, v43
	v_rndne_f32_e32 v7, v7
	v_rndne_f32_e32 v15, v15
	v_cvt_i32_f32_e32 v5, v5
	v_cvt_i32_f32_sdwa v31, v31 dst_sel:WORD_1 dst_unused:UNUSED_PAD src0_sel:DWORD
	v_cvt_i32_f32_e32 v33, v33
	v_cvt_i32_f32_sdwa v35, v35 dst_sel:WORD_1 dst_unused:UNUSED_PAD src0_sel:DWORD
	v_cvt_i32_f32_e32 v8, v8
	v_cvt_i32_f32_e32 v16, v16
	v_cvt_i32_f32_e32 v38, v38
	v_cvt_i32_f32_e32 v42, v42
	v_cvt_i32_f32_e32 v9, v9
	v_cvt_i32_f32_sdwa v11, v11 dst_sel:WORD_1 dst_unused:UNUSED_PAD src0_sel:DWORD
	v_cvt_i32_f32_e32 v17, v17
	v_cvt_i32_f32_sdwa v19, v19 dst_sel:WORD_1 dst_unused:UNUSED_PAD src0_sel:DWORD
	v_add_co_u32_e32 v26, vcc, s40, v22
	v_rndne_f32_e32 v12, v12
	v_rndne_f32_e32 v20, v20
	v_rndne_f32_e32 v40, v40
	v_rndne_f32_e32 v44, v44
	v_rndne_f32_e32 v13, v13
	v_rndne_f32_e32 v21, v21
	v_cvt_i32_f32_sdwa v32, v32 dst_sel:BYTE_3 dst_unused:UNUSED_PAD src0_sel:DWORD
	v_cvt_i32_f32_sdwa v36, v36 dst_sel:BYTE_3 dst_unused:UNUSED_PAD src0_sel:DWORD
	v_cvt_i32_f32_e32 v6, v6
	v_cvt_i32_f32_sdwa v10, v10 dst_sel:WORD_1 dst_unused:UNUSED_PAD src0_sel:DWORD
	v_cvt_i32_f32_e32 v14, v14
	v_cvt_i32_f32_sdwa v18, v18 dst_sel:WORD_1 dst_unused:UNUSED_PAD src0_sel:DWORD
	v_cvt_i32_f32_e32 v37, v37
	v_cvt_i32_f32_sdwa v39, v39 dst_sel:WORD_1 dst_unused:UNUSED_PAD src0_sel:DWORD
	v_cvt_i32_f32_e32 v41, v41
	v_cvt_i32_f32_sdwa v43, v43 dst_sel:WORD_1 dst_unused:UNUSED_PAD src0_sel:DWORD
	v_cvt_i32_f32_e32 v7, v7
	v_cvt_i32_f32_e32 v15, v15
	v_addc_co_u32_e32 v27, vcc, 0, v23, vcc
	v_cvt_i32_f32_sdwa v12, v12 dst_sel:BYTE_3 dst_unused:UNUSED_PAD src0_sel:DWORD
	v_cvt_i32_f32_sdwa v20, v20 dst_sel:BYTE_3 dst_unused:UNUSED_PAD src0_sel:DWORD
	v_cvt_i32_f32_sdwa v40, v40 dst_sel:BYTE_3 dst_unused:UNUSED_PAD src0_sel:DWORD
	v_cvt_i32_f32_sdwa v44, v44 dst_sel:BYTE_3 dst_unused:UNUSED_PAD src0_sel:DWORD
	v_cvt_i32_f32_sdwa v13, v13 dst_sel:BYTE_3 dst_unused:UNUSED_PAD src0_sel:DWORD
	v_cvt_i32_f32_sdwa v21, v21 dst_sel:BYTE_3 dst_unused:UNUSED_PAD src0_sel:DWORD
	s_add_u32 s16, s16, 0x200
	v_add_co_u32_e32 v28, vcc, s41, v22
	v_lshlrev_b32_e32 v30, 8, v30
	v_lshlrev_b32_e32 v34, 8, v34
	v_addc_co_u32_e32 v29, vcc, 0, v23, vcc
	s_addc_u32 s17, s17, 0
	v_and_b32_e32 v31, 0xff0000, v31
	v_and_b32_e32 v35, 0xff0000, v35
	v_lshlrev_b32_e32 v8, 8, v8
	v_lshlrev_b32_e32 v16, 8, v16
	v_lshlrev_b32_e32 v38, 8, v38
	v_lshlrev_b32_e32 v42, 8, v42
	v_lshlrev_b32_e32 v9, 8, v9
	v_and_b32_e32 v45, 0xff0000, v11
	v_lshlrev_b32_e32 v11, 8, v17
	v_and_b32_e32 v17, 0xff0000, v19
	v_perm_b32 v5, v30, v5, s38
	v_perm_b32 v19, v34, v33, s38
	v_add_u32_e32 v4, 0x8000, v4
	v_add_co_u32_e32 v22, vcc, s42, v22
	s_cmpk_lg_i32 s16, 0x800
	v_and_b32_e32 v10, 0xff0000, v10
	v_and_b32_e32 v18, 0xff0000, v18
	v_and_b32_e32 v39, 0xff0000, v39
	v_and_b32_e32 v43, 0xff0000, v43
	v_perm_b32 v8, v8, v6, s38
	v_perm_b32 v14, v16, v14, s38
	v_perm_b32 v16, v38, v37, s38
	v_perm_b32 v30, v42, v41, s38
	v_perm_b32 v33, v9, v7, s38
	v_perm_b32 v15, v11, v15, s38
	v_or3_b32 v6, v5, v32, v31
	v_or3_b32 v7, v19, v36, v35
	v_addc_co_u32_e32 v23, vcc, 0, v23, vcc
	v_or3_b32 v8, v8, v12, v10
	v_or3_b32 v9, v14, v20, v18
	v_or3_b32 v10, v16, v40, v39
	v_or3_b32 v11, v30, v44, v43
	v_or3_b32 v12, v33, v13, v45
	v_or3_b32 v13, v15, v21, v17
	global_store_dwordx2 v[24:25], v[6:7], off offset:2048 nt
	global_store_dwordx2 v[26:27], v[8:9], off offset:2048 nt
	global_store_dwordx2 v[28:29], v[10:11], off offset:2048 nt
	global_store_dwordx2 v[22:23], v[12:13], off offset:2048 nt
	s_cbranch_scc1 .LBB0_247
	s_add_i32 s43, s43, s3
	s_add_i32 s28, s28, s79
	s_add_i32 s15, s15, s3
	v_add_u32_e32 v216, s79, v216
	s_cmpk_gt_i32 s43, 0x337
	v_add_u32_e32 v200, s79, v200
	s_barrier
	s_cbranch_scc0 .LBB0_8

.LBB0_354:
	v_ashrrev_i32_e32 v133, 31, v132
	s_waitcnt vmcnt(1)
	v_bfe_u32 v130, v106, 16, 1
	v_lshlrev_b64 v[132:133], 13, v[132:133]
	v_add3_u32 v106, v106, v130, s26
	s_waitcnt vmcnt(0)
	v_bfe_u32 v130, v102, 16, 1
	v_lshl_add_u64 v[132:133], s[8:9], 0, v[132:133]
	v_lshrrev_b32_e32 v106, 16, v106
	v_add3_u32 v102, v102, v130, s26
	v_lshl_add_u64 v[136:137], v[134:135], 1, v[132:133]
	v_and_or_b32 v132, v102, s27, v106
	v_bfe_u32 v102, v110, 16, 1
	v_add3_u32 v102, v110, v102, s26
	v_bfe_u32 v106, v98, 16, 1
	v_lshrrev_b32_e32 v102, 16, v102
	v_add3_u32 v98, v98, v106, s26
	v_and_or_b32 v133, v98, s27, v102
	v_bfe_u32 v98, v122, 16, 1
	v_add3_u32 v98, v122, v98, s26
	v_bfe_u32 v102, v118, 16, 1
	v_lshrrev_b32_e32 v98, 16, v98
	v_add3_u32 v102, v118, v102, s26
	v_and_or_b32 v134, v102, s27, v98
	v_bfe_u32 v98, v126, 16, 1
	v_add3_u32 v98, v126, v98, s26
	v_bfe_u32 v102, v114, 16, 1
	v_lshrrev_b32_e32 v98, 16, v98
	v_add3_u32 v102, v114, v102, s26
	v_and_or_b32 v135, v102, s27, v98
	v_bfe_u32 v98, v107, 16, 1
	v_add3_u32 v98, v107, v98, s26
	v_bfe_u32 v102, v103, 16, 1
	v_lshrrev_b32_e32 v98, 16, v98
	v_add3_u32 v102, v103, v102, s26
	global_store_dwordx4 v[136:137], v[132:135], off nt
	s_nop 1
	v_and_or_b32 v132, v102, s27, v98
	v_bfe_u32 v98, v111, 16, 1
	v_add3_u32 v98, v111, v98, s26
	v_bfe_u32 v102, v99, 16, 1
	v_lshrrev_b32_e32 v98, 16, v98
	v_add3_u32 v99, v99, v102, s26
	v_and_or_b32 v133, v99, s27, v98
	v_bfe_u32 v98, v123, 16, 1
	v_add3_u32 v98, v123, v98, s26
	v_bfe_u32 v99, v119, 16, 1
	v_lshrrev_b32_e32 v98, 16, v98
	v_add3_u32 v99, v119, v99, s26
	v_and_or_b32 v134, v99, s27, v98
	v_bfe_u32 v98, v127, 16, 1
	v_add3_u32 v98, v127, v98, s26
	v_bfe_u32 v99, v115, 16, 1
	v_lshrrev_b32_e32 v98, 16, v98
	v_add3_u32 v99, v115, v99, s26
	v_and_or_b32 v135, v99, s27, v98
	v_add_co_u32_e32 v98, vcc, s28, v136
	v_bfe_u32 v102, v117, 16, 1
	s_nop 0
	v_addc_co_u32_e32 v99, vcc, 0, v137, vcc
	global_store_dwordx4 v[98:99], v[132:135], off nt
	v_bfe_u32 v98, v108, 16, 1
	v_add3_u32 v98, v108, v98, s26
	v_bfe_u32 v99, v104, 16, 1
	v_lshrrev_b32_e32 v98, 16, v98
	v_add3_u32 v99, v104, v99, s26
	v_and_or_b32 v132, v99, s27, v98
	v_bfe_u32 v98, v112, 16, 1
	v_add3_u32 v98, v112, v98, s26
	v_bfe_u32 v99, v100, 16, 1
	v_lshrrev_b32_e32 v98, 16, v98
	v_add3_u32 v99, v100, v99, s26
	v_and_or_b32 v133, v99, s27, v98
	v_bfe_u32 v98, v124, 16, 1
	v_add3_u32 v98, v124, v98, s26
	v_bfe_u32 v99, v120, 16, 1
	v_lshrrev_b32_e32 v98, 16, v98
	v_add3_u32 v99, v120, v99, s26
	v_and_or_b32 v134, v99, s27, v98
	v_bfe_u32 v98, v128, 16, 1
	v_add3_u32 v98, v128, v98, s26
	v_bfe_u32 v99, v116, 16, 1
	v_lshrrev_b32_e32 v98, 16, v98
	v_add3_u32 v99, v116, v99, s26
	v_and_or_b32 v135, v99, s27, v98
	v_add_co_u32_e32 v98, vcc, s29, v136
	v_bfe_u32 v100, v101, 16, 1
	s_nop 0
	v_addc_co_u32_e32 v99, vcc, 0, v137, vcc
	global_store_dwordx4 v[98:99], v[132:135], off nt
	v_bfe_u32 v98, v109, 16, 1
	v_add3_u32 v98, v109, v98, s26
	v_bfe_u32 v99, v105, 16, 1
	v_lshrrev_b32_e32 v98, 16, v98
	v_add3_u32 v99, v105, v99, s26
	v_and_or_b32 v98, v99, s27, v98
	v_bfe_u32 v99, v113, 16, 1
	v_add3_u32 v99, v113, v99, s26
	v_lshrrev_b32_e32 v99, 16, v99
	v_add3_u32 v100, v101, v100, s26
	v_and_or_b32 v99, v100, s27, v99
	v_bfe_u32 v100, v125, 16, 1
	v_add3_u32 v100, v125, v100, s26
	v_bfe_u32 v101, v121, 16, 1
	v_lshrrev_b32_e32 v100, 16, v100
	v_add3_u32 v101, v121, v101, s26
	v_and_or_b32 v100, v101, s27, v100
	v_bfe_u32 v101, v129, 16, 1
	v_add3_u32 v101, v129, v101, s26
	v_lshrrev_b32_e32 v101, 16, v101
	v_add3_u32 v102, v117, v102, s26
	v_and_or_b32 v101, v102, s27, v101
	v_add_co_u32_e32 v102, vcc, 0x6000, v136
	s_nop 1
	v_addc_co_u32_e32 v103, vcc, 0, v137, vcc
	s_andn2_b64 vcc, exec, s[16:17]
	global_store_dwordx4 v[102:103], v[98:101], off nt
	s_cbranch_vccnz .LBB0_357
	s_lshr_b32 s4, s31, 31
	s_ashr_i32 s5, s31, 4
	s_add_i32 s4, s5, s4
	v_lshl_or_b32 v98, s4, 6, v138
	s_mulk_i32 s4, 0xf400
	s_add_i32 s4, s4, s0
	v_add_u32_e32 v100, s4, v143
	v_ashrrev_i32_e32 v101, 31, v100
	v_lshlrev_b64 v[100:101], 13, v[100:101]
	v_ashrrev_i32_e32 v99, 31, v98
	v_lshl_add_u64 v[100:101], s[8:9], 0, v[100:101]
	v_lshl_add_u64 v[102:103], v[98:99], 1, v[100:101]
	v_bfe_u32 v98, v38, 16, 1
	v_add3_u32 v98, v38, v98, s26
	v_bfe_u32 v99, v34, 16, 1
	v_lshrrev_b32_e32 v98, 16, v98
	v_add3_u32 v99, v34, v99, s26
	v_and_or_b32 v98, v99, s27, v98
	v_bfe_u32 v99, v58, 16, 1
	v_add3_u32 v99, v58, v99, s26
	v_bfe_u32 v100, v30, 16, 1
	v_lshrrev_b32_e32 v99, 16, v99
	v_add3_u32 v100, v30, v100, s26
	v_and_or_b32 v99, v100, s27, v99
	v_bfe_u32 v100, v86, 16, 1
	v_add3_u32 v100, v86, v100, s26
	v_bfe_u32 v101, v82, 16, 1
	v_lshrrev_b32_e32 v100, 16, v100
	v_add3_u32 v101, v82, v101, s26
	v_and_or_b32 v100, v101, s27, v100
	v_bfe_u32 v101, v78, 16, 1
	v_add3_u32 v101, v78, v101, s26
	v_bfe_u32 v104, v94, 16, 1
	v_lshrrev_b32_e32 v101, 16, v101
	v_add3_u32 v104, v94, v104, s26
	v_and_or_b32 v101, v104, s27, v101
	global_store_dwordx4 v[102:103], v[98:101], off nt
	v_bfe_u32 v104, v95, 16, 1
	v_add3_u32 v104, v95, v104, s26
	v_bfe_u32 v98, v39, 16, 1
	v_add3_u32 v98, v39, v98, s26
	v_bfe_u32 v99, v35, 16, 1
	v_lshrrev_b32_e32 v98, 16, v98
	v_add3_u32 v99, v35, v99, s26
	v_and_or_b32 v98, v99, s27, v98
	v_bfe_u32 v99, v59, 16, 1
	v_add3_u32 v99, v59, v99, s26
	v_bfe_u32 v100, v31, 16, 1
	v_lshrrev_b32_e32 v99, 16, v99
	v_add3_u32 v100, v31, v100, s26
	v_and_or_b32 v99, v100, s27, v99
	v_bfe_u32 v100, v87, 16, 1
	v_add3_u32 v100, v87, v100, s26
	v_bfe_u32 v101, v83, 16, 1
	v_lshrrev_b32_e32 v100, 16, v100
	v_add3_u32 v101, v83, v101, s26
	v_and_or_b32 v100, v101, s27, v100
	v_bfe_u32 v101, v79, 16, 1
	v_add3_u32 v101, v79, v101, s26
	v_lshrrev_b32_e32 v101, 16, v101
	v_and_or_b32 v101, v104, s27, v101
	v_add_co_u32_e32 v104, vcc, s28, v102
	s_nop 1
	v_addc_co_u32_e32 v105, vcc, 0, v103, vcc
	global_store_dwordx4 v[104:105], v[98:101], off nt
	v_bfe_u32 v104, v96, 16, 1
	v_add3_u32 v104, v96, v104, s26
	v_bfe_u32 v98, v40, 16, 1
	v_add3_u32 v98, v40, v98, s26
	v_bfe_u32 v99, v36, 16, 1
	v_lshrrev_b32_e32 v98, 16, v98
	v_add3_u32 v99, v36, v99, s26
	v_and_or_b32 v98, v99, s27, v98
	v_bfe_u32 v99, v60, 16, 1
	v_add3_u32 v99, v60, v99, s26
	v_bfe_u32 v100, v32, 16, 1
	v_lshrrev_b32_e32 v99, 16, v99
	v_add3_u32 v100, v32, v100, s26
	v_and_or_b32 v99, v100, s27, v99
	v_bfe_u32 v100, v88, 16, 1
	v_add3_u32 v100, v88, v100, s26
	v_bfe_u32 v101, v84, 16, 1
	v_lshrrev_b32_e32 v100, 16, v100
	v_add3_u32 v101, v84, v101, s26
	v_and_or_b32 v100, v101, s27, v100
	v_bfe_u32 v101, v80, 16, 1
	v_add3_u32 v101, v80, v101, s26
	v_lshrrev_b32_e32 v101, 16, v101
	v_and_or_b32 v101, v104, s27, v101
	v_add_co_u32_e32 v104, vcc, s29, v102
	s_nop 1
	v_addc_co_u32_e32 v105, vcc, 0, v103, vcc
	global_store_dwordx4 v[104:105], v[98:101], off nt
	v_bfe_u32 v104, v97, 16, 1
	v_add3_u32 v104, v97, v104, s26
	v_bfe_u32 v98, v41, 16, 1
	v_add3_u32 v98, v41, v98, s26
	v_bfe_u32 v99, v37, 16, 1
	v_lshrrev_b32_e32 v98, 16, v98
	v_add3_u32 v99, v37, v99, s26
	v_and_or_b32 v98, v99, s27, v98
	v_bfe_u32 v99, v61, 16, 1
	v_add3_u32 v99, v61, v99, s26
	v_bfe_u32 v100, v33, 16, 1
	v_lshrrev_b32_e32 v99, 16, v99
	v_add3_u32 v100, v33, v100, s26
	v_and_or_b32 v99, v100, s27, v99
	v_bfe_u32 v100, v89, 16, 1
	v_add3_u32 v100, v89, v100, s26
	v_bfe_u32 v101, v85, 16, 1
	v_lshrrev_b32_e32 v100, 16, v100
	v_add3_u32 v101, v85, v101, s26
	v_and_or_b32 v100, v101, s27, v100
	v_bfe_u32 v101, v81, 16, 1
	v_add3_u32 v101, v81, v101, s26
	v_lshrrev_b32_e32 v101, 16, v101
	v_add_co_u32_e32 v102, vcc, 0x6000, v102
	v_and_or_b32 v101, v104, s27, v101
	s_nop 0
	v_addc_co_u32_e32 v103, vcc, 0, v103, vcc
	global_store_dwordx4 v[102:103], v[98:101], off nt
	s_andn2_b64 vcc, exec, s[18:19]
	s_cbranch_vccz .LBB0_358

.LBB0_358:
	s_lshr_b32 s4, s33, 31
	s_ashr_i32 s5, s33, 4
	s_add_i32 s4, s5, s4
	v_lshl_or_b32 v98, s4, 6, v138
	s_mulk_i32 s4, 0xf400
	s_add_i32 s4, s4, s0
	v_add_u32_e32 v100, s4, v141
	v_ashrrev_i32_e32 v101, 31, v100
	v_lshlrev_b64 v[100:101], 13, v[100:101]
	v_ashrrev_i32_e32 v99, 31, v98
	v_lshl_add_u64 v[100:101], s[8:9], 0, v[100:101]
	v_lshl_add_u64 v[102:103], v[98:99], 1, v[100:101]
	v_bfe_u32 v98, v22, 16, 1
	v_add3_u32 v98, v22, v98, s26
	v_bfe_u32 v99, v18, 16, 1
	v_lshrrev_b32_e32 v98, 16, v98
	v_add3_u32 v99, v18, v99, s26
	v_and_or_b32 v98, v99, s27, v98
	v_bfe_u32 v99, v42, 16, 1
	v_add3_u32 v99, v42, v99, s26
	v_bfe_u32 v100, v14, 16, 1
	v_lshrrev_b32_e32 v99, 16, v99
	v_add3_u32 v100, v14, v100, s26
	v_and_or_b32 v99, v100, s27, v99
	v_bfe_u32 v100, v70, 16, 1
	v_add3_u32 v100, v70, v100, s26
	v_bfe_u32 v101, v66, 16, 1
	v_lshrrev_b32_e32 v100, 16, v100
	v_add3_u32 v101, v66, v101, s26
	v_and_or_b32 v100, v101, s27, v100
	v_bfe_u32 v101, v62, 16, 1
	v_add3_u32 v101, v62, v101, s26
	v_bfe_u32 v104, v90, 16, 1
	v_lshrrev_b32_e32 v101, 16, v101
	v_add3_u32 v104, v90, v104, s26
	v_and_or_b32 v101, v104, s27, v101
	global_store_dwordx4 v[102:103], v[98:101], off nt
	v_bfe_u32 v104, v91, 16, 1
	v_add3_u32 v104, v91, v104, s26
	v_bfe_u32 v98, v23, 16, 1
	v_add3_u32 v98, v23, v98, s26
	v_bfe_u32 v99, v19, 16, 1
	v_lshrrev_b32_e32 v98, 16, v98
	v_add3_u32 v99, v19, v99, s26
	v_and_or_b32 v98, v99, s27, v98
	v_bfe_u32 v99, v43, 16, 1
	v_add3_u32 v99, v43, v99, s26
	v_bfe_u32 v100, v15, 16, 1
	v_lshrrev_b32_e32 v99, 16, v99
	v_add3_u32 v100, v15, v100, s26
	v_and_or_b32 v99, v100, s27, v99
	v_bfe_u32 v100, v71, 16, 1
	v_add3_u32 v100, v71, v100, s26
	v_bfe_u32 v101, v67, 16, 1
	v_lshrrev_b32_e32 v100, 16, v100
	v_add3_u32 v101, v67, v101, s26
	v_and_or_b32 v100, v101, s27, v100
	v_bfe_u32 v101, v63, 16, 1
	v_add3_u32 v101, v63, v101, s26
	v_lshrrev_b32_e32 v101, 16, v101
	v_and_or_b32 v101, v104, s27, v101
	v_add_co_u32_e32 v104, vcc, s28, v102
	s_nop 1
	v_addc_co_u32_e32 v105, vcc, 0, v103, vcc
	global_store_dwordx4 v[104:105], v[98:101], off nt
	v_bfe_u32 v104, v92, 16, 1
	v_add3_u32 v104, v92, v104, s26
	v_bfe_u32 v98, v24, 16, 1
	v_add3_u32 v98, v24, v98, s26
	v_bfe_u32 v99, v20, 16, 1
	v_lshrrev_b32_e32 v98, 16, v98
	v_add3_u32 v99, v20, v99, s26
	v_and_or_b32 v98, v99, s27, v98
	v_bfe_u32 v99, v44, 16, 1
	v_add3_u32 v99, v44, v99, s26
	v_bfe_u32 v100, v16, 16, 1
	v_lshrrev_b32_e32 v99, 16, v99
	v_add3_u32 v100, v16, v100, s26
	v_and_or_b32 v99, v100, s27, v99
	v_bfe_u32 v100, v72, 16, 1
	v_add3_u32 v100, v72, v100, s26
	v_bfe_u32 v101, v68, 16, 1
	v_lshrrev_b32_e32 v100, 16, v100
	v_add3_u32 v101, v68, v101, s26
	v_and_or_b32 v100, v101, s27, v100
	v_bfe_u32 v101, v64, 16, 1
	v_add3_u32 v101, v64, v101, s26
	v_lshrrev_b32_e32 v101, 16, v101
	v_and_or_b32 v101, v104, s27, v101
	v_add_co_u32_e32 v104, vcc, s29, v102
	s_nop 1
	v_addc_co_u32_e32 v105, vcc, 0, v103, vcc
	global_store_dwordx4 v[104:105], v[98:101], off nt
	v_bfe_u32 v104, v93, 16, 1
	v_add3_u32 v104, v93, v104, s26
	v_bfe_u32 v98, v25, 16, 1
	v_add3_u32 v98, v25, v98, s26
	v_bfe_u32 v99, v21, 16, 1
	v_lshrrev_b32_e32 v98, 16, v98
	v_add3_u32 v99, v21, v99, s26
	v_and_or_b32 v98, v99, s27, v98
	v_bfe_u32 v99, v45, 16, 1
	v_add3_u32 v99, v45, v99, s26
	v_bfe_u32 v100, v17, 16, 1
	v_lshrrev_b32_e32 v99, 16, v99
	v_add3_u32 v100, v17, v100, s26
	v_and_or_b32 v99, v100, s27, v99
	v_bfe_u32 v100, v73, 16, 1
	v_add3_u32 v100, v73, v100, s26
	v_bfe_u32 v101, v69, 16, 1
	v_lshrrev_b32_e32 v100, 16, v100
	v_add3_u32 v101, v69, v101, s26
	v_and_or_b32 v100, v101, s27, v100
	v_bfe_u32 v101, v65, 16, 1
	v_add3_u32 v101, v65, v101, s26
	v_lshrrev_b32_e32 v101, 16, v101
	v_add_co_u32_e32 v102, vcc, 0x6000, v102
	v_and_or_b32 v101, v104, s27, v101
	s_nop 0
	v_addc_co_u32_e32 v103, vcc, 0, v103, vcc
	global_store_dwordx4 v[102:103], v[98:101], off nt
	s_andn2_b64 vcc, exec, s[20:21]
	s_cbranch_vccnz .LBB0_251
.LBB0_359:
	s_lshr_b32 s4, s34, 31
	s_ashr_i32 s5, s34, 4
	s_add_i32 s4, s5, s4
	v_lshl_or_b32 v98, s4, 6, v138
	s_mulk_i32 s4, 0xf400
	s_add_i32 s4, s4, s0
	v_add_u32_e32 v100, s4, v142
	v_ashrrev_i32_e32 v101, 31, v100
	v_lshlrev_b64 v[100:101], 13, v[100:101]
	v_ashrrev_i32_e32 v99, 31, v98
	v_lshl_add_u64 v[100:101], s[8:9], 0, v[100:101]
	v_lshl_add_u64 v[102:103], v[98:99], 1, v[100:101]
	v_bfe_u32 v98, v10, 16, 1
	v_add3_u32 v98, v10, v98, s26
	v_bfe_u32 v99, v6, 16, 1
	v_lshrrev_b32_e32 v98, 16, v98
	v_add3_u32 v99, v6, v99, s26
	v_and_or_b32 v98, v99, s27, v98
	v_bfe_u32 v99, v26, 16, 1
	v_add3_u32 v99, v26, v99, s26
	v_bfe_u32 v100, v2, 16, 1
	v_lshrrev_b32_e32 v99, 16, v99
	v_add3_u32 v100, v2, v100, s26
	v_and_or_b32 v99, v100, s27, v99
	v_bfe_u32 v100, v54, 16, 1
	v_add3_u32 v100, v54, v100, s26
	v_bfe_u32 v101, v50, 16, 1
	v_lshrrev_b32_e32 v100, 16, v100
	v_add3_u32 v101, v50, v101, s26
	v_and_or_b32 v100, v101, s27, v100
	v_bfe_u32 v101, v46, 16, 1
	v_add3_u32 v101, v46, v101, s26
	v_bfe_u32 v104, v74, 16, 1
	v_lshrrev_b32_e32 v101, 16, v101
	v_add3_u32 v104, v74, v104, s26
	v_and_or_b32 v101, v104, s27, v101
	global_store_dwordx4 v[102:103], v[98:101], off nt
	v_bfe_u32 v104, v75, 16, 1
	v_add3_u32 v104, v75, v104, s26
	v_bfe_u32 v98, v11, 16, 1
	v_add3_u32 v98, v11, v98, s26
	v_bfe_u32 v99, v7, 16, 1
	v_lshrrev_b32_e32 v98, 16, v98
	v_add3_u32 v99, v7, v99, s26
	v_and_or_b32 v98, v99, s27, v98
	v_bfe_u32 v99, v27, 16, 1
	v_add3_u32 v99, v27, v99, s26
	v_bfe_u32 v100, v3, 16, 1
	v_lshrrev_b32_e32 v99, 16, v99
	v_add3_u32 v100, v3, v100, s26
	v_and_or_b32 v99, v100, s27, v99
	v_bfe_u32 v100, v55, 16, 1
	v_add3_u32 v100, v55, v100, s26
	v_bfe_u32 v101, v51, 16, 1
	v_lshrrev_b32_e32 v100, 16, v100
	v_add3_u32 v101, v51, v101, s26
	v_and_or_b32 v100, v101, s27, v100
	v_bfe_u32 v101, v47, 16, 1
	v_add3_u32 v101, v47, v101, s26
	v_lshrrev_b32_e32 v101, 16, v101
	v_and_or_b32 v101, v104, s27, v101
	v_add_co_u32_e32 v104, vcc, s28, v102
	s_nop 1
	v_addc_co_u32_e32 v105, vcc, 0, v103, vcc
	global_store_dwordx4 v[104:105], v[98:101], off nt
	v_bfe_u32 v104, v76, 16, 1
	v_add3_u32 v104, v76, v104, s26
	v_bfe_u32 v98, v12, 16, 1
	v_add3_u32 v98, v12, v98, s26
	v_bfe_u32 v99, v8, 16, 1
	v_lshrrev_b32_e32 v98, 16, v98
	v_add3_u32 v99, v8, v99, s26
	v_and_or_b32 v98, v99, s27, v98
	v_bfe_u32 v99, v28, 16, 1
	v_add3_u32 v99, v28, v99, s26
	v_bfe_u32 v100, v4, 16, 1
	v_lshrrev_b32_e32 v99, 16, v99
	v_add3_u32 v100, v4, v100, s26
	v_and_or_b32 v99, v100, s27, v99
	v_bfe_u32 v100, v56, 16, 1
	v_add3_u32 v100, v56, v100, s26
	v_bfe_u32 v101, v52, 16, 1
	v_lshrrev_b32_e32 v100, 16, v100
	v_add3_u32 v101, v52, v101, s26
	v_and_or_b32 v100, v101, s27, v100
	v_bfe_u32 v101, v48, 16, 1
	v_add3_u32 v101, v48, v101, s26
	v_lshrrev_b32_e32 v101, 16, v101
	v_and_or_b32 v101, v104, s27, v101
	v_add_co_u32_e32 v104, vcc, s29, v102
	s_nop 1
	v_addc_co_u32_e32 v105, vcc, 0, v103, vcc
	global_store_dwordx4 v[104:105], v[98:101], off nt
	v_bfe_u32 v104, v77, 16, 1
	v_add3_u32 v104, v77, v104, s26
	v_bfe_u32 v98, v13, 16, 1
	v_add3_u32 v98, v13, v98, s26
	v_bfe_u32 v99, v9, 16, 1
	v_lshrrev_b32_e32 v98, 16, v98
	v_add3_u32 v99, v9, v99, s26
	v_and_or_b32 v98, v99, s27, v98
	v_bfe_u32 v99, v29, 16, 1
	v_add3_u32 v99, v29, v99, s26
	v_bfe_u32 v100, v5, 16, 1
	v_lshrrev_b32_e32 v99, 16, v99
	v_add3_u32 v100, v5, v100, s26
	v_and_or_b32 v99, v100, s27, v99
	v_bfe_u32 v100, v57, 16, 1
	v_add3_u32 v100, v57, v100, s26
	v_bfe_u32 v101, v53, 16, 1
	v_lshrrev_b32_e32 v100, 16, v100
	v_add3_u32 v101, v53, v101, s26
	v_and_or_b32 v100, v101, s27, v100
	v_bfe_u32 v101, v49, 16, 1
	v_add3_u32 v101, v49, v101, s26
	v_lshrrev_b32_e32 v101, 16, v101
	v_add_co_u32_e32 v102, vcc, 0x6000, v102
	v_and_or_b32 v101, v104, s27, v101
	s_nop 0
	v_addc_co_u32_e32 v103, vcc, 0, v103, vcc
	global_store_dwordx4 v[102:103], v[98:101], off nt
	s_branch .LBB0_251

.LBB0_362:
	s_mul_i32 s4, s20, 0xfffff400
	s_add_i32 s4, s4, s0
	v_add_u32_e32 v3, s4, v143
	v_mov_b64_e32 v[102:103], s[16:17]
	v_mad_i64_i32 v[102:103], s[4:5], v3, s29, v[102:103]
	v_bfe_u32 v3, v6, 16, 1
	v_lshl_add_u64 v[4:5], v[4:5], 1, v[102:103]
	v_add3_u32 v3, v6, v3, s31
	v_bfe_u32 v102, v14, 16, 1
	v_lshrrev_b32_e32 v3, 16, v3
	v_add3_u32 v102, v14, v102, s31
	v_and_or_b32 v102, v102, s33, v3
	v_bfe_u32 v3, v42, 16, 1
	v_add3_u32 v3, v42, v3, s31
	v_bfe_u32 v103, v10, 16, 1
	v_lshrrev_b32_e32 v3, 16, v3
	v_add3_u32 v103, v10, v103, s31
	v_and_or_b32 v103, v103, s33, v3
	v_bfe_u32 v3, v54, 16, 1
	v_add3_u32 v3, v54, v3, s31
	v_bfe_u32 v104, v58, 16, 1
	v_lshrrev_b32_e32 v3, 16, v3
	v_add3_u32 v104, v58, v104, s31
	v_and_or_b32 v104, v104, s33, v3
	v_bfe_u32 v3, v78, 16, 1
	v_add3_u32 v3, v78, v3, s31
	v_bfe_u32 v105, v82, 16, 1
	v_lshrrev_b32_e32 v3, 16, v3
	v_add3_u32 v105, v82, v105, s31
	v_and_or_b32 v105, v105, s33, v3
	v_bfe_u32 v3, v7, 16, 1
	global_store_dwordx4 v[4:5], v[102:105], off nt
	v_add3_u32 v3, v7, v3, s31
	v_lshrrev_b32_e32 v3, 16, v3
	v_bfe_u32 v102, v15, 16, 1
	v_add3_u32 v102, v15, v102, s31
	v_and_or_b32 v102, v102, s33, v3
	v_bfe_u32 v3, v43, 16, 1
	v_add3_u32 v3, v43, v3, s31
	v_bfe_u32 v103, v11, 16, 1
	v_lshrrev_b32_e32 v3, 16, v3
	v_add3_u32 v103, v11, v103, s31
	v_and_or_b32 v103, v103, s33, v3
	v_bfe_u32 v3, v55, 16, 1
	v_add3_u32 v3, v55, v3, s31
	v_bfe_u32 v104, v59, 16, 1
	v_lshrrev_b32_e32 v3, 16, v3
	v_add3_u32 v104, v59, v104, s31
	v_and_or_b32 v104, v104, s33, v3
	v_bfe_u32 v3, v79, 16, 1
	v_add3_u32 v3, v79, v3, s31
	v_bfe_u32 v105, v83, 16, 1
	v_lshrrev_b32_e32 v3, 16, v3
	v_add3_u32 v105, v83, v105, s31
	v_and_or_b32 v105, v105, s33, v3
	v_bfe_u32 v3, v8, 16, 1
	global_store_dwordx4 v[4:5], v[102:105], off offset:3072 nt
	v_add3_u32 v3, v8, v3, s31
	v_lshrrev_b32_e32 v3, 16, v3
	v_bfe_u32 v102, v16, 16, 1
	v_add3_u32 v102, v16, v102, s31
	v_and_or_b32 v102, v102, s33, v3
	v_bfe_u32 v3, v44, 16, 1
	v_add3_u32 v3, v44, v3, s31
	v_bfe_u32 v103, v12, 16, 1
	v_lshrrev_b32_e32 v3, 16, v3
	v_add3_u32 v103, v12, v103, s31
	v_and_or_b32 v103, v103, s33, v3
	v_bfe_u32 v3, v56, 16, 1
	v_add3_u32 v3, v56, v3, s31
	v_bfe_u32 v104, v60, 16, 1
	v_lshrrev_b32_e32 v3, 16, v3
	v_add3_u32 v104, v60, v104, s31
	v_and_or_b32 v104, v104, s33, v3
	v_bfe_u32 v3, v80, 16, 1
	v_add3_u32 v3, v80, v3, s31
	v_bfe_u32 v105, v84, 16, 1
	v_lshrrev_b32_e32 v3, 16, v3
	v_add3_u32 v105, v84, v105, s31
	v_add_co_u32_e32 v106, vcc, s34, v4
	v_and_or_b32 v105, v105, s33, v3
	s_nop 0
	v_addc_co_u32_e32 v107, vcc, 0, v5, vcc
	v_bfe_u32 v3, v9, 16, 1
	global_store_dwordx4 v[106:107], v[102:105], off offset:2048 nt
	v_add3_u32 v3, v9, v3, s31
	v_lshrrev_b32_e32 v3, 16, v3
	v_bfe_u32 v102, v17, 16, 1
	v_add3_u32 v102, v17, v102, s31
	v_and_or_b32 v102, v102, s33, v3
	v_bfe_u32 v3, v45, 16, 1
	v_add3_u32 v3, v45, v3, s31
	v_bfe_u32 v103, v13, 16, 1
	v_lshrrev_b32_e32 v3, 16, v3
	v_add3_u32 v103, v13, v103, s31
	v_and_or_b32 v103, v103, s33, v3
	v_bfe_u32 v3, v57, 16, 1
	v_add3_u32 v3, v57, v3, s31
	v_bfe_u32 v104, v61, 16, 1
	v_lshrrev_b32_e32 v3, 16, v3
	v_add3_u32 v104, v61, v104, s31
	v_and_or_b32 v104, v104, s33, v3
	v_bfe_u32 v3, v81, 16, 1
	v_add3_u32 v3, v81, v3, s31
	v_bfe_u32 v105, v85, 16, 1
	v_lshrrev_b32_e32 v3, 16, v3
	v_add3_u32 v105, v85, v105, s31
	v_add_co_u32_e32 v4, vcc, 0x2000, v4
	v_and_or_b32 v105, v105, s33, v3
	s_nop 0
	v_addc_co_u32_e32 v5, vcc, 0, v5, vcc
	global_store_dwordx4 v[4:5], v[102:105], off offset:1024 nt

.LBB0_404:
	s_waitcnt vmcnt(1)
	v_bfe_u32 v3, v106, 16, 1
	v_mov_b64_e32 v[4:5], s[16:17]
	v_add3_u32 v3, v106, v3, s31
	s_waitcnt vmcnt(0)
	v_bfe_u32 v106, v102, 16, 1
	v_mad_i64_i32 v[4:5], s[26:27], v145, s29, v[4:5]
	v_lshrrev_b32_e32 v3, 16, v3
	v_add3_u32 v102, v102, v106, s31
	v_lshl_add_u64 v[4:5], v[136:137], 1, v[4:5]
	v_and_or_b32 v136, v102, s33, v3
	v_bfe_u32 v3, v114, 16, 1
	v_add3_u32 v3, v114, v3, s31
	v_bfe_u32 v102, v110, 16, 1
	v_lshrrev_b32_e32 v3, 16, v3
	v_add3_u32 v102, v110, v102, s31
	v_and_or_b32 v137, v102, s33, v3
	v_bfe_u32 v3, v122, 16, 1
	v_add3_u32 v3, v122, v3, s31
	v_bfe_u32 v102, v118, 16, 1
	v_lshrrev_b32_e32 v3, 16, v3
	v_add3_u32 v102, v118, v102, s31
	v_and_or_b32 v138, v102, s33, v3
	v_bfe_u32 v3, v130, 16, 1
	v_add3_u32 v3, v130, v3, s31
	v_bfe_u32 v102, v126, 16, 1
	v_lshrrev_b32_e32 v3, 16, v3
	v_add3_u32 v102, v126, v102, s31
	v_and_or_b32 v139, v102, s33, v3
	v_bfe_u32 v3, v107, 16, 1
	v_add3_u32 v3, v107, v3, s31
	v_bfe_u32 v102, v103, 16, 1
	v_lshrrev_b32_e32 v3, 16, v3
	v_add3_u32 v102, v103, v102, s31
	global_store_dwordx4 v[4:5], v[136:139], off nt
	s_nop 1
	v_and_or_b32 v136, v102, s33, v3
	v_bfe_u32 v3, v115, 16, 1
	v_add3_u32 v3, v115, v3, s31
	v_bfe_u32 v102, v111, 16, 1
	v_lshrrev_b32_e32 v3, 16, v3
	v_add3_u32 v102, v111, v102, s31
	v_and_or_b32 v137, v102, s33, v3
	v_bfe_u32 v3, v123, 16, 1
	v_add3_u32 v3, v123, v3, s31
	v_bfe_u32 v102, v119, 16, 1
	v_lshrrev_b32_e32 v3, 16, v3
	v_add3_u32 v102, v119, v102, s31
	v_and_or_b32 v138, v102, s33, v3
	v_bfe_u32 v3, v131, 16, 1
	v_add3_u32 v3, v131, v3, s31
	v_bfe_u32 v102, v127, 16, 1
	v_lshrrev_b32_e32 v3, 16, v3
	v_add3_u32 v102, v127, v102, s31
	v_and_or_b32 v139, v102, s33, v3
	v_bfe_u32 v3, v108, 16, 1
	v_add3_u32 v3, v108, v3, s31
	v_bfe_u32 v102, v104, 16, 1
	v_lshrrev_b32_e32 v3, 16, v3
	v_add3_u32 v102, v104, v102, s31
	global_store_dwordx4 v[4:5], v[136:139], off offset:3072 nt
	v_bfe_u32 v104, v121, 16, 1
	v_add3_u32 v104, v121, v104, s31
	v_and_or_b32 v136, v102, s33, v3
	v_bfe_u32 v3, v116, 16, 1
	v_add3_u32 v3, v116, v3, s31
	v_bfe_u32 v102, v112, 16, 1
	v_lshrrev_b32_e32 v3, 16, v3
	v_add3_u32 v102, v112, v102, s31
	v_and_or_b32 v137, v102, s33, v3
	v_bfe_u32 v3, v124, 16, 1
	v_add3_u32 v3, v124, v3, s31
	v_bfe_u32 v102, v120, 16, 1
	v_lshrrev_b32_e32 v3, 16, v3
	v_add3_u32 v102, v120, v102, s31
	v_and_or_b32 v138, v102, s33, v3
	v_bfe_u32 v3, v132, 16, 1
	v_add3_u32 v3, v132, v3, s31
	v_bfe_u32 v102, v128, 16, 1
	v_lshrrev_b32_e32 v3, 16, v3
	v_add3_u32 v102, v128, v102, s31
	v_and_or_b32 v139, v102, s33, v3
	v_add_co_u32_e32 v102, vcc, s34, v4
	v_bfe_u32 v3, v109, 16, 1
	s_nop 0
	v_addc_co_u32_e32 v103, vcc, 0, v5, vcc
	global_store_dwordx4 v[102:103], v[136:139], off offset:2048 nt
	v_add3_u32 v3, v109, v3, s31
	v_bfe_u32 v102, v105, 16, 1
	v_lshrrev_b32_e32 v3, 16, v3
	v_add3_u32 v102, v105, v102, s31
	v_and_or_b32 v102, v102, s33, v3
	v_bfe_u32 v3, v117, 16, 1
	v_add3_u32 v3, v117, v3, s31
	v_bfe_u32 v103, v113, 16, 1
	v_lshrrev_b32_e32 v3, 16, v3
	v_add3_u32 v103, v113, v103, s31
	v_and_or_b32 v103, v103, s33, v3
	v_bfe_u32 v3, v125, 16, 1
	v_add3_u32 v3, v125, v3, s31
	v_lshrrev_b32_e32 v3, 16, v3
	v_and_or_b32 v104, v104, s33, v3
	v_bfe_u32 v3, v133, 16, 1
	v_add3_u32 v3, v133, v3, s31
	v_bfe_u32 v105, v129, 16, 1
	v_add_co_u32_e32 v4, vcc, 0x2000, v4
	v_lshrrev_b32_e32 v3, 16, v3
	v_add3_u32 v105, v129, v105, s31
	v_addc_co_u32_e32 v5, vcc, 0, v5, vcc
	v_and_or_b32 v105, v105, s33, v3
	s_andn2_b64 vcc, exec, s[24:25]
	global_store_dwordx4 v[4:5], v[102:105], off offset:1024 nt
	s_cbranch_vccnz .LBB0_409
	s_lshr_b32 s24, s39, 31
	s_ashr_i32 s25, s39, 4
	s_add_i32 s24, s25, s24
	v_lshl_or_b32 v4, s24, 6, v140
	s_and_b64 vcc, exec, s[4:5]
	v_ashrrev_i32_e32 v5, 31, v4
	s_cbranch_vccnz .LBB0_407
	v_lshl_add_u64 v[106:107], v[4:5], 2, s[8:9]
	global_load_dwordx4 v[102:105], v[106:107], off
	s_nop 0
	global_load_dwordx4 v[106:109], v[106:107], off offset:16
	s_waitcnt vmcnt(1)
	v_pk_mul_f32 v[32:33], v[102:103], v[32:33] op_sel_hi:[0,1]
	v_pk_mul_f32 v[30:31], v[102:103], v[30:31] op_sel_hi:[0,1]
	v_pk_mul_f32 v[40:41], v[102:103], v[40:41] op_sel:[1,0]
	v_pk_mul_f32 v[38:39], v[102:103], v[38:39] op_sel:[1,0]
	v_pk_mul_f32 v[52:53], v[104:105], v[52:53] op_sel_hi:[0,1]
	v_pk_mul_f32 v[50:51], v[104:105], v[50:51] op_sel_hi:[0,1]
	v_mov_b32_e32 v102, v105
	s_waitcnt vmcnt(0)
	v_mov_b32_e32 v104, v109
	v_pk_mul_f32 v[72:73], v[106:107], v[72:73] op_sel_hi:[0,1]
	v_pk_mul_f32 v[70:71], v[106:107], v[70:71] op_sel_hi:[0,1]
	v_pk_mul_f32 v[76:77], v[106:107], v[76:77] op_sel:[1,0]
	v_pk_mul_f32 v[74:75], v[106:107], v[74:75] op_sel:[1,0]
	v_pk_mul_f32 v[96:97], v[108:109], v[96:97] op_sel_hi:[0,1]
	v_pk_mul_f32 v[94:95], v[108:109], v[94:95] op_sel_hi:[0,1]
	v_pk_mul_f32 v[36:37], v[102:103], v[36:37] op_sel_hi:[0,1]
	v_pk_mul_f32 v[34:35], v[102:103], v[34:35] op_sel_hi:[0,1]
	v_pk_mul_f32 v[100:101], v[104:105], v[100:101] op_sel_hi:[0,1]
	v_pk_mul_f32 v[98:99], v[104:105], v[98:99] op_sel_hi:[0,1]
.LBB0_407:
	s_mulk_i32 s24, 0xf400
	s_add_i32 s24, s24, s0
	v_add_u32_e32 v3, s24, v144
	v_mov_b64_e32 v[102:103], s[16:17]
	v_mad_i64_i32 v[102:103], s[24:25], v3, s29, v[102:103]
	v_bfe_u32 v3, v30, 16, 1
	v_lshl_add_u64 v[4:5], v[4:5], 1, v[102:103]
	v_add3_u32 v3, v30, v3, s31
	v_bfe_u32 v102, v38, 16, 1
	v_lshrrev_b32_e32 v3, 16, v3
	v_add3_u32 v102, v38, v102, s31
	v_and_or_b32 v102, v102, s33, v3
	v_bfe_u32 v3, v50, 16, 1
	v_add3_u32 v3, v50, v3, s31
	v_bfe_u32 v103, v34, 16, 1
	v_lshrrev_b32_e32 v3, 16, v3
	v_add3_u32 v103, v34, v103, s31
	v_and_or_b32 v103, v103, s33, v3
	v_bfe_u32 v3, v70, 16, 1
	v_add3_u32 v3, v70, v3, s31
	v_bfe_u32 v104, v74, 16, 1
	v_lshrrev_b32_e32 v3, 16, v3
	v_add3_u32 v104, v74, v104, s31
	v_and_or_b32 v104, v104, s33, v3
	v_bfe_u32 v3, v94, 16, 1
	v_add3_u32 v3, v94, v3, s31
	v_bfe_u32 v105, v98, 16, 1
	v_lshrrev_b32_e32 v3, 16, v3
	v_add3_u32 v105, v98, v105, s31
	v_and_or_b32 v105, v105, s33, v3
	v_bfe_u32 v3, v31, 16, 1
	global_store_dwordx4 v[4:5], v[102:105], off nt
	v_add3_u32 v3, v31, v3, s31
	v_lshrrev_b32_e32 v3, 16, v3
	v_bfe_u32 v102, v39, 16, 1
	v_add3_u32 v102, v39, v102, s31
	v_and_or_b32 v102, v102, s33, v3
	v_bfe_u32 v3, v51, 16, 1
	v_add3_u32 v3, v51, v3, s31
	v_bfe_u32 v103, v35, 16, 1
	v_lshrrev_b32_e32 v3, 16, v3
	v_add3_u32 v103, v35, v103, s31
	v_and_or_b32 v103, v103, s33, v3
	v_bfe_u32 v3, v71, 16, 1
	v_add3_u32 v3, v71, v3, s31
	v_bfe_u32 v104, v75, 16, 1
	v_lshrrev_b32_e32 v3, 16, v3
	v_add3_u32 v104, v75, v104, s31
	v_and_or_b32 v104, v104, s33, v3
	v_bfe_u32 v3, v95, 16, 1
	v_add3_u32 v3, v95, v3, s31
	v_bfe_u32 v105, v99, 16, 1
	v_lshrrev_b32_e32 v3, 16, v3
	v_add3_u32 v105, v99, v105, s31
	v_and_or_b32 v105, v105, s33, v3
	v_bfe_u32 v3, v32, 16, 1
	global_store_dwordx4 v[4:5], v[102:105], off offset:3072 nt
	v_add3_u32 v3, v32, v3, s31
	v_lshrrev_b32_e32 v3, 16, v3
	v_bfe_u32 v102, v40, 16, 1
	v_add3_u32 v102, v40, v102, s31
	v_and_or_b32 v102, v102, s33, v3
	v_bfe_u32 v3, v52, 16, 1
	v_add3_u32 v3, v52, v3, s31
	v_bfe_u32 v103, v36, 16, 1
	v_lshrrev_b32_e32 v3, 16, v3
	v_add3_u32 v103, v36, v103, s31
	v_and_or_b32 v103, v103, s33, v3
	v_bfe_u32 v3, v72, 16, 1
	v_add3_u32 v3, v72, v3, s31
	v_bfe_u32 v104, v76, 16, 1
	v_lshrrev_b32_e32 v3, 16, v3
	v_add3_u32 v104, v76, v104, s31
	v_and_or_b32 v104, v104, s33, v3
	v_bfe_u32 v3, v96, 16, 1
	v_add3_u32 v3, v96, v3, s31
	v_bfe_u32 v105, v100, 16, 1
	v_lshrrev_b32_e32 v3, 16, v3
	v_add3_u32 v105, v100, v105, s31
	v_add_co_u32_e32 v106, vcc, s34, v4
	v_and_or_b32 v105, v105, s33, v3
	s_nop 0
	v_addc_co_u32_e32 v107, vcc, 0, v5, vcc
	v_bfe_u32 v3, v33, 16, 1
	global_store_dwordx4 v[106:107], v[102:105], off offset:2048 nt
	v_add3_u32 v3, v33, v3, s31
	v_lshrrev_b32_e32 v3, 16, v3
	v_bfe_u32 v102, v41, 16, 1
	v_add3_u32 v102, v41, v102, s31
	v_and_or_b32 v102, v102, s33, v3
	v_bfe_u32 v3, v53, 16, 1
	v_add3_u32 v3, v53, v3, s31
	v_bfe_u32 v103, v37, 16, 1
	v_lshrrev_b32_e32 v3, 16, v3
	v_add3_u32 v103, v37, v103, s31
	v_and_or_b32 v103, v103, s33, v3
	v_bfe_u32 v3, v73, 16, 1
	v_add3_u32 v3, v73, v3, s31
	v_bfe_u32 v104, v77, 16, 1
	v_lshrrev_b32_e32 v3, 16, v3
	v_add3_u32 v104, v77, v104, s31
	v_and_or_b32 v104, v104, s33, v3
	v_bfe_u32 v3, v97, 16, 1
	v_add3_u32 v3, v97, v3, s31
	v_bfe_u32 v105, v101, 16, 1
	v_lshrrev_b32_e32 v3, 16, v3
	v_add3_u32 v105, v101, v105, s31
	v_add_co_u32_e32 v4, vcc, 0x2000, v4
	v_and_or_b32 v105, v105, s33, v3
	s_nop 0
	v_addc_co_u32_e32 v5, vcc, 0, v5, vcc
	global_store_dwordx4 v[4:5], v[102:105], off offset:1024 nt
	s_andn2_b64 vcc, exec, s[22:23]
	s_cbranch_vccz .LBB0_410

.LBB0_412:
	s_mulk_i32 s22, 0xf400
	s_add_i32 s22, s22, s0
	v_add_u32_e32 v3, s22, v142
	v_mov_b64_e32 v[102:103], s[16:17]
	v_mad_i64_i32 v[102:103], s[22:23], v3, s29, v[102:103]
	v_bfe_u32 v3, v18, 16, 1
	v_lshl_add_u64 v[4:5], v[4:5], 1, v[102:103]
	v_add3_u32 v3, v18, v3, s31
	v_bfe_u32 v102, v26, 16, 1
	v_lshrrev_b32_e32 v3, 16, v3
	v_add3_u32 v102, v26, v102, s31
	v_and_or_b32 v102, v102, s33, v3
	v_bfe_u32 v3, v46, 16, 1
	v_add3_u32 v3, v46, v3, s31
	v_bfe_u32 v103, v22, 16, 1
	v_lshrrev_b32_e32 v3, 16, v3
	v_add3_u32 v103, v22, v103, s31
	v_and_or_b32 v103, v103, s33, v3
	v_bfe_u32 v3, v62, 16, 1
	v_add3_u32 v3, v62, v3, s31
	v_bfe_u32 v104, v66, 16, 1
	v_lshrrev_b32_e32 v3, 16, v3
	v_add3_u32 v104, v66, v104, s31
	v_and_or_b32 v104, v104, s33, v3
	v_bfe_u32 v3, v86, 16, 1
	v_add3_u32 v3, v86, v3, s31
	v_bfe_u32 v105, v90, 16, 1
	v_lshrrev_b32_e32 v3, 16, v3
	v_add3_u32 v105, v90, v105, s31
	v_and_or_b32 v105, v105, s33, v3
	v_bfe_u32 v3, v19, 16, 1
	global_store_dwordx4 v[4:5], v[102:105], off nt
	v_add3_u32 v3, v19, v3, s31
	v_lshrrev_b32_e32 v3, 16, v3
	v_bfe_u32 v102, v27, 16, 1
	v_add3_u32 v102, v27, v102, s31
	v_and_or_b32 v102, v102, s33, v3
	v_bfe_u32 v3, v47, 16, 1
	v_add3_u32 v3, v47, v3, s31
	v_bfe_u32 v103, v23, 16, 1
	v_lshrrev_b32_e32 v3, 16, v3
	v_add3_u32 v103, v23, v103, s31
	v_and_or_b32 v103, v103, s33, v3
	v_bfe_u32 v3, v63, 16, 1
	v_add3_u32 v3, v63, v3, s31
	v_bfe_u32 v104, v67, 16, 1
	v_lshrrev_b32_e32 v3, 16, v3
	v_add3_u32 v104, v67, v104, s31
	v_and_or_b32 v104, v104, s33, v3
	v_bfe_u32 v3, v87, 16, 1
	v_add3_u32 v3, v87, v3, s31
	v_bfe_u32 v105, v91, 16, 1
	v_lshrrev_b32_e32 v3, 16, v3
	v_add3_u32 v105, v91, v105, s31
	v_and_or_b32 v105, v105, s33, v3
	v_bfe_u32 v3, v20, 16, 1
	global_store_dwordx4 v[4:5], v[102:105], off offset:3072 nt
	v_add3_u32 v3, v20, v3, s31
	v_lshrrev_b32_e32 v3, 16, v3
	v_bfe_u32 v102, v28, 16, 1
	v_add3_u32 v102, v28, v102, s31
	v_and_or_b32 v102, v102, s33, v3
	v_bfe_u32 v3, v48, 16, 1
	v_add3_u32 v3, v48, v3, s31
	v_bfe_u32 v103, v24, 16, 1
	v_lshrrev_b32_e32 v3, 16, v3
	v_add3_u32 v103, v24, v103, s31
	v_and_or_b32 v103, v103, s33, v3
	v_bfe_u32 v3, v64, 16, 1
	v_add3_u32 v3, v64, v3, s31
	v_bfe_u32 v104, v68, 16, 1
	v_lshrrev_b32_e32 v3, 16, v3
	v_add3_u32 v104, v68, v104, s31
	v_and_or_b32 v104, v104, s33, v3
	v_bfe_u32 v3, v88, 16, 1
	v_add3_u32 v3, v88, v3, s31
	v_bfe_u32 v105, v92, 16, 1
	v_lshrrev_b32_e32 v3, 16, v3
	v_add3_u32 v105, v92, v105, s31
	v_add_co_u32_e32 v106, vcc, s34, v4
	v_and_or_b32 v105, v105, s33, v3
	s_nop 0
	v_addc_co_u32_e32 v107, vcc, 0, v5, vcc
	v_bfe_u32 v3, v21, 16, 1
	global_store_dwordx4 v[106:107], v[102:105], off offset:2048 nt
	v_add3_u32 v3, v21, v3, s31
	v_lshrrev_b32_e32 v3, 16, v3
	v_bfe_u32 v102, v29, 16, 1
	v_add3_u32 v102, v29, v102, s31
	v_and_or_b32 v102, v102, s33, v3
	v_bfe_u32 v3, v49, 16, 1
	v_add3_u32 v3, v49, v3, s31
	v_bfe_u32 v103, v25, 16, 1
	v_lshrrev_b32_e32 v3, 16, v3
	v_add3_u32 v103, v25, v103, s31
	v_and_or_b32 v103, v103, s33, v3
	v_bfe_u32 v3, v65, 16, 1
	v_add3_u32 v3, v65, v3, s31
	v_bfe_u32 v104, v69, 16, 1
	v_lshrrev_b32_e32 v3, 16, v3
	v_add3_u32 v104, v69, v104, s31
	v_and_or_b32 v104, v104, s33, v3
	v_bfe_u32 v3, v89, 16, 1
	v_add3_u32 v3, v89, v3, s31
	v_bfe_u32 v105, v93, 16, 1
	v_lshrrev_b32_e32 v3, 16, v3
	v_add3_u32 v105, v93, v105, s31
	v_add_co_u32_e32 v4, vcc, 0x2000, v4
	v_and_or_b32 v105, v105, s33, v3
	s_nop 0
	v_addc_co_u32_e32 v5, vcc, 0, v5, vcc
	global_store_dwordx4 v[4:5], v[102:105], off offset:1024 nt
	s_andn2_b64 vcc, exec, s[20:21]
	s_cbranch_vccnz .LBB0_363

.LBB0_417:
	s_lshl_b32 s4, s22, 12
	v_subrev_u32_e32 v102, s4, v149
	v_ashrrev_i32_e32 v103, 31, v102
	v_lshlrev_b64 v[102:103], 10, v[102:103]
	v_lshl_add_u64 v[102:103], s[18:19], 0, v[102:103]
	v_bfe_u32 v3, v6, 16, 1
	v_lshl_add_u64 v[4:5], v[4:5], 1, v[102:103]
	v_add3_u32 v3, v6, v3, s15
	v_bfe_u32 v102, v14, 16, 1
	v_lshrrev_b32_e32 v3, 16, v3
	v_add3_u32 v102, v14, v102, s15
	v_and_or_b32 v102, v102, s30, v3
	v_bfe_u32 v3, v42, 16, 1
	v_add3_u32 v3, v42, v3, s15
	v_bfe_u32 v103, v10, 16, 1
	v_lshrrev_b32_e32 v3, 16, v3
	v_add3_u32 v103, v10, v103, s15
	v_and_or_b32 v103, v103, s30, v3
	v_bfe_u32 v3, v54, 16, 1
	v_add3_u32 v3, v54, v3, s15
	v_bfe_u32 v104, v58, 16, 1
	v_lshrrev_b32_e32 v3, 16, v3
	v_add3_u32 v104, v58, v104, s15
	v_and_or_b32 v104, v104, s30, v3
	v_bfe_u32 v3, v78, 16, 1
	v_add3_u32 v3, v78, v3, s15
	v_bfe_u32 v105, v82, 16, 1
	v_lshrrev_b32_e32 v3, 16, v3
	v_add3_u32 v105, v82, v105, s15
	v_and_or_b32 v105, v105, s30, v3
	v_bfe_u32 v3, v7, 16, 1
	global_store_dwordx4 v[4:5], v[102:105], off nt
	v_add3_u32 v3, v7, v3, s15
	v_lshrrev_b32_e32 v3, 16, v3
	v_bfe_u32 v102, v15, 16, 1
	v_add3_u32 v102, v15, v102, s15
	v_and_or_b32 v102, v102, s30, v3
	v_bfe_u32 v3, v43, 16, 1
	v_add3_u32 v3, v43, v3, s15
	v_bfe_u32 v103, v11, 16, 1
	v_lshrrev_b32_e32 v3, 16, v3
	v_add3_u32 v103, v11, v103, s15
	v_and_or_b32 v103, v103, s30, v3
	v_bfe_u32 v3, v55, 16, 1
	v_add3_u32 v3, v55, v3, s15
	v_bfe_u32 v104, v59, 16, 1
	v_lshrrev_b32_e32 v3, 16, v3
	v_add3_u32 v104, v59, v104, s15
	v_and_or_b32 v104, v104, s30, v3
	v_bfe_u32 v3, v79, 16, 1
	v_add3_u32 v3, v79, v3, s15
	v_bfe_u32 v105, v83, 16, 1
	v_lshrrev_b32_e32 v3, 16, v3
	v_add3_u32 v105, v83, v105, s15
	v_and_or_b32 v105, v105, s30, v3
	v_bfe_u32 v3, v8, 16, 1
	global_store_dwordx4 v[4:5], v[102:105], off offset:1024 nt
	v_add3_u32 v3, v8, v3, s15
	v_lshrrev_b32_e32 v3, 16, v3
	v_bfe_u32 v102, v16, 16, 1
	v_add3_u32 v102, v16, v102, s15
	v_and_or_b32 v102, v102, s30, v3
	v_bfe_u32 v3, v44, 16, 1
	v_add3_u32 v3, v44, v3, s15
	v_bfe_u32 v103, v12, 16, 1
	v_lshrrev_b32_e32 v3, 16, v3
	v_add3_u32 v103, v12, v103, s15
	v_and_or_b32 v103, v103, s30, v3
	v_bfe_u32 v3, v56, 16, 1
	v_add3_u32 v3, v56, v3, s15
	v_bfe_u32 v104, v60, 16, 1
	v_lshrrev_b32_e32 v3, 16, v3
	v_add3_u32 v104, v60, v104, s15
	v_and_or_b32 v104, v104, s30, v3
	v_bfe_u32 v3, v80, 16, 1
	v_add3_u32 v3, v80, v3, s15
	v_bfe_u32 v105, v84, 16, 1
	v_lshrrev_b32_e32 v3, 16, v3
	v_add3_u32 v105, v84, v105, s15
	v_and_or_b32 v105, v105, s30, v3
	v_bfe_u32 v3, v9, 16, 1
	global_store_dwordx4 v[4:5], v[102:105], off offset:2048 nt
	v_add3_u32 v3, v9, v3, s15
	v_lshrrev_b32_e32 v3, 16, v3
	v_bfe_u32 v102, v17, 16, 1
	v_add3_u32 v102, v17, v102, s15
	v_and_or_b32 v102, v102, s30, v3
	v_bfe_u32 v3, v45, 16, 1
	v_add3_u32 v3, v45, v3, s15
	v_bfe_u32 v103, v13, 16, 1
	v_lshrrev_b32_e32 v3, 16, v3
	v_add3_u32 v103, v13, v103, s15
	v_and_or_b32 v103, v103, s30, v3
	v_bfe_u32 v3, v57, 16, 1
	v_add3_u32 v3, v57, v3, s15
	v_bfe_u32 v104, v61, 16, 1
	v_lshrrev_b32_e32 v3, 16, v3
	v_add3_u32 v104, v61, v104, s15
	v_and_or_b32 v104, v104, s30, v3
	v_bfe_u32 v3, v81, 16, 1
	v_add3_u32 v3, v81, v3, s15
	v_bfe_u32 v105, v85, 16, 1
	v_lshrrev_b32_e32 v3, 16, v3
	v_add3_u32 v105, v85, v105, s15
	v_and_or_b32 v105, v105, s30, v3
	global_store_dwordx4 v[4:5], v[102:105], off offset:3072 nt

.LBB0_459:
	v_ashrrev_i32_e32 v137, 31, v136
	s_waitcnt vmcnt(1)
	v_bfe_u32 v3, v106, 16, 1
	v_lshlrev_b64 v[4:5], 10, v[136:137]
	v_add3_u32 v3, v106, v3, s15
	s_waitcnt vmcnt(0)
	v_bfe_u32 v106, v102, 16, 1
	v_lshl_add_u64 v[4:5], s[18:19], 0, v[4:5]
	v_lshrrev_b32_e32 v3, 16, v3
	v_add3_u32 v102, v102, v106, s15
	v_lshl_add_u64 v[4:5], v[134:135], 1, v[4:5]
	v_and_or_b32 v134, v102, s30, v3
	v_bfe_u32 v3, v114, 16, 1
	v_add3_u32 v3, v114, v3, s15
	v_bfe_u32 v102, v110, 16, 1
	v_lshrrev_b32_e32 v3, 16, v3
	v_add3_u32 v102, v110, v102, s15
	v_and_or_b32 v135, v102, s30, v3
	v_bfe_u32 v3, v122, 16, 1
	v_add3_u32 v3, v122, v3, s15
	v_bfe_u32 v102, v118, 16, 1
	v_lshrrev_b32_e32 v3, 16, v3
	v_add3_u32 v102, v118, v102, s15
	v_and_or_b32 v136, v102, s30, v3
	v_bfe_u32 v3, v130, 16, 1
	v_add3_u32 v3, v130, v3, s15
	v_bfe_u32 v102, v126, 16, 1
	v_lshrrev_b32_e32 v3, 16, v3
	v_add3_u32 v102, v126, v102, s15
	v_and_or_b32 v137, v102, s30, v3
	v_bfe_u32 v3, v107, 16, 1
	v_add3_u32 v3, v107, v3, s15
	v_bfe_u32 v102, v103, 16, 1
	v_lshrrev_b32_e32 v3, 16, v3
	v_add3_u32 v102, v103, v102, s15
	global_store_dwordx4 v[4:5], v[134:137], off nt
	v_bfe_u32 v103, v113, 16, 1
	v_add3_u32 v103, v113, v103, s15
	v_and_or_b32 v134, v102, s30, v3
	v_bfe_u32 v3, v115, 16, 1
	v_add3_u32 v3, v115, v3, s15
	v_bfe_u32 v102, v111, 16, 1
	v_lshrrev_b32_e32 v3, 16, v3
	v_add3_u32 v102, v111, v102, s15
	v_and_or_b32 v135, v102, s30, v3
	v_bfe_u32 v3, v123, 16, 1
	v_add3_u32 v3, v123, v3, s15
	v_bfe_u32 v102, v119, 16, 1
	v_lshrrev_b32_e32 v3, 16, v3
	v_add3_u32 v102, v119, v102, s15
	v_and_or_b32 v136, v102, s30, v3
	v_bfe_u32 v3, v131, 16, 1
	v_add3_u32 v3, v131, v3, s15
	v_bfe_u32 v102, v127, 16, 1
	v_lshrrev_b32_e32 v3, 16, v3
	v_add3_u32 v102, v127, v102, s15
	v_and_or_b32 v137, v102, s30, v3
	v_bfe_u32 v3, v108, 16, 1
	v_add3_u32 v3, v108, v3, s15
	v_bfe_u32 v102, v104, 16, 1
	v_lshrrev_b32_e32 v3, 16, v3
	v_add3_u32 v102, v104, v102, s15
	global_store_dwordx4 v[4:5], v[134:137], off offset:1024 nt
	v_bfe_u32 v104, v121, 16, 1
	v_add3_u32 v104, v121, v104, s15
	v_and_or_b32 v134, v102, s30, v3
	v_bfe_u32 v3, v116, 16, 1
	v_add3_u32 v3, v116, v3, s15
	v_bfe_u32 v102, v112, 16, 1
	v_lshrrev_b32_e32 v3, 16, v3
	v_add3_u32 v102, v112, v102, s15
	v_and_or_b32 v135, v102, s30, v3
	v_bfe_u32 v3, v124, 16, 1
	v_add3_u32 v3, v124, v3, s15
	v_bfe_u32 v102, v120, 16, 1
	v_lshrrev_b32_e32 v3, 16, v3
	v_add3_u32 v102, v120, v102, s15
	v_and_or_b32 v136, v102, s30, v3
	v_bfe_u32 v3, v132, 16, 1
	v_add3_u32 v3, v132, v3, s15
	v_bfe_u32 v102, v128, 16, 1
	v_lshrrev_b32_e32 v3, 16, v3
	v_add3_u32 v102, v128, v102, s15
	v_and_or_b32 v137, v102, s30, v3
	v_bfe_u32 v3, v109, 16, 1
	v_add3_u32 v3, v109, v3, s15
	v_bfe_u32 v102, v105, 16, 1
	v_lshrrev_b32_e32 v3, 16, v3
	v_add3_u32 v102, v105, v102, s15
	v_and_or_b32 v102, v102, s30, v3
	v_bfe_u32 v3, v117, 16, 1
	v_add3_u32 v3, v117, v3, s15
	v_lshrrev_b32_e32 v3, 16, v3
	v_and_or_b32 v103, v103, s30, v3
	v_bfe_u32 v3, v125, 16, 1
	v_add3_u32 v3, v125, v3, s15
	v_lshrrev_b32_e32 v3, 16, v3
	v_and_or_b32 v104, v104, s30, v3
	v_bfe_u32 v3, v133, 16, 1
	v_add3_u32 v3, v133, v3, s15
	v_bfe_u32 v105, v129, 16, 1
	v_lshrrev_b32_e32 v3, 16, v3
	v_add3_u32 v105, v129, v105, s15
	v_and_or_b32 v105, v105, s30, v3
	s_andn2_b64 vcc, exec, s[26:27]
	global_store_dwordx4 v[4:5], v[134:137], off offset:2048 nt
	global_store_dwordx4 v[4:5], v[102:105], off offset:3072 nt
	s_cbranch_vccnz .LBB0_464
	s_ashr_i32 s26, s35, 31
	s_lshr_b32 s26, s26, 25
	s_add_i32 s35, s35, s26
	s_ashr_i32 s26, s35, 7
	v_lshl_or_b32 v4, s26, 6, v140
	s_and_b64 vcc, exec, s[4:5]
	v_ashrrev_i32_e32 v5, 31, v4
	s_cbranch_vccnz .LBB0_462
	v_lshl_add_u64 v[110:111], v[4:5], 2, s[16:17]
	global_load_dwordx4 v[102:105], v[110:111], off
	global_load_dwordx4 v[106:109], v[110:111], off offset:16
	s_waitcnt vmcnt(1)
	v_pk_mul_f32 v[32:33], v[102:103], v[32:33] op_sel_hi:[0,1]
	v_pk_mul_f32 v[30:31], v[102:103], v[30:31] op_sel_hi:[0,1]
	v_pk_mul_f32 v[40:41], v[102:103], v[40:41] op_sel:[1,0]
	v_pk_mul_f32 v[38:39], v[102:103], v[38:39] op_sel:[1,0]
	v_pk_mul_f32 v[52:53], v[104:105], v[52:53] op_sel_hi:[0,1]
	v_pk_mul_f32 v[50:51], v[104:105], v[50:51] op_sel_hi:[0,1]
	v_mov_b32_e32 v102, v105
	s_waitcnt vmcnt(0)
	v_mov_b32_e32 v104, v109
	v_pk_mul_f32 v[72:73], v[106:107], v[72:73] op_sel_hi:[0,1]
	v_pk_mul_f32 v[70:71], v[106:107], v[70:71] op_sel_hi:[0,1]
	v_pk_mul_f32 v[76:77], v[106:107], v[76:77] op_sel:[1,0]
	v_pk_mul_f32 v[74:75], v[106:107], v[74:75] op_sel:[1,0]
	v_pk_mul_f32 v[96:97], v[108:109], v[96:97] op_sel_hi:[0,1]
	v_pk_mul_f32 v[94:95], v[108:109], v[94:95] op_sel_hi:[0,1]
	v_pk_mul_f32 v[36:37], v[102:103], v[36:37] op_sel_hi:[0,1]
	v_pk_mul_f32 v[34:35], v[102:103], v[34:35] op_sel_hi:[0,1]
	v_pk_mul_f32 v[100:101], v[104:105], v[100:101] op_sel_hi:[0,1]
	v_pk_mul_f32 v[98:99], v[104:105], v[98:99] op_sel_hi:[0,1]
.LBB0_462:
	s_lshl_b32 s26, s26, 12
	v_subrev_u32_e32 v102, s26, v151
	v_ashrrev_i32_e32 v103, 31, v102
	v_lshlrev_b64 v[102:103], 10, v[102:103]
	v_lshl_add_u64 v[102:103], s[18:19], 0, v[102:103]
	v_bfe_u32 v3, v30, 16, 1
	v_lshl_add_u64 v[4:5], v[4:5], 1, v[102:103]
	v_add3_u32 v3, v30, v3, s15
	v_bfe_u32 v102, v38, 16, 1
	v_lshrrev_b32_e32 v3, 16, v3
	v_add3_u32 v102, v38, v102, s15
	v_and_or_b32 v102, v102, s30, v3
	v_bfe_u32 v3, v50, 16, 1
	v_add3_u32 v3, v50, v3, s15
	v_bfe_u32 v103, v34, 16, 1
	v_lshrrev_b32_e32 v3, 16, v3
	v_add3_u32 v103, v34, v103, s15
	v_and_or_b32 v103, v103, s30, v3
	v_bfe_u32 v3, v70, 16, 1
	v_add3_u32 v3, v70, v3, s15
	v_bfe_u32 v104, v74, 16, 1
	v_lshrrev_b32_e32 v3, 16, v3
	v_add3_u32 v104, v74, v104, s15
	v_and_or_b32 v104, v104, s30, v3
	v_bfe_u32 v3, v94, 16, 1
	v_add3_u32 v3, v94, v3, s15
	v_bfe_u32 v105, v98, 16, 1
	v_lshrrev_b32_e32 v3, 16, v3
	v_add3_u32 v105, v98, v105, s15
	v_and_or_b32 v105, v105, s30, v3
	v_bfe_u32 v3, v31, 16, 1
	global_store_dwordx4 v[4:5], v[102:105], off nt
	v_add3_u32 v3, v31, v3, s15
	v_lshrrev_b32_e32 v3, 16, v3
	v_bfe_u32 v102, v39, 16, 1
	v_add3_u32 v102, v39, v102, s15
	v_and_or_b32 v102, v102, s30, v3
	v_bfe_u32 v3, v51, 16, 1
	v_add3_u32 v3, v51, v3, s15
	v_bfe_u32 v103, v35, 16, 1
	v_lshrrev_b32_e32 v3, 16, v3
	v_add3_u32 v103, v35, v103, s15
	v_and_or_b32 v103, v103, s30, v3
	v_bfe_u32 v3, v71, 16, 1
	v_add3_u32 v3, v71, v3, s15
	v_bfe_u32 v104, v75, 16, 1
	v_lshrrev_b32_e32 v3, 16, v3
	v_add3_u32 v104, v75, v104, s15
	v_and_or_b32 v104, v104, s30, v3
	v_bfe_u32 v3, v95, 16, 1
	v_add3_u32 v3, v95, v3, s15
	v_bfe_u32 v105, v99, 16, 1
	v_lshrrev_b32_e32 v3, 16, v3
	v_add3_u32 v105, v99, v105, s15
	v_and_or_b32 v105, v105, s30, v3
	v_bfe_u32 v3, v32, 16, 1
	global_store_dwordx4 v[4:5], v[102:105], off offset:1024 nt
	v_add3_u32 v3, v32, v3, s15
	v_lshrrev_b32_e32 v3, 16, v3
	v_bfe_u32 v102, v40, 16, 1
	v_add3_u32 v102, v40, v102, s15
	v_and_or_b32 v102, v102, s30, v3
	v_bfe_u32 v3, v52, 16, 1
	v_add3_u32 v3, v52, v3, s15
	v_bfe_u32 v103, v36, 16, 1
	v_lshrrev_b32_e32 v3, 16, v3
	v_add3_u32 v103, v36, v103, s15
	v_and_or_b32 v103, v103, s30, v3
	v_bfe_u32 v3, v72, 16, 1
	v_add3_u32 v3, v72, v3, s15
	v_bfe_u32 v104, v76, 16, 1
	v_lshrrev_b32_e32 v3, 16, v3
	v_add3_u32 v104, v76, v104, s15
	v_and_or_b32 v104, v104, s30, v3
	v_bfe_u32 v3, v96, 16, 1
	v_add3_u32 v3, v96, v3, s15
	v_bfe_u32 v105, v100, 16, 1
	v_lshrrev_b32_e32 v3, 16, v3
	v_add3_u32 v105, v100, v105, s15
	v_and_or_b32 v105, v105, s30, v3
	v_bfe_u32 v3, v33, 16, 1
	global_store_dwordx4 v[4:5], v[102:105], off offset:2048 nt
	v_add3_u32 v3, v33, v3, s15
	v_lshrrev_b32_e32 v3, 16, v3
	v_bfe_u32 v102, v41, 16, 1
	v_add3_u32 v102, v41, v102, s15
	v_and_or_b32 v102, v102, s30, v3
	v_bfe_u32 v3, v53, 16, 1
	v_add3_u32 v3, v53, v3, s15
	v_bfe_u32 v103, v37, 16, 1
	v_lshrrev_b32_e32 v3, 16, v3
	v_add3_u32 v103, v37, v103, s15
	v_and_or_b32 v103, v103, s30, v3
	v_bfe_u32 v3, v73, 16, 1
	v_add3_u32 v3, v73, v3, s15
	v_bfe_u32 v104, v77, 16, 1
	v_lshrrev_b32_e32 v3, 16, v3
	v_add3_u32 v104, v77, v104, s15
	v_and_or_b32 v104, v104, s30, v3
	v_bfe_u32 v3, v97, 16, 1
	v_add3_u32 v3, v97, v3, s15
	v_bfe_u32 v105, v101, 16, 1
	v_lshrrev_b32_e32 v3, 16, v3
	v_add3_u32 v105, v101, v105, s15
	v_and_or_b32 v105, v105, s30, v3
	global_store_dwordx4 v[4:5], v[102:105], off offset:3072 nt
	s_andn2_b64 vcc, exec, s[24:25]
	s_cbranch_vccz .LBB0_465

.LBB0_467:
	s_lshl_b32 s24, s24, 12
	v_subrev_u32_e32 v102, s24, v150
	v_ashrrev_i32_e32 v103, 31, v102
	v_lshlrev_b64 v[102:103], 10, v[102:103]
	v_lshl_add_u64 v[102:103], s[18:19], 0, v[102:103]
	v_bfe_u32 v3, v18, 16, 1
	v_lshl_add_u64 v[4:5], v[4:5], 1, v[102:103]
	v_add3_u32 v3, v18, v3, s15
	v_bfe_u32 v102, v26, 16, 1
	v_lshrrev_b32_e32 v3, 16, v3
	v_add3_u32 v102, v26, v102, s15
	v_and_or_b32 v102, v102, s30, v3
	v_bfe_u32 v3, v46, 16, 1
	v_add3_u32 v3, v46, v3, s15
	v_bfe_u32 v103, v22, 16, 1
	v_lshrrev_b32_e32 v3, 16, v3
	v_add3_u32 v103, v22, v103, s15
	v_and_or_b32 v103, v103, s30, v3
	v_bfe_u32 v3, v62, 16, 1
	v_add3_u32 v3, v62, v3, s15
	v_bfe_u32 v104, v66, 16, 1
	v_lshrrev_b32_e32 v3, 16, v3
	v_add3_u32 v104, v66, v104, s15
	v_and_or_b32 v104, v104, s30, v3
	v_bfe_u32 v3, v86, 16, 1
	v_add3_u32 v3, v86, v3, s15
	v_bfe_u32 v105, v90, 16, 1
	v_lshrrev_b32_e32 v3, 16, v3
	v_add3_u32 v105, v90, v105, s15
	v_and_or_b32 v105, v105, s30, v3
	v_bfe_u32 v3, v19, 16, 1
	global_store_dwordx4 v[4:5], v[102:105], off nt
	v_add3_u32 v3, v19, v3, s15
	v_lshrrev_b32_e32 v3, 16, v3
	v_bfe_u32 v102, v27, 16, 1
	v_add3_u32 v102, v27, v102, s15
	v_and_or_b32 v102, v102, s30, v3
	v_bfe_u32 v3, v47, 16, 1
	v_add3_u32 v3, v47, v3, s15
	v_bfe_u32 v103, v23, 16, 1
	v_lshrrev_b32_e32 v3, 16, v3
	v_add3_u32 v103, v23, v103, s15
	v_and_or_b32 v103, v103, s30, v3
	v_bfe_u32 v3, v63, 16, 1
	v_add3_u32 v3, v63, v3, s15
	v_bfe_u32 v104, v67, 16, 1
	v_lshrrev_b32_e32 v3, 16, v3
	v_add3_u32 v104, v67, v104, s15
	v_and_or_b32 v104, v104, s30, v3
	v_bfe_u32 v3, v87, 16, 1
	v_add3_u32 v3, v87, v3, s15
	v_bfe_u32 v105, v91, 16, 1
	v_lshrrev_b32_e32 v3, 16, v3
	v_add3_u32 v105, v91, v105, s15
	v_and_or_b32 v105, v105, s30, v3
	v_bfe_u32 v3, v20, 16, 1
	global_store_dwordx4 v[4:5], v[102:105], off offset:1024 nt
	v_add3_u32 v3, v20, v3, s15
	v_lshrrev_b32_e32 v3, 16, v3
	v_bfe_u32 v102, v28, 16, 1
	v_add3_u32 v102, v28, v102, s15
	v_and_or_b32 v102, v102, s30, v3
	v_bfe_u32 v3, v48, 16, 1
	v_add3_u32 v3, v48, v3, s15
	v_bfe_u32 v103, v24, 16, 1
	v_lshrrev_b32_e32 v3, 16, v3
	v_add3_u32 v103, v24, v103, s15
	v_and_or_b32 v103, v103, s30, v3
	v_bfe_u32 v3, v64, 16, 1
	v_add3_u32 v3, v64, v3, s15
	v_bfe_u32 v104, v68, 16, 1
	v_lshrrev_b32_e32 v3, 16, v3
	v_add3_u32 v104, v68, v104, s15
	v_and_or_b32 v104, v104, s30, v3
	v_bfe_u32 v3, v88, 16, 1
	v_add3_u32 v3, v88, v3, s15
	v_bfe_u32 v105, v92, 16, 1
	v_lshrrev_b32_e32 v3, 16, v3
	v_add3_u32 v105, v92, v105, s15
	v_and_or_b32 v105, v105, s30, v3
	v_bfe_u32 v3, v21, 16, 1
	global_store_dwordx4 v[4:5], v[102:105], off offset:2048 nt
	v_add3_u32 v3, v21, v3, s15
	v_lshrrev_b32_e32 v3, 16, v3
	v_bfe_u32 v102, v29, 16, 1
	v_add3_u32 v102, v29, v102, s15
	v_and_or_b32 v102, v102, s30, v3
	v_bfe_u32 v3, v49, 16, 1
	v_add3_u32 v3, v49, v3, s15
	v_bfe_u32 v103, v25, 16, 1
	v_lshrrev_b32_e32 v3, 16, v3
	v_add3_u32 v103, v25, v103, s15
	v_and_or_b32 v103, v103, s30, v3
	v_bfe_u32 v3, v65, 16, 1
	v_add3_u32 v3, v65, v3, s15
	v_bfe_u32 v104, v69, 16, 1
	v_lshrrev_b32_e32 v3, 16, v3
	v_add3_u32 v104, v69, v104, s15
	v_and_or_b32 v104, v104, s30, v3
	v_bfe_u32 v3, v89, 16, 1
	v_add3_u32 v3, v89, v3, s15
	v_bfe_u32 v105, v93, 16, 1
	v_lshrrev_b32_e32 v3, 16, v3
	v_add3_u32 v105, v93, v105, s15
	v_and_or_b32 v105, v105, s30, v3
	global_store_dwordx4 v[4:5], v[102:105], off offset:3072 nt
	s_andn2_b64 vcc, exec, s[22:23]
	s_cbranch_vccnz .LBB0_418

.LBB0_516:
	s_waitcnt vmcnt(1)
	v_bfe_u32 v130, v102, 16, 1
	v_mov_b64_e32 v[140:141], s[18:19]
	v_add3_u32 v102, v102, v130, s26
	s_waitcnt vmcnt(0)
	v_bfe_u32 v130, v98, 16, 1
	v_mad_i64_i32 v[140:141], s[4:5], v139, s15, v[140:141]
	v_lshrrev_b32_e32 v102, 16, v102
	v_add3_u32 v98, v98, v130, s26
	v_lshl_add_u64 v[132:133], v[132:133], 1, v[140:141]
	v_and_or_b32 v140, v98, s27, v102
	v_bfe_u32 v98, v114, 16, 1
	v_add3_u32 v98, v114, v98, s26
	v_bfe_u32 v102, v110, 16, 1
	v_lshrrev_b32_e32 v98, 16, v98
	v_add3_u32 v102, v110, v102, s26
	v_and_or_b32 v141, v102, s27, v98
	v_bfe_u32 v98, v118, 16, 1
	v_add3_u32 v98, v118, v98, s26
	v_bfe_u32 v102, v106, 16, 1
	v_lshrrev_b32_e32 v98, 16, v98
	v_add3_u32 v102, v106, v102, s26
	v_and_or_b32 v142, v102, s27, v98
	v_bfe_u32 v98, v126, 16, 1
	v_add3_u32 v98, v126, v98, s26
	v_bfe_u32 v102, v122, 16, 1
	v_lshrrev_b32_e32 v98, 16, v98
	v_add3_u32 v102, v122, v102, s26
	v_and_or_b32 v143, v102, s27, v98
	v_bfe_u32 v98, v103, 16, 1
	v_add3_u32 v98, v103, v98, s26
	v_bfe_u32 v102, v99, 16, 1
	v_lshrrev_b32_e32 v98, 16, v98
	v_add3_u32 v99, v99, v102, s26
	global_store_dwordx4 v[132:133], v[140:143], off nt
	v_bfe_u32 v102, v125, 16, 1
	v_add3_u32 v102, v125, v102, s26
	v_and_or_b32 v140, v99, s27, v98
	v_bfe_u32 v98, v115, 16, 1
	v_add3_u32 v98, v115, v98, s26
	v_bfe_u32 v99, v111, 16, 1
	v_lshrrev_b32_e32 v98, 16, v98
	v_add3_u32 v99, v111, v99, s26
	v_and_or_b32 v141, v99, s27, v98
	v_bfe_u32 v98, v119, 16, 1
	v_add3_u32 v98, v119, v98, s26
	v_bfe_u32 v99, v107, 16, 1
	v_lshrrev_b32_e32 v98, 16, v98
	v_add3_u32 v99, v107, v99, s26
	v_and_or_b32 v142, v99, s27, v98
	v_bfe_u32 v98, v127, 16, 1
	v_add3_u32 v98, v127, v98, s26
	v_bfe_u32 v99, v123, 16, 1
	v_lshrrev_b32_e32 v98, 16, v98
	v_add3_u32 v99, v123, v99, s26
	v_and_or_b32 v143, v99, s27, v98
	v_add_co_u32_e32 v98, vcc, s15, v132
	s_nop 1
	v_addc_co_u32_e32 v99, vcc, 0, v133, vcc
	global_store_dwordx4 v[98:99], v[140:143], off nt
	v_bfe_u32 v98, v104, 16, 1
	v_add3_u32 v98, v104, v98, s26
	v_bfe_u32 v99, v100, 16, 1
	v_lshrrev_b32_e32 v98, 16, v98
	v_add3_u32 v99, v100, v99, s26
	v_and_or_b32 v140, v99, s27, v98
	v_bfe_u32 v98, v116, 16, 1
	v_add3_u32 v98, v116, v98, s26
	v_bfe_u32 v99, v112, 16, 1
	v_lshrrev_b32_e32 v98, 16, v98
	v_add3_u32 v99, v112, v99, s26
	v_and_or_b32 v141, v99, s27, v98
	v_bfe_u32 v98, v120, 16, 1
	v_add3_u32 v98, v120, v98, s26
	v_bfe_u32 v99, v108, 16, 1
	v_lshrrev_b32_e32 v98, 16, v98
	v_add3_u32 v99, v108, v99, s26
	v_and_or_b32 v142, v99, s27, v98
	v_bfe_u32 v98, v128, 16, 1
	v_add3_u32 v98, v128, v98, s26
	v_bfe_u32 v99, v124, 16, 1
	v_lshrrev_b32_e32 v98, 16, v98
	v_add3_u32 v99, v124, v99, s26
	v_and_or_b32 v143, v99, s27, v98
	v_add_co_u32_e32 v98, vcc, s28, v132
	v_bfe_u32 v100, v113, 16, 1
	s_nop 0
	v_addc_co_u32_e32 v99, vcc, 0, v133, vcc
	global_store_dwordx4 v[98:99], v[140:143], off nt
	v_bfe_u32 v98, v105, 16, 1
	v_add3_u32 v98, v105, v98, s26
	v_bfe_u32 v99, v101, 16, 1
	v_lshrrev_b32_e32 v98, 16, v98
	v_add3_u32 v99, v101, v99, s26
	v_and_or_b32 v98, v99, s27, v98
	v_bfe_u32 v99, v117, 16, 1
	v_add3_u32 v99, v117, v99, s26
	v_lshrrev_b32_e32 v99, 16, v99
	v_add3_u32 v100, v113, v100, s26
	v_and_or_b32 v99, v100, s27, v99
	v_bfe_u32 v100, v121, 16, 1
	v_add3_u32 v100, v121, v100, s26
	v_bfe_u32 v101, v109, 16, 1
	v_lshrrev_b32_e32 v100, 16, v100
	v_add3_u32 v101, v109, v101, s26
	v_and_or_b32 v100, v101, s27, v100
	v_bfe_u32 v101, v129, 16, 1
	v_add3_u32 v101, v129, v101, s26
	v_lshrrev_b32_e32 v101, 16, v101
	v_and_or_b32 v101, v102, s27, v101
	v_add_co_u32_e32 v102, vcc, 0x9000, v132
	s_nop 1
	v_addc_co_u32_e32 v103, vcc, 0, v133, vcc
	s_andn2_b64 vcc, exec, s[20:21]
	global_store_dwordx4 v[102:103], v[98:101], off nt
	s_cbranch_vccnz .LBB0_519
	s_ashr_i32 s4, s30, 31
	s_lshr_b32 s4, s4, 25
	s_add_i32 s30, s30, s4
	s_ashr_i32 s4, s30, 7
	v_lshl_or_b32 v98, s4, 6, v134
	v_add_u32_e32 v100, s0, v138
	s_lshl_b32 s4, s4, 12
	v_subrev_u32_e32 v102, s4, v100
	v_mov_b64_e32 v[100:101], s[18:19]
	v_ashrrev_i32_e32 v99, 31, v98
	v_mad_i64_i32 v[100:101], s[4:5], v102, s15, v[100:101]
	v_lshl_add_u64 v[102:103], v[98:99], 1, v[100:101]
	v_bfe_u32 v98, v38, 16, 1
	v_add3_u32 v98, v38, v98, s26
	v_bfe_u32 v99, v30, 16, 1
	v_lshrrev_b32_e32 v98, 16, v98
	v_add3_u32 v99, v30, v99, s26
	v_and_or_b32 v98, v99, s27, v98
	v_bfe_u32 v99, v62, 16, 1
	v_add3_u32 v99, v62, v99, s26
	v_bfe_u32 v100, v58, 16, 1
	v_lshrrev_b32_e32 v99, 16, v99
	v_add3_u32 v100, v58, v100, s26
	v_and_or_b32 v99, v100, s27, v99
	v_bfe_u32 v100, v78, 16, 1
	v_add3_u32 v100, v78, v100, s26
	v_bfe_u32 v101, v54, 16, 1
	v_lshrrev_b32_e32 v100, 16, v100
	v_add3_u32 v101, v54, v101, s26
	v_and_or_b32 v100, v101, s27, v100
	v_bfe_u32 v101, v90, 16, 1
	v_add3_u32 v101, v90, v101, s26
	v_bfe_u32 v104, v94, 16, 1
	v_lshrrev_b32_e32 v101, 16, v101
	v_add3_u32 v104, v94, v104, s26
	v_and_or_b32 v101, v104, s27, v101
	global_store_dwordx4 v[102:103], v[98:101], off nt
	v_bfe_u32 v104, v95, 16, 1
	v_add3_u32 v104, v95, v104, s26
	v_bfe_u32 v98, v39, 16, 1
	v_add3_u32 v98, v39, v98, s26
	v_bfe_u32 v99, v31, 16, 1
	v_lshrrev_b32_e32 v98, 16, v98
	v_add3_u32 v99, v31, v99, s26
	v_and_or_b32 v98, v99, s27, v98
	v_bfe_u32 v99, v63, 16, 1
	v_add3_u32 v99, v63, v99, s26
	v_bfe_u32 v100, v59, 16, 1
	v_lshrrev_b32_e32 v99, 16, v99
	v_add3_u32 v100, v59, v100, s26
	v_and_or_b32 v99, v100, s27, v99
	v_bfe_u32 v100, v79, 16, 1
	v_add3_u32 v100, v79, v100, s26
	v_bfe_u32 v101, v55, 16, 1
	v_lshrrev_b32_e32 v100, 16, v100
	v_add3_u32 v101, v55, v101, s26
	v_and_or_b32 v100, v101, s27, v100
	v_bfe_u32 v101, v91, 16, 1
	v_add3_u32 v101, v91, v101, s26
	v_lshrrev_b32_e32 v101, 16, v101
	v_and_or_b32 v101, v104, s27, v101
	v_add_co_u32_e32 v104, vcc, s15, v102
	s_nop 1
	v_addc_co_u32_e32 v105, vcc, 0, v103, vcc
	global_store_dwordx4 v[104:105], v[98:101], off nt
	v_bfe_u32 v104, v96, 16, 1
	v_add3_u32 v104, v96, v104, s26
	v_bfe_u32 v98, v40, 16, 1
	v_add3_u32 v98, v40, v98, s26
	v_bfe_u32 v99, v32, 16, 1
	v_lshrrev_b32_e32 v98, 16, v98
	v_add3_u32 v99, v32, v99, s26
	v_and_or_b32 v98, v99, s27, v98
	v_bfe_u32 v99, v64, 16, 1
	v_add3_u32 v99, v64, v99, s26
	v_bfe_u32 v100, v60, 16, 1
	v_lshrrev_b32_e32 v99, 16, v99
	v_add3_u32 v100, v60, v100, s26
	v_and_or_b32 v99, v100, s27, v99
	v_bfe_u32 v100, v80, 16, 1
	v_add3_u32 v100, v80, v100, s26
	v_bfe_u32 v101, v56, 16, 1
	v_lshrrev_b32_e32 v100, 16, v100
	v_add3_u32 v101, v56, v101, s26
	v_and_or_b32 v100, v101, s27, v100
	v_bfe_u32 v101, v92, 16, 1
	v_add3_u32 v101, v92, v101, s26
	v_lshrrev_b32_e32 v101, 16, v101
	v_and_or_b32 v101, v104, s27, v101
	v_add_co_u32_e32 v104, vcc, s28, v102
	s_nop 1
	v_addc_co_u32_e32 v105, vcc, 0, v103, vcc
	global_store_dwordx4 v[104:105], v[98:101], off nt
	v_bfe_u32 v104, v97, 16, 1
	v_add3_u32 v104, v97, v104, s26
	v_bfe_u32 v98, v41, 16, 1
	v_add3_u32 v98, v41, v98, s26
	v_bfe_u32 v99, v33, 16, 1
	v_lshrrev_b32_e32 v98, 16, v98
	v_add3_u32 v99, v33, v99, s26
	v_and_or_b32 v98, v99, s27, v98
	v_bfe_u32 v99, v65, 16, 1
	v_add3_u32 v99, v65, v99, s26
	v_bfe_u32 v100, v61, 16, 1
	v_lshrrev_b32_e32 v99, 16, v99
	v_add3_u32 v100, v61, v100, s26
	v_and_or_b32 v99, v100, s27, v99
	v_bfe_u32 v100, v81, 16, 1
	v_add3_u32 v100, v81, v100, s26
	v_bfe_u32 v101, v57, 16, 1
	v_lshrrev_b32_e32 v100, 16, v100
	v_add3_u32 v101, v57, v101, s26
	v_and_or_b32 v100, v101, s27, v100
	v_bfe_u32 v101, v93, 16, 1
	v_add3_u32 v101, v93, v101, s26
	v_lshrrev_b32_e32 v101, 16, v101
	v_add_co_u32_e32 v102, vcc, 0x9000, v102
	v_and_or_b32 v101, v104, s27, v101
	s_nop 0
	v_addc_co_u32_e32 v103, vcc, 0, v103, vcc
	global_store_dwordx4 v[102:103], v[98:101], off nt
	s_andn2_b64 vcc, exec, s[22:23]
	s_cbranch_vccz .LBB0_520

.LBB0_520:
	s_ashr_i32 s4, s31, 31
	s_lshr_b32 s4, s4, 25
	s_add_i32 s31, s31, s4
	s_ashr_i32 s4, s31, 7
	v_lshl_or_b32 v98, s4, 6, v134
	v_add_u32_e32 v100, s0, v136
	s_lshl_b32 s4, s4, 12
	v_subrev_u32_e32 v102, s4, v100
	v_mov_b64_e32 v[100:101], s[18:19]
	v_ashrrev_i32_e32 v99, 31, v98
	v_mad_i64_i32 v[100:101], s[4:5], v102, s15, v[100:101]
	v_lshl_add_u64 v[102:103], v[98:99], 1, v[100:101]
	v_bfe_u32 v98, v18, 16, 1
	v_add3_u32 v98, v18, v98, s26
	v_bfe_u32 v99, v10, 16, 1
	v_lshrrev_b32_e32 v98, 16, v98
	v_add3_u32 v99, v10, v99, s26
	v_and_or_b32 v98, v99, s27, v98
	v_bfe_u32 v99, v46, 16, 1
	v_add3_u32 v99, v46, v99, s26
	v_bfe_u32 v100, v42, 16, 1
	v_lshrrev_b32_e32 v99, 16, v99
	v_add3_u32 v100, v42, v100, s26
	v_and_or_b32 v99, v100, s27, v99
	v_bfe_u32 v100, v66, 16, 1
	v_add3_u32 v100, v66, v100, s26
	v_bfe_u32 v101, v34, 16, 1
	v_lshrrev_b32_e32 v100, 16, v100
	v_add3_u32 v101, v34, v101, s26
	v_and_or_b32 v100, v101, s27, v100
	v_bfe_u32 v101, v82, 16, 1
	v_add3_u32 v101, v82, v101, s26
	v_bfe_u32 v104, v86, 16, 1
	v_lshrrev_b32_e32 v101, 16, v101
	v_add3_u32 v104, v86, v104, s26
	v_and_or_b32 v101, v104, s27, v101
	global_store_dwordx4 v[102:103], v[98:101], off nt
	v_bfe_u32 v104, v87, 16, 1
	v_add3_u32 v104, v87, v104, s26
	v_bfe_u32 v98, v19, 16, 1
	v_add3_u32 v98, v19, v98, s26
	v_bfe_u32 v99, v11, 16, 1
	v_lshrrev_b32_e32 v98, 16, v98
	v_add3_u32 v99, v11, v99, s26
	v_and_or_b32 v98, v99, s27, v98
	v_bfe_u32 v99, v47, 16, 1
	v_add3_u32 v99, v47, v99, s26
	v_bfe_u32 v100, v43, 16, 1
	v_lshrrev_b32_e32 v99, 16, v99
	v_add3_u32 v100, v43, v100, s26
	v_and_or_b32 v99, v100, s27, v99
	v_bfe_u32 v100, v67, 16, 1
	v_add3_u32 v100, v67, v100, s26
	v_bfe_u32 v101, v35, 16, 1
	v_lshrrev_b32_e32 v100, 16, v100
	v_add3_u32 v101, v35, v101, s26
	v_and_or_b32 v100, v101, s27, v100
	v_bfe_u32 v101, v83, 16, 1
	v_add3_u32 v101, v83, v101, s26
	v_lshrrev_b32_e32 v101, 16, v101
	v_and_or_b32 v101, v104, s27, v101
	v_add_co_u32_e32 v104, vcc, s15, v102
	s_nop 1
	v_addc_co_u32_e32 v105, vcc, 0, v103, vcc
	global_store_dwordx4 v[104:105], v[98:101], off nt
	v_bfe_u32 v104, v88, 16, 1
	v_add3_u32 v104, v88, v104, s26
	v_bfe_u32 v98, v20, 16, 1
	v_add3_u32 v98, v20, v98, s26
	v_bfe_u32 v99, v12, 16, 1
	v_lshrrev_b32_e32 v98, 16, v98
	v_add3_u32 v99, v12, v99, s26
	v_and_or_b32 v98, v99, s27, v98
	v_bfe_u32 v99, v48, 16, 1
	v_add3_u32 v99, v48, v99, s26
	v_bfe_u32 v100, v44, 16, 1
	v_lshrrev_b32_e32 v99, 16, v99
	v_add3_u32 v100, v44, v100, s26
	v_and_or_b32 v99, v100, s27, v99
	v_bfe_u32 v100, v68, 16, 1
	v_add3_u32 v100, v68, v100, s26
	v_bfe_u32 v101, v36, 16, 1
	v_lshrrev_b32_e32 v100, 16, v100
	v_add3_u32 v101, v36, v101, s26
	v_and_or_b32 v100, v101, s27, v100
	v_bfe_u32 v101, v84, 16, 1
	v_add3_u32 v101, v84, v101, s26
	v_lshrrev_b32_e32 v101, 16, v101
	v_and_or_b32 v101, v104, s27, v101
	v_add_co_u32_e32 v104, vcc, s28, v102
	s_nop 1
	v_addc_co_u32_e32 v105, vcc, 0, v103, vcc
	global_store_dwordx4 v[104:105], v[98:101], off nt
	v_bfe_u32 v104, v89, 16, 1
	v_add3_u32 v104, v89, v104, s26
	v_bfe_u32 v98, v21, 16, 1
	v_add3_u32 v98, v21, v98, s26
	v_bfe_u32 v99, v13, 16, 1
	v_lshrrev_b32_e32 v98, 16, v98
	v_add3_u32 v99, v13, v99, s26
	v_and_or_b32 v98, v99, s27, v98
	v_bfe_u32 v99, v49, 16, 1
	v_add3_u32 v99, v49, v99, s26
	v_bfe_u32 v100, v45, 16, 1
	v_lshrrev_b32_e32 v99, 16, v99
	v_add3_u32 v100, v45, v100, s26
	v_and_or_b32 v99, v100, s27, v99
	v_bfe_u32 v100, v69, 16, 1
	v_add3_u32 v100, v69, v100, s26
	v_bfe_u32 v101, v37, 16, 1
	v_lshrrev_b32_e32 v100, 16, v100
	v_add3_u32 v101, v37, v101, s26
	v_and_or_b32 v100, v101, s27, v100
	v_bfe_u32 v101, v85, 16, 1
	v_add3_u32 v101, v85, v101, s26
	v_lshrrev_b32_e32 v101, 16, v101
	v_add_co_u32_e32 v102, vcc, 0x9000, v102
	v_and_or_b32 v101, v104, s27, v101
	s_nop 0
	v_addc_co_u32_e32 v103, vcc, 0, v103, vcc
	global_store_dwordx4 v[102:103], v[98:101], off nt
	s_andn2_b64 vcc, exec, s[24:25]
	s_cbranch_vccnz .LBB0_472
.LBB0_521:
	s_ashr_i32 s4, s33, 31
	s_lshr_b32 s4, s4, 25
	s_add_i32 s33, s33, s4
	s_ashr_i32 s4, s33, 7
	v_lshl_or_b32 v98, s4, 6, v134
	v_add_u32_e32 v100, s0, v137
	s_lshl_b32 s4, s4, 12
	v_subrev_u32_e32 v102, s4, v100
	v_mov_b64_e32 v[100:101], s[18:19]
	v_ashrrev_i32_e32 v99, 31, v98
	v_mad_i64_i32 v[100:101], s[4:5], v102, s15, v[100:101]
	v_lshl_add_u64 v[102:103], v[98:99], 1, v[100:101]
	v_bfe_u32 v98, v6, 16, 1
	v_add3_u32 v98, v6, v98, s26
	v_bfe_u32 v99, v2, 16, 1
	v_lshrrev_b32_e32 v98, 16, v98
	v_add3_u32 v99, v2, v99, s26
	v_and_or_b32 v98, v99, s27, v98
	v_bfe_u32 v99, v26, 16, 1
	v_add3_u32 v99, v26, v99, s26
	v_bfe_u32 v100, v22, 16, 1
	v_lshrrev_b32_e32 v99, 16, v99
	v_add3_u32 v100, v22, v100, s26
	v_and_or_b32 v99, v100, s27, v99
	v_bfe_u32 v100, v50, 16, 1
	v_add3_u32 v100, v50, v100, s26
	v_bfe_u32 v101, v14, 16, 1
	v_lshrrev_b32_e32 v100, 16, v100
	v_add3_u32 v101, v14, v101, s26
	v_and_or_b32 v100, v101, s27, v100
	v_bfe_u32 v101, v70, 16, 1
	v_add3_u32 v101, v70, v101, s26
	v_bfe_u32 v104, v74, 16, 1
	v_lshrrev_b32_e32 v101, 16, v101
	v_add3_u32 v104, v74, v104, s26
	v_and_or_b32 v101, v104, s27, v101
	global_store_dwordx4 v[102:103], v[98:101], off nt
	v_bfe_u32 v104, v75, 16, 1
	v_add3_u32 v104, v75, v104, s26
	v_bfe_u32 v98, v7, 16, 1
	v_add3_u32 v98, v7, v98, s26
	v_bfe_u32 v99, v3, 16, 1
	v_lshrrev_b32_e32 v98, 16, v98
	v_add3_u32 v99, v3, v99, s26
	v_and_or_b32 v98, v99, s27, v98
	v_bfe_u32 v99, v27, 16, 1
	v_add3_u32 v99, v27, v99, s26
	v_bfe_u32 v100, v23, 16, 1
	v_lshrrev_b32_e32 v99, 16, v99
	v_add3_u32 v100, v23, v100, s26
	v_and_or_b32 v99, v100, s27, v99
	v_bfe_u32 v100, v51, 16, 1
	v_add3_u32 v100, v51, v100, s26
	v_bfe_u32 v101, v15, 16, 1
	v_lshrrev_b32_e32 v100, 16, v100
	v_add3_u32 v101, v15, v101, s26
	v_and_or_b32 v100, v101, s27, v100
	v_bfe_u32 v101, v71, 16, 1
	v_add3_u32 v101, v71, v101, s26
	v_lshrrev_b32_e32 v101, 16, v101
	v_and_or_b32 v101, v104, s27, v101
	v_add_co_u32_e32 v104, vcc, s15, v102
	s_nop 1
	v_addc_co_u32_e32 v105, vcc, 0, v103, vcc
	global_store_dwordx4 v[104:105], v[98:101], off nt
	v_bfe_u32 v104, v76, 16, 1
	v_add3_u32 v104, v76, v104, s26
	v_bfe_u32 v98, v8, 16, 1
	v_add3_u32 v98, v8, v98, s26
	v_bfe_u32 v99, v4, 16, 1
	v_lshrrev_b32_e32 v98, 16, v98
	v_add3_u32 v99, v4, v99, s26
	v_and_or_b32 v98, v99, s27, v98
	v_bfe_u32 v99, v28, 16, 1
	v_add3_u32 v99, v28, v99, s26
	v_bfe_u32 v100, v24, 16, 1
	v_lshrrev_b32_e32 v99, 16, v99
	v_add3_u32 v100, v24, v100, s26
	v_and_or_b32 v99, v100, s27, v99
	v_bfe_u32 v100, v52, 16, 1
	v_add3_u32 v100, v52, v100, s26
	v_bfe_u32 v101, v16, 16, 1
	v_lshrrev_b32_e32 v100, 16, v100
	v_add3_u32 v101, v16, v101, s26
	v_and_or_b32 v100, v101, s27, v100
	v_bfe_u32 v101, v72, 16, 1
	v_add3_u32 v101, v72, v101, s26
	v_lshrrev_b32_e32 v101, 16, v101
	v_and_or_b32 v101, v104, s27, v101
	v_add_co_u32_e32 v104, vcc, s28, v102
	s_nop 1
	v_addc_co_u32_e32 v105, vcc, 0, v103, vcc
	global_store_dwordx4 v[104:105], v[98:101], off nt
	v_bfe_u32 v104, v77, 16, 1
	v_add3_u32 v104, v77, v104, s26
	v_bfe_u32 v98, v9, 16, 1
	v_add3_u32 v98, v9, v98, s26
	v_bfe_u32 v99, v5, 16, 1
	v_lshrrev_b32_e32 v98, 16, v98
	v_add3_u32 v99, v5, v99, s26
	v_and_or_b32 v98, v99, s27, v98
	v_bfe_u32 v99, v29, 16, 1
	v_add3_u32 v99, v29, v99, s26
	v_bfe_u32 v100, v25, 16, 1
	v_lshrrev_b32_e32 v99, 16, v99
	v_add3_u32 v100, v25, v100, s26
	v_and_or_b32 v99, v100, s27, v99
	v_bfe_u32 v100, v53, 16, 1
	v_add3_u32 v100, v53, v100, s26
	v_bfe_u32 v101, v17, 16, 1
	v_lshrrev_b32_e32 v100, 16, v100
	v_add3_u32 v101, v17, v101, s26
	v_and_or_b32 v100, v101, s27, v100
	v_bfe_u32 v101, v73, 16, 1
	v_add3_u32 v101, v73, v101, s26
	v_lshrrev_b32_e32 v101, 16, v101
	v_add_co_u32_e32 v102, vcc, 0x9000, v102
	v_and_or_b32 v101, v104, s27, v101
	s_nop 0
	v_addc_co_u32_e32 v103, vcc, 0, v103, vcc
	global_store_dwordx4 v[102:103], v[98:101], off nt
	s_branch .LBB0_472

.LBB0_568:
	s_waitcnt vmcnt(1)
	v_bfe_u32 v130, v102, 16, 1
	v_mov_b64_e32 v[140:141], s[18:19]
	v_add3_u32 v102, v102, v130, s26
	s_waitcnt vmcnt(0)
	v_bfe_u32 v130, v98, 16, 1
	v_mad_i64_i32 v[140:141], s[6:7], v139, s15, v[140:141]
	v_lshrrev_b32_e32 v102, 16, v102
	v_add3_u32 v98, v98, v130, s26
	v_lshl_add_u64 v[132:133], v[132:133], 1, v[140:141]
	v_and_or_b32 v140, v98, s27, v102
	v_bfe_u32 v98, v114, 16, 1
	v_add3_u32 v98, v114, v98, s26
	v_bfe_u32 v102, v110, 16, 1
	v_lshrrev_b32_e32 v98, 16, v98
	v_add3_u32 v102, v110, v102, s26
	v_and_or_b32 v141, v102, s27, v98
	v_bfe_u32 v98, v118, 16, 1
	v_add3_u32 v98, v118, v98, s26
	v_bfe_u32 v102, v106, 16, 1
	v_lshrrev_b32_e32 v98, 16, v98
	v_add3_u32 v102, v106, v102, s26
	v_and_or_b32 v142, v102, s27, v98
	v_bfe_u32 v98, v126, 16, 1
	v_add3_u32 v98, v126, v98, s26
	v_bfe_u32 v102, v122, 16, 1
	v_lshrrev_b32_e32 v98, 16, v98
	v_add3_u32 v102, v122, v102, s26
	v_and_or_b32 v143, v102, s27, v98
	v_bfe_u32 v98, v103, 16, 1
	v_add3_u32 v98, v103, v98, s26
	v_bfe_u32 v102, v99, 16, 1
	v_lshrrev_b32_e32 v98, 16, v98
	v_add3_u32 v99, v99, v102, s26
	global_store_dwordx4 v[132:133], v[140:143], off nt
	v_bfe_u32 v102, v125, 16, 1
	v_add3_u32 v102, v125, v102, s26
	v_and_or_b32 v140, v99, s27, v98
	v_bfe_u32 v98, v115, 16, 1
	v_add3_u32 v98, v115, v98, s26
	v_bfe_u32 v99, v111, 16, 1
	v_lshrrev_b32_e32 v98, 16, v98
	v_add3_u32 v99, v111, v99, s26
	v_and_or_b32 v141, v99, s27, v98
	v_bfe_u32 v98, v119, 16, 1
	v_add3_u32 v98, v119, v98, s26
	v_bfe_u32 v99, v107, 16, 1
	v_lshrrev_b32_e32 v98, 16, v98
	v_add3_u32 v99, v107, v99, s26
	v_and_or_b32 v142, v99, s27, v98
	v_bfe_u32 v98, v127, 16, 1
	v_add3_u32 v98, v127, v98, s26
	v_bfe_u32 v99, v123, 16, 1
	v_lshrrev_b32_e32 v98, 16, v98
	v_add3_u32 v99, v123, v99, s26
	v_and_or_b32 v143, v99, s27, v98
	v_add_co_u32_e32 v98, vcc, s15, v132
	s_nop 1
	v_addc_co_u32_e32 v99, vcc, 0, v133, vcc
	global_store_dwordx4 v[98:99], v[140:143], off nt
	v_bfe_u32 v98, v104, 16, 1
	v_add3_u32 v98, v104, v98, s26
	v_bfe_u32 v99, v100, 16, 1
	v_lshrrev_b32_e32 v98, 16, v98
	v_add3_u32 v99, v100, v99, s26
	v_and_or_b32 v140, v99, s27, v98
	v_bfe_u32 v98, v116, 16, 1
	v_add3_u32 v98, v116, v98, s26
	v_bfe_u32 v99, v112, 16, 1
	v_lshrrev_b32_e32 v98, 16, v98
	v_add3_u32 v99, v112, v99, s26
	v_and_or_b32 v141, v99, s27, v98
	v_bfe_u32 v98, v120, 16, 1
	v_add3_u32 v98, v120, v98, s26
	v_bfe_u32 v99, v108, 16, 1
	v_lshrrev_b32_e32 v98, 16, v98
	v_add3_u32 v99, v108, v99, s26
	v_and_or_b32 v142, v99, s27, v98
	v_bfe_u32 v98, v128, 16, 1
	v_add3_u32 v98, v128, v98, s26
	v_bfe_u32 v99, v124, 16, 1
	v_lshrrev_b32_e32 v98, 16, v98
	v_add3_u32 v99, v124, v99, s26
	v_and_or_b32 v143, v99, s27, v98
	v_add_co_u32_e32 v98, vcc, s28, v132
	v_bfe_u32 v100, v113, 16, 1
	s_nop 0
	v_addc_co_u32_e32 v99, vcc, 0, v133, vcc
	global_store_dwordx4 v[98:99], v[140:143], off nt
	v_bfe_u32 v98, v105, 16, 1
	v_add3_u32 v98, v105, v98, s26
	v_bfe_u32 v99, v101, 16, 1
	v_lshrrev_b32_e32 v98, 16, v98
	v_add3_u32 v99, v101, v99, s26
	v_and_or_b32 v98, v99, s27, v98
	v_bfe_u32 v99, v117, 16, 1
	v_add3_u32 v99, v117, v99, s26
	v_lshrrev_b32_e32 v99, 16, v99
	v_add3_u32 v100, v113, v100, s26
	v_and_or_b32 v99, v100, s27, v99
	v_bfe_u32 v100, v121, 16, 1
	v_add3_u32 v100, v121, v100, s26
	v_bfe_u32 v101, v109, 16, 1
	v_lshrrev_b32_e32 v100, 16, v100
	v_add3_u32 v101, v109, v101, s26
	v_and_or_b32 v100, v101, s27, v100
	v_bfe_u32 v101, v129, 16, 1
	v_add3_u32 v101, v129, v101, s26
	v_lshrrev_b32_e32 v101, 16, v101
	v_and_or_b32 v101, v102, s27, v101
	v_add_co_u32_e32 v102, vcc, 0x9000, v132
	s_nop 1
	v_addc_co_u32_e32 v103, vcc, 0, v133, vcc
	s_andn2_b64 vcc, exec, s[20:21]
	global_store_dwordx4 v[102:103], v[98:101], off nt
	s_cbranch_vccnz .LBB0_571
	s_ashr_i32 s6, s30, 31
	s_lshr_b32 s6, s6, 25
	s_add_i32 s30, s30, s6
	s_ashr_i32 s6, s30, 7
	v_lshl_or_b32 v98, s6, 6, v134
	v_add_u32_e32 v100, s0, v138
	s_lshl_b32 s6, s6, 12
	v_subrev_u32_e32 v102, s6, v100
	v_mov_b64_e32 v[100:101], s[18:19]
	v_ashrrev_i32_e32 v99, 31, v98
	v_mad_i64_i32 v[100:101], s[6:7], v102, s15, v[100:101]
	v_lshl_add_u64 v[102:103], v[98:99], 1, v[100:101]
	v_bfe_u32 v98, v38, 16, 1
	v_add3_u32 v98, v38, v98, s26
	v_bfe_u32 v99, v30, 16, 1
	v_lshrrev_b32_e32 v98, 16, v98
	v_add3_u32 v99, v30, v99, s26
	v_and_or_b32 v98, v99, s27, v98
	v_bfe_u32 v99, v62, 16, 1
	v_add3_u32 v99, v62, v99, s26
	v_bfe_u32 v100, v58, 16, 1
	v_lshrrev_b32_e32 v99, 16, v99
	v_add3_u32 v100, v58, v100, s26
	v_and_or_b32 v99, v100, s27, v99
	v_bfe_u32 v100, v78, 16, 1
	v_add3_u32 v100, v78, v100, s26
	v_bfe_u32 v101, v54, 16, 1
	v_lshrrev_b32_e32 v100, 16, v100
	v_add3_u32 v101, v54, v101, s26
	v_and_or_b32 v100, v101, s27, v100
	v_bfe_u32 v101, v90, 16, 1
	v_add3_u32 v101, v90, v101, s26
	v_bfe_u32 v104, v94, 16, 1
	v_lshrrev_b32_e32 v101, 16, v101
	v_add3_u32 v104, v94, v104, s26
	v_and_or_b32 v101, v104, s27, v101
	global_store_dwordx4 v[102:103], v[98:101], off nt
	v_bfe_u32 v104, v95, 16, 1
	v_add3_u32 v104, v95, v104, s26
	v_bfe_u32 v98, v39, 16, 1
	v_add3_u32 v98, v39, v98, s26
	v_bfe_u32 v99, v31, 16, 1
	v_lshrrev_b32_e32 v98, 16, v98
	v_add3_u32 v99, v31, v99, s26
	v_and_or_b32 v98, v99, s27, v98
	v_bfe_u32 v99, v63, 16, 1
	v_add3_u32 v99, v63, v99, s26
	v_bfe_u32 v100, v59, 16, 1
	v_lshrrev_b32_e32 v99, 16, v99
	v_add3_u32 v100, v59, v100, s26
	v_and_or_b32 v99, v100, s27, v99
	v_bfe_u32 v100, v79, 16, 1
	v_add3_u32 v100, v79, v100, s26
	v_bfe_u32 v101, v55, 16, 1
	v_lshrrev_b32_e32 v100, 16, v100
	v_add3_u32 v101, v55, v101, s26
	v_and_or_b32 v100, v101, s27, v100
	v_bfe_u32 v101, v91, 16, 1
	v_add3_u32 v101, v91, v101, s26
	v_lshrrev_b32_e32 v101, 16, v101
	v_and_or_b32 v101, v104, s27, v101
	v_add_co_u32_e32 v104, vcc, s15, v102
	s_nop 1
	v_addc_co_u32_e32 v105, vcc, 0, v103, vcc
	global_store_dwordx4 v[104:105], v[98:101], off nt
	v_bfe_u32 v104, v96, 16, 1
	v_add3_u32 v104, v96, v104, s26
	v_bfe_u32 v98, v40, 16, 1
	v_add3_u32 v98, v40, v98, s26
	v_bfe_u32 v99, v32, 16, 1
	v_lshrrev_b32_e32 v98, 16, v98
	v_add3_u32 v99, v32, v99, s26
	v_and_or_b32 v98, v99, s27, v98
	v_bfe_u32 v99, v64, 16, 1
	v_add3_u32 v99, v64, v99, s26
	v_bfe_u32 v100, v60, 16, 1
	v_lshrrev_b32_e32 v99, 16, v99
	v_add3_u32 v100, v60, v100, s26
	v_and_or_b32 v99, v100, s27, v99
	v_bfe_u32 v100, v80, 16, 1
	v_add3_u32 v100, v80, v100, s26
	v_bfe_u32 v101, v56, 16, 1
	v_lshrrev_b32_e32 v100, 16, v100
	v_add3_u32 v101, v56, v101, s26
	v_and_or_b32 v100, v101, s27, v100
	v_bfe_u32 v101, v92, 16, 1
	v_add3_u32 v101, v92, v101, s26
	v_lshrrev_b32_e32 v101, 16, v101
	v_and_or_b32 v101, v104, s27, v101
	v_add_co_u32_e32 v104, vcc, s28, v102
	s_nop 1
	v_addc_co_u32_e32 v105, vcc, 0, v103, vcc
	global_store_dwordx4 v[104:105], v[98:101], off nt
	v_bfe_u32 v104, v97, 16, 1
	v_add3_u32 v104, v97, v104, s26
	v_bfe_u32 v98, v41, 16, 1
	v_add3_u32 v98, v41, v98, s26
	v_bfe_u32 v99, v33, 16, 1
	v_lshrrev_b32_e32 v98, 16, v98
	v_add3_u32 v99, v33, v99, s26
	v_and_or_b32 v98, v99, s27, v98
	v_bfe_u32 v99, v65, 16, 1
	v_add3_u32 v99, v65, v99, s26
	v_bfe_u32 v100, v61, 16, 1
	v_lshrrev_b32_e32 v99, 16, v99
	v_add3_u32 v100, v61, v100, s26
	v_and_or_b32 v99, v100, s27, v99
	v_bfe_u32 v100, v81, 16, 1
	v_add3_u32 v100, v81, v100, s26
	v_bfe_u32 v101, v57, 16, 1
	v_lshrrev_b32_e32 v100, 16, v100
	v_add3_u32 v101, v57, v101, s26
	v_and_or_b32 v100, v101, s27, v100
	v_bfe_u32 v101, v93, 16, 1
	v_add3_u32 v101, v93, v101, s26
	v_lshrrev_b32_e32 v101, 16, v101
	v_add_co_u32_e32 v102, vcc, 0x9000, v102
	v_and_or_b32 v101, v104, s27, v101
	s_nop 0
	v_addc_co_u32_e32 v103, vcc, 0, v103, vcc
	global_store_dwordx4 v[102:103], v[98:101], off nt
	s_andn2_b64 vcc, exec, s[22:23]
	s_cbranch_vccz .LBB0_572

.LBB0_572:
	s_ashr_i32 s6, s31, 31
	s_lshr_b32 s6, s6, 25
	s_add_i32 s31, s31, s6
	s_ashr_i32 s6, s31, 7
	v_lshl_or_b32 v98, s6, 6, v134
	v_add_u32_e32 v100, s0, v136
	s_lshl_b32 s6, s6, 12
	v_subrev_u32_e32 v102, s6, v100
	v_mov_b64_e32 v[100:101], s[18:19]
	v_ashrrev_i32_e32 v99, 31, v98
	v_mad_i64_i32 v[100:101], s[6:7], v102, s15, v[100:101]
	v_lshl_add_u64 v[102:103], v[98:99], 1, v[100:101]
	v_bfe_u32 v98, v18, 16, 1
	v_add3_u32 v98, v18, v98, s26
	v_bfe_u32 v99, v10, 16, 1
	v_lshrrev_b32_e32 v98, 16, v98
	v_add3_u32 v99, v10, v99, s26
	v_and_or_b32 v98, v99, s27, v98
	v_bfe_u32 v99, v46, 16, 1
	v_add3_u32 v99, v46, v99, s26
	v_bfe_u32 v100, v42, 16, 1
	v_lshrrev_b32_e32 v99, 16, v99
	v_add3_u32 v100, v42, v100, s26
	v_and_or_b32 v99, v100, s27, v99
	v_bfe_u32 v100, v66, 16, 1
	v_add3_u32 v100, v66, v100, s26
	v_bfe_u32 v101, v34, 16, 1
	v_lshrrev_b32_e32 v100, 16, v100
	v_add3_u32 v101, v34, v101, s26
	v_and_or_b32 v100, v101, s27, v100
	v_bfe_u32 v101, v82, 16, 1
	v_add3_u32 v101, v82, v101, s26
	v_bfe_u32 v104, v86, 16, 1
	v_lshrrev_b32_e32 v101, 16, v101
	v_add3_u32 v104, v86, v104, s26
	v_and_or_b32 v101, v104, s27, v101
	global_store_dwordx4 v[102:103], v[98:101], off nt
	v_bfe_u32 v104, v87, 16, 1
	v_add3_u32 v104, v87, v104, s26
	v_bfe_u32 v98, v19, 16, 1
	v_add3_u32 v98, v19, v98, s26
	v_bfe_u32 v99, v11, 16, 1
	v_lshrrev_b32_e32 v98, 16, v98
	v_add3_u32 v99, v11, v99, s26
	v_and_or_b32 v98, v99, s27, v98
	v_bfe_u32 v99, v47, 16, 1
	v_add3_u32 v99, v47, v99, s26
	v_bfe_u32 v100, v43, 16, 1
	v_lshrrev_b32_e32 v99, 16, v99
	v_add3_u32 v100, v43, v100, s26
	v_and_or_b32 v99, v100, s27, v99
	v_bfe_u32 v100, v67, 16, 1
	v_add3_u32 v100, v67, v100, s26
	v_bfe_u32 v101, v35, 16, 1
	v_lshrrev_b32_e32 v100, 16, v100
	v_add3_u32 v101, v35, v101, s26
	v_and_or_b32 v100, v101, s27, v100
	v_bfe_u32 v101, v83, 16, 1
	v_add3_u32 v101, v83, v101, s26
	v_lshrrev_b32_e32 v101, 16, v101
	v_and_or_b32 v101, v104, s27, v101
	v_add_co_u32_e32 v104, vcc, s15, v102
	s_nop 1
	v_addc_co_u32_e32 v105, vcc, 0, v103, vcc
	global_store_dwordx4 v[104:105], v[98:101], off nt
	v_bfe_u32 v104, v88, 16, 1
	v_add3_u32 v104, v88, v104, s26
	v_bfe_u32 v98, v20, 16, 1
	v_add3_u32 v98, v20, v98, s26
	v_bfe_u32 v99, v12, 16, 1
	v_lshrrev_b32_e32 v98, 16, v98
	v_add3_u32 v99, v12, v99, s26
	v_and_or_b32 v98, v99, s27, v98
	v_bfe_u32 v99, v48, 16, 1
	v_add3_u32 v99, v48, v99, s26
	v_bfe_u32 v100, v44, 16, 1
	v_lshrrev_b32_e32 v99, 16, v99
	v_add3_u32 v100, v44, v100, s26
	v_and_or_b32 v99, v100, s27, v99
	v_bfe_u32 v100, v68, 16, 1
	v_add3_u32 v100, v68, v100, s26
	v_bfe_u32 v101, v36, 16, 1
	v_lshrrev_b32_e32 v100, 16, v100
	v_add3_u32 v101, v36, v101, s26
	v_and_or_b32 v100, v101, s27, v100
	v_bfe_u32 v101, v84, 16, 1
	v_add3_u32 v101, v84, v101, s26
	v_lshrrev_b32_e32 v101, 16, v101
	v_and_or_b32 v101, v104, s27, v101
	v_add_co_u32_e32 v104, vcc, s28, v102
	s_nop 1
	v_addc_co_u32_e32 v105, vcc, 0, v103, vcc
	global_store_dwordx4 v[104:105], v[98:101], off nt
	v_bfe_u32 v104, v89, 16, 1
	v_add3_u32 v104, v89, v104, s26
	v_bfe_u32 v98, v21, 16, 1
	v_add3_u32 v98, v21, v98, s26
	v_bfe_u32 v99, v13, 16, 1
	v_lshrrev_b32_e32 v98, 16, v98
	v_add3_u32 v99, v13, v99, s26
	v_and_or_b32 v98, v99, s27, v98
	v_bfe_u32 v99, v49, 16, 1
	v_add3_u32 v99, v49, v99, s26
	v_bfe_u32 v100, v45, 16, 1
	v_lshrrev_b32_e32 v99, 16, v99
	v_add3_u32 v100, v45, v100, s26
	v_and_or_b32 v99, v100, s27, v99
	v_bfe_u32 v100, v69, 16, 1
	v_add3_u32 v100, v69, v100, s26
	v_bfe_u32 v101, v37, 16, 1
	v_lshrrev_b32_e32 v100, 16, v100
	v_add3_u32 v101, v37, v101, s26
	v_and_or_b32 v100, v101, s27, v100
	v_bfe_u32 v101, v85, 16, 1
	v_add3_u32 v101, v85, v101, s26
	v_lshrrev_b32_e32 v101, 16, v101
	v_add_co_u32_e32 v102, vcc, 0x9000, v102
	v_and_or_b32 v101, v104, s27, v101
	s_nop 0
	v_addc_co_u32_e32 v103, vcc, 0, v103, vcc
	global_store_dwordx4 v[102:103], v[98:101], off nt
	s_andn2_b64 vcc, exec, s[24:25]
	s_cbranch_vccnz .LBB0_524
.LBB0_573:
	s_ashr_i32 s6, s33, 31
	s_lshr_b32 s6, s6, 25
	s_add_i32 s33, s33, s6
	s_ashr_i32 s6, s33, 7
	v_lshl_or_b32 v98, s6, 6, v134
	v_add_u32_e32 v100, s0, v137
	s_lshl_b32 s6, s6, 12
	v_subrev_u32_e32 v102, s6, v100
	v_mov_b64_e32 v[100:101], s[18:19]
	v_ashrrev_i32_e32 v99, 31, v98
	v_mad_i64_i32 v[100:101], s[6:7], v102, s15, v[100:101]
	v_lshl_add_u64 v[102:103], v[98:99], 1, v[100:101]
	v_bfe_u32 v98, v6, 16, 1
	v_add3_u32 v98, v6, v98, s26
	v_bfe_u32 v99, v2, 16, 1
	v_lshrrev_b32_e32 v98, 16, v98
	v_add3_u32 v99, v2, v99, s26
	v_and_or_b32 v98, v99, s27, v98
	v_bfe_u32 v99, v26, 16, 1
	v_add3_u32 v99, v26, v99, s26
	v_bfe_u32 v100, v22, 16, 1
	v_lshrrev_b32_e32 v99, 16, v99
	v_add3_u32 v100, v22, v100, s26
	v_and_or_b32 v99, v100, s27, v99
	v_bfe_u32 v100, v50, 16, 1
	v_add3_u32 v100, v50, v100, s26
	v_bfe_u32 v101, v14, 16, 1
	v_lshrrev_b32_e32 v100, 16, v100
	v_add3_u32 v101, v14, v101, s26
	v_and_or_b32 v100, v101, s27, v100
	v_bfe_u32 v101, v70, 16, 1
	v_add3_u32 v101, v70, v101, s26
	v_bfe_u32 v104, v74, 16, 1
	v_lshrrev_b32_e32 v101, 16, v101
	v_add3_u32 v104, v74, v104, s26
	v_and_or_b32 v101, v104, s27, v101
	global_store_dwordx4 v[102:103], v[98:101], off nt
	v_bfe_u32 v104, v75, 16, 1
	v_add3_u32 v104, v75, v104, s26
	v_bfe_u32 v98, v7, 16, 1
	v_add3_u32 v98, v7, v98, s26
	v_bfe_u32 v99, v3, 16, 1
	v_lshrrev_b32_e32 v98, 16, v98
	v_add3_u32 v99, v3, v99, s26
	v_and_or_b32 v98, v99, s27, v98
	v_bfe_u32 v99, v27, 16, 1
	v_add3_u32 v99, v27, v99, s26
	v_bfe_u32 v100, v23, 16, 1
	v_lshrrev_b32_e32 v99, 16, v99
	v_add3_u32 v100, v23, v100, s26
	v_and_or_b32 v99, v100, s27, v99
	v_bfe_u32 v100, v51, 16, 1
	v_add3_u32 v100, v51, v100, s26
	v_bfe_u32 v101, v15, 16, 1
	v_lshrrev_b32_e32 v100, 16, v100
	v_add3_u32 v101, v15, v101, s26
	v_and_or_b32 v100, v101, s27, v100
	v_bfe_u32 v101, v71, 16, 1
	v_add3_u32 v101, v71, v101, s26
	v_lshrrev_b32_e32 v101, 16, v101
	v_and_or_b32 v101, v104, s27, v101
	v_add_co_u32_e32 v104, vcc, s15, v102
	s_nop 1
	v_addc_co_u32_e32 v105, vcc, 0, v103, vcc
	global_store_dwordx4 v[104:105], v[98:101], off nt
	v_bfe_u32 v104, v76, 16, 1
	v_add3_u32 v104, v76, v104, s26
	v_bfe_u32 v98, v8, 16, 1
	v_add3_u32 v98, v8, v98, s26
	v_bfe_u32 v99, v4, 16, 1
	v_lshrrev_b32_e32 v98, 16, v98
	v_add3_u32 v99, v4, v99, s26
	v_and_or_b32 v98, v99, s27, v98
	v_bfe_u32 v99, v28, 16, 1
	v_add3_u32 v99, v28, v99, s26
	v_bfe_u32 v100, v24, 16, 1
	v_lshrrev_b32_e32 v99, 16, v99
	v_add3_u32 v100, v24, v100, s26
	v_and_or_b32 v99, v100, s27, v99
	v_bfe_u32 v100, v52, 16, 1
	v_add3_u32 v100, v52, v100, s26
	v_bfe_u32 v101, v16, 16, 1
	v_lshrrev_b32_e32 v100, 16, v100
	v_add3_u32 v101, v16, v101, s26
	v_and_or_b32 v100, v101, s27, v100
	v_bfe_u32 v101, v72, 16, 1
	v_add3_u32 v101, v72, v101, s26
	v_lshrrev_b32_e32 v101, 16, v101
	v_and_or_b32 v101, v104, s27, v101
	v_add_co_u32_e32 v104, vcc, s28, v102
	s_nop 1
	v_addc_co_u32_e32 v105, vcc, 0, v103, vcc
	global_store_dwordx4 v[104:105], v[98:101], off nt
	v_bfe_u32 v104, v77, 16, 1
	v_add3_u32 v104, v77, v104, s26
	v_bfe_u32 v98, v9, 16, 1
	v_add3_u32 v98, v9, v98, s26
	v_bfe_u32 v99, v5, 16, 1
	v_lshrrev_b32_e32 v98, 16, v98
	v_add3_u32 v99, v5, v99, s26
	v_and_or_b32 v98, v99, s27, v98
	v_bfe_u32 v99, v29, 16, 1
	v_add3_u32 v99, v29, v99, s26
	v_bfe_u32 v100, v25, 16, 1
	v_lshrrev_b32_e32 v99, 16, v99
	v_add3_u32 v100, v25, v100, s26
	v_and_or_b32 v99, v100, s27, v99
	v_bfe_u32 v100, v53, 16, 1
	v_add3_u32 v100, v53, v100, s26
	v_bfe_u32 v101, v17, 16, 1
	v_lshrrev_b32_e32 v100, 16, v100
	v_add3_u32 v101, v17, v101, s26
	v_and_or_b32 v100, v101, s27, v100
	v_bfe_u32 v101, v73, 16, 1
	v_add3_u32 v101, v73, v101, s26
	v_lshrrev_b32_e32 v101, 16, v101
	v_add_co_u32_e32 v102, vcc, 0x9000, v102
	v_and_or_b32 v101, v104, s27, v101
	s_nop 0
	v_addc_co_u32_e32 v103, vcc, 0, v103, vcc
	global_store_dwordx4 v[102:103], v[98:101], off nt
	s_branch .LBB0_524

.LBB0_620:
	s_waitcnt vmcnt(1)
	v_bfe_u32 v130, v102, 16, 1
	v_mov_b64_e32 v[140:141], s[16:17]
	v_add3_u32 v102, v102, v130, s24
	s_waitcnt vmcnt(0)
	v_bfe_u32 v130, v98, 16, 1
	v_mad_i64_i32 v[140:141], s[4:5], v139, s15, v[140:141]
	v_lshrrev_b32_e32 v102, 16, v102
	v_add3_u32 v98, v98, v130, s24
	v_lshl_add_u64 v[132:133], v[132:133], 1, v[140:141]
	v_and_or_b32 v140, v98, s25, v102
	v_bfe_u32 v98, v114, 16, 1
	v_add3_u32 v98, v114, v98, s24
	v_bfe_u32 v102, v110, 16, 1
	v_lshrrev_b32_e32 v98, 16, v98
	v_add3_u32 v102, v110, v102, s24
	v_and_or_b32 v141, v102, s25, v98
	v_bfe_u32 v98, v118, 16, 1
	v_add3_u32 v98, v118, v98, s24
	v_bfe_u32 v102, v106, 16, 1
	v_lshrrev_b32_e32 v98, 16, v98
	v_add3_u32 v102, v106, v102, s24
	v_and_or_b32 v142, v102, s25, v98
	v_bfe_u32 v98, v126, 16, 1
	v_add3_u32 v98, v126, v98, s24
	v_bfe_u32 v102, v122, 16, 1
	v_lshrrev_b32_e32 v98, 16, v98
	v_add3_u32 v102, v122, v102, s24
	v_and_or_b32 v143, v102, s25, v98
	v_bfe_u32 v98, v103, 16, 1
	v_add3_u32 v98, v103, v98, s24
	v_bfe_u32 v102, v99, 16, 1
	v_lshrrev_b32_e32 v98, 16, v98
	v_add3_u32 v99, v99, v102, s24
	global_store_dwordx4 v[132:133], v[140:143], off nt
	v_bfe_u32 v102, v125, 16, 1
	v_add3_u32 v102, v125, v102, s24
	v_and_or_b32 v140, v99, s25, v98
	v_bfe_u32 v98, v115, 16, 1
	v_add3_u32 v98, v115, v98, s24
	v_bfe_u32 v99, v111, 16, 1
	v_lshrrev_b32_e32 v98, 16, v98
	v_add3_u32 v99, v111, v99, s24
	v_and_or_b32 v141, v99, s25, v98
	v_bfe_u32 v98, v119, 16, 1
	v_add3_u32 v98, v119, v98, s24
	v_bfe_u32 v99, v107, 16, 1
	v_lshrrev_b32_e32 v98, 16, v98
	v_add3_u32 v99, v107, v99, s24
	v_and_or_b32 v142, v99, s25, v98
	v_bfe_u32 v98, v127, 16, 1
	v_add3_u32 v98, v127, v98, s24
	v_bfe_u32 v99, v123, 16, 1
	v_lshrrev_b32_e32 v98, 16, v98
	v_add3_u32 v99, v123, v99, s24
	v_and_or_b32 v143, v99, s25, v98
	v_add_co_u32_e32 v98, vcc, s15, v132
	s_nop 1
	v_addc_co_u32_e32 v99, vcc, 0, v133, vcc
	global_store_dwordx4 v[98:99], v[140:143], off nt
	v_bfe_u32 v98, v104, 16, 1
	v_add3_u32 v98, v104, v98, s24
	v_bfe_u32 v99, v100, 16, 1
	v_lshrrev_b32_e32 v98, 16, v98
	v_add3_u32 v99, v100, v99, s24
	v_and_or_b32 v140, v99, s25, v98
	v_bfe_u32 v98, v116, 16, 1
	v_add3_u32 v98, v116, v98, s24
	v_bfe_u32 v99, v112, 16, 1
	v_lshrrev_b32_e32 v98, 16, v98
	v_add3_u32 v99, v112, v99, s24
	v_and_or_b32 v141, v99, s25, v98
	v_bfe_u32 v98, v120, 16, 1
	v_add3_u32 v98, v120, v98, s24
	v_bfe_u32 v99, v108, 16, 1
	v_lshrrev_b32_e32 v98, 16, v98
	v_add3_u32 v99, v108, v99, s24
	v_and_or_b32 v142, v99, s25, v98
	v_bfe_u32 v98, v128, 16, 1
	v_add3_u32 v98, v128, v98, s24
	v_bfe_u32 v99, v124, 16, 1
	v_lshrrev_b32_e32 v98, 16, v98
	v_add3_u32 v99, v124, v99, s24
	v_and_or_b32 v143, v99, s25, v98
	v_add_co_u32_e32 v98, vcc, s26, v132
	v_bfe_u32 v100, v113, 16, 1
	s_nop 0
	v_addc_co_u32_e32 v99, vcc, 0, v133, vcc
	global_store_dwordx4 v[98:99], v[140:143], off nt
	v_bfe_u32 v98, v105, 16, 1
	v_add3_u32 v98, v105, v98, s24
	v_bfe_u32 v99, v101, 16, 1
	v_lshrrev_b32_e32 v98, 16, v98
	v_add3_u32 v99, v101, v99, s24
	v_and_or_b32 v98, v99, s25, v98
	v_bfe_u32 v99, v117, 16, 1
	v_add3_u32 v99, v117, v99, s24
	v_lshrrev_b32_e32 v99, 16, v99
	v_add3_u32 v100, v113, v100, s24
	v_and_or_b32 v99, v100, s25, v99
	v_bfe_u32 v100, v121, 16, 1
	v_add3_u32 v100, v121, v100, s24
	v_bfe_u32 v101, v109, 16, 1
	v_lshrrev_b32_e32 v100, 16, v100
	v_add3_u32 v101, v109, v101, s24
	v_and_or_b32 v100, v101, s25, v100
	v_bfe_u32 v101, v129, 16, 1
	v_add3_u32 v101, v129, v101, s24
	v_lshrrev_b32_e32 v101, 16, v101
	v_and_or_b32 v101, v102, s25, v101
	v_add_co_u32_e32 v102, vcc, 0x9000, v132
	s_nop 1
	v_addc_co_u32_e32 v103, vcc, 0, v133, vcc
	s_andn2_b64 vcc, exec, s[18:19]
	global_store_dwordx4 v[102:103], v[98:101], off nt
	s_cbranch_vccnz .LBB0_623
	s_ashr_i32 s4, s28, 31
	s_lshr_b32 s4, s4, 25
	s_add_i32 s28, s28, s4
	s_ashr_i32 s4, s28, 7
	v_lshl_or_b32 v98, s4, 6, v134
	v_add_u32_e32 v100, s0, v138
	s_lshl_b32 s4, s4, 12
	v_subrev_u32_e32 v102, s4, v100
	v_mov_b64_e32 v[100:101], s[16:17]
	v_ashrrev_i32_e32 v99, 31, v98
	v_mad_i64_i32 v[100:101], s[4:5], v102, s15, v[100:101]
	v_lshl_add_u64 v[102:103], v[98:99], 1, v[100:101]
	v_bfe_u32 v98, v38, 16, 1
	v_add3_u32 v98, v38, v98, s24
	v_bfe_u32 v99, v30, 16, 1
	v_lshrrev_b32_e32 v98, 16, v98
	v_add3_u32 v99, v30, v99, s24
	v_and_or_b32 v98, v99, s25, v98
	v_bfe_u32 v99, v62, 16, 1
	v_add3_u32 v99, v62, v99, s24
	v_bfe_u32 v100, v58, 16, 1
	v_lshrrev_b32_e32 v99, 16, v99
	v_add3_u32 v100, v58, v100, s24
	v_and_or_b32 v99, v100, s25, v99
	v_bfe_u32 v100, v78, 16, 1
	v_add3_u32 v100, v78, v100, s24
	v_bfe_u32 v101, v54, 16, 1
	v_lshrrev_b32_e32 v100, 16, v100
	v_add3_u32 v101, v54, v101, s24
	v_and_or_b32 v100, v101, s25, v100
	v_bfe_u32 v101, v90, 16, 1
	v_add3_u32 v101, v90, v101, s24
	v_bfe_u32 v104, v94, 16, 1
	v_lshrrev_b32_e32 v101, 16, v101
	v_add3_u32 v104, v94, v104, s24
	v_and_or_b32 v101, v104, s25, v101
	global_store_dwordx4 v[102:103], v[98:101], off nt
	v_bfe_u32 v104, v95, 16, 1
	v_add3_u32 v104, v95, v104, s24
	v_bfe_u32 v98, v39, 16, 1
	v_add3_u32 v98, v39, v98, s24
	v_bfe_u32 v99, v31, 16, 1
	v_lshrrev_b32_e32 v98, 16, v98
	v_add3_u32 v99, v31, v99, s24
	v_and_or_b32 v98, v99, s25, v98
	v_bfe_u32 v99, v63, 16, 1
	v_add3_u32 v99, v63, v99, s24
	v_bfe_u32 v100, v59, 16, 1
	v_lshrrev_b32_e32 v99, 16, v99
	v_add3_u32 v100, v59, v100, s24
	v_and_or_b32 v99, v100, s25, v99
	v_bfe_u32 v100, v79, 16, 1
	v_add3_u32 v100, v79, v100, s24
	v_bfe_u32 v101, v55, 16, 1
	v_lshrrev_b32_e32 v100, 16, v100
	v_add3_u32 v101, v55, v101, s24
	v_and_or_b32 v100, v101, s25, v100
	v_bfe_u32 v101, v91, 16, 1
	v_add3_u32 v101, v91, v101, s24
	v_lshrrev_b32_e32 v101, 16, v101
	v_and_or_b32 v101, v104, s25, v101
	v_add_co_u32_e32 v104, vcc, s15, v102
	s_nop 1
	v_addc_co_u32_e32 v105, vcc, 0, v103, vcc
	global_store_dwordx4 v[104:105], v[98:101], off nt
	v_bfe_u32 v104, v96, 16, 1
	v_add3_u32 v104, v96, v104, s24
	v_bfe_u32 v98, v40, 16, 1
	v_add3_u32 v98, v40, v98, s24
	v_bfe_u32 v99, v32, 16, 1
	v_lshrrev_b32_e32 v98, 16, v98
	v_add3_u32 v99, v32, v99, s24
	v_and_or_b32 v98, v99, s25, v98
	v_bfe_u32 v99, v64, 16, 1
	v_add3_u32 v99, v64, v99, s24
	v_bfe_u32 v100, v60, 16, 1
	v_lshrrev_b32_e32 v99, 16, v99
	v_add3_u32 v100, v60, v100, s24
	v_and_or_b32 v99, v100, s25, v99
	v_bfe_u32 v100, v80, 16, 1
	v_add3_u32 v100, v80, v100, s24
	v_bfe_u32 v101, v56, 16, 1
	v_lshrrev_b32_e32 v100, 16, v100
	v_add3_u32 v101, v56, v101, s24
	v_and_or_b32 v100, v101, s25, v100
	v_bfe_u32 v101, v92, 16, 1
	v_add3_u32 v101, v92, v101, s24
	v_lshrrev_b32_e32 v101, 16, v101
	v_and_or_b32 v101, v104, s25, v101
	v_add_co_u32_e32 v104, vcc, s26, v102
	s_nop 1
	v_addc_co_u32_e32 v105, vcc, 0, v103, vcc
	global_store_dwordx4 v[104:105], v[98:101], off nt
	v_bfe_u32 v104, v97, 16, 1
	v_add3_u32 v104, v97, v104, s24
	v_bfe_u32 v98, v41, 16, 1
	v_add3_u32 v98, v41, v98, s24
	v_bfe_u32 v99, v33, 16, 1
	v_lshrrev_b32_e32 v98, 16, v98
	v_add3_u32 v99, v33, v99, s24
	v_and_or_b32 v98, v99, s25, v98
	v_bfe_u32 v99, v65, 16, 1
	v_add3_u32 v99, v65, v99, s24
	v_bfe_u32 v100, v61, 16, 1
	v_lshrrev_b32_e32 v99, 16, v99
	v_add3_u32 v100, v61, v100, s24
	v_and_or_b32 v99, v100, s25, v99
	v_bfe_u32 v100, v81, 16, 1
	v_add3_u32 v100, v81, v100, s24
	v_bfe_u32 v101, v57, 16, 1
	v_lshrrev_b32_e32 v100, 16, v100
	v_add3_u32 v101, v57, v101, s24
	v_and_or_b32 v100, v101, s25, v100
	v_bfe_u32 v101, v93, 16, 1
	v_add3_u32 v101, v93, v101, s24
	v_lshrrev_b32_e32 v101, 16, v101
	v_add_co_u32_e32 v102, vcc, 0x9000, v102
	v_and_or_b32 v101, v104, s25, v101
	s_nop 0
	v_addc_co_u32_e32 v103, vcc, 0, v103, vcc
	global_store_dwordx4 v[102:103], v[98:101], off nt
	s_andn2_b64 vcc, exec, s[20:21]
	s_cbranch_vccz .LBB0_624

.LBB0_624:
	s_ashr_i32 s4, s29, 31
	s_lshr_b32 s4, s4, 25
	s_add_i32 s29, s29, s4
	s_ashr_i32 s4, s29, 7
	v_lshl_or_b32 v98, s4, 6, v134
	v_add_u32_e32 v100, s0, v136
	s_lshl_b32 s4, s4, 12
	v_subrev_u32_e32 v102, s4, v100
	v_mov_b64_e32 v[100:101], s[16:17]
	v_ashrrev_i32_e32 v99, 31, v98
	v_mad_i64_i32 v[100:101], s[4:5], v102, s15, v[100:101]
	v_lshl_add_u64 v[102:103], v[98:99], 1, v[100:101]
	v_bfe_u32 v98, v18, 16, 1
	v_add3_u32 v98, v18, v98, s24
	v_bfe_u32 v99, v10, 16, 1
	v_lshrrev_b32_e32 v98, 16, v98
	v_add3_u32 v99, v10, v99, s24
	v_and_or_b32 v98, v99, s25, v98
	v_bfe_u32 v99, v46, 16, 1
	v_add3_u32 v99, v46, v99, s24
	v_bfe_u32 v100, v42, 16, 1
	v_lshrrev_b32_e32 v99, 16, v99
	v_add3_u32 v100, v42, v100, s24
	v_and_or_b32 v99, v100, s25, v99
	v_bfe_u32 v100, v66, 16, 1
	v_add3_u32 v100, v66, v100, s24
	v_bfe_u32 v101, v34, 16, 1
	v_lshrrev_b32_e32 v100, 16, v100
	v_add3_u32 v101, v34, v101, s24
	v_and_or_b32 v100, v101, s25, v100
	v_bfe_u32 v101, v82, 16, 1
	v_add3_u32 v101, v82, v101, s24
	v_bfe_u32 v104, v86, 16, 1
	v_lshrrev_b32_e32 v101, 16, v101
	v_add3_u32 v104, v86, v104, s24
	v_and_or_b32 v101, v104, s25, v101
	global_store_dwordx4 v[102:103], v[98:101], off nt
	v_bfe_u32 v104, v87, 16, 1
	v_add3_u32 v104, v87, v104, s24
	v_bfe_u32 v98, v19, 16, 1
	v_add3_u32 v98, v19, v98, s24
	v_bfe_u32 v99, v11, 16, 1
	v_lshrrev_b32_e32 v98, 16, v98
	v_add3_u32 v99, v11, v99, s24
	v_and_or_b32 v98, v99, s25, v98
	v_bfe_u32 v99, v47, 16, 1
	v_add3_u32 v99, v47, v99, s24
	v_bfe_u32 v100, v43, 16, 1
	v_lshrrev_b32_e32 v99, 16, v99
	v_add3_u32 v100, v43, v100, s24
	v_and_or_b32 v99, v100, s25, v99
	v_bfe_u32 v100, v67, 16, 1
	v_add3_u32 v100, v67, v100, s24
	v_bfe_u32 v101, v35, 16, 1
	v_lshrrev_b32_e32 v100, 16, v100
	v_add3_u32 v101, v35, v101, s24
	v_and_or_b32 v100, v101, s25, v100
	v_bfe_u32 v101, v83, 16, 1
	v_add3_u32 v101, v83, v101, s24
	v_lshrrev_b32_e32 v101, 16, v101
	v_and_or_b32 v101, v104, s25, v101
	v_add_co_u32_e32 v104, vcc, s15, v102
	s_nop 1
	v_addc_co_u32_e32 v105, vcc, 0, v103, vcc
	global_store_dwordx4 v[104:105], v[98:101], off nt
	v_bfe_u32 v104, v88, 16, 1
	v_add3_u32 v104, v88, v104, s24
	v_bfe_u32 v98, v20, 16, 1
	v_add3_u32 v98, v20, v98, s24
	v_bfe_u32 v99, v12, 16, 1
	v_lshrrev_b32_e32 v98, 16, v98
	v_add3_u32 v99, v12, v99, s24
	v_and_or_b32 v98, v99, s25, v98
	v_bfe_u32 v99, v48, 16, 1
	v_add3_u32 v99, v48, v99, s24
	v_bfe_u32 v100, v44, 16, 1
	v_lshrrev_b32_e32 v99, 16, v99
	v_add3_u32 v100, v44, v100, s24
	v_and_or_b32 v99, v100, s25, v99
	v_bfe_u32 v100, v68, 16, 1
	v_add3_u32 v100, v68, v100, s24
	v_bfe_u32 v101, v36, 16, 1
	v_lshrrev_b32_e32 v100, 16, v100
	v_add3_u32 v101, v36, v101, s24
	v_and_or_b32 v100, v101, s25, v100
	v_bfe_u32 v101, v84, 16, 1
	v_add3_u32 v101, v84, v101, s24
	v_lshrrev_b32_e32 v101, 16, v101
	v_and_or_b32 v101, v104, s25, v101
	v_add_co_u32_e32 v104, vcc, s26, v102
	s_nop 1
	v_addc_co_u32_e32 v105, vcc, 0, v103, vcc
	global_store_dwordx4 v[104:105], v[98:101], off nt
	v_bfe_u32 v104, v89, 16, 1
	v_add3_u32 v104, v89, v104, s24
	v_bfe_u32 v98, v21, 16, 1
	v_add3_u32 v98, v21, v98, s24
	v_bfe_u32 v99, v13, 16, 1
	v_lshrrev_b32_e32 v98, 16, v98
	v_add3_u32 v99, v13, v99, s24
	v_and_or_b32 v98, v99, s25, v98
	v_bfe_u32 v99, v49, 16, 1
	v_add3_u32 v99, v49, v99, s24
	v_bfe_u32 v100, v45, 16, 1
	v_lshrrev_b32_e32 v99, 16, v99
	v_add3_u32 v100, v45, v100, s24
	v_and_or_b32 v99, v100, s25, v99
	v_bfe_u32 v100, v69, 16, 1
	v_add3_u32 v100, v69, v100, s24
	v_bfe_u32 v101, v37, 16, 1
	v_lshrrev_b32_e32 v100, 16, v100
	v_add3_u32 v101, v37, v101, s24
	v_and_or_b32 v100, v101, s25, v100
	v_bfe_u32 v101, v85, 16, 1
	v_add3_u32 v101, v85, v101, s24
	v_lshrrev_b32_e32 v101, 16, v101
	v_add_co_u32_e32 v102, vcc, 0x9000, v102
	v_and_or_b32 v101, v104, s25, v101
	s_nop 0
	v_addc_co_u32_e32 v103, vcc, 0, v103, vcc
	global_store_dwordx4 v[102:103], v[98:101], off nt
	s_andn2_b64 vcc, exec, s[22:23]
	s_cbranch_vccnz .LBB0_576
.LBB0_625:
	s_ashr_i32 s4, s30, 31
	s_lshr_b32 s4, s4, 25
	s_add_i32 s30, s30, s4
	s_ashr_i32 s4, s30, 7
	v_lshl_or_b32 v98, s4, 6, v134
	v_add_u32_e32 v100, s0, v137
	s_lshl_b32 s4, s4, 12
	v_subrev_u32_e32 v102, s4, v100
	v_mov_b64_e32 v[100:101], s[16:17]
	v_ashrrev_i32_e32 v99, 31, v98
	v_mad_i64_i32 v[100:101], s[4:5], v102, s15, v[100:101]
	v_lshl_add_u64 v[102:103], v[98:99], 1, v[100:101]
	v_bfe_u32 v98, v6, 16, 1
	v_add3_u32 v98, v6, v98, s24
	v_bfe_u32 v99, v2, 16, 1
	v_lshrrev_b32_e32 v98, 16, v98
	v_add3_u32 v99, v2, v99, s24
	v_and_or_b32 v98, v99, s25, v98
	v_bfe_u32 v99, v26, 16, 1
	v_add3_u32 v99, v26, v99, s24
	v_bfe_u32 v100, v22, 16, 1
	v_lshrrev_b32_e32 v99, 16, v99
	v_add3_u32 v100, v22, v100, s24
	v_and_or_b32 v99, v100, s25, v99
	v_bfe_u32 v100, v50, 16, 1
	v_add3_u32 v100, v50, v100, s24
	v_bfe_u32 v101, v14, 16, 1
	v_lshrrev_b32_e32 v100, 16, v100
	v_add3_u32 v101, v14, v101, s24
	v_and_or_b32 v100, v101, s25, v100
	v_bfe_u32 v101, v70, 16, 1
	v_add3_u32 v101, v70, v101, s24
	v_bfe_u32 v104, v74, 16, 1
	v_lshrrev_b32_e32 v101, 16, v101
	v_add3_u32 v104, v74, v104, s24
	v_and_or_b32 v101, v104, s25, v101
	global_store_dwordx4 v[102:103], v[98:101], off nt
	v_bfe_u32 v104, v75, 16, 1
	v_add3_u32 v104, v75, v104, s24
	v_bfe_u32 v98, v7, 16, 1
	v_add3_u32 v98, v7, v98, s24
	v_bfe_u32 v99, v3, 16, 1
	v_lshrrev_b32_e32 v98, 16, v98
	v_add3_u32 v99, v3, v99, s24
	v_and_or_b32 v98, v99, s25, v98
	v_bfe_u32 v99, v27, 16, 1
	v_add3_u32 v99, v27, v99, s24
	v_bfe_u32 v100, v23, 16, 1
	v_lshrrev_b32_e32 v99, 16, v99
	v_add3_u32 v100, v23, v100, s24
	v_and_or_b32 v99, v100, s25, v99
	v_bfe_u32 v100, v51, 16, 1
	v_add3_u32 v100, v51, v100, s24
	v_bfe_u32 v101, v15, 16, 1
	v_lshrrev_b32_e32 v100, 16, v100
	v_add3_u32 v101, v15, v101, s24
	v_and_or_b32 v100, v101, s25, v100
	v_bfe_u32 v101, v71, 16, 1
	v_add3_u32 v101, v71, v101, s24
	v_lshrrev_b32_e32 v101, 16, v101
	v_and_or_b32 v101, v104, s25, v101
	v_add_co_u32_e32 v104, vcc, s15, v102
	s_nop 1
	v_addc_co_u32_e32 v105, vcc, 0, v103, vcc
	global_store_dwordx4 v[104:105], v[98:101], off nt
	v_bfe_u32 v104, v76, 16, 1
	v_add3_u32 v104, v76, v104, s24
	v_bfe_u32 v98, v8, 16, 1
	v_add3_u32 v98, v8, v98, s24
	v_bfe_u32 v99, v4, 16, 1
	v_lshrrev_b32_e32 v98, 16, v98
	v_add3_u32 v99, v4, v99, s24
	v_and_or_b32 v98, v99, s25, v98
	v_bfe_u32 v99, v28, 16, 1
	v_add3_u32 v99, v28, v99, s24
	v_bfe_u32 v100, v24, 16, 1
	v_lshrrev_b32_e32 v99, 16, v99
	v_add3_u32 v100, v24, v100, s24
	v_and_or_b32 v99, v100, s25, v99
	v_bfe_u32 v100, v52, 16, 1
	v_add3_u32 v100, v52, v100, s24
	v_bfe_u32 v101, v16, 16, 1
	v_lshrrev_b32_e32 v100, 16, v100
	v_add3_u32 v101, v16, v101, s24
	v_and_or_b32 v100, v101, s25, v100
	v_bfe_u32 v101, v72, 16, 1
	v_add3_u32 v101, v72, v101, s24
	v_lshrrev_b32_e32 v101, 16, v101
	v_and_or_b32 v101, v104, s25, v101
	v_add_co_u32_e32 v104, vcc, s26, v102
	s_nop 1
	v_addc_co_u32_e32 v105, vcc, 0, v103, vcc
	global_store_dwordx4 v[104:105], v[98:101], off nt
	v_bfe_u32 v104, v77, 16, 1
	v_add3_u32 v104, v77, v104, s24
	v_bfe_u32 v98, v9, 16, 1
	v_add3_u32 v98, v9, v98, s24
	v_bfe_u32 v99, v5, 16, 1
	v_lshrrev_b32_e32 v98, 16, v98
	v_add3_u32 v99, v5, v99, s24
	v_and_or_b32 v98, v99, s25, v98
	v_bfe_u32 v99, v29, 16, 1
	v_add3_u32 v99, v29, v99, s24
	v_bfe_u32 v100, v25, 16, 1
	v_lshrrev_b32_e32 v99, 16, v99
	v_add3_u32 v100, v25, v100, s24
	v_and_or_b32 v99, v100, s25, v99
	v_bfe_u32 v100, v53, 16, 1
	v_add3_u32 v100, v53, v100, s24
	v_bfe_u32 v101, v17, 16, 1
	v_lshrrev_b32_e32 v100, 16, v100
	v_add3_u32 v101, v17, v101, s24
	v_and_or_b32 v100, v101, s25, v100
	v_bfe_u32 v101, v73, 16, 1
	v_add3_u32 v101, v73, v101, s24
	v_lshrrev_b32_e32 v101, 16, v101
	v_add_co_u32_e32 v102, vcc, 0x9000, v102
	v_and_or_b32 v101, v104, s25, v101
	s_nop 0
	v_addc_co_u32_e32 v103, vcc, 0, v103, vcc
	global_store_dwordx4 v[102:103], v[98:101], off nt
	s_branch .LBB0_576

.LBB0_672:
	v_ashrrev_i32_e32 v135, 31, v134
	s_waitcnt vmcnt(1)
	v_bfe_u32 v130, v102, 16, 1
	v_lshlrev_b64 v[134:135], 13, v[134:135]
	v_add3_u32 v102, v102, v130, s24
	s_waitcnt vmcnt(0)
	v_bfe_u32 v130, v98, 16, 1
	v_lshl_add_u64 v[134:135], s[16:17], 0, v[134:135]
	v_lshrrev_b32_e32 v102, 16, v102
	v_add3_u32 v98, v98, v130, s24
	v_lshl_add_u64 v[142:143], v[132:133], 1, v[134:135]
	v_and_or_b32 v132, v98, s25, v102
	v_bfe_u32 v98, v114, 16, 1
	v_add3_u32 v98, v114, v98, s24
	v_bfe_u32 v102, v110, 16, 1
	v_lshrrev_b32_e32 v98, 16, v98
	v_add3_u32 v102, v110, v102, s24
	v_and_or_b32 v133, v102, s25, v98
	v_bfe_u32 v98, v118, 16, 1
	v_add3_u32 v98, v118, v98, s24
	v_bfe_u32 v102, v106, 16, 1
	v_lshrrev_b32_e32 v98, 16, v98
	v_add3_u32 v102, v106, v102, s24
	v_and_or_b32 v134, v102, s25, v98
	v_bfe_u32 v98, v126, 16, 1
	v_add3_u32 v98, v126, v98, s24
	v_bfe_u32 v102, v122, 16, 1
	v_lshrrev_b32_e32 v98, 16, v98
	v_add3_u32 v102, v122, v102, s24
	v_and_or_b32 v135, v102, s25, v98
	v_bfe_u32 v98, v103, 16, 1
	v_add3_u32 v98, v103, v98, s24
	v_bfe_u32 v102, v99, 16, 1
	v_lshrrev_b32_e32 v98, 16, v98
	v_add3_u32 v99, v99, v102, s24
	global_store_dwordx4 v[142:143], v[132:135], off nt
	v_bfe_u32 v102, v125, 16, 1
	v_add3_u32 v102, v125, v102, s24
	v_and_or_b32 v132, v99, s25, v98
	v_bfe_u32 v98, v115, 16, 1
	v_add3_u32 v98, v115, v98, s24
	v_bfe_u32 v99, v111, 16, 1
	v_lshrrev_b32_e32 v98, 16, v98
	v_add3_u32 v99, v111, v99, s24
	v_and_or_b32 v133, v99, s25, v98
	v_bfe_u32 v98, v119, 16, 1
	v_add3_u32 v98, v119, v98, s24
	v_bfe_u32 v99, v107, 16, 1
	v_lshrrev_b32_e32 v98, 16, v98
	v_add3_u32 v99, v107, v99, s24
	v_and_or_b32 v134, v99, s25, v98
	v_bfe_u32 v98, v127, 16, 1
	v_add3_u32 v98, v127, v98, s24
	v_bfe_u32 v99, v123, 16, 1
	v_lshrrev_b32_e32 v98, 16, v98
	v_add3_u32 v99, v123, v99, s24
	v_and_or_b32 v135, v99, s25, v98
	v_add_co_u32_e32 v98, vcc, s15, v142
	s_nop 1
	v_addc_co_u32_e32 v99, vcc, 0, v143, vcc
	global_store_dwordx4 v[98:99], v[132:135], off nt
	v_bfe_u32 v98, v104, 16, 1
	v_add3_u32 v98, v104, v98, s24
	v_bfe_u32 v99, v100, 16, 1
	v_lshrrev_b32_e32 v98, 16, v98
	v_add3_u32 v99, v100, v99, s24
	v_and_or_b32 v132, v99, s25, v98
	v_bfe_u32 v98, v116, 16, 1
	v_add3_u32 v98, v116, v98, s24
	v_bfe_u32 v99, v112, 16, 1
	v_lshrrev_b32_e32 v98, 16, v98
	v_add3_u32 v99, v112, v99, s24
	v_and_or_b32 v133, v99, s25, v98
	v_bfe_u32 v98, v120, 16, 1
	v_add3_u32 v98, v120, v98, s24
	v_bfe_u32 v99, v108, 16, 1
	v_lshrrev_b32_e32 v98, 16, v98
	v_add3_u32 v99, v108, v99, s24
	v_and_or_b32 v134, v99, s25, v98
	v_bfe_u32 v98, v128, 16, 1
	v_add3_u32 v98, v128, v98, s24
	v_bfe_u32 v99, v124, 16, 1
	v_lshrrev_b32_e32 v98, 16, v98
	v_add3_u32 v99, v124, v99, s24
	v_and_or_b32 v135, v99, s25, v98
	v_add_co_u32_e32 v98, vcc, s14, v142
	v_bfe_u32 v100, v113, 16, 1
	s_nop 0
	v_addc_co_u32_e32 v99, vcc, 0, v143, vcc
	global_store_dwordx4 v[98:99], v[132:135], off nt
	v_bfe_u32 v98, v105, 16, 1
	v_add3_u32 v98, v105, v98, s24
	v_bfe_u32 v99, v101, 16, 1
	v_lshrrev_b32_e32 v98, 16, v98
	v_add3_u32 v99, v101, v99, s24
	v_and_or_b32 v98, v99, s25, v98
	v_bfe_u32 v99, v117, 16, 1
	v_add3_u32 v99, v117, v99, s24
	v_lshrrev_b32_e32 v99, 16, v99
	v_add3_u32 v100, v113, v100, s24
	v_and_or_b32 v99, v100, s25, v99
	v_bfe_u32 v100, v121, 16, 1
	v_add3_u32 v100, v121, v100, s24
	v_bfe_u32 v101, v109, 16, 1
	v_lshrrev_b32_e32 v100, 16, v100
	v_add3_u32 v101, v109, v101, s24
	v_and_or_b32 v100, v101, s25, v100
	v_bfe_u32 v101, v129, 16, 1
	v_add3_u32 v101, v129, v101, s24
	v_lshrrev_b32_e32 v101, 16, v101
	v_and_or_b32 v101, v102, s25, v101
	v_add_co_u32_e32 v102, vcc, 0x6000, v142
	s_nop 1
	v_addc_co_u32_e32 v103, vcc, 0, v143, vcc
	s_andn2_b64 vcc, exec, s[18:19]
	global_store_dwordx4 v[102:103], v[98:101], off nt
	s_cbranch_vccnz .LBB0_675
	s_ashr_i32 s4, s27, 31
	s_lshr_b32 s4, s4, 25
	s_add_i32 s27, s27, s4
	s_ashr_i32 s4, s27, 7
	v_lshl_or_b32 v98, s4, 6, v136
	v_add_u32_e32 v100, s0, v140
	s_lshl_b32 s4, s4, 12
	v_subrev_u32_e32 v100, s4, v100
	v_ashrrev_i32_e32 v101, 31, v100
	v_lshlrev_b64 v[100:101], 13, v[100:101]
	v_ashrrev_i32_e32 v99, 31, v98
	v_lshl_add_u64 v[100:101], s[16:17], 0, v[100:101]
	v_lshl_add_u64 v[102:103], v[98:99], 1, v[100:101]
	v_bfe_u32 v98, v38, 16, 1
	v_add3_u32 v98, v38, v98, s24
	v_bfe_u32 v99, v30, 16, 1
	v_lshrrev_b32_e32 v98, 16, v98
	v_add3_u32 v99, v30, v99, s24
	v_and_or_b32 v98, v99, s25, v98
	v_bfe_u32 v99, v62, 16, 1
	v_add3_u32 v99, v62, v99, s24
	v_bfe_u32 v100, v58, 16, 1
	v_lshrrev_b32_e32 v99, 16, v99
	v_add3_u32 v100, v58, v100, s24
	v_and_or_b32 v99, v100, s25, v99
	v_bfe_u32 v100, v78, 16, 1
	v_add3_u32 v100, v78, v100, s24
	v_bfe_u32 v101, v54, 16, 1
	v_lshrrev_b32_e32 v100, 16, v100
	v_add3_u32 v101, v54, v101, s24
	v_and_or_b32 v100, v101, s25, v100
	v_bfe_u32 v101, v90, 16, 1
	v_add3_u32 v101, v90, v101, s24
	v_bfe_u32 v104, v94, 16, 1
	v_lshrrev_b32_e32 v101, 16, v101
	v_add3_u32 v104, v94, v104, s24
	v_and_or_b32 v101, v104, s25, v101
	global_store_dwordx4 v[102:103], v[98:101], off nt
	v_bfe_u32 v104, v95, 16, 1
	v_add3_u32 v104, v95, v104, s24
	v_bfe_u32 v98, v39, 16, 1
	v_add3_u32 v98, v39, v98, s24
	v_bfe_u32 v99, v31, 16, 1
	v_lshrrev_b32_e32 v98, 16, v98
	v_add3_u32 v99, v31, v99, s24
	v_and_or_b32 v98, v99, s25, v98
	v_bfe_u32 v99, v63, 16, 1
	v_add3_u32 v99, v63, v99, s24
	v_bfe_u32 v100, v59, 16, 1
	v_lshrrev_b32_e32 v99, 16, v99
	v_add3_u32 v100, v59, v100, s24
	v_and_or_b32 v99, v100, s25, v99
	v_bfe_u32 v100, v79, 16, 1
	v_add3_u32 v100, v79, v100, s24
	v_bfe_u32 v101, v55, 16, 1
	v_lshrrev_b32_e32 v100, 16, v100
	v_add3_u32 v101, v55, v101, s24
	v_and_or_b32 v100, v101, s25, v100
	v_bfe_u32 v101, v91, 16, 1
	v_add3_u32 v101, v91, v101, s24
	v_lshrrev_b32_e32 v101, 16, v101
	v_and_or_b32 v101, v104, s25, v101
	v_add_co_u32_e32 v104, vcc, s15, v102
	s_nop 1
	v_addc_co_u32_e32 v105, vcc, 0, v103, vcc
	global_store_dwordx4 v[104:105], v[98:101], off nt
	v_bfe_u32 v104, v96, 16, 1
	v_add3_u32 v104, v96, v104, s24
	v_bfe_u32 v98, v40, 16, 1
	v_add3_u32 v98, v40, v98, s24
	v_bfe_u32 v99, v32, 16, 1
	v_lshrrev_b32_e32 v98, 16, v98
	v_add3_u32 v99, v32, v99, s24
	v_and_or_b32 v98, v99, s25, v98
	v_bfe_u32 v99, v64, 16, 1
	v_add3_u32 v99, v64, v99, s24
	v_bfe_u32 v100, v60, 16, 1
	v_lshrrev_b32_e32 v99, 16, v99
	v_add3_u32 v100, v60, v100, s24
	v_and_or_b32 v99, v100, s25, v99
	v_bfe_u32 v100, v80, 16, 1
	v_add3_u32 v100, v80, v100, s24
	v_bfe_u32 v101, v56, 16, 1
	v_lshrrev_b32_e32 v100, 16, v100
	v_add3_u32 v101, v56, v101, s24
	v_and_or_b32 v100, v101, s25, v100
	v_bfe_u32 v101, v92, 16, 1
	v_add3_u32 v101, v92, v101, s24
	v_lshrrev_b32_e32 v101, 16, v101
	v_and_or_b32 v101, v104, s25, v101
	v_add_co_u32_e32 v104, vcc, s14, v102
	s_nop 1
	v_addc_co_u32_e32 v105, vcc, 0, v103, vcc
	global_store_dwordx4 v[104:105], v[98:101], off nt
	v_bfe_u32 v104, v97, 16, 1
	v_add3_u32 v104, v97, v104, s24
	v_bfe_u32 v98, v41, 16, 1
	v_add3_u32 v98, v41, v98, s24
	v_bfe_u32 v99, v33, 16, 1
	v_lshrrev_b32_e32 v98, 16, v98
	v_add3_u32 v99, v33, v99, s24
	v_and_or_b32 v98, v99, s25, v98
	v_bfe_u32 v99, v65, 16, 1
	v_add3_u32 v99, v65, v99, s24
	v_bfe_u32 v100, v61, 16, 1
	v_lshrrev_b32_e32 v99, 16, v99
	v_add3_u32 v100, v61, v100, s24
	v_and_or_b32 v99, v100, s25, v99
	v_bfe_u32 v100, v81, 16, 1
	v_add3_u32 v100, v81, v100, s24
	v_bfe_u32 v101, v57, 16, 1
	v_lshrrev_b32_e32 v100, 16, v100
	v_add3_u32 v101, v57, v101, s24
	v_and_or_b32 v100, v101, s25, v100
	v_bfe_u32 v101, v93, 16, 1
	v_add3_u32 v101, v93, v101, s24
	v_lshrrev_b32_e32 v101, 16, v101
	v_add_co_u32_e32 v102, vcc, 0x6000, v102
	v_and_or_b32 v101, v104, s25, v101
	s_nop 0
	v_addc_co_u32_e32 v103, vcc, 0, v103, vcc
	global_store_dwordx4 v[102:103], v[98:101], off nt
	s_andn2_b64 vcc, exec, s[20:21]
	s_cbranch_vccz .LBB0_676

.LBB0_676:
	s_ashr_i32 s4, s28, 31
	s_lshr_b32 s4, s4, 25
	s_add_i32 s28, s28, s4
	s_ashr_i32 s4, s28, 7
	v_lshl_or_b32 v98, s4, 6, v136
	v_add_u32_e32 v100, s0, v138
	s_lshl_b32 s4, s4, 12
	v_subrev_u32_e32 v100, s4, v100
	v_ashrrev_i32_e32 v101, 31, v100
	v_lshlrev_b64 v[100:101], 13, v[100:101]
	v_ashrrev_i32_e32 v99, 31, v98
	v_lshl_add_u64 v[100:101], s[16:17], 0, v[100:101]
	v_lshl_add_u64 v[102:103], v[98:99], 1, v[100:101]
	v_bfe_u32 v98, v18, 16, 1
	v_add3_u32 v98, v18, v98, s24
	v_bfe_u32 v99, v10, 16, 1
	v_lshrrev_b32_e32 v98, 16, v98
	v_add3_u32 v99, v10, v99, s24
	v_and_or_b32 v98, v99, s25, v98
	v_bfe_u32 v99, v46, 16, 1
	v_add3_u32 v99, v46, v99, s24
	v_bfe_u32 v100, v42, 16, 1
	v_lshrrev_b32_e32 v99, 16, v99
	v_add3_u32 v100, v42, v100, s24
	v_and_or_b32 v99, v100, s25, v99
	v_bfe_u32 v100, v66, 16, 1
	v_add3_u32 v100, v66, v100, s24
	v_bfe_u32 v101, v34, 16, 1
	v_lshrrev_b32_e32 v100, 16, v100
	v_add3_u32 v101, v34, v101, s24
	v_and_or_b32 v100, v101, s25, v100
	v_bfe_u32 v101, v82, 16, 1
	v_add3_u32 v101, v82, v101, s24
	v_bfe_u32 v104, v86, 16, 1
	v_lshrrev_b32_e32 v101, 16, v101
	v_add3_u32 v104, v86, v104, s24
	v_and_or_b32 v101, v104, s25, v101
	global_store_dwordx4 v[102:103], v[98:101], off nt
	v_bfe_u32 v104, v87, 16, 1
	v_add3_u32 v104, v87, v104, s24
	v_bfe_u32 v98, v19, 16, 1
	v_add3_u32 v98, v19, v98, s24
	v_bfe_u32 v99, v11, 16, 1
	v_lshrrev_b32_e32 v98, 16, v98
	v_add3_u32 v99, v11, v99, s24
	v_and_or_b32 v98, v99, s25, v98
	v_bfe_u32 v99, v47, 16, 1
	v_add3_u32 v99, v47, v99, s24
	v_bfe_u32 v100, v43, 16, 1
	v_lshrrev_b32_e32 v99, 16, v99
	v_add3_u32 v100, v43, v100, s24
	v_and_or_b32 v99, v100, s25, v99
	v_bfe_u32 v100, v67, 16, 1
	v_add3_u32 v100, v67, v100, s24
	v_bfe_u32 v101, v35, 16, 1
	v_lshrrev_b32_e32 v100, 16, v100
	v_add3_u32 v101, v35, v101, s24
	v_and_or_b32 v100, v101, s25, v100
	v_bfe_u32 v101, v83, 16, 1
	v_add3_u32 v101, v83, v101, s24
	v_lshrrev_b32_e32 v101, 16, v101
	v_and_or_b32 v101, v104, s25, v101
	v_add_co_u32_e32 v104, vcc, s15, v102
	s_nop 1
	v_addc_co_u32_e32 v105, vcc, 0, v103, vcc
	global_store_dwordx4 v[104:105], v[98:101], off nt
	v_bfe_u32 v104, v88, 16, 1
	v_add3_u32 v104, v88, v104, s24
	v_bfe_u32 v98, v20, 16, 1
	v_add3_u32 v98, v20, v98, s24
	v_bfe_u32 v99, v12, 16, 1
	v_lshrrev_b32_e32 v98, 16, v98
	v_add3_u32 v99, v12, v99, s24
	v_and_or_b32 v98, v99, s25, v98
	v_bfe_u32 v99, v48, 16, 1
	v_add3_u32 v99, v48, v99, s24
	v_bfe_u32 v100, v44, 16, 1
	v_lshrrev_b32_e32 v99, 16, v99
	v_add3_u32 v100, v44, v100, s24
	v_and_or_b32 v99, v100, s25, v99
	v_bfe_u32 v100, v68, 16, 1
	v_add3_u32 v100, v68, v100, s24
	v_bfe_u32 v101, v36, 16, 1
	v_lshrrev_b32_e32 v100, 16, v100
	v_add3_u32 v101, v36, v101, s24
	v_and_or_b32 v100, v101, s25, v100
	v_bfe_u32 v101, v84, 16, 1
	v_add3_u32 v101, v84, v101, s24
	v_lshrrev_b32_e32 v101, 16, v101
	v_and_or_b32 v101, v104, s25, v101
	v_add_co_u32_e32 v104, vcc, s14, v102
	s_nop 1
	v_addc_co_u32_e32 v105, vcc, 0, v103, vcc
	global_store_dwordx4 v[104:105], v[98:101], off nt
	v_bfe_u32 v104, v89, 16, 1
	v_add3_u32 v104, v89, v104, s24
	v_bfe_u32 v98, v21, 16, 1
	v_add3_u32 v98, v21, v98, s24
	v_bfe_u32 v99, v13, 16, 1
	v_lshrrev_b32_e32 v98, 16, v98
	v_add3_u32 v99, v13, v99, s24
	v_and_or_b32 v98, v99, s25, v98
	v_bfe_u32 v99, v49, 16, 1
	v_add3_u32 v99, v49, v99, s24
	v_bfe_u32 v100, v45, 16, 1
	v_lshrrev_b32_e32 v99, 16, v99
	v_add3_u32 v100, v45, v100, s24
	v_and_or_b32 v99, v100, s25, v99
	v_bfe_u32 v100, v69, 16, 1
	v_add3_u32 v100, v69, v100, s24
	v_bfe_u32 v101, v37, 16, 1
	v_lshrrev_b32_e32 v100, 16, v100
	v_add3_u32 v101, v37, v101, s24
	v_and_or_b32 v100, v101, s25, v100
	v_bfe_u32 v101, v85, 16, 1
	v_add3_u32 v101, v85, v101, s24
	v_lshrrev_b32_e32 v101, 16, v101
	v_add_co_u32_e32 v102, vcc, 0x6000, v102
	v_and_or_b32 v101, v104, s25, v101
	s_nop 0
	v_addc_co_u32_e32 v103, vcc, 0, v103, vcc
	global_store_dwordx4 v[102:103], v[98:101], off nt
	s_andn2_b64 vcc, exec, s[22:23]
	s_cbranch_vccnz .LBB0_628
.LBB0_677:
	s_ashr_i32 s4, s29, 31
	s_lshr_b32 s4, s4, 25
	s_add_i32 s29, s29, s4
	s_ashr_i32 s4, s29, 7
	v_lshl_or_b32 v98, s4, 6, v136
	v_add_u32_e32 v100, s0, v139
	s_lshl_b32 s4, s4, 12
	v_subrev_u32_e32 v100, s4, v100
	v_ashrrev_i32_e32 v101, 31, v100
	v_lshlrev_b64 v[100:101], 13, v[100:101]
	v_ashrrev_i32_e32 v99, 31, v98
	v_lshl_add_u64 v[100:101], s[16:17], 0, v[100:101]
	v_lshl_add_u64 v[102:103], v[98:99], 1, v[100:101]
	v_bfe_u32 v98, v6, 16, 1
	v_add3_u32 v98, v6, v98, s24
	v_bfe_u32 v99, v2, 16, 1
	v_lshrrev_b32_e32 v98, 16, v98
	v_add3_u32 v99, v2, v99, s24
	v_and_or_b32 v98, v99, s25, v98
	v_bfe_u32 v99, v26, 16, 1
	v_add3_u32 v99, v26, v99, s24
	v_bfe_u32 v100, v22, 16, 1
	v_lshrrev_b32_e32 v99, 16, v99
	v_add3_u32 v100, v22, v100, s24
	v_and_or_b32 v99, v100, s25, v99
	v_bfe_u32 v100, v50, 16, 1
	v_add3_u32 v100, v50, v100, s24
	v_bfe_u32 v101, v14, 16, 1
	v_lshrrev_b32_e32 v100, 16, v100
	v_add3_u32 v101, v14, v101, s24
	v_and_or_b32 v100, v101, s25, v100
	v_bfe_u32 v101, v70, 16, 1
	v_add3_u32 v101, v70, v101, s24
	v_bfe_u32 v104, v74, 16, 1
	v_lshrrev_b32_e32 v101, 16, v101
	v_add3_u32 v104, v74, v104, s24
	v_and_or_b32 v101, v104, s25, v101
	global_store_dwordx4 v[102:103], v[98:101], off nt
	v_bfe_u32 v104, v75, 16, 1
	v_add3_u32 v104, v75, v104, s24
	v_bfe_u32 v98, v7, 16, 1
	v_add3_u32 v98, v7, v98, s24
	v_bfe_u32 v99, v3, 16, 1
	v_lshrrev_b32_e32 v98, 16, v98
	v_add3_u32 v99, v3, v99, s24
	v_and_or_b32 v98, v99, s25, v98
	v_bfe_u32 v99, v27, 16, 1
	v_add3_u32 v99, v27, v99, s24
	v_bfe_u32 v100, v23, 16, 1
	v_lshrrev_b32_e32 v99, 16, v99
	v_add3_u32 v100, v23, v100, s24
	v_and_or_b32 v99, v100, s25, v99
	v_bfe_u32 v100, v51, 16, 1
	v_add3_u32 v100, v51, v100, s24
	v_bfe_u32 v101, v15, 16, 1
	v_lshrrev_b32_e32 v100, 16, v100
	v_add3_u32 v101, v15, v101, s24
	v_and_or_b32 v100, v101, s25, v100
	v_bfe_u32 v101, v71, 16, 1
	v_add3_u32 v101, v71, v101, s24
	v_lshrrev_b32_e32 v101, 16, v101
	v_and_or_b32 v101, v104, s25, v101
	v_add_co_u32_e32 v104, vcc, s15, v102
	s_nop 1
	v_addc_co_u32_e32 v105, vcc, 0, v103, vcc
	global_store_dwordx4 v[104:105], v[98:101], off nt
	v_bfe_u32 v104, v76, 16, 1
	v_add3_u32 v104, v76, v104, s24
	v_bfe_u32 v98, v8, 16, 1
	v_add3_u32 v98, v8, v98, s24
	v_bfe_u32 v99, v4, 16, 1
	v_lshrrev_b32_e32 v98, 16, v98
	v_add3_u32 v99, v4, v99, s24
	v_and_or_b32 v98, v99, s25, v98
	v_bfe_u32 v99, v28, 16, 1
	v_add3_u32 v99, v28, v99, s24
	v_bfe_u32 v100, v24, 16, 1
	v_lshrrev_b32_e32 v99, 16, v99
	v_add3_u32 v100, v24, v100, s24
	v_and_or_b32 v99, v100, s25, v99
	v_bfe_u32 v100, v52, 16, 1
	v_add3_u32 v100, v52, v100, s24
	v_bfe_u32 v101, v16, 16, 1
	v_lshrrev_b32_e32 v100, 16, v100
	v_add3_u32 v101, v16, v101, s24
	v_and_or_b32 v100, v101, s25, v100
	v_bfe_u32 v101, v72, 16, 1
	v_add3_u32 v101, v72, v101, s24
	v_lshrrev_b32_e32 v101, 16, v101
	v_and_or_b32 v101, v104, s25, v101
	v_add_co_u32_e32 v104, vcc, s14, v102
	s_nop 1
	v_addc_co_u32_e32 v105, vcc, 0, v103, vcc
	global_store_dwordx4 v[104:105], v[98:101], off nt
	v_bfe_u32 v104, v77, 16, 1
	v_add3_u32 v104, v77, v104, s24
	v_bfe_u32 v98, v9, 16, 1
	v_add3_u32 v98, v9, v98, s24
	v_bfe_u32 v99, v5, 16, 1
	v_lshrrev_b32_e32 v98, 16, v98
	v_add3_u32 v99, v5, v99, s24
	v_and_or_b32 v98, v99, s25, v98
	v_bfe_u32 v99, v29, 16, 1
	v_add3_u32 v99, v29, v99, s24
	v_bfe_u32 v100, v25, 16, 1
	v_lshrrev_b32_e32 v99, 16, v99
	v_add3_u32 v100, v25, v100, s24
	v_and_or_b32 v99, v100, s25, v99
	v_bfe_u32 v100, v53, 16, 1
	v_add3_u32 v100, v53, v100, s24
	v_bfe_u32 v101, v17, 16, 1
	v_lshrrev_b32_e32 v100, 16, v100
	v_add3_u32 v101, v17, v101, s24
	v_and_or_b32 v100, v101, s25, v100
	v_bfe_u32 v101, v73, 16, 1
	v_add3_u32 v101, v73, v101, s24
	v_lshrrev_b32_e32 v101, 16, v101
	v_add_co_u32_e32 v102, vcc, 0x6000, v102
	v_and_or_b32 v101, v104, s25, v101
	s_nop 0
	v_addc_co_u32_e32 v103, vcc, 0, v103, vcc
	global_store_dwordx4 v[102:103], v[98:101], off nt
	s_branch .LBB0_628

.LBB0_1504:
	s_or_b64 exec, exec, s[16:17]
	s_waitcnt lgkmcnt(0)
	v_max_f32_e32 v2, v132, v132
	v_max_f32_e32 v2, 0xda24260, v2
	v_div_scale_f32 v132, s[16:17], v2, v2, s88
	v_rcp_f32_e32 v136, v132
	v_div_scale_f32 v137, vcc, s88, v2, s88
	v_max_f32_e32 v133, v133, v133
	v_fma_f32 v139, -v132, v136, 1.0
	v_fmac_f32_e32 v136, v139, v136
	v_mul_f32_e32 v139, v137, v136
	v_fma_f32 v140, -v132, v139, v137
	v_fmac_f32_e32 v139, v140, v136
	v_max_f32_e32 v133, 0xda24260, v133
	v_fma_f32 v132, -v132, v139, v137
	v_div_scale_f32 v137, s[16:17], v133, v133, s88
	v_rcp_f32_e32 v140, v137
	v_div_fmas_f32 v132, v132, v136, v139
	v_div_fixup_f32 v2, v132, v2, s88
	v_max_f32_e32 v134, v134, v134
	v_fma_f32 v132, -v137, v140, 1.0
	v_fmac_f32_e32 v140, v132, v140
	v_div_scale_f32 v132, vcc, s88, v133, s88
	v_mul_f32_e32 v136, v132, v140
	v_fma_f32 v139, -v137, v136, v132
	v_fmac_f32_e32 v136, v139, v140
	v_max_f32_e32 v134, 0xda24260, v134
	v_fma_f32 v132, -v137, v136, v132
	v_div_scale_f32 v137, s[16:17], v134, v134, s88
	v_rcp_f32_e32 v139, v137
	v_div_fmas_f32 v132, v132, v140, v136
	v_div_fixup_f32 v132, v132, v133, s88
	v_max_f32_e32 v135, v135, v135
	v_fma_f32 v133, -v137, v139, 1.0
	v_fmac_f32_e32 v139, v133, v139
	v_div_scale_f32 v133, vcc, s88, v134, s88
	v_mul_f32_e32 v136, v133, v139
	v_fma_f32 v140, -v137, v136, v133
	v_fmac_f32_e32 v136, v140, v139
	v_max_f32_e32 v135, 0xda24260, v135
	v_fma_f32 v133, -v137, v136, v133
	v_div_scale_f32 v137, s[16:17], v135, v135, s88
	v_rcp_f32_e32 v140, v137
	v_div_fmas_f32 v133, v133, v139, v136
	v_div_fixup_f32 v133, v133, v134, s88
	v_bfe_u32 v176, v126, 16, 1
	v_fma_f32 v134, -v137, v140, 1.0
	v_fmac_f32_e32 v140, v134, v140
	v_div_scale_f32 v134, vcc, s88, v135, s88
	v_mul_f32_e32 v136, v134, v140
	v_fma_f32 v139, -v137, v136, v134
	v_fmac_f32_e32 v136, v139, v140
	v_fma_f32 v134, -v137, v136, v134
	v_div_fmas_f32 v134, v134, v140, v136
	v_bfe_u32 v136, v79, 16, 1
	v_add3_u32 v169, v79, v136, s80
	v_bfe_u32 v79, v72, 16, 1
	v_add3_u32 v136, v72, v79, s80
	v_add3_u32 v79, v126, v176, s80
	v_bfe_u32 v126, v12, 16, 1
	v_add3_u32 v12, v12, v126, s80
	v_bfe_u32 v126, v13, 16, 1
	v_add3_u32 v13, v13, v126, s80
	v_bfe_u32 v126, v14, 16, 1
	v_add3_u32 v14, v14, v126, s80
	v_bfe_u32 v126, v15, 16, 1
	v_add3_u32 v15, v15, v126, s80
	v_bfe_u32 v126, v8, 16, 1
	v_add3_u32 v8, v8, v126, s80
	v_bfe_u32 v126, v9, 16, 1
	v_bfe_u32 v147, v91, 16, 1
	v_add3_u32 v9, v9, v126, s80
	v_bfe_u32 v160, v125, 16, 1
	v_add3_u32 v147, v91, v147, s80
	v_bfe_u32 v91, v96, 16, 1
	v_bfe_u32 v179, v128, 16, 1
	v_and_b32_e32 v126, 0xffff0000, v9
	v_bfe_u32 v9, v10, 16, 1
	v_div_fixup_f32 v134, v134, v135, s88
	v_bfe_u32 v135, v77, 16, 1
	v_bfe_u32 v139, v75, 16, 1
	v_add3_u32 v160, v125, v160, s80
	v_add3_u32 v125, v96, v91, s80
	v_add3_u32 v91, v128, v179, s80
	v_add3_u32 v128, v10, v9, s80
	v_bfe_u32 v9, v11, 16, 1
	v_bfe_u32 v162, v121, 16, 1
	v_add3_u32 v77, v77, v135, s80
	v_bfe_u32 v135, v78, 16, 1
	v_add3_u32 v139, v75, v139, s80
	v_bfe_u32 v75, v80, 16, 1
	v_bfe_u32 v180, v130, 16, 1
	v_add3_u32 v9, v11, v9, s80
	v_add3_u32 v162, v121, v162, s80
	v_add3_u32 v121, v78, v135, s80
	v_add3_u32 v135, v80, v75, s80
	v_add3_u32 v75, v130, v180, s80
	v_and_b32_e32 v130, 0xffff0000, v9
	v_bfe_u32 v9, v20, 16, 1
	v_bfe_u32 v11, v22, 16, 1
	v_add3_u32 v9, v20, v9, s80
	v_add3_u32 v20, v22, v11, s80
	v_bfe_u32 v11, v23, 16, 1
	v_bfe_u32 v10, v21, 16, 1
	v_add3_u32 v11, v23, v11, s80
	v_add3_u32 v10, v21, v10, s80
	v_and_b32_e32 v21, 0xffff0000, v11
	v_bfe_u32 v11, v4, 16, 1
	v_add3_u32 v11, v4, v11, s80
	v_bfe_u32 v4, v5, 16, 1
	v_add3_u32 v4, v5, v4, s80
	v_and_b32_e32 v22, 0xffff0000, v4
	v_bfe_u32 v4, v6, 16, 1
	v_bfe_u32 v149, v99, 16, 1
	v_bfe_u32 v151, v87, 16, 1
	v_add3_u32 v23, v6, v4, s80
	v_bfe_u32 v4, v7, 16, 1
	v_bfe_u32 v163, v123, 16, 1
	v_add3_u32 v149, v99, v149, s80
	v_bfe_u32 v99, v84, 16, 1
	v_add3_u32 v87, v87, v151, s80
	v_bfe_u32 v151, v108, 16, 1
	v_add3_u32 v4, v7, v4, s80
	v_add3_u32 v163, v123, v163, s80
	v_add3_u32 v123, v84, v99, s80
	v_add3_u32 v99, v108, v151, s80
	v_and_b32_e32 v108, 0xffff0000, v139
	v_and_b32_e32 v139, 0xffff0000, v4
	v_bfe_u32 v4, v28, 16, 1
	v_add3_u32 v28, v28, v4, s80
	v_bfe_u32 v4, v29, 16, 1
	v_add3_u32 v4, v29, v4, s80
	v_and_b32_e32 v29, 0xffff0000, v4
	v_bfe_u32 v4, v30, 16, 1
	v_add3_u32 v30, v30, v4, s80
	v_bfe_u32 v4, v31, 16, 1
	v_add3_u32 v4, v31, v4, s80
	v_and_b32_e32 v31, 0xffff0000, v4
	v_bfe_u32 v4, v24, 16, 1
	v_add3_u32 v24, v24, v4, s80
	v_bfe_u32 v4, v25, 16, 1
	v_add3_u32 v4, v25, v4, s80
	v_and_b32_e32 v25, 0xffff0000, v4
	v_bfe_u32 v4, v26, 16, 1
	v_add3_u32 v26, v26, v4, s80
	v_bfe_u32 v4, v27, 16, 1
	v_and_b32_e32 v8, 0xffff0000, v8
	v_add3_u32 v4, v27, v4, s80
	v_and_b32_e32 v12, 0xffff0000, v12
	v_mul_f32_e32 v8, v2, v8
	v_and_b32_e32 v9, 0xffff0000, v9
	v_and_b32_e32 v11, 0xffff0000, v11
	v_and_b32_e32 v27, 0xffff0000, v4
	v_bfe_u32 v4, v32, 16, 1
	v_mul_f32_e32 v12, v2, v12
	v_rndne_f32_e32 v8, v8
	v_mul_f32_e32 v9, v2, v9
	v_mul_f32_e32 v11, v2, v11
	v_add3_u32 v32, v32, v4, s80
	v_bfe_u32 v4, v33, 16, 1
	v_rndne_f32_e32 v12, v12
	v_cvt_i32_f32_e32 v8, v8
	v_rndne_f32_e32 v9, v9
	v_rndne_f32_e32 v11, v11
	v_add3_u32 v4, v33, v4, s80
	v_cvt_i32_f32_e32 v12, v12
	v_cvt_i32_f32_sdwa v9, v9 dst_sel:WORD_1 dst_unused:UNUSED_PAD src0_sel:DWORD
	v_cvt_i32_f32_e32 v11, v11
	v_and_b32_e32 v33, 0xffff0000, v4
	v_bfe_u32 v4, v34, 16, 1
	v_add3_u32 v34, v34, v4, s80
	v_bfe_u32 v4, v35, 16, 1
	v_add3_u32 v4, v35, v4, s80
	v_lshlrev_b32_e32 v8, 8, v8
	v_and_b32_e32 v35, 0xffff0000, v4
	v_bfe_u32 v4, v16, 16, 1
	v_and_b32_e32 v8, 0xff00, v8
	v_and_b32_e32 v9, 0xff0000, v9
	v_perm_b32 v11, v11, v12, s89
	v_add3_u32 v16, v16, v4, s80
	v_or3_b32 v8, v11, v8, v9
	v_and_b32_e32 v11, 0xffff0000, v24
	v_and_b32_e32 v9, 0xffff0000, v28
	v_mul_f32_e32 v11, v2, v11
	v_and_b32_e32 v12, 0xffff0000, v32
	v_and_b32_e32 v16, 0xffff0000, v16
	v_mul_f32_e32 v9, v2, v9
	v_rndne_f32_e32 v11, v11
	v_mul_f32_e32 v12, v2, v12
	v_mul_f32_e32 v16, v2, v16
	v_rndne_f32_e32 v9, v9
	v_cvt_i32_f32_e32 v11, v11
	v_rndne_f32_e32 v12, v12
	v_rndne_f32_e32 v16, v16
	v_cvt_i32_f32_e32 v9, v9
	v_cvt_i32_f32_sdwa v12, v12 dst_sel:WORD_1 dst_unused:UNUSED_PAD src0_sel:DWORD
	v_cvt_i32_f32_e32 v16, v16
	v_or_b32_e32 v6, v138, v233
	v_ashrrev_i32_e32 v7, 31, v6
	v_lshlrev_b32_e32 v11, 8, v11
	v_lshlrev_b64 v[6:7], 12, v[6:7]
	v_and_b32_e32 v11, 0xff00, v11
	v_and_b32_e32 v12, 0xff0000, v12
	v_perm_b32 v9, v16, v9, s89
	v_lshl_add_u64 v[6:7], v[206:207], 0, v[6:7]
	v_or3_b32 v9, v9, v11, v12
	v_and_b32_e32 v13, 0xffff0000, v13
	v_and_b32_e32 v10, 0xffff0000, v10
	global_store_dwordx2 v[6:7], v[8:9], off nt
	v_mul_f32_e32 v9, v132, v126
	v_mul_f32_e32 v8, v132, v13
	v_rndne_f32_e32 v9, v9
	v_mul_f32_e32 v10, v132, v10
	v_mul_f32_e32 v11, v132, v22
	v_rndne_f32_e32 v8, v8
	v_cvt_i32_f32_e32 v9, v9
	v_rndne_f32_e32 v10, v10
	v_rndne_f32_e32 v11, v11
	v_cvt_i32_f32_e32 v8, v8
	v_cvt_i32_f32_sdwa v10, v10 dst_sel:WORD_1 dst_unused:UNUSED_PAD src0_sel:DWORD
	v_cvt_i32_f32_e32 v11, v11
	v_bfe_u32 v4, v17, 16, 1
	v_lshlrev_b32_e32 v9, 8, v9
	v_add3_u32 v4, v17, v4, s80
	v_and_b32_e32 v9, 0xff00, v9
	v_and_b32_e32 v10, 0xff0000, v10
	v_perm_b32 v8, v11, v8, s89
	v_and_b32_e32 v17, 0xffff0000, v4
	v_or3_b32 v12, v8, v9, v10
	v_mul_f32_e32 v9, v132, v25
	v_mul_f32_e32 v8, v132, v29
	v_rndne_f32_e32 v9, v9
	v_mul_f32_e32 v10, v132, v33
	v_mul_f32_e32 v11, v132, v17
	v_rndne_f32_e32 v8, v8
	v_cvt_i32_f32_e32 v9, v9
	v_rndne_f32_e32 v10, v10
	v_rndne_f32_e32 v11, v11
	v_cvt_i32_f32_e32 v8, v8
	v_cvt_i32_f32_sdwa v10, v10 dst_sel:WORD_1 dst_unused:UNUSED_PAD src0_sel:DWORD
	v_cvt_i32_f32_e32 v11, v11
	v_lshlrev_b32_e32 v9, 8, v9
	v_and_b32_e32 v9, 0xff00, v9
	v_and_b32_e32 v10, 0xff0000, v10
	v_perm_b32 v8, v11, v8, s89
	s_movk_i32 s15, 0x1000
	v_or3_b32 v13, v8, v9, v10
	v_add_co_u32_e32 v10, vcc, s15, v6
	v_bfe_u32 v4, v18, 16, 1
	s_nop 0
	v_addc_co_u32_e32 v11, vcc, 0, v7, vcc
	v_add_co_u32_e32 v8, vcc, s84, v6
	v_add3_u32 v18, v18, v4, s80
	s_nop 0
	v_addc_co_u32_e32 v9, vcc, 0, v7, vcc
	global_store_dwordx2 v[8:9], v[12:13], off offset:-4096 nt
	v_and_b32_e32 v13, 0xffff0000, v128
	v_bfe_u32 v4, v19, 16, 1
	v_and_b32_e32 v12, 0xffff0000, v14
	v_mul_f32_e32 v13, v133, v13
	v_and_b32_e32 v14, 0xffff0000, v20
	v_and_b32_e32 v16, 0xffff0000, v23
	v_add3_u32 v4, v19, v4, s80
	v_mul_f32_e32 v12, v133, v12
	v_rndne_f32_e32 v13, v13
	v_mul_f32_e32 v14, v133, v14
	v_mul_f32_e32 v16, v133, v16
	v_and_b32_e32 v19, 0xffff0000, v4
	v_bfe_u32 v4, v44, 16, 1
	v_rndne_f32_e32 v12, v12
	v_cvt_i32_f32_e32 v13, v13
	v_rndne_f32_e32 v14, v14
	v_rndne_f32_e32 v16, v16
	v_add3_u32 v44, v44, v4, s80
	v_bfe_u32 v4, v45, 16, 1
	v_cvt_i32_f32_e32 v12, v12
	v_cvt_i32_f32_sdwa v14, v14 dst_sel:WORD_1 dst_unused:UNUSED_PAD src0_sel:DWORD
	v_cvt_i32_f32_e32 v16, v16
	v_add3_u32 v4, v45, v4, s80
	v_and_b32_e32 v45, 0xffff0000, v4
	v_bfe_u32 v4, v46, 16, 1
	v_add3_u32 v46, v46, v4, s80
	v_bfe_u32 v4, v47, 16, 1
	v_lshlrev_b32_e32 v13, 8, v13
	v_add3_u32 v4, v47, v4, s80
	v_and_b32_e32 v13, 0xff00, v13
	v_and_b32_e32 v14, 0xff0000, v14
	v_perm_b32 v12, v16, v12, s89
	v_and_b32_e32 v47, 0xffff0000, v4
	v_bfe_u32 v4, v40, 16, 1
	v_or3_b32 v12, v12, v13, v14
	v_and_b32_e32 v14, 0xffff0000, v26
	v_add3_u32 v40, v40, v4, s80
	v_bfe_u32 v4, v41, 16, 1
	v_and_b32_e32 v13, 0xffff0000, v30
	v_mul_f32_e32 v14, v133, v14
	v_and_b32_e32 v16, 0xffff0000, v34
	v_and_b32_e32 v17, 0xffff0000, v18
	v_add3_u32 v4, v41, v4, s80
	v_mul_f32_e32 v13, v133, v13
	v_rndne_f32_e32 v14, v14
	v_mul_f32_e32 v16, v133, v16
	v_mul_f32_e32 v17, v133, v17
	v_and_b32_e32 v41, 0xffff0000, v4
	v_bfe_u32 v4, v42, 16, 1
	v_rndne_f32_e32 v13, v13
	v_cvt_i32_f32_e32 v14, v14
	v_rndne_f32_e32 v16, v16
	v_rndne_f32_e32 v17, v17
	v_add3_u32 v42, v42, v4, s80
	v_bfe_u32 v4, v43, 16, 1
	v_cvt_i32_f32_e32 v13, v13
	v_cvt_i32_f32_sdwa v16, v16 dst_sel:WORD_1 dst_unused:UNUSED_PAD src0_sel:DWORD
	v_cvt_i32_f32_e32 v17, v17
	v_add3_u32 v4, v43, v4, s80
	v_and_b32_e32 v43, 0xffff0000, v4
	v_bfe_u32 v4, v52, 16, 1
	v_add3_u32 v52, v52, v4, s80
	v_bfe_u32 v4, v53, 16, 1
	v_lshlrev_b32_e32 v14, 8, v14
	v_add3_u32 v4, v53, v4, s80
	v_and_b32_e32 v14, 0xff00, v14
	v_and_b32_e32 v16, 0xff0000, v16
	v_perm_b32 v13, v17, v13, s89
	v_and_b32_e32 v53, 0xffff0000, v4
	v_bfe_u32 v4, v54, 16, 1
	v_or3_b32 v13, v13, v14, v16
	v_and_b32_e32 v15, 0xffff0000, v15
	v_add3_u32 v54, v54, v4, s80
	v_bfe_u32 v4, v55, 16, 1
	global_store_dwordx2 v[8:9], v[12:13], off nt
	v_mul_f32_e32 v13, v134, v130
	v_add3_u32 v4, v55, v4, s80
	v_mul_f32_e32 v12, v134, v15
	v_rndne_f32_e32 v13, v13
	v_mul_f32_e32 v14, v134, v21
	v_mul_f32_e32 v15, v134, v139
	v_and_b32_e32 v55, 0xffff0000, v4
	v_bfe_u32 v4, v36, 16, 1
	v_rndne_f32_e32 v12, v12
	v_cvt_i32_f32_e32 v13, v13
	v_rndne_f32_e32 v14, v14
	v_rndne_f32_e32 v15, v15
	v_add3_u32 v36, v36, v4, s80
	v_bfe_u32 v4, v37, 16, 1
	v_cvt_i32_f32_e32 v12, v12
	v_cvt_i32_f32_sdwa v14, v14 dst_sel:WORD_1 dst_unused:UNUSED_PAD src0_sel:DWORD
	v_cvt_i32_f32_e32 v15, v15
	v_add3_u32 v4, v37, v4, s80
	v_and_b32_e32 v37, 0xffff0000, v4
	v_bfe_u32 v4, v38, 16, 1
	v_add3_u32 v38, v38, v4, s80
	v_bfe_u32 v4, v39, 16, 1
	v_lshlrev_b32_e32 v13, 8, v13
	v_add3_u32 v4, v39, v4, s80
	v_and_b32_e32 v13, 0xff00, v13
	v_and_b32_e32 v14, 0xff0000, v14
	v_perm_b32 v12, v15, v12, s89
	v_and_b32_e32 v39, 0xffff0000, v4
	v_bfe_u32 v4, v60, 16, 1
	v_or3_b32 v14, v12, v13, v14
	v_mul_f32_e32 v13, v134, v27
	v_add3_u32 v60, v60, v4, s80
	v_bfe_u32 v4, v61, 16, 1
	v_mul_f32_e32 v12, v134, v31
	v_rndne_f32_e32 v13, v13
	v_mul_f32_e32 v15, v134, v35
	v_mul_f32_e32 v16, v134, v19
	v_add3_u32 v4, v61, v4, s80
	v_rndne_f32_e32 v12, v12
	v_cvt_i32_f32_e32 v13, v13
	v_rndne_f32_e32 v15, v15
	v_rndne_f32_e32 v16, v16
	v_and_b32_e32 v61, 0xffff0000, v4
	v_bfe_u32 v4, v62, 16, 1
	v_cvt_i32_f32_e32 v12, v12
	v_cvt_i32_f32_sdwa v15, v15 dst_sel:WORD_1 dst_unused:UNUSED_PAD src0_sel:DWORD
	v_cvt_i32_f32_e32 v16, v16
	v_add3_u32 v62, v62, v4, s80
	v_bfe_u32 v4, v63, 16, 1
	v_add3_u32 v4, v63, v4, s80
	v_and_b32_e32 v63, 0xffff0000, v4
	v_bfe_u32 v4, v56, 16, 1
	v_lshlrev_b32_e32 v13, 8, v13
	v_add3_u32 v56, v56, v4, s80
	v_bfe_u32 v4, v57, 16, 1
	v_and_b32_e32 v13, 0xff00, v13
	v_and_b32_e32 v15, 0xff0000, v15
	v_perm_b32 v12, v16, v12, s89
	v_add3_u32 v4, v57, v4, s80
	v_or3_b32 v15, v12, v13, v15
	v_add_co_u32_e32 v12, vcc, s91, v6
	v_and_b32_e32 v57, 0xffff0000, v4
	v_bfe_u32 v4, v58, 16, 1
	v_addc_co_u32_e32 v13, vcc, 0, v7, vcc
	v_add3_u32 v58, v58, v4, s80
	v_bfe_u32 v4, v59, 16, 1
	global_store_dwordx2 v[12:13], v[14:15], off nt
	v_and_b32_e32 v15, 0xffff0000, v40
	v_add3_u32 v4, v59, v4, s80
	v_and_b32_e32 v14, 0xffff0000, v44
	v_mul_f32_e32 v15, v2, v15
	v_and_b32_e32 v16, 0xffff0000, v52
	v_and_b32_e32 v17, 0xffff0000, v36
	v_and_b32_e32 v59, 0xffff0000, v4
	v_bfe_u32 v4, v64, 16, 1
	v_mul_f32_e32 v14, v2, v14
	v_rndne_f32_e32 v15, v15
	v_mul_f32_e32 v16, v2, v16
	v_mul_f32_e32 v17, v2, v17
	v_add3_u32 v64, v64, v4, s80
	v_bfe_u32 v4, v65, 16, 1
	v_rndne_f32_e32 v14, v14
	v_cvt_i32_f32_e32 v15, v15
	v_rndne_f32_e32 v16, v16
	v_rndne_f32_e32 v17, v17
	v_add3_u32 v4, v65, v4, s80
	v_cvt_i32_f32_e32 v14, v14
	v_cvt_i32_f32_sdwa v16, v16 dst_sel:WORD_1 dst_unused:UNUSED_PAD src0_sel:DWORD
	v_cvt_i32_f32_e32 v17, v17
	v_and_b32_e32 v65, 0xffff0000, v4
	v_bfe_u32 v4, v66, 16, 1
	v_add3_u32 v66, v66, v4, s80
	v_bfe_u32 v4, v67, 16, 1
	v_add3_u32 v4, v67, v4, s80
	v_lshlrev_b32_e32 v15, 8, v15
	v_and_b32_e32 v67, 0xffff0000, v4
	v_bfe_u32 v4, v48, 16, 1
	v_and_b32_e32 v15, 0xff00, v15
	v_and_b32_e32 v16, 0xff0000, v16
	v_perm_b32 v14, v17, v14, s89
	v_add3_u32 v48, v48, v4, s80
	v_or3_b32 v14, v14, v15, v16
	v_and_b32_e32 v16, 0xffff0000, v56
	v_and_b32_e32 v15, 0xffff0000, v60
	v_mul_f32_e32 v16, v2, v16
	v_and_b32_e32 v17, 0xffff0000, v64
	v_and_b32_e32 v18, 0xffff0000, v48
	v_mul_f32_e32 v15, v2, v15
	v_rndne_f32_e32 v16, v16
	v_mul_f32_e32 v17, v2, v17
	v_mul_f32_e32 v18, v2, v18
	v_rndne_f32_e32 v15, v15
	v_cvt_i32_f32_e32 v16, v16
	v_rndne_f32_e32 v17, v17
	v_rndne_f32_e32 v18, v18
	v_cvt_i32_f32_e32 v15, v15
	v_cvt_i32_f32_sdwa v17, v17 dst_sel:WORD_1 dst_unused:UNUSED_PAD src0_sel:DWORD
	v_cvt_i32_f32_e32 v18, v18
	v_lshlrev_b32_e32 v16, 8, v16
	v_and_b32_e32 v16, 0xff00, v16
	v_and_b32_e32 v17, 0xff0000, v17
	v_perm_b32 v15, v18, v15, s89
	v_or3_b32 v15, v15, v16, v17
	global_store_dwordx2 v[6:7], v[14:15], off offset:512 nt
	v_mul_f32_e32 v15, v132, v41
	v_mul_f32_e32 v14, v132, v45
	v_rndne_f32_e32 v15, v15
	v_mul_f32_e32 v16, v132, v53
	v_mul_f32_e32 v17, v132, v37
	v_rndne_f32_e32 v14, v14
	v_cvt_i32_f32_e32 v15, v15
	v_rndne_f32_e32 v16, v16
	v_rndne_f32_e32 v17, v17
	v_cvt_i32_f32_e32 v14, v14
	v_cvt_i32_f32_sdwa v16, v16 dst_sel:WORD_1 dst_unused:UNUSED_PAD src0_sel:DWORD
	v_cvt_i32_f32_e32 v17, v17
	v_bfe_u32 v4, v49, 16, 1
	v_lshlrev_b32_e32 v15, 8, v15
	v_add3_u32 v4, v49, v4, s80
	v_and_b32_e32 v15, 0xff00, v15
	v_and_b32_e32 v16, 0xff0000, v16
	v_perm_b32 v14, v17, v14, s89
	v_and_b32_e32 v49, 0xffff0000, v4
	v_or3_b32 v14, v14, v15, v16
	v_mul_f32_e32 v16, v132, v57
	v_mul_f32_e32 v15, v132, v61
	v_rndne_f32_e32 v16, v16
	v_mul_f32_e32 v17, v132, v65
	v_mul_f32_e32 v18, v132, v49
	v_rndne_f32_e32 v15, v15
	v_cvt_i32_f32_e32 v16, v16
	v_rndne_f32_e32 v17, v17
	v_rndne_f32_e32 v18, v18
	v_cvt_i32_f32_e32 v15, v15
	v_cvt_i32_f32_sdwa v17, v17 dst_sel:WORD_1 dst_unused:UNUSED_PAD src0_sel:DWORD
	v_cvt_i32_f32_e32 v18, v18
	v_lshlrev_b32_e32 v16, 8, v16
	v_and_b32_e32 v16, 0xff00, v16
	v_and_b32_e32 v17, 0xff0000, v17
	v_perm_b32 v15, v18, v15, s89
	v_or3_b32 v15, v15, v16, v17
	global_store_dwordx2 v[10:11], v[14:15], off offset:512 nt
	v_and_b32_e32 v15, 0xffff0000, v42
	v_and_b32_e32 v14, 0xffff0000, v46
	v_mul_f32_e32 v15, v133, v15
	v_and_b32_e32 v16, 0xffff0000, v54
	v_and_b32_e32 v17, 0xffff0000, v38
	v_mul_f32_e32 v14, v133, v14
	v_rndne_f32_e32 v15, v15
	v_mul_f32_e32 v16, v133, v16
	v_mul_f32_e32 v17, v133, v17
	v_rndne_f32_e32 v14, v14
	v_cvt_i32_f32_e32 v15, v15
	v_rndne_f32_e32 v16, v16
	v_rndne_f32_e32 v17, v17
	v_cvt_i32_f32_e32 v14, v14
	v_cvt_i32_f32_sdwa v16, v16 dst_sel:WORD_1 dst_unused:UNUSED_PAD src0_sel:DWORD
	v_cvt_i32_f32_e32 v17, v17
	v_lshlrev_b32_e32 v15, 8, v15
	v_bfe_u32 v4, v50, 16, 1
	v_and_b32_e32 v15, 0xff00, v15
	v_and_b32_e32 v16, 0xff0000, v16
	v_perm_b32 v14, v17, v14, s89
	v_add3_u32 v50, v50, v4, s80
	v_or3_b32 v14, v14, v15, v16
	v_and_b32_e32 v16, 0xffff0000, v58
	v_and_b32_e32 v15, 0xffff0000, v62
	v_mul_f32_e32 v16, v133, v16
	v_and_b32_e32 v17, 0xffff0000, v66
	v_and_b32_e32 v18, 0xffff0000, v50
	v_mul_f32_e32 v15, v133, v15
	v_rndne_f32_e32 v16, v16
	v_mul_f32_e32 v17, v133, v17
	v_mul_f32_e32 v18, v133, v18
	v_rndne_f32_e32 v15, v15
	v_cvt_i32_f32_e32 v16, v16
	v_rndne_f32_e32 v17, v17
	v_rndne_f32_e32 v18, v18
	v_cvt_i32_f32_e32 v15, v15
	v_cvt_i32_f32_sdwa v17, v17 dst_sel:WORD_1 dst_unused:UNUSED_PAD src0_sel:DWORD
	v_cvt_i32_f32_e32 v18, v18
	v_lshlrev_b32_e32 v16, 8, v16
	v_and_b32_e32 v16, 0xff00, v16
	v_and_b32_e32 v17, 0xff0000, v17
	v_perm_b32 v15, v18, v15, s89
	v_or3_b32 v15, v15, v16, v17
	global_store_dwordx2 v[8:9], v[14:15], off offset:512 nt
	v_mul_f32_e32 v15, v134, v43
	v_mul_f32_e32 v14, v134, v47
	v_rndne_f32_e32 v15, v15
	v_mul_f32_e32 v16, v134, v55
	v_mul_f32_e32 v17, v134, v39
	v_rndne_f32_e32 v14, v14
	v_cvt_i32_f32_e32 v15, v15
	v_rndne_f32_e32 v16, v16
	v_rndne_f32_e32 v17, v17
	v_cvt_i32_f32_e32 v14, v14
	v_cvt_i32_f32_sdwa v16, v16 dst_sel:WORD_1 dst_unused:UNUSED_PAD src0_sel:DWORD
	v_cvt_i32_f32_e32 v17, v17
	v_bfe_u32 v4, v51, 16, 1
	v_lshlrev_b32_e32 v15, 8, v15
	v_add3_u32 v4, v51, v4, s80
	v_and_b32_e32 v15, 0xff00, v15
	v_and_b32_e32 v16, 0xff0000, v16
	v_perm_b32 v14, v17, v14, s89
	v_and_b32_e32 v51, 0xffff0000, v4
	v_or3_b32 v14, v14, v15, v16
	v_mul_f32_e32 v16, v134, v59
	v_mul_f32_e32 v15, v134, v63
	v_rndne_f32_e32 v16, v16
	v_mul_f32_e32 v17, v134, v67
	v_mul_f32_e32 v18, v134, v51
	v_rndne_f32_e32 v15, v15
	v_cvt_i32_f32_e32 v16, v16
	v_rndne_f32_e32 v17, v17
	v_rndne_f32_e32 v18, v18
	v_cvt_i32_f32_e32 v15, v15
	v_cvt_i32_f32_sdwa v17, v17 dst_sel:WORD_1 dst_unused:UNUSED_PAD src0_sel:DWORD
	v_cvt_i32_f32_e32 v18, v18
	v_lshlrev_b32_e32 v16, 8, v16
	v_bfe_u32 v141, v83, 16, 1
	v_and_b32_e32 v16, 0xff00, v16
	v_and_b32_e32 v17, 0xff0000, v17
	v_perm_b32 v15, v18, v15, s89
	v_bfe_u32 v137, v73, 16, 1
	v_bfe_u32 v165, v131, 16, 1
	v_bfe_u32 v168, v76, 16, 1
	v_add3_u32 v141, v83, v141, s80
	v_bfe_u32 v83, v68, 16, 1
	v_or3_b32 v15, v15, v16, v17
	v_add3_u32 v73, v73, v137, s80
	v_add3_u32 v165, v131, v165, s80
	v_add3_u32 v137, v76, v168, s80
	v_add3_u32 v131, v68, v83, s80
	global_store_dwordx2 v[12:13], v[14:15], off offset:512 nt
	v_and_b32_e32 v15, 0xffff0000, v136
	v_and_b32_e32 v14, 0xffff0000, v137
	v_mul_f32_e32 v15, v2, v15
	v_and_b32_e32 v16, 0xffff0000, v135
	v_and_b32_e32 v17, 0xffff0000, v131
	v_mul_f32_e32 v14, v2, v14
	v_rndne_f32_e32 v15, v15
	v_mul_f32_e32 v16, v2, v16
	v_mul_f32_e32 v17, v2, v17
	v_rndne_f32_e32 v14, v14
	v_cvt_i32_f32_e32 v15, v15
	v_rndne_f32_e32 v16, v16
	v_rndne_f32_e32 v17, v17
	v_cvt_i32_f32_e32 v14, v14
	v_cvt_i32_f32_sdwa v16, v16 dst_sel:WORD_1 dst_unused:UNUSED_PAD src0_sel:DWORD
	v_cvt_i32_f32_e32 v17, v17
	v_bfe_u32 v145, v95, 16, 1
	v_bfe_u32 v143, v71, 16, 1
	v_bfe_u32 v161, v127, 16, 1
	v_add3_u32 v145, v95, v145, s80
	v_bfe_u32 v95, v88, 16, 1
	v_lshlrev_b32_e32 v15, 8, v15
	v_bfe_u32 v164, v129, 16, 1
	v_add3_u32 v71, v71, v143, s80
	v_bfe_u32 v143, v92, 16, 1
	v_add3_u32 v161, v127, v161, s80
	v_add3_u32 v127, v88, v95, s80
	v_and_b32_e32 v15, 0xff00, v15
	v_and_b32_e32 v16, 0xff0000, v16
	v_perm_b32 v14, v17, v14, s89
	v_add3_u32 v164, v129, v164, s80
	v_add3_u32 v129, v92, v143, s80
	v_or3_b32 v14, v14, v15, v16
	v_and_b32_e32 v16, 0xffff0000, v127
	v_and_b32_e32 v15, 0xffff0000, v129
	v_mul_f32_e32 v16, v2, v16
	v_and_b32_e32 v17, 0xffff0000, v125
	v_and_b32_e32 v18, 0xffff0000, v123
	v_mul_f32_e32 v15, v2, v15
	v_rndne_f32_e32 v16, v16
	v_mul_f32_e32 v17, v2, v17
	v_mul_f32_e32 v18, v2, v18
	v_rndne_f32_e32 v15, v15
	v_cvt_i32_f32_e32 v16, v16
	v_rndne_f32_e32 v17, v17
	v_rndne_f32_e32 v18, v18
	v_cvt_i32_f32_e32 v15, v15
	v_cvt_i32_f32_sdwa v17, v17 dst_sel:WORD_1 dst_unused:UNUSED_PAD src0_sel:DWORD
	v_cvt_i32_f32_e32 v18, v18
	v_lshlrev_b32_e32 v16, 8, v16
	v_bfe_u32 v140, v81, 16, 1
	v_bfe_u32 v142, v69, 16, 1
	v_bfe_u32 v144, v93, 16, 1
	v_bfe_u32 v159, v103, 16, 1
	v_bfe_u32 v178, v122, 16, 1
	v_and_b32_e32 v16, 0xff00, v16
	v_and_b32_e32 v17, 0xff0000, v17
	v_perm_b32 v15, v18, v15, s89
	v_bfe_u32 v156, v113, 16, 1
	v_add3_u32 v140, v81, v140, s80
	v_add3_u32 v69, v69, v142, s80
	v_add3_u32 v93, v93, v144, s80
	v_bfe_u32 v144, v94, 16, 1
	v_add3_u32 v159, v103, v159, s80
	v_bfe_u32 v103, v124, 16, 1
	v_bfe_u32 v177, v120, 16, 1
	v_bfe_u32 v182, v118, 16, 1
	v_add3_u32 v78, v122, v178, s80
	v_and_b32_e32 v122, 0xffff0000, v73
	v_or3_b32 v15, v15, v16, v17
	v_add3_u32 v156, v113, v156, s80
	v_add3_u32 v113, v94, v144, s80
	v_add3_u32 v95, v124, v103, s80
	v_add3_u32 v94, v120, v177, s80
	v_add3_u32 v72, v118, v182, s80
	v_and_b32_e32 v124, 0xffff0000, v77
	v_and_b32_e32 v120, 0xffff0000, v140
	v_and_b32_e32 v118, 0xffff0000, v69
	global_store_dwordx2 v[6:7], v[14:15], off offset:1024 nt
	v_mul_f32_e32 v15, v132, v122
	v_mul_f32_e32 v14, v132, v124
	v_rndne_f32_e32 v15, v15
	v_mul_f32_e32 v16, v132, v120
	v_mul_f32_e32 v17, v132, v118
	v_rndne_f32_e32 v14, v14
	v_cvt_i32_f32_e32 v15, v15
	v_rndne_f32_e32 v16, v16
	v_rndne_f32_e32 v17, v17
	v_cvt_i32_f32_e32 v14, v14
	v_cvt_i32_f32_sdwa v16, v16 dst_sel:WORD_1 dst_unused:UNUSED_PAD src0_sel:DWORD
	v_cvt_i32_f32_e32 v17, v17
	v_bfe_u32 v146, v89, 16, 1
	v_bfe_u32 v148, v97, 16, 1
	v_bfe_u32 v150, v85, 16, 1
	v_bfe_u32 v152, v109, 16, 1
	v_bfe_u32 v166, v117, 16, 1
	v_bfe_u32 v81, v82, 16, 1
	v_add3_u32 v89, v89, v146, s80
	v_bfe_u32 v174, v114, 16, 1
	v_lshlrev_b32_e32 v15, 8, v15
	v_bfe_u32 v155, v107, 16, 1
	v_add3_u32 v148, v97, v148, s80
	v_bfe_u32 v97, v98, 16, 1
	v_add3_u32 v85, v85, v150, s80
	v_add3_u32 v152, v109, v152, s80
	v_bfe_u32 v109, v110, 16, 1
	v_bfe_u32 v173, v112, 16, 1
	v_bfe_u32 v181, v116, 16, 1
	v_add3_u32 v166, v117, v166, s80
	v_add3_u32 v117, v82, v81, s80
	v_add3_u32 v81, v114, v174, s80
	v_and_b32_e32 v114, 0xffff0000, v89
	v_and_b32_e32 v15, 0xff00, v15
	v_and_b32_e32 v16, 0xff0000, v16
	v_perm_b32 v14, v17, v14, s89
	v_add3_u32 v155, v107, v155, s80
	v_add3_u32 v107, v98, v97, s80
	v_add3_u32 v83, v110, v109, s80
	v_add3_u32 v97, v112, v173, s80
	v_add3_u32 v88, v116, v181, s80
	v_and_b32_e32 v116, 0xffff0000, v93
	v_and_b32_e32 v112, 0xffff0000, v148
	v_and_b32_e32 v110, 0xffff0000, v85
	v_or3_b32 v14, v14, v15, v16
	v_mul_f32_e32 v16, v132, v114
	v_mul_f32_e32 v15, v132, v116
	v_rndne_f32_e32 v16, v16
	v_mul_f32_e32 v17, v132, v112
	v_mul_f32_e32 v18, v132, v110
	v_rndne_f32_e32 v15, v15
	v_cvt_i32_f32_e32 v16, v16
	v_rndne_f32_e32 v17, v17
	v_rndne_f32_e32 v18, v18
	v_cvt_i32_f32_e32 v15, v15
	v_cvt_i32_f32_sdwa v17, v17 dst_sel:WORD_1 dst_unused:UNUSED_PAD src0_sel:DWORD
	v_cvt_i32_f32_e32 v18, v18
	v_lshlrev_b32_e32 v16, 8, v16
	v_bfe_u32 v167, v119, 16, 1
	v_bfe_u32 v170, v74, 16, 1
	v_and_b32_e32 v16, 0xff00, v16
	v_and_b32_e32 v17, 0xff0000, v17
	v_perm_b32 v15, v18, v15, s89
	v_bfe_u32 v157, v115, 16, 1
	v_bfe_u32 v142, v70, 16, 1
	v_add3_u32 v167, v119, v167, s80
	v_add3_u32 v119, v74, v170, s80
	v_or3_b32 v15, v15, v16, v17
	v_add3_u32 v157, v115, v157, s80
	v_add3_u32 v115, v70, v142, s80
	global_store_dwordx2 v[10:11], v[14:15], off offset:1024 nt
	v_and_b32_e32 v15, 0xffff0000, v119
	v_and_b32_e32 v14, 0xffff0000, v121
	v_mul_f32_e32 v15, v133, v15
	v_and_b32_e32 v16, 0xffff0000, v117
	v_and_b32_e32 v17, 0xffff0000, v115
	v_mul_f32_e32 v14, v133, v14
	v_rndne_f32_e32 v15, v15
	v_mul_f32_e32 v16, v133, v16
	v_mul_f32_e32 v17, v133, v17
	v_rndne_f32_e32 v14, v14
	v_cvt_i32_f32_e32 v15, v15
	v_rndne_f32_e32 v16, v16
	v_rndne_f32_e32 v17, v17
	v_cvt_i32_f32_e32 v14, v14
	v_cvt_i32_f32_sdwa v16, v16 dst_sel:WORD_1 dst_unused:UNUSED_PAD src0_sel:DWORD
	v_cvt_i32_f32_e32 v17, v17
	v_bfe_u32 v153, v111, 16, 1
	v_bfe_u32 v146, v90, 16, 1
	v_lshlrev_b32_e32 v15, 8, v15
	v_bfe_u32 v154, v105, 16, 1
	v_bfe_u32 v150, v86, 16, 1
	v_add3_u32 v153, v111, v153, s80
	v_add3_u32 v111, v90, v146, s80
	v_and_b32_e32 v15, 0xff00, v15
	v_and_b32_e32 v16, 0xff0000, v16
	v_perm_b32 v14, v17, v14, s89
	v_add3_u32 v154, v105, v154, s80
	v_add3_u32 v105, v86, v150, s80
	v_or3_b32 v14, v14, v15, v16
	v_and_b32_e32 v16, 0xffff0000, v111
	v_and_b32_e32 v15, 0xffff0000, v113
	v_mul_f32_e32 v16, v133, v16
	v_and_b32_e32 v17, 0xffff0000, v107
	v_and_b32_e32 v18, 0xffff0000, v105
	v_mul_f32_e32 v15, v133, v15
	v_rndne_f32_e32 v16, v16
	v_mul_f32_e32 v17, v133, v17
	v_mul_f32_e32 v18, v133, v18
	v_rndne_f32_e32 v15, v15
	v_cvt_i32_f32_e32 v16, v16
	v_rndne_f32_e32 v17, v17
	v_rndne_f32_e32 v18, v18
	v_cvt_i32_f32_e32 v15, v15
	v_cvt_i32_f32_sdwa v17, v17 dst_sel:WORD_1 dst_unused:UNUSED_PAD src0_sel:DWORD
	v_cvt_i32_f32_e32 v18, v18
	v_lshlrev_b32_e32 v16, 8, v16
	v_and_b32_e32 v16, 0xff00, v16
	v_and_b32_e32 v17, 0xff0000, v17
	v_perm_b32 v15, v18, v15, s89
	v_bfe_u32 v171, v104, 16, 1
	v_bfe_u32 v172, v106, 16, 1
	v_or3_b32 v15, v15, v16, v17
	v_add3_u32 v98, v104, v171, s80
	v_add3_u32 v82, v106, v172, s80
	v_and_b32_e32 v109, 0xffff0000, v169
	v_and_b32_e32 v106, 0xffff0000, v141
	v_and_b32_e32 v104, 0xffff0000, v71
	global_store_dwordx2 v[8:9], v[14:15], off offset:1024 nt
	v_mul_f32_e32 v15, v134, v108
	v_mul_f32_e32 v14, v134, v109
	v_rndne_f32_e32 v15, v15
	v_mul_f32_e32 v16, v134, v106
	v_mul_f32_e32 v17, v134, v104
	v_rndne_f32_e32 v14, v14
	v_cvt_i32_f32_e32 v15, v15
	v_rndne_f32_e32 v16, v16
	v_rndne_f32_e32 v17, v17
	v_cvt_i32_f32_e32 v14, v14
	v_cvt_i32_f32_sdwa v16, v16 dst_sel:WORD_1 dst_unused:UNUSED_PAD src0_sel:DWORD
	v_cvt_i32_f32_e32 v17, v17
	v_bfe_u32 v158, v101, 16, 1
	v_add3_u32 v158, v101, v158, s80
	v_bfe_u32 v101, v102, 16, 1
	v_lshlrev_b32_e32 v15, 8, v15
	v_bfe_u32 v175, v100, 16, 1
	v_add3_u32 v80, v102, v101, s80
	v_and_b32_e32 v102, 0xffff0000, v147
	v_and_b32_e32 v15, 0xff00, v15
	v_and_b32_e32 v16, 0xff0000, v16
	v_perm_b32 v14, v17, v14, s89
	v_add3_u32 v96, v100, v175, s80
	v_and_b32_e32 v103, 0xffff0000, v145
	v_and_b32_e32 v101, 0xffff0000, v149
	v_and_b32_e32 v100, 0xffff0000, v87
	v_or3_b32 v14, v14, v15, v16
	v_mul_f32_e32 v16, v134, v102
	v_mul_f32_e32 v15, v134, v103
	v_rndne_f32_e32 v16, v16
	v_mul_f32_e32 v17, v134, v101
	v_mul_f32_e32 v18, v134, v100
	v_rndne_f32_e32 v15, v15
	v_cvt_i32_f32_e32 v16, v16
	v_rndne_f32_e32 v17, v17
	v_rndne_f32_e32 v18, v18
	v_cvt_i32_f32_e32 v15, v15
	v_cvt_i32_f32_sdwa v17, v17 dst_sel:WORD_1 dst_unused:UNUSED_PAD src0_sel:DWORD
	v_cvt_i32_f32_e32 v18, v18
	v_lshlrev_b32_e32 v16, 8, v16
	v_and_b32_e32 v16, 0xff00, v16
	v_and_b32_e32 v17, 0xff0000, v17
	v_perm_b32 v15, v18, v15, s89
	v_or3_b32 v15, v15, v16, v17
	global_store_dwordx2 v[12:13], v[14:15], off offset:1024 nt
	v_and_b32_e32 v15, 0xffff0000, v98
	v_and_b32_e32 v14, 0xffff0000, v99
	v_mul_f32_e32 v15, v2, v15
	v_and_b32_e32 v16, 0xffff0000, v97
	v_and_b32_e32 v17, 0xffff0000, v96
	v_mul_f32_e32 v14, v2, v14
	v_rndne_f32_e32 v15, v15
	v_mul_f32_e32 v16, v2, v16
	v_mul_f32_e32 v17, v2, v17
	v_rndne_f32_e32 v14, v14
	v_cvt_i32_f32_e32 v15, v15
	v_rndne_f32_e32 v16, v16
	v_rndne_f32_e32 v17, v17
	v_cvt_i32_f32_e32 v14, v14
	v_cvt_i32_f32_sdwa v16, v16 dst_sel:WORD_1 dst_unused:UNUSED_PAD src0_sel:DWORD
	v_cvt_i32_f32_e32 v17, v17
	v_lshlrev_b32_e32 v15, 8, v15
	v_and_b32_e32 v15, 0xff00, v15
	v_and_b32_e32 v16, 0xff0000, v16
	v_perm_b32 v14, v17, v14, s89
	v_or3_b32 v14, v14, v15, v16
	v_and_b32_e32 v16, 0xffff0000, v94
	v_and_b32_e32 v15, 0xffff0000, v95
	v_mul_f32_e32 v16, v2, v16
	v_and_b32_e32 v17, 0xffff0000, v91
	v_and_b32_e32 v18, 0xffff0000, v88
	v_mul_f32_e32 v15, v2, v15
	v_rndne_f32_e32 v16, v16
	v_mul_f32_e32 v17, v2, v17
	v_mul_f32_e32 v18, v2, v18
	v_rndne_f32_e32 v15, v15
	v_cvt_i32_f32_e32 v16, v16
	v_rndne_f32_e32 v17, v17
	v_rndne_f32_e32 v18, v18
	v_cvt_i32_f32_e32 v15, v15
	v_cvt_i32_f32_sdwa v17, v17 dst_sel:WORD_1 dst_unused:UNUSED_PAD src0_sel:DWORD
	v_cvt_i32_f32_e32 v18, v18
	v_lshlrev_b32_e32 v16, 8, v16
	v_and_b32_e32 v16, 0xff00, v16
	v_and_b32_e32 v17, 0xff0000, v17
	v_perm_b32 v15, v18, v15, s89
	v_and_b32_e32 v92, 0xffff0000, v154
	v_or3_b32 v15, v15, v16, v17
	v_and_b32_e32 v93, 0xffff0000, v152
	v_and_b32_e32 v90, 0xffff0000, v156
	v_and_b32_e32 v89, 0xffff0000, v158
	global_store_dwordx2 v[6:7], v[14:15], off offset:1536 nt
	v_mul_f32_e32 v7, v132, v92
	v_mul_f32_e32 v6, v132, v93
	v_rndne_f32_e32 v7, v7
	v_mul_f32_e32 v14, v132, v90
	v_mul_f32_e32 v15, v132, v89
	v_rndne_f32_e32 v6, v6
	v_cvt_i32_f32_e32 v7, v7
	v_rndne_f32_e32 v14, v14
	v_rndne_f32_e32 v15, v15
	v_cvt_i32_f32_e32 v6, v6
	v_cvt_i32_f32_sdwa v14, v14 dst_sel:WORD_1 dst_unused:UNUSED_PAD src0_sel:DWORD
	v_cvt_i32_f32_e32 v15, v15
	v_lshlrev_b32_e32 v7, 8, v7
	v_and_b32_e32 v86, 0xffff0000, v162
	v_and_b32_e32 v7, 0xff00, v7
	v_and_b32_e32 v14, 0xff0000, v14
	v_perm_b32 v6, v15, v6, s89
	v_and_b32_e32 v87, 0xffff0000, v160
	v_and_b32_e32 v85, 0xffff0000, v164
	v_and_b32_e32 v84, 0xffff0000, v166
	v_or3_b32 v6, v6, v7, v14
	v_mul_f32_e32 v14, v132, v86
	v_mul_f32_e32 v7, v132, v87
	v_rndne_f32_e32 v14, v14
	v_mul_f32_e32 v15, v132, v85
	v_mul_f32_e32 v16, v132, v84
	v_rndne_f32_e32 v7, v7
	v_cvt_i32_f32_e32 v14, v14
	v_rndne_f32_e32 v15, v15
	v_rndne_f32_e32 v16, v16
	v_cvt_i32_f32_e32 v7, v7
	v_cvt_i32_f32_sdwa v15, v15 dst_sel:WORD_1 dst_unused:UNUSED_PAD src0_sel:DWORD
	v_cvt_i32_f32_e32 v16, v16
	v_lshlrev_b32_e32 v14, 8, v14
	v_and_b32_e32 v14, 0xff00, v14
	v_and_b32_e32 v15, 0xff0000, v15
	v_perm_b32 v7, v16, v7, s89
	v_or3_b32 v7, v7, v14, v15
	global_store_dwordx2 v[10:11], v[6:7], off offset:1536 nt
	v_and_b32_e32 v7, 0xffff0000, v82
	v_and_b32_e32 v6, 0xffff0000, v83
	v_mul_f32_e32 v7, v133, v7
	v_and_b32_e32 v10, 0xffff0000, v81
	v_and_b32_e32 v11, 0xffff0000, v80
	v_mul_f32_e32 v6, v133, v6
	v_rndne_f32_e32 v7, v7
	v_mul_f32_e32 v10, v133, v10
	v_mul_f32_e32 v11, v133, v11
	v_rndne_f32_e32 v6, v6
	v_cvt_i32_f32_e32 v7, v7
	v_rndne_f32_e32 v10, v10
	v_rndne_f32_e32 v11, v11
	v_cvt_i32_f32_e32 v6, v6
	v_cvt_i32_f32_sdwa v10, v10 dst_sel:WORD_1 dst_unused:UNUSED_PAD src0_sel:DWORD
	v_cvt_i32_f32_e32 v11, v11
	v_lshlrev_b32_e32 v7, 8, v7
	v_and_b32_e32 v7, 0xff00, v7
	v_and_b32_e32 v10, 0xff0000, v10
	v_perm_b32 v6, v11, v6, s89
	v_or3_b32 v6, v6, v7, v10
	v_and_b32_e32 v10, 0xffff0000, v78
	v_and_b32_e32 v7, 0xffff0000, v79
	v_mul_f32_e32 v10, v133, v10
	v_and_b32_e32 v11, 0xffff0000, v75
	v_and_b32_e32 v14, 0xffff0000, v72
	v_mul_f32_e32 v7, v133, v7
	v_rndne_f32_e32 v10, v10
	v_mul_f32_e32 v11, v133, v11
	v_mul_f32_e32 v14, v133, v14
	v_rndne_f32_e32 v7, v7
	v_cvt_i32_f32_e32 v10, v10
	v_rndne_f32_e32 v11, v11
	v_rndne_f32_e32 v14, v14
	v_cvt_i32_f32_e32 v7, v7
	v_cvt_i32_f32_sdwa v11, v11 dst_sel:WORD_1 dst_unused:UNUSED_PAD src0_sel:DWORD
	v_cvt_i32_f32_e32 v14, v14
	v_lshlrev_b32_e32 v10, 8, v10
	v_and_b32_e32 v10, 0xff00, v10
	v_and_b32_e32 v11, 0xff0000, v11
	v_perm_b32 v7, v14, v7, s89
	v_and_b32_e32 v76, 0xffff0000, v155
	v_or3_b32 v7, v7, v10, v11
	v_and_b32_e32 v77, 0xffff0000, v153
	v_and_b32_e32 v74, 0xffff0000, v157
	v_and_b32_e32 v73, 0xffff0000, v159
	global_store_dwordx2 v[8:9], v[6:7], off offset:1536 nt
	v_mul_f32_e32 v7, v134, v76
	v_mul_f32_e32 v6, v134, v77
	v_rndne_f32_e32 v7, v7
	v_mul_f32_e32 v8, v134, v74
	v_mul_f32_e32 v9, v134, v73
	v_rndne_f32_e32 v6, v6
	v_cvt_i32_f32_e32 v7, v7
	v_rndne_f32_e32 v8, v8
	v_rndne_f32_e32 v9, v9
	v_cvt_i32_f32_e32 v6, v6
	v_cvt_i32_f32_sdwa v8, v8 dst_sel:WORD_1 dst_unused:UNUSED_PAD src0_sel:DWORD
	v_cvt_i32_f32_e32 v9, v9
	v_lshlrev_b32_e32 v7, 8, v7
	v_and_b32_e32 v70, 0xffff0000, v163
	v_and_b32_e32 v7, 0xff00, v7
	v_and_b32_e32 v8, 0xff0000, v8
	v_perm_b32 v6, v9, v6, s89
	v_and_b32_e32 v71, 0xffff0000, v161
	v_and_b32_e32 v69, 0xffff0000, v165
	v_and_b32_e32 v68, 0xffff0000, v167
	v_or3_b32 v6, v6, v7, v8
	v_mul_f32_e32 v8, v134, v70
	v_mul_f32_e32 v7, v134, v71
	v_rndne_f32_e32 v8, v8
	v_mul_f32_e32 v9, v134, v69
	v_mul_f32_e32 v10, v134, v68
	v_rndne_f32_e32 v7, v7
	v_cvt_i32_f32_e32 v8, v8
	v_rndne_f32_e32 v9, v9
	v_rndne_f32_e32 v10, v10
	v_cvt_i32_f32_e32 v7, v7
	v_cvt_i32_f32_sdwa v9, v9 dst_sel:WORD_1 dst_unused:UNUSED_PAD src0_sel:DWORD
	v_cvt_i32_f32_e32 v10, v10
	v_lshlrev_b32_e32 v8, 8, v8
	v_ashrrev_i32_e32 v209, 31, v208
	v_and_b32_e32 v8, 0xff00, v8
	v_and_b32_e32 v9, 0xff0000, v9
	v_perm_b32 v7, v10, v7, s89
	v_lshlrev_b64 v[4:5], 12, v[208:209]
	v_or3_b32 v7, v7, v8, v9
	v_lshl_add_u64 v[4:5], v[204:205], 0, v[4:5]
	global_store_dwordx2 v[12:13], v[6:7], off offset:1536 nt
	s_mov_b64 s[16:17], 0
	v_mov_b32_e32 v6, v234
.LBB0_1505:
	ds_read_b128 v[8:11], v6
	ds_read_b128 v[12:15], v6 offset:8192
	ds_read_b128 v[16:19], v6 offset:16384
	ds_read_b128 v[20:23], v6 offset:24576
	v_lshl_add_u64 v[24:25], v[4:5], 0, s[16:17]
	s_waitcnt lgkmcnt(3)
	v_lshlrev_b32_e32 v26, 16, v10
	v_lshlrev_b32_e32 v7, 16, v8
	v_mul_f32_e32 v26, v2, v26
	s_waitcnt lgkmcnt(2)
	v_lshlrev_b32_e32 v27, 16, v12
	v_mul_f32_e32 v7, v2, v7
	v_rndne_f32_e32 v26, v26
	v_mul_f32_e32 v27, v2, v27
	v_lshlrev_b32_e32 v28, 16, v14
	v_rndne_f32_e32 v7, v7
	v_cvt_i32_f32_e32 v26, v26
	v_rndne_f32_e32 v27, v27
	v_mul_f32_e32 v28, v2, v28
	v_cvt_i32_f32_e32 v7, v7
	v_cvt_i32_f32_sdwa v27, v27 dst_sel:WORD_1 dst_unused:UNUSED_PAD src0_sel:DWORD
	v_rndne_f32_e32 v28, v28
	v_cvt_i32_f32_sdwa v28, v28 dst_sel:BYTE_3 dst_unused:UNUSED_PAD src0_sel:DWORD
	v_lshlrev_b32_e32 v26, 8, v26
	v_and_b32_e32 v27, 0xff0000, v27
	v_perm_b32 v7, v26, v7, s76
	v_or3_b32 v26, v7, v28, v27
	s_waitcnt lgkmcnt(1)
	v_lshlrev_b32_e32 v27, 16, v18
	v_lshlrev_b32_e32 v7, 16, v16
	v_mul_f32_e32 v27, v2, v27
	s_waitcnt lgkmcnt(0)
	v_lshlrev_b32_e32 v28, 16, v20
	v_mul_f32_e32 v7, v2, v7
	v_rndne_f32_e32 v27, v27
	v_mul_f32_e32 v28, v2, v28
	v_lshlrev_b32_e32 v29, 16, v22
	v_rndne_f32_e32 v7, v7
	v_cvt_i32_f32_e32 v27, v27
	v_rndne_f32_e32 v28, v28
	v_mul_f32_e32 v29, v2, v29
	v_cvt_i32_f32_e32 v7, v7
	v_cvt_i32_f32_sdwa v28, v28 dst_sel:WORD_1 dst_unused:UNUSED_PAD src0_sel:DWORD
	v_rndne_f32_e32 v29, v29
	v_cvt_i32_f32_sdwa v29, v29 dst_sel:BYTE_3 dst_unused:UNUSED_PAD src0_sel:DWORD
	v_lshlrev_b32_e32 v27, 8, v27
	v_and_b32_e32 v28, 0xff0000, v28
	v_perm_b32 v7, v27, v7, s76
	v_or3_b32 v27, v7, v29, v28
	v_and_b32_e32 v7, 0xffff0000, v8
	v_and_b32_e32 v8, 0xffff0000, v10
	v_mul_f32_e32 v8, v132, v8
	v_and_b32_e32 v10, 0xffff0000, v12
	v_mul_f32_e32 v7, v132, v7
	v_rndne_f32_e32 v8, v8
	v_mul_f32_e32 v10, v132, v10
	v_and_b32_e32 v12, 0xffff0000, v14
	v_rndne_f32_e32 v7, v7
	v_cvt_i32_f32_e32 v8, v8
	v_rndne_f32_e32 v10, v10
	v_mul_f32_e32 v12, v132, v12
	v_cvt_i32_f32_e32 v7, v7
	v_cvt_i32_f32_sdwa v10, v10 dst_sel:WORD_1 dst_unused:UNUSED_PAD src0_sel:DWORD
	v_rndne_f32_e32 v12, v12
	v_cvt_i32_f32_sdwa v12, v12 dst_sel:BYTE_3 dst_unused:UNUSED_PAD src0_sel:DWORD
	v_add_co_u32_e32 v28, vcc, s77, v24
	v_lshlrev_b32_e32 v8, 8, v8
	s_nop 0
	v_addc_co_u32_e32 v29, vcc, 0, v25, vcc
	v_and_b32_e32 v10, 0xff0000, v10
	v_perm_b32 v7, v8, v7, s76
	v_and_b32_e32 v8, 0xffff0000, v18
	global_store_dwordx2 v[28:29], v[26:27], off offset:2048 nt
	v_or3_b32 v26, v7, v12, v10
	v_and_b32_e32 v7, 0xffff0000, v16
	v_mul_f32_e32 v8, v132, v8
	v_and_b32_e32 v10, 0xffff0000, v20
	v_mul_f32_e32 v7, v132, v7
	v_rndne_f32_e32 v8, v8
	v_mul_f32_e32 v10, v132, v10
	v_and_b32_e32 v12, 0xffff0000, v22
	v_rndne_f32_e32 v7, v7
	v_cvt_i32_f32_e32 v8, v8
	v_rndne_f32_e32 v10, v10
	v_mul_f32_e32 v12, v132, v12
	v_cvt_i32_f32_e32 v7, v7
	v_cvt_i32_f32_sdwa v10, v10 dst_sel:WORD_1 dst_unused:UNUSED_PAD src0_sel:DWORD
	v_rndne_f32_e32 v12, v12
	v_cvt_i32_f32_sdwa v12, v12 dst_sel:BYTE_3 dst_unused:UNUSED_PAD src0_sel:DWORD
	v_lshlrev_b32_e32 v8, 8, v8
	v_and_b32_e32 v10, 0xff0000, v10
	v_perm_b32 v7, v8, v7, s76
	v_lshlrev_b32_e32 v8, 16, v11
	v_or3_b32 v27, v7, v12, v10
	v_lshlrev_b32_e32 v7, 16, v9
	v_mul_f32_e32 v8, v133, v8
	v_lshlrev_b32_e32 v10, 16, v13
	v_mul_f32_e32 v7, v133, v7
	v_rndne_f32_e32 v8, v8
	v_mul_f32_e32 v10, v133, v10
	v_lshlrev_b32_e32 v12, 16, v15
	v_rndne_f32_e32 v7, v7
	v_cvt_i32_f32_e32 v8, v8
	v_rndne_f32_e32 v10, v10
	v_mul_f32_e32 v12, v133, v12
	v_cvt_i32_f32_e32 v7, v7
	v_cvt_i32_f32_sdwa v10, v10 dst_sel:WORD_1 dst_unused:UNUSED_PAD src0_sel:DWORD
	v_rndne_f32_e32 v12, v12
	v_cvt_i32_f32_sdwa v12, v12 dst_sel:BYTE_3 dst_unused:UNUSED_PAD src0_sel:DWORD
	v_add_co_u32_e32 v28, vcc, s82, v24
	v_lshlrev_b32_e32 v8, 8, v8
	s_nop 0
	v_addc_co_u32_e32 v29, vcc, 0, v25, vcc
	v_and_b32_e32 v10, 0xff0000, v10
	v_perm_b32 v7, v8, v7, s76
	v_lshlrev_b32_e32 v8, 16, v19
	global_store_dwordx2 v[28:29], v[26:27], off offset:2048 nt
	v_or3_b32 v26, v7, v12, v10
	v_lshlrev_b32_e32 v7, 16, v17
	v_mul_f32_e32 v8, v133, v8
	v_lshlrev_b32_e32 v10, 16, v21
	v_mul_f32_e32 v7, v133, v7
	v_rndne_f32_e32 v8, v8
	v_mul_f32_e32 v10, v133, v10
	v_lshlrev_b32_e32 v12, 16, v23
	v_rndne_f32_e32 v7, v7
	v_cvt_i32_f32_e32 v8, v8
	v_rndne_f32_e32 v10, v10
	v_mul_f32_e32 v12, v133, v12
	v_cvt_i32_f32_e32 v7, v7
	v_cvt_i32_f32_sdwa v10, v10 dst_sel:WORD_1 dst_unused:UNUSED_PAD src0_sel:DWORD
	v_rndne_f32_e32 v12, v12
	v_cvt_i32_f32_sdwa v12, v12 dst_sel:BYTE_3 dst_unused:UNUSED_PAD src0_sel:DWORD
	v_lshlrev_b32_e32 v8, 8, v8
	v_and_b32_e32 v10, 0xff0000, v10
	v_perm_b32 v7, v8, v7, s76
	v_and_b32_e32 v8, 0xffff0000, v11
	v_or3_b32 v27, v7, v12, v10
	v_and_b32_e32 v7, 0xffff0000, v9
	v_mul_f32_e32 v8, v134, v8
	v_and_b32_e32 v9, 0xffff0000, v13
	v_mul_f32_e32 v7, v134, v7
	v_rndne_f32_e32 v8, v8
	v_mul_f32_e32 v9, v134, v9
	v_and_b32_e32 v10, 0xffff0000, v15
	v_rndne_f32_e32 v7, v7
	v_cvt_i32_f32_e32 v8, v8
	v_rndne_f32_e32 v9, v9
	v_mul_f32_e32 v10, v134, v10
	v_cvt_i32_f32_e32 v7, v7
	v_cvt_i32_f32_sdwa v9, v9 dst_sel:WORD_1 dst_unused:UNUSED_PAD src0_sel:DWORD
	v_rndne_f32_e32 v10, v10
	v_cvt_i32_f32_sdwa v10, v10 dst_sel:BYTE_3 dst_unused:UNUSED_PAD src0_sel:DWORD
	v_lshlrev_b32_e32 v8, 8, v8
	v_and_b32_e32 v9, 0xff0000, v9
	v_perm_b32 v7, v8, v7, s76
	v_or3_b32 v8, v7, v10, v9
	v_and_b32_e32 v9, 0xffff0000, v19
	v_and_b32_e32 v7, 0xffff0000, v17
	v_mul_f32_e32 v9, v134, v9
	v_and_b32_e32 v10, 0xffff0000, v21
	v_mul_f32_e32 v7, v134, v7
	v_rndne_f32_e32 v9, v9
	v_mul_f32_e32 v10, v134, v10
	v_and_b32_e32 v11, 0xffff0000, v23
	v_rndne_f32_e32 v7, v7
	v_cvt_i32_f32_e32 v9, v9
	v_rndne_f32_e32 v10, v10
	v_mul_f32_e32 v11, v134, v11
	v_cvt_i32_f32_e32 v7, v7
	v_cvt_i32_f32_sdwa v10, v10 dst_sel:WORD_1 dst_unused:UNUSED_PAD src0_sel:DWORD
	v_rndne_f32_e32 v11, v11
	v_cvt_i32_f32_sdwa v11, v11 dst_sel:BYTE_3 dst_unused:UNUSED_PAD src0_sel:DWORD
	v_add_co_u32_e32 v28, vcc, s83, v24
	v_lshlrev_b32_e32 v9, 8, v9
	s_nop 0
	v_addc_co_u32_e32 v29, vcc, 0, v25, vcc
	v_and_b32_e32 v10, 0xff0000, v10
	v_perm_b32 v7, v9, v7, s76
	s_add_u32 s16, s16, 0x200
	v_or3_b32 v9, v7, v11, v10
	v_add_co_u32_e32 v10, vcc, s97, v24
	s_addc_u32 s17, s17, 0
	s_nop 0
	v_addc_co_u32_e32 v11, vcc, 0, v25, vcc
	v_add_u32_e32 v6, 0x8000, v6
	s_cmpk_lg_i32 s16, 0x800
	global_store_dwordx2 v[28:29], v[26:27], off offset:2048 nt
	global_store_dwordx2 v[10:11], v[8:9], off offset:2048 nt
	s_cbranch_scc1 .LBB0_1505
	s_add_i32 s30, s30, s3
	s_add_i32 s29, s29, s79
	s_add_i32 s14, s14, s3
	v_add_u32_e32 v237, s79, v237
	s_cmpk_gt_i32 s30, 0x337
	v_add_u32_e32 v208, s79, v208
	s_barrier
	s_cbranch_scc0 .LBB0_1266

.LBB0_1612:
	v_ashrrev_i32_e32 v133, 31, v132
	s_waitcnt vmcnt(1)
	v_bfe_u32 v2, v108, 16, 1
	v_lshlrev_b64 v[132:133], 13, v[132:133]
	v_add3_u32 v2, v108, v2, s80
	s_waitcnt vmcnt(0)
	v_bfe_u32 v108, v104, 16, 1
	v_lshl_add_u64 v[132:133], s[8:9], 0, v[132:133]
	v_lshrrev_b32_e32 v2, 16, v2
	v_add3_u32 v104, v104, v108, s80
	v_lshl_add_u64 v[136:137], v[134:135], 1, v[132:133]
	v_and_or_b32 v132, v104, s85, v2
	v_bfe_u32 v2, v112, 16, 1
	v_add3_u32 v2, v112, v2, s80
	v_bfe_u32 v104, v100, 16, 1
	v_lshrrev_b32_e32 v2, 16, v2
	v_add3_u32 v100, v100, v104, s80
	v_and_or_b32 v133, v100, s85, v2
	v_bfe_u32 v2, v124, 16, 1
	v_add3_u32 v2, v124, v2, s80
	v_bfe_u32 v100, v120, 16, 1
	v_lshrrev_b32_e32 v2, 16, v2
	v_add3_u32 v100, v120, v100, s80
	v_and_or_b32 v134, v100, s85, v2
	v_bfe_u32 v2, v128, 16, 1
	v_add3_u32 v2, v128, v2, s80
	v_bfe_u32 v100, v116, 16, 1
	v_lshrrev_b32_e32 v2, 16, v2
	v_add3_u32 v100, v116, v100, s80
	v_and_or_b32 v135, v100, s85, v2
	v_bfe_u32 v2, v109, 16, 1
	v_add3_u32 v2, v109, v2, s80
	v_bfe_u32 v100, v105, 16, 1
	v_lshrrev_b32_e32 v2, 16, v2
	v_add3_u32 v100, v105, v100, s80
	global_store_dwordx4 v[136:137], v[132:135], off nt
	s_nop 1
	v_and_or_b32 v132, v100, s85, v2
	v_bfe_u32 v2, v113, 16, 1
	v_add3_u32 v2, v113, v2, s80
	v_bfe_u32 v100, v101, 16, 1
	v_lshrrev_b32_e32 v2, 16, v2
	v_add3_u32 v100, v101, v100, s80
	v_and_or_b32 v133, v100, s85, v2
	v_bfe_u32 v2, v125, 16, 1
	v_add3_u32 v2, v125, v2, s80
	v_bfe_u32 v100, v121, 16, 1
	v_lshrrev_b32_e32 v2, 16, v2
	v_add3_u32 v100, v121, v100, s80
	v_and_or_b32 v134, v100, s85, v2
	v_bfe_u32 v2, v129, 16, 1
	v_add3_u32 v2, v129, v2, s80
	v_bfe_u32 v100, v117, 16, 1
	v_lshrrev_b32_e32 v2, 16, v2
	v_add3_u32 v100, v117, v100, s80
	v_and_or_b32 v135, v100, s85, v2
	v_add_co_u32_e32 v100, vcc, s84, v136
	v_bfe_u32 v2, v110, 16, 1
	s_nop 0
	v_addc_co_u32_e32 v101, vcc, 0, v137, vcc
	global_store_dwordx4 v[100:101], v[132:135], off nt
	v_add3_u32 v2, v110, v2, s80
	v_bfe_u32 v100, v106, 16, 1
	v_lshrrev_b32_e32 v2, 16, v2
	v_add3_u32 v100, v106, v100, s80
	v_and_or_b32 v132, v100, s85, v2
	v_bfe_u32 v2, v114, 16, 1
	v_add3_u32 v2, v114, v2, s80
	v_bfe_u32 v100, v102, 16, 1
	v_lshrrev_b32_e32 v2, 16, v2
	v_add3_u32 v100, v102, v100, s80
	v_and_or_b32 v133, v100, s85, v2
	v_bfe_u32 v2, v126, 16, 1
	v_add3_u32 v2, v126, v2, s80
	v_bfe_u32 v100, v122, 16, 1
	v_lshrrev_b32_e32 v2, 16, v2
	v_add3_u32 v100, v122, v100, s80
	v_and_or_b32 v134, v100, s85, v2
	v_bfe_u32 v2, v130, 16, 1
	v_add3_u32 v2, v130, v2, s80
	v_bfe_u32 v100, v118, 16, 1
	v_lshrrev_b32_e32 v2, 16, v2
	v_add3_u32 v100, v118, v100, s80
	v_and_or_b32 v135, v100, s85, v2
	v_add_co_u32_e32 v100, vcc, s81, v136
	v_bfe_u32 v2, v111, 16, 1
	s_nop 0
	v_addc_co_u32_e32 v101, vcc, 0, v137, vcc
	global_store_dwordx4 v[100:101], v[132:135], off nt
	v_add3_u32 v2, v111, v2, s80
	v_bfe_u32 v100, v107, 16, 1
	v_lshrrev_b32_e32 v2, 16, v2
	v_add3_u32 v100, v107, v100, s80
	v_and_or_b32 v100, v100, s85, v2
	v_bfe_u32 v2, v115, 16, 1
	v_add3_u32 v2, v115, v2, s80
	v_bfe_u32 v101, v103, 16, 1
	v_lshrrev_b32_e32 v2, 16, v2
	v_add3_u32 v101, v103, v101, s80
	v_and_or_b32 v101, v101, s85, v2
	v_bfe_u32 v2, v127, 16, 1
	v_add3_u32 v2, v127, v2, s80
	v_bfe_u32 v102, v123, 16, 1
	v_lshrrev_b32_e32 v2, 16, v2
	v_add3_u32 v102, v123, v102, s80
	v_and_or_b32 v102, v102, s85, v2
	v_bfe_u32 v2, v131, 16, 1
	v_add3_u32 v2, v131, v2, s80
	v_bfe_u32 v103, v119, 16, 1
	v_add_co_u32_e32 v104, vcc, 0x6000, v136
	v_lshrrev_b32_e32 v2, 16, v2
	v_add3_u32 v103, v119, v103, s80
	v_addc_co_u32_e32 v105, vcc, 0, v137, vcc
	v_and_or_b32 v103, v103, s85, v2
	s_andn2_b64 vcc, exec, s[12:13]
	global_store_dwordx4 v[104:105], v[100:103], off nt
	s_cbranch_vccnz .LBB0_1615
	s_mul_hi_i32 s4, s14, 0x2aaaaaab
	s_lshr_b32 s5, s4, 31
	s_ashr_i32 s4, s4, 4
	s_add_i32 s4, s4, s5
	v_lshl_or_b32 v100, s4, 6, v138
	s_mulk_i32 s4, 0xf400
	s_add_i32 s4, s4, s0
	v_add_u32_e32 v102, s4, v143
	v_ashrrev_i32_e32 v103, 31, v102
	v_lshlrev_b64 v[102:103], 13, v[102:103]
	v_ashrrev_i32_e32 v101, 31, v100
	v_lshl_add_u64 v[102:103], s[8:9], 0, v[102:103]
	v_bfe_u32 v2, v40, 16, 1
	v_lshl_add_u64 v[104:105], v[100:101], 1, v[102:103]
	v_add3_u32 v2, v40, v2, s80
	v_bfe_u32 v100, v36, 16, 1
	v_lshrrev_b32_e32 v2, 16, v2
	v_add3_u32 v100, v36, v100, s80
	v_and_or_b32 v100, v100, s85, v2
	v_bfe_u32 v2, v60, 16, 1
	v_add3_u32 v2, v60, v2, s80
	v_bfe_u32 v101, v28, 16, 1
	v_lshrrev_b32_e32 v2, 16, v2
	v_add3_u32 v101, v28, v101, s80
	v_and_or_b32 v101, v101, s85, v2
	v_bfe_u32 v2, v88, 16, 1
	v_add3_u32 v2, v88, v2, s80
	v_bfe_u32 v102, v84, 16, 1
	v_lshrrev_b32_e32 v2, 16, v2
	v_add3_u32 v102, v84, v102, s80
	v_and_or_b32 v102, v102, s85, v2
	v_bfe_u32 v2, v80, 16, 1
	v_add3_u32 v2, v80, v2, s80
	v_bfe_u32 v103, v96, 16, 1
	v_lshrrev_b32_e32 v2, 16, v2
	v_add3_u32 v103, v96, v103, s80
	v_and_or_b32 v103, v103, s85, v2
	v_bfe_u32 v2, v41, 16, 1
	global_store_dwordx4 v[104:105], v[100:103], off nt
	v_add3_u32 v2, v41, v2, s80
	v_lshrrev_b32_e32 v2, 16, v2
	v_bfe_u32 v100, v37, 16, 1
	v_add3_u32 v100, v37, v100, s80
	v_and_or_b32 v100, v100, s85, v2
	v_bfe_u32 v2, v61, 16, 1
	v_add3_u32 v2, v61, v2, s80
	v_bfe_u32 v101, v29, 16, 1
	v_lshrrev_b32_e32 v2, 16, v2
	v_add3_u32 v101, v29, v101, s80
	v_and_or_b32 v101, v101, s85, v2
	v_bfe_u32 v2, v89, 16, 1
	v_add3_u32 v2, v89, v2, s80
	v_bfe_u32 v102, v85, 16, 1
	v_lshrrev_b32_e32 v2, 16, v2
	v_add3_u32 v102, v85, v102, s80
	v_and_or_b32 v102, v102, s85, v2
	v_bfe_u32 v2, v81, 16, 1
	v_add3_u32 v2, v81, v2, s80
	v_bfe_u32 v103, v97, 16, 1
	v_lshrrev_b32_e32 v2, 16, v2
	v_add3_u32 v103, v97, v103, s80
	v_add_co_u32_e32 v106, vcc, s84, v104
	v_and_or_b32 v103, v103, s85, v2
	s_nop 0
	v_addc_co_u32_e32 v107, vcc, 0, v105, vcc
	v_bfe_u32 v2, v42, 16, 1
	global_store_dwordx4 v[106:107], v[100:103], off nt
	v_add3_u32 v2, v42, v2, s80
	v_lshrrev_b32_e32 v2, 16, v2
	v_bfe_u32 v100, v38, 16, 1
	v_add3_u32 v100, v38, v100, s80
	v_and_or_b32 v100, v100, s85, v2
	v_bfe_u32 v2, v62, 16, 1
	v_add3_u32 v2, v62, v2, s80
	v_bfe_u32 v101, v30, 16, 1
	v_lshrrev_b32_e32 v2, 16, v2
	v_add3_u32 v101, v30, v101, s80
	v_and_or_b32 v101, v101, s85, v2
	v_bfe_u32 v2, v90, 16, 1
	v_add3_u32 v2, v90, v2, s80
	v_bfe_u32 v102, v86, 16, 1
	v_lshrrev_b32_e32 v2, 16, v2
	v_add3_u32 v102, v86, v102, s80
	v_and_or_b32 v102, v102, s85, v2
	v_bfe_u32 v2, v82, 16, 1
	v_add3_u32 v2, v82, v2, s80
	v_bfe_u32 v103, v98, 16, 1
	v_lshrrev_b32_e32 v2, 16, v2
	v_add3_u32 v103, v98, v103, s80
	v_add_co_u32_e32 v106, vcc, s81, v104
	v_and_or_b32 v103, v103, s85, v2
	s_nop 0
	v_addc_co_u32_e32 v107, vcc, 0, v105, vcc
	v_bfe_u32 v2, v43, 16, 1
	global_store_dwordx4 v[106:107], v[100:103], off nt
	v_add3_u32 v2, v43, v2, s80
	v_lshrrev_b32_e32 v2, 16, v2
	v_bfe_u32 v100, v39, 16, 1
	v_add3_u32 v100, v39, v100, s80
	v_and_or_b32 v100, v100, s85, v2
	v_bfe_u32 v2, v63, 16, 1
	v_add3_u32 v2, v63, v2, s80
	v_bfe_u32 v101, v31, 16, 1
	v_lshrrev_b32_e32 v2, 16, v2
	v_add3_u32 v101, v31, v101, s80
	v_and_or_b32 v101, v101, s85, v2
	v_bfe_u32 v2, v91, 16, 1
	v_add3_u32 v2, v91, v2, s80
	v_bfe_u32 v102, v87, 16, 1
	v_lshrrev_b32_e32 v2, 16, v2
	v_add3_u32 v102, v87, v102, s80
	v_and_or_b32 v102, v102, s85, v2
	v_bfe_u32 v2, v83, 16, 1
	v_add3_u32 v2, v83, v2, s80
	v_bfe_u32 v103, v99, 16, 1
	v_lshrrev_b32_e32 v2, 16, v2
	v_add3_u32 v103, v99, v103, s80
	v_add_co_u32_e32 v104, vcc, 0x6000, v104
	v_and_or_b32 v103, v103, s85, v2
	s_nop 0
	v_addc_co_u32_e32 v105, vcc, 0, v105, vcc
	global_store_dwordx4 v[104:105], v[100:103], off nt
	s_andn2_b64 vcc, exec, s[16:17]
	s_cbranch_vccz .LBB0_1616

.LBB0_1616:
	s_mul_hi_i32 s4, s15, 0x2aaaaaab
	s_lshr_b32 s5, s4, 31
	s_ashr_i32 s4, s4, 4
	s_add_i32 s4, s4, s5
	v_lshl_or_b32 v100, s4, 6, v138
	s_mulk_i32 s4, 0xf400
	s_add_i32 s4, s4, s0
	v_add_u32_e32 v102, s4, v141
	v_ashrrev_i32_e32 v103, 31, v102
	v_lshlrev_b64 v[102:103], 13, v[102:103]
	v_ashrrev_i32_e32 v101, 31, v100
	v_lshl_add_u64 v[102:103], s[8:9], 0, v[102:103]
	v_bfe_u32 v2, v24, 16, 1
	v_lshl_add_u64 v[104:105], v[100:101], 1, v[102:103]
	v_add3_u32 v2, v24, v2, s80
	v_bfe_u32 v100, v20, 16, 1
	v_lshrrev_b32_e32 v2, 16, v2
	v_add3_u32 v100, v20, v100, s80
	v_and_or_b32 v100, v100, s85, v2
	v_bfe_u32 v2, v44, 16, 1
	v_add3_u32 v2, v44, v2, s80
	v_bfe_u32 v101, v16, 16, 1
	v_lshrrev_b32_e32 v2, 16, v2
	v_add3_u32 v101, v16, v101, s80
	v_and_or_b32 v101, v101, s85, v2
	v_bfe_u32 v2, v72, 16, 1
	v_add3_u32 v2, v72, v2, s80
	v_bfe_u32 v102, v68, 16, 1
	v_lshrrev_b32_e32 v2, 16, v2
	v_add3_u32 v102, v68, v102, s80
	v_and_or_b32 v102, v102, s85, v2
	v_bfe_u32 v2, v64, 16, 1
	v_add3_u32 v2, v64, v2, s80
	v_bfe_u32 v103, v92, 16, 1
	v_lshrrev_b32_e32 v2, 16, v2
	v_add3_u32 v103, v92, v103, s80
	v_and_or_b32 v103, v103, s85, v2
	v_bfe_u32 v2, v25, 16, 1
	global_store_dwordx4 v[104:105], v[100:103], off nt
	v_add3_u32 v2, v25, v2, s80
	v_lshrrev_b32_e32 v2, 16, v2
	v_bfe_u32 v100, v21, 16, 1
	v_add3_u32 v100, v21, v100, s80
	v_and_or_b32 v100, v100, s85, v2
	v_bfe_u32 v2, v45, 16, 1
	v_add3_u32 v2, v45, v2, s80
	v_bfe_u32 v101, v17, 16, 1
	v_lshrrev_b32_e32 v2, 16, v2
	v_add3_u32 v101, v17, v101, s80
	v_and_or_b32 v101, v101, s85, v2
	v_bfe_u32 v2, v73, 16, 1
	v_add3_u32 v2, v73, v2, s80
	v_bfe_u32 v102, v69, 16, 1
	v_lshrrev_b32_e32 v2, 16, v2
	v_add3_u32 v102, v69, v102, s80
	v_and_or_b32 v102, v102, s85, v2
	v_bfe_u32 v2, v65, 16, 1
	v_add3_u32 v2, v65, v2, s80
	v_bfe_u32 v103, v93, 16, 1
	v_lshrrev_b32_e32 v2, 16, v2
	v_add3_u32 v103, v93, v103, s80
	v_add_co_u32_e32 v106, vcc, s84, v104
	v_and_or_b32 v103, v103, s85, v2
	s_nop 0
	v_addc_co_u32_e32 v107, vcc, 0, v105, vcc
	v_bfe_u32 v2, v26, 16, 1
	global_store_dwordx4 v[106:107], v[100:103], off nt
	v_add3_u32 v2, v26, v2, s80
	v_lshrrev_b32_e32 v2, 16, v2
	v_bfe_u32 v100, v22, 16, 1
	v_add3_u32 v100, v22, v100, s80
	v_and_or_b32 v100, v100, s85, v2
	v_bfe_u32 v2, v46, 16, 1
	v_add3_u32 v2, v46, v2, s80
	v_bfe_u32 v101, v18, 16, 1
	v_lshrrev_b32_e32 v2, 16, v2
	v_add3_u32 v101, v18, v101, s80
	v_and_or_b32 v101, v101, s85, v2
	v_bfe_u32 v2, v74, 16, 1
	v_add3_u32 v2, v74, v2, s80
	v_bfe_u32 v102, v70, 16, 1
	v_lshrrev_b32_e32 v2, 16, v2
	v_add3_u32 v102, v70, v102, s80
	v_and_or_b32 v102, v102, s85, v2
	v_bfe_u32 v2, v66, 16, 1
	v_add3_u32 v2, v66, v2, s80
	v_bfe_u32 v103, v94, 16, 1
	v_lshrrev_b32_e32 v2, 16, v2
	v_add3_u32 v103, v94, v103, s80
	v_add_co_u32_e32 v106, vcc, s81, v104
	v_and_or_b32 v103, v103, s85, v2
	s_nop 0
	v_addc_co_u32_e32 v107, vcc, 0, v105, vcc
	v_bfe_u32 v2, v27, 16, 1
	global_store_dwordx4 v[106:107], v[100:103], off nt
	v_add3_u32 v2, v27, v2, s80
	v_lshrrev_b32_e32 v2, 16, v2
	v_bfe_u32 v100, v23, 16, 1
	v_add3_u32 v100, v23, v100, s80
	v_and_or_b32 v100, v100, s85, v2
	v_bfe_u32 v2, v47, 16, 1
	v_add3_u32 v2, v47, v2, s80
	v_bfe_u32 v101, v19, 16, 1
	v_lshrrev_b32_e32 v2, 16, v2
	v_add3_u32 v101, v19, v101, s80
	v_and_or_b32 v101, v101, s85, v2
	v_bfe_u32 v2, v75, 16, 1
	v_add3_u32 v2, v75, v2, s80
	v_bfe_u32 v102, v71, 16, 1
	v_lshrrev_b32_e32 v2, 16, v2
	v_add3_u32 v102, v71, v102, s80
	v_and_or_b32 v102, v102, s85, v2
	v_bfe_u32 v2, v67, 16, 1
	v_add3_u32 v2, v67, v2, s80
	v_bfe_u32 v103, v95, 16, 1
	v_lshrrev_b32_e32 v2, 16, v2
	v_add3_u32 v103, v95, v103, s80
	v_add_co_u32_e32 v104, vcc, 0x6000, v104
	v_and_or_b32 v103, v103, s85, v2
	s_nop 0
	v_addc_co_u32_e32 v105, vcc, 0, v105, vcc
	global_store_dwordx4 v[104:105], v[100:103], off nt
	s_andn2_b64 vcc, exec, s[18:19]
	s_cbranch_vccnz .LBB0_1509
.LBB0_1617:
	s_mul_hi_i32 s4, s22, 0x2aaaaaab
	s_lshr_b32 s5, s4, 31
	s_ashr_i32 s4, s4, 4
	s_add_i32 s4, s4, s5
	v_lshl_or_b32 v100, s4, 6, v138
	s_mulk_i32 s4, 0xf400
	s_add_i32 s4, s4, s0
	v_add_u32_e32 v102, s4, v142
	v_ashrrev_i32_e32 v103, 31, v102
	v_lshlrev_b64 v[102:103], 13, v[102:103]
	v_ashrrev_i32_e32 v101, 31, v100
	v_lshl_add_u64 v[102:103], s[8:9], 0, v[102:103]
	v_bfe_u32 v2, v12, 16, 1
	v_lshl_add_u64 v[104:105], v[100:101], 1, v[102:103]
	v_add3_u32 v2, v12, v2, s80
	v_bfe_u32 v100, v8, 16, 1
	v_lshrrev_b32_e32 v2, 16, v2
	v_add3_u32 v100, v8, v100, s80
	v_and_or_b32 v100, v100, s85, v2
	v_bfe_u32 v2, v32, 16, 1
	v_add3_u32 v2, v32, v2, s80
	v_bfe_u32 v101, v4, 16, 1
	v_lshrrev_b32_e32 v2, 16, v2
	v_add3_u32 v101, v4, v101, s80
	v_and_or_b32 v101, v101, s85, v2
	v_bfe_u32 v2, v56, 16, 1
	v_add3_u32 v2, v56, v2, s80
	v_bfe_u32 v102, v52, 16, 1
	v_lshrrev_b32_e32 v2, 16, v2
	v_add3_u32 v102, v52, v102, s80
	v_and_or_b32 v102, v102, s85, v2
	v_bfe_u32 v2, v48, 16, 1
	v_add3_u32 v2, v48, v2, s80
	v_bfe_u32 v103, v76, 16, 1
	v_lshrrev_b32_e32 v2, 16, v2
	v_add3_u32 v103, v76, v103, s80
	v_and_or_b32 v103, v103, s85, v2
	v_bfe_u32 v2, v13, 16, 1
	global_store_dwordx4 v[104:105], v[100:103], off nt
	v_add3_u32 v2, v13, v2, s80
	v_lshrrev_b32_e32 v2, 16, v2
	v_bfe_u32 v100, v9, 16, 1
	v_add3_u32 v100, v9, v100, s80
	v_and_or_b32 v100, v100, s85, v2
	v_bfe_u32 v2, v33, 16, 1
	v_add3_u32 v2, v33, v2, s80
	v_bfe_u32 v101, v5, 16, 1
	v_lshrrev_b32_e32 v2, 16, v2
	v_add3_u32 v101, v5, v101, s80
	v_and_or_b32 v101, v101, s85, v2
	v_bfe_u32 v2, v57, 16, 1
	v_add3_u32 v2, v57, v2, s80
	v_bfe_u32 v102, v53, 16, 1
	v_lshrrev_b32_e32 v2, 16, v2
	v_add3_u32 v102, v53, v102, s80
	v_and_or_b32 v102, v102, s85, v2
	v_bfe_u32 v2, v49, 16, 1
	v_add3_u32 v2, v49, v2, s80
	v_bfe_u32 v103, v77, 16, 1
	v_lshrrev_b32_e32 v2, 16, v2
	v_add3_u32 v103, v77, v103, s80
	v_add_co_u32_e32 v106, vcc, s84, v104
	v_and_or_b32 v103, v103, s85, v2
	s_nop 0
	v_addc_co_u32_e32 v107, vcc, 0, v105, vcc
	v_bfe_u32 v2, v14, 16, 1
	global_store_dwordx4 v[106:107], v[100:103], off nt
	v_add3_u32 v2, v14, v2, s80
	v_lshrrev_b32_e32 v2, 16, v2
	v_bfe_u32 v100, v10, 16, 1
	v_add3_u32 v100, v10, v100, s80
	v_and_or_b32 v100, v100, s85, v2
	v_bfe_u32 v2, v34, 16, 1
	v_add3_u32 v2, v34, v2, s80
	v_bfe_u32 v101, v6, 16, 1
	v_lshrrev_b32_e32 v2, 16, v2
	v_add3_u32 v101, v6, v101, s80
	v_and_or_b32 v101, v101, s85, v2
	v_bfe_u32 v2, v58, 16, 1
	v_add3_u32 v2, v58, v2, s80
	v_bfe_u32 v102, v54, 16, 1
	v_lshrrev_b32_e32 v2, 16, v2
	v_add3_u32 v102, v54, v102, s80
	v_and_or_b32 v102, v102, s85, v2
	v_bfe_u32 v2, v50, 16, 1
	v_add3_u32 v2, v50, v2, s80
	v_bfe_u32 v103, v78, 16, 1
	v_lshrrev_b32_e32 v2, 16, v2
	v_add3_u32 v103, v78, v103, s80
	v_add_co_u32_e32 v106, vcc, s81, v104
	v_and_or_b32 v103, v103, s85, v2
	s_nop 0
	v_addc_co_u32_e32 v107, vcc, 0, v105, vcc
	v_bfe_u32 v2, v15, 16, 1
	global_store_dwordx4 v[106:107], v[100:103], off nt
	v_add3_u32 v2, v15, v2, s80
	v_lshrrev_b32_e32 v2, 16, v2
	v_bfe_u32 v100, v11, 16, 1
	v_add3_u32 v100, v11, v100, s80
	v_and_or_b32 v100, v100, s85, v2
	v_bfe_u32 v2, v35, 16, 1
	v_add3_u32 v2, v35, v2, s80
	v_bfe_u32 v101, v7, 16, 1
	v_lshrrev_b32_e32 v2, 16, v2
	v_add3_u32 v101, v7, v101, s80
	v_and_or_b32 v101, v101, s85, v2
	v_bfe_u32 v2, v59, 16, 1
	v_add3_u32 v2, v59, v2, s80
	v_bfe_u32 v102, v55, 16, 1
	v_lshrrev_b32_e32 v2, 16, v2
	v_add3_u32 v102, v55, v102, s80
	v_and_or_b32 v102, v102, s85, v2
	v_bfe_u32 v2, v51, 16, 1
	v_add3_u32 v2, v51, v2, s80
	v_bfe_u32 v103, v79, 16, 1
	v_lshrrev_b32_e32 v2, 16, v2
	v_add3_u32 v103, v79, v103, s80
	v_add_co_u32_e32 v104, vcc, 0x6000, v104
	v_and_or_b32 v103, v103, s85, v2
	s_nop 0
	v_addc_co_u32_e32 v105, vcc, 0, v105, vcc
	global_store_dwordx4 v[104:105], v[100:103], off nt
	s_branch .LBB0_1509

.LBB0_1659:
	v_lshl_add_u64 v[4:5], v[134:135], 2, s[8:9]
	global_load_dwordx4 v[152:155], v[4:5], off offset:16
	global_load_dwordx4 v[138:141], v[4:5], off
	s_waitcnt vmcnt(1)
	v_pk_mul_f32 v[126:127], v[126:127], v[152:153] op_sel_hi:[1,0]
	s_waitcnt vmcnt(0)
	v_mov_b32_e32 v2, v141
	v_pk_mul_f32 v[136:137], v[112:113], v[138:139] op_sel_hi:[1,0]
	v_pk_mul_f32 v[144:145], v[110:111], v[138:139] op_sel_hi:[1,0]
	v_pk_mul_f32 v[112:113], v[108:109], v[138:139] op_sel:[0,1]
	v_pk_mul_f32 v[142:143], v[106:107], v[138:139] op_sel:[0,1]
	v_pk_mul_f32 v[108:109], v[116:117], v[140:141] op_sel_hi:[1,0]
	v_pk_mul_f32 v[138:139], v[114:115], v[140:141] op_sel_hi:[1,0]
	v_pk_mul_f32 v[110:111], v[104:105], v[2:3] op_sel_hi:[1,0]
	v_pk_mul_f32 v[140:141], v[102:103], v[2:3] op_sel_hi:[1,0]
	v_mov_b32_e32 v2, v155
	v_pk_mul_f32 v[102:103], v[120:121], v[2:3] op_sel_hi:[1,0]
	v_pk_mul_f32 v[118:119], v[118:119], v[2:3] op_sel_hi:[1,0]
	v_bfe_u32 v2, v144, 16, 1
	v_add3_u32 v2, v144, v2, s80
	v_bfe_u32 v120, v142, 16, 1
	v_lshrrev_b32_e32 v2, 16, v2
	v_add3_u32 v120, v142, v120, s80
	v_pk_mul_f32 v[106:107], v[128:129], v[152:153] op_sel_hi:[1,0]
	v_and_or_b32 v128, v120, s85, v2
	v_bfe_u32 v2, v138, 16, 1
	v_add3_u32 v2, v138, v2, s80
	v_bfe_u32 v120, v140, 16, 1
	v_lshrrev_b32_e32 v2, 16, v2
	v_add3_u32 v120, v140, v120, s80
	v_pk_mul_f32 v[122:123], v[122:123], v[152:153] op_sel:[0,1]
	v_and_or_b32 v129, v120, s85, v2
	v_bfe_u32 v2, v126, 16, 1
	v_add3_u32 v2, v126, v2, s80
	v_bfe_u32 v120, v122, 16, 1
	v_pk_mul_f32 v[116:117], v[130:131], v[154:155] op_sel_hi:[1,0]
	v_lshrrev_b32_e32 v2, 16, v2
	v_add3_u32 v120, v122, v120, s80
	v_and_or_b32 v130, v120, s85, v2
	v_bfe_u32 v2, v116, 16, 1
	v_add3_u32 v2, v116, v2, s80
	v_bfe_u32 v116, v118, 16, 1
	v_lshrrev_b32_e32 v2, 16, v2
	v_add3_u32 v116, v118, v116, s80
	v_and_or_b32 v131, v116, s85, v2
	v_bfe_u32 v2, v145, 16, 1
	v_add3_u32 v2, v145, v2, s80
	v_bfe_u32 v116, v143, 16, 1
	v_lshrrev_b32_e32 v2, 16, v2
	v_add3_u32 v116, v143, v116, s80
	v_and_or_b32 v120, v116, s85, v2
	v_bfe_u32 v2, v139, 16, 1
	v_add3_u32 v2, v139, v2, s80
	v_bfe_u32 v116, v141, 16, 1
	v_lshrrev_b32_e32 v2, 16, v2
	v_add3_u32 v116, v141, v116, s80
	v_and_or_b32 v121, v116, s85, v2
	v_bfe_u32 v2, v127, 16, 1
	v_add3_u32 v2, v127, v2, s80
	v_bfe_u32 v116, v123, 16, 1
	v_lshrrev_b32_e32 v2, 16, v2
	v_add3_u32 v116, v123, v116, s80
	v_and_or_b32 v122, v116, s85, v2
	v_bfe_u32 v2, v117, 16, 1
	v_add3_u32 v2, v117, v2, s80
	v_bfe_u32 v116, v119, 16, 1
	v_lshrrev_b32_e32 v2, 16, v2
	v_add3_u32 v116, v119, v116, s80
	v_and_or_b32 v123, v116, s85, v2
	v_bfe_u32 v2, v136, 16, 1
	v_add3_u32 v2, v136, v2, s80
	v_bfe_u32 v116, v112, 16, 1
	v_lshrrev_b32_e32 v2, 16, v2
	v_add3_u32 v112, v112, v116, s80
	v_and_or_b32 v116, v112, s85, v2
	v_bfe_u32 v2, v108, 16, 1
	v_add3_u32 v2, v108, v2, s80
	v_bfe_u32 v108, v110, 16, 1
	v_lshrrev_b32_e32 v2, 16, v2
	v_add3_u32 v108, v110, v108, s80
	v_pk_mul_f32 v[104:105], v[124:125], v[152:153] op_sel:[0,1]
	v_and_or_b32 v117, v108, s85, v2
	v_bfe_u32 v2, v106, 16, 1
	v_add3_u32 v2, v106, v2, s80
	v_bfe_u32 v106, v104, 16, 1
	v_pk_mul_f32 v[4:5], v[132:133], v[154:155] op_sel_hi:[1,0]
	v_lshrrev_b32_e32 v2, 16, v2
	v_add3_u32 v104, v104, v106, s80
	v_and_or_b32 v118, v104, s85, v2
	v_bfe_u32 v2, v4, 16, 1
	v_add3_u32 v2, v4, v2, s80
	v_bfe_u32 v4, v102, 16, 1
	v_lshrrev_b32_e32 v2, 16, v2
	v_add3_u32 v4, v102, v4, s80
	v_and_or_b32 v119, v4, s85, v2
	v_bfe_u32 v2, v137, 16, 1
	v_add3_u32 v2, v137, v2, s80
	v_bfe_u32 v4, v113, 16, 1
	v_lshrrev_b32_e32 v2, 16, v2
	v_add3_u32 v4, v113, v4, s80
	v_and_or_b32 v108, v4, s85, v2
	v_bfe_u32 v2, v109, 16, 1
	v_add3_u32 v2, v109, v2, s80
	v_bfe_u32 v4, v111, 16, 1
	v_lshrrev_b32_e32 v2, 16, v2
	v_add3_u32 v4, v111, v4, s80
	v_and_or_b32 v109, v4, s85, v2
	v_bfe_u32 v2, v107, 16, 1
	v_mov_b64_e32 v[114:115], s[12:13]
	v_add3_u32 v2, v107, v2, s80
	v_bfe_u32 v4, v105, 16, 1
	v_mad_i64_i32 v[114:115], s[4:5], v151, s68, v[114:115]
	v_lshrrev_b32_e32 v2, 16, v2
	v_add3_u32 v4, v105, v4, s80
	v_lshl_add_u64 v[114:115], v[134:135], 1, v[114:115]
	s_movk_i32 s4, 0x1000
	v_and_or_b32 v110, v4, s85, v2
	v_bfe_u32 v2, v5, 16, 1
	global_store_dwordx4 v[114:115], v[120:123], off offset:3072 nt
	v_add3_u32 v2, v5, v2, s80
	v_bfe_u32 v4, v103, 16, 1
	v_add_co_u32_e32 v120, vcc, s4, v114
	v_lshrrev_b32_e32 v2, 16, v2
	s_nop 0
	v_addc_co_u32_e32 v121, vcc, 0, v115, vcc
	v_add3_u32 v4, v103, v4, s80
	v_and_or_b32 v111, v4, s85, v2
	v_add_co_u32_e32 v4, vcc, 0x2000, v114
	global_store_dwordx4 v[114:115], v[128:131], off nt
	s_nop 0
	v_addc_co_u32_e32 v5, vcc, 0, v115, vcc
	s_andn2_b64 vcc, exec, s[20:21]
	global_store_dwordx4 v[120:121], v[116:119], off offset:2048 nt
	global_store_dwordx4 v[4:5], v[108:111], off offset:1024 nt
	s_cbranch_vccnz .LBB0_1662
	s_mul_hi_i32 s4, s25, 0x2aaaaaab
	s_lshr_b32 s5, s4, 31
	s_ashr_i32 s4, s4, 4
	s_add_i32 s4, s4, s5
	v_lshl_or_b32 v4, s4, 6, v146
	v_ashrrev_i32_e32 v5, 31, v4
	v_lshl_add_u64 v[106:107], v[4:5], 2, s[8:9]
	global_load_dwordx4 v[102:105], v[106:107], off offset:16
	s_nop 0
	global_load_dwordx4 v[106:109], v[106:107], off
	s_mulk_i32 s4, 0xf400
	s_add_i32 s4, s4, s0
	s_waitcnt vmcnt(1)
	v_pk_mul_f32 v[72:73], v[72:73], v[102:103] op_sel_hi:[1,0]
	s_waitcnt vmcnt(0)
	v_mov_b32_e32 v2, v109
	v_pk_mul_f32 v[36:37], v[36:37], v[2:3] op_sel_hi:[1,0]
	v_pk_mul_f32 v[34:35], v[34:35], v[2:3] op_sel_hi:[1,0]
	v_mov_b32_e32 v2, v105
	v_pk_mul_f32 v[30:31], v[30:31], v[106:107] op_sel_hi:[1,0]
	v_pk_mul_f32 v[70:71], v[70:71], v[102:103] op_sel_hi:[1,0]
	v_pk_mul_f32 v[76:77], v[76:77], v[102:103] op_sel:[0,1]
	v_pk_mul_f32 v[74:75], v[74:75], v[102:103] op_sel:[0,1]
	v_pk_mul_f32 v[100:101], v[100:101], v[2:3] op_sel_hi:[1,0]
	v_pk_mul_f32 v[98:99], v[98:99], v[2:3] op_sel_hi:[1,0]
	v_add_u32_e32 v2, s4, v150
	v_mov_b64_e32 v[102:103], s[12:13]
	v_pk_mul_f32 v[38:39], v[38:39], v[106:107] op_sel:[0,1]
	v_mad_i64_i32 v[102:103], s[4:5], v2, s68, v[102:103]
	v_bfe_u32 v2, v30, 16, 1
	v_lshl_add_u64 v[4:5], v[4:5], 1, v[102:103]
	v_add3_u32 v2, v30, v2, s80
	v_bfe_u32 v102, v38, 16, 1
	v_pk_mul_f32 v[50:51], v[50:51], v[108:109] op_sel_hi:[1,0]
	v_lshrrev_b32_e32 v2, 16, v2
	v_add3_u32 v102, v38, v102, s80
	v_and_or_b32 v102, v102, s85, v2
	v_bfe_u32 v2, v50, 16, 1
	v_add3_u32 v2, v50, v2, s80
	v_bfe_u32 v103, v34, 16, 1
	v_lshrrev_b32_e32 v2, 16, v2
	v_add3_u32 v103, v34, v103, s80
	v_and_or_b32 v103, v103, s85, v2
	v_bfe_u32 v2, v70, 16, 1
	v_pk_mul_f32 v[96:97], v[96:97], v[104:105] op_sel_hi:[1,0]
	v_pk_mul_f32 v[94:95], v[94:95], v[104:105] op_sel_hi:[1,0]
	v_add3_u32 v2, v70, v2, s80
	v_bfe_u32 v104, v74, 16, 1
	v_lshrrev_b32_e32 v2, 16, v2
	v_add3_u32 v104, v74, v104, s80
	v_and_or_b32 v104, v104, s85, v2
	v_bfe_u32 v2, v94, 16, 1
	v_add3_u32 v2, v94, v2, s80
	v_bfe_u32 v105, v98, 16, 1
	v_lshrrev_b32_e32 v2, 16, v2
	v_add3_u32 v105, v98, v105, s80
	v_and_or_b32 v105, v105, s85, v2
	v_bfe_u32 v2, v31, 16, 1
	global_store_dwordx4 v[4:5], v[102:105], off nt
	v_add3_u32 v2, v31, v2, s80
	v_lshrrev_b32_e32 v2, 16, v2
	v_bfe_u32 v102, v39, 16, 1
	v_add3_u32 v102, v39, v102, s80
	v_and_or_b32 v102, v102, s85, v2
	v_bfe_u32 v2, v51, 16, 1
	v_add3_u32 v2, v51, v2, s80
	v_bfe_u32 v103, v35, 16, 1
	v_lshrrev_b32_e32 v2, 16, v2
	v_add3_u32 v103, v35, v103, s80
	v_and_or_b32 v103, v103, s85, v2
	v_bfe_u32 v2, v71, 16, 1
	v_add3_u32 v2, v71, v2, s80
	v_bfe_u32 v104, v75, 16, 1
	v_lshrrev_b32_e32 v2, 16, v2
	v_add3_u32 v104, v75, v104, s80
	v_and_or_b32 v104, v104, s85, v2
	v_bfe_u32 v2, v95, 16, 1
	v_add3_u32 v2, v95, v2, s80
	v_bfe_u32 v105, v99, 16, 1
	v_pk_mul_f32 v[32:33], v[32:33], v[106:107] op_sel_hi:[1,0]
	v_lshrrev_b32_e32 v2, 16, v2
	v_add3_u32 v105, v99, v105, s80
	v_pk_mul_f32 v[40:41], v[40:41], v[106:107] op_sel:[0,1]
	v_and_or_b32 v105, v105, s85, v2
	v_bfe_u32 v2, v32, 16, 1
	global_store_dwordx4 v[4:5], v[102:105], off offset:3072 nt
	v_add3_u32 v2, v32, v2, s80
	v_pk_mul_f32 v[52:53], v[52:53], v[108:109] op_sel_hi:[1,0]
	v_bfe_u32 v102, v40, 16, 1
	v_lshrrev_b32_e32 v2, 16, v2
	v_add3_u32 v102, v40, v102, s80
	v_and_or_b32 v102, v102, s85, v2
	v_bfe_u32 v2, v52, 16, 1
	v_add3_u32 v2, v52, v2, s80
	v_bfe_u32 v103, v36, 16, 1
	v_lshrrev_b32_e32 v2, 16, v2
	v_add3_u32 v103, v36, v103, s80
	v_and_or_b32 v103, v103, s85, v2
	v_bfe_u32 v2, v72, 16, 1
	v_add3_u32 v2, v72, v2, s80
	v_bfe_u32 v104, v76, 16, 1
	v_lshrrev_b32_e32 v2, 16, v2
	v_add3_u32 v104, v76, v104, s80
	v_and_or_b32 v104, v104, s85, v2
	v_bfe_u32 v2, v96, 16, 1
	s_movk_i32 s4, 0x1000
	v_add3_u32 v2, v96, v2, s80
	v_bfe_u32 v105, v100, 16, 1
	v_lshrrev_b32_e32 v2, 16, v2
	v_add3_u32 v105, v100, v105, s80
	v_add_co_u32_e32 v106, vcc, s4, v4
	v_and_or_b32 v105, v105, s85, v2
	s_nop 0
	v_addc_co_u32_e32 v107, vcc, 0, v5, vcc
	v_bfe_u32 v2, v33, 16, 1
	global_store_dwordx4 v[106:107], v[102:105], off offset:2048 nt
	v_add3_u32 v2, v33, v2, s80
	v_lshrrev_b32_e32 v2, 16, v2
	v_bfe_u32 v102, v41, 16, 1
	v_add3_u32 v102, v41, v102, s80
	v_and_or_b32 v102, v102, s85, v2
	v_bfe_u32 v2, v53, 16, 1
	v_add3_u32 v2, v53, v2, s80
	v_bfe_u32 v103, v37, 16, 1
	v_lshrrev_b32_e32 v2, 16, v2
	v_add3_u32 v103, v37, v103, s80
	v_and_or_b32 v103, v103, s85, v2
	v_bfe_u32 v2, v73, 16, 1
	v_add3_u32 v2, v73, v2, s80
	v_bfe_u32 v104, v77, 16, 1
	v_lshrrev_b32_e32 v2, 16, v2
	v_add3_u32 v104, v77, v104, s80
	v_and_or_b32 v104, v104, s85, v2
	v_bfe_u32 v2, v97, 16, 1
	v_add3_u32 v2, v97, v2, s80
	v_bfe_u32 v105, v101, 16, 1
	v_lshrrev_b32_e32 v2, 16, v2
	v_add3_u32 v105, v101, v105, s80
	v_add_co_u32_e32 v4, vcc, 0x2000, v4
	v_and_or_b32 v105, v105, s85, v2
	s_nop 0
	v_addc_co_u32_e32 v5, vcc, 0, v5, vcc
	global_store_dwordx4 v[4:5], v[102:105], off offset:1024 nt
	s_andn2_b64 vcc, exec, s[18:19]
	s_cbranch_vccz .LBB0_1663

.LBB0_1663:
	s_mul_hi_i32 s4, s15, 0x2aaaaaab
	s_lshr_b32 s5, s4, 31
	s_ashr_i32 s4, s4, 4
	s_add_i32 s4, s4, s5
	v_lshl_or_b32 v4, s4, 6, v146
	v_ashrrev_i32_e32 v5, 31, v4
	v_lshl_add_u64 v[106:107], v[4:5], 2, s[8:9]
	global_load_dwordx4 v[102:105], v[106:107], off offset:16
	s_nop 0
	global_load_dwordx4 v[106:109], v[106:107], off
	s_mulk_i32 s4, 0xf400
	s_add_i32 s4, s4, s0
	s_waitcnt vmcnt(1)
	v_pk_mul_f32 v[64:65], v[64:65], v[102:103] op_sel_hi:[1,0]
	s_waitcnt vmcnt(0)
	v_mov_b32_e32 v2, v109
	v_pk_mul_f32 v[20:21], v[20:21], v[2:3] op_sel_hi:[1,0]
	v_pk_mul_f32 v[18:19], v[18:19], v[2:3] op_sel_hi:[1,0]
	v_mov_b32_e32 v2, v105
	v_pk_mul_f32 v[22:23], v[22:23], v[106:107] op_sel_hi:[1,0]
	v_pk_mul_f32 v[62:63], v[62:63], v[102:103] op_sel_hi:[1,0]
	v_pk_mul_f32 v[68:69], v[68:69], v[102:103] op_sel:[0,1]
	v_pk_mul_f32 v[66:67], v[66:67], v[102:103] op_sel:[0,1]
	v_pk_mul_f32 v[92:93], v[92:93], v[2:3] op_sel_hi:[1,0]
	v_pk_mul_f32 v[90:91], v[90:91], v[2:3] op_sel_hi:[1,0]
	v_add_u32_e32 v2, s4, v148
	v_mov_b64_e32 v[102:103], s[12:13]
	v_pk_mul_f32 v[26:27], v[26:27], v[106:107] op_sel:[0,1]
	v_mad_i64_i32 v[102:103], s[4:5], v2, s68, v[102:103]
	v_bfe_u32 v2, v22, 16, 1
	v_lshl_add_u64 v[4:5], v[4:5], 1, v[102:103]
	v_add3_u32 v2, v22, v2, s80
	v_bfe_u32 v102, v26, 16, 1
	v_pk_mul_f32 v[46:47], v[46:47], v[108:109] op_sel_hi:[1,0]
	v_lshrrev_b32_e32 v2, 16, v2
	v_add3_u32 v102, v26, v102, s80
	v_and_or_b32 v102, v102, s85, v2
	v_bfe_u32 v2, v46, 16, 1
	v_add3_u32 v2, v46, v2, s80
	v_bfe_u32 v103, v18, 16, 1
	v_lshrrev_b32_e32 v2, 16, v2
	v_add3_u32 v103, v18, v103, s80
	v_and_or_b32 v103, v103, s85, v2
	v_bfe_u32 v2, v62, 16, 1
	v_pk_mul_f32 v[88:89], v[88:89], v[104:105] op_sel_hi:[1,0]
	v_pk_mul_f32 v[86:87], v[86:87], v[104:105] op_sel_hi:[1,0]
	v_add3_u32 v2, v62, v2, s80
	v_bfe_u32 v104, v66, 16, 1
	v_lshrrev_b32_e32 v2, 16, v2
	v_add3_u32 v104, v66, v104, s80
	v_and_or_b32 v104, v104, s85, v2
	v_bfe_u32 v2, v86, 16, 1
	v_add3_u32 v2, v86, v2, s80
	v_bfe_u32 v105, v90, 16, 1
	v_lshrrev_b32_e32 v2, 16, v2
	v_add3_u32 v105, v90, v105, s80
	v_and_or_b32 v105, v105, s85, v2
	v_bfe_u32 v2, v23, 16, 1
	global_store_dwordx4 v[4:5], v[102:105], off nt
	v_add3_u32 v2, v23, v2, s80
	v_lshrrev_b32_e32 v2, 16, v2
	v_bfe_u32 v102, v27, 16, 1
	v_add3_u32 v102, v27, v102, s80
	v_and_or_b32 v102, v102, s85, v2
	v_bfe_u32 v2, v47, 16, 1
	v_add3_u32 v2, v47, v2, s80
	v_bfe_u32 v103, v19, 16, 1
	v_lshrrev_b32_e32 v2, 16, v2
	v_add3_u32 v103, v19, v103, s80
	v_and_or_b32 v103, v103, s85, v2
	v_bfe_u32 v2, v63, 16, 1
	v_add3_u32 v2, v63, v2, s80
	v_bfe_u32 v104, v67, 16, 1
	v_lshrrev_b32_e32 v2, 16, v2
	v_add3_u32 v104, v67, v104, s80
	v_and_or_b32 v104, v104, s85, v2
	v_bfe_u32 v2, v87, 16, 1
	v_add3_u32 v2, v87, v2, s80
	v_bfe_u32 v105, v91, 16, 1
	v_pk_mul_f32 v[24:25], v[24:25], v[106:107] op_sel_hi:[1,0]
	v_lshrrev_b32_e32 v2, 16, v2
	v_add3_u32 v105, v91, v105, s80
	v_pk_mul_f32 v[28:29], v[28:29], v[106:107] op_sel:[0,1]
	v_and_or_b32 v105, v105, s85, v2
	v_bfe_u32 v2, v24, 16, 1
	global_store_dwordx4 v[4:5], v[102:105], off offset:3072 nt
	v_add3_u32 v2, v24, v2, s80
	v_pk_mul_f32 v[48:49], v[48:49], v[108:109] op_sel_hi:[1,0]
	v_bfe_u32 v102, v28, 16, 1
	v_lshrrev_b32_e32 v2, 16, v2
	v_add3_u32 v102, v28, v102, s80
	v_and_or_b32 v102, v102, s85, v2
	v_bfe_u32 v2, v48, 16, 1
	v_add3_u32 v2, v48, v2, s80
	v_bfe_u32 v103, v20, 16, 1
	v_lshrrev_b32_e32 v2, 16, v2
	v_add3_u32 v103, v20, v103, s80
	v_and_or_b32 v103, v103, s85, v2
	v_bfe_u32 v2, v64, 16, 1
	v_add3_u32 v2, v64, v2, s80
	v_bfe_u32 v104, v68, 16, 1
	v_lshrrev_b32_e32 v2, 16, v2
	v_add3_u32 v104, v68, v104, s80
	v_and_or_b32 v104, v104, s85, v2
	v_bfe_u32 v2, v88, 16, 1
	s_movk_i32 s4, 0x1000
	v_add3_u32 v2, v88, v2, s80
	v_bfe_u32 v105, v92, 16, 1
	v_lshrrev_b32_e32 v2, 16, v2
	v_add3_u32 v105, v92, v105, s80
	v_add_co_u32_e32 v106, vcc, s4, v4
	v_and_or_b32 v105, v105, s85, v2
	s_nop 0
	v_addc_co_u32_e32 v107, vcc, 0, v5, vcc
	v_bfe_u32 v2, v25, 16, 1
	global_store_dwordx4 v[106:107], v[102:105], off offset:2048 nt
	v_add3_u32 v2, v25, v2, s80
	v_lshrrev_b32_e32 v2, 16, v2
	v_bfe_u32 v102, v29, 16, 1
	v_add3_u32 v102, v29, v102, s80
	v_and_or_b32 v102, v102, s85, v2
	v_bfe_u32 v2, v49, 16, 1
	v_add3_u32 v2, v49, v2, s80
	v_bfe_u32 v103, v21, 16, 1
	v_lshrrev_b32_e32 v2, 16, v2
	v_add3_u32 v103, v21, v103, s80
	v_and_or_b32 v103, v103, s85, v2
	v_bfe_u32 v2, v65, 16, 1
	v_add3_u32 v2, v65, v2, s80
	v_bfe_u32 v104, v69, 16, 1
	v_lshrrev_b32_e32 v2, 16, v2
	v_add3_u32 v104, v69, v104, s80
	v_and_or_b32 v104, v104, s85, v2
	v_bfe_u32 v2, v89, 16, 1
	v_add3_u32 v2, v89, v2, s80
	v_bfe_u32 v105, v93, 16, 1
	v_lshrrev_b32_e32 v2, 16, v2
	v_add3_u32 v105, v93, v105, s80
	v_add_co_u32_e32 v4, vcc, 0x2000, v4
	v_and_or_b32 v105, v105, s85, v2
	s_nop 0
	v_addc_co_u32_e32 v5, vcc, 0, v5, vcc
	global_store_dwordx4 v[4:5], v[102:105], off offset:1024 nt
	s_andn2_b64 vcc, exec, s[16:17]
	s_cbranch_vccnz .LBB0_1620
.LBB0_1664:
	s_mul_hi_i32 s4, s14, 0x2aaaaaab
	s_lshr_b32 s5, s4, 31
	s_ashr_i32 s4, s4, 4
	s_add_i32 s4, s4, s5
	v_lshl_or_b32 v4, s4, 6, v146
	v_ashrrev_i32_e32 v5, 31, v4
	v_lshl_add_u64 v[106:107], v[4:5], 2, s[8:9]
	global_load_dwordx4 v[102:105], v[106:107], off offset:16
	s_nop 0
	global_load_dwordx4 v[106:109], v[106:107], off
	s_mulk_i32 s4, 0xf400
	s_add_i32 s4, s4, s0
	s_movk_i32 s15, 0x1000
	s_waitcnt vmcnt(1)
	v_pk_mul_f32 v[56:57], v[56:57], v[102:103] op_sel_hi:[1,0]
	s_waitcnt vmcnt(0)
	v_mov_b32_e32 v2, v109
	v_pk_mul_f32 v[12:13], v[12:13], v[2:3] op_sel_hi:[1,0]
	v_pk_mul_f32 v[10:11], v[10:11], v[2:3] op_sel_hi:[1,0]
	v_mov_b32_e32 v2, v105
	v_pk_mul_f32 v[6:7], v[6:7], v[106:107] op_sel_hi:[1,0]
	v_pk_mul_f32 v[54:55], v[54:55], v[102:103] op_sel_hi:[1,0]
	v_pk_mul_f32 v[60:61], v[60:61], v[102:103] op_sel:[0,1]
	v_pk_mul_f32 v[58:59], v[58:59], v[102:103] op_sel:[0,1]
	v_pk_mul_f32 v[84:85], v[84:85], v[2:3] op_sel_hi:[1,0]
	v_pk_mul_f32 v[82:83], v[82:83], v[2:3] op_sel_hi:[1,0]
	v_add_u32_e32 v2, s4, v149
	v_mov_b64_e32 v[102:103], s[12:13]
	v_pk_mul_f32 v[14:15], v[14:15], v[106:107] op_sel:[0,1]
	v_mad_i64_i32 v[102:103], s[4:5], v2, s68, v[102:103]
	v_bfe_u32 v2, v6, 16, 1
	v_lshl_add_u64 v[4:5], v[4:5], 1, v[102:103]
	v_add3_u32 v2, v6, v2, s80
	v_bfe_u32 v102, v14, 16, 1
	v_pk_mul_f32 v[42:43], v[42:43], v[108:109] op_sel_hi:[1,0]
	v_lshrrev_b32_e32 v2, 16, v2
	v_add3_u32 v102, v14, v102, s80
	v_and_or_b32 v102, v102, s85, v2
	v_bfe_u32 v2, v42, 16, 1
	v_add3_u32 v2, v42, v2, s80
	v_bfe_u32 v103, v10, 16, 1
	v_lshrrev_b32_e32 v2, 16, v2
	v_add3_u32 v103, v10, v103, s80
	v_and_or_b32 v103, v103, s85, v2
	v_bfe_u32 v2, v54, 16, 1
	v_pk_mul_f32 v[80:81], v[80:81], v[104:105] op_sel_hi:[1,0]
	v_pk_mul_f32 v[78:79], v[78:79], v[104:105] op_sel_hi:[1,0]
	v_add3_u32 v2, v54, v2, s80
	v_bfe_u32 v104, v58, 16, 1
	v_lshrrev_b32_e32 v2, 16, v2
	v_add3_u32 v104, v58, v104, s80
	v_and_or_b32 v104, v104, s85, v2
	v_bfe_u32 v2, v78, 16, 1
	v_add3_u32 v2, v78, v2, s80
	v_bfe_u32 v105, v82, 16, 1
	v_lshrrev_b32_e32 v2, 16, v2
	v_add3_u32 v105, v82, v105, s80
	v_and_or_b32 v105, v105, s85, v2
	v_bfe_u32 v2, v7, 16, 1
	global_store_dwordx4 v[4:5], v[102:105], off nt
	v_add3_u32 v2, v7, v2, s80
	v_lshrrev_b32_e32 v2, 16, v2
	v_bfe_u32 v102, v15, 16, 1
	v_add3_u32 v102, v15, v102, s80
	v_and_or_b32 v102, v102, s85, v2
	v_bfe_u32 v2, v43, 16, 1
	v_add3_u32 v2, v43, v2, s80
	v_bfe_u32 v103, v11, 16, 1
	v_lshrrev_b32_e32 v2, 16, v2
	v_add3_u32 v103, v11, v103, s80
	v_and_or_b32 v103, v103, s85, v2
	v_bfe_u32 v2, v55, 16, 1
	v_add3_u32 v2, v55, v2, s80
	v_bfe_u32 v104, v59, 16, 1
	v_lshrrev_b32_e32 v2, 16, v2
	v_add3_u32 v104, v59, v104, s80
	v_and_or_b32 v104, v104, s85, v2
	v_bfe_u32 v2, v79, 16, 1
	v_add3_u32 v2, v79, v2, s80
	v_bfe_u32 v105, v83, 16, 1
	v_pk_mul_f32 v[8:9], v[8:9], v[106:107] op_sel_hi:[1,0]
	v_lshrrev_b32_e32 v2, 16, v2
	v_add3_u32 v105, v83, v105, s80
	v_pk_mul_f32 v[16:17], v[16:17], v[106:107] op_sel:[0,1]
	v_and_or_b32 v105, v105, s85, v2
	v_bfe_u32 v2, v8, 16, 1
	global_store_dwordx4 v[4:5], v[102:105], off offset:3072 nt
	v_add3_u32 v2, v8, v2, s80
	v_pk_mul_f32 v[44:45], v[44:45], v[108:109] op_sel_hi:[1,0]
	v_bfe_u32 v102, v16, 16, 1
	v_lshrrev_b32_e32 v2, 16, v2
	v_add3_u32 v102, v16, v102, s80
	v_and_or_b32 v102, v102, s85, v2
	v_bfe_u32 v2, v44, 16, 1
	v_add3_u32 v2, v44, v2, s80
	v_bfe_u32 v103, v12, 16, 1
	v_lshrrev_b32_e32 v2, 16, v2
	v_add3_u32 v103, v12, v103, s80
	v_and_or_b32 v103, v103, s85, v2
	v_bfe_u32 v2, v56, 16, 1
	v_add3_u32 v2, v56, v2, s80
	v_bfe_u32 v104, v60, 16, 1
	v_lshrrev_b32_e32 v2, 16, v2
	v_add3_u32 v104, v60, v104, s80
	v_and_or_b32 v104, v104, s85, v2
	v_bfe_u32 v2, v80, 16, 1
	v_add3_u32 v2, v80, v2, s80
	v_bfe_u32 v105, v84, 16, 1
	v_lshrrev_b32_e32 v2, 16, v2
	v_add3_u32 v105, v84, v105, s80
	v_add_co_u32_e32 v106, vcc, s15, v4
	v_and_or_b32 v105, v105, s85, v2
	s_nop 0
	v_addc_co_u32_e32 v107, vcc, 0, v5, vcc
	v_bfe_u32 v2, v9, 16, 1
	global_store_dwordx4 v[106:107], v[102:105], off offset:2048 nt
	v_add3_u32 v2, v9, v2, s80
	v_lshrrev_b32_e32 v2, 16, v2
	v_bfe_u32 v102, v17, 16, 1
	v_add3_u32 v102, v17, v102, s80
	v_and_or_b32 v102, v102, s85, v2
	v_bfe_u32 v2, v45, 16, 1
	v_add3_u32 v2, v45, v2, s80
	v_bfe_u32 v103, v13, 16, 1
	v_lshrrev_b32_e32 v2, 16, v2
	v_add3_u32 v103, v13, v103, s80
	v_and_or_b32 v103, v103, s85, v2
	v_bfe_u32 v2, v57, 16, 1
	v_add3_u32 v2, v57, v2, s80
	v_bfe_u32 v104, v61, 16, 1
	v_lshrrev_b32_e32 v2, 16, v2
	v_add3_u32 v104, v61, v104, s80
	v_and_or_b32 v104, v104, s85, v2
	v_bfe_u32 v2, v81, 16, 1
	v_add3_u32 v2, v81, v2, s80
	v_bfe_u32 v105, v85, 16, 1
	v_lshrrev_b32_e32 v2, 16, v2
	v_add3_u32 v105, v85, v105, s80
	v_add_co_u32_e32 v4, vcc, 0x2000, v4
	v_and_or_b32 v105, v105, s85, v2
	s_nop 0
	v_addc_co_u32_e32 v5, vcc, 0, v5, vcc
	global_store_dwordx4 v[4:5], v[102:105], off offset:1024 nt
	s_branch .LBB0_1620

.LBB0_1706:
	v_lshl_add_u64 v[4:5], v[134:135], 2, s[6:7]
	global_load_dwordx4 v[146:149], v[4:5], off offset:2048
	global_load_dwordx4 v[150:153], v[4:5], off offset:2064
	v_ashrrev_i32_e32 v137, 31, v136
	v_lshlrev_b64 v[4:5], 10, v[136:137]
	v_lshl_add_u64 v[4:5], s[8:9], 0, v[4:5]
	v_lshl_add_u64 v[4:5], v[134:135], 1, v[4:5]
	s_andn2_b64 vcc, exec, s[18:19]
	s_waitcnt vmcnt(1)
	v_pk_mul_f32 v[134:135], v[112:113], v[146:147] op_sel_hi:[1,0]
	v_pk_mul_f32 v[110:111], v[110:111], v[146:147] op_sel_hi:[1,0]
	v_pk_mul_f32 v[136:137], v[108:109], v[146:147] op_sel:[0,1]
	v_pk_mul_f32 v[106:107], v[106:107], v[146:147] op_sel:[0,1]
	v_pk_mul_f32 v[108:109], v[114:115], v[148:149] op_sel_hi:[1,0]
	v_mov_b32_e32 v2, v149
	s_waitcnt vmcnt(0)
	v_pk_mul_f32 v[114:115], v[128:129], v[150:151] op_sel_hi:[1,0]
	v_pk_mul_f32 v[112:113], v[126:127], v[150:151] op_sel_hi:[1,0]
	v_pk_mul_f32 v[122:123], v[122:123], v[150:151] op_sel:[0,1]
	v_pk_mul_f32 v[128:129], v[130:131], v[152:153] op_sel_hi:[1,0]
	v_mov_b32_e32 v130, v153
	v_pk_mul_f32 v[126:127], v[132:133], v[152:153] op_sel_hi:[1,0]
	v_pk_mul_f32 v[132:133], v[104:105], v[2:3] op_sel_hi:[1,0]
	v_pk_mul_f32 v[102:103], v[102:103], v[2:3] op_sel_hi:[1,0]
	v_pk_mul_f32 v[120:121], v[120:121], v[130:131] op_sel_hi:[1,0]
	v_pk_mul_f32 v[104:105], v[118:119], v[130:131] op_sel_hi:[1,0]
	v_bfe_u32 v2, v110, 16, 1
	v_bfe_u32 v118, v106, 16, 1
	v_bfe_u32 v119, v108, 16, 1
	v_bfe_u32 v130, v112, 16, 1
	v_bfe_u32 v131, v122, 16, 1
	v_bfe_u32 v138, v128, 16, 1
	v_pk_mul_f32 v[116:117], v[116:117], v[148:149] op_sel_hi:[1,0]
	v_bfe_u32 v139, v111, 16, 1
	v_bfe_u32 v146, v109, 16, 1
	v_bfe_u32 v147, v113, 16, 1
	v_bfe_u32 v149, v129, 16, 1
	v_add3_u32 v2, v110, v2, s80
	v_add3_u32 v106, v106, v118, s80
	v_add3_u32 v108, v108, v119, s80
	v_bfe_u32 v110, v102, 16, 1
	v_add3_u32 v112, v112, v130, s80
	v_add3_u32 v118, v122, v131, s80
	v_add3_u32 v119, v128, v138, s80
	v_bfe_u32 v122, v104, 16, 1
	v_bfe_u32 v145, v107, 16, 1
	v_bfe_u32 v148, v123, 16, 1
	v_add3_u32 v111, v111, v139, s80
	v_add3_u32 v109, v109, v146, s80
	v_bfe_u32 v128, v103, 16, 1
	v_add3_u32 v113, v113, v147, s80
	v_add3_u32 v129, v129, v149, s80
	v_bfe_u32 v130, v105, 16, 1
	v_lshrrev_b32_e32 v2, 16, v2
	v_lshrrev_b32_e32 v108, 16, v108
	v_add3_u32 v110, v102, v110, s80
	v_lshrrev_b32_e32 v112, 16, v112
	v_lshrrev_b32_e32 v119, 16, v119
	v_add3_u32 v122, v104, v122, s80
	v_pk_mul_f32 v[124:125], v[124:125], v[150:151] op_sel:[0,1]
	v_add3_u32 v107, v107, v145, s80
	v_add3_u32 v123, v123, v148, s80
	v_lshrrev_b32_e32 v111, 16, v111
	v_lshrrev_b32_e32 v109, 16, v109
	v_add3_u32 v128, v103, v128, s80
	v_lshrrev_b32_e32 v113, 16, v113
	v_lshrrev_b32_e32 v129, 16, v129
	v_add3_u32 v130, v105, v130, s80
	v_and_or_b32 v102, v106, s85, v2
	v_and_or_b32 v103, v110, s85, v108
	v_and_or_b32 v104, v118, s85, v112
	v_and_or_b32 v105, v122, s85, v119
	v_bfe_u32 v2, v114, 16, 1
	v_and_or_b32 v106, v107, s85, v111
	v_and_or_b32 v107, v128, s85, v109
	v_and_or_b32 v108, v123, s85, v113
	v_and_or_b32 v109, v130, s85, v129
	global_store_dwordx4 v[4:5], v[102:105], off nt
	global_store_dwordx4 v[4:5], v[106:109], off offset:1024 nt
	v_add3_u32 v2, v114, v2, s80
	v_bfe_u32 v102, v124, 16, 1
	v_lshrrev_b32_e32 v2, 16, v2
	v_add3_u32 v102, v124, v102, s80
	v_and_or_b32 v112, v102, s85, v2
	v_bfe_u32 v2, v126, 16, 1
	v_add3_u32 v2, v126, v2, s80
	v_bfe_u32 v102, v120, 16, 1
	v_lshrrev_b32_e32 v2, 16, v2
	v_add3_u32 v102, v120, v102, s80
	v_and_or_b32 v113, v102, s85, v2
	v_bfe_u32 v2, v135, 16, 1
	v_add3_u32 v2, v135, v2, s80
	v_bfe_u32 v102, v137, 16, 1
	v_lshrrev_b32_e32 v2, 16, v2
	v_add3_u32 v102, v137, v102, s80
	v_and_or_b32 v102, v102, s85, v2
	v_bfe_u32 v2, v117, 16, 1
	v_add3_u32 v2, v117, v2, s80
	v_bfe_u32 v103, v133, 16, 1
	v_lshrrev_b32_e32 v2, 16, v2
	v_add3_u32 v103, v133, v103, s80
	v_and_or_b32 v103, v103, s85, v2
	v_bfe_u32 v2, v115, 16, 1
	v_add3_u32 v2, v115, v2, s80
	v_bfe_u32 v104, v125, 16, 1
	v_lshrrev_b32_e32 v2, 16, v2
	v_add3_u32 v104, v125, v104, s80
	v_bfe_u32 v150, v134, 16, 1
	v_bfe_u32 v151, v136, 16, 1
	v_bfe_u32 v152, v116, 16, 1
	v_and_or_b32 v104, v104, s85, v2
	v_bfe_u32 v2, v127, 16, 1
	v_add3_u32 v131, v134, v150, s80
	v_add3_u32 v134, v136, v151, s80
	v_add3_u32 v116, v116, v152, s80
	v_bfe_u32 v136, v132, 16, 1
	v_add3_u32 v2, v127, v2, s80
	v_bfe_u32 v105, v121, 16, 1
	v_lshrrev_b32_e32 v131, 16, v131
	v_lshrrev_b32_e32 v116, 16, v116
	v_add3_u32 v132, v132, v136, s80
	v_lshrrev_b32_e32 v2, 16, v2
	v_add3_u32 v105, v121, v105, s80
	v_and_or_b32 v110, v134, s85, v131
	v_and_or_b32 v111, v132, s85, v116
	v_and_or_b32 v105, v105, s85, v2
	global_store_dwordx4 v[4:5], v[110:113], off offset:2048 nt
	global_store_dwordx4 v[4:5], v[102:105], off offset:3072 nt
	s_cbranch_vccnz .LBB0_1709
	s_ashr_i32 s4, s27, 31
	s_lshr_b32 s4, s4, 25
	s_add_i32 s27, s27, s4
	s_ashr_i32 s4, s27, 7
	v_lshl_or_b32 v4, s4, 6, v140
	v_ashrrev_i32_e32 v5, 31, v4
	v_lshl_add_u64 v[106:107], v[4:5], 2, s[6:7]
	global_load_dwordx4 v[102:105], v[106:107], off offset:2064
	s_nop 0
	global_load_dwordx4 v[106:109], v[106:107], off offset:2048
	s_lshl_b32 s4, s4, 12
	s_waitcnt vmcnt(1)
	v_pk_mul_f32 v[72:73], v[72:73], v[102:103] op_sel_hi:[1,0]
	s_waitcnt vmcnt(0)
	v_mov_b32_e32 v2, v109
	v_pk_mul_f32 v[36:37], v[36:37], v[2:3] op_sel_hi:[1,0]
	v_pk_mul_f32 v[34:35], v[34:35], v[2:3] op_sel_hi:[1,0]
	v_mov_b32_e32 v2, v105
	v_pk_mul_f32 v[100:101], v[100:101], v[2:3] op_sel_hi:[1,0]
	v_pk_mul_f32 v[98:99], v[98:99], v[2:3] op_sel_hi:[1,0]
	v_add_u32_e32 v2, s23, v144
	v_pk_mul_f32 v[70:71], v[70:71], v[102:103] op_sel_hi:[1,0]
	v_pk_mul_f32 v[76:77], v[76:77], v[102:103] op_sel:[0,1]
	v_pk_mul_f32 v[74:75], v[74:75], v[102:103] op_sel:[0,1]
	v_subrev_u32_e32 v102, s4, v2
	v_ashrrev_i32_e32 v103, 31, v102
	v_pk_mul_f32 v[30:31], v[30:31], v[106:107] op_sel_hi:[1,0]
	v_lshlrev_b64 v[102:103], 10, v[102:103]
	v_pk_mul_f32 v[38:39], v[38:39], v[106:107] op_sel:[0,1]
	v_lshl_add_u64 v[102:103], s[8:9], 0, v[102:103]
	v_bfe_u32 v2, v30, 16, 1
	v_lshl_add_u64 v[4:5], v[4:5], 1, v[102:103]
	v_add3_u32 v2, v30, v2, s80
	v_bfe_u32 v102, v38, 16, 1
	v_pk_mul_f32 v[50:51], v[50:51], v[108:109] op_sel_hi:[1,0]
	v_lshrrev_b32_e32 v2, 16, v2
	v_add3_u32 v102, v38, v102, s80
	v_and_or_b32 v102, v102, s85, v2
	v_bfe_u32 v2, v50, 16, 1
	v_add3_u32 v2, v50, v2, s80
	v_bfe_u32 v103, v34, 16, 1
	v_lshrrev_b32_e32 v2, 16, v2
	v_add3_u32 v103, v34, v103, s80
	v_and_or_b32 v103, v103, s85, v2
	v_bfe_u32 v2, v70, 16, 1
	v_pk_mul_f32 v[96:97], v[96:97], v[104:105] op_sel_hi:[1,0]
	v_pk_mul_f32 v[94:95], v[94:95], v[104:105] op_sel_hi:[1,0]
	v_add3_u32 v2, v70, v2, s80
	v_bfe_u32 v104, v74, 16, 1
	v_lshrrev_b32_e32 v2, 16, v2
	v_add3_u32 v104, v74, v104, s80
	v_and_or_b32 v104, v104, s85, v2
	v_bfe_u32 v2, v94, 16, 1
	v_add3_u32 v2, v94, v2, s80
	v_bfe_u32 v105, v98, 16, 1
	v_lshrrev_b32_e32 v2, 16, v2
	v_add3_u32 v105, v98, v105, s80
	v_and_or_b32 v105, v105, s85, v2
	v_bfe_u32 v2, v31, 16, 1
	global_store_dwordx4 v[4:5], v[102:105], off nt
	v_add3_u32 v2, v31, v2, s80
	v_lshrrev_b32_e32 v2, 16, v2
	v_bfe_u32 v102, v39, 16, 1
	v_add3_u32 v102, v39, v102, s80
	v_and_or_b32 v102, v102, s85, v2
	v_bfe_u32 v2, v51, 16, 1
	v_add3_u32 v2, v51, v2, s80
	v_bfe_u32 v103, v35, 16, 1
	v_lshrrev_b32_e32 v2, 16, v2
	v_add3_u32 v103, v35, v103, s80
	v_and_or_b32 v103, v103, s85, v2
	v_bfe_u32 v2, v71, 16, 1
	v_add3_u32 v2, v71, v2, s80
	v_bfe_u32 v104, v75, 16, 1
	v_lshrrev_b32_e32 v2, 16, v2
	v_add3_u32 v104, v75, v104, s80
	v_and_or_b32 v104, v104, s85, v2
	v_bfe_u32 v2, v95, 16, 1
	v_add3_u32 v2, v95, v2, s80
	v_bfe_u32 v105, v99, 16, 1
	v_pk_mul_f32 v[32:33], v[32:33], v[106:107] op_sel_hi:[1,0]
	v_lshrrev_b32_e32 v2, 16, v2
	v_add3_u32 v105, v99, v105, s80
	v_pk_mul_f32 v[40:41], v[40:41], v[106:107] op_sel:[0,1]
	v_and_or_b32 v105, v105, s85, v2
	v_bfe_u32 v2, v32, 16, 1
	global_store_dwordx4 v[4:5], v[102:105], off offset:1024 nt
	v_add3_u32 v2, v32, v2, s80
	v_pk_mul_f32 v[52:53], v[52:53], v[108:109] op_sel_hi:[1,0]
	v_bfe_u32 v102, v40, 16, 1
	v_lshrrev_b32_e32 v2, 16, v2
	v_add3_u32 v102, v40, v102, s80
	v_and_or_b32 v102, v102, s85, v2
	v_bfe_u32 v2, v52, 16, 1
	v_add3_u32 v2, v52, v2, s80
	v_bfe_u32 v103, v36, 16, 1
	v_lshrrev_b32_e32 v2, 16, v2
	v_add3_u32 v103, v36, v103, s80
	v_and_or_b32 v103, v103, s85, v2
	v_bfe_u32 v2, v72, 16, 1
	v_add3_u32 v2, v72, v2, s80
	v_bfe_u32 v104, v76, 16, 1
	v_lshrrev_b32_e32 v2, 16, v2
	v_add3_u32 v104, v76, v104, s80
	v_and_or_b32 v104, v104, s85, v2
	v_bfe_u32 v2, v96, 16, 1
	v_add3_u32 v2, v96, v2, s80
	v_bfe_u32 v105, v100, 16, 1
	v_lshrrev_b32_e32 v2, 16, v2
	v_add3_u32 v105, v100, v105, s80
	v_and_or_b32 v105, v105, s85, v2
	v_bfe_u32 v2, v33, 16, 1
	global_store_dwordx4 v[4:5], v[102:105], off offset:2048 nt
	v_add3_u32 v2, v33, v2, s80
	v_lshrrev_b32_e32 v2, 16, v2
	v_bfe_u32 v102, v41, 16, 1
	v_add3_u32 v102, v41, v102, s80
	v_and_or_b32 v102, v102, s85, v2
	v_bfe_u32 v2, v53, 16, 1
	v_add3_u32 v2, v53, v2, s80
	v_bfe_u32 v103, v37, 16, 1
	v_lshrrev_b32_e32 v2, 16, v2
	v_add3_u32 v103, v37, v103, s80
	v_and_or_b32 v103, v103, s85, v2
	v_bfe_u32 v2, v73, 16, 1
	v_add3_u32 v2, v73, v2, s80
	v_bfe_u32 v104, v77, 16, 1
	v_lshrrev_b32_e32 v2, 16, v2
	v_add3_u32 v104, v77, v104, s80
	v_and_or_b32 v104, v104, s85, v2
	v_bfe_u32 v2, v97, 16, 1
	v_add3_u32 v2, v97, v2, s80
	v_bfe_u32 v105, v101, 16, 1
	v_lshrrev_b32_e32 v2, 16, v2
	v_add3_u32 v105, v101, v105, s80
	v_and_or_b32 v105, v105, s85, v2
	global_store_dwordx4 v[4:5], v[102:105], off offset:3072 nt
	s_andn2_b64 vcc, exec, s[16:17]
	s_cbranch_vccz .LBB0_1710

.LBB0_1710:
	s_ashr_i32 s4, s26, 31
	s_lshr_b32 s4, s4, 25
	s_add_i32 s26, s26, s4
	s_ashr_i32 s4, s26, 7
	v_lshl_or_b32 v4, s4, 6, v140
	v_ashrrev_i32_e32 v5, 31, v4
	v_lshl_add_u64 v[106:107], v[4:5], 2, s[6:7]
	global_load_dwordx4 v[102:105], v[106:107], off offset:2064
	s_nop 0
	global_load_dwordx4 v[106:109], v[106:107], off offset:2048
	s_lshl_b32 s4, s4, 12
	s_waitcnt vmcnt(1)
	v_pk_mul_f32 v[64:65], v[64:65], v[102:103] op_sel_hi:[1,0]
	s_waitcnt vmcnt(0)
	v_mov_b32_e32 v2, v109
	v_pk_mul_f32 v[20:21], v[20:21], v[2:3] op_sel_hi:[1,0]
	v_pk_mul_f32 v[18:19], v[18:19], v[2:3] op_sel_hi:[1,0]
	v_mov_b32_e32 v2, v105
	v_pk_mul_f32 v[92:93], v[92:93], v[2:3] op_sel_hi:[1,0]
	v_pk_mul_f32 v[90:91], v[90:91], v[2:3] op_sel_hi:[1,0]
	v_add_u32_e32 v2, s23, v142
	v_pk_mul_f32 v[62:63], v[62:63], v[102:103] op_sel_hi:[1,0]
	v_pk_mul_f32 v[68:69], v[68:69], v[102:103] op_sel:[0,1]
	v_pk_mul_f32 v[66:67], v[66:67], v[102:103] op_sel:[0,1]
	v_subrev_u32_e32 v102, s4, v2
	v_ashrrev_i32_e32 v103, 31, v102
	v_pk_mul_f32 v[22:23], v[22:23], v[106:107] op_sel_hi:[1,0]
	v_lshlrev_b64 v[102:103], 10, v[102:103]
	v_pk_mul_f32 v[26:27], v[26:27], v[106:107] op_sel:[0,1]
	v_lshl_add_u64 v[102:103], s[8:9], 0, v[102:103]
	v_bfe_u32 v2, v22, 16, 1
	v_lshl_add_u64 v[4:5], v[4:5], 1, v[102:103]
	v_add3_u32 v2, v22, v2, s80
	v_bfe_u32 v102, v26, 16, 1
	v_pk_mul_f32 v[46:47], v[46:47], v[108:109] op_sel_hi:[1,0]
	v_lshrrev_b32_e32 v2, 16, v2
	v_add3_u32 v102, v26, v102, s80
	v_and_or_b32 v102, v102, s85, v2
	v_bfe_u32 v2, v46, 16, 1
	v_add3_u32 v2, v46, v2, s80
	v_bfe_u32 v103, v18, 16, 1
	v_lshrrev_b32_e32 v2, 16, v2
	v_add3_u32 v103, v18, v103, s80
	v_and_or_b32 v103, v103, s85, v2
	v_bfe_u32 v2, v62, 16, 1
	v_pk_mul_f32 v[88:89], v[88:89], v[104:105] op_sel_hi:[1,0]
	v_pk_mul_f32 v[86:87], v[86:87], v[104:105] op_sel_hi:[1,0]
	v_add3_u32 v2, v62, v2, s80
	v_bfe_u32 v104, v66, 16, 1
	v_lshrrev_b32_e32 v2, 16, v2
	v_add3_u32 v104, v66, v104, s80
	v_and_or_b32 v104, v104, s85, v2
	v_bfe_u32 v2, v86, 16, 1
	v_add3_u32 v2, v86, v2, s80
	v_bfe_u32 v105, v90, 16, 1
	v_lshrrev_b32_e32 v2, 16, v2
	v_add3_u32 v105, v90, v105, s80
	v_and_or_b32 v105, v105, s85, v2
	v_bfe_u32 v2, v23, 16, 1
	global_store_dwordx4 v[4:5], v[102:105], off nt
	v_add3_u32 v2, v23, v2, s80
	v_lshrrev_b32_e32 v2, 16, v2
	v_bfe_u32 v102, v27, 16, 1
	v_add3_u32 v102, v27, v102, s80
	v_and_or_b32 v102, v102, s85, v2
	v_bfe_u32 v2, v47, 16, 1
	v_add3_u32 v2, v47, v2, s80
	v_bfe_u32 v103, v19, 16, 1
	v_lshrrev_b32_e32 v2, 16, v2
	v_add3_u32 v103, v19, v103, s80
	v_and_or_b32 v103, v103, s85, v2
	v_bfe_u32 v2, v63, 16, 1
	v_add3_u32 v2, v63, v2, s80
	v_bfe_u32 v104, v67, 16, 1
	v_lshrrev_b32_e32 v2, 16, v2
	v_add3_u32 v104, v67, v104, s80
	v_and_or_b32 v104, v104, s85, v2
	v_bfe_u32 v2, v87, 16, 1
	v_add3_u32 v2, v87, v2, s80
	v_bfe_u32 v105, v91, 16, 1
	v_pk_mul_f32 v[24:25], v[24:25], v[106:107] op_sel_hi:[1,0]
	v_lshrrev_b32_e32 v2, 16, v2
	v_add3_u32 v105, v91, v105, s80
	v_pk_mul_f32 v[28:29], v[28:29], v[106:107] op_sel:[0,1]
	v_and_or_b32 v105, v105, s85, v2
	v_bfe_u32 v2, v24, 16, 1
	global_store_dwordx4 v[4:5], v[102:105], off offset:1024 nt
	v_add3_u32 v2, v24, v2, s80
	v_pk_mul_f32 v[48:49], v[48:49], v[108:109] op_sel_hi:[1,0]
	v_bfe_u32 v102, v28, 16, 1
	v_lshrrev_b32_e32 v2, 16, v2
	v_add3_u32 v102, v28, v102, s80
	v_and_or_b32 v102, v102, s85, v2
	v_bfe_u32 v2, v48, 16, 1
	v_add3_u32 v2, v48, v2, s80
	v_bfe_u32 v103, v20, 16, 1
	v_lshrrev_b32_e32 v2, 16, v2
	v_add3_u32 v103, v20, v103, s80
	v_and_or_b32 v103, v103, s85, v2
	v_bfe_u32 v2, v64, 16, 1
	v_add3_u32 v2, v64, v2, s80
	v_bfe_u32 v104, v68, 16, 1
	v_lshrrev_b32_e32 v2, 16, v2
	v_add3_u32 v104, v68, v104, s80
	v_and_or_b32 v104, v104, s85, v2
	v_bfe_u32 v2, v88, 16, 1
	v_add3_u32 v2, v88, v2, s80
	v_bfe_u32 v105, v92, 16, 1
	v_lshrrev_b32_e32 v2, 16, v2
	v_add3_u32 v105, v92, v105, s80
	v_and_or_b32 v105, v105, s85, v2
	v_bfe_u32 v2, v25, 16, 1
	global_store_dwordx4 v[4:5], v[102:105], off offset:2048 nt
	v_add3_u32 v2, v25, v2, s80
	v_lshrrev_b32_e32 v2, 16, v2
	v_bfe_u32 v102, v29, 16, 1
	v_add3_u32 v102, v29, v102, s80
	v_and_or_b32 v102, v102, s85, v2
	v_bfe_u32 v2, v49, 16, 1
	v_add3_u32 v2, v49, v2, s80
	v_bfe_u32 v103, v21, 16, 1
	v_lshrrev_b32_e32 v2, 16, v2
	v_add3_u32 v103, v21, v103, s80
	v_and_or_b32 v103, v103, s85, v2
	v_bfe_u32 v2, v65, 16, 1
	v_add3_u32 v2, v65, v2, s80
	v_bfe_u32 v104, v69, 16, 1
	v_lshrrev_b32_e32 v2, 16, v2
	v_add3_u32 v104, v69, v104, s80
	v_and_or_b32 v104, v104, s85, v2
	v_bfe_u32 v2, v89, 16, 1
	v_add3_u32 v2, v89, v2, s80
	v_bfe_u32 v105, v93, 16, 1
	v_lshrrev_b32_e32 v2, 16, v2
	v_add3_u32 v105, v93, v105, s80
	v_and_or_b32 v105, v105, s85, v2
	global_store_dwordx4 v[4:5], v[102:105], off offset:3072 nt
	s_andn2_b64 vcc, exec, s[12:13]
	s_cbranch_vccnz .LBB0_1667
.LBB0_1711:
	s_ashr_i32 s4, s15, 31
	s_lshr_b32 s4, s4, 25
	s_add_i32 s15, s15, s4
	s_ashr_i32 s4, s15, 7
	v_lshl_or_b32 v4, s4, 6, v140
	v_ashrrev_i32_e32 v5, 31, v4
	v_lshl_add_u64 v[106:107], v[4:5], 2, s[6:7]
	global_load_dwordx4 v[102:105], v[106:107], off offset:2064
	s_nop 0
	global_load_dwordx4 v[106:109], v[106:107], off offset:2048
	s_lshl_b32 s4, s4, 12
	s_waitcnt vmcnt(1)
	v_pk_mul_f32 v[56:57], v[56:57], v[102:103] op_sel_hi:[1,0]
	s_waitcnt vmcnt(0)
	v_mov_b32_e32 v2, v109
	v_pk_mul_f32 v[12:13], v[12:13], v[2:3] op_sel_hi:[1,0]
	v_pk_mul_f32 v[10:11], v[10:11], v[2:3] op_sel_hi:[1,0]
	v_mov_b32_e32 v2, v105
	v_pk_mul_f32 v[84:85], v[84:85], v[2:3] op_sel_hi:[1,0]
	v_pk_mul_f32 v[82:83], v[82:83], v[2:3] op_sel_hi:[1,0]
	v_add_u32_e32 v2, s23, v143
	v_pk_mul_f32 v[54:55], v[54:55], v[102:103] op_sel_hi:[1,0]
	v_pk_mul_f32 v[60:61], v[60:61], v[102:103] op_sel:[0,1]
	v_pk_mul_f32 v[58:59], v[58:59], v[102:103] op_sel:[0,1]
	v_subrev_u32_e32 v102, s4, v2
	v_ashrrev_i32_e32 v103, 31, v102
	v_pk_mul_f32 v[6:7], v[6:7], v[106:107] op_sel_hi:[1,0]
	v_lshlrev_b64 v[102:103], 10, v[102:103]
	v_pk_mul_f32 v[14:15], v[14:15], v[106:107] op_sel:[0,1]
	v_lshl_add_u64 v[102:103], s[8:9], 0, v[102:103]
	v_bfe_u32 v2, v6, 16, 1
	v_lshl_add_u64 v[4:5], v[4:5], 1, v[102:103]
	v_add3_u32 v2, v6, v2, s80
	v_bfe_u32 v102, v14, 16, 1
	v_pk_mul_f32 v[42:43], v[42:43], v[108:109] op_sel_hi:[1,0]
	v_lshrrev_b32_e32 v2, 16, v2
	v_add3_u32 v102, v14, v102, s80
	v_and_or_b32 v102, v102, s85, v2
	v_bfe_u32 v2, v42, 16, 1
	v_add3_u32 v2, v42, v2, s80
	v_bfe_u32 v103, v10, 16, 1
	v_lshrrev_b32_e32 v2, 16, v2
	v_add3_u32 v103, v10, v103, s80
	v_and_or_b32 v103, v103, s85, v2
	v_bfe_u32 v2, v54, 16, 1
	v_pk_mul_f32 v[80:81], v[80:81], v[104:105] op_sel_hi:[1,0]
	v_pk_mul_f32 v[78:79], v[78:79], v[104:105] op_sel_hi:[1,0]
	v_add3_u32 v2, v54, v2, s80
	v_bfe_u32 v104, v58, 16, 1
	v_lshrrev_b32_e32 v2, 16, v2
	v_add3_u32 v104, v58, v104, s80
	v_and_or_b32 v104, v104, s85, v2
	v_bfe_u32 v2, v78, 16, 1
	v_add3_u32 v2, v78, v2, s80
	v_bfe_u32 v105, v82, 16, 1
	v_lshrrev_b32_e32 v2, 16, v2
	v_add3_u32 v105, v82, v105, s80
	v_and_or_b32 v105, v105, s85, v2
	v_bfe_u32 v2, v7, 16, 1
	global_store_dwordx4 v[4:5], v[102:105], off nt
	v_add3_u32 v2, v7, v2, s80
	v_lshrrev_b32_e32 v2, 16, v2
	v_bfe_u32 v102, v15, 16, 1
	v_add3_u32 v102, v15, v102, s80
	v_and_or_b32 v102, v102, s85, v2
	v_bfe_u32 v2, v43, 16, 1
	v_add3_u32 v2, v43, v2, s80
	v_bfe_u32 v103, v11, 16, 1
	v_lshrrev_b32_e32 v2, 16, v2
	v_add3_u32 v103, v11, v103, s80
	v_and_or_b32 v103, v103, s85, v2
	v_bfe_u32 v2, v55, 16, 1
	v_add3_u32 v2, v55, v2, s80
	v_bfe_u32 v104, v59, 16, 1
	v_lshrrev_b32_e32 v2, 16, v2
	v_add3_u32 v104, v59, v104, s80
	v_and_or_b32 v104, v104, s85, v2
	v_bfe_u32 v2, v79, 16, 1
	v_add3_u32 v2, v79, v2, s80
	v_bfe_u32 v105, v83, 16, 1
	v_pk_mul_f32 v[8:9], v[8:9], v[106:107] op_sel_hi:[1,0]
	v_lshrrev_b32_e32 v2, 16, v2
	v_add3_u32 v105, v83, v105, s80
	v_pk_mul_f32 v[16:17], v[16:17], v[106:107] op_sel:[0,1]
	v_and_or_b32 v105, v105, s85, v2
	v_bfe_u32 v2, v8, 16, 1
	global_store_dwordx4 v[4:5], v[102:105], off offset:1024 nt
	v_add3_u32 v2, v8, v2, s80
	v_pk_mul_f32 v[44:45], v[44:45], v[108:109] op_sel_hi:[1,0]
	v_bfe_u32 v102, v16, 16, 1
	v_lshrrev_b32_e32 v2, 16, v2
	v_add3_u32 v102, v16, v102, s80
	v_and_or_b32 v102, v102, s85, v2
	v_bfe_u32 v2, v44, 16, 1
	v_add3_u32 v2, v44, v2, s80
	v_bfe_u32 v103, v12, 16, 1
	v_lshrrev_b32_e32 v2, 16, v2
	v_add3_u32 v103, v12, v103, s80
	v_and_or_b32 v103, v103, s85, v2
	v_bfe_u32 v2, v56, 16, 1
	v_add3_u32 v2, v56, v2, s80
	v_bfe_u32 v104, v60, 16, 1
	v_lshrrev_b32_e32 v2, 16, v2
	v_add3_u32 v104, v60, v104, s80
	v_and_or_b32 v104, v104, s85, v2
	v_bfe_u32 v2, v80, 16, 1
	v_add3_u32 v2, v80, v2, s80
	v_bfe_u32 v105, v84, 16, 1
	v_lshrrev_b32_e32 v2, 16, v2
	v_add3_u32 v105, v84, v105, s80
	v_and_or_b32 v105, v105, s85, v2
	v_bfe_u32 v2, v9, 16, 1
	global_store_dwordx4 v[4:5], v[102:105], off offset:2048 nt
	v_add3_u32 v2, v9, v2, s80
	v_lshrrev_b32_e32 v2, 16, v2
	v_bfe_u32 v102, v17, 16, 1
	v_add3_u32 v102, v17, v102, s80
	v_and_or_b32 v102, v102, s85, v2
	v_bfe_u32 v2, v45, 16, 1
	v_add3_u32 v2, v45, v2, s80
	v_bfe_u32 v103, v13, 16, 1
	v_lshrrev_b32_e32 v2, 16, v2
	v_add3_u32 v103, v13, v103, s80
	v_and_or_b32 v103, v103, s85, v2
	v_bfe_u32 v2, v57, 16, 1
	v_add3_u32 v2, v57, v2, s80
	v_bfe_u32 v104, v61, 16, 1
	v_lshrrev_b32_e32 v2, 16, v2
	v_add3_u32 v104, v61, v104, s80
	v_and_or_b32 v104, v104, s85, v2
	v_bfe_u32 v2, v81, 16, 1
	v_add3_u32 v2, v81, v2, s80
	v_bfe_u32 v105, v85, 16, 1
	v_lshrrev_b32_e32 v2, 16, v2
	v_add3_u32 v105, v85, v105, s80
	v_and_or_b32 v105, v105, s85, v2
	global_store_dwordx4 v[4:5], v[102:105], off offset:3072 nt
	s_branch .LBB0_1667

.LBB0_1758:
	s_waitcnt vmcnt(1)
	v_bfe_u32 v2, v104, 16, 1
	v_mov_b64_e32 v[140:141], s[16:17]
	v_add3_u32 v2, v104, v2, s80
	s_waitcnt vmcnt(0)
	v_bfe_u32 v104, v100, 16, 1
	v_mad_i64_i32 v[140:141], s[4:5], v139, s91, v[140:141]
	v_lshrrev_b32_e32 v2, 16, v2
	v_add3_u32 v100, v100, v104, s80
	v_lshl_add_u64 v[132:133], v[132:133], 1, v[140:141]
	v_and_or_b32 v140, v100, s85, v2
	v_bfe_u32 v2, v116, 16, 1
	v_add3_u32 v2, v116, v2, s80
	v_bfe_u32 v100, v112, 16, 1
	v_lshrrev_b32_e32 v2, 16, v2
	v_add3_u32 v100, v112, v100, s80
	v_and_or_b32 v141, v100, s85, v2
	v_bfe_u32 v2, v120, 16, 1
	v_add3_u32 v2, v120, v2, s80
	v_bfe_u32 v100, v108, 16, 1
	v_lshrrev_b32_e32 v2, 16, v2
	v_add3_u32 v100, v108, v100, s80
	v_and_or_b32 v142, v100, s85, v2
	v_bfe_u32 v2, v128, 16, 1
	v_add3_u32 v2, v128, v2, s80
	v_bfe_u32 v100, v124, 16, 1
	v_lshrrev_b32_e32 v2, 16, v2
	v_add3_u32 v100, v124, v100, s80
	v_and_or_b32 v143, v100, s85, v2
	v_bfe_u32 v2, v105, 16, 1
	v_add3_u32 v2, v105, v2, s80
	v_bfe_u32 v100, v101, 16, 1
	v_lshrrev_b32_e32 v2, 16, v2
	v_add3_u32 v100, v101, v100, s80
	global_store_dwordx4 v[132:133], v[140:143], off nt
	s_nop 1
	v_and_or_b32 v140, v100, s85, v2
	v_bfe_u32 v2, v117, 16, 1
	v_add3_u32 v2, v117, v2, s80
	v_bfe_u32 v100, v113, 16, 1
	v_lshrrev_b32_e32 v2, 16, v2
	v_add3_u32 v100, v113, v100, s80
	v_and_or_b32 v141, v100, s85, v2
	v_bfe_u32 v2, v121, 16, 1
	v_add3_u32 v2, v121, v2, s80
	v_bfe_u32 v100, v109, 16, 1
	v_lshrrev_b32_e32 v2, 16, v2
	v_add3_u32 v100, v109, v100, s80
	v_and_or_b32 v142, v100, s85, v2
	v_bfe_u32 v2, v129, 16, 1
	v_add3_u32 v2, v129, v2, s80
	v_bfe_u32 v100, v125, 16, 1
	v_lshrrev_b32_e32 v2, 16, v2
	v_add3_u32 v100, v125, v100, s80
	v_and_or_b32 v143, v100, s85, v2
	v_add_co_u32_e32 v100, vcc, s91, v132
	v_bfe_u32 v2, v106, 16, 1
	s_nop 0
	v_addc_co_u32_e32 v101, vcc, 0, v133, vcc
	global_store_dwordx4 v[100:101], v[140:143], off nt
	v_add3_u32 v2, v106, v2, s80
	v_bfe_u32 v100, v102, 16, 1
	v_lshrrev_b32_e32 v2, 16, v2
	v_add3_u32 v100, v102, v100, s80
	v_and_or_b32 v140, v100, s85, v2
	v_bfe_u32 v2, v118, 16, 1
	v_add3_u32 v2, v118, v2, s80
	v_bfe_u32 v100, v114, 16, 1
	v_lshrrev_b32_e32 v2, 16, v2
	v_add3_u32 v100, v114, v100, s80
	v_and_or_b32 v141, v100, s85, v2
	v_bfe_u32 v2, v122, 16, 1
	v_add3_u32 v2, v122, v2, s80
	v_bfe_u32 v100, v110, 16, 1
	v_lshrrev_b32_e32 v2, 16, v2
	v_add3_u32 v100, v110, v100, s80
	v_and_or_b32 v142, v100, s85, v2
	v_bfe_u32 v2, v130, 16, 1
	v_add3_u32 v2, v130, v2, s80
	v_bfe_u32 v100, v126, 16, 1
	v_lshrrev_b32_e32 v2, 16, v2
	v_add3_u32 v100, v126, v100, s80
	v_and_or_b32 v143, v100, s85, v2
	v_add_co_u32_e32 v100, vcc, s87, v132
	v_bfe_u32 v2, v107, 16, 1
	s_nop 0
	v_addc_co_u32_e32 v101, vcc, 0, v133, vcc
	global_store_dwordx4 v[100:101], v[140:143], off nt
	v_add3_u32 v2, v107, v2, s80
	v_bfe_u32 v100, v103, 16, 1
	v_lshrrev_b32_e32 v2, 16, v2
	v_add3_u32 v100, v103, v100, s80
	v_and_or_b32 v100, v100, s85, v2
	v_bfe_u32 v2, v119, 16, 1
	v_add3_u32 v2, v119, v2, s80
	v_bfe_u32 v101, v115, 16, 1
	v_lshrrev_b32_e32 v2, 16, v2
	v_add3_u32 v101, v115, v101, s80
	v_and_or_b32 v101, v101, s85, v2
	v_bfe_u32 v2, v123, 16, 1
	v_add3_u32 v2, v123, v2, s80
	v_bfe_u32 v102, v111, 16, 1
	v_lshrrev_b32_e32 v2, 16, v2
	v_add3_u32 v102, v111, v102, s80
	v_and_or_b32 v102, v102, s85, v2
	v_bfe_u32 v2, v131, 16, 1
	v_add3_u32 v2, v131, v2, s80
	v_bfe_u32 v103, v127, 16, 1
	v_add_co_u32_e32 v104, vcc, 0x9000, v132
	v_lshrrev_b32_e32 v2, 16, v2
	v_add3_u32 v103, v127, v103, s80
	v_addc_co_u32_e32 v105, vcc, 0, v133, vcc
	v_and_or_b32 v103, v103, s85, v2
	s_andn2_b64 vcc, exec, s[18:19]
	global_store_dwordx4 v[104:105], v[100:103], off nt
	s_cbranch_vccnz .LBB0_1761
	s_ashr_i32 s4, s14, 31
	s_lshr_b32 s4, s4, 25
	s_add_i32 s14, s14, s4
	s_ashr_i32 s4, s14, 7
	v_lshl_or_b32 v100, s4, 6, v134
	v_add_u32_e32 v2, s0, v138
	s_lshl_b32 s4, s4, 12
	v_subrev_u32_e32 v2, s4, v2
	v_mov_b64_e32 v[102:103], s[16:17]
	v_ashrrev_i32_e32 v101, 31, v100
	v_mad_i64_i32 v[102:103], s[4:5], v2, s91, v[102:103]
	v_bfe_u32 v2, v36, 16, 1
	v_lshl_add_u64 v[104:105], v[100:101], 1, v[102:103]
	v_add3_u32 v2, v36, v2, s80
	v_bfe_u32 v100, v32, 16, 1
	v_lshrrev_b32_e32 v2, 16, v2
	v_add3_u32 v100, v32, v100, s80
	v_and_or_b32 v100, v100, s85, v2
	v_bfe_u32 v2, v64, 16, 1
	v_add3_u32 v2, v64, v2, s80
	v_bfe_u32 v101, v60, 16, 1
	v_lshrrev_b32_e32 v2, 16, v2
	v_add3_u32 v101, v60, v101, s80
	v_and_or_b32 v101, v101, s85, v2
	v_bfe_u32 v2, v80, 16, 1
	v_add3_u32 v2, v80, v2, s80
	v_bfe_u32 v102, v56, 16, 1
	v_lshrrev_b32_e32 v2, 16, v2
	v_add3_u32 v102, v56, v102, s80
	v_and_or_b32 v102, v102, s85, v2
	v_bfe_u32 v2, v92, 16, 1
	v_add3_u32 v2, v92, v2, s80
	v_bfe_u32 v103, v96, 16, 1
	v_lshrrev_b32_e32 v2, 16, v2
	v_add3_u32 v103, v96, v103, s80
	v_and_or_b32 v103, v103, s85, v2
	v_bfe_u32 v2, v37, 16, 1
	global_store_dwordx4 v[104:105], v[100:103], off nt
	v_add3_u32 v2, v37, v2, s80
	v_lshrrev_b32_e32 v2, 16, v2
	v_bfe_u32 v100, v33, 16, 1
	v_add3_u32 v100, v33, v100, s80
	v_and_or_b32 v100, v100, s85, v2
	v_bfe_u32 v2, v65, 16, 1
	v_add3_u32 v2, v65, v2, s80
	v_bfe_u32 v101, v61, 16, 1
	v_lshrrev_b32_e32 v2, 16, v2
	v_add3_u32 v101, v61, v101, s80
	v_and_or_b32 v101, v101, s85, v2
	v_bfe_u32 v2, v81, 16, 1
	v_add3_u32 v2, v81, v2, s80
	v_bfe_u32 v102, v57, 16, 1
	v_lshrrev_b32_e32 v2, 16, v2
	v_add3_u32 v102, v57, v102, s80
	v_and_or_b32 v102, v102, s85, v2
	v_bfe_u32 v2, v93, 16, 1
	v_add3_u32 v2, v93, v2, s80
	v_bfe_u32 v103, v97, 16, 1
	v_lshrrev_b32_e32 v2, 16, v2
	v_add3_u32 v103, v97, v103, s80
	v_add_co_u32_e32 v106, vcc, s91, v104
	v_and_or_b32 v103, v103, s85, v2
	s_nop 0
	v_addc_co_u32_e32 v107, vcc, 0, v105, vcc
	v_bfe_u32 v2, v38, 16, 1
	global_store_dwordx4 v[106:107], v[100:103], off nt
	v_add3_u32 v2, v38, v2, s80
	v_lshrrev_b32_e32 v2, 16, v2
	v_bfe_u32 v100, v34, 16, 1
	v_add3_u32 v100, v34, v100, s80
	v_and_or_b32 v100, v100, s85, v2
	v_bfe_u32 v2, v66, 16, 1
	v_add3_u32 v2, v66, v2, s80
	v_bfe_u32 v101, v62, 16, 1
	v_lshrrev_b32_e32 v2, 16, v2
	v_add3_u32 v101, v62, v101, s80
	v_and_or_b32 v101, v101, s85, v2
	v_bfe_u32 v2, v82, 16, 1
	v_add3_u32 v2, v82, v2, s80
	v_bfe_u32 v102, v58, 16, 1
	v_lshrrev_b32_e32 v2, 16, v2
	v_add3_u32 v102, v58, v102, s80
	v_and_or_b32 v102, v102, s85, v2
	v_bfe_u32 v2, v94, 16, 1
	v_add3_u32 v2, v94, v2, s80
	v_bfe_u32 v103, v98, 16, 1
	v_lshrrev_b32_e32 v2, 16, v2
	v_add3_u32 v103, v98, v103, s80
	v_add_co_u32_e32 v106, vcc, s87, v104
	v_and_or_b32 v103, v103, s85, v2
	s_nop 0
	v_addc_co_u32_e32 v107, vcc, 0, v105, vcc
	v_bfe_u32 v2, v39, 16, 1
	global_store_dwordx4 v[106:107], v[100:103], off nt
	v_add3_u32 v2, v39, v2, s80
	v_lshrrev_b32_e32 v2, 16, v2
	v_bfe_u32 v100, v35, 16, 1
	v_add3_u32 v100, v35, v100, s80
	v_and_or_b32 v100, v100, s85, v2
	v_bfe_u32 v2, v67, 16, 1
	v_add3_u32 v2, v67, v2, s80
	v_bfe_u32 v101, v63, 16, 1
	v_lshrrev_b32_e32 v2, 16, v2
	v_add3_u32 v101, v63, v101, s80
	v_and_or_b32 v101, v101, s85, v2
	v_bfe_u32 v2, v83, 16, 1
	v_add3_u32 v2, v83, v2, s80
	v_bfe_u32 v102, v59, 16, 1
	v_lshrrev_b32_e32 v2, 16, v2
	v_add3_u32 v102, v59, v102, s80
	v_and_or_b32 v102, v102, s85, v2
	v_bfe_u32 v2, v95, 16, 1
	v_add3_u32 v2, v95, v2, s80
	v_bfe_u32 v103, v99, 16, 1
	v_lshrrev_b32_e32 v2, 16, v2
	v_add3_u32 v103, v99, v103, s80
	v_add_co_u32_e32 v104, vcc, 0x9000, v104
	v_and_or_b32 v103, v103, s85, v2
	s_nop 0
	v_addc_co_u32_e32 v105, vcc, 0, v105, vcc
	global_store_dwordx4 v[104:105], v[100:103], off nt
	s_andn2_b64 vcc, exec, s[20:21]
	s_cbranch_vccz .LBB0_1762

.LBB0_1762:
	s_ashr_i32 s4, s15, 31
	s_lshr_b32 s4, s4, 25
	s_add_i32 s15, s15, s4
	s_ashr_i32 s4, s15, 7
	v_lshl_or_b32 v100, s4, 6, v134
	v_add_u32_e32 v2, s0, v136
	s_lshl_b32 s4, s4, 12
	v_subrev_u32_e32 v2, s4, v2
	v_mov_b64_e32 v[102:103], s[16:17]
	v_ashrrev_i32_e32 v101, 31, v100
	v_mad_i64_i32 v[102:103], s[4:5], v2, s91, v[102:103]
	v_bfe_u32 v2, v20, 16, 1
	v_lshl_add_u64 v[104:105], v[100:101], 1, v[102:103]
	v_add3_u32 v2, v20, v2, s80
	v_bfe_u32 v100, v12, 16, 1
	v_lshrrev_b32_e32 v2, 16, v2
	v_add3_u32 v100, v12, v100, s80
	v_and_or_b32 v100, v100, s85, v2
	v_bfe_u32 v2, v48, 16, 1
	v_add3_u32 v2, v48, v2, s80
	v_bfe_u32 v101, v44, 16, 1
	v_lshrrev_b32_e32 v2, 16, v2
	v_add3_u32 v101, v44, v101, s80
	v_and_or_b32 v101, v101, s85, v2
	v_bfe_u32 v2, v68, 16, 1
	v_add3_u32 v2, v68, v2, s80
	v_bfe_u32 v102, v40, 16, 1
	v_lshrrev_b32_e32 v2, 16, v2
	v_add3_u32 v102, v40, v102, s80
	v_and_or_b32 v102, v102, s85, v2
	v_bfe_u32 v2, v84, 16, 1
	v_add3_u32 v2, v84, v2, s80
	v_bfe_u32 v103, v88, 16, 1
	v_lshrrev_b32_e32 v2, 16, v2
	v_add3_u32 v103, v88, v103, s80
	v_and_or_b32 v103, v103, s85, v2
	v_bfe_u32 v2, v21, 16, 1
	global_store_dwordx4 v[104:105], v[100:103], off nt
	v_add3_u32 v2, v21, v2, s80
	v_lshrrev_b32_e32 v2, 16, v2
	v_bfe_u32 v100, v13, 16, 1
	v_add3_u32 v100, v13, v100, s80
	v_and_or_b32 v100, v100, s85, v2
	v_bfe_u32 v2, v49, 16, 1
	v_add3_u32 v2, v49, v2, s80
	v_bfe_u32 v101, v45, 16, 1
	v_lshrrev_b32_e32 v2, 16, v2
	v_add3_u32 v101, v45, v101, s80
	v_and_or_b32 v101, v101, s85, v2
	v_bfe_u32 v2, v69, 16, 1
	v_add3_u32 v2, v69, v2, s80
	v_bfe_u32 v102, v41, 16, 1
	v_lshrrev_b32_e32 v2, 16, v2
	v_add3_u32 v102, v41, v102, s80
	v_and_or_b32 v102, v102, s85, v2
	v_bfe_u32 v2, v85, 16, 1
	v_add3_u32 v2, v85, v2, s80
	v_bfe_u32 v103, v89, 16, 1
	v_lshrrev_b32_e32 v2, 16, v2
	v_add3_u32 v103, v89, v103, s80
	v_add_co_u32_e32 v106, vcc, s91, v104
	v_and_or_b32 v103, v103, s85, v2
	s_nop 0
	v_addc_co_u32_e32 v107, vcc, 0, v105, vcc
	v_bfe_u32 v2, v22, 16, 1
	global_store_dwordx4 v[106:107], v[100:103], off nt
	v_add3_u32 v2, v22, v2, s80
	v_lshrrev_b32_e32 v2, 16, v2
	v_bfe_u32 v100, v14, 16, 1
	v_add3_u32 v100, v14, v100, s80
	v_and_or_b32 v100, v100, s85, v2
	v_bfe_u32 v2, v50, 16, 1
	v_add3_u32 v2, v50, v2, s80
	v_bfe_u32 v101, v46, 16, 1
	v_lshrrev_b32_e32 v2, 16, v2
	v_add3_u32 v101, v46, v101, s80
	v_and_or_b32 v101, v101, s85, v2
	v_bfe_u32 v2, v70, 16, 1
	v_add3_u32 v2, v70, v2, s80
	v_bfe_u32 v102, v42, 16, 1
	v_lshrrev_b32_e32 v2, 16, v2
	v_add3_u32 v102, v42, v102, s80
	v_and_or_b32 v102, v102, s85, v2
	v_bfe_u32 v2, v86, 16, 1
	v_add3_u32 v2, v86, v2, s80
	v_bfe_u32 v103, v90, 16, 1
	v_lshrrev_b32_e32 v2, 16, v2
	v_add3_u32 v103, v90, v103, s80
	v_add_co_u32_e32 v106, vcc, s87, v104
	v_and_or_b32 v103, v103, s85, v2
	s_nop 0
	v_addc_co_u32_e32 v107, vcc, 0, v105, vcc
	v_bfe_u32 v2, v23, 16, 1
	global_store_dwordx4 v[106:107], v[100:103], off nt
	v_add3_u32 v2, v23, v2, s80
	v_lshrrev_b32_e32 v2, 16, v2
	v_bfe_u32 v100, v15, 16, 1
	v_add3_u32 v100, v15, v100, s80
	v_and_or_b32 v100, v100, s85, v2
	v_bfe_u32 v2, v51, 16, 1
	v_add3_u32 v2, v51, v2, s80
	v_bfe_u32 v101, v47, 16, 1
	v_lshrrev_b32_e32 v2, 16, v2
	v_add3_u32 v101, v47, v101, s80
	v_and_or_b32 v101, v101, s85, v2
	v_bfe_u32 v2, v71, 16, 1
	v_add3_u32 v2, v71, v2, s80
	v_bfe_u32 v102, v43, 16, 1
	v_lshrrev_b32_e32 v2, 16, v2
	v_add3_u32 v102, v43, v102, s80
	v_and_or_b32 v102, v102, s85, v2
	v_bfe_u32 v2, v87, 16, 1
	v_add3_u32 v2, v87, v2, s80
	v_bfe_u32 v103, v91, 16, 1
	v_lshrrev_b32_e32 v2, 16, v2
	v_add3_u32 v103, v91, v103, s80
	v_add_co_u32_e32 v104, vcc, 0x9000, v104
	v_and_or_b32 v103, v103, s85, v2
	s_nop 0
	v_addc_co_u32_e32 v105, vcc, 0, v105, vcc
	global_store_dwordx4 v[104:105], v[100:103], off nt
	s_andn2_b64 vcc, exec, s[22:23]
	s_cbranch_vccnz .LBB0_1714
.LBB0_1763:
	s_ashr_i32 s4, s25, 31
	s_lshr_b32 s4, s4, 25
	s_add_i32 s25, s25, s4
	s_ashr_i32 s4, s25, 7
	v_lshl_or_b32 v100, s4, 6, v134
	v_add_u32_e32 v2, s0, v137
	s_lshl_b32 s4, s4, 12
	v_subrev_u32_e32 v2, s4, v2
	v_mov_b64_e32 v[102:103], s[16:17]
	v_ashrrev_i32_e32 v101, 31, v100
	v_mad_i64_i32 v[102:103], s[4:5], v2, s91, v[102:103]
	v_bfe_u32 v2, v8, 16, 1
	v_lshl_add_u64 v[104:105], v[100:101], 1, v[102:103]
	v_add3_u32 v2, v8, v2, s80
	v_bfe_u32 v100, v4, 16, 1
	v_lshrrev_b32_e32 v2, 16, v2
	v_add3_u32 v100, v4, v100, s80
	v_and_or_b32 v100, v100, s85, v2
	v_bfe_u32 v2, v28, 16, 1
	v_add3_u32 v2, v28, v2, s80
	v_bfe_u32 v101, v24, 16, 1
	v_lshrrev_b32_e32 v2, 16, v2
	v_add3_u32 v101, v24, v101, s80
	v_and_or_b32 v101, v101, s85, v2
	v_bfe_u32 v2, v52, 16, 1
	v_add3_u32 v2, v52, v2, s80
	v_bfe_u32 v102, v16, 16, 1
	v_lshrrev_b32_e32 v2, 16, v2
	v_add3_u32 v102, v16, v102, s80
	v_and_or_b32 v102, v102, s85, v2
	v_bfe_u32 v2, v72, 16, 1
	v_add3_u32 v2, v72, v2, s80
	v_bfe_u32 v103, v76, 16, 1
	v_lshrrev_b32_e32 v2, 16, v2
	v_add3_u32 v103, v76, v103, s80
	v_and_or_b32 v103, v103, s85, v2
	v_bfe_u32 v2, v9, 16, 1
	global_store_dwordx4 v[104:105], v[100:103], off nt
	v_add3_u32 v2, v9, v2, s80
	v_lshrrev_b32_e32 v2, 16, v2
	v_bfe_u32 v100, v5, 16, 1
	v_add3_u32 v100, v5, v100, s80
	v_and_or_b32 v100, v100, s85, v2
	v_bfe_u32 v2, v29, 16, 1
	v_add3_u32 v2, v29, v2, s80
	v_bfe_u32 v101, v25, 16, 1
	v_lshrrev_b32_e32 v2, 16, v2
	v_add3_u32 v101, v25, v101, s80
	v_and_or_b32 v101, v101, s85, v2
	v_bfe_u32 v2, v53, 16, 1
	v_add3_u32 v2, v53, v2, s80
	v_bfe_u32 v102, v17, 16, 1
	v_lshrrev_b32_e32 v2, 16, v2
	v_add3_u32 v102, v17, v102, s80
	v_and_or_b32 v102, v102, s85, v2
	v_bfe_u32 v2, v73, 16, 1
	v_add3_u32 v2, v73, v2, s80
	v_bfe_u32 v103, v77, 16, 1
	v_lshrrev_b32_e32 v2, 16, v2
	v_add3_u32 v103, v77, v103, s80
	v_add_co_u32_e32 v106, vcc, s91, v104
	v_and_or_b32 v103, v103, s85, v2
	s_nop 0
	v_addc_co_u32_e32 v107, vcc, 0, v105, vcc
	v_bfe_u32 v2, v10, 16, 1
	global_store_dwordx4 v[106:107], v[100:103], off nt
	v_add3_u32 v2, v10, v2, s80
	v_lshrrev_b32_e32 v2, 16, v2
	v_bfe_u32 v100, v6, 16, 1
	v_add3_u32 v100, v6, v100, s80
	v_and_or_b32 v100, v100, s85, v2
	v_bfe_u32 v2, v30, 16, 1
	v_add3_u32 v2, v30, v2, s80
	v_bfe_u32 v101, v26, 16, 1
	v_lshrrev_b32_e32 v2, 16, v2
	v_add3_u32 v101, v26, v101, s80
	v_and_or_b32 v101, v101, s85, v2
	v_bfe_u32 v2, v54, 16, 1
	v_add3_u32 v2, v54, v2, s80
	v_bfe_u32 v102, v18, 16, 1
	v_lshrrev_b32_e32 v2, 16, v2
	v_add3_u32 v102, v18, v102, s80
	v_and_or_b32 v102, v102, s85, v2
	v_bfe_u32 v2, v74, 16, 1
	v_add3_u32 v2, v74, v2, s80
	v_bfe_u32 v103, v78, 16, 1
	v_lshrrev_b32_e32 v2, 16, v2
	v_add3_u32 v103, v78, v103, s80
	v_add_co_u32_e32 v106, vcc, s87, v104
	v_and_or_b32 v103, v103, s85, v2
	s_nop 0
	v_addc_co_u32_e32 v107, vcc, 0, v105, vcc
	v_bfe_u32 v2, v11, 16, 1
	global_store_dwordx4 v[106:107], v[100:103], off nt
	v_add3_u32 v2, v11, v2, s80
	v_lshrrev_b32_e32 v2, 16, v2
	v_bfe_u32 v100, v7, 16, 1
	v_add3_u32 v100, v7, v100, s80
	v_and_or_b32 v100, v100, s85, v2
	v_bfe_u32 v2, v31, 16, 1
	v_add3_u32 v2, v31, v2, s80
	v_bfe_u32 v101, v27, 16, 1
	v_lshrrev_b32_e32 v2, 16, v2
	v_add3_u32 v101, v27, v101, s80
	v_and_or_b32 v101, v101, s85, v2
	v_bfe_u32 v2, v55, 16, 1
	v_add3_u32 v2, v55, v2, s80
	v_bfe_u32 v102, v19, 16, 1
	v_lshrrev_b32_e32 v2, 16, v2
	v_add3_u32 v102, v19, v102, s80
	v_and_or_b32 v102, v102, s85, v2
	v_bfe_u32 v2, v75, 16, 1
	v_add3_u32 v2, v75, v2, s80
	v_bfe_u32 v103, v79, 16, 1
	v_lshrrev_b32_e32 v2, 16, v2
	v_add3_u32 v103, v79, v103, s80
	v_add_co_u32_e32 v104, vcc, 0x9000, v104
	v_and_or_b32 v103, v103, s85, v2
	s_nop 0
	v_addc_co_u32_e32 v105, vcc, 0, v105, vcc
	global_store_dwordx4 v[104:105], v[100:103], off nt
	s_branch .LBB0_1714

.LBB0_1810:
	s_waitcnt vmcnt(1)
	v_bfe_u32 v2, v104, 16, 1
	v_mov_b64_e32 v[140:141], s[16:17]
	v_add3_u32 v2, v104, v2, s80
	s_waitcnt vmcnt(0)
	v_bfe_u32 v104, v100, 16, 1
	v_mad_i64_i32 v[140:141], s[6:7], v139, s91, v[140:141]
	v_lshrrev_b32_e32 v2, 16, v2
	v_add3_u32 v100, v100, v104, s80
	v_lshl_add_u64 v[132:133], v[132:133], 1, v[140:141]
	v_and_or_b32 v140, v100, s85, v2
	v_bfe_u32 v2, v116, 16, 1
	v_add3_u32 v2, v116, v2, s80
	v_bfe_u32 v100, v112, 16, 1
	v_lshrrev_b32_e32 v2, 16, v2
	v_add3_u32 v100, v112, v100, s80
	v_and_or_b32 v141, v100, s85, v2
	v_bfe_u32 v2, v120, 16, 1
	v_add3_u32 v2, v120, v2, s80
	v_bfe_u32 v100, v108, 16, 1
	v_lshrrev_b32_e32 v2, 16, v2
	v_add3_u32 v100, v108, v100, s80
	v_and_or_b32 v142, v100, s85, v2
	v_bfe_u32 v2, v128, 16, 1
	v_add3_u32 v2, v128, v2, s80
	v_bfe_u32 v100, v124, 16, 1
	v_lshrrev_b32_e32 v2, 16, v2
	v_add3_u32 v100, v124, v100, s80
	v_and_or_b32 v143, v100, s85, v2
	v_bfe_u32 v2, v105, 16, 1
	v_add3_u32 v2, v105, v2, s80
	v_bfe_u32 v100, v101, 16, 1
	v_lshrrev_b32_e32 v2, 16, v2
	v_add3_u32 v100, v101, v100, s80
	global_store_dwordx4 v[132:133], v[140:143], off nt
	s_nop 1
	v_and_or_b32 v140, v100, s85, v2
	v_bfe_u32 v2, v117, 16, 1
	v_add3_u32 v2, v117, v2, s80
	v_bfe_u32 v100, v113, 16, 1
	v_lshrrev_b32_e32 v2, 16, v2
	v_add3_u32 v100, v113, v100, s80
	v_and_or_b32 v141, v100, s85, v2
	v_bfe_u32 v2, v121, 16, 1
	v_add3_u32 v2, v121, v2, s80
	v_bfe_u32 v100, v109, 16, 1
	v_lshrrev_b32_e32 v2, 16, v2
	v_add3_u32 v100, v109, v100, s80
	v_and_or_b32 v142, v100, s85, v2
	v_bfe_u32 v2, v129, 16, 1
	v_add3_u32 v2, v129, v2, s80
	v_bfe_u32 v100, v125, 16, 1
	v_lshrrev_b32_e32 v2, 16, v2
	v_add3_u32 v100, v125, v100, s80
	v_and_or_b32 v143, v100, s85, v2
	v_add_co_u32_e32 v100, vcc, s91, v132
	v_bfe_u32 v2, v106, 16, 1
	s_nop 0
	v_addc_co_u32_e32 v101, vcc, 0, v133, vcc
	global_store_dwordx4 v[100:101], v[140:143], off nt
	v_add3_u32 v2, v106, v2, s80
	v_bfe_u32 v100, v102, 16, 1
	v_lshrrev_b32_e32 v2, 16, v2
	v_add3_u32 v100, v102, v100, s80
	v_and_or_b32 v140, v100, s85, v2
	v_bfe_u32 v2, v118, 16, 1
	v_add3_u32 v2, v118, v2, s80
	v_bfe_u32 v100, v114, 16, 1
	v_lshrrev_b32_e32 v2, 16, v2
	v_add3_u32 v100, v114, v100, s80
	v_and_or_b32 v141, v100, s85, v2
	v_bfe_u32 v2, v122, 16, 1
	v_add3_u32 v2, v122, v2, s80
	v_bfe_u32 v100, v110, 16, 1
	v_lshrrev_b32_e32 v2, 16, v2
	v_add3_u32 v100, v110, v100, s80
	v_and_or_b32 v142, v100, s85, v2
	v_bfe_u32 v2, v130, 16, 1
	v_add3_u32 v2, v130, v2, s80
	v_bfe_u32 v100, v126, 16, 1
	v_lshrrev_b32_e32 v2, 16, v2
	v_add3_u32 v100, v126, v100, s80
	v_and_or_b32 v143, v100, s85, v2
	v_add_co_u32_e32 v100, vcc, s87, v132
	v_bfe_u32 v2, v107, 16, 1
	s_nop 0
	v_addc_co_u32_e32 v101, vcc, 0, v133, vcc
	global_store_dwordx4 v[100:101], v[140:143], off nt
	v_add3_u32 v2, v107, v2, s80
	v_bfe_u32 v100, v103, 16, 1
	v_lshrrev_b32_e32 v2, 16, v2
	v_add3_u32 v100, v103, v100, s80
	v_and_or_b32 v100, v100, s85, v2
	v_bfe_u32 v2, v119, 16, 1
	v_add3_u32 v2, v119, v2, s80
	v_bfe_u32 v101, v115, 16, 1
	v_lshrrev_b32_e32 v2, 16, v2
	v_add3_u32 v101, v115, v101, s80
	v_and_or_b32 v101, v101, s85, v2
	v_bfe_u32 v2, v123, 16, 1
	v_add3_u32 v2, v123, v2, s80
	v_bfe_u32 v102, v111, 16, 1
	v_lshrrev_b32_e32 v2, 16, v2
	v_add3_u32 v102, v111, v102, s80
	v_and_or_b32 v102, v102, s85, v2
	v_bfe_u32 v2, v131, 16, 1
	v_add3_u32 v2, v131, v2, s80
	v_bfe_u32 v103, v127, 16, 1
	v_add_co_u32_e32 v104, vcc, 0x9000, v132
	v_lshrrev_b32_e32 v2, 16, v2
	v_add3_u32 v103, v127, v103, s80
	v_addc_co_u32_e32 v105, vcc, 0, v133, vcc
	v_and_or_b32 v103, v103, s85, v2
	s_andn2_b64 vcc, exec, s[18:19]
	global_store_dwordx4 v[104:105], v[100:103], off nt
	s_cbranch_vccnz .LBB0_1813
	s_ashr_i32 s6, s14, 31
	s_lshr_b32 s6, s6, 25
	s_add_i32 s14, s14, s6
	s_ashr_i32 s6, s14, 7
	v_lshl_or_b32 v100, s6, 6, v134
	v_add_u32_e32 v2, s0, v138
	s_lshl_b32 s6, s6, 12
	v_subrev_u32_e32 v2, s6, v2
	v_mov_b64_e32 v[102:103], s[16:17]
	v_ashrrev_i32_e32 v101, 31, v100
	v_mad_i64_i32 v[102:103], s[6:7], v2, s91, v[102:103]
	v_bfe_u32 v2, v36, 16, 1
	v_lshl_add_u64 v[104:105], v[100:101], 1, v[102:103]
	v_add3_u32 v2, v36, v2, s80
	v_bfe_u32 v100, v32, 16, 1
	v_lshrrev_b32_e32 v2, 16, v2
	v_add3_u32 v100, v32, v100, s80
	v_and_or_b32 v100, v100, s85, v2
	v_bfe_u32 v2, v64, 16, 1
	v_add3_u32 v2, v64, v2, s80
	v_bfe_u32 v101, v60, 16, 1
	v_lshrrev_b32_e32 v2, 16, v2
	v_add3_u32 v101, v60, v101, s80
	v_and_or_b32 v101, v101, s85, v2
	v_bfe_u32 v2, v80, 16, 1
	v_add3_u32 v2, v80, v2, s80
	v_bfe_u32 v102, v56, 16, 1
	v_lshrrev_b32_e32 v2, 16, v2
	v_add3_u32 v102, v56, v102, s80
	v_and_or_b32 v102, v102, s85, v2
	v_bfe_u32 v2, v92, 16, 1
	v_add3_u32 v2, v92, v2, s80
	v_bfe_u32 v103, v96, 16, 1
	v_lshrrev_b32_e32 v2, 16, v2
	v_add3_u32 v103, v96, v103, s80
	v_and_or_b32 v103, v103, s85, v2
	v_bfe_u32 v2, v37, 16, 1
	global_store_dwordx4 v[104:105], v[100:103], off nt
	v_add3_u32 v2, v37, v2, s80
	v_lshrrev_b32_e32 v2, 16, v2
	v_bfe_u32 v100, v33, 16, 1
	v_add3_u32 v100, v33, v100, s80
	v_and_or_b32 v100, v100, s85, v2
	v_bfe_u32 v2, v65, 16, 1
	v_add3_u32 v2, v65, v2, s80
	v_bfe_u32 v101, v61, 16, 1
	v_lshrrev_b32_e32 v2, 16, v2
	v_add3_u32 v101, v61, v101, s80
	v_and_or_b32 v101, v101, s85, v2
	v_bfe_u32 v2, v81, 16, 1
	v_add3_u32 v2, v81, v2, s80
	v_bfe_u32 v102, v57, 16, 1
	v_lshrrev_b32_e32 v2, 16, v2
	v_add3_u32 v102, v57, v102, s80
	v_and_or_b32 v102, v102, s85, v2
	v_bfe_u32 v2, v93, 16, 1
	v_add3_u32 v2, v93, v2, s80
	v_bfe_u32 v103, v97, 16, 1
	v_lshrrev_b32_e32 v2, 16, v2
	v_add3_u32 v103, v97, v103, s80
	v_add_co_u32_e32 v106, vcc, s91, v104
	v_and_or_b32 v103, v103, s85, v2
	s_nop 0
	v_addc_co_u32_e32 v107, vcc, 0, v105, vcc
	v_bfe_u32 v2, v38, 16, 1
	global_store_dwordx4 v[106:107], v[100:103], off nt
	v_add3_u32 v2, v38, v2, s80
	v_lshrrev_b32_e32 v2, 16, v2
	v_bfe_u32 v100, v34, 16, 1
	v_add3_u32 v100, v34, v100, s80
	v_and_or_b32 v100, v100, s85, v2
	v_bfe_u32 v2, v66, 16, 1
	v_add3_u32 v2, v66, v2, s80
	v_bfe_u32 v101, v62, 16, 1
	v_lshrrev_b32_e32 v2, 16, v2
	v_add3_u32 v101, v62, v101, s80
	v_and_or_b32 v101, v101, s85, v2
	v_bfe_u32 v2, v82, 16, 1
	v_add3_u32 v2, v82, v2, s80
	v_bfe_u32 v102, v58, 16, 1
	v_lshrrev_b32_e32 v2, 16, v2
	v_add3_u32 v102, v58, v102, s80
	v_and_or_b32 v102, v102, s85, v2
	v_bfe_u32 v2, v94, 16, 1
	v_add3_u32 v2, v94, v2, s80
	v_bfe_u32 v103, v98, 16, 1
	v_lshrrev_b32_e32 v2, 16, v2
	v_add3_u32 v103, v98, v103, s80
	v_add_co_u32_e32 v106, vcc, s87, v104
	v_and_or_b32 v103, v103, s85, v2
	s_nop 0
	v_addc_co_u32_e32 v107, vcc, 0, v105, vcc
	v_bfe_u32 v2, v39, 16, 1
	global_store_dwordx4 v[106:107], v[100:103], off nt
	v_add3_u32 v2, v39, v2, s80
	v_lshrrev_b32_e32 v2, 16, v2
	v_bfe_u32 v100, v35, 16, 1
	v_add3_u32 v100, v35, v100, s80
	v_and_or_b32 v100, v100, s85, v2
	v_bfe_u32 v2, v67, 16, 1
	v_add3_u32 v2, v67, v2, s80
	v_bfe_u32 v101, v63, 16, 1
	v_lshrrev_b32_e32 v2, 16, v2
	v_add3_u32 v101, v63, v101, s80
	v_and_or_b32 v101, v101, s85, v2
	v_bfe_u32 v2, v83, 16, 1
	v_add3_u32 v2, v83, v2, s80
	v_bfe_u32 v102, v59, 16, 1
	v_lshrrev_b32_e32 v2, 16, v2
	v_add3_u32 v102, v59, v102, s80
	v_and_or_b32 v102, v102, s85, v2
	v_bfe_u32 v2, v95, 16, 1
	v_add3_u32 v2, v95, v2, s80
	v_bfe_u32 v103, v99, 16, 1
	v_lshrrev_b32_e32 v2, 16, v2
	v_add3_u32 v103, v99, v103, s80
	v_add_co_u32_e32 v104, vcc, 0x9000, v104
	v_and_or_b32 v103, v103, s85, v2
	s_nop 0
	v_addc_co_u32_e32 v105, vcc, 0, v105, vcc
	global_store_dwordx4 v[104:105], v[100:103], off nt
	s_andn2_b64 vcc, exec, s[20:21]
	s_cbranch_vccz .LBB0_1814

.LBB0_1814:
	s_ashr_i32 s6, s15, 31
	s_lshr_b32 s6, s6, 25
	s_add_i32 s15, s15, s6
	s_ashr_i32 s6, s15, 7
	v_lshl_or_b32 v100, s6, 6, v134
	v_add_u32_e32 v2, s0, v136
	s_lshl_b32 s6, s6, 12
	v_subrev_u32_e32 v2, s6, v2
	v_mov_b64_e32 v[102:103], s[16:17]
	v_ashrrev_i32_e32 v101, 31, v100
	v_mad_i64_i32 v[102:103], s[6:7], v2, s91, v[102:103]
	v_bfe_u32 v2, v20, 16, 1
	v_lshl_add_u64 v[104:105], v[100:101], 1, v[102:103]
	v_add3_u32 v2, v20, v2, s80
	v_bfe_u32 v100, v12, 16, 1
	v_lshrrev_b32_e32 v2, 16, v2
	v_add3_u32 v100, v12, v100, s80
	v_and_or_b32 v100, v100, s85, v2
	v_bfe_u32 v2, v48, 16, 1
	v_add3_u32 v2, v48, v2, s80
	v_bfe_u32 v101, v44, 16, 1
	v_lshrrev_b32_e32 v2, 16, v2
	v_add3_u32 v101, v44, v101, s80
	v_and_or_b32 v101, v101, s85, v2
	v_bfe_u32 v2, v68, 16, 1
	v_add3_u32 v2, v68, v2, s80
	v_bfe_u32 v102, v40, 16, 1
	v_lshrrev_b32_e32 v2, 16, v2
	v_add3_u32 v102, v40, v102, s80
	v_and_or_b32 v102, v102, s85, v2
	v_bfe_u32 v2, v84, 16, 1
	v_add3_u32 v2, v84, v2, s80
	v_bfe_u32 v103, v88, 16, 1
	v_lshrrev_b32_e32 v2, 16, v2
	v_add3_u32 v103, v88, v103, s80
	v_and_or_b32 v103, v103, s85, v2
	v_bfe_u32 v2, v21, 16, 1
	global_store_dwordx4 v[104:105], v[100:103], off nt
	v_add3_u32 v2, v21, v2, s80
	v_lshrrev_b32_e32 v2, 16, v2
	v_bfe_u32 v100, v13, 16, 1
	v_add3_u32 v100, v13, v100, s80
	v_and_or_b32 v100, v100, s85, v2
	v_bfe_u32 v2, v49, 16, 1
	v_add3_u32 v2, v49, v2, s80
	v_bfe_u32 v101, v45, 16, 1
	v_lshrrev_b32_e32 v2, 16, v2
	v_add3_u32 v101, v45, v101, s80
	v_and_or_b32 v101, v101, s85, v2
	v_bfe_u32 v2, v69, 16, 1
	v_add3_u32 v2, v69, v2, s80
	v_bfe_u32 v102, v41, 16, 1
	v_lshrrev_b32_e32 v2, 16, v2
	v_add3_u32 v102, v41, v102, s80
	v_and_or_b32 v102, v102, s85, v2
	v_bfe_u32 v2, v85, 16, 1
	v_add3_u32 v2, v85, v2, s80
	v_bfe_u32 v103, v89, 16, 1
	v_lshrrev_b32_e32 v2, 16, v2
	v_add3_u32 v103, v89, v103, s80
	v_add_co_u32_e32 v106, vcc, s91, v104
	v_and_or_b32 v103, v103, s85, v2
	s_nop 0
	v_addc_co_u32_e32 v107, vcc, 0, v105, vcc
	v_bfe_u32 v2, v22, 16, 1
	global_store_dwordx4 v[106:107], v[100:103], off nt
	v_add3_u32 v2, v22, v2, s80
	v_lshrrev_b32_e32 v2, 16, v2
	v_bfe_u32 v100, v14, 16, 1
	v_add3_u32 v100, v14, v100, s80
	v_and_or_b32 v100, v100, s85, v2
	v_bfe_u32 v2, v50, 16, 1
	v_add3_u32 v2, v50, v2, s80
	v_bfe_u32 v101, v46, 16, 1
	v_lshrrev_b32_e32 v2, 16, v2
	v_add3_u32 v101, v46, v101, s80
	v_and_or_b32 v101, v101, s85, v2
	v_bfe_u32 v2, v70, 16, 1
	v_add3_u32 v2, v70, v2, s80
	v_bfe_u32 v102, v42, 16, 1
	v_lshrrev_b32_e32 v2, 16, v2
	v_add3_u32 v102, v42, v102, s80
	v_and_or_b32 v102, v102, s85, v2
	v_bfe_u32 v2, v86, 16, 1
	v_add3_u32 v2, v86, v2, s80
	v_bfe_u32 v103, v90, 16, 1
	v_lshrrev_b32_e32 v2, 16, v2
	v_add3_u32 v103, v90, v103, s80
	v_add_co_u32_e32 v106, vcc, s87, v104
	v_and_or_b32 v103, v103, s85, v2
	s_nop 0
	v_addc_co_u32_e32 v107, vcc, 0, v105, vcc
	v_bfe_u32 v2, v23, 16, 1
	global_store_dwordx4 v[106:107], v[100:103], off nt
	v_add3_u32 v2, v23, v2, s80
	v_lshrrev_b32_e32 v2, 16, v2
	v_bfe_u32 v100, v15, 16, 1
	v_add3_u32 v100, v15, v100, s80
	v_and_or_b32 v100, v100, s85, v2
	v_bfe_u32 v2, v51, 16, 1
	v_add3_u32 v2, v51, v2, s80
	v_bfe_u32 v101, v47, 16, 1
	v_lshrrev_b32_e32 v2, 16, v2
	v_add3_u32 v101, v47, v101, s80
	v_and_or_b32 v101, v101, s85, v2
	v_bfe_u32 v2, v71, 16, 1
	v_add3_u32 v2, v71, v2, s80
	v_bfe_u32 v102, v43, 16, 1
	v_lshrrev_b32_e32 v2, 16, v2
	v_add3_u32 v102, v43, v102, s80
	v_and_or_b32 v102, v102, s85, v2
	v_bfe_u32 v2, v87, 16, 1
	v_add3_u32 v2, v87, v2, s80
	v_bfe_u32 v103, v91, 16, 1
	v_lshrrev_b32_e32 v2, 16, v2
	v_add3_u32 v103, v91, v103, s80
	v_add_co_u32_e32 v104, vcc, 0x9000, v104
	v_and_or_b32 v103, v103, s85, v2
	s_nop 0
	v_addc_co_u32_e32 v105, vcc, 0, v105, vcc
	global_store_dwordx4 v[104:105], v[100:103], off nt
	s_andn2_b64 vcc, exec, s[22:23]
	s_cbranch_vccnz .LBB0_1766
.LBB0_1815:
	s_ashr_i32 s6, s25, 31
	s_lshr_b32 s6, s6, 25
	s_add_i32 s25, s25, s6
	s_ashr_i32 s6, s25, 7
	v_lshl_or_b32 v100, s6, 6, v134
	v_add_u32_e32 v2, s0, v137
	s_lshl_b32 s6, s6, 12
	v_subrev_u32_e32 v2, s6, v2
	v_mov_b64_e32 v[102:103], s[16:17]
	v_ashrrev_i32_e32 v101, 31, v100
	v_mad_i64_i32 v[102:103], s[6:7], v2, s91, v[102:103]
	v_bfe_u32 v2, v8, 16, 1
	v_lshl_add_u64 v[104:105], v[100:101], 1, v[102:103]
	v_add3_u32 v2, v8, v2, s80
	v_bfe_u32 v100, v4, 16, 1
	v_lshrrev_b32_e32 v2, 16, v2
	v_add3_u32 v100, v4, v100, s80
	v_and_or_b32 v100, v100, s85, v2
	v_bfe_u32 v2, v28, 16, 1
	v_add3_u32 v2, v28, v2, s80
	v_bfe_u32 v101, v24, 16, 1
	v_lshrrev_b32_e32 v2, 16, v2
	v_add3_u32 v101, v24, v101, s80
	v_and_or_b32 v101, v101, s85, v2
	v_bfe_u32 v2, v52, 16, 1
	v_add3_u32 v2, v52, v2, s80
	v_bfe_u32 v102, v16, 16, 1
	v_lshrrev_b32_e32 v2, 16, v2
	v_add3_u32 v102, v16, v102, s80
	v_and_or_b32 v102, v102, s85, v2
	v_bfe_u32 v2, v72, 16, 1
	v_add3_u32 v2, v72, v2, s80
	v_bfe_u32 v103, v76, 16, 1
	v_lshrrev_b32_e32 v2, 16, v2
	v_add3_u32 v103, v76, v103, s80
	v_and_or_b32 v103, v103, s85, v2
	v_bfe_u32 v2, v9, 16, 1
	global_store_dwordx4 v[104:105], v[100:103], off nt
	v_add3_u32 v2, v9, v2, s80
	v_lshrrev_b32_e32 v2, 16, v2
	v_bfe_u32 v100, v5, 16, 1
	v_add3_u32 v100, v5, v100, s80
	v_and_or_b32 v100, v100, s85, v2
	v_bfe_u32 v2, v29, 16, 1
	v_add3_u32 v2, v29, v2, s80
	v_bfe_u32 v101, v25, 16, 1
	v_lshrrev_b32_e32 v2, 16, v2
	v_add3_u32 v101, v25, v101, s80
	v_and_or_b32 v101, v101, s85, v2
	v_bfe_u32 v2, v53, 16, 1
	v_add3_u32 v2, v53, v2, s80
	v_bfe_u32 v102, v17, 16, 1
	v_lshrrev_b32_e32 v2, 16, v2
	v_add3_u32 v102, v17, v102, s80
	v_and_or_b32 v102, v102, s85, v2
	v_bfe_u32 v2, v73, 16, 1
	v_add3_u32 v2, v73, v2, s80
	v_bfe_u32 v103, v77, 16, 1
	v_lshrrev_b32_e32 v2, 16, v2
	v_add3_u32 v103, v77, v103, s80
	v_add_co_u32_e32 v106, vcc, s91, v104
	v_and_or_b32 v103, v103, s85, v2
	s_nop 0
	v_addc_co_u32_e32 v107, vcc, 0, v105, vcc
	v_bfe_u32 v2, v10, 16, 1
	global_store_dwordx4 v[106:107], v[100:103], off nt
	v_add3_u32 v2, v10, v2, s80
	v_lshrrev_b32_e32 v2, 16, v2
	v_bfe_u32 v100, v6, 16, 1
	v_add3_u32 v100, v6, v100, s80
	v_and_or_b32 v100, v100, s85, v2
	v_bfe_u32 v2, v30, 16, 1
	v_add3_u32 v2, v30, v2, s80
	v_bfe_u32 v101, v26, 16, 1
	v_lshrrev_b32_e32 v2, 16, v2
	v_add3_u32 v101, v26, v101, s80
	v_and_or_b32 v101, v101, s85, v2
	v_bfe_u32 v2, v54, 16, 1
	v_add3_u32 v2, v54, v2, s80
	v_bfe_u32 v102, v18, 16, 1
	v_lshrrev_b32_e32 v2, 16, v2
	v_add3_u32 v102, v18, v102, s80
	v_and_or_b32 v102, v102, s85, v2
	v_bfe_u32 v2, v74, 16, 1
	v_add3_u32 v2, v74, v2, s80
	v_bfe_u32 v103, v78, 16, 1
	v_lshrrev_b32_e32 v2, 16, v2
	v_add3_u32 v103, v78, v103, s80
	v_add_co_u32_e32 v106, vcc, s87, v104
	v_and_or_b32 v103, v103, s85, v2
	s_nop 0
	v_addc_co_u32_e32 v107, vcc, 0, v105, vcc
	v_bfe_u32 v2, v11, 16, 1
	global_store_dwordx4 v[106:107], v[100:103], off nt
	v_add3_u32 v2, v11, v2, s80
	v_lshrrev_b32_e32 v2, 16, v2
	v_bfe_u32 v100, v7, 16, 1
	v_add3_u32 v100, v7, v100, s80
	v_and_or_b32 v100, v100, s85, v2
	v_bfe_u32 v2, v31, 16, 1
	v_add3_u32 v2, v31, v2, s80
	v_bfe_u32 v101, v27, 16, 1
	v_lshrrev_b32_e32 v2, 16, v2
	v_add3_u32 v101, v27, v101, s80
	v_and_or_b32 v101, v101, s85, v2
	v_bfe_u32 v2, v55, 16, 1
	v_add3_u32 v2, v55, v2, s80
	v_bfe_u32 v102, v19, 16, 1
	v_lshrrev_b32_e32 v2, 16, v2
	v_add3_u32 v102, v19, v102, s80
	v_and_or_b32 v102, v102, s85, v2
	v_bfe_u32 v2, v75, 16, 1
	v_add3_u32 v2, v75, v2, s80
	v_bfe_u32 v103, v79, 16, 1
	v_lshrrev_b32_e32 v2, 16, v2
	v_add3_u32 v103, v79, v103, s80
	v_add_co_u32_e32 v104, vcc, 0x9000, v104
	v_and_or_b32 v103, v103, s85, v2
	s_nop 0
	v_addc_co_u32_e32 v105, vcc, 0, v105, vcc
	global_store_dwordx4 v[104:105], v[100:103], off nt
	s_branch .LBB0_1766

.LBB0_1862:
	s_waitcnt vmcnt(1)
	v_bfe_u32 v2, v104, 16, 1
	v_mov_b64_e32 v[140:141], s[12:13]
	v_add3_u32 v2, v104, v2, s80
	s_waitcnt vmcnt(0)
	v_bfe_u32 v104, v100, 16, 1
	v_mad_i64_i32 v[140:141], s[4:5], v139, s91, v[140:141]
	v_lshrrev_b32_e32 v2, 16, v2
	v_add3_u32 v100, v100, v104, s80
	v_lshl_add_u64 v[132:133], v[132:133], 1, v[140:141]
	v_and_or_b32 v140, v100, s85, v2
	v_bfe_u32 v2, v116, 16, 1
	v_add3_u32 v2, v116, v2, s80
	v_bfe_u32 v100, v112, 16, 1
	v_lshrrev_b32_e32 v2, 16, v2
	v_add3_u32 v100, v112, v100, s80
	v_and_or_b32 v141, v100, s85, v2
	v_bfe_u32 v2, v120, 16, 1
	v_add3_u32 v2, v120, v2, s80
	v_bfe_u32 v100, v108, 16, 1
	v_lshrrev_b32_e32 v2, 16, v2
	v_add3_u32 v100, v108, v100, s80
	v_and_or_b32 v142, v100, s85, v2
	v_bfe_u32 v2, v128, 16, 1
	v_add3_u32 v2, v128, v2, s80
	v_bfe_u32 v100, v124, 16, 1
	v_lshrrev_b32_e32 v2, 16, v2
	v_add3_u32 v100, v124, v100, s80
	v_and_or_b32 v143, v100, s85, v2
	v_bfe_u32 v2, v105, 16, 1
	v_add3_u32 v2, v105, v2, s80
	v_bfe_u32 v100, v101, 16, 1
	v_lshrrev_b32_e32 v2, 16, v2
	v_add3_u32 v100, v101, v100, s80
	global_store_dwordx4 v[132:133], v[140:143], off nt
	s_nop 1
	v_and_or_b32 v140, v100, s85, v2
	v_bfe_u32 v2, v117, 16, 1
	v_add3_u32 v2, v117, v2, s80
	v_bfe_u32 v100, v113, 16, 1
	v_lshrrev_b32_e32 v2, 16, v2
	v_add3_u32 v100, v113, v100, s80
	v_and_or_b32 v141, v100, s85, v2
	v_bfe_u32 v2, v121, 16, 1
	v_add3_u32 v2, v121, v2, s80
	v_bfe_u32 v100, v109, 16, 1
	v_lshrrev_b32_e32 v2, 16, v2
	v_add3_u32 v100, v109, v100, s80
	v_and_or_b32 v142, v100, s85, v2
	v_bfe_u32 v2, v129, 16, 1
	v_add3_u32 v2, v129, v2, s80
	v_bfe_u32 v100, v125, 16, 1
	v_lshrrev_b32_e32 v2, 16, v2
	v_add3_u32 v100, v125, v100, s80
	v_and_or_b32 v143, v100, s85, v2
	v_add_co_u32_e32 v100, vcc, s91, v132
	v_bfe_u32 v2, v106, 16, 1
	s_nop 0
	v_addc_co_u32_e32 v101, vcc, 0, v133, vcc
	global_store_dwordx4 v[100:101], v[140:143], off nt
	v_add3_u32 v2, v106, v2, s80
	v_bfe_u32 v100, v102, 16, 1
	v_lshrrev_b32_e32 v2, 16, v2
	v_add3_u32 v100, v102, v100, s80
	v_and_or_b32 v140, v100, s85, v2
	v_bfe_u32 v2, v118, 16, 1
	v_add3_u32 v2, v118, v2, s80
	v_bfe_u32 v100, v114, 16, 1
	v_lshrrev_b32_e32 v2, 16, v2
	v_add3_u32 v100, v114, v100, s80
	v_and_or_b32 v141, v100, s85, v2
	v_bfe_u32 v2, v122, 16, 1
	v_add3_u32 v2, v122, v2, s80
	v_bfe_u32 v100, v110, 16, 1
	v_lshrrev_b32_e32 v2, 16, v2
	v_add3_u32 v100, v110, v100, s80
	v_and_or_b32 v142, v100, s85, v2
	v_bfe_u32 v2, v130, 16, 1
	v_add3_u32 v2, v130, v2, s80
	v_bfe_u32 v100, v126, 16, 1
	v_lshrrev_b32_e32 v2, 16, v2
	v_add3_u32 v100, v126, v100, s80
	v_and_or_b32 v143, v100, s85, v2
	v_add_co_u32_e32 v100, vcc, s87, v132
	v_bfe_u32 v2, v107, 16, 1
	s_nop 0
	v_addc_co_u32_e32 v101, vcc, 0, v133, vcc
	global_store_dwordx4 v[100:101], v[140:143], off nt
	v_add3_u32 v2, v107, v2, s80
	v_bfe_u32 v100, v103, 16, 1
	v_lshrrev_b32_e32 v2, 16, v2
	v_add3_u32 v100, v103, v100, s80
	v_and_or_b32 v100, v100, s85, v2
	v_bfe_u32 v2, v119, 16, 1
	v_add3_u32 v2, v119, v2, s80
	v_bfe_u32 v101, v115, 16, 1
	v_lshrrev_b32_e32 v2, 16, v2
	v_add3_u32 v101, v115, v101, s80
	v_and_or_b32 v101, v101, s85, v2
	v_bfe_u32 v2, v123, 16, 1
	v_add3_u32 v2, v123, v2, s80
	v_bfe_u32 v102, v111, 16, 1
	v_lshrrev_b32_e32 v2, 16, v2
	v_add3_u32 v102, v111, v102, s80
	v_and_or_b32 v102, v102, s85, v2
	v_bfe_u32 v2, v131, 16, 1
	v_add3_u32 v2, v131, v2, s80
	v_bfe_u32 v103, v127, 16, 1
	v_add_co_u32_e32 v104, vcc, 0x9000, v132
	v_lshrrev_b32_e32 v2, 16, v2
	v_add3_u32 v103, v127, v103, s80
	v_addc_co_u32_e32 v105, vcc, 0, v133, vcc
	v_and_or_b32 v103, v103, s85, v2
	s_andn2_b64 vcc, exec, s[16:17]
	global_store_dwordx4 v[104:105], v[100:103], off nt
	s_cbranch_vccnz .LBB0_1865
	s_ashr_i32 s4, s14, 31
	s_lshr_b32 s4, s4, 25
	s_add_i32 s14, s14, s4
	s_ashr_i32 s4, s14, 7
	v_lshl_or_b32 v100, s4, 6, v134
	v_add_u32_e32 v2, s0, v138
	s_lshl_b32 s4, s4, 12
	v_subrev_u32_e32 v2, s4, v2
	v_mov_b64_e32 v[102:103], s[12:13]
	v_ashrrev_i32_e32 v101, 31, v100
	v_mad_i64_i32 v[102:103], s[4:5], v2, s91, v[102:103]
	v_bfe_u32 v2, v36, 16, 1
	v_lshl_add_u64 v[104:105], v[100:101], 1, v[102:103]
	v_add3_u32 v2, v36, v2, s80
	v_bfe_u32 v100, v32, 16, 1
	v_lshrrev_b32_e32 v2, 16, v2
	v_add3_u32 v100, v32, v100, s80
	v_and_or_b32 v100, v100, s85, v2
	v_bfe_u32 v2, v64, 16, 1
	v_add3_u32 v2, v64, v2, s80
	v_bfe_u32 v101, v60, 16, 1
	v_lshrrev_b32_e32 v2, 16, v2
	v_add3_u32 v101, v60, v101, s80
	v_and_or_b32 v101, v101, s85, v2
	v_bfe_u32 v2, v80, 16, 1
	v_add3_u32 v2, v80, v2, s80
	v_bfe_u32 v102, v56, 16, 1
	v_lshrrev_b32_e32 v2, 16, v2
	v_add3_u32 v102, v56, v102, s80
	v_and_or_b32 v102, v102, s85, v2
	v_bfe_u32 v2, v92, 16, 1
	v_add3_u32 v2, v92, v2, s80
	v_bfe_u32 v103, v96, 16, 1
	v_lshrrev_b32_e32 v2, 16, v2
	v_add3_u32 v103, v96, v103, s80
	v_and_or_b32 v103, v103, s85, v2
	v_bfe_u32 v2, v37, 16, 1
	global_store_dwordx4 v[104:105], v[100:103], off nt
	v_add3_u32 v2, v37, v2, s80
	v_lshrrev_b32_e32 v2, 16, v2
	v_bfe_u32 v100, v33, 16, 1
	v_add3_u32 v100, v33, v100, s80
	v_and_or_b32 v100, v100, s85, v2
	v_bfe_u32 v2, v65, 16, 1
	v_add3_u32 v2, v65, v2, s80
	v_bfe_u32 v101, v61, 16, 1
	v_lshrrev_b32_e32 v2, 16, v2
	v_add3_u32 v101, v61, v101, s80
	v_and_or_b32 v101, v101, s85, v2
	v_bfe_u32 v2, v81, 16, 1
	v_add3_u32 v2, v81, v2, s80
	v_bfe_u32 v102, v57, 16, 1
	v_lshrrev_b32_e32 v2, 16, v2
	v_add3_u32 v102, v57, v102, s80
	v_and_or_b32 v102, v102, s85, v2
	v_bfe_u32 v2, v93, 16, 1
	v_add3_u32 v2, v93, v2, s80
	v_bfe_u32 v103, v97, 16, 1
	v_lshrrev_b32_e32 v2, 16, v2
	v_add3_u32 v103, v97, v103, s80
	v_add_co_u32_e32 v106, vcc, s91, v104
	v_and_or_b32 v103, v103, s85, v2
	s_nop 0
	v_addc_co_u32_e32 v107, vcc, 0, v105, vcc
	v_bfe_u32 v2, v38, 16, 1
	global_store_dwordx4 v[106:107], v[100:103], off nt
	v_add3_u32 v2, v38, v2, s80
	v_lshrrev_b32_e32 v2, 16, v2
	v_bfe_u32 v100, v34, 16, 1
	v_add3_u32 v100, v34, v100, s80
	v_and_or_b32 v100, v100, s85, v2
	v_bfe_u32 v2, v66, 16, 1
	v_add3_u32 v2, v66, v2, s80
	v_bfe_u32 v101, v62, 16, 1
	v_lshrrev_b32_e32 v2, 16, v2
	v_add3_u32 v101, v62, v101, s80
	v_and_or_b32 v101, v101, s85, v2
	v_bfe_u32 v2, v82, 16, 1
	v_add3_u32 v2, v82, v2, s80
	v_bfe_u32 v102, v58, 16, 1
	v_lshrrev_b32_e32 v2, 16, v2
	v_add3_u32 v102, v58, v102, s80
	v_and_or_b32 v102, v102, s85, v2
	v_bfe_u32 v2, v94, 16, 1
	v_add3_u32 v2, v94, v2, s80
	v_bfe_u32 v103, v98, 16, 1
	v_lshrrev_b32_e32 v2, 16, v2
	v_add3_u32 v103, v98, v103, s80
	v_add_co_u32_e32 v106, vcc, s87, v104
	v_and_or_b32 v103, v103, s85, v2
	s_nop 0
	v_addc_co_u32_e32 v107, vcc, 0, v105, vcc
	v_bfe_u32 v2, v39, 16, 1
	global_store_dwordx4 v[106:107], v[100:103], off nt
	v_add3_u32 v2, v39, v2, s80
	v_lshrrev_b32_e32 v2, 16, v2
	v_bfe_u32 v100, v35, 16, 1
	v_add3_u32 v100, v35, v100, s80
	v_and_or_b32 v100, v100, s85, v2
	v_bfe_u32 v2, v67, 16, 1
	v_add3_u32 v2, v67, v2, s80
	v_bfe_u32 v101, v63, 16, 1
	v_lshrrev_b32_e32 v2, 16, v2
	v_add3_u32 v101, v63, v101, s80
	v_and_or_b32 v101, v101, s85, v2
	v_bfe_u32 v2, v83, 16, 1
	v_add3_u32 v2, v83, v2, s80
	v_bfe_u32 v102, v59, 16, 1
	v_lshrrev_b32_e32 v2, 16, v2
	v_add3_u32 v102, v59, v102, s80
	v_and_or_b32 v102, v102, s85, v2
	v_bfe_u32 v2, v95, 16, 1
	v_add3_u32 v2, v95, v2, s80
	v_bfe_u32 v103, v99, 16, 1
	v_lshrrev_b32_e32 v2, 16, v2
	v_add3_u32 v103, v99, v103, s80
	v_add_co_u32_e32 v104, vcc, 0x9000, v104
	v_and_or_b32 v103, v103, s85, v2
	s_nop 0
	v_addc_co_u32_e32 v105, vcc, 0, v105, vcc
	global_store_dwordx4 v[104:105], v[100:103], off nt
	s_andn2_b64 vcc, exec, s[18:19]
	s_cbranch_vccz .LBB0_1866

.LBB0_1866:
	s_ashr_i32 s4, s15, 31
	s_lshr_b32 s4, s4, 25
	s_add_i32 s15, s15, s4
	s_ashr_i32 s4, s15, 7
	v_lshl_or_b32 v100, s4, 6, v134
	v_add_u32_e32 v2, s0, v136
	s_lshl_b32 s4, s4, 12
	v_subrev_u32_e32 v2, s4, v2
	v_mov_b64_e32 v[102:103], s[12:13]
	v_ashrrev_i32_e32 v101, 31, v100
	v_mad_i64_i32 v[102:103], s[4:5], v2, s91, v[102:103]
	v_bfe_u32 v2, v20, 16, 1
	v_lshl_add_u64 v[104:105], v[100:101], 1, v[102:103]
	v_add3_u32 v2, v20, v2, s80
	v_bfe_u32 v100, v12, 16, 1
	v_lshrrev_b32_e32 v2, 16, v2
	v_add3_u32 v100, v12, v100, s80
	v_and_or_b32 v100, v100, s85, v2
	v_bfe_u32 v2, v48, 16, 1
	v_add3_u32 v2, v48, v2, s80
	v_bfe_u32 v101, v44, 16, 1
	v_lshrrev_b32_e32 v2, 16, v2
	v_add3_u32 v101, v44, v101, s80
	v_and_or_b32 v101, v101, s85, v2
	v_bfe_u32 v2, v68, 16, 1
	v_add3_u32 v2, v68, v2, s80
	v_bfe_u32 v102, v40, 16, 1
	v_lshrrev_b32_e32 v2, 16, v2
	v_add3_u32 v102, v40, v102, s80
	v_and_or_b32 v102, v102, s85, v2
	v_bfe_u32 v2, v84, 16, 1
	v_add3_u32 v2, v84, v2, s80
	v_bfe_u32 v103, v88, 16, 1
	v_lshrrev_b32_e32 v2, 16, v2
	v_add3_u32 v103, v88, v103, s80
	v_and_or_b32 v103, v103, s85, v2
	v_bfe_u32 v2, v21, 16, 1
	global_store_dwordx4 v[104:105], v[100:103], off nt
	v_add3_u32 v2, v21, v2, s80
	v_lshrrev_b32_e32 v2, 16, v2
	v_bfe_u32 v100, v13, 16, 1
	v_add3_u32 v100, v13, v100, s80
	v_and_or_b32 v100, v100, s85, v2
	v_bfe_u32 v2, v49, 16, 1
	v_add3_u32 v2, v49, v2, s80
	v_bfe_u32 v101, v45, 16, 1
	v_lshrrev_b32_e32 v2, 16, v2
	v_add3_u32 v101, v45, v101, s80
	v_and_or_b32 v101, v101, s85, v2
	v_bfe_u32 v2, v69, 16, 1
	v_add3_u32 v2, v69, v2, s80
	v_bfe_u32 v102, v41, 16, 1
	v_lshrrev_b32_e32 v2, 16, v2
	v_add3_u32 v102, v41, v102, s80
	v_and_or_b32 v102, v102, s85, v2
	v_bfe_u32 v2, v85, 16, 1
	v_add3_u32 v2, v85, v2, s80
	v_bfe_u32 v103, v89, 16, 1
	v_lshrrev_b32_e32 v2, 16, v2
	v_add3_u32 v103, v89, v103, s80
	v_add_co_u32_e32 v106, vcc, s91, v104
	v_and_or_b32 v103, v103, s85, v2
	s_nop 0
	v_addc_co_u32_e32 v107, vcc, 0, v105, vcc
	v_bfe_u32 v2, v22, 16, 1
	global_store_dwordx4 v[106:107], v[100:103], off nt
	v_add3_u32 v2, v22, v2, s80
	v_lshrrev_b32_e32 v2, 16, v2
	v_bfe_u32 v100, v14, 16, 1
	v_add3_u32 v100, v14, v100, s80
	v_and_or_b32 v100, v100, s85, v2
	v_bfe_u32 v2, v50, 16, 1
	v_add3_u32 v2, v50, v2, s80
	v_bfe_u32 v101, v46, 16, 1
	v_lshrrev_b32_e32 v2, 16, v2
	v_add3_u32 v101, v46, v101, s80
	v_and_or_b32 v101, v101, s85, v2
	v_bfe_u32 v2, v70, 16, 1
	v_add3_u32 v2, v70, v2, s80
	v_bfe_u32 v102, v42, 16, 1
	v_lshrrev_b32_e32 v2, 16, v2
	v_add3_u32 v102, v42, v102, s80
	v_and_or_b32 v102, v102, s85, v2
	v_bfe_u32 v2, v86, 16, 1
	v_add3_u32 v2, v86, v2, s80
	v_bfe_u32 v103, v90, 16, 1
	v_lshrrev_b32_e32 v2, 16, v2
	v_add3_u32 v103, v90, v103, s80
	v_add_co_u32_e32 v106, vcc, s87, v104
	v_and_or_b32 v103, v103, s85, v2
	s_nop 0
	v_addc_co_u32_e32 v107, vcc, 0, v105, vcc
	v_bfe_u32 v2, v23, 16, 1
	global_store_dwordx4 v[106:107], v[100:103], off nt
	v_add3_u32 v2, v23, v2, s80
	v_lshrrev_b32_e32 v2, 16, v2
	v_bfe_u32 v100, v15, 16, 1
	v_add3_u32 v100, v15, v100, s80
	v_and_or_b32 v100, v100, s85, v2
	v_bfe_u32 v2, v51, 16, 1
	v_add3_u32 v2, v51, v2, s80
	v_bfe_u32 v101, v47, 16, 1
	v_lshrrev_b32_e32 v2, 16, v2
	v_add3_u32 v101, v47, v101, s80
	v_and_or_b32 v101, v101, s85, v2
	v_bfe_u32 v2, v71, 16, 1
	v_add3_u32 v2, v71, v2, s80
	v_bfe_u32 v102, v43, 16, 1
	v_lshrrev_b32_e32 v2, 16, v2
	v_add3_u32 v102, v43, v102, s80
	v_and_or_b32 v102, v102, s85, v2
	v_bfe_u32 v2, v87, 16, 1
	v_add3_u32 v2, v87, v2, s80
	v_bfe_u32 v103, v91, 16, 1
	v_lshrrev_b32_e32 v2, 16, v2
	v_add3_u32 v103, v91, v103, s80
	v_add_co_u32_e32 v104, vcc, 0x9000, v104
	v_and_or_b32 v103, v103, s85, v2
	s_nop 0
	v_addc_co_u32_e32 v105, vcc, 0, v105, vcc
	global_store_dwordx4 v[104:105], v[100:103], off nt
	s_andn2_b64 vcc, exec, s[20:21]
	s_cbranch_vccnz .LBB0_1818
.LBB0_1867:
	s_ashr_i32 s4, s22, 31
	s_lshr_b32 s4, s4, 25
	s_add_i32 s22, s22, s4
	s_ashr_i32 s4, s22, 7
	v_lshl_or_b32 v100, s4, 6, v134
	v_add_u32_e32 v2, s0, v137
	s_lshl_b32 s4, s4, 12
	v_subrev_u32_e32 v2, s4, v2
	v_mov_b64_e32 v[102:103], s[12:13]
	v_ashrrev_i32_e32 v101, 31, v100
	v_mad_i64_i32 v[102:103], s[4:5], v2, s91, v[102:103]
	v_bfe_u32 v2, v8, 16, 1
	v_lshl_add_u64 v[104:105], v[100:101], 1, v[102:103]
	v_add3_u32 v2, v8, v2, s80
	v_bfe_u32 v100, v4, 16, 1
	v_lshrrev_b32_e32 v2, 16, v2
	v_add3_u32 v100, v4, v100, s80
	v_and_or_b32 v100, v100, s85, v2
	v_bfe_u32 v2, v28, 16, 1
	v_add3_u32 v2, v28, v2, s80
	v_bfe_u32 v101, v24, 16, 1
	v_lshrrev_b32_e32 v2, 16, v2
	v_add3_u32 v101, v24, v101, s80
	v_and_or_b32 v101, v101, s85, v2
	v_bfe_u32 v2, v52, 16, 1
	v_add3_u32 v2, v52, v2, s80
	v_bfe_u32 v102, v16, 16, 1
	v_lshrrev_b32_e32 v2, 16, v2
	v_add3_u32 v102, v16, v102, s80
	v_and_or_b32 v102, v102, s85, v2
	v_bfe_u32 v2, v72, 16, 1
	v_add3_u32 v2, v72, v2, s80
	v_bfe_u32 v103, v76, 16, 1
	v_lshrrev_b32_e32 v2, 16, v2
	v_add3_u32 v103, v76, v103, s80
	v_and_or_b32 v103, v103, s85, v2
	v_bfe_u32 v2, v9, 16, 1
	global_store_dwordx4 v[104:105], v[100:103], off nt
	v_add3_u32 v2, v9, v2, s80
	v_lshrrev_b32_e32 v2, 16, v2
	v_bfe_u32 v100, v5, 16, 1
	v_add3_u32 v100, v5, v100, s80
	v_and_or_b32 v100, v100, s85, v2
	v_bfe_u32 v2, v29, 16, 1
	v_add3_u32 v2, v29, v2, s80
	v_bfe_u32 v101, v25, 16, 1
	v_lshrrev_b32_e32 v2, 16, v2
	v_add3_u32 v101, v25, v101, s80
	v_and_or_b32 v101, v101, s85, v2
	v_bfe_u32 v2, v53, 16, 1
	v_add3_u32 v2, v53, v2, s80
	v_bfe_u32 v102, v17, 16, 1
	v_lshrrev_b32_e32 v2, 16, v2
	v_add3_u32 v102, v17, v102, s80
	v_and_or_b32 v102, v102, s85, v2
	v_bfe_u32 v2, v73, 16, 1
	v_add3_u32 v2, v73, v2, s80
	v_bfe_u32 v103, v77, 16, 1
	v_lshrrev_b32_e32 v2, 16, v2
	v_add3_u32 v103, v77, v103, s80
	v_add_co_u32_e32 v106, vcc, s91, v104
	v_and_or_b32 v103, v103, s85, v2
	s_nop 0
	v_addc_co_u32_e32 v107, vcc, 0, v105, vcc
	v_bfe_u32 v2, v10, 16, 1
	global_store_dwordx4 v[106:107], v[100:103], off nt
	v_add3_u32 v2, v10, v2, s80
	v_lshrrev_b32_e32 v2, 16, v2
	v_bfe_u32 v100, v6, 16, 1
	v_add3_u32 v100, v6, v100, s80
	v_and_or_b32 v100, v100, s85, v2
	v_bfe_u32 v2, v30, 16, 1
	v_add3_u32 v2, v30, v2, s80
	v_bfe_u32 v101, v26, 16, 1
	v_lshrrev_b32_e32 v2, 16, v2
	v_add3_u32 v101, v26, v101, s80
	v_and_or_b32 v101, v101, s85, v2
	v_bfe_u32 v2, v54, 16, 1
	v_add3_u32 v2, v54, v2, s80
	v_bfe_u32 v102, v18, 16, 1
	v_lshrrev_b32_e32 v2, 16, v2
	v_add3_u32 v102, v18, v102, s80
	v_and_or_b32 v102, v102, s85, v2
	v_bfe_u32 v2, v74, 16, 1
	v_add3_u32 v2, v74, v2, s80
	v_bfe_u32 v103, v78, 16, 1
	v_lshrrev_b32_e32 v2, 16, v2
	v_add3_u32 v103, v78, v103, s80
	v_add_co_u32_e32 v106, vcc, s87, v104
	v_and_or_b32 v103, v103, s85, v2
	s_nop 0
	v_addc_co_u32_e32 v107, vcc, 0, v105, vcc
	v_bfe_u32 v2, v11, 16, 1
	global_store_dwordx4 v[106:107], v[100:103], off nt
	v_add3_u32 v2, v11, v2, s80
	v_lshrrev_b32_e32 v2, 16, v2
	v_bfe_u32 v100, v7, 16, 1
	v_add3_u32 v100, v7, v100, s80
	v_and_or_b32 v100, v100, s85, v2
	v_bfe_u32 v2, v31, 16, 1
	v_add3_u32 v2, v31, v2, s80
	v_bfe_u32 v101, v27, 16, 1
	v_lshrrev_b32_e32 v2, 16, v2
	v_add3_u32 v101, v27, v101, s80
	v_and_or_b32 v101, v101, s85, v2
	v_bfe_u32 v2, v55, 16, 1
	v_add3_u32 v2, v55, v2, s80
	v_bfe_u32 v102, v19, 16, 1
	v_lshrrev_b32_e32 v2, 16, v2
	v_add3_u32 v102, v19, v102, s80
	v_and_or_b32 v102, v102, s85, v2
	v_bfe_u32 v2, v75, 16, 1
	v_add3_u32 v2, v75, v2, s80
	v_bfe_u32 v103, v79, 16, 1
	v_lshrrev_b32_e32 v2, 16, v2
	v_add3_u32 v103, v79, v103, s80
	v_add_co_u32_e32 v104, vcc, 0x9000, v104
	v_and_or_b32 v103, v103, s85, v2
	s_nop 0
	v_addc_co_u32_e32 v105, vcc, 0, v105, vcc
	global_store_dwordx4 v[104:105], v[100:103], off nt
	s_branch .LBB0_1818

.LBB0_1914:
	v_ashrrev_i32_e32 v135, 31, v134
	s_waitcnt vmcnt(1)
	v_bfe_u32 v2, v104, 16, 1
	v_lshlrev_b64 v[134:135], 13, v[134:135]
	v_add3_u32 v2, v104, v2, s80
	s_waitcnt vmcnt(0)
	v_bfe_u32 v104, v100, 16, 1
	v_lshl_add_u64 v[134:135], s[10:11], 0, v[134:135]
	v_lshrrev_b32_e32 v2, 16, v2
	v_add3_u32 v100, v100, v104, s80
	v_lshl_add_u64 v[142:143], v[132:133], 1, v[134:135]
	v_and_or_b32 v132, v100, s85, v2
	v_bfe_u32 v2, v116, 16, 1
	v_add3_u32 v2, v116, v2, s80
	v_bfe_u32 v100, v112, 16, 1
	v_lshrrev_b32_e32 v2, 16, v2
	v_add3_u32 v100, v112, v100, s80
	v_and_or_b32 v133, v100, s85, v2
	v_bfe_u32 v2, v120, 16, 1
	v_add3_u32 v2, v120, v2, s80
	v_bfe_u32 v100, v108, 16, 1
	v_lshrrev_b32_e32 v2, 16, v2
	v_add3_u32 v100, v108, v100, s80
	v_and_or_b32 v134, v100, s85, v2
	v_bfe_u32 v2, v128, 16, 1
	v_add3_u32 v2, v128, v2, s80
	v_bfe_u32 v100, v124, 16, 1
	v_lshrrev_b32_e32 v2, 16, v2
	v_add3_u32 v100, v124, v100, s80
	v_and_or_b32 v135, v100, s85, v2
	v_bfe_u32 v2, v105, 16, 1
	v_add3_u32 v2, v105, v2, s80
	v_bfe_u32 v100, v101, 16, 1
	v_lshrrev_b32_e32 v2, 16, v2
	v_add3_u32 v100, v101, v100, s80
	global_store_dwordx4 v[142:143], v[132:135], off nt
	s_nop 1
	v_and_or_b32 v132, v100, s85, v2
	v_bfe_u32 v2, v117, 16, 1
	v_add3_u32 v2, v117, v2, s80
	v_bfe_u32 v100, v113, 16, 1
	v_lshrrev_b32_e32 v2, 16, v2
	v_add3_u32 v100, v113, v100, s80
	v_and_or_b32 v133, v100, s85, v2
	v_bfe_u32 v2, v121, 16, 1
	v_add3_u32 v2, v121, v2, s80
	v_bfe_u32 v100, v109, 16, 1
	v_lshrrev_b32_e32 v2, 16, v2
	v_add3_u32 v100, v109, v100, s80
	v_and_or_b32 v134, v100, s85, v2
	v_bfe_u32 v2, v129, 16, 1
	v_add3_u32 v2, v129, v2, s80
	v_bfe_u32 v100, v125, 16, 1
	v_lshrrev_b32_e32 v2, 16, v2
	v_add3_u32 v100, v125, v100, s80
	v_and_or_b32 v135, v100, s85, v2
	v_add_co_u32_e32 v100, vcc, s84, v142
	v_bfe_u32 v2, v106, 16, 1
	s_nop 0
	v_addc_co_u32_e32 v101, vcc, 0, v143, vcc
	global_store_dwordx4 v[100:101], v[132:135], off nt
	v_add3_u32 v2, v106, v2, s80
	v_bfe_u32 v100, v102, 16, 1
	v_lshrrev_b32_e32 v2, 16, v2
	v_add3_u32 v100, v102, v100, s80
	v_and_or_b32 v132, v100, s85, v2
	v_bfe_u32 v2, v118, 16, 1
	v_add3_u32 v2, v118, v2, s80
	v_bfe_u32 v100, v114, 16, 1
	v_lshrrev_b32_e32 v2, 16, v2
	v_add3_u32 v100, v114, v100, s80
	v_and_or_b32 v133, v100, s85, v2
	v_bfe_u32 v2, v122, 16, 1
	v_add3_u32 v2, v122, v2, s80
	v_bfe_u32 v100, v110, 16, 1
	v_lshrrev_b32_e32 v2, 16, v2
	v_add3_u32 v100, v110, v100, s80
	v_and_or_b32 v134, v100, s85, v2
	v_bfe_u32 v2, v130, 16, 1
	v_add3_u32 v2, v130, v2, s80
	v_bfe_u32 v100, v126, 16, 1
	v_lshrrev_b32_e32 v2, 16, v2
	v_add3_u32 v100, v126, v100, s80
	v_and_or_b32 v135, v100, s85, v2
	v_add_co_u32_e32 v100, vcc, s81, v142
	v_bfe_u32 v2, v107, 16, 1
	s_nop 0
	v_addc_co_u32_e32 v101, vcc, 0, v143, vcc
	global_store_dwordx4 v[100:101], v[132:135], off nt
	v_add3_u32 v2, v107, v2, s80
	v_bfe_u32 v100, v103, 16, 1
	v_lshrrev_b32_e32 v2, 16, v2
	v_add3_u32 v100, v103, v100, s80
	v_and_or_b32 v100, v100, s85, v2
	v_bfe_u32 v2, v119, 16, 1
	v_add3_u32 v2, v119, v2, s80
	v_bfe_u32 v101, v115, 16, 1
	v_lshrrev_b32_e32 v2, 16, v2
	v_add3_u32 v101, v115, v101, s80
	v_and_or_b32 v101, v101, s85, v2
	v_bfe_u32 v2, v123, 16, 1
	v_add3_u32 v2, v123, v2, s80
	v_bfe_u32 v102, v111, 16, 1
	v_lshrrev_b32_e32 v2, 16, v2
	v_add3_u32 v102, v111, v102, s80
	v_and_or_b32 v102, v102, s85, v2
	v_bfe_u32 v2, v131, 16, 1
	v_add3_u32 v2, v131, v2, s80
	v_bfe_u32 v103, v127, 16, 1
	v_add_co_u32_e32 v104, vcc, 0x6000, v142
	v_lshrrev_b32_e32 v2, 16, v2
	v_add3_u32 v103, v127, v103, s80
	v_addc_co_u32_e32 v105, vcc, 0, v143, vcc
	v_and_or_b32 v103, v103, s85, v2
	s_andn2_b64 vcc, exec, s[12:13]
	global_store_dwordx4 v[104:105], v[100:103], off nt
	s_cbranch_vccnz .LBB0_1917
	s_ashr_i32 s4, s1, 31
	s_lshr_b32 s4, s4, 25
	s_add_i32 s1, s1, s4
	s_ashr_i32 s1, s1, 7
	v_lshl_or_b32 v100, s1, 6, v136
	v_add_u32_e32 v2, s0, v140
	s_lshl_b32 s1, s1, 12
	v_subrev_u32_e32 v102, s1, v2
	v_ashrrev_i32_e32 v103, 31, v102
	v_lshlrev_b64 v[102:103], 13, v[102:103]
	v_ashrrev_i32_e32 v101, 31, v100
	v_lshl_add_u64 v[102:103], s[10:11], 0, v[102:103]
	v_bfe_u32 v2, v36, 16, 1
	v_lshl_add_u64 v[104:105], v[100:101], 1, v[102:103]
	v_add3_u32 v2, v36, v2, s80
	v_bfe_u32 v100, v32, 16, 1
	v_lshrrev_b32_e32 v2, 16, v2
	v_add3_u32 v100, v32, v100, s80
	v_and_or_b32 v100, v100, s85, v2
	v_bfe_u32 v2, v64, 16, 1
	v_add3_u32 v2, v64, v2, s80
	v_bfe_u32 v101, v60, 16, 1
	v_lshrrev_b32_e32 v2, 16, v2
	v_add3_u32 v101, v60, v101, s80
	v_and_or_b32 v101, v101, s85, v2
	v_bfe_u32 v2, v80, 16, 1
	v_add3_u32 v2, v80, v2, s80
	v_bfe_u32 v102, v56, 16, 1
	v_lshrrev_b32_e32 v2, 16, v2
	v_add3_u32 v102, v56, v102, s80
	v_and_or_b32 v102, v102, s85, v2
	v_bfe_u32 v2, v92, 16, 1
	v_add3_u32 v2, v92, v2, s80
	v_bfe_u32 v103, v96, 16, 1
	v_lshrrev_b32_e32 v2, 16, v2
	v_add3_u32 v103, v96, v103, s80
	v_and_or_b32 v103, v103, s85, v2
	v_bfe_u32 v2, v37, 16, 1
	global_store_dwordx4 v[104:105], v[100:103], off nt
	v_add3_u32 v2, v37, v2, s80
	v_lshrrev_b32_e32 v2, 16, v2
	v_bfe_u32 v100, v33, 16, 1
	v_add3_u32 v100, v33, v100, s80
	v_and_or_b32 v100, v100, s85, v2
	v_bfe_u32 v2, v65, 16, 1
	v_add3_u32 v2, v65, v2, s80
	v_bfe_u32 v101, v61, 16, 1
	v_lshrrev_b32_e32 v2, 16, v2
	v_add3_u32 v101, v61, v101, s80
	v_and_or_b32 v101, v101, s85, v2
	v_bfe_u32 v2, v81, 16, 1
	v_add3_u32 v2, v81, v2, s80
	v_bfe_u32 v102, v57, 16, 1
	v_lshrrev_b32_e32 v2, 16, v2
	v_add3_u32 v102, v57, v102, s80
	v_and_or_b32 v102, v102, s85, v2
	v_bfe_u32 v2, v93, 16, 1
	v_add3_u32 v2, v93, v2, s80
	v_bfe_u32 v103, v97, 16, 1
	v_lshrrev_b32_e32 v2, 16, v2
	v_add3_u32 v103, v97, v103, s80
	v_add_co_u32_e32 v106, vcc, s84, v104
	v_and_or_b32 v103, v103, s85, v2
	s_nop 0
	v_addc_co_u32_e32 v107, vcc, 0, v105, vcc
	v_bfe_u32 v2, v38, 16, 1
	global_store_dwordx4 v[106:107], v[100:103], off nt
	v_add3_u32 v2, v38, v2, s80
	v_lshrrev_b32_e32 v2, 16, v2
	v_bfe_u32 v100, v34, 16, 1
	v_add3_u32 v100, v34, v100, s80
	v_and_or_b32 v100, v100, s85, v2
	v_bfe_u32 v2, v66, 16, 1
	v_add3_u32 v2, v66, v2, s80
	v_bfe_u32 v101, v62, 16, 1
	v_lshrrev_b32_e32 v2, 16, v2
	v_add3_u32 v101, v62, v101, s80
	v_and_or_b32 v101, v101, s85, v2
	v_bfe_u32 v2, v82, 16, 1
	v_add3_u32 v2, v82, v2, s80
	v_bfe_u32 v102, v58, 16, 1
	v_lshrrev_b32_e32 v2, 16, v2
	v_add3_u32 v102, v58, v102, s80
	v_and_or_b32 v102, v102, s85, v2
	v_bfe_u32 v2, v94, 16, 1
	v_add3_u32 v2, v94, v2, s80
	v_bfe_u32 v103, v98, 16, 1
	v_lshrrev_b32_e32 v2, 16, v2
	v_add3_u32 v103, v98, v103, s80
	v_add_co_u32_e32 v106, vcc, s81, v104
	v_and_or_b32 v103, v103, s85, v2
	s_nop 0
	v_addc_co_u32_e32 v107, vcc, 0, v105, vcc
	v_bfe_u32 v2, v39, 16, 1
	global_store_dwordx4 v[106:107], v[100:103], off nt
	v_add3_u32 v2, v39, v2, s80
	v_lshrrev_b32_e32 v2, 16, v2
	v_bfe_u32 v100, v35, 16, 1
	v_add3_u32 v100, v35, v100, s80
	v_and_or_b32 v100, v100, s85, v2
	v_bfe_u32 v2, v67, 16, 1
	v_add3_u32 v2, v67, v2, s80
	v_bfe_u32 v101, v63, 16, 1
	v_lshrrev_b32_e32 v2, 16, v2
	v_add3_u32 v101, v63, v101, s80
	v_and_or_b32 v101, v101, s85, v2
	v_bfe_u32 v2, v83, 16, 1
	v_add3_u32 v2, v83, v2, s80
	v_bfe_u32 v102, v59, 16, 1
	v_lshrrev_b32_e32 v2, 16, v2
	v_add3_u32 v102, v59, v102, s80
	v_and_or_b32 v102, v102, s85, v2
	v_bfe_u32 v2, v95, 16, 1
	v_add3_u32 v2, v95, v2, s80
	v_bfe_u32 v103, v99, 16, 1
	v_lshrrev_b32_e32 v2, 16, v2
	v_add3_u32 v103, v99, v103, s80
	v_add_co_u32_e32 v104, vcc, 0x6000, v104
	v_and_or_b32 v103, v103, s85, v2
	s_nop 0
	v_addc_co_u32_e32 v105, vcc, 0, v105, vcc
	global_store_dwordx4 v[104:105], v[100:103], off nt
	s_andn2_b64 vcc, exec, s[16:17]
	s_cbranch_vccz .LBB0_1918

.LBB0_1918:
	s_ashr_i32 s1, s14, 31
	s_lshr_b32 s1, s1, 25
	s_add_i32 s14, s14, s1
	s_ashr_i32 s1, s14, 7
	v_lshl_or_b32 v100, s1, 6, v136
	v_add_u32_e32 v2, s0, v138
	s_lshl_b32 s1, s1, 12
	v_subrev_u32_e32 v102, s1, v2
	v_ashrrev_i32_e32 v103, 31, v102
	v_lshlrev_b64 v[102:103], 13, v[102:103]
	v_ashrrev_i32_e32 v101, 31, v100
	v_lshl_add_u64 v[102:103], s[10:11], 0, v[102:103]
	v_bfe_u32 v2, v20, 16, 1
	v_lshl_add_u64 v[104:105], v[100:101], 1, v[102:103]
	v_add3_u32 v2, v20, v2, s80
	v_bfe_u32 v100, v12, 16, 1
	v_lshrrev_b32_e32 v2, 16, v2
	v_add3_u32 v100, v12, v100, s80
	v_and_or_b32 v100, v100, s85, v2
	v_bfe_u32 v2, v48, 16, 1
	v_add3_u32 v2, v48, v2, s80
	v_bfe_u32 v101, v44, 16, 1
	v_lshrrev_b32_e32 v2, 16, v2
	v_add3_u32 v101, v44, v101, s80
	v_and_or_b32 v101, v101, s85, v2
	v_bfe_u32 v2, v68, 16, 1
	v_add3_u32 v2, v68, v2, s80
	v_bfe_u32 v102, v40, 16, 1
	v_lshrrev_b32_e32 v2, 16, v2
	v_add3_u32 v102, v40, v102, s80
	v_and_or_b32 v102, v102, s85, v2
	v_bfe_u32 v2, v84, 16, 1
	v_add3_u32 v2, v84, v2, s80
	v_bfe_u32 v103, v88, 16, 1
	v_lshrrev_b32_e32 v2, 16, v2
	v_add3_u32 v103, v88, v103, s80
	v_and_or_b32 v103, v103, s85, v2
	v_bfe_u32 v2, v21, 16, 1
	global_store_dwordx4 v[104:105], v[100:103], off nt
	v_add3_u32 v2, v21, v2, s80
	v_lshrrev_b32_e32 v2, 16, v2
	v_bfe_u32 v100, v13, 16, 1
	v_add3_u32 v100, v13, v100, s80
	v_and_or_b32 v100, v100, s85, v2
	v_bfe_u32 v2, v49, 16, 1
	v_add3_u32 v2, v49, v2, s80
	v_bfe_u32 v101, v45, 16, 1
	v_lshrrev_b32_e32 v2, 16, v2
	v_add3_u32 v101, v45, v101, s80
	v_and_or_b32 v101, v101, s85, v2
	v_bfe_u32 v2, v69, 16, 1
	v_add3_u32 v2, v69, v2, s80
	v_bfe_u32 v102, v41, 16, 1
	v_lshrrev_b32_e32 v2, 16, v2
	v_add3_u32 v102, v41, v102, s80
	v_and_or_b32 v102, v102, s85, v2
	v_bfe_u32 v2, v85, 16, 1
	v_add3_u32 v2, v85, v2, s80
	v_bfe_u32 v103, v89, 16, 1
	v_lshrrev_b32_e32 v2, 16, v2
	v_add3_u32 v103, v89, v103, s80
	v_add_co_u32_e32 v106, vcc, s84, v104
	v_and_or_b32 v103, v103, s85, v2
	s_nop 0
	v_addc_co_u32_e32 v107, vcc, 0, v105, vcc
	v_bfe_u32 v2, v22, 16, 1
	global_store_dwordx4 v[106:107], v[100:103], off nt
	v_add3_u32 v2, v22, v2, s80
	v_lshrrev_b32_e32 v2, 16, v2
	v_bfe_u32 v100, v14, 16, 1
	v_add3_u32 v100, v14, v100, s80
	v_and_or_b32 v100, v100, s85, v2
	v_bfe_u32 v2, v50, 16, 1
	v_add3_u32 v2, v50, v2, s80
	v_bfe_u32 v101, v46, 16, 1
	v_lshrrev_b32_e32 v2, 16, v2
	v_add3_u32 v101, v46, v101, s80
	v_and_or_b32 v101, v101, s85, v2
	v_bfe_u32 v2, v70, 16, 1
	v_add3_u32 v2, v70, v2, s80
	v_bfe_u32 v102, v42, 16, 1
	v_lshrrev_b32_e32 v2, 16, v2
	v_add3_u32 v102, v42, v102, s80
	v_and_or_b32 v102, v102, s85, v2
	v_bfe_u32 v2, v86, 16, 1
	v_add3_u32 v2, v86, v2, s80
	v_bfe_u32 v103, v90, 16, 1
	v_lshrrev_b32_e32 v2, 16, v2
	v_add3_u32 v103, v90, v103, s80
	v_add_co_u32_e32 v106, vcc, s81, v104
	v_and_or_b32 v103, v103, s85, v2
	s_nop 0
	v_addc_co_u32_e32 v107, vcc, 0, v105, vcc
	v_bfe_u32 v2, v23, 16, 1
	global_store_dwordx4 v[106:107], v[100:103], off nt
	v_add3_u32 v2, v23, v2, s80
	v_lshrrev_b32_e32 v2, 16, v2
	v_bfe_u32 v100, v15, 16, 1
	v_add3_u32 v100, v15, v100, s80
	v_and_or_b32 v100, v100, s85, v2
	v_bfe_u32 v2, v51, 16, 1
	v_add3_u32 v2, v51, v2, s80
	v_bfe_u32 v101, v47, 16, 1
	v_lshrrev_b32_e32 v2, 16, v2
	v_add3_u32 v101, v47, v101, s80
	v_and_or_b32 v101, v101, s85, v2
	v_bfe_u32 v2, v71, 16, 1
	v_add3_u32 v2, v71, v2, s80
	v_bfe_u32 v102, v43, 16, 1
	v_lshrrev_b32_e32 v2, 16, v2
	v_add3_u32 v102, v43, v102, s80
	v_and_or_b32 v102, v102, s85, v2
	v_bfe_u32 v2, v87, 16, 1
	v_add3_u32 v2, v87, v2, s80
	v_bfe_u32 v103, v91, 16, 1
	v_lshrrev_b32_e32 v2, 16, v2
	v_add3_u32 v103, v91, v103, s80
	v_add_co_u32_e32 v104, vcc, 0x6000, v104
	v_and_or_b32 v103, v103, s85, v2
	s_nop 0
	v_addc_co_u32_e32 v105, vcc, 0, v105, vcc
	global_store_dwordx4 v[104:105], v[100:103], off nt
	s_andn2_b64 vcc, exec, s[18:19]
	s_cbranch_vccnz .LBB0_1870
.LBB0_1919:
	s_ashr_i32 s1, s15, 31
	s_lshr_b32 s1, s1, 25
	s_add_i32 s15, s15, s1
	s_ashr_i32 s1, s15, 7
	v_lshl_or_b32 v100, s1, 6, v136
	v_add_u32_e32 v2, s0, v139
	s_lshl_b32 s1, s1, 12
	v_subrev_u32_e32 v102, s1, v2
	v_ashrrev_i32_e32 v103, 31, v102
	v_lshlrev_b64 v[102:103], 13, v[102:103]
	v_ashrrev_i32_e32 v101, 31, v100
	v_lshl_add_u64 v[102:103], s[10:11], 0, v[102:103]
	v_bfe_u32 v2, v8, 16, 1
	v_lshl_add_u64 v[104:105], v[100:101], 1, v[102:103]
	v_add3_u32 v2, v8, v2, s80
	v_bfe_u32 v100, v4, 16, 1
	v_lshrrev_b32_e32 v2, 16, v2
	v_add3_u32 v100, v4, v100, s80
	v_and_or_b32 v100, v100, s85, v2
	v_bfe_u32 v2, v28, 16, 1
	v_add3_u32 v2, v28, v2, s80
	v_bfe_u32 v101, v24, 16, 1
	v_lshrrev_b32_e32 v2, 16, v2
	v_add3_u32 v101, v24, v101, s80
	v_and_or_b32 v101, v101, s85, v2
	v_bfe_u32 v2, v52, 16, 1
	v_add3_u32 v2, v52, v2, s80
	v_bfe_u32 v102, v16, 16, 1
	v_lshrrev_b32_e32 v2, 16, v2
	v_add3_u32 v102, v16, v102, s80
	v_and_or_b32 v102, v102, s85, v2
	v_bfe_u32 v2, v72, 16, 1
	v_add3_u32 v2, v72, v2, s80
	v_bfe_u32 v103, v76, 16, 1
	v_lshrrev_b32_e32 v2, 16, v2
	v_add3_u32 v103, v76, v103, s80
	v_and_or_b32 v103, v103, s85, v2
	v_bfe_u32 v2, v9, 16, 1
	global_store_dwordx4 v[104:105], v[100:103], off nt
	v_add3_u32 v2, v9, v2, s80
	v_lshrrev_b32_e32 v2, 16, v2
	v_bfe_u32 v100, v5, 16, 1
	v_add3_u32 v100, v5, v100, s80
	v_and_or_b32 v100, v100, s85, v2
	v_bfe_u32 v2, v29, 16, 1
	v_add3_u32 v2, v29, v2, s80
	v_bfe_u32 v101, v25, 16, 1
	v_lshrrev_b32_e32 v2, 16, v2
	v_add3_u32 v101, v25, v101, s80
	v_and_or_b32 v101, v101, s85, v2
	v_bfe_u32 v2, v53, 16, 1
	v_add3_u32 v2, v53, v2, s80
	v_bfe_u32 v102, v17, 16, 1
	v_lshrrev_b32_e32 v2, 16, v2
	v_add3_u32 v102, v17, v102, s80
	v_and_or_b32 v102, v102, s85, v2
	v_bfe_u32 v2, v73, 16, 1
	v_add3_u32 v2, v73, v2, s80
	v_bfe_u32 v103, v77, 16, 1
	v_lshrrev_b32_e32 v2, 16, v2
	v_add3_u32 v103, v77, v103, s80
	v_add_co_u32_e32 v106, vcc, s84, v104
	v_and_or_b32 v103, v103, s85, v2
	s_nop 0
	v_addc_co_u32_e32 v107, vcc, 0, v105, vcc
	v_bfe_u32 v2, v10, 16, 1
	global_store_dwordx4 v[106:107], v[100:103], off nt
	v_add3_u32 v2, v10, v2, s80
	v_lshrrev_b32_e32 v2, 16, v2
	v_bfe_u32 v100, v6, 16, 1
	v_add3_u32 v100, v6, v100, s80
	v_and_or_b32 v100, v100, s85, v2
	v_bfe_u32 v2, v30, 16, 1
	v_add3_u32 v2, v30, v2, s80
	v_bfe_u32 v101, v26, 16, 1
	v_lshrrev_b32_e32 v2, 16, v2
	v_add3_u32 v101, v26, v101, s80
	v_and_or_b32 v101, v101, s85, v2
	v_bfe_u32 v2, v54, 16, 1
	v_add3_u32 v2, v54, v2, s80
	v_bfe_u32 v102, v18, 16, 1
	v_lshrrev_b32_e32 v2, 16, v2
	v_add3_u32 v102, v18, v102, s80
	v_and_or_b32 v102, v102, s85, v2
	v_bfe_u32 v2, v74, 16, 1
	v_add3_u32 v2, v74, v2, s80
	v_bfe_u32 v103, v78, 16, 1
	v_lshrrev_b32_e32 v2, 16, v2
	v_add3_u32 v103, v78, v103, s80
	v_add_co_u32_e32 v106, vcc, s81, v104
	v_and_or_b32 v103, v103, s85, v2
	s_nop 0
	v_addc_co_u32_e32 v107, vcc, 0, v105, vcc
	v_bfe_u32 v2, v11, 16, 1
	global_store_dwordx4 v[106:107], v[100:103], off nt
	v_add3_u32 v2, v11, v2, s80
	v_lshrrev_b32_e32 v2, 16, v2
	v_bfe_u32 v100, v7, 16, 1
	v_add3_u32 v100, v7, v100, s80
	v_and_or_b32 v100, v100, s85, v2
	v_bfe_u32 v2, v31, 16, 1
	v_add3_u32 v2, v31, v2, s80
	v_bfe_u32 v101, v27, 16, 1
	v_lshrrev_b32_e32 v2, 16, v2
	v_add3_u32 v101, v27, v101, s80
	v_and_or_b32 v101, v101, s85, v2
	v_bfe_u32 v2, v55, 16, 1
	v_add3_u32 v2, v55, v2, s80
	v_bfe_u32 v102, v19, 16, 1
	v_lshrrev_b32_e32 v2, 16, v2
	v_add3_u32 v102, v19, v102, s80
	v_and_or_b32 v102, v102, s85, v2
	v_bfe_u32 v2, v75, 16, 1
	v_add3_u32 v2, v75, v2, s80
	v_bfe_u32 v103, v79, 16, 1
	v_lshrrev_b32_e32 v2, 16, v2
	v_add3_u32 v103, v79, v103, s80
	v_add_co_u32_e32 v104, vcc, 0x6000, v104
	v_and_or_b32 v103, v103, s85, v2
	s_nop 0
	v_addc_co_u32_e32 v105, vcc, 0, v105, vcc
	global_store_dwordx4 v[104:105], v[100:103], off nt
	s_branch .LBB0_1870

.LBB0_2245:
	s_or_b64 exec, exec, s[18:19]
	s_waitcnt lgkmcnt(0)
	v_max_f32_e32 v2, v132, v132
	v_max_f32_e32 v2, 0xda24260, v2
	v_div_scale_f32 v132, s[18:19], v2, v2, s88
	v_rcp_f32_e32 v136, v132
	v_div_scale_f32 v137, vcc, s88, v2, s88
	v_max_f32_e32 v133, v133, v133
	v_fma_f32 v139, -v132, v136, 1.0
	v_fmac_f32_e32 v136, v139, v136
	v_mul_f32_e32 v139, v137, v136
	v_fma_f32 v140, -v132, v139, v137
	v_fmac_f32_e32 v139, v140, v136
	v_max_f32_e32 v133, 0xda24260, v133
	v_fma_f32 v132, -v132, v139, v137
	v_div_scale_f32 v137, s[18:19], v133, v133, s88
	v_rcp_f32_e32 v140, v137
	v_div_fmas_f32 v132, v132, v136, v139
	v_div_fixup_f32 v2, v132, v2, s88
	v_max_f32_e32 v134, v134, v134
	v_fma_f32 v132, -v137, v140, 1.0
	v_fmac_f32_e32 v140, v132, v140
	v_div_scale_f32 v132, vcc, s88, v133, s88
	v_mul_f32_e32 v136, v132, v140
	v_fma_f32 v139, -v137, v136, v132
	v_fmac_f32_e32 v136, v139, v140
	v_max_f32_e32 v134, 0xda24260, v134
	v_fma_f32 v132, -v137, v136, v132
	v_div_scale_f32 v137, s[18:19], v134, v134, s88
	v_rcp_f32_e32 v139, v137
	v_div_fmas_f32 v132, v132, v140, v136
	v_div_fixup_f32 v132, v132, v133, s88
	v_max_f32_e32 v135, v135, v135
	v_fma_f32 v133, -v137, v139, 1.0
	v_fmac_f32_e32 v139, v133, v139
	v_div_scale_f32 v133, vcc, s88, v134, s88
	v_mul_f32_e32 v136, v133, v139
	v_fma_f32 v140, -v137, v136, v133
	v_fmac_f32_e32 v136, v140, v139
	v_max_f32_e32 v135, 0xda24260, v135
	v_fma_f32 v133, -v137, v136, v133
	v_div_scale_f32 v137, s[18:19], v135, v135, s88
	v_rcp_f32_e32 v140, v137
	v_div_fmas_f32 v133, v133, v139, v136
	v_div_fixup_f32 v133, v133, v134, s88
	v_bfe_u32 v176, v126, 16, 1
	v_fma_f32 v134, -v137, v140, 1.0
	v_fmac_f32_e32 v140, v134, v140
	v_div_scale_f32 v134, vcc, s88, v135, s88
	v_mul_f32_e32 v136, v134, v140
	v_fma_f32 v139, -v137, v136, v134
	v_fmac_f32_e32 v136, v139, v140
	v_fma_f32 v134, -v137, v136, v134
	v_div_fmas_f32 v134, v134, v140, v136
	v_bfe_u32 v136, v79, 16, 1
	v_add3_u32 v169, v79, v136, s80
	v_bfe_u32 v79, v72, 16, 1
	v_add3_u32 v136, v72, v79, s80
	v_add3_u32 v79, v126, v176, s80
	v_bfe_u32 v126, v12, 16, 1
	v_add3_u32 v12, v12, v126, s80
	v_bfe_u32 v126, v13, 16, 1
	v_add3_u32 v13, v13, v126, s80
	v_bfe_u32 v126, v14, 16, 1
	v_add3_u32 v14, v14, v126, s80
	v_bfe_u32 v126, v15, 16, 1
	v_add3_u32 v15, v15, v126, s80
	v_bfe_u32 v126, v8, 16, 1
	v_add3_u32 v8, v8, v126, s80
	v_bfe_u32 v126, v9, 16, 1
	v_bfe_u32 v147, v91, 16, 1
	v_add3_u32 v9, v9, v126, s80
	v_bfe_u32 v160, v125, 16, 1
	v_add3_u32 v147, v91, v147, s80
	v_bfe_u32 v91, v96, 16, 1
	v_bfe_u32 v179, v128, 16, 1
	v_and_b32_e32 v126, 0xffff0000, v9
	v_bfe_u32 v9, v10, 16, 1
	v_div_fixup_f32 v134, v134, v135, s88
	v_bfe_u32 v135, v77, 16, 1
	v_bfe_u32 v139, v75, 16, 1
	v_add3_u32 v160, v125, v160, s80
	v_add3_u32 v125, v96, v91, s80
	v_add3_u32 v91, v128, v179, s80
	v_add3_u32 v128, v10, v9, s80
	v_bfe_u32 v9, v11, 16, 1
	v_bfe_u32 v162, v121, 16, 1
	v_add3_u32 v77, v77, v135, s80
	v_bfe_u32 v135, v78, 16, 1
	v_add3_u32 v139, v75, v139, s80
	v_bfe_u32 v75, v80, 16, 1
	v_bfe_u32 v180, v130, 16, 1
	v_add3_u32 v9, v11, v9, s80
	v_add3_u32 v162, v121, v162, s80
	v_add3_u32 v121, v78, v135, s80
	v_add3_u32 v135, v80, v75, s80
	v_add3_u32 v75, v130, v180, s80
	v_and_b32_e32 v130, 0xffff0000, v9
	v_bfe_u32 v9, v20, 16, 1
	v_bfe_u32 v11, v22, 16, 1
	v_add3_u32 v9, v20, v9, s80
	v_add3_u32 v20, v22, v11, s80
	v_bfe_u32 v11, v23, 16, 1
	v_bfe_u32 v10, v21, 16, 1
	v_add3_u32 v11, v23, v11, s80
	v_add3_u32 v10, v21, v10, s80
	v_and_b32_e32 v21, 0xffff0000, v11
	v_bfe_u32 v11, v4, 16, 1
	v_add3_u32 v11, v4, v11, s80
	v_bfe_u32 v4, v5, 16, 1
	v_add3_u32 v4, v5, v4, s80
	v_and_b32_e32 v22, 0xffff0000, v4
	v_bfe_u32 v4, v6, 16, 1
	v_bfe_u32 v149, v99, 16, 1
	v_bfe_u32 v151, v87, 16, 1
	v_add3_u32 v23, v6, v4, s80
	v_bfe_u32 v4, v7, 16, 1
	v_bfe_u32 v163, v123, 16, 1
	v_add3_u32 v149, v99, v149, s80
	v_bfe_u32 v99, v84, 16, 1
	v_add3_u32 v87, v87, v151, s80
	v_bfe_u32 v151, v108, 16, 1
	v_add3_u32 v4, v7, v4, s80
	v_add3_u32 v163, v123, v163, s80
	v_add3_u32 v123, v84, v99, s80
	v_add3_u32 v99, v108, v151, s80
	v_and_b32_e32 v108, 0xffff0000, v139
	v_and_b32_e32 v139, 0xffff0000, v4
	v_bfe_u32 v4, v28, 16, 1
	v_add3_u32 v28, v28, v4, s80
	v_bfe_u32 v4, v29, 16, 1
	v_add3_u32 v4, v29, v4, s80
	v_and_b32_e32 v29, 0xffff0000, v4
	v_bfe_u32 v4, v30, 16, 1
	v_add3_u32 v30, v30, v4, s80
	v_bfe_u32 v4, v31, 16, 1
	v_add3_u32 v4, v31, v4, s80
	v_and_b32_e32 v31, 0xffff0000, v4
	v_bfe_u32 v4, v24, 16, 1
	v_add3_u32 v24, v24, v4, s80
	v_bfe_u32 v4, v25, 16, 1
	v_add3_u32 v4, v25, v4, s80
	v_and_b32_e32 v25, 0xffff0000, v4
	v_bfe_u32 v4, v26, 16, 1
	v_add3_u32 v26, v26, v4, s80
	v_bfe_u32 v4, v27, 16, 1
	v_and_b32_e32 v8, 0xffff0000, v8
	v_add3_u32 v4, v27, v4, s80
	v_and_b32_e32 v12, 0xffff0000, v12
	v_mul_f32_e32 v8, v2, v8
	v_and_b32_e32 v9, 0xffff0000, v9
	v_and_b32_e32 v11, 0xffff0000, v11
	v_and_b32_e32 v27, 0xffff0000, v4
	v_bfe_u32 v4, v32, 16, 1
	v_mul_f32_e32 v12, v2, v12
	v_rndne_f32_e32 v8, v8
	v_mul_f32_e32 v9, v2, v9
	v_mul_f32_e32 v11, v2, v11
	v_add3_u32 v32, v32, v4, s80
	v_bfe_u32 v4, v33, 16, 1
	v_rndne_f32_e32 v12, v12
	v_cvt_i32_f32_e32 v8, v8
	v_rndne_f32_e32 v9, v9
	v_rndne_f32_e32 v11, v11
	v_add3_u32 v4, v33, v4, s80
	v_cvt_i32_f32_e32 v12, v12
	v_cvt_i32_f32_sdwa v9, v9 dst_sel:WORD_1 dst_unused:UNUSED_PAD src0_sel:DWORD
	v_cvt_i32_f32_e32 v11, v11
	v_and_b32_e32 v33, 0xffff0000, v4
	v_bfe_u32 v4, v34, 16, 1
	v_add3_u32 v34, v34, v4, s80
	v_bfe_u32 v4, v35, 16, 1
	v_add3_u32 v4, v35, v4, s80
	v_lshlrev_b32_e32 v8, 8, v8
	v_and_b32_e32 v35, 0xffff0000, v4
	v_bfe_u32 v4, v16, 16, 1
	v_and_b32_e32 v8, 0xff00, v8
	v_and_b32_e32 v9, 0xff0000, v9
	v_perm_b32 v11, v11, v12, s89
	v_add3_u32 v16, v16, v4, s80
	v_or3_b32 v8, v11, v8, v9
	v_and_b32_e32 v11, 0xffff0000, v24
	v_and_b32_e32 v9, 0xffff0000, v28
	v_mul_f32_e32 v11, v2, v11
	v_and_b32_e32 v12, 0xffff0000, v32
	v_and_b32_e32 v16, 0xffff0000, v16
	v_mul_f32_e32 v9, v2, v9
	v_rndne_f32_e32 v11, v11
	v_mul_f32_e32 v12, v2, v12
	v_mul_f32_e32 v16, v2, v16
	v_rndne_f32_e32 v9, v9
	v_cvt_i32_f32_e32 v11, v11
	v_rndne_f32_e32 v12, v12
	v_rndne_f32_e32 v16, v16
	v_cvt_i32_f32_e32 v9, v9
	v_cvt_i32_f32_sdwa v12, v12 dst_sel:WORD_1 dst_unused:UNUSED_PAD src0_sel:DWORD
	v_cvt_i32_f32_e32 v16, v16
	v_or_b32_e32 v6, v138, v230
	v_ashrrev_i32_e32 v7, 31, v6
	v_lshlrev_b32_e32 v11, 8, v11
	v_lshlrev_b64 v[6:7], 12, v[6:7]
	v_and_b32_e32 v11, 0xff00, v11
	v_and_b32_e32 v12, 0xff0000, v12
	v_perm_b32 v9, v16, v9, s89
	v_lshl_add_u64 v[6:7], v[206:207], 0, v[6:7]
	v_or3_b32 v9, v9, v11, v12
	v_and_b32_e32 v13, 0xffff0000, v13
	v_and_b32_e32 v10, 0xffff0000, v10
	global_store_dwordx2 v[6:7], v[8:9], off nt
	v_mul_f32_e32 v9, v132, v126
	v_mul_f32_e32 v8, v132, v13
	v_rndne_f32_e32 v9, v9
	v_mul_f32_e32 v10, v132, v10
	v_mul_f32_e32 v11, v132, v22
	v_rndne_f32_e32 v8, v8
	v_cvt_i32_f32_e32 v9, v9
	v_rndne_f32_e32 v10, v10
	v_rndne_f32_e32 v11, v11
	v_cvt_i32_f32_e32 v8, v8
	v_cvt_i32_f32_sdwa v10, v10 dst_sel:WORD_1 dst_unused:UNUSED_PAD src0_sel:DWORD
	v_cvt_i32_f32_e32 v11, v11
	v_bfe_u32 v4, v17, 16, 1
	v_lshlrev_b32_e32 v9, 8, v9
	v_add3_u32 v4, v17, v4, s80
	v_and_b32_e32 v9, 0xff00, v9
	v_and_b32_e32 v10, 0xff0000, v10
	v_perm_b32 v8, v11, v8, s89
	v_and_b32_e32 v17, 0xffff0000, v4
	v_or3_b32 v12, v8, v9, v10
	v_mul_f32_e32 v9, v132, v25
	v_mul_f32_e32 v8, v132, v29
	v_rndne_f32_e32 v9, v9
	v_mul_f32_e32 v10, v132, v33
	v_mul_f32_e32 v11, v132, v17
	v_rndne_f32_e32 v8, v8
	v_cvt_i32_f32_e32 v9, v9
	v_rndne_f32_e32 v10, v10
	v_rndne_f32_e32 v11, v11
	v_cvt_i32_f32_e32 v8, v8
	v_cvt_i32_f32_sdwa v10, v10 dst_sel:WORD_1 dst_unused:UNUSED_PAD src0_sel:DWORD
	v_cvt_i32_f32_e32 v11, v11
	v_lshlrev_b32_e32 v9, 8, v9
	v_and_b32_e32 v9, 0xff00, v9
	v_and_b32_e32 v10, 0xff0000, v10
	v_perm_b32 v8, v11, v8, s89
	s_movk_i32 s15, 0x1000
	v_or3_b32 v13, v8, v9, v10
	v_add_co_u32_e32 v10, vcc, s15, v6
	v_bfe_u32 v4, v18, 16, 1
	s_nop 0
	v_addc_co_u32_e32 v11, vcc, 0, v7, vcc
	v_add_co_u32_e32 v8, vcc, s84, v6
	v_add3_u32 v18, v18, v4, s80
	s_nop 0
	v_addc_co_u32_e32 v9, vcc, 0, v7, vcc
	global_store_dwordx2 v[8:9], v[12:13], off offset:-4096 nt
	v_and_b32_e32 v13, 0xffff0000, v128
	v_bfe_u32 v4, v19, 16, 1
	v_and_b32_e32 v12, 0xffff0000, v14
	v_mul_f32_e32 v13, v133, v13
	v_and_b32_e32 v14, 0xffff0000, v20
	v_and_b32_e32 v16, 0xffff0000, v23
	v_add3_u32 v4, v19, v4, s80
	v_mul_f32_e32 v12, v133, v12
	v_rndne_f32_e32 v13, v13
	v_mul_f32_e32 v14, v133, v14
	v_mul_f32_e32 v16, v133, v16
	v_and_b32_e32 v19, 0xffff0000, v4
	v_bfe_u32 v4, v44, 16, 1
	v_rndne_f32_e32 v12, v12
	v_cvt_i32_f32_e32 v13, v13
	v_rndne_f32_e32 v14, v14
	v_rndne_f32_e32 v16, v16
	v_add3_u32 v44, v44, v4, s80
	v_bfe_u32 v4, v45, 16, 1
	v_cvt_i32_f32_e32 v12, v12
	v_cvt_i32_f32_sdwa v14, v14 dst_sel:WORD_1 dst_unused:UNUSED_PAD src0_sel:DWORD
	v_cvt_i32_f32_e32 v16, v16
	v_add3_u32 v4, v45, v4, s80
	v_and_b32_e32 v45, 0xffff0000, v4
	v_bfe_u32 v4, v46, 16, 1
	v_add3_u32 v46, v46, v4, s80
	v_bfe_u32 v4, v47, 16, 1
	v_lshlrev_b32_e32 v13, 8, v13
	v_add3_u32 v4, v47, v4, s80
	v_and_b32_e32 v13, 0xff00, v13
	v_and_b32_e32 v14, 0xff0000, v14
	v_perm_b32 v12, v16, v12, s89
	v_and_b32_e32 v47, 0xffff0000, v4
	v_bfe_u32 v4, v40, 16, 1
	v_or3_b32 v12, v12, v13, v14
	v_and_b32_e32 v14, 0xffff0000, v26
	v_add3_u32 v40, v40, v4, s80
	v_bfe_u32 v4, v41, 16, 1
	v_and_b32_e32 v13, 0xffff0000, v30
	v_mul_f32_e32 v14, v133, v14
	v_and_b32_e32 v16, 0xffff0000, v34
	v_and_b32_e32 v17, 0xffff0000, v18
	v_add3_u32 v4, v41, v4, s80
	v_mul_f32_e32 v13, v133, v13
	v_rndne_f32_e32 v14, v14
	v_mul_f32_e32 v16, v133, v16
	v_mul_f32_e32 v17, v133, v17
	v_and_b32_e32 v41, 0xffff0000, v4
	v_bfe_u32 v4, v42, 16, 1
	v_rndne_f32_e32 v13, v13
	v_cvt_i32_f32_e32 v14, v14
	v_rndne_f32_e32 v16, v16
	v_rndne_f32_e32 v17, v17
	v_add3_u32 v42, v42, v4, s80
	v_bfe_u32 v4, v43, 16, 1
	v_cvt_i32_f32_e32 v13, v13
	v_cvt_i32_f32_sdwa v16, v16 dst_sel:WORD_1 dst_unused:UNUSED_PAD src0_sel:DWORD
	v_cvt_i32_f32_e32 v17, v17
	v_add3_u32 v4, v43, v4, s80
	v_and_b32_e32 v43, 0xffff0000, v4
	v_bfe_u32 v4, v52, 16, 1
	v_add3_u32 v52, v52, v4, s80
	v_bfe_u32 v4, v53, 16, 1
	v_lshlrev_b32_e32 v14, 8, v14
	v_add3_u32 v4, v53, v4, s80
	v_and_b32_e32 v14, 0xff00, v14
	v_and_b32_e32 v16, 0xff0000, v16
	v_perm_b32 v13, v17, v13, s89
	v_and_b32_e32 v53, 0xffff0000, v4
	v_bfe_u32 v4, v54, 16, 1
	v_or3_b32 v13, v13, v14, v16
	v_and_b32_e32 v15, 0xffff0000, v15
	v_add3_u32 v54, v54, v4, s80
	v_bfe_u32 v4, v55, 16, 1
	global_store_dwordx2 v[8:9], v[12:13], off nt
	v_mul_f32_e32 v13, v134, v130
	v_add3_u32 v4, v55, v4, s80
	v_mul_f32_e32 v12, v134, v15
	v_rndne_f32_e32 v13, v13
	v_mul_f32_e32 v14, v134, v21
	v_mul_f32_e32 v15, v134, v139
	v_and_b32_e32 v55, 0xffff0000, v4
	v_bfe_u32 v4, v36, 16, 1
	v_rndne_f32_e32 v12, v12
	v_cvt_i32_f32_e32 v13, v13
	v_rndne_f32_e32 v14, v14
	v_rndne_f32_e32 v15, v15
	v_add3_u32 v36, v36, v4, s80
	v_bfe_u32 v4, v37, 16, 1
	v_cvt_i32_f32_e32 v12, v12
	v_cvt_i32_f32_sdwa v14, v14 dst_sel:WORD_1 dst_unused:UNUSED_PAD src0_sel:DWORD
	v_cvt_i32_f32_e32 v15, v15
	v_add3_u32 v4, v37, v4, s80
	v_and_b32_e32 v37, 0xffff0000, v4
	v_bfe_u32 v4, v38, 16, 1
	v_add3_u32 v38, v38, v4, s80
	v_bfe_u32 v4, v39, 16, 1
	v_lshlrev_b32_e32 v13, 8, v13
	v_add3_u32 v4, v39, v4, s80
	v_and_b32_e32 v13, 0xff00, v13
	v_and_b32_e32 v14, 0xff0000, v14
	v_perm_b32 v12, v15, v12, s89
	v_and_b32_e32 v39, 0xffff0000, v4
	v_bfe_u32 v4, v60, 16, 1
	v_or3_b32 v14, v12, v13, v14
	v_mul_f32_e32 v13, v134, v27
	v_add3_u32 v60, v60, v4, s80
	v_bfe_u32 v4, v61, 16, 1
	v_mul_f32_e32 v12, v134, v31
	v_rndne_f32_e32 v13, v13
	v_mul_f32_e32 v15, v134, v35
	v_mul_f32_e32 v16, v134, v19
	v_add3_u32 v4, v61, v4, s80
	v_rndne_f32_e32 v12, v12
	v_cvt_i32_f32_e32 v13, v13
	v_rndne_f32_e32 v15, v15
	v_rndne_f32_e32 v16, v16
	v_and_b32_e32 v61, 0xffff0000, v4
	v_bfe_u32 v4, v62, 16, 1
	v_cvt_i32_f32_e32 v12, v12
	v_cvt_i32_f32_sdwa v15, v15 dst_sel:WORD_1 dst_unused:UNUSED_PAD src0_sel:DWORD
	v_cvt_i32_f32_e32 v16, v16
	v_add3_u32 v62, v62, v4, s80
	v_bfe_u32 v4, v63, 16, 1
	v_add3_u32 v4, v63, v4, s80
	v_and_b32_e32 v63, 0xffff0000, v4
	v_bfe_u32 v4, v56, 16, 1
	v_lshlrev_b32_e32 v13, 8, v13
	v_add3_u32 v56, v56, v4, s80
	v_bfe_u32 v4, v57, 16, 1
	v_and_b32_e32 v13, 0xff00, v13
	v_and_b32_e32 v15, 0xff0000, v15
	v_perm_b32 v12, v16, v12, s89
	v_add3_u32 v4, v57, v4, s80
	v_or3_b32 v15, v12, v13, v15
	v_add_co_u32_e32 v12, vcc, s91, v6
	v_and_b32_e32 v57, 0xffff0000, v4
	v_bfe_u32 v4, v58, 16, 1
	v_addc_co_u32_e32 v13, vcc, 0, v7, vcc
	v_add3_u32 v58, v58, v4, s80
	v_bfe_u32 v4, v59, 16, 1
	global_store_dwordx2 v[12:13], v[14:15], off nt
	v_and_b32_e32 v15, 0xffff0000, v40
	v_add3_u32 v4, v59, v4, s80
	v_and_b32_e32 v14, 0xffff0000, v44
	v_mul_f32_e32 v15, v2, v15
	v_and_b32_e32 v16, 0xffff0000, v52
	v_and_b32_e32 v17, 0xffff0000, v36
	v_and_b32_e32 v59, 0xffff0000, v4
	v_bfe_u32 v4, v64, 16, 1
	v_mul_f32_e32 v14, v2, v14
	v_rndne_f32_e32 v15, v15
	v_mul_f32_e32 v16, v2, v16
	v_mul_f32_e32 v17, v2, v17
	v_add3_u32 v64, v64, v4, s80
	v_bfe_u32 v4, v65, 16, 1
	v_rndne_f32_e32 v14, v14
	v_cvt_i32_f32_e32 v15, v15
	v_rndne_f32_e32 v16, v16
	v_rndne_f32_e32 v17, v17
	v_add3_u32 v4, v65, v4, s80
	v_cvt_i32_f32_e32 v14, v14
	v_cvt_i32_f32_sdwa v16, v16 dst_sel:WORD_1 dst_unused:UNUSED_PAD src0_sel:DWORD
	v_cvt_i32_f32_e32 v17, v17
	v_and_b32_e32 v65, 0xffff0000, v4
	v_bfe_u32 v4, v66, 16, 1
	v_add3_u32 v66, v66, v4, s80
	v_bfe_u32 v4, v67, 16, 1
	v_add3_u32 v4, v67, v4, s80
	v_lshlrev_b32_e32 v15, 8, v15
	v_and_b32_e32 v67, 0xffff0000, v4
	v_bfe_u32 v4, v48, 16, 1
	v_and_b32_e32 v15, 0xff00, v15
	v_and_b32_e32 v16, 0xff0000, v16
	v_perm_b32 v14, v17, v14, s89
	v_add3_u32 v48, v48, v4, s80
	v_or3_b32 v14, v14, v15, v16
	v_and_b32_e32 v16, 0xffff0000, v56
	v_and_b32_e32 v15, 0xffff0000, v60
	v_mul_f32_e32 v16, v2, v16
	v_and_b32_e32 v17, 0xffff0000, v64
	v_and_b32_e32 v18, 0xffff0000, v48
	v_mul_f32_e32 v15, v2, v15
	v_rndne_f32_e32 v16, v16
	v_mul_f32_e32 v17, v2, v17
	v_mul_f32_e32 v18, v2, v18
	v_rndne_f32_e32 v15, v15
	v_cvt_i32_f32_e32 v16, v16
	v_rndne_f32_e32 v17, v17
	v_rndne_f32_e32 v18, v18
	v_cvt_i32_f32_e32 v15, v15
	v_cvt_i32_f32_sdwa v17, v17 dst_sel:WORD_1 dst_unused:UNUSED_PAD src0_sel:DWORD
	v_cvt_i32_f32_e32 v18, v18
	v_lshlrev_b32_e32 v16, 8, v16
	v_and_b32_e32 v16, 0xff00, v16
	v_and_b32_e32 v17, 0xff0000, v17
	v_perm_b32 v15, v18, v15, s89
	v_or3_b32 v15, v15, v16, v17
	global_store_dwordx2 v[6:7], v[14:15], off offset:512 nt
	v_mul_f32_e32 v15, v132, v41
	v_mul_f32_e32 v14, v132, v45
	v_rndne_f32_e32 v15, v15
	v_mul_f32_e32 v16, v132, v53
	v_mul_f32_e32 v17, v132, v37
	v_rndne_f32_e32 v14, v14
	v_cvt_i32_f32_e32 v15, v15
	v_rndne_f32_e32 v16, v16
	v_rndne_f32_e32 v17, v17
	v_cvt_i32_f32_e32 v14, v14
	v_cvt_i32_f32_sdwa v16, v16 dst_sel:WORD_1 dst_unused:UNUSED_PAD src0_sel:DWORD
	v_cvt_i32_f32_e32 v17, v17
	v_bfe_u32 v4, v49, 16, 1
	v_lshlrev_b32_e32 v15, 8, v15
	v_add3_u32 v4, v49, v4, s80
	v_and_b32_e32 v15, 0xff00, v15
	v_and_b32_e32 v16, 0xff0000, v16
	v_perm_b32 v14, v17, v14, s89
	v_and_b32_e32 v49, 0xffff0000, v4
	v_or3_b32 v14, v14, v15, v16
	v_mul_f32_e32 v16, v132, v57
	v_mul_f32_e32 v15, v132, v61
	v_rndne_f32_e32 v16, v16
	v_mul_f32_e32 v17, v132, v65
	v_mul_f32_e32 v18, v132, v49
	v_rndne_f32_e32 v15, v15
	v_cvt_i32_f32_e32 v16, v16
	v_rndne_f32_e32 v17, v17
	v_rndne_f32_e32 v18, v18
	v_cvt_i32_f32_e32 v15, v15
	v_cvt_i32_f32_sdwa v17, v17 dst_sel:WORD_1 dst_unused:UNUSED_PAD src0_sel:DWORD
	v_cvt_i32_f32_e32 v18, v18
	v_lshlrev_b32_e32 v16, 8, v16
	v_and_b32_e32 v16, 0xff00, v16
	v_and_b32_e32 v17, 0xff0000, v17
	v_perm_b32 v15, v18, v15, s89
	v_or3_b32 v15, v15, v16, v17
	global_store_dwordx2 v[10:11], v[14:15], off offset:512 nt
	v_and_b32_e32 v15, 0xffff0000, v42
	v_and_b32_e32 v14, 0xffff0000, v46
	v_mul_f32_e32 v15, v133, v15
	v_and_b32_e32 v16, 0xffff0000, v54
	v_and_b32_e32 v17, 0xffff0000, v38
	v_mul_f32_e32 v14, v133, v14
	v_rndne_f32_e32 v15, v15
	v_mul_f32_e32 v16, v133, v16
	v_mul_f32_e32 v17, v133, v17
	v_rndne_f32_e32 v14, v14
	v_cvt_i32_f32_e32 v15, v15
	v_rndne_f32_e32 v16, v16
	v_rndne_f32_e32 v17, v17
	v_cvt_i32_f32_e32 v14, v14
	v_cvt_i32_f32_sdwa v16, v16 dst_sel:WORD_1 dst_unused:UNUSED_PAD src0_sel:DWORD
	v_cvt_i32_f32_e32 v17, v17
	v_lshlrev_b32_e32 v15, 8, v15
	v_bfe_u32 v4, v50, 16, 1
	v_and_b32_e32 v15, 0xff00, v15
	v_and_b32_e32 v16, 0xff0000, v16
	v_perm_b32 v14, v17, v14, s89
	v_add3_u32 v50, v50, v4, s80
	v_or3_b32 v14, v14, v15, v16
	v_and_b32_e32 v16, 0xffff0000, v58
	v_and_b32_e32 v15, 0xffff0000, v62
	v_mul_f32_e32 v16, v133, v16
	v_and_b32_e32 v17, 0xffff0000, v66
	v_and_b32_e32 v18, 0xffff0000, v50
	v_mul_f32_e32 v15, v133, v15
	v_rndne_f32_e32 v16, v16
	v_mul_f32_e32 v17, v133, v17
	v_mul_f32_e32 v18, v133, v18
	v_rndne_f32_e32 v15, v15
	v_cvt_i32_f32_e32 v16, v16
	v_rndne_f32_e32 v17, v17
	v_rndne_f32_e32 v18, v18
	v_cvt_i32_f32_e32 v15, v15
	v_cvt_i32_f32_sdwa v17, v17 dst_sel:WORD_1 dst_unused:UNUSED_PAD src0_sel:DWORD
	v_cvt_i32_f32_e32 v18, v18
	v_lshlrev_b32_e32 v16, 8, v16
	v_and_b32_e32 v16, 0xff00, v16
	v_and_b32_e32 v17, 0xff0000, v17
	v_perm_b32 v15, v18, v15, s89
	v_or3_b32 v15, v15, v16, v17
	global_store_dwordx2 v[8:9], v[14:15], off offset:512 nt
	v_mul_f32_e32 v15, v134, v43
	v_mul_f32_e32 v14, v134, v47
	v_rndne_f32_e32 v15, v15
	v_mul_f32_e32 v16, v134, v55
	v_mul_f32_e32 v17, v134, v39
	v_rndne_f32_e32 v14, v14
	v_cvt_i32_f32_e32 v15, v15
	v_rndne_f32_e32 v16, v16
	v_rndne_f32_e32 v17, v17
	v_cvt_i32_f32_e32 v14, v14
	v_cvt_i32_f32_sdwa v16, v16 dst_sel:WORD_1 dst_unused:UNUSED_PAD src0_sel:DWORD
	v_cvt_i32_f32_e32 v17, v17
	v_bfe_u32 v4, v51, 16, 1
	v_lshlrev_b32_e32 v15, 8, v15
	v_add3_u32 v4, v51, v4, s80
	v_and_b32_e32 v15, 0xff00, v15
	v_and_b32_e32 v16, 0xff0000, v16
	v_perm_b32 v14, v17, v14, s89
	v_and_b32_e32 v51, 0xffff0000, v4
	v_or3_b32 v14, v14, v15, v16
	v_mul_f32_e32 v16, v134, v59
	v_mul_f32_e32 v15, v134, v63
	v_rndne_f32_e32 v16, v16
	v_mul_f32_e32 v17, v134, v67
	v_mul_f32_e32 v18, v134, v51
	v_rndne_f32_e32 v15, v15
	v_cvt_i32_f32_e32 v16, v16
	v_rndne_f32_e32 v17, v17
	v_rndne_f32_e32 v18, v18
	v_cvt_i32_f32_e32 v15, v15
	v_cvt_i32_f32_sdwa v17, v17 dst_sel:WORD_1 dst_unused:UNUSED_PAD src0_sel:DWORD
	v_cvt_i32_f32_e32 v18, v18
	v_lshlrev_b32_e32 v16, 8, v16
	v_bfe_u32 v141, v83, 16, 1
	v_and_b32_e32 v16, 0xff00, v16
	v_and_b32_e32 v17, 0xff0000, v17
	v_perm_b32 v15, v18, v15, s89
	v_bfe_u32 v137, v73, 16, 1
	v_bfe_u32 v165, v131, 16, 1
	v_bfe_u32 v168, v76, 16, 1
	v_add3_u32 v141, v83, v141, s80
	v_bfe_u32 v83, v68, 16, 1
	v_or3_b32 v15, v15, v16, v17
	v_add3_u32 v73, v73, v137, s80
	v_add3_u32 v165, v131, v165, s80
	v_add3_u32 v137, v76, v168, s80
	v_add3_u32 v131, v68, v83, s80
	global_store_dwordx2 v[12:13], v[14:15], off offset:512 nt
	v_and_b32_e32 v15, 0xffff0000, v136
	v_and_b32_e32 v14, 0xffff0000, v137
	v_mul_f32_e32 v15, v2, v15
	v_and_b32_e32 v16, 0xffff0000, v135
	v_and_b32_e32 v17, 0xffff0000, v131
	v_mul_f32_e32 v14, v2, v14
	v_rndne_f32_e32 v15, v15
	v_mul_f32_e32 v16, v2, v16
	v_mul_f32_e32 v17, v2, v17
	v_rndne_f32_e32 v14, v14
	v_cvt_i32_f32_e32 v15, v15
	v_rndne_f32_e32 v16, v16
	v_rndne_f32_e32 v17, v17
	v_cvt_i32_f32_e32 v14, v14
	v_cvt_i32_f32_sdwa v16, v16 dst_sel:WORD_1 dst_unused:UNUSED_PAD src0_sel:DWORD
	v_cvt_i32_f32_e32 v17, v17
	v_bfe_u32 v145, v95, 16, 1
	v_bfe_u32 v143, v71, 16, 1
	v_bfe_u32 v161, v127, 16, 1
	v_add3_u32 v145, v95, v145, s80
	v_bfe_u32 v95, v88, 16, 1
	v_lshlrev_b32_e32 v15, 8, v15
	v_bfe_u32 v164, v129, 16, 1
	v_add3_u32 v71, v71, v143, s80
	v_bfe_u32 v143, v92, 16, 1
	v_add3_u32 v161, v127, v161, s80
	v_add3_u32 v127, v88, v95, s80
	v_and_b32_e32 v15, 0xff00, v15
	v_and_b32_e32 v16, 0xff0000, v16
	v_perm_b32 v14, v17, v14, s89
	v_add3_u32 v164, v129, v164, s80
	v_add3_u32 v129, v92, v143, s80
	v_or3_b32 v14, v14, v15, v16
	v_and_b32_e32 v16, 0xffff0000, v127
	v_and_b32_e32 v15, 0xffff0000, v129
	v_mul_f32_e32 v16, v2, v16
	v_and_b32_e32 v17, 0xffff0000, v125
	v_and_b32_e32 v18, 0xffff0000, v123
	v_mul_f32_e32 v15, v2, v15
	v_rndne_f32_e32 v16, v16
	v_mul_f32_e32 v17, v2, v17
	v_mul_f32_e32 v18, v2, v18
	v_rndne_f32_e32 v15, v15
	v_cvt_i32_f32_e32 v16, v16
	v_rndne_f32_e32 v17, v17
	v_rndne_f32_e32 v18, v18
	v_cvt_i32_f32_e32 v15, v15
	v_cvt_i32_f32_sdwa v17, v17 dst_sel:WORD_1 dst_unused:UNUSED_PAD src0_sel:DWORD
	v_cvt_i32_f32_e32 v18, v18
	v_lshlrev_b32_e32 v16, 8, v16
	v_bfe_u32 v140, v81, 16, 1
	v_bfe_u32 v142, v69, 16, 1
	v_bfe_u32 v144, v93, 16, 1
	v_bfe_u32 v159, v103, 16, 1
	v_bfe_u32 v178, v122, 16, 1
	v_and_b32_e32 v16, 0xff00, v16
	v_and_b32_e32 v17, 0xff0000, v17
	v_perm_b32 v15, v18, v15, s89
	v_bfe_u32 v156, v113, 16, 1
	v_add3_u32 v140, v81, v140, s80
	v_add3_u32 v69, v69, v142, s80
	v_add3_u32 v93, v93, v144, s80
	v_bfe_u32 v144, v94, 16, 1
	v_add3_u32 v159, v103, v159, s80
	v_bfe_u32 v103, v124, 16, 1
	v_bfe_u32 v177, v120, 16, 1
	v_bfe_u32 v182, v118, 16, 1
	v_add3_u32 v78, v122, v178, s80
	v_and_b32_e32 v122, 0xffff0000, v73
	v_or3_b32 v15, v15, v16, v17
	v_add3_u32 v156, v113, v156, s80
	v_add3_u32 v113, v94, v144, s80
	v_add3_u32 v95, v124, v103, s80
	v_add3_u32 v94, v120, v177, s80
	v_add3_u32 v72, v118, v182, s80
	v_and_b32_e32 v124, 0xffff0000, v77
	v_and_b32_e32 v120, 0xffff0000, v140
	v_and_b32_e32 v118, 0xffff0000, v69
	global_store_dwordx2 v[6:7], v[14:15], off offset:1024 nt
	v_mul_f32_e32 v15, v132, v122
	v_mul_f32_e32 v14, v132, v124
	v_rndne_f32_e32 v15, v15
	v_mul_f32_e32 v16, v132, v120
	v_mul_f32_e32 v17, v132, v118
	v_rndne_f32_e32 v14, v14
	v_cvt_i32_f32_e32 v15, v15
	v_rndne_f32_e32 v16, v16
	v_rndne_f32_e32 v17, v17
	v_cvt_i32_f32_e32 v14, v14
	v_cvt_i32_f32_sdwa v16, v16 dst_sel:WORD_1 dst_unused:UNUSED_PAD src0_sel:DWORD
	v_cvt_i32_f32_e32 v17, v17
	v_bfe_u32 v146, v89, 16, 1
	v_bfe_u32 v148, v97, 16, 1
	v_bfe_u32 v150, v85, 16, 1
	v_bfe_u32 v152, v109, 16, 1
	v_bfe_u32 v166, v117, 16, 1
	v_bfe_u32 v81, v82, 16, 1
	v_add3_u32 v89, v89, v146, s80
	v_bfe_u32 v174, v114, 16, 1
	v_lshlrev_b32_e32 v15, 8, v15
	v_bfe_u32 v155, v107, 16, 1
	v_add3_u32 v148, v97, v148, s80
	v_bfe_u32 v97, v98, 16, 1
	v_add3_u32 v85, v85, v150, s80
	v_add3_u32 v152, v109, v152, s80
	v_bfe_u32 v109, v110, 16, 1
	v_bfe_u32 v173, v112, 16, 1
	v_bfe_u32 v181, v116, 16, 1
	v_add3_u32 v166, v117, v166, s80
	v_add3_u32 v117, v82, v81, s80
	v_add3_u32 v81, v114, v174, s80
	v_and_b32_e32 v114, 0xffff0000, v89
	v_and_b32_e32 v15, 0xff00, v15
	v_and_b32_e32 v16, 0xff0000, v16
	v_perm_b32 v14, v17, v14, s89
	v_add3_u32 v155, v107, v155, s80
	v_add3_u32 v107, v98, v97, s80
	v_add3_u32 v83, v110, v109, s80
	v_add3_u32 v97, v112, v173, s80
	v_add3_u32 v88, v116, v181, s80
	v_and_b32_e32 v116, 0xffff0000, v93
	v_and_b32_e32 v112, 0xffff0000, v148
	v_and_b32_e32 v110, 0xffff0000, v85
	v_or3_b32 v14, v14, v15, v16
	v_mul_f32_e32 v16, v132, v114
	v_mul_f32_e32 v15, v132, v116
	v_rndne_f32_e32 v16, v16
	v_mul_f32_e32 v17, v132, v112
	v_mul_f32_e32 v18, v132, v110
	v_rndne_f32_e32 v15, v15
	v_cvt_i32_f32_e32 v16, v16
	v_rndne_f32_e32 v17, v17
	v_rndne_f32_e32 v18, v18
	v_cvt_i32_f32_e32 v15, v15
	v_cvt_i32_f32_sdwa v17, v17 dst_sel:WORD_1 dst_unused:UNUSED_PAD src0_sel:DWORD
	v_cvt_i32_f32_e32 v18, v18
	v_lshlrev_b32_e32 v16, 8, v16
	v_bfe_u32 v167, v119, 16, 1
	v_bfe_u32 v170, v74, 16, 1
	v_and_b32_e32 v16, 0xff00, v16
	v_and_b32_e32 v17, 0xff0000, v17
	v_perm_b32 v15, v18, v15, s89
	v_bfe_u32 v157, v115, 16, 1
	v_bfe_u32 v142, v70, 16, 1
	v_add3_u32 v167, v119, v167, s80
	v_add3_u32 v119, v74, v170, s80
	v_or3_b32 v15, v15, v16, v17
	v_add3_u32 v157, v115, v157, s80
	v_add3_u32 v115, v70, v142, s80
	global_store_dwordx2 v[10:11], v[14:15], off offset:1024 nt
	v_and_b32_e32 v15, 0xffff0000, v119
	v_and_b32_e32 v14, 0xffff0000, v121
	v_mul_f32_e32 v15, v133, v15
	v_and_b32_e32 v16, 0xffff0000, v117
	v_and_b32_e32 v17, 0xffff0000, v115
	v_mul_f32_e32 v14, v133, v14
	v_rndne_f32_e32 v15, v15
	v_mul_f32_e32 v16, v133, v16
	v_mul_f32_e32 v17, v133, v17
	v_rndne_f32_e32 v14, v14
	v_cvt_i32_f32_e32 v15, v15
	v_rndne_f32_e32 v16, v16
	v_rndne_f32_e32 v17, v17
	v_cvt_i32_f32_e32 v14, v14
	v_cvt_i32_f32_sdwa v16, v16 dst_sel:WORD_1 dst_unused:UNUSED_PAD src0_sel:DWORD
	v_cvt_i32_f32_e32 v17, v17
	v_bfe_u32 v153, v111, 16, 1
	v_bfe_u32 v146, v90, 16, 1
	v_lshlrev_b32_e32 v15, 8, v15
	v_bfe_u32 v154, v105, 16, 1
	v_bfe_u32 v150, v86, 16, 1
	v_add3_u32 v153, v111, v153, s80
	v_add3_u32 v111, v90, v146, s80
	v_and_b32_e32 v15, 0xff00, v15
	v_and_b32_e32 v16, 0xff0000, v16
	v_perm_b32 v14, v17, v14, s89
	v_add3_u32 v154, v105, v154, s80
	v_add3_u32 v105, v86, v150, s80
	v_or3_b32 v14, v14, v15, v16
	v_and_b32_e32 v16, 0xffff0000, v111
	v_and_b32_e32 v15, 0xffff0000, v113
	v_mul_f32_e32 v16, v133, v16
	v_and_b32_e32 v17, 0xffff0000, v107
	v_and_b32_e32 v18, 0xffff0000, v105
	v_mul_f32_e32 v15, v133, v15
	v_rndne_f32_e32 v16, v16
	v_mul_f32_e32 v17, v133, v17
	v_mul_f32_e32 v18, v133, v18
	v_rndne_f32_e32 v15, v15
	v_cvt_i32_f32_e32 v16, v16
	v_rndne_f32_e32 v17, v17
	v_rndne_f32_e32 v18, v18
	v_cvt_i32_f32_e32 v15, v15
	v_cvt_i32_f32_sdwa v17, v17 dst_sel:WORD_1 dst_unused:UNUSED_PAD src0_sel:DWORD
	v_cvt_i32_f32_e32 v18, v18
	v_lshlrev_b32_e32 v16, 8, v16
	v_and_b32_e32 v16, 0xff00, v16
	v_and_b32_e32 v17, 0xff0000, v17
	v_perm_b32 v15, v18, v15, s89
	v_bfe_u32 v171, v104, 16, 1
	v_bfe_u32 v172, v106, 16, 1
	v_or3_b32 v15, v15, v16, v17
	v_add3_u32 v98, v104, v171, s80
	v_add3_u32 v82, v106, v172, s80
	v_and_b32_e32 v109, 0xffff0000, v169
	v_and_b32_e32 v106, 0xffff0000, v141
	v_and_b32_e32 v104, 0xffff0000, v71
	global_store_dwordx2 v[8:9], v[14:15], off offset:1024 nt
	v_mul_f32_e32 v15, v134, v108
	v_mul_f32_e32 v14, v134, v109
	v_rndne_f32_e32 v15, v15
	v_mul_f32_e32 v16, v134, v106
	v_mul_f32_e32 v17, v134, v104
	v_rndne_f32_e32 v14, v14
	v_cvt_i32_f32_e32 v15, v15
	v_rndne_f32_e32 v16, v16
	v_rndne_f32_e32 v17, v17
	v_cvt_i32_f32_e32 v14, v14
	v_cvt_i32_f32_sdwa v16, v16 dst_sel:WORD_1 dst_unused:UNUSED_PAD src0_sel:DWORD
	v_cvt_i32_f32_e32 v17, v17
	v_bfe_u32 v158, v101, 16, 1
	v_add3_u32 v158, v101, v158, s80
	v_bfe_u32 v101, v102, 16, 1
	v_lshlrev_b32_e32 v15, 8, v15
	v_bfe_u32 v175, v100, 16, 1
	v_add3_u32 v80, v102, v101, s80
	v_and_b32_e32 v102, 0xffff0000, v147
	v_and_b32_e32 v15, 0xff00, v15
	v_and_b32_e32 v16, 0xff0000, v16
	v_perm_b32 v14, v17, v14, s89
	v_add3_u32 v96, v100, v175, s80
	v_and_b32_e32 v103, 0xffff0000, v145
	v_and_b32_e32 v101, 0xffff0000, v149
	v_and_b32_e32 v100, 0xffff0000, v87
	v_or3_b32 v14, v14, v15, v16
	v_mul_f32_e32 v16, v134, v102
	v_mul_f32_e32 v15, v134, v103
	v_rndne_f32_e32 v16, v16
	v_mul_f32_e32 v17, v134, v101
	v_mul_f32_e32 v18, v134, v100
	v_rndne_f32_e32 v15, v15
	v_cvt_i32_f32_e32 v16, v16
	v_rndne_f32_e32 v17, v17
	v_rndne_f32_e32 v18, v18
	v_cvt_i32_f32_e32 v15, v15
	v_cvt_i32_f32_sdwa v17, v17 dst_sel:WORD_1 dst_unused:UNUSED_PAD src0_sel:DWORD
	v_cvt_i32_f32_e32 v18, v18
	v_lshlrev_b32_e32 v16, 8, v16
	v_and_b32_e32 v16, 0xff00, v16
	v_and_b32_e32 v17, 0xff0000, v17
	v_perm_b32 v15, v18, v15, s89
	v_or3_b32 v15, v15, v16, v17
	global_store_dwordx2 v[12:13], v[14:15], off offset:1024 nt
	v_and_b32_e32 v15, 0xffff0000, v98
	v_and_b32_e32 v14, 0xffff0000, v99
	v_mul_f32_e32 v15, v2, v15
	v_and_b32_e32 v16, 0xffff0000, v97
	v_and_b32_e32 v17, 0xffff0000, v96
	v_mul_f32_e32 v14, v2, v14
	v_rndne_f32_e32 v15, v15
	v_mul_f32_e32 v16, v2, v16
	v_mul_f32_e32 v17, v2, v17
	v_rndne_f32_e32 v14, v14
	v_cvt_i32_f32_e32 v15, v15
	v_rndne_f32_e32 v16, v16
	v_rndne_f32_e32 v17, v17
	v_cvt_i32_f32_e32 v14, v14
	v_cvt_i32_f32_sdwa v16, v16 dst_sel:WORD_1 dst_unused:UNUSED_PAD src0_sel:DWORD
	v_cvt_i32_f32_e32 v17, v17
	v_lshlrev_b32_e32 v15, 8, v15
	v_and_b32_e32 v15, 0xff00, v15
	v_and_b32_e32 v16, 0xff0000, v16
	v_perm_b32 v14, v17, v14, s89
	v_or3_b32 v14, v14, v15, v16
	v_and_b32_e32 v16, 0xffff0000, v94
	v_and_b32_e32 v15, 0xffff0000, v95
	v_mul_f32_e32 v16, v2, v16
	v_and_b32_e32 v17, 0xffff0000, v91
	v_and_b32_e32 v18, 0xffff0000, v88
	v_mul_f32_e32 v15, v2, v15
	v_rndne_f32_e32 v16, v16
	v_mul_f32_e32 v17, v2, v17
	v_mul_f32_e32 v18, v2, v18
	v_rndne_f32_e32 v15, v15
	v_cvt_i32_f32_e32 v16, v16
	v_rndne_f32_e32 v17, v17
	v_rndne_f32_e32 v18, v18
	v_cvt_i32_f32_e32 v15, v15
	v_cvt_i32_f32_sdwa v17, v17 dst_sel:WORD_1 dst_unused:UNUSED_PAD src0_sel:DWORD
	v_cvt_i32_f32_e32 v18, v18
	v_lshlrev_b32_e32 v16, 8, v16
	v_and_b32_e32 v16, 0xff00, v16
	v_and_b32_e32 v17, 0xff0000, v17
	v_perm_b32 v15, v18, v15, s89
	v_and_b32_e32 v92, 0xffff0000, v154
	v_or3_b32 v15, v15, v16, v17
	v_and_b32_e32 v93, 0xffff0000, v152
	v_and_b32_e32 v90, 0xffff0000, v156
	v_and_b32_e32 v89, 0xffff0000, v158
	global_store_dwordx2 v[6:7], v[14:15], off offset:1536 nt
	v_mul_f32_e32 v7, v132, v92
	v_mul_f32_e32 v6, v132, v93
	v_rndne_f32_e32 v7, v7
	v_mul_f32_e32 v14, v132, v90
	v_mul_f32_e32 v15, v132, v89
	v_rndne_f32_e32 v6, v6
	v_cvt_i32_f32_e32 v7, v7
	v_rndne_f32_e32 v14, v14
	v_rndne_f32_e32 v15, v15
	v_cvt_i32_f32_e32 v6, v6
	v_cvt_i32_f32_sdwa v14, v14 dst_sel:WORD_1 dst_unused:UNUSED_PAD src0_sel:DWORD
	v_cvt_i32_f32_e32 v15, v15
	v_lshlrev_b32_e32 v7, 8, v7
	v_and_b32_e32 v86, 0xffff0000, v162
	v_and_b32_e32 v7, 0xff00, v7
	v_and_b32_e32 v14, 0xff0000, v14
	v_perm_b32 v6, v15, v6, s89
	v_and_b32_e32 v87, 0xffff0000, v160
	v_and_b32_e32 v85, 0xffff0000, v164
	v_and_b32_e32 v84, 0xffff0000, v166
	v_or3_b32 v6, v6, v7, v14
	v_mul_f32_e32 v14, v132, v86
	v_mul_f32_e32 v7, v132, v87
	v_rndne_f32_e32 v14, v14
	v_mul_f32_e32 v15, v132, v85
	v_mul_f32_e32 v16, v132, v84
	v_rndne_f32_e32 v7, v7
	v_cvt_i32_f32_e32 v14, v14
	v_rndne_f32_e32 v15, v15
	v_rndne_f32_e32 v16, v16
	v_cvt_i32_f32_e32 v7, v7
	v_cvt_i32_f32_sdwa v15, v15 dst_sel:WORD_1 dst_unused:UNUSED_PAD src0_sel:DWORD
	v_cvt_i32_f32_e32 v16, v16
	v_lshlrev_b32_e32 v14, 8, v14
	v_and_b32_e32 v14, 0xff00, v14
	v_and_b32_e32 v15, 0xff0000, v15
	v_perm_b32 v7, v16, v7, s89
	v_or3_b32 v7, v7, v14, v15
	global_store_dwordx2 v[10:11], v[6:7], off offset:1536 nt
	v_and_b32_e32 v7, 0xffff0000, v82
	v_and_b32_e32 v6, 0xffff0000, v83
	v_mul_f32_e32 v7, v133, v7
	v_and_b32_e32 v10, 0xffff0000, v81
	v_and_b32_e32 v11, 0xffff0000, v80
	v_mul_f32_e32 v6, v133, v6
	v_rndne_f32_e32 v7, v7
	v_mul_f32_e32 v10, v133, v10
	v_mul_f32_e32 v11, v133, v11
	v_rndne_f32_e32 v6, v6
	v_cvt_i32_f32_e32 v7, v7
	v_rndne_f32_e32 v10, v10
	v_rndne_f32_e32 v11, v11
	v_cvt_i32_f32_e32 v6, v6
	v_cvt_i32_f32_sdwa v10, v10 dst_sel:WORD_1 dst_unused:UNUSED_PAD src0_sel:DWORD
	v_cvt_i32_f32_e32 v11, v11
	v_lshlrev_b32_e32 v7, 8, v7
	v_and_b32_e32 v7, 0xff00, v7
	v_and_b32_e32 v10, 0xff0000, v10
	v_perm_b32 v6, v11, v6, s89
	v_or3_b32 v6, v6, v7, v10
	v_and_b32_e32 v10, 0xffff0000, v78
	v_and_b32_e32 v7, 0xffff0000, v79
	v_mul_f32_e32 v10, v133, v10
	v_and_b32_e32 v11, 0xffff0000, v75
	v_and_b32_e32 v14, 0xffff0000, v72
	v_mul_f32_e32 v7, v133, v7
	v_rndne_f32_e32 v10, v10
	v_mul_f32_e32 v11, v133, v11
	v_mul_f32_e32 v14, v133, v14
	v_rndne_f32_e32 v7, v7
	v_cvt_i32_f32_e32 v10, v10
	v_rndne_f32_e32 v11, v11
	v_rndne_f32_e32 v14, v14
	v_cvt_i32_f32_e32 v7, v7
	v_cvt_i32_f32_sdwa v11, v11 dst_sel:WORD_1 dst_unused:UNUSED_PAD src0_sel:DWORD
	v_cvt_i32_f32_e32 v14, v14
	v_lshlrev_b32_e32 v10, 8, v10
	v_and_b32_e32 v10, 0xff00, v10
	v_and_b32_e32 v11, 0xff0000, v11
	v_perm_b32 v7, v14, v7, s89
	v_and_b32_e32 v76, 0xffff0000, v155
	v_or3_b32 v7, v7, v10, v11
	v_and_b32_e32 v77, 0xffff0000, v153
	v_and_b32_e32 v74, 0xffff0000, v157
	v_and_b32_e32 v73, 0xffff0000, v159
	global_store_dwordx2 v[8:9], v[6:7], off offset:1536 nt
	v_mul_f32_e32 v7, v134, v76
	v_mul_f32_e32 v6, v134, v77
	v_rndne_f32_e32 v7, v7
	v_mul_f32_e32 v8, v134, v74
	v_mul_f32_e32 v9, v134, v73
	v_rndne_f32_e32 v6, v6
	v_cvt_i32_f32_e32 v7, v7
	v_rndne_f32_e32 v8, v8
	v_rndne_f32_e32 v9, v9
	v_cvt_i32_f32_e32 v6, v6
	v_cvt_i32_f32_sdwa v8, v8 dst_sel:WORD_1 dst_unused:UNUSED_PAD src0_sel:DWORD
	v_cvt_i32_f32_e32 v9, v9
	v_lshlrev_b32_e32 v7, 8, v7
	v_and_b32_e32 v70, 0xffff0000, v163
	v_and_b32_e32 v7, 0xff00, v7
	v_and_b32_e32 v8, 0xff0000, v8
	v_perm_b32 v6, v9, v6, s89
	v_and_b32_e32 v71, 0xffff0000, v161
	v_and_b32_e32 v69, 0xffff0000, v165
	v_and_b32_e32 v68, 0xffff0000, v167
	v_or3_b32 v6, v6, v7, v8
	v_mul_f32_e32 v8, v134, v70
	v_mul_f32_e32 v7, v134, v71
	v_rndne_f32_e32 v8, v8
	v_mul_f32_e32 v9, v134, v69
	v_mul_f32_e32 v10, v134, v68
	v_rndne_f32_e32 v7, v7
	v_cvt_i32_f32_e32 v8, v8
	v_rndne_f32_e32 v9, v9
	v_rndne_f32_e32 v10, v10
	v_cvt_i32_f32_e32 v7, v7
	v_cvt_i32_f32_sdwa v9, v9 dst_sel:WORD_1 dst_unused:UNUSED_PAD src0_sel:DWORD
	v_cvt_i32_f32_e32 v10, v10
	v_lshlrev_b32_e32 v8, 8, v8
	v_ashrrev_i32_e32 v209, 31, v208
	v_and_b32_e32 v8, 0xff00, v8
	v_and_b32_e32 v9, 0xff0000, v9
	v_perm_b32 v7, v10, v7, s89
	v_lshlrev_b64 v[4:5], 12, v[208:209]
	v_or3_b32 v7, v7, v8, v9
	v_lshl_add_u64 v[4:5], v[204:205], 0, v[4:5]
	global_store_dwordx2 v[12:13], v[6:7], off offset:1536 nt
	s_mov_b64 s[18:19], 0
	v_mov_b32_e32 v6, v235
.LBB0_2246:
	ds_read_b128 v[8:11], v6
	ds_read_b128 v[12:15], v6 offset:8192
	ds_read_b128 v[16:19], v6 offset:16384
	ds_read_b128 v[20:23], v6 offset:24576
	v_lshl_add_u64 v[24:25], v[4:5], 0, s[18:19]
	s_waitcnt lgkmcnt(3)
	v_lshlrev_b32_e32 v26, 16, v10
	v_lshlrev_b32_e32 v7, 16, v8
	v_mul_f32_e32 v26, v2, v26
	s_waitcnt lgkmcnt(2)
	v_lshlrev_b32_e32 v27, 16, v12
	v_mul_f32_e32 v7, v2, v7
	v_rndne_f32_e32 v26, v26
	v_mul_f32_e32 v27, v2, v27
	v_lshlrev_b32_e32 v28, 16, v14
	v_rndne_f32_e32 v7, v7
	v_cvt_i32_f32_e32 v26, v26
	v_rndne_f32_e32 v27, v27
	v_mul_f32_e32 v28, v2, v28
	v_cvt_i32_f32_e32 v7, v7
	v_cvt_i32_f32_sdwa v27, v27 dst_sel:WORD_1 dst_unused:UNUSED_PAD src0_sel:DWORD
	v_rndne_f32_e32 v28, v28
	v_cvt_i32_f32_sdwa v28, v28 dst_sel:BYTE_3 dst_unused:UNUSED_PAD src0_sel:DWORD
	v_lshlrev_b32_e32 v26, 8, v26
	v_and_b32_e32 v27, 0xff0000, v27
	v_perm_b32 v7, v26, v7, s76
	v_or3_b32 v26, v7, v28, v27
	s_waitcnt lgkmcnt(1)
	v_lshlrev_b32_e32 v27, 16, v18
	v_lshlrev_b32_e32 v7, 16, v16
	v_mul_f32_e32 v27, v2, v27
	s_waitcnt lgkmcnt(0)
	v_lshlrev_b32_e32 v28, 16, v20
	v_mul_f32_e32 v7, v2, v7
	v_rndne_f32_e32 v27, v27
	v_mul_f32_e32 v28, v2, v28
	v_lshlrev_b32_e32 v29, 16, v22
	v_rndne_f32_e32 v7, v7
	v_cvt_i32_f32_e32 v27, v27
	v_rndne_f32_e32 v28, v28
	v_mul_f32_e32 v29, v2, v29
	v_cvt_i32_f32_e32 v7, v7
	v_cvt_i32_f32_sdwa v28, v28 dst_sel:WORD_1 dst_unused:UNUSED_PAD src0_sel:DWORD
	v_rndne_f32_e32 v29, v29
	v_cvt_i32_f32_sdwa v29, v29 dst_sel:BYTE_3 dst_unused:UNUSED_PAD src0_sel:DWORD
	v_lshlrev_b32_e32 v27, 8, v27
	v_and_b32_e32 v28, 0xff0000, v28
	v_perm_b32 v7, v27, v7, s76
	v_or3_b32 v27, v7, v29, v28
	v_and_b32_e32 v7, 0xffff0000, v8
	v_and_b32_e32 v8, 0xffff0000, v10
	v_mul_f32_e32 v8, v132, v8
	v_and_b32_e32 v10, 0xffff0000, v12
	v_mul_f32_e32 v7, v132, v7
	v_rndne_f32_e32 v8, v8
	v_mul_f32_e32 v10, v132, v10
	v_and_b32_e32 v12, 0xffff0000, v14
	v_rndne_f32_e32 v7, v7
	v_cvt_i32_f32_e32 v8, v8
	v_rndne_f32_e32 v10, v10
	v_mul_f32_e32 v12, v132, v12
	v_cvt_i32_f32_e32 v7, v7
	v_cvt_i32_f32_sdwa v10, v10 dst_sel:WORD_1 dst_unused:UNUSED_PAD src0_sel:DWORD
	v_rndne_f32_e32 v12, v12
	v_cvt_i32_f32_sdwa v12, v12 dst_sel:BYTE_3 dst_unused:UNUSED_PAD src0_sel:DWORD
	v_add_co_u32_e32 v28, vcc, s77, v24
	v_lshlrev_b32_e32 v8, 8, v8
	s_nop 0
	v_addc_co_u32_e32 v29, vcc, 0, v25, vcc
	v_and_b32_e32 v10, 0xff0000, v10
	v_perm_b32 v7, v8, v7, s76
	v_and_b32_e32 v8, 0xffff0000, v18
	global_store_dwordx2 v[28:29], v[26:27], off offset:2048 nt
	v_or3_b32 v26, v7, v12, v10
	v_and_b32_e32 v7, 0xffff0000, v16
	v_mul_f32_e32 v8, v132, v8
	v_and_b32_e32 v10, 0xffff0000, v20
	v_mul_f32_e32 v7, v132, v7
	v_rndne_f32_e32 v8, v8
	v_mul_f32_e32 v10, v132, v10
	v_and_b32_e32 v12, 0xffff0000, v22
	v_rndne_f32_e32 v7, v7
	v_cvt_i32_f32_e32 v8, v8
	v_rndne_f32_e32 v10, v10
	v_mul_f32_e32 v12, v132, v12
	v_cvt_i32_f32_e32 v7, v7
	v_cvt_i32_f32_sdwa v10, v10 dst_sel:WORD_1 dst_unused:UNUSED_PAD src0_sel:DWORD
	v_rndne_f32_e32 v12, v12
	v_cvt_i32_f32_sdwa v12, v12 dst_sel:BYTE_3 dst_unused:UNUSED_PAD src0_sel:DWORD
	v_lshlrev_b32_e32 v8, 8, v8
	v_and_b32_e32 v10, 0xff0000, v10
	v_perm_b32 v7, v8, v7, s76
	v_lshlrev_b32_e32 v8, 16, v11
	v_or3_b32 v27, v7, v12, v10
	v_lshlrev_b32_e32 v7, 16, v9
	v_mul_f32_e32 v8, v133, v8
	v_lshlrev_b32_e32 v10, 16, v13
	v_mul_f32_e32 v7, v133, v7
	v_rndne_f32_e32 v8, v8
	v_mul_f32_e32 v10, v133, v10
	v_lshlrev_b32_e32 v12, 16, v15
	v_rndne_f32_e32 v7, v7
	v_cvt_i32_f32_e32 v8, v8
	v_rndne_f32_e32 v10, v10
	v_mul_f32_e32 v12, v133, v12
	v_cvt_i32_f32_e32 v7, v7
	v_cvt_i32_f32_sdwa v10, v10 dst_sel:WORD_1 dst_unused:UNUSED_PAD src0_sel:DWORD
	v_rndne_f32_e32 v12, v12
	v_cvt_i32_f32_sdwa v12, v12 dst_sel:BYTE_3 dst_unused:UNUSED_PAD src0_sel:DWORD
	v_add_co_u32_e32 v28, vcc, s82, v24
	v_lshlrev_b32_e32 v8, 8, v8
	s_nop 0
	v_addc_co_u32_e32 v29, vcc, 0, v25, vcc
	v_and_b32_e32 v10, 0xff0000, v10
	v_perm_b32 v7, v8, v7, s76
	v_lshlrev_b32_e32 v8, 16, v19
	global_store_dwordx2 v[28:29], v[26:27], off offset:2048 nt
	v_or3_b32 v26, v7, v12, v10
	v_lshlrev_b32_e32 v7, 16, v17
	v_mul_f32_e32 v8, v133, v8
	v_lshlrev_b32_e32 v10, 16, v21
	v_mul_f32_e32 v7, v133, v7
	v_rndne_f32_e32 v8, v8
	v_mul_f32_e32 v10, v133, v10
	v_lshlrev_b32_e32 v12, 16, v23
	v_rndne_f32_e32 v7, v7
	v_cvt_i32_f32_e32 v8, v8
	v_rndne_f32_e32 v10, v10
	v_mul_f32_e32 v12, v133, v12
	v_cvt_i32_f32_e32 v7, v7
	v_cvt_i32_f32_sdwa v10, v10 dst_sel:WORD_1 dst_unused:UNUSED_PAD src0_sel:DWORD
	v_rndne_f32_e32 v12, v12
	v_cvt_i32_f32_sdwa v12, v12 dst_sel:BYTE_3 dst_unused:UNUSED_PAD src0_sel:DWORD
	v_lshlrev_b32_e32 v8, 8, v8
	v_and_b32_e32 v10, 0xff0000, v10
	v_perm_b32 v7, v8, v7, s76
	v_and_b32_e32 v8, 0xffff0000, v11
	v_or3_b32 v27, v7, v12, v10
	v_and_b32_e32 v7, 0xffff0000, v9
	v_mul_f32_e32 v8, v134, v8
	v_and_b32_e32 v9, 0xffff0000, v13
	v_mul_f32_e32 v7, v134, v7
	v_rndne_f32_e32 v8, v8
	v_mul_f32_e32 v9, v134, v9
	v_and_b32_e32 v10, 0xffff0000, v15
	v_rndne_f32_e32 v7, v7
	v_cvt_i32_f32_e32 v8, v8
	v_rndne_f32_e32 v9, v9
	v_mul_f32_e32 v10, v134, v10
	v_cvt_i32_f32_e32 v7, v7
	v_cvt_i32_f32_sdwa v9, v9 dst_sel:WORD_1 dst_unused:UNUSED_PAD src0_sel:DWORD
	v_rndne_f32_e32 v10, v10
	v_cvt_i32_f32_sdwa v10, v10 dst_sel:BYTE_3 dst_unused:UNUSED_PAD src0_sel:DWORD
	v_lshlrev_b32_e32 v8, 8, v8
	v_and_b32_e32 v9, 0xff0000, v9
	v_perm_b32 v7, v8, v7, s76
	v_or3_b32 v8, v7, v10, v9
	v_and_b32_e32 v9, 0xffff0000, v19
	v_and_b32_e32 v7, 0xffff0000, v17
	v_mul_f32_e32 v9, v134, v9
	v_and_b32_e32 v10, 0xffff0000, v21
	v_mul_f32_e32 v7, v134, v7
	v_rndne_f32_e32 v9, v9
	v_mul_f32_e32 v10, v134, v10
	v_and_b32_e32 v11, 0xffff0000, v23
	v_rndne_f32_e32 v7, v7
	v_cvt_i32_f32_e32 v9, v9
	v_rndne_f32_e32 v10, v10
	v_mul_f32_e32 v11, v134, v11
	v_cvt_i32_f32_e32 v7, v7
	v_cvt_i32_f32_sdwa v10, v10 dst_sel:WORD_1 dst_unused:UNUSED_PAD src0_sel:DWORD
	v_rndne_f32_e32 v11, v11
	v_cvt_i32_f32_sdwa v11, v11 dst_sel:BYTE_3 dst_unused:UNUSED_PAD src0_sel:DWORD
	v_add_co_u32_e32 v28, vcc, s83, v24
	v_lshlrev_b32_e32 v9, 8, v9
	s_nop 0
	v_addc_co_u32_e32 v29, vcc, 0, v25, vcc
	v_and_b32_e32 v10, 0xff0000, v10
	v_perm_b32 v7, v9, v7, s76
	s_add_u32 s18, s18, 0x200
	v_or3_b32 v9, v7, v11, v10
	v_add_co_u32_e32 v10, vcc, s97, v24
	s_addc_u32 s19, s19, 0
	s_nop 0
	v_addc_co_u32_e32 v11, vcc, 0, v25, vcc
	v_add_u32_e32 v6, 0x8000, v6
	s_cmpk_lg_i32 s18, 0x800
	global_store_dwordx2 v[28:29], v[26:27], off offset:2048 nt
	global_store_dwordx2 v[10:11], v[8:9], off offset:2048 nt
	s_cbranch_scc1 .LBB0_2246
	s_add_i32 s14, s14, s3
	s_add_i32 s5, s5, s79
	s_add_i32 s4, s4, s3
	v_add_u32_e32 v237, s79, v237
	s_cmpk_gt_i32 s14, 0x337
	v_add_u32_e32 v208, s79, v208
	s_barrier
	s_cbranch_scc0 .LBB0_2007

.LBB0_2353:
	v_ashrrev_i32_e32 v133, 31, v132
	s_waitcnt vmcnt(1)
	v_bfe_u32 v2, v108, 16, 1
	v_lshlrev_b64 v[132:133], 13, v[132:133]
	v_add3_u32 v2, v108, v2, s80
	s_waitcnt vmcnt(0)
	v_bfe_u32 v108, v104, 16, 1
	v_lshl_add_u64 v[132:133], s[10:11], 0, v[132:133]
	v_lshrrev_b32_e32 v2, 16, v2
	v_add3_u32 v104, v104, v108, s80
	v_lshl_add_u64 v[136:137], v[134:135], 1, v[132:133]
	v_and_or_b32 v132, v104, s85, v2
	v_bfe_u32 v2, v112, 16, 1
	v_add3_u32 v2, v112, v2, s80
	v_bfe_u32 v104, v100, 16, 1
	v_lshrrev_b32_e32 v2, 16, v2
	v_add3_u32 v100, v100, v104, s80
	v_and_or_b32 v133, v100, s85, v2
	v_bfe_u32 v2, v124, 16, 1
	v_add3_u32 v2, v124, v2, s80
	v_bfe_u32 v100, v120, 16, 1
	v_lshrrev_b32_e32 v2, 16, v2
	v_add3_u32 v100, v120, v100, s80
	v_and_or_b32 v134, v100, s85, v2
	v_bfe_u32 v2, v128, 16, 1
	v_add3_u32 v2, v128, v2, s80
	v_bfe_u32 v100, v116, 16, 1
	v_lshrrev_b32_e32 v2, 16, v2
	v_add3_u32 v100, v116, v100, s80
	v_and_or_b32 v135, v100, s85, v2
	v_bfe_u32 v2, v109, 16, 1
	v_add3_u32 v2, v109, v2, s80
	v_bfe_u32 v100, v105, 16, 1
	v_lshrrev_b32_e32 v2, 16, v2
	v_add3_u32 v100, v105, v100, s80
	global_store_dwordx4 v[136:137], v[132:135], off nt
	s_nop 1
	v_and_or_b32 v132, v100, s85, v2
	v_bfe_u32 v2, v113, 16, 1
	v_add3_u32 v2, v113, v2, s80
	v_bfe_u32 v100, v101, 16, 1
	v_lshrrev_b32_e32 v2, 16, v2
	v_add3_u32 v100, v101, v100, s80
	v_and_or_b32 v133, v100, s85, v2
	v_bfe_u32 v2, v125, 16, 1
	v_add3_u32 v2, v125, v2, s80
	v_bfe_u32 v100, v121, 16, 1
	v_lshrrev_b32_e32 v2, 16, v2
	v_add3_u32 v100, v121, v100, s80
	v_and_or_b32 v134, v100, s85, v2
	v_bfe_u32 v2, v129, 16, 1
	v_add3_u32 v2, v129, v2, s80
	v_bfe_u32 v100, v117, 16, 1
	v_lshrrev_b32_e32 v2, 16, v2
	v_add3_u32 v100, v117, v100, s80
	v_and_or_b32 v135, v100, s85, v2
	v_add_co_u32_e32 v100, vcc, s84, v136
	v_bfe_u32 v2, v110, 16, 1
	s_nop 0
	v_addc_co_u32_e32 v101, vcc, 0, v137, vcc
	global_store_dwordx4 v[100:101], v[132:135], off nt
	v_add3_u32 v2, v110, v2, s80
	v_bfe_u32 v100, v106, 16, 1
	v_lshrrev_b32_e32 v2, 16, v2
	v_add3_u32 v100, v106, v100, s80
	v_and_or_b32 v132, v100, s85, v2
	v_bfe_u32 v2, v114, 16, 1
	v_add3_u32 v2, v114, v2, s80
	v_bfe_u32 v100, v102, 16, 1
	v_lshrrev_b32_e32 v2, 16, v2
	v_add3_u32 v100, v102, v100, s80
	v_and_or_b32 v133, v100, s85, v2
	v_bfe_u32 v2, v126, 16, 1
	v_add3_u32 v2, v126, v2, s80
	v_bfe_u32 v100, v122, 16, 1
	v_lshrrev_b32_e32 v2, 16, v2
	v_add3_u32 v100, v122, v100, s80
	v_and_or_b32 v134, v100, s85, v2
	v_bfe_u32 v2, v130, 16, 1
	v_add3_u32 v2, v130, v2, s80
	v_bfe_u32 v100, v118, 16, 1
	v_lshrrev_b32_e32 v2, 16, v2
	v_add3_u32 v100, v118, v100, s80
	v_and_or_b32 v135, v100, s85, v2
	v_add_co_u32_e32 v100, vcc, s81, v136
	v_bfe_u32 v2, v111, 16, 1
	s_nop 0
	v_addc_co_u32_e32 v101, vcc, 0, v137, vcc
	global_store_dwordx4 v[100:101], v[132:135], off nt
	v_add3_u32 v2, v111, v2, s80
	v_bfe_u32 v100, v107, 16, 1
	v_lshrrev_b32_e32 v2, 16, v2
	v_add3_u32 v100, v107, v100, s80
	v_and_or_b32 v100, v100, s85, v2
	v_bfe_u32 v2, v115, 16, 1
	v_add3_u32 v2, v115, v2, s80
	v_bfe_u32 v101, v103, 16, 1
	v_lshrrev_b32_e32 v2, 16, v2
	v_add3_u32 v101, v103, v101, s80
	v_and_or_b32 v101, v101, s85, v2
	v_bfe_u32 v2, v127, 16, 1
	v_add3_u32 v2, v127, v2, s80
	v_bfe_u32 v102, v123, 16, 1
	v_lshrrev_b32_e32 v2, 16, v2
	v_add3_u32 v102, v123, v102, s80
	v_and_or_b32 v102, v102, s85, v2
	v_bfe_u32 v2, v131, 16, 1
	v_add3_u32 v2, v131, v2, s80
	v_bfe_u32 v103, v119, 16, 1
	v_add_co_u32_e32 v104, vcc, 0x6000, v136
	v_lshrrev_b32_e32 v2, 16, v2
	v_add3_u32 v103, v119, v103, s80
	v_addc_co_u32_e32 v105, vcc, 0, v137, vcc
	v_and_or_b32 v103, v103, s85, v2
	s_andn2_b64 vcc, exec, s[16:17]
	global_store_dwordx4 v[104:105], v[100:103], off nt
	s_cbranch_vccnz .LBB0_2356
	s_lshr_b32 s6, s4, 31
	s_ashr_i32 s4, s4, 4
	s_add_i32 s4, s4, s6
	v_lshl_or_b32 v100, s4, 6, v231
	s_mulk_i32 s4, 0xf400
	s_add_i32 s4, s4, s0
	v_add_u32_e32 v102, s4, v142
	v_ashrrev_i32_e32 v103, 31, v102
	v_lshlrev_b64 v[102:103], 13, v[102:103]
	v_ashrrev_i32_e32 v101, 31, v100
	v_lshl_add_u64 v[102:103], s[10:11], 0, v[102:103]
	v_bfe_u32 v2, v40, 16, 1
	v_lshl_add_u64 v[104:105], v[100:101], 1, v[102:103]
	v_add3_u32 v2, v40, v2, s80
	v_bfe_u32 v100, v36, 16, 1
	v_lshrrev_b32_e32 v2, 16, v2
	v_add3_u32 v100, v36, v100, s80
	v_and_or_b32 v100, v100, s85, v2
	v_bfe_u32 v2, v60, 16, 1
	v_add3_u32 v2, v60, v2, s80
	v_bfe_u32 v101, v28, 16, 1
	v_lshrrev_b32_e32 v2, 16, v2
	v_add3_u32 v101, v28, v101, s80
	v_and_or_b32 v101, v101, s85, v2
	v_bfe_u32 v2, v88, 16, 1
	v_add3_u32 v2, v88, v2, s80
	v_bfe_u32 v102, v84, 16, 1
	v_lshrrev_b32_e32 v2, 16, v2
	v_add3_u32 v102, v84, v102, s80
	v_and_or_b32 v102, v102, s85, v2
	v_bfe_u32 v2, v80, 16, 1
	v_add3_u32 v2, v80, v2, s80
	v_bfe_u32 v103, v96, 16, 1
	v_lshrrev_b32_e32 v2, 16, v2
	v_add3_u32 v103, v96, v103, s80
	v_and_or_b32 v103, v103, s85, v2
	v_bfe_u32 v2, v41, 16, 1
	global_store_dwordx4 v[104:105], v[100:103], off nt
	v_add3_u32 v2, v41, v2, s80
	v_lshrrev_b32_e32 v2, 16, v2
	v_bfe_u32 v100, v37, 16, 1
	v_add3_u32 v100, v37, v100, s80
	v_and_or_b32 v100, v100, s85, v2
	v_bfe_u32 v2, v61, 16, 1
	v_add3_u32 v2, v61, v2, s80
	v_bfe_u32 v101, v29, 16, 1
	v_lshrrev_b32_e32 v2, 16, v2
	v_add3_u32 v101, v29, v101, s80
	v_and_or_b32 v101, v101, s85, v2
	v_bfe_u32 v2, v89, 16, 1
	v_add3_u32 v2, v89, v2, s80
	v_bfe_u32 v102, v85, 16, 1
	v_lshrrev_b32_e32 v2, 16, v2
	v_add3_u32 v102, v85, v102, s80
	v_and_or_b32 v102, v102, s85, v2
	v_bfe_u32 v2, v81, 16, 1
	v_add3_u32 v2, v81, v2, s80
	v_bfe_u32 v103, v97, 16, 1
	v_lshrrev_b32_e32 v2, 16, v2
	v_add3_u32 v103, v97, v103, s80
	v_add_co_u32_e32 v106, vcc, s84, v104
	v_and_or_b32 v103, v103, s85, v2
	s_nop 0
	v_addc_co_u32_e32 v107, vcc, 0, v105, vcc
	v_bfe_u32 v2, v42, 16, 1
	global_store_dwordx4 v[106:107], v[100:103], off nt
	v_add3_u32 v2, v42, v2, s80
	v_lshrrev_b32_e32 v2, 16, v2
	v_bfe_u32 v100, v38, 16, 1
	v_add3_u32 v100, v38, v100, s80
	v_and_or_b32 v100, v100, s85, v2
	v_bfe_u32 v2, v62, 16, 1
	v_add3_u32 v2, v62, v2, s80
	v_bfe_u32 v101, v30, 16, 1
	v_lshrrev_b32_e32 v2, 16, v2
	v_add3_u32 v101, v30, v101, s80
	v_and_or_b32 v101, v101, s85, v2
	v_bfe_u32 v2, v90, 16, 1
	v_add3_u32 v2, v90, v2, s80
	v_bfe_u32 v102, v86, 16, 1
	v_lshrrev_b32_e32 v2, 16, v2
	v_add3_u32 v102, v86, v102, s80
	v_and_or_b32 v102, v102, s85, v2
	v_bfe_u32 v2, v82, 16, 1
	v_add3_u32 v2, v82, v2, s80
	v_bfe_u32 v103, v98, 16, 1
	v_lshrrev_b32_e32 v2, 16, v2
	v_add3_u32 v103, v98, v103, s80
	v_add_co_u32_e32 v106, vcc, s81, v104
	v_and_or_b32 v103, v103, s85, v2
	s_nop 0
	v_addc_co_u32_e32 v107, vcc, 0, v105, vcc
	v_bfe_u32 v2, v43, 16, 1
	global_store_dwordx4 v[106:107], v[100:103], off nt
	v_add3_u32 v2, v43, v2, s80
	v_lshrrev_b32_e32 v2, 16, v2
	v_bfe_u32 v100, v39, 16, 1
	v_add3_u32 v100, v39, v100, s80
	v_and_or_b32 v100, v100, s85, v2
	v_bfe_u32 v2, v63, 16, 1
	v_add3_u32 v2, v63, v2, s80
	v_bfe_u32 v101, v31, 16, 1
	v_lshrrev_b32_e32 v2, 16, v2
	v_add3_u32 v101, v31, v101, s80
	v_and_or_b32 v101, v101, s85, v2
	v_bfe_u32 v2, v91, 16, 1
	v_add3_u32 v2, v91, v2, s80
	v_bfe_u32 v102, v87, 16, 1
	v_lshrrev_b32_e32 v2, 16, v2
	v_add3_u32 v102, v87, v102, s80
	v_and_or_b32 v102, v102, s85, v2
	v_bfe_u32 v2, v83, 16, 1
	v_add3_u32 v2, v83, v2, s80
	v_bfe_u32 v103, v99, 16, 1
	v_lshrrev_b32_e32 v2, 16, v2
	v_add3_u32 v103, v99, v103, s80
	v_add_co_u32_e32 v104, vcc, 0x6000, v104
	v_and_or_b32 v103, v103, s85, v2
	s_nop 0
	v_addc_co_u32_e32 v105, vcc, 0, v105, vcc
	global_store_dwordx4 v[104:105], v[100:103], off nt
	s_andn2_b64 vcc, exec, s[18:19]
	s_cbranch_vccz .LBB0_2357

.LBB0_2357:
	s_lshr_b32 s4, s5, 31
	s_ashr_i32 s5, s5, 4
	s_add_i32 s4, s5, s4
	v_lshl_or_b32 v100, s4, 6, v231
	s_mulk_i32 s4, 0xf400
	s_add_i32 s4, s4, s0
	v_add_u32_e32 v102, s4, v140
	v_ashrrev_i32_e32 v103, 31, v102
	v_lshlrev_b64 v[102:103], 13, v[102:103]
	v_ashrrev_i32_e32 v101, 31, v100
	v_lshl_add_u64 v[102:103], s[10:11], 0, v[102:103]
	v_bfe_u32 v2, v24, 16, 1
	v_lshl_add_u64 v[104:105], v[100:101], 1, v[102:103]
	v_add3_u32 v2, v24, v2, s80
	v_bfe_u32 v100, v20, 16, 1
	v_lshrrev_b32_e32 v2, 16, v2
	v_add3_u32 v100, v20, v100, s80
	v_and_or_b32 v100, v100, s85, v2
	v_bfe_u32 v2, v44, 16, 1
	v_add3_u32 v2, v44, v2, s80
	v_bfe_u32 v101, v16, 16, 1
	v_lshrrev_b32_e32 v2, 16, v2
	v_add3_u32 v101, v16, v101, s80
	v_and_or_b32 v101, v101, s85, v2
	v_bfe_u32 v2, v72, 16, 1
	v_add3_u32 v2, v72, v2, s80
	v_bfe_u32 v102, v68, 16, 1
	v_lshrrev_b32_e32 v2, 16, v2
	v_add3_u32 v102, v68, v102, s80
	v_and_or_b32 v102, v102, s85, v2
	v_bfe_u32 v2, v64, 16, 1
	v_add3_u32 v2, v64, v2, s80
	v_bfe_u32 v103, v92, 16, 1
	v_lshrrev_b32_e32 v2, 16, v2
	v_add3_u32 v103, v92, v103, s80
	v_and_or_b32 v103, v103, s85, v2
	v_bfe_u32 v2, v25, 16, 1
	global_store_dwordx4 v[104:105], v[100:103], off nt
	v_add3_u32 v2, v25, v2, s80
	v_lshrrev_b32_e32 v2, 16, v2
	v_bfe_u32 v100, v21, 16, 1
	v_add3_u32 v100, v21, v100, s80
	v_and_or_b32 v100, v100, s85, v2
	v_bfe_u32 v2, v45, 16, 1
	v_add3_u32 v2, v45, v2, s80
	v_bfe_u32 v101, v17, 16, 1
	v_lshrrev_b32_e32 v2, 16, v2
	v_add3_u32 v101, v17, v101, s80
	v_and_or_b32 v101, v101, s85, v2
	v_bfe_u32 v2, v73, 16, 1
	v_add3_u32 v2, v73, v2, s80
	v_bfe_u32 v102, v69, 16, 1
	v_lshrrev_b32_e32 v2, 16, v2
	v_add3_u32 v102, v69, v102, s80
	v_and_or_b32 v102, v102, s85, v2
	v_bfe_u32 v2, v65, 16, 1
	v_add3_u32 v2, v65, v2, s80
	v_bfe_u32 v103, v93, 16, 1
	v_lshrrev_b32_e32 v2, 16, v2
	v_add3_u32 v103, v93, v103, s80
	v_add_co_u32_e32 v106, vcc, s84, v104
	v_and_or_b32 v103, v103, s85, v2
	s_nop 0
	v_addc_co_u32_e32 v107, vcc, 0, v105, vcc
	v_bfe_u32 v2, v26, 16, 1
	global_store_dwordx4 v[106:107], v[100:103], off nt
	v_add3_u32 v2, v26, v2, s80
	v_lshrrev_b32_e32 v2, 16, v2
	v_bfe_u32 v100, v22, 16, 1
	v_add3_u32 v100, v22, v100, s80
	v_and_or_b32 v100, v100, s85, v2
	v_bfe_u32 v2, v46, 16, 1
	v_add3_u32 v2, v46, v2, s80
	v_bfe_u32 v101, v18, 16, 1
	v_lshrrev_b32_e32 v2, 16, v2
	v_add3_u32 v101, v18, v101, s80
	v_and_or_b32 v101, v101, s85, v2
	v_bfe_u32 v2, v74, 16, 1
	v_add3_u32 v2, v74, v2, s80
	v_bfe_u32 v102, v70, 16, 1
	v_lshrrev_b32_e32 v2, 16, v2
	v_add3_u32 v102, v70, v102, s80
	v_and_or_b32 v102, v102, s85, v2
	v_bfe_u32 v2, v66, 16, 1
	v_add3_u32 v2, v66, v2, s80
	v_bfe_u32 v103, v94, 16, 1
	v_lshrrev_b32_e32 v2, 16, v2
	v_add3_u32 v103, v94, v103, s80
	v_add_co_u32_e32 v106, vcc, s81, v104
	v_and_or_b32 v103, v103, s85, v2
	s_nop 0
	v_addc_co_u32_e32 v107, vcc, 0, v105, vcc
	v_bfe_u32 v2, v27, 16, 1
	global_store_dwordx4 v[106:107], v[100:103], off nt
	v_add3_u32 v2, v27, v2, s80
	v_lshrrev_b32_e32 v2, 16, v2
	v_bfe_u32 v100, v23, 16, 1
	v_add3_u32 v100, v23, v100, s80
	v_and_or_b32 v100, v100, s85, v2
	v_bfe_u32 v2, v47, 16, 1
	v_add3_u32 v2, v47, v2, s80
	v_bfe_u32 v101, v19, 16, 1
	v_lshrrev_b32_e32 v2, 16, v2
	v_add3_u32 v101, v19, v101, s80
	v_and_or_b32 v101, v101, s85, v2
	v_bfe_u32 v2, v75, 16, 1
	v_add3_u32 v2, v75, v2, s80
	v_bfe_u32 v102, v71, 16, 1
	v_lshrrev_b32_e32 v2, 16, v2
	v_add3_u32 v102, v71, v102, s80
	v_and_or_b32 v102, v102, s85, v2
	v_bfe_u32 v2, v67, 16, 1
	v_add3_u32 v2, v67, v2, s80
	v_bfe_u32 v103, v95, 16, 1
	v_lshrrev_b32_e32 v2, 16, v2
	v_add3_u32 v103, v95, v103, s80
	v_add_co_u32_e32 v104, vcc, 0x6000, v104
	v_and_or_b32 v103, v103, s85, v2
	s_nop 0
	v_addc_co_u32_e32 v105, vcc, 0, v105, vcc
	global_store_dwordx4 v[104:105], v[100:103], off nt
	s_andn2_b64 vcc, exec, s[20:21]
	s_cbranch_vccnz .LBB0_2250
.LBB0_2358:
	s_lshr_b32 s4, s14, 31
	s_ashr_i32 s5, s14, 4
	s_add_i32 s4, s5, s4
	v_lshl_or_b32 v100, s4, 6, v231
	s_mulk_i32 s4, 0xf400
	s_add_i32 s4, s4, s0
	v_add_u32_e32 v102, s4, v141
	v_ashrrev_i32_e32 v103, 31, v102
	v_lshlrev_b64 v[102:103], 13, v[102:103]
	v_ashrrev_i32_e32 v101, 31, v100
	v_lshl_add_u64 v[102:103], s[10:11], 0, v[102:103]
	v_bfe_u32 v2, v12, 16, 1
	v_lshl_add_u64 v[104:105], v[100:101], 1, v[102:103]
	v_add3_u32 v2, v12, v2, s80
	v_bfe_u32 v100, v8, 16, 1
	v_lshrrev_b32_e32 v2, 16, v2
	v_add3_u32 v100, v8, v100, s80
	v_and_or_b32 v100, v100, s85, v2
	v_bfe_u32 v2, v32, 16, 1
	v_add3_u32 v2, v32, v2, s80
	v_bfe_u32 v101, v4, 16, 1
	v_lshrrev_b32_e32 v2, 16, v2
	v_add3_u32 v101, v4, v101, s80
	v_and_or_b32 v101, v101, s85, v2
	v_bfe_u32 v2, v56, 16, 1
	v_add3_u32 v2, v56, v2, s80
	v_bfe_u32 v102, v52, 16, 1
	v_lshrrev_b32_e32 v2, 16, v2
	v_add3_u32 v102, v52, v102, s80
	v_and_or_b32 v102, v102, s85, v2
	v_bfe_u32 v2, v48, 16, 1
	v_add3_u32 v2, v48, v2, s80
	v_bfe_u32 v103, v76, 16, 1
	v_lshrrev_b32_e32 v2, 16, v2
	v_add3_u32 v103, v76, v103, s80
	v_and_or_b32 v103, v103, s85, v2
	v_bfe_u32 v2, v13, 16, 1
	global_store_dwordx4 v[104:105], v[100:103], off nt
	v_add3_u32 v2, v13, v2, s80
	v_lshrrev_b32_e32 v2, 16, v2
	v_bfe_u32 v100, v9, 16, 1
	v_add3_u32 v100, v9, v100, s80
	v_and_or_b32 v100, v100, s85, v2
	v_bfe_u32 v2, v33, 16, 1
	v_add3_u32 v2, v33, v2, s80
	v_bfe_u32 v101, v5, 16, 1
	v_lshrrev_b32_e32 v2, 16, v2
	v_add3_u32 v101, v5, v101, s80
	v_and_or_b32 v101, v101, s85, v2
	v_bfe_u32 v2, v57, 16, 1
	v_add3_u32 v2, v57, v2, s80
	v_bfe_u32 v102, v53, 16, 1
	v_lshrrev_b32_e32 v2, 16, v2
	v_add3_u32 v102, v53, v102, s80
	v_and_or_b32 v102, v102, s85, v2
	v_bfe_u32 v2, v49, 16, 1
	v_add3_u32 v2, v49, v2, s80
	v_bfe_u32 v103, v77, 16, 1
	v_lshrrev_b32_e32 v2, 16, v2
	v_add3_u32 v103, v77, v103, s80
	v_add_co_u32_e32 v106, vcc, s84, v104
	v_and_or_b32 v103, v103, s85, v2
	s_nop 0
	v_addc_co_u32_e32 v107, vcc, 0, v105, vcc
	v_bfe_u32 v2, v14, 16, 1
	global_store_dwordx4 v[106:107], v[100:103], off nt
	v_add3_u32 v2, v14, v2, s80
	v_lshrrev_b32_e32 v2, 16, v2
	v_bfe_u32 v100, v10, 16, 1
	v_add3_u32 v100, v10, v100, s80
	v_and_or_b32 v100, v100, s85, v2
	v_bfe_u32 v2, v34, 16, 1
	v_add3_u32 v2, v34, v2, s80
	v_bfe_u32 v101, v6, 16, 1
	v_lshrrev_b32_e32 v2, 16, v2
	v_add3_u32 v101, v6, v101, s80
	v_and_or_b32 v101, v101, s85, v2
	v_bfe_u32 v2, v58, 16, 1
	v_add3_u32 v2, v58, v2, s80
	v_bfe_u32 v102, v54, 16, 1
	v_lshrrev_b32_e32 v2, 16, v2
	v_add3_u32 v102, v54, v102, s80
	v_and_or_b32 v102, v102, s85, v2
	v_bfe_u32 v2, v50, 16, 1
	v_add3_u32 v2, v50, v2, s80
	v_bfe_u32 v103, v78, 16, 1
	v_lshrrev_b32_e32 v2, 16, v2
	v_add3_u32 v103, v78, v103, s80
	v_add_co_u32_e32 v106, vcc, s81, v104
	v_and_or_b32 v103, v103, s85, v2
	s_nop 0
	v_addc_co_u32_e32 v107, vcc, 0, v105, vcc
	v_bfe_u32 v2, v15, 16, 1
	global_store_dwordx4 v[106:107], v[100:103], off nt
	v_add3_u32 v2, v15, v2, s80
	v_lshrrev_b32_e32 v2, 16, v2
	v_bfe_u32 v100, v11, 16, 1
	v_add3_u32 v100, v11, v100, s80
	v_and_or_b32 v100, v100, s85, v2
	v_bfe_u32 v2, v35, 16, 1
	v_add3_u32 v2, v35, v2, s80
	v_bfe_u32 v101, v7, 16, 1
	v_lshrrev_b32_e32 v2, 16, v2
	v_add3_u32 v101, v7, v101, s80
	v_and_or_b32 v101, v101, s85, v2
	v_bfe_u32 v2, v59, 16, 1
	v_add3_u32 v2, v59, v2, s80
	v_bfe_u32 v102, v55, 16, 1
	v_lshrrev_b32_e32 v2, 16, v2
	v_add3_u32 v102, v55, v102, s80
	v_and_or_b32 v102, v102, s85, v2
	v_bfe_u32 v2, v51, 16, 1
	v_add3_u32 v2, v51, v2, s80
	v_bfe_u32 v103, v79, 16, 1
	v_lshrrev_b32_e32 v2, 16, v2
	v_add3_u32 v103, v79, v103, s80
	v_add_co_u32_e32 v104, vcc, 0x6000, v104
	v_and_or_b32 v103, v103, s85, v2
	s_nop 0
	v_addc_co_u32_e32 v105, vcc, 0, v105, vcc
	global_store_dwordx4 v[104:105], v[100:103], off nt
	s_branch .LBB0_2250

.LBB0_2400:
	v_lshl_add_u64 v[4:5], v[134:135], 2, s[10:11]
	global_load_dwordx4 v[150:153], v[4:5], off offset:16
	global_load_dwordx4 v[138:141], v[4:5], off
	s_movk_i32 s15, 0x1000
	s_waitcnt vmcnt(1)
	v_pk_mul_f32 v[126:127], v[126:127], v[150:151] op_sel_hi:[1,0]
	s_waitcnt vmcnt(0)
	v_mov_b32_e32 v2, v141
	v_pk_mul_f32 v[136:137], v[112:113], v[138:139] op_sel_hi:[1,0]
	v_pk_mul_f32 v[144:145], v[110:111], v[138:139] op_sel_hi:[1,0]
	v_pk_mul_f32 v[112:113], v[108:109], v[138:139] op_sel:[0,1]
	v_pk_mul_f32 v[142:143], v[106:107], v[138:139] op_sel:[0,1]
	v_pk_mul_f32 v[108:109], v[116:117], v[140:141] op_sel_hi:[1,0]
	v_pk_mul_f32 v[138:139], v[114:115], v[140:141] op_sel_hi:[1,0]
	v_pk_mul_f32 v[110:111], v[104:105], v[2:3] op_sel_hi:[1,0]
	v_pk_mul_f32 v[140:141], v[102:103], v[2:3] op_sel_hi:[1,0]
	v_mov_b32_e32 v2, v153
	v_pk_mul_f32 v[102:103], v[120:121], v[2:3] op_sel_hi:[1,0]
	v_pk_mul_f32 v[118:119], v[118:119], v[2:3] op_sel_hi:[1,0]
	v_bfe_u32 v2, v144, 16, 1
	v_add3_u32 v2, v144, v2, s80
	v_bfe_u32 v120, v142, 16, 1
	v_lshrrev_b32_e32 v2, 16, v2
	v_add3_u32 v120, v142, v120, s80
	v_pk_mul_f32 v[106:107], v[128:129], v[150:151] op_sel_hi:[1,0]
	v_and_or_b32 v128, v120, s85, v2
	v_bfe_u32 v2, v138, 16, 1
	v_add3_u32 v2, v138, v2, s80
	v_bfe_u32 v120, v140, 16, 1
	v_lshrrev_b32_e32 v2, 16, v2
	v_add3_u32 v120, v140, v120, s80
	v_pk_mul_f32 v[122:123], v[122:123], v[150:151] op_sel:[0,1]
	v_and_or_b32 v129, v120, s85, v2
	v_bfe_u32 v2, v126, 16, 1
	v_add3_u32 v2, v126, v2, s80
	v_bfe_u32 v120, v122, 16, 1
	v_pk_mul_f32 v[116:117], v[130:131], v[152:153] op_sel_hi:[1,0]
	v_lshrrev_b32_e32 v2, 16, v2
	v_add3_u32 v120, v122, v120, s80
	v_and_or_b32 v130, v120, s85, v2
	v_bfe_u32 v2, v116, 16, 1
	v_add3_u32 v2, v116, v2, s80
	v_bfe_u32 v116, v118, 16, 1
	v_lshrrev_b32_e32 v2, 16, v2
	v_add3_u32 v116, v118, v116, s80
	v_and_or_b32 v131, v116, s85, v2
	v_bfe_u32 v2, v145, 16, 1
	v_add3_u32 v2, v145, v2, s80
	v_bfe_u32 v116, v143, 16, 1
	v_lshrrev_b32_e32 v2, 16, v2
	v_add3_u32 v116, v143, v116, s80
	v_and_or_b32 v120, v116, s85, v2
	v_bfe_u32 v2, v139, 16, 1
	v_add3_u32 v2, v139, v2, s80
	v_bfe_u32 v116, v141, 16, 1
	v_lshrrev_b32_e32 v2, 16, v2
	v_add3_u32 v116, v141, v116, s80
	v_and_or_b32 v121, v116, s85, v2
	v_bfe_u32 v2, v127, 16, 1
	v_add3_u32 v2, v127, v2, s80
	v_bfe_u32 v116, v123, 16, 1
	v_lshrrev_b32_e32 v2, 16, v2
	v_add3_u32 v116, v123, v116, s80
	v_and_or_b32 v122, v116, s85, v2
	v_bfe_u32 v2, v117, 16, 1
	v_add3_u32 v2, v117, v2, s80
	v_bfe_u32 v116, v119, 16, 1
	v_lshrrev_b32_e32 v2, 16, v2
	v_add3_u32 v116, v119, v116, s80
	v_and_or_b32 v123, v116, s85, v2
	v_bfe_u32 v2, v136, 16, 1
	v_add3_u32 v2, v136, v2, s80
	v_bfe_u32 v116, v112, 16, 1
	v_lshrrev_b32_e32 v2, 16, v2
	v_add3_u32 v112, v112, v116, s80
	v_and_or_b32 v116, v112, s85, v2
	v_bfe_u32 v2, v108, 16, 1
	v_add3_u32 v2, v108, v2, s80
	v_bfe_u32 v108, v110, 16, 1
	v_lshrrev_b32_e32 v2, 16, v2
	v_add3_u32 v108, v110, v108, s80
	v_pk_mul_f32 v[104:105], v[124:125], v[150:151] op_sel:[0,1]
	v_and_or_b32 v117, v108, s85, v2
	v_bfe_u32 v2, v106, 16, 1
	v_add3_u32 v2, v106, v2, s80
	v_bfe_u32 v106, v104, 16, 1
	v_pk_mul_f32 v[4:5], v[132:133], v[152:153] op_sel_hi:[1,0]
	v_lshrrev_b32_e32 v2, 16, v2
	v_add3_u32 v104, v104, v106, s80
	v_and_or_b32 v118, v104, s85, v2
	v_bfe_u32 v2, v4, 16, 1
	v_add3_u32 v2, v4, v2, s80
	v_bfe_u32 v4, v102, 16, 1
	v_lshrrev_b32_e32 v2, 16, v2
	v_add3_u32 v4, v102, v4, s80
	v_and_or_b32 v119, v4, s85, v2
	v_bfe_u32 v2, v137, 16, 1
	v_add3_u32 v2, v137, v2, s80
	v_bfe_u32 v4, v113, 16, 1
	v_lshrrev_b32_e32 v2, 16, v2
	v_add3_u32 v4, v113, v4, s80
	v_and_or_b32 v108, v4, s85, v2
	v_bfe_u32 v2, v109, 16, 1
	v_add3_u32 v2, v109, v2, s80
	v_bfe_u32 v4, v111, 16, 1
	v_lshrrev_b32_e32 v2, 16, v2
	v_add3_u32 v4, v111, v4, s80
	v_and_or_b32 v109, v4, s85, v2
	v_bfe_u32 v2, v107, 16, 1
	v_mov_b64_e32 v[114:115], s[16:17]
	v_add3_u32 v2, v107, v2, s80
	v_bfe_u32 v4, v105, 16, 1
	v_mad_i64_i32 v[114:115], s[6:7], v149, s68, v[114:115]
	v_lshrrev_b32_e32 v2, 16, v2
	v_add3_u32 v4, v105, v4, s80
	v_lshl_add_u64 v[114:115], v[134:135], 1, v[114:115]
	v_and_or_b32 v110, v4, s85, v2
	v_bfe_u32 v2, v5, 16, 1
	global_store_dwordx4 v[114:115], v[120:123], off offset:3072 nt
	v_add3_u32 v2, v5, v2, s80
	v_bfe_u32 v4, v103, 16, 1
	v_add_co_u32_e32 v120, vcc, s15, v114
	v_lshrrev_b32_e32 v2, 16, v2
	s_nop 0
	v_addc_co_u32_e32 v121, vcc, 0, v115, vcc
	v_add3_u32 v4, v103, v4, s80
	v_and_or_b32 v111, v4, s85, v2
	v_add_co_u32_e32 v4, vcc, 0x2000, v114
	global_store_dwordx4 v[114:115], v[128:131], off nt
	s_nop 0
	v_addc_co_u32_e32 v5, vcc, 0, v115, vcc
	s_andn2_b64 vcc, exec, s[22:23]
	global_store_dwordx4 v[120:121], v[116:119], off offset:2048 nt
	global_store_dwordx4 v[4:5], v[108:111], off offset:1024 nt
	s_cbranch_vccnz .LBB0_2403
	s_lshr_b32 s6, s14, 31
	s_ashr_i32 s7, s14, 4
	s_add_i32 s6, s7, s6
	v_lshl_or_b32 v4, s6, 6, v231
	v_ashrrev_i32_e32 v5, 31, v4
	v_lshl_add_u64 v[106:107], v[4:5], 2, s[10:11]
	global_load_dwordx4 v[102:105], v[106:107], off offset:16
	s_nop 0
	global_load_dwordx4 v[106:109], v[106:107], off
	s_mulk_i32 s6, 0xf400
	s_add_i32 s6, s6, s0
	s_waitcnt vmcnt(1)
	v_pk_mul_f32 v[72:73], v[72:73], v[102:103] op_sel_hi:[1,0]
	s_waitcnt vmcnt(0)
	v_mov_b32_e32 v2, v109
	v_pk_mul_f32 v[36:37], v[36:37], v[2:3] op_sel_hi:[1,0]
	v_pk_mul_f32 v[34:35], v[34:35], v[2:3] op_sel_hi:[1,0]
	v_mov_b32_e32 v2, v105
	v_pk_mul_f32 v[30:31], v[30:31], v[106:107] op_sel_hi:[1,0]
	v_pk_mul_f32 v[70:71], v[70:71], v[102:103] op_sel_hi:[1,0]
	v_pk_mul_f32 v[76:77], v[76:77], v[102:103] op_sel:[0,1]
	v_pk_mul_f32 v[74:75], v[74:75], v[102:103] op_sel:[0,1]
	v_pk_mul_f32 v[100:101], v[100:101], v[2:3] op_sel_hi:[1,0]
	v_pk_mul_f32 v[98:99], v[98:99], v[2:3] op_sel_hi:[1,0]
	v_add_u32_e32 v2, s6, v148
	v_mov_b64_e32 v[102:103], s[16:17]
	v_pk_mul_f32 v[38:39], v[38:39], v[106:107] op_sel:[0,1]
	v_mad_i64_i32 v[102:103], s[6:7], v2, s68, v[102:103]
	v_bfe_u32 v2, v30, 16, 1
	v_lshl_add_u64 v[4:5], v[4:5], 1, v[102:103]
	v_add3_u32 v2, v30, v2, s80
	v_bfe_u32 v102, v38, 16, 1
	v_pk_mul_f32 v[50:51], v[50:51], v[108:109] op_sel_hi:[1,0]
	v_lshrrev_b32_e32 v2, 16, v2
	v_add3_u32 v102, v38, v102, s80
	v_and_or_b32 v102, v102, s85, v2
	v_bfe_u32 v2, v50, 16, 1
	v_add3_u32 v2, v50, v2, s80
	v_bfe_u32 v103, v34, 16, 1
	v_lshrrev_b32_e32 v2, 16, v2
	v_add3_u32 v103, v34, v103, s80
	v_and_or_b32 v103, v103, s85, v2
	v_bfe_u32 v2, v70, 16, 1
	v_pk_mul_f32 v[96:97], v[96:97], v[104:105] op_sel_hi:[1,0]
	v_pk_mul_f32 v[94:95], v[94:95], v[104:105] op_sel_hi:[1,0]
	v_add3_u32 v2, v70, v2, s80
	v_bfe_u32 v104, v74, 16, 1
	v_lshrrev_b32_e32 v2, 16, v2
	v_add3_u32 v104, v74, v104, s80
	v_and_or_b32 v104, v104, s85, v2
	v_bfe_u32 v2, v94, 16, 1
	v_add3_u32 v2, v94, v2, s80
	v_bfe_u32 v105, v98, 16, 1
	v_lshrrev_b32_e32 v2, 16, v2
	v_add3_u32 v105, v98, v105, s80
	v_and_or_b32 v105, v105, s85, v2
	v_bfe_u32 v2, v31, 16, 1
	global_store_dwordx4 v[4:5], v[102:105], off nt
	v_add3_u32 v2, v31, v2, s80
	v_lshrrev_b32_e32 v2, 16, v2
	v_bfe_u32 v102, v39, 16, 1
	v_add3_u32 v102, v39, v102, s80
	v_and_or_b32 v102, v102, s85, v2
	v_bfe_u32 v2, v51, 16, 1
	v_add3_u32 v2, v51, v2, s80
	v_bfe_u32 v103, v35, 16, 1
	v_lshrrev_b32_e32 v2, 16, v2
	v_add3_u32 v103, v35, v103, s80
	v_and_or_b32 v103, v103, s85, v2
	v_bfe_u32 v2, v71, 16, 1
	v_add3_u32 v2, v71, v2, s80
	v_bfe_u32 v104, v75, 16, 1
	v_lshrrev_b32_e32 v2, 16, v2
	v_add3_u32 v104, v75, v104, s80
	v_and_or_b32 v104, v104, s85, v2
	v_bfe_u32 v2, v95, 16, 1
	v_add3_u32 v2, v95, v2, s80
	v_bfe_u32 v105, v99, 16, 1
	v_pk_mul_f32 v[32:33], v[32:33], v[106:107] op_sel_hi:[1,0]
	v_lshrrev_b32_e32 v2, 16, v2
	v_add3_u32 v105, v99, v105, s80
	v_pk_mul_f32 v[40:41], v[40:41], v[106:107] op_sel:[0,1]
	v_and_or_b32 v105, v105, s85, v2
	v_bfe_u32 v2, v32, 16, 1
	global_store_dwordx4 v[4:5], v[102:105], off offset:3072 nt
	v_add3_u32 v2, v32, v2, s80
	v_pk_mul_f32 v[52:53], v[52:53], v[108:109] op_sel_hi:[1,0]
	v_bfe_u32 v102, v40, 16, 1
	v_lshrrev_b32_e32 v2, 16, v2
	v_add3_u32 v102, v40, v102, s80
	v_and_or_b32 v102, v102, s85, v2
	v_bfe_u32 v2, v52, 16, 1
	v_add3_u32 v2, v52, v2, s80
	v_bfe_u32 v103, v36, 16, 1
	v_lshrrev_b32_e32 v2, 16, v2
	v_add3_u32 v103, v36, v103, s80
	v_and_or_b32 v103, v103, s85, v2
	v_bfe_u32 v2, v72, 16, 1
	v_add3_u32 v2, v72, v2, s80
	v_bfe_u32 v104, v76, 16, 1
	v_lshrrev_b32_e32 v2, 16, v2
	v_add3_u32 v104, v76, v104, s80
	v_and_or_b32 v104, v104, s85, v2
	v_bfe_u32 v2, v96, 16, 1
	v_add3_u32 v2, v96, v2, s80
	v_bfe_u32 v105, v100, 16, 1
	v_lshrrev_b32_e32 v2, 16, v2
	v_add3_u32 v105, v100, v105, s80
	v_add_co_u32_e32 v106, vcc, s15, v4
	v_and_or_b32 v105, v105, s85, v2
	s_nop 0
	v_addc_co_u32_e32 v107, vcc, 0, v5, vcc
	v_bfe_u32 v2, v33, 16, 1
	global_store_dwordx4 v[106:107], v[102:105], off offset:2048 nt
	v_add3_u32 v2, v33, v2, s80
	v_lshrrev_b32_e32 v2, 16, v2
	v_bfe_u32 v102, v41, 16, 1
	v_add3_u32 v102, v41, v102, s80
	v_and_or_b32 v102, v102, s85, v2
	v_bfe_u32 v2, v53, 16, 1
	v_add3_u32 v2, v53, v2, s80
	v_bfe_u32 v103, v37, 16, 1
	v_lshrrev_b32_e32 v2, 16, v2
	v_add3_u32 v103, v37, v103, s80
	v_and_or_b32 v103, v103, s85, v2
	v_bfe_u32 v2, v73, 16, 1
	v_add3_u32 v2, v73, v2, s80
	v_bfe_u32 v104, v77, 16, 1
	v_lshrrev_b32_e32 v2, 16, v2
	v_add3_u32 v104, v77, v104, s80
	v_and_or_b32 v104, v104, s85, v2
	v_bfe_u32 v2, v97, 16, 1
	v_add3_u32 v2, v97, v2, s80
	v_bfe_u32 v105, v101, 16, 1
	v_lshrrev_b32_e32 v2, 16, v2
	v_add3_u32 v105, v101, v105, s80
	v_add_co_u32_e32 v4, vcc, 0x2000, v4
	v_and_or_b32 v105, v105, s85, v2
	s_nop 0
	v_addc_co_u32_e32 v5, vcc, 0, v5, vcc
	global_store_dwordx4 v[4:5], v[102:105], off offset:1024 nt
	s_andn2_b64 vcc, exec, s[20:21]
	s_cbranch_vccz .LBB0_2404

.LBB0_2404:
	s_lshr_b32 s6, s5, 31
	s_ashr_i32 s5, s5, 4
	s_add_i32 s5, s5, s6
	v_lshl_or_b32 v4, s5, 6, v231
	v_ashrrev_i32_e32 v5, 31, v4
	v_lshl_add_u64 v[106:107], v[4:5], 2, s[10:11]
	global_load_dwordx4 v[102:105], v[106:107], off offset:16
	s_nop 0
	global_load_dwordx4 v[106:109], v[106:107], off
	s_mulk_i32 s5, 0xf400
	s_add_i32 s5, s5, s0
	s_waitcnt vmcnt(1)
	v_pk_mul_f32 v[64:65], v[64:65], v[102:103] op_sel_hi:[1,0]
	s_waitcnt vmcnt(0)
	v_mov_b32_e32 v2, v109
	v_pk_mul_f32 v[20:21], v[20:21], v[2:3] op_sel_hi:[1,0]
	v_pk_mul_f32 v[18:19], v[18:19], v[2:3] op_sel_hi:[1,0]
	v_mov_b32_e32 v2, v105
	v_pk_mul_f32 v[22:23], v[22:23], v[106:107] op_sel_hi:[1,0]
	v_pk_mul_f32 v[62:63], v[62:63], v[102:103] op_sel_hi:[1,0]
	v_pk_mul_f32 v[68:69], v[68:69], v[102:103] op_sel:[0,1]
	v_pk_mul_f32 v[66:67], v[66:67], v[102:103] op_sel:[0,1]
	v_pk_mul_f32 v[92:93], v[92:93], v[2:3] op_sel_hi:[1,0]
	v_pk_mul_f32 v[90:91], v[90:91], v[2:3] op_sel_hi:[1,0]
	v_add_u32_e32 v2, s5, v146
	v_mov_b64_e32 v[102:103], s[16:17]
	v_pk_mul_f32 v[26:27], v[26:27], v[106:107] op_sel:[0,1]
	v_mad_i64_i32 v[102:103], s[6:7], v2, s68, v[102:103]
	v_bfe_u32 v2, v22, 16, 1
	v_lshl_add_u64 v[4:5], v[4:5], 1, v[102:103]
	v_add3_u32 v2, v22, v2, s80
	v_bfe_u32 v102, v26, 16, 1
	v_pk_mul_f32 v[46:47], v[46:47], v[108:109] op_sel_hi:[1,0]
	v_lshrrev_b32_e32 v2, 16, v2
	v_add3_u32 v102, v26, v102, s80
	v_and_or_b32 v102, v102, s85, v2
	v_bfe_u32 v2, v46, 16, 1
	v_add3_u32 v2, v46, v2, s80
	v_bfe_u32 v103, v18, 16, 1
	v_lshrrev_b32_e32 v2, 16, v2
	v_add3_u32 v103, v18, v103, s80
	v_and_or_b32 v103, v103, s85, v2
	v_bfe_u32 v2, v62, 16, 1
	v_pk_mul_f32 v[88:89], v[88:89], v[104:105] op_sel_hi:[1,0]
	v_pk_mul_f32 v[86:87], v[86:87], v[104:105] op_sel_hi:[1,0]
	v_add3_u32 v2, v62, v2, s80
	v_bfe_u32 v104, v66, 16, 1
	v_lshrrev_b32_e32 v2, 16, v2
	v_add3_u32 v104, v66, v104, s80
	v_and_or_b32 v104, v104, s85, v2
	v_bfe_u32 v2, v86, 16, 1
	v_add3_u32 v2, v86, v2, s80
	v_bfe_u32 v105, v90, 16, 1
	v_lshrrev_b32_e32 v2, 16, v2
	v_add3_u32 v105, v90, v105, s80
	v_and_or_b32 v105, v105, s85, v2
	v_bfe_u32 v2, v23, 16, 1
	global_store_dwordx4 v[4:5], v[102:105], off nt
	v_add3_u32 v2, v23, v2, s80
	v_lshrrev_b32_e32 v2, 16, v2
	v_bfe_u32 v102, v27, 16, 1
	v_add3_u32 v102, v27, v102, s80
	v_and_or_b32 v102, v102, s85, v2
	v_bfe_u32 v2, v47, 16, 1
	v_add3_u32 v2, v47, v2, s80
	v_bfe_u32 v103, v19, 16, 1
	v_lshrrev_b32_e32 v2, 16, v2
	v_add3_u32 v103, v19, v103, s80
	v_and_or_b32 v103, v103, s85, v2
	v_bfe_u32 v2, v63, 16, 1
	v_add3_u32 v2, v63, v2, s80
	v_bfe_u32 v104, v67, 16, 1
	v_lshrrev_b32_e32 v2, 16, v2
	v_add3_u32 v104, v67, v104, s80
	v_and_or_b32 v104, v104, s85, v2
	v_bfe_u32 v2, v87, 16, 1
	v_add3_u32 v2, v87, v2, s80
	v_bfe_u32 v105, v91, 16, 1
	v_pk_mul_f32 v[24:25], v[24:25], v[106:107] op_sel_hi:[1,0]
	v_lshrrev_b32_e32 v2, 16, v2
	v_add3_u32 v105, v91, v105, s80
	v_pk_mul_f32 v[28:29], v[28:29], v[106:107] op_sel:[0,1]
	v_and_or_b32 v105, v105, s85, v2
	v_bfe_u32 v2, v24, 16, 1
	global_store_dwordx4 v[4:5], v[102:105], off offset:3072 nt
	v_add3_u32 v2, v24, v2, s80
	v_pk_mul_f32 v[48:49], v[48:49], v[108:109] op_sel_hi:[1,0]
	v_bfe_u32 v102, v28, 16, 1
	v_lshrrev_b32_e32 v2, 16, v2
	v_add3_u32 v102, v28, v102, s80
	v_and_or_b32 v102, v102, s85, v2
	v_bfe_u32 v2, v48, 16, 1
	v_add3_u32 v2, v48, v2, s80
	v_bfe_u32 v103, v20, 16, 1
	v_lshrrev_b32_e32 v2, 16, v2
	v_add3_u32 v103, v20, v103, s80
	v_and_or_b32 v103, v103, s85, v2
	v_bfe_u32 v2, v64, 16, 1
	v_add3_u32 v2, v64, v2, s80
	v_bfe_u32 v104, v68, 16, 1
	v_lshrrev_b32_e32 v2, 16, v2
	v_add3_u32 v104, v68, v104, s80
	v_and_or_b32 v104, v104, s85, v2
	v_bfe_u32 v2, v88, 16, 1
	v_add3_u32 v2, v88, v2, s80
	v_bfe_u32 v105, v92, 16, 1
	s_movk_i32 s5, 0x1000
	v_lshrrev_b32_e32 v2, 16, v2
	v_add3_u32 v105, v92, v105, s80
	v_add_co_u32_e32 v106, vcc, s5, v4
	v_and_or_b32 v105, v105, s85, v2
	s_nop 0
	v_addc_co_u32_e32 v107, vcc, 0, v5, vcc
	v_bfe_u32 v2, v25, 16, 1
	global_store_dwordx4 v[106:107], v[102:105], off offset:2048 nt
	v_add3_u32 v2, v25, v2, s80
	v_lshrrev_b32_e32 v2, 16, v2
	v_bfe_u32 v102, v29, 16, 1
	v_add3_u32 v102, v29, v102, s80
	v_and_or_b32 v102, v102, s85, v2
	v_bfe_u32 v2, v49, 16, 1
	v_add3_u32 v2, v49, v2, s80
	v_bfe_u32 v103, v21, 16, 1
	v_lshrrev_b32_e32 v2, 16, v2
	v_add3_u32 v103, v21, v103, s80
	v_and_or_b32 v103, v103, s85, v2
	v_bfe_u32 v2, v65, 16, 1
	v_add3_u32 v2, v65, v2, s80
	v_bfe_u32 v104, v69, 16, 1
	v_lshrrev_b32_e32 v2, 16, v2
	v_add3_u32 v104, v69, v104, s80
	v_and_or_b32 v104, v104, s85, v2
	v_bfe_u32 v2, v89, 16, 1
	v_add3_u32 v2, v89, v2, s80
	v_bfe_u32 v105, v93, 16, 1
	v_lshrrev_b32_e32 v2, 16, v2
	v_add3_u32 v105, v93, v105, s80
	v_add_co_u32_e32 v4, vcc, 0x2000, v4
	v_and_or_b32 v105, v105, s85, v2
	s_nop 0
	v_addc_co_u32_e32 v5, vcc, 0, v5, vcc
	global_store_dwordx4 v[4:5], v[102:105], off offset:1024 nt
	s_andn2_b64 vcc, exec, s[18:19]
	s_cbranch_vccnz .LBB0_2361
.LBB0_2405:
	s_lshr_b32 s5, s4, 31
	s_ashr_i32 s4, s4, 4
	s_add_i32 s4, s4, s5
	v_lshl_or_b32 v4, s4, 6, v231
	v_ashrrev_i32_e32 v5, 31, v4
	v_lshl_add_u64 v[106:107], v[4:5], 2, s[10:11]
	global_load_dwordx4 v[102:105], v[106:107], off offset:16
	s_nop 0
	global_load_dwordx4 v[106:109], v[106:107], off
	s_mulk_i32 s4, 0xf400
	s_add_i32 s4, s4, s0
	s_waitcnt vmcnt(1)
	v_pk_mul_f32 v[56:57], v[56:57], v[102:103] op_sel_hi:[1,0]
	s_waitcnt vmcnt(0)
	v_mov_b32_e32 v2, v109
	v_pk_mul_f32 v[12:13], v[12:13], v[2:3] op_sel_hi:[1,0]
	v_pk_mul_f32 v[10:11], v[10:11], v[2:3] op_sel_hi:[1,0]
	v_mov_b32_e32 v2, v105
	v_pk_mul_f32 v[6:7], v[6:7], v[106:107] op_sel_hi:[1,0]
	v_pk_mul_f32 v[54:55], v[54:55], v[102:103] op_sel_hi:[1,0]
	v_pk_mul_f32 v[60:61], v[60:61], v[102:103] op_sel:[0,1]
	v_pk_mul_f32 v[58:59], v[58:59], v[102:103] op_sel:[0,1]
	v_pk_mul_f32 v[84:85], v[84:85], v[2:3] op_sel_hi:[1,0]
	v_pk_mul_f32 v[82:83], v[82:83], v[2:3] op_sel_hi:[1,0]
	v_add_u32_e32 v2, s4, v147
	v_mov_b64_e32 v[102:103], s[16:17]
	v_pk_mul_f32 v[14:15], v[14:15], v[106:107] op_sel:[0,1]
	v_mad_i64_i32 v[102:103], s[4:5], v2, s68, v[102:103]
	v_bfe_u32 v2, v6, 16, 1
	v_lshl_add_u64 v[4:5], v[4:5], 1, v[102:103]
	v_add3_u32 v2, v6, v2, s80
	v_bfe_u32 v102, v14, 16, 1
	v_pk_mul_f32 v[42:43], v[42:43], v[108:109] op_sel_hi:[1,0]
	v_lshrrev_b32_e32 v2, 16, v2
	v_add3_u32 v102, v14, v102, s80
	v_and_or_b32 v102, v102, s85, v2
	v_bfe_u32 v2, v42, 16, 1
	v_add3_u32 v2, v42, v2, s80
	v_bfe_u32 v103, v10, 16, 1
	v_lshrrev_b32_e32 v2, 16, v2
	v_add3_u32 v103, v10, v103, s80
	v_and_or_b32 v103, v103, s85, v2
	v_bfe_u32 v2, v54, 16, 1
	v_pk_mul_f32 v[80:81], v[80:81], v[104:105] op_sel_hi:[1,0]
	v_pk_mul_f32 v[78:79], v[78:79], v[104:105] op_sel_hi:[1,0]
	v_add3_u32 v2, v54, v2, s80
	v_bfe_u32 v104, v58, 16, 1
	v_lshrrev_b32_e32 v2, 16, v2
	v_add3_u32 v104, v58, v104, s80
	v_and_or_b32 v104, v104, s85, v2
	v_bfe_u32 v2, v78, 16, 1
	v_add3_u32 v2, v78, v2, s80
	v_bfe_u32 v105, v82, 16, 1
	v_lshrrev_b32_e32 v2, 16, v2
	v_add3_u32 v105, v82, v105, s80
	v_and_or_b32 v105, v105, s85, v2
	v_bfe_u32 v2, v7, 16, 1
	global_store_dwordx4 v[4:5], v[102:105], off nt
	v_add3_u32 v2, v7, v2, s80
	v_lshrrev_b32_e32 v2, 16, v2
	v_bfe_u32 v102, v15, 16, 1
	v_add3_u32 v102, v15, v102, s80
	v_and_or_b32 v102, v102, s85, v2
	v_bfe_u32 v2, v43, 16, 1
	v_add3_u32 v2, v43, v2, s80
	v_bfe_u32 v103, v11, 16, 1
	v_lshrrev_b32_e32 v2, 16, v2
	v_add3_u32 v103, v11, v103, s80
	v_and_or_b32 v103, v103, s85, v2
	v_bfe_u32 v2, v55, 16, 1
	v_add3_u32 v2, v55, v2, s80
	v_bfe_u32 v104, v59, 16, 1
	v_lshrrev_b32_e32 v2, 16, v2
	v_add3_u32 v104, v59, v104, s80
	v_and_or_b32 v104, v104, s85, v2
	v_bfe_u32 v2, v79, 16, 1
	v_add3_u32 v2, v79, v2, s80
	v_bfe_u32 v105, v83, 16, 1
	v_pk_mul_f32 v[8:9], v[8:9], v[106:107] op_sel_hi:[1,0]
	v_lshrrev_b32_e32 v2, 16, v2
	v_add3_u32 v105, v83, v105, s80
	v_pk_mul_f32 v[16:17], v[16:17], v[106:107] op_sel:[0,1]
	v_and_or_b32 v105, v105, s85, v2
	v_bfe_u32 v2, v8, 16, 1
	global_store_dwordx4 v[4:5], v[102:105], off offset:3072 nt
	v_add3_u32 v2, v8, v2, s80
	v_pk_mul_f32 v[44:45], v[44:45], v[108:109] op_sel_hi:[1,0]
	v_bfe_u32 v102, v16, 16, 1
	v_lshrrev_b32_e32 v2, 16, v2
	v_add3_u32 v102, v16, v102, s80
	v_and_or_b32 v102, v102, s85, v2
	v_bfe_u32 v2, v44, 16, 1
	v_add3_u32 v2, v44, v2, s80
	v_bfe_u32 v103, v12, 16, 1
	v_lshrrev_b32_e32 v2, 16, v2
	v_add3_u32 v103, v12, v103, s80
	v_and_or_b32 v103, v103, s85, v2
	v_bfe_u32 v2, v56, 16, 1
	v_add3_u32 v2, v56, v2, s80
	v_bfe_u32 v104, v60, 16, 1
	v_lshrrev_b32_e32 v2, 16, v2
	v_add3_u32 v104, v60, v104, s80
	v_and_or_b32 v104, v104, s85, v2
	v_bfe_u32 v2, v80, 16, 1
	v_add3_u32 v2, v80, v2, s80
	v_bfe_u32 v105, v84, 16, 1
	s_movk_i32 s4, 0x1000
	v_lshrrev_b32_e32 v2, 16, v2
	v_add3_u32 v105, v84, v105, s80
	v_add_co_u32_e32 v106, vcc, s4, v4
	v_and_or_b32 v105, v105, s85, v2
	s_nop 0
	v_addc_co_u32_e32 v107, vcc, 0, v5, vcc
	v_bfe_u32 v2, v9, 16, 1
	global_store_dwordx4 v[106:107], v[102:105], off offset:2048 nt
	v_add3_u32 v2, v9, v2, s80
	v_lshrrev_b32_e32 v2, 16, v2
	v_bfe_u32 v102, v17, 16, 1
	v_add3_u32 v102, v17, v102, s80
	v_and_or_b32 v102, v102, s85, v2
	v_bfe_u32 v2, v45, 16, 1
	v_add3_u32 v2, v45, v2, s80
	v_bfe_u32 v103, v13, 16, 1
	v_lshrrev_b32_e32 v2, 16, v2
	v_add3_u32 v103, v13, v103, s80
	v_and_or_b32 v103, v103, s85, v2
	v_bfe_u32 v2, v57, 16, 1
	v_add3_u32 v2, v57, v2, s80
	v_bfe_u32 v104, v61, 16, 1
	v_lshrrev_b32_e32 v2, 16, v2
	v_add3_u32 v104, v61, v104, s80
	v_and_or_b32 v104, v104, s85, v2
	v_bfe_u32 v2, v81, 16, 1
	v_add3_u32 v2, v81, v2, s80
	v_bfe_u32 v105, v85, 16, 1
	v_lshrrev_b32_e32 v2, 16, v2
	v_add3_u32 v105, v85, v105, s80
	v_add_co_u32_e32 v4, vcc, 0x2000, v4
	v_and_or_b32 v105, v105, s85, v2
	s_nop 0
	v_addc_co_u32_e32 v5, vcc, 0, v5, vcc
	global_store_dwordx4 v[4:5], v[102:105], off offset:1024 nt
	s_branch .LBB0_2361

.LBB0_2447:
	v_lshl_add_u64 v[4:5], v[134:135], 2, s[8:9]
	global_load_dwordx4 v[146:149], v[4:5], off offset:2048
	global_load_dwordx4 v[150:153], v[4:5], off offset:2064
	v_ashrrev_i32_e32 v137, 31, v136
	v_lshlrev_b64 v[4:5], 10, v[136:137]
	v_lshl_add_u64 v[4:5], s[10:11], 0, v[4:5]
	v_lshl_add_u64 v[4:5], v[134:135], 1, v[4:5]
	s_andn2_b64 vcc, exec, s[20:21]
	s_waitcnt vmcnt(1)
	v_pk_mul_f32 v[134:135], v[112:113], v[146:147] op_sel_hi:[1,0]
	v_pk_mul_f32 v[110:111], v[110:111], v[146:147] op_sel_hi:[1,0]
	v_pk_mul_f32 v[136:137], v[108:109], v[146:147] op_sel:[0,1]
	v_pk_mul_f32 v[106:107], v[106:107], v[146:147] op_sel:[0,1]
	v_pk_mul_f32 v[108:109], v[114:115], v[148:149] op_sel_hi:[1,0]
	v_mov_b32_e32 v2, v149
	s_waitcnt vmcnt(0)
	v_pk_mul_f32 v[114:115], v[128:129], v[150:151] op_sel_hi:[1,0]
	v_pk_mul_f32 v[112:113], v[126:127], v[150:151] op_sel_hi:[1,0]
	v_pk_mul_f32 v[122:123], v[122:123], v[150:151] op_sel:[0,1]
	v_pk_mul_f32 v[128:129], v[130:131], v[152:153] op_sel_hi:[1,0]
	v_mov_b32_e32 v130, v153
	v_pk_mul_f32 v[126:127], v[132:133], v[152:153] op_sel_hi:[1,0]
	v_pk_mul_f32 v[132:133], v[104:105], v[2:3] op_sel_hi:[1,0]
	v_pk_mul_f32 v[102:103], v[102:103], v[2:3] op_sel_hi:[1,0]
	v_pk_mul_f32 v[120:121], v[120:121], v[130:131] op_sel_hi:[1,0]
	v_pk_mul_f32 v[104:105], v[118:119], v[130:131] op_sel_hi:[1,0]
	v_bfe_u32 v2, v110, 16, 1
	v_bfe_u32 v118, v106, 16, 1
	v_bfe_u32 v119, v108, 16, 1
	v_bfe_u32 v130, v112, 16, 1
	v_bfe_u32 v131, v122, 16, 1
	v_bfe_u32 v138, v128, 16, 1
	v_pk_mul_f32 v[116:117], v[116:117], v[148:149] op_sel_hi:[1,0]
	v_pk_mul_f32 v[124:125], v[124:125], v[150:151] op_sel:[0,1]
	v_bfe_u32 v139, v111, 16, 1
	v_bfe_u32 v147, v109, 16, 1
	v_bfe_u32 v148, v113, 16, 1
	v_bfe_u32 v150, v129, 16, 1
	v_add3_u32 v2, v110, v2, s80
	v_add3_u32 v106, v106, v118, s80
	v_add3_u32 v108, v108, v119, s80
	v_bfe_u32 v110, v102, 16, 1
	v_add3_u32 v112, v112, v130, s80
	v_add3_u32 v118, v122, v131, s80
	v_add3_u32 v119, v128, v138, s80
	v_bfe_u32 v122, v104, 16, 1
	v_bfe_u32 v146, v107, 16, 1
	v_bfe_u32 v149, v123, 16, 1
	v_add3_u32 v111, v111, v139, s80
	v_add3_u32 v109, v109, v147, s80
	v_bfe_u32 v128, v103, 16, 1
	v_add3_u32 v113, v113, v148, s80
	v_add3_u32 v129, v129, v150, s80
	v_bfe_u32 v130, v105, 16, 1
	v_lshrrev_b32_e32 v2, 16, v2
	v_lshrrev_b32_e32 v108, 16, v108
	v_add3_u32 v110, v102, v110, s80
	v_lshrrev_b32_e32 v112, 16, v112
	v_lshrrev_b32_e32 v119, 16, v119
	v_add3_u32 v122, v104, v122, s80
	v_add3_u32 v107, v107, v146, s80
	v_add3_u32 v123, v123, v149, s80
	v_lshrrev_b32_e32 v111, 16, v111
	v_lshrrev_b32_e32 v109, 16, v109
	v_add3_u32 v128, v103, v128, s80
	v_lshrrev_b32_e32 v113, 16, v113
	v_lshrrev_b32_e32 v129, 16, v129
	v_add3_u32 v130, v105, v130, s80
	v_and_or_b32 v102, v106, s85, v2
	v_and_or_b32 v103, v110, s85, v108
	v_and_or_b32 v104, v118, s85, v112
	v_and_or_b32 v105, v122, s85, v119
	v_bfe_u32 v2, v114, 16, 1
	v_and_or_b32 v106, v107, s85, v111
	v_and_or_b32 v107, v128, s85, v109
	v_and_or_b32 v108, v123, s85, v113
	v_and_or_b32 v109, v130, s85, v129
	global_store_dwordx4 v[4:5], v[102:105], off nt
	global_store_dwordx4 v[4:5], v[106:109], off offset:1024 nt
	v_add3_u32 v2, v114, v2, s80
	v_bfe_u32 v102, v124, 16, 1
	v_lshrrev_b32_e32 v2, 16, v2
	v_add3_u32 v102, v124, v102, s80
	v_and_or_b32 v112, v102, s85, v2
	v_bfe_u32 v2, v126, 16, 1
	v_add3_u32 v2, v126, v2, s80
	v_bfe_u32 v102, v120, 16, 1
	v_lshrrev_b32_e32 v2, 16, v2
	v_add3_u32 v102, v120, v102, s80
	v_and_or_b32 v113, v102, s85, v2
	v_bfe_u32 v2, v135, 16, 1
	v_add3_u32 v2, v135, v2, s80
	v_bfe_u32 v102, v137, 16, 1
	v_lshrrev_b32_e32 v2, 16, v2
	v_add3_u32 v102, v137, v102, s80
	v_and_or_b32 v102, v102, s85, v2
	v_bfe_u32 v2, v117, 16, 1
	v_add3_u32 v2, v117, v2, s80
	v_bfe_u32 v103, v133, 16, 1
	v_lshrrev_b32_e32 v2, 16, v2
	v_add3_u32 v103, v133, v103, s80
	v_and_or_b32 v103, v103, s85, v2
	v_bfe_u32 v2, v115, 16, 1
	v_add3_u32 v2, v115, v2, s80
	v_bfe_u32 v104, v125, 16, 1
	v_lshrrev_b32_e32 v2, 16, v2
	v_add3_u32 v104, v125, v104, s80
	v_bfe_u32 v151, v134, 16, 1
	v_bfe_u32 v152, v136, 16, 1
	v_bfe_u32 v153, v116, 16, 1
	v_and_or_b32 v104, v104, s85, v2
	v_bfe_u32 v2, v127, 16, 1
	v_add3_u32 v131, v134, v151, s80
	v_add3_u32 v134, v136, v152, s80
	v_add3_u32 v116, v116, v153, s80
	v_bfe_u32 v136, v132, 16, 1
	v_add3_u32 v2, v127, v2, s80
	v_bfe_u32 v105, v121, 16, 1
	v_lshrrev_b32_e32 v131, 16, v131
	v_lshrrev_b32_e32 v116, 16, v116
	v_add3_u32 v132, v132, v136, s80
	v_lshrrev_b32_e32 v2, 16, v2
	v_add3_u32 v105, v121, v105, s80
	v_and_or_b32 v110, v134, s85, v131
	v_and_or_b32 v111, v132, s85, v116
	v_and_or_b32 v105, v105, s85, v2
	global_store_dwordx4 v[4:5], v[110:113], off offset:2048 nt
	global_store_dwordx4 v[4:5], v[102:105], off offset:3072 nt
	s_cbranch_vccnz .LBB0_2450
	s_ashr_i32 s6, s27, 31
	s_lshr_b32 s6, s6, 25
	s_add_i32 s27, s27, s6
	s_ashr_i32 s6, s27, 7
	v_lshl_or_b32 v4, s6, 6, v231
	v_ashrrev_i32_e32 v5, 31, v4
	v_lshl_add_u64 v[106:107], v[4:5], 2, s[8:9]
	global_load_dwordx4 v[102:105], v[106:107], off offset:2064
	s_nop 0
	global_load_dwordx4 v[106:109], v[106:107], off offset:2048
	s_lshl_b32 s6, s6, 12
	s_waitcnt vmcnt(1)
	v_pk_mul_f32 v[72:73], v[72:73], v[102:103] op_sel_hi:[1,0]
	v_pk_mul_f32 v[70:71], v[70:71], v[102:103] op_sel_hi:[1,0]
	v_pk_mul_f32 v[76:77], v[76:77], v[102:103] op_sel:[0,1]
	v_pk_mul_f32 v[74:75], v[74:75], v[102:103] op_sel:[0,1]
	v_subrev_u32_e32 v102, s6, v145
	s_waitcnt vmcnt(0)
	v_mov_b32_e32 v2, v109
	v_ashrrev_i32_e32 v103, 31, v102
	v_pk_mul_f32 v[30:31], v[30:31], v[106:107] op_sel_hi:[1,0]
	v_pk_mul_f32 v[36:37], v[36:37], v[2:3] op_sel_hi:[1,0]
	v_pk_mul_f32 v[34:35], v[34:35], v[2:3] op_sel_hi:[1,0]
	v_mov_b32_e32 v2, v105
	v_lshlrev_b64 v[102:103], 10, v[102:103]
	v_pk_mul_f32 v[38:39], v[38:39], v[106:107] op_sel:[0,1]
	v_pk_mul_f32 v[100:101], v[100:101], v[2:3] op_sel_hi:[1,0]
	v_pk_mul_f32 v[98:99], v[98:99], v[2:3] op_sel_hi:[1,0]
	v_lshl_add_u64 v[102:103], s[10:11], 0, v[102:103]
	v_bfe_u32 v2, v30, 16, 1
	v_lshl_add_u64 v[4:5], v[4:5], 1, v[102:103]
	v_add3_u32 v2, v30, v2, s80
	v_bfe_u32 v102, v38, 16, 1
	v_pk_mul_f32 v[50:51], v[50:51], v[108:109] op_sel_hi:[1,0]
	v_lshrrev_b32_e32 v2, 16, v2
	v_add3_u32 v102, v38, v102, s80
	v_and_or_b32 v102, v102, s85, v2
	v_bfe_u32 v2, v50, 16, 1
	v_add3_u32 v2, v50, v2, s80
	v_bfe_u32 v103, v34, 16, 1
	v_lshrrev_b32_e32 v2, 16, v2
	v_add3_u32 v103, v34, v103, s80
	v_and_or_b32 v103, v103, s85, v2
	v_bfe_u32 v2, v70, 16, 1
	v_pk_mul_f32 v[96:97], v[96:97], v[104:105] op_sel_hi:[1,0]
	v_pk_mul_f32 v[94:95], v[94:95], v[104:105] op_sel_hi:[1,0]
	v_add3_u32 v2, v70, v2, s80
	v_bfe_u32 v104, v74, 16, 1
	v_lshrrev_b32_e32 v2, 16, v2
	v_add3_u32 v104, v74, v104, s80
	v_and_or_b32 v104, v104, s85, v2
	v_bfe_u32 v2, v94, 16, 1
	v_add3_u32 v2, v94, v2, s80
	v_bfe_u32 v105, v98, 16, 1
	v_lshrrev_b32_e32 v2, 16, v2
	v_add3_u32 v105, v98, v105, s80
	v_and_or_b32 v105, v105, s85, v2
	v_bfe_u32 v2, v31, 16, 1
	global_store_dwordx4 v[4:5], v[102:105], off nt
	v_add3_u32 v2, v31, v2, s80
	v_lshrrev_b32_e32 v2, 16, v2
	v_bfe_u32 v102, v39, 16, 1
	v_add3_u32 v102, v39, v102, s80
	v_and_or_b32 v102, v102, s85, v2
	v_bfe_u32 v2, v51, 16, 1
	v_add3_u32 v2, v51, v2, s80
	v_bfe_u32 v103, v35, 16, 1
	v_lshrrev_b32_e32 v2, 16, v2
	v_add3_u32 v103, v35, v103, s80
	v_and_or_b32 v103, v103, s85, v2
	v_bfe_u32 v2, v71, 16, 1
	v_add3_u32 v2, v71, v2, s80
	v_bfe_u32 v104, v75, 16, 1
	v_lshrrev_b32_e32 v2, 16, v2
	v_add3_u32 v104, v75, v104, s80
	v_and_or_b32 v104, v104, s85, v2
	v_bfe_u32 v2, v95, 16, 1
	v_add3_u32 v2, v95, v2, s80
	v_bfe_u32 v105, v99, 16, 1
	v_pk_mul_f32 v[32:33], v[32:33], v[106:107] op_sel_hi:[1,0]
	v_lshrrev_b32_e32 v2, 16, v2
	v_add3_u32 v105, v99, v105, s80
	v_pk_mul_f32 v[40:41], v[40:41], v[106:107] op_sel:[0,1]
	v_and_or_b32 v105, v105, s85, v2
	v_bfe_u32 v2, v32, 16, 1
	global_store_dwordx4 v[4:5], v[102:105], off offset:1024 nt
	v_add3_u32 v2, v32, v2, s80
	v_pk_mul_f32 v[52:53], v[52:53], v[108:109] op_sel_hi:[1,0]
	v_bfe_u32 v102, v40, 16, 1
	v_lshrrev_b32_e32 v2, 16, v2
	v_add3_u32 v102, v40, v102, s80
	v_and_or_b32 v102, v102, s85, v2
	v_bfe_u32 v2, v52, 16, 1
	v_add3_u32 v2, v52, v2, s80
	v_bfe_u32 v103, v36, 16, 1
	v_lshrrev_b32_e32 v2, 16, v2
	v_add3_u32 v103, v36, v103, s80
	v_and_or_b32 v103, v103, s85, v2
	v_bfe_u32 v2, v72, 16, 1
	v_add3_u32 v2, v72, v2, s80
	v_bfe_u32 v104, v76, 16, 1
	v_lshrrev_b32_e32 v2, 16, v2
	v_add3_u32 v104, v76, v104, s80
	v_and_or_b32 v104, v104, s85, v2
	v_bfe_u32 v2, v96, 16, 1
	v_add3_u32 v2, v96, v2, s80
	v_bfe_u32 v105, v100, 16, 1
	v_lshrrev_b32_e32 v2, 16, v2
	v_add3_u32 v105, v100, v105, s80
	v_and_or_b32 v105, v105, s85, v2
	v_bfe_u32 v2, v33, 16, 1
	global_store_dwordx4 v[4:5], v[102:105], off offset:2048 nt
	v_add3_u32 v2, v33, v2, s80
	v_lshrrev_b32_e32 v2, 16, v2
	v_bfe_u32 v102, v41, 16, 1
	v_add3_u32 v102, v41, v102, s80
	v_and_or_b32 v102, v102, s85, v2
	v_bfe_u32 v2, v53, 16, 1
	v_add3_u32 v2, v53, v2, s80
	v_bfe_u32 v103, v37, 16, 1
	v_lshrrev_b32_e32 v2, 16, v2
	v_add3_u32 v103, v37, v103, s80
	v_and_or_b32 v103, v103, s85, v2
	v_bfe_u32 v2, v73, 16, 1
	v_add3_u32 v2, v73, v2, s80
	v_bfe_u32 v104, v77, 16, 1
	v_lshrrev_b32_e32 v2, 16, v2
	v_add3_u32 v104, v77, v104, s80
	v_and_or_b32 v104, v104, s85, v2
	v_bfe_u32 v2, v97, 16, 1
	v_add3_u32 v2, v97, v2, s80
	v_bfe_u32 v105, v101, 16, 1
	v_lshrrev_b32_e32 v2, 16, v2
	v_add3_u32 v105, v101, v105, s80
	v_and_or_b32 v105, v105, s85, v2
	global_store_dwordx4 v[4:5], v[102:105], off offset:3072 nt
	s_andn2_b64 vcc, exec, s[18:19]
	s_cbranch_vccz .LBB0_2451

.LBB0_2451:
	s_ashr_i32 s6, s25, 31
	s_lshr_b32 s6, s6, 25
	s_add_i32 s25, s25, s6
	s_ashr_i32 s6, s25, 7
	v_lshl_or_b32 v4, s6, 6, v231
	v_ashrrev_i32_e32 v5, 31, v4
	v_lshl_add_u64 v[106:107], v[4:5], 2, s[8:9]
	global_load_dwordx4 v[102:105], v[106:107], off offset:2064
	s_nop 0
	global_load_dwordx4 v[106:109], v[106:107], off offset:2048
	s_lshl_b32 s6, s6, 12
	s_waitcnt vmcnt(1)
	v_pk_mul_f32 v[64:65], v[64:65], v[102:103] op_sel_hi:[1,0]
	v_pk_mul_f32 v[62:63], v[62:63], v[102:103] op_sel_hi:[1,0]
	v_pk_mul_f32 v[68:69], v[68:69], v[102:103] op_sel:[0,1]
	v_pk_mul_f32 v[66:67], v[66:67], v[102:103] op_sel:[0,1]
	v_subrev_u32_e32 v102, s6, v144
	s_waitcnt vmcnt(0)
	v_mov_b32_e32 v2, v109
	v_ashrrev_i32_e32 v103, 31, v102
	v_pk_mul_f32 v[22:23], v[22:23], v[106:107] op_sel_hi:[1,0]
	v_pk_mul_f32 v[20:21], v[20:21], v[2:3] op_sel_hi:[1,0]
	v_pk_mul_f32 v[18:19], v[18:19], v[2:3] op_sel_hi:[1,0]
	v_mov_b32_e32 v2, v105
	v_lshlrev_b64 v[102:103], 10, v[102:103]
	v_pk_mul_f32 v[26:27], v[26:27], v[106:107] op_sel:[0,1]
	v_pk_mul_f32 v[92:93], v[92:93], v[2:3] op_sel_hi:[1,0]
	v_pk_mul_f32 v[90:91], v[90:91], v[2:3] op_sel_hi:[1,0]
	v_lshl_add_u64 v[102:103], s[10:11], 0, v[102:103]
	v_bfe_u32 v2, v22, 16, 1
	v_lshl_add_u64 v[4:5], v[4:5], 1, v[102:103]
	v_add3_u32 v2, v22, v2, s80
	v_bfe_u32 v102, v26, 16, 1
	v_pk_mul_f32 v[46:47], v[46:47], v[108:109] op_sel_hi:[1,0]
	v_lshrrev_b32_e32 v2, 16, v2
	v_add3_u32 v102, v26, v102, s80
	v_and_or_b32 v102, v102, s85, v2
	v_bfe_u32 v2, v46, 16, 1
	v_add3_u32 v2, v46, v2, s80
	v_bfe_u32 v103, v18, 16, 1
	v_lshrrev_b32_e32 v2, 16, v2
	v_add3_u32 v103, v18, v103, s80
	v_and_or_b32 v103, v103, s85, v2
	v_bfe_u32 v2, v62, 16, 1
	v_pk_mul_f32 v[88:89], v[88:89], v[104:105] op_sel_hi:[1,0]
	v_pk_mul_f32 v[86:87], v[86:87], v[104:105] op_sel_hi:[1,0]
	v_add3_u32 v2, v62, v2, s80
	v_bfe_u32 v104, v66, 16, 1
	v_lshrrev_b32_e32 v2, 16, v2
	v_add3_u32 v104, v66, v104, s80
	v_and_or_b32 v104, v104, s85, v2
	v_bfe_u32 v2, v86, 16, 1
	v_add3_u32 v2, v86, v2, s80
	v_bfe_u32 v105, v90, 16, 1
	v_lshrrev_b32_e32 v2, 16, v2
	v_add3_u32 v105, v90, v105, s80
	v_and_or_b32 v105, v105, s85, v2
	v_bfe_u32 v2, v23, 16, 1
	global_store_dwordx4 v[4:5], v[102:105], off nt
	v_add3_u32 v2, v23, v2, s80
	v_lshrrev_b32_e32 v2, 16, v2
	v_bfe_u32 v102, v27, 16, 1
	v_add3_u32 v102, v27, v102, s80
	v_and_or_b32 v102, v102, s85, v2
	v_bfe_u32 v2, v47, 16, 1
	v_add3_u32 v2, v47, v2, s80
	v_bfe_u32 v103, v19, 16, 1
	v_lshrrev_b32_e32 v2, 16, v2
	v_add3_u32 v103, v19, v103, s80
	v_and_or_b32 v103, v103, s85, v2
	v_bfe_u32 v2, v63, 16, 1
	v_add3_u32 v2, v63, v2, s80
	v_bfe_u32 v104, v67, 16, 1
	v_lshrrev_b32_e32 v2, 16, v2
	v_add3_u32 v104, v67, v104, s80
	v_and_or_b32 v104, v104, s85, v2
	v_bfe_u32 v2, v87, 16, 1
	v_add3_u32 v2, v87, v2, s80
	v_bfe_u32 v105, v91, 16, 1
	v_pk_mul_f32 v[24:25], v[24:25], v[106:107] op_sel_hi:[1,0]
	v_lshrrev_b32_e32 v2, 16, v2
	v_add3_u32 v105, v91, v105, s80
	v_pk_mul_f32 v[28:29], v[28:29], v[106:107] op_sel:[0,1]
	v_and_or_b32 v105, v105, s85, v2
	v_bfe_u32 v2, v24, 16, 1
	global_store_dwordx4 v[4:5], v[102:105], off offset:1024 nt
	v_add3_u32 v2, v24, v2, s80
	v_pk_mul_f32 v[48:49], v[48:49], v[108:109] op_sel_hi:[1,0]
	v_bfe_u32 v102, v28, 16, 1
	v_lshrrev_b32_e32 v2, 16, v2
	v_add3_u32 v102, v28, v102, s80
	v_and_or_b32 v102, v102, s85, v2
	v_bfe_u32 v2, v48, 16, 1
	v_add3_u32 v2, v48, v2, s80
	v_bfe_u32 v103, v20, 16, 1
	v_lshrrev_b32_e32 v2, 16, v2
	v_add3_u32 v103, v20, v103, s80
	v_and_or_b32 v103, v103, s85, v2
	v_bfe_u32 v2, v64, 16, 1
	v_add3_u32 v2, v64, v2, s80
	v_bfe_u32 v104, v68, 16, 1
	v_lshrrev_b32_e32 v2, 16, v2
	v_add3_u32 v104, v68, v104, s80
	v_and_or_b32 v104, v104, s85, v2
	v_bfe_u32 v2, v88, 16, 1
	v_add3_u32 v2, v88, v2, s80
	v_bfe_u32 v105, v92, 16, 1
	v_lshrrev_b32_e32 v2, 16, v2
	v_add3_u32 v105, v92, v105, s80
	v_and_or_b32 v105, v105, s85, v2
	v_bfe_u32 v2, v25, 16, 1
	global_store_dwordx4 v[4:5], v[102:105], off offset:2048 nt
	v_add3_u32 v2, v25, v2, s80
	v_lshrrev_b32_e32 v2, 16, v2
	v_bfe_u32 v102, v29, 16, 1
	v_add3_u32 v102, v29, v102, s80
	v_and_or_b32 v102, v102, s85, v2
	v_bfe_u32 v2, v49, 16, 1
	v_add3_u32 v2, v49, v2, s80
	v_bfe_u32 v103, v21, 16, 1
	v_lshrrev_b32_e32 v2, 16, v2
	v_add3_u32 v103, v21, v103, s80
	v_and_or_b32 v103, v103, s85, v2
	v_bfe_u32 v2, v65, 16, 1
	v_add3_u32 v2, v65, v2, s80
	v_bfe_u32 v104, v69, 16, 1
	v_lshrrev_b32_e32 v2, 16, v2
	v_add3_u32 v104, v69, v104, s80
	v_and_or_b32 v104, v104, s85, v2
	v_bfe_u32 v2, v89, 16, 1
	v_add3_u32 v2, v89, v2, s80
	v_bfe_u32 v105, v93, 16, 1
	v_lshrrev_b32_e32 v2, 16, v2
	v_add3_u32 v105, v93, v105, s80
	v_and_or_b32 v105, v105, s85, v2
	global_store_dwordx4 v[4:5], v[102:105], off offset:3072 nt
	s_andn2_b64 vcc, exec, s[16:17]
	s_cbranch_vccnz .LBB0_2408
.LBB0_2452:
	s_ashr_i32 s6, s15, 31
	s_lshr_b32 s6, s6, 25
	s_add_i32 s15, s15, s6
	s_ashr_i32 s6, s15, 7
	v_lshl_or_b32 v4, s6, 6, v231
	v_ashrrev_i32_e32 v5, 31, v4
	v_lshl_add_u64 v[106:107], v[4:5], 2, s[8:9]
	global_load_dwordx4 v[102:105], v[106:107], off offset:2064
	s_nop 0
	global_load_dwordx4 v[106:109], v[106:107], off offset:2048
	s_lshl_b32 s6, s6, 12
	s_waitcnt vmcnt(1)
	v_pk_mul_f32 v[56:57], v[56:57], v[102:103] op_sel_hi:[1,0]
	v_pk_mul_f32 v[54:55], v[54:55], v[102:103] op_sel_hi:[1,0]
	v_pk_mul_f32 v[60:61], v[60:61], v[102:103] op_sel:[0,1]
	v_pk_mul_f32 v[58:59], v[58:59], v[102:103] op_sel:[0,1]
	v_subrev_u32_e32 v102, s6, v143
	s_waitcnt vmcnt(0)
	v_mov_b32_e32 v2, v109
	v_ashrrev_i32_e32 v103, 31, v102
	v_pk_mul_f32 v[6:7], v[6:7], v[106:107] op_sel_hi:[1,0]
	v_pk_mul_f32 v[12:13], v[12:13], v[2:3] op_sel_hi:[1,0]
	v_pk_mul_f32 v[10:11], v[10:11], v[2:3] op_sel_hi:[1,0]
	v_mov_b32_e32 v2, v105
	v_lshlrev_b64 v[102:103], 10, v[102:103]
	v_pk_mul_f32 v[14:15], v[14:15], v[106:107] op_sel:[0,1]
	v_pk_mul_f32 v[84:85], v[84:85], v[2:3] op_sel_hi:[1,0]
	v_pk_mul_f32 v[82:83], v[82:83], v[2:3] op_sel_hi:[1,0]
	v_lshl_add_u64 v[102:103], s[10:11], 0, v[102:103]
	v_bfe_u32 v2, v6, 16, 1
	v_lshl_add_u64 v[4:5], v[4:5], 1, v[102:103]
	v_add3_u32 v2, v6, v2, s80
	v_bfe_u32 v102, v14, 16, 1
	v_pk_mul_f32 v[42:43], v[42:43], v[108:109] op_sel_hi:[1,0]
	v_lshrrev_b32_e32 v2, 16, v2
	v_add3_u32 v102, v14, v102, s80
	v_and_or_b32 v102, v102, s85, v2
	v_bfe_u32 v2, v42, 16, 1
	v_add3_u32 v2, v42, v2, s80
	v_bfe_u32 v103, v10, 16, 1
	v_lshrrev_b32_e32 v2, 16, v2
	v_add3_u32 v103, v10, v103, s80
	v_and_or_b32 v103, v103, s85, v2
	v_bfe_u32 v2, v54, 16, 1
	v_pk_mul_f32 v[80:81], v[80:81], v[104:105] op_sel_hi:[1,0]
	v_pk_mul_f32 v[78:79], v[78:79], v[104:105] op_sel_hi:[1,0]
	v_add3_u32 v2, v54, v2, s80
	v_bfe_u32 v104, v58, 16, 1
	v_lshrrev_b32_e32 v2, 16, v2
	v_add3_u32 v104, v58, v104, s80
	v_and_or_b32 v104, v104, s85, v2
	v_bfe_u32 v2, v78, 16, 1
	v_add3_u32 v2, v78, v2, s80
	v_bfe_u32 v105, v82, 16, 1
	v_lshrrev_b32_e32 v2, 16, v2
	v_add3_u32 v105, v82, v105, s80
	v_and_or_b32 v105, v105, s85, v2
	v_bfe_u32 v2, v7, 16, 1
	global_store_dwordx4 v[4:5], v[102:105], off nt
	v_add3_u32 v2, v7, v2, s80
	v_lshrrev_b32_e32 v2, 16, v2
	v_bfe_u32 v102, v15, 16, 1
	v_add3_u32 v102, v15, v102, s80
	v_and_or_b32 v102, v102, s85, v2
	v_bfe_u32 v2, v43, 16, 1
	v_add3_u32 v2, v43, v2, s80
	v_bfe_u32 v103, v11, 16, 1
	v_lshrrev_b32_e32 v2, 16, v2
	v_add3_u32 v103, v11, v103, s80
	v_and_or_b32 v103, v103, s85, v2
	v_bfe_u32 v2, v55, 16, 1
	v_add3_u32 v2, v55, v2, s80
	v_bfe_u32 v104, v59, 16, 1
	v_lshrrev_b32_e32 v2, 16, v2
	v_add3_u32 v104, v59, v104, s80
	v_and_or_b32 v104, v104, s85, v2
	v_bfe_u32 v2, v79, 16, 1
	v_add3_u32 v2, v79, v2, s80
	v_bfe_u32 v105, v83, 16, 1
	v_pk_mul_f32 v[8:9], v[8:9], v[106:107] op_sel_hi:[1,0]
	v_lshrrev_b32_e32 v2, 16, v2
	v_add3_u32 v105, v83, v105, s80
	v_pk_mul_f32 v[16:17], v[16:17], v[106:107] op_sel:[0,1]
	v_and_or_b32 v105, v105, s85, v2
	v_bfe_u32 v2, v8, 16, 1
	global_store_dwordx4 v[4:5], v[102:105], off offset:1024 nt
	v_add3_u32 v2, v8, v2, s80
	v_pk_mul_f32 v[44:45], v[44:45], v[108:109] op_sel_hi:[1,0]
	v_bfe_u32 v102, v16, 16, 1
	v_lshrrev_b32_e32 v2, 16, v2
	v_add3_u32 v102, v16, v102, s80
	v_and_or_b32 v102, v102, s85, v2
	v_bfe_u32 v2, v44, 16, 1
	v_add3_u32 v2, v44, v2, s80
	v_bfe_u32 v103, v12, 16, 1
	v_lshrrev_b32_e32 v2, 16, v2
	v_add3_u32 v103, v12, v103, s80
	v_and_or_b32 v103, v103, s85, v2
	v_bfe_u32 v2, v56, 16, 1
	v_add3_u32 v2, v56, v2, s80
	v_bfe_u32 v104, v60, 16, 1
	v_lshrrev_b32_e32 v2, 16, v2
	v_add3_u32 v104, v60, v104, s80
	v_and_or_b32 v104, v104, s85, v2
	v_bfe_u32 v2, v80, 16, 1
	v_add3_u32 v2, v80, v2, s80
	v_bfe_u32 v105, v84, 16, 1
	v_lshrrev_b32_e32 v2, 16, v2
	v_add3_u32 v105, v84, v105, s80
	v_and_or_b32 v105, v105, s85, v2
	v_bfe_u32 v2, v9, 16, 1
	global_store_dwordx4 v[4:5], v[102:105], off offset:2048 nt
	v_add3_u32 v2, v9, v2, s80
	v_lshrrev_b32_e32 v2, 16, v2
	v_bfe_u32 v102, v17, 16, 1
	v_add3_u32 v102, v17, v102, s80
	v_and_or_b32 v102, v102, s85, v2
	v_bfe_u32 v2, v45, 16, 1
	v_add3_u32 v2, v45, v2, s80
	v_bfe_u32 v103, v13, 16, 1
	v_lshrrev_b32_e32 v2, 16, v2
	v_add3_u32 v103, v13, v103, s80
	v_and_or_b32 v103, v103, s85, v2
	v_bfe_u32 v2, v57, 16, 1
	v_add3_u32 v2, v57, v2, s80
	v_bfe_u32 v104, v61, 16, 1
	v_lshrrev_b32_e32 v2, 16, v2
	v_add3_u32 v104, v61, v104, s80
	v_and_or_b32 v104, v104, s85, v2
	v_bfe_u32 v2, v81, 16, 1
	v_add3_u32 v2, v81, v2, s80
	v_bfe_u32 v105, v85, 16, 1
	v_lshrrev_b32_e32 v2, 16, v2
	v_add3_u32 v105, v85, v105, s80
	v_and_or_b32 v105, v105, s85, v2
	global_store_dwordx4 v[4:5], v[102:105], off offset:3072 nt
	s_branch .LBB0_2408

.LBB0_2499:
	s_waitcnt vmcnt(1)
	v_bfe_u32 v2, v104, 16, 1
	v_mov_b64_e32 v[138:139], s[18:19]
	v_add3_u32 v2, v104, v2, s80
	s_waitcnt vmcnt(0)
	v_bfe_u32 v104, v100, 16, 1
	v_mad_i64_i32 v[138:139], s[6:7], v137, s91, v[138:139]
	v_lshrrev_b32_e32 v2, 16, v2
	v_add3_u32 v100, v100, v104, s80
	v_lshl_add_u64 v[132:133], v[132:133], 1, v[138:139]
	v_and_or_b32 v138, v100, s85, v2
	v_bfe_u32 v2, v116, 16, 1
	v_add3_u32 v2, v116, v2, s80
	v_bfe_u32 v100, v112, 16, 1
	v_lshrrev_b32_e32 v2, 16, v2
	v_add3_u32 v100, v112, v100, s80
	v_and_or_b32 v139, v100, s85, v2
	v_bfe_u32 v2, v120, 16, 1
	v_add3_u32 v2, v120, v2, s80
	v_bfe_u32 v100, v108, 16, 1
	v_lshrrev_b32_e32 v2, 16, v2
	v_add3_u32 v100, v108, v100, s80
	v_and_or_b32 v140, v100, s85, v2
	v_bfe_u32 v2, v128, 16, 1
	v_add3_u32 v2, v128, v2, s80
	v_bfe_u32 v100, v124, 16, 1
	v_lshrrev_b32_e32 v2, 16, v2
	v_add3_u32 v100, v124, v100, s80
	v_and_or_b32 v141, v100, s85, v2
	v_bfe_u32 v2, v105, 16, 1
	v_add3_u32 v2, v105, v2, s80
	v_bfe_u32 v100, v101, 16, 1
	v_lshrrev_b32_e32 v2, 16, v2
	v_add3_u32 v100, v101, v100, s80
	global_store_dwordx4 v[132:133], v[138:141], off nt
	s_nop 1
	v_and_or_b32 v138, v100, s85, v2
	v_bfe_u32 v2, v117, 16, 1
	v_add3_u32 v2, v117, v2, s80
	v_bfe_u32 v100, v113, 16, 1
	v_lshrrev_b32_e32 v2, 16, v2
	v_add3_u32 v100, v113, v100, s80
	v_and_or_b32 v139, v100, s85, v2
	v_bfe_u32 v2, v121, 16, 1
	v_add3_u32 v2, v121, v2, s80
	v_bfe_u32 v100, v109, 16, 1
	v_lshrrev_b32_e32 v2, 16, v2
	v_add3_u32 v100, v109, v100, s80
	v_and_or_b32 v140, v100, s85, v2
	v_bfe_u32 v2, v129, 16, 1
	v_add3_u32 v2, v129, v2, s80
	v_bfe_u32 v100, v125, 16, 1
	v_lshrrev_b32_e32 v2, 16, v2
	v_add3_u32 v100, v125, v100, s80
	v_and_or_b32 v141, v100, s85, v2
	v_add_co_u32_e32 v100, vcc, s91, v132
	v_bfe_u32 v2, v106, 16, 1
	s_nop 0
	v_addc_co_u32_e32 v101, vcc, 0, v133, vcc
	global_store_dwordx4 v[100:101], v[138:141], off nt
	v_add3_u32 v2, v106, v2, s80
	v_bfe_u32 v100, v102, 16, 1
	v_lshrrev_b32_e32 v2, 16, v2
	v_add3_u32 v100, v102, v100, s80
	v_and_or_b32 v138, v100, s85, v2
	v_bfe_u32 v2, v118, 16, 1
	v_add3_u32 v2, v118, v2, s80
	v_bfe_u32 v100, v114, 16, 1
	v_lshrrev_b32_e32 v2, 16, v2
	v_add3_u32 v100, v114, v100, s80
	v_and_or_b32 v139, v100, s85, v2
	v_bfe_u32 v2, v122, 16, 1
	v_add3_u32 v2, v122, v2, s80
	v_bfe_u32 v100, v110, 16, 1
	v_lshrrev_b32_e32 v2, 16, v2
	v_add3_u32 v100, v110, v100, s80
	v_and_or_b32 v140, v100, s85, v2
	v_bfe_u32 v2, v130, 16, 1
	v_add3_u32 v2, v130, v2, s80
	v_bfe_u32 v100, v126, 16, 1
	v_lshrrev_b32_e32 v2, 16, v2
	v_add3_u32 v100, v126, v100, s80
	v_and_or_b32 v141, v100, s85, v2
	v_add_co_u32_e32 v100, vcc, s87, v132
	v_bfe_u32 v2, v107, 16, 1
	s_nop 0
	v_addc_co_u32_e32 v101, vcc, 0, v133, vcc
	global_store_dwordx4 v[100:101], v[138:141], off nt
	v_add3_u32 v2, v107, v2, s80
	v_bfe_u32 v100, v103, 16, 1
	v_lshrrev_b32_e32 v2, 16, v2
	v_add3_u32 v100, v103, v100, s80
	v_and_or_b32 v100, v100, s85, v2
	v_bfe_u32 v2, v119, 16, 1
	v_add3_u32 v2, v119, v2, s80
	v_bfe_u32 v101, v115, 16, 1
	v_lshrrev_b32_e32 v2, 16, v2
	v_add3_u32 v101, v115, v101, s80
	v_and_or_b32 v101, v101, s85, v2
	v_bfe_u32 v2, v123, 16, 1
	v_add3_u32 v2, v123, v2, s80
	v_bfe_u32 v102, v111, 16, 1
	v_lshrrev_b32_e32 v2, 16, v2
	v_add3_u32 v102, v111, v102, s80
	v_and_or_b32 v102, v102, s85, v2
	v_bfe_u32 v2, v131, 16, 1
	v_add3_u32 v2, v131, v2, s80
	v_bfe_u32 v103, v127, 16, 1
	v_add_co_u32_e32 v104, vcc, 0x9000, v132
	v_lshrrev_b32_e32 v2, 16, v2
	v_add3_u32 v103, v127, v103, s80
	v_addc_co_u32_e32 v105, vcc, 0, v133, vcc
	v_and_or_b32 v103, v103, s85, v2
	s_andn2_b64 vcc, exec, s[20:21]
	global_store_dwordx4 v[104:105], v[100:103], off nt
	s_cbranch_vccnz .LBB0_2502
	s_ashr_i32 s6, s4, 31
	s_lshr_b32 s6, s6, 25
	s_add_i32 s4, s4, s6
	s_ashr_i32 s4, s4, 7
	v_lshl_or_b32 v100, s4, 6, v231
	v_add_u32_e32 v2, s0, v136
	s_lshl_b32 s4, s4, 12
	v_subrev_u32_e32 v2, s4, v2
	v_mov_b64_e32 v[102:103], s[18:19]
	v_ashrrev_i32_e32 v101, 31, v100
	v_mad_i64_i32 v[102:103], s[6:7], v2, s91, v[102:103]
	v_bfe_u32 v2, v36, 16, 1
	v_lshl_add_u64 v[104:105], v[100:101], 1, v[102:103]
	v_add3_u32 v2, v36, v2, s80
	v_bfe_u32 v100, v32, 16, 1
	v_lshrrev_b32_e32 v2, 16, v2
	v_add3_u32 v100, v32, v100, s80
	v_and_or_b32 v100, v100, s85, v2
	v_bfe_u32 v2, v64, 16, 1
	v_add3_u32 v2, v64, v2, s80
	v_bfe_u32 v101, v60, 16, 1
	v_lshrrev_b32_e32 v2, 16, v2
	v_add3_u32 v101, v60, v101, s80
	v_and_or_b32 v101, v101, s85, v2
	v_bfe_u32 v2, v80, 16, 1
	v_add3_u32 v2, v80, v2, s80
	v_bfe_u32 v102, v56, 16, 1
	v_lshrrev_b32_e32 v2, 16, v2
	v_add3_u32 v102, v56, v102, s80
	v_and_or_b32 v102, v102, s85, v2
	v_bfe_u32 v2, v92, 16, 1
	v_add3_u32 v2, v92, v2, s80
	v_bfe_u32 v103, v96, 16, 1
	v_lshrrev_b32_e32 v2, 16, v2
	v_add3_u32 v103, v96, v103, s80
	v_and_or_b32 v103, v103, s85, v2
	v_bfe_u32 v2, v37, 16, 1
	global_store_dwordx4 v[104:105], v[100:103], off nt
	v_add3_u32 v2, v37, v2, s80
	v_lshrrev_b32_e32 v2, 16, v2
	v_bfe_u32 v100, v33, 16, 1
	v_add3_u32 v100, v33, v100, s80
	v_and_or_b32 v100, v100, s85, v2
	v_bfe_u32 v2, v65, 16, 1
	v_add3_u32 v2, v65, v2, s80
	v_bfe_u32 v101, v61, 16, 1
	v_lshrrev_b32_e32 v2, 16, v2
	v_add3_u32 v101, v61, v101, s80
	v_and_or_b32 v101, v101, s85, v2
	v_bfe_u32 v2, v81, 16, 1
	v_add3_u32 v2, v81, v2, s80
	v_bfe_u32 v102, v57, 16, 1
	v_lshrrev_b32_e32 v2, 16, v2
	v_add3_u32 v102, v57, v102, s80
	v_and_or_b32 v102, v102, s85, v2
	v_bfe_u32 v2, v93, 16, 1
	v_add3_u32 v2, v93, v2, s80
	v_bfe_u32 v103, v97, 16, 1
	v_lshrrev_b32_e32 v2, 16, v2
	v_add3_u32 v103, v97, v103, s80
	v_add_co_u32_e32 v106, vcc, s91, v104
	v_and_or_b32 v103, v103, s85, v2
	s_nop 0
	v_addc_co_u32_e32 v107, vcc, 0, v105, vcc
	v_bfe_u32 v2, v38, 16, 1
	global_store_dwordx4 v[106:107], v[100:103], off nt
	v_add3_u32 v2, v38, v2, s80
	v_lshrrev_b32_e32 v2, 16, v2
	v_bfe_u32 v100, v34, 16, 1
	v_add3_u32 v100, v34, v100, s80
	v_and_or_b32 v100, v100, s85, v2
	v_bfe_u32 v2, v66, 16, 1
	v_add3_u32 v2, v66, v2, s80
	v_bfe_u32 v101, v62, 16, 1
	v_lshrrev_b32_e32 v2, 16, v2
	v_add3_u32 v101, v62, v101, s80
	v_and_or_b32 v101, v101, s85, v2
	v_bfe_u32 v2, v82, 16, 1
	v_add3_u32 v2, v82, v2, s80
	v_bfe_u32 v102, v58, 16, 1
	v_lshrrev_b32_e32 v2, 16, v2
	v_add3_u32 v102, v58, v102, s80
	v_and_or_b32 v102, v102, s85, v2
	v_bfe_u32 v2, v94, 16, 1
	v_add3_u32 v2, v94, v2, s80
	v_bfe_u32 v103, v98, 16, 1
	v_lshrrev_b32_e32 v2, 16, v2
	v_add3_u32 v103, v98, v103, s80
	v_add_co_u32_e32 v106, vcc, s87, v104
	v_and_or_b32 v103, v103, s85, v2
	s_nop 0
	v_addc_co_u32_e32 v107, vcc, 0, v105, vcc
	v_bfe_u32 v2, v39, 16, 1
	global_store_dwordx4 v[106:107], v[100:103], off nt
	v_add3_u32 v2, v39, v2, s80
	v_lshrrev_b32_e32 v2, 16, v2
	v_bfe_u32 v100, v35, 16, 1
	v_add3_u32 v100, v35, v100, s80
	v_and_or_b32 v100, v100, s85, v2
	v_bfe_u32 v2, v67, 16, 1
	v_add3_u32 v2, v67, v2, s80
	v_bfe_u32 v101, v63, 16, 1
	v_lshrrev_b32_e32 v2, 16, v2
	v_add3_u32 v101, v63, v101, s80
	v_and_or_b32 v101, v101, s85, v2
	v_bfe_u32 v2, v83, 16, 1
	v_add3_u32 v2, v83, v2, s80
	v_bfe_u32 v102, v59, 16, 1
	v_lshrrev_b32_e32 v2, 16, v2
	v_add3_u32 v102, v59, v102, s80
	v_and_or_b32 v102, v102, s85, v2
	v_bfe_u32 v2, v95, 16, 1
	v_add3_u32 v2, v95, v2, s80
	v_bfe_u32 v103, v99, 16, 1
	v_lshrrev_b32_e32 v2, 16, v2
	v_add3_u32 v103, v99, v103, s80
	v_add_co_u32_e32 v104, vcc, 0x9000, v104
	v_and_or_b32 v103, v103, s85, v2
	s_nop 0
	v_addc_co_u32_e32 v105, vcc, 0, v105, vcc
	global_store_dwordx4 v[104:105], v[100:103], off nt
	s_andn2_b64 vcc, exec, s[22:23]
	s_cbranch_vccz .LBB0_2503

.LBB0_2503:
	s_ashr_i32 s4, s5, 31
	s_lshr_b32 s4, s4, 25
	s_add_i32 s5, s5, s4
	s_ashr_i32 s4, s5, 7
	v_lshl_or_b32 v100, s4, 6, v231
	v_add_u32_e32 v2, s0, v134
	s_lshl_b32 s4, s4, 12
	v_subrev_u32_e32 v2, s4, v2
	v_mov_b64_e32 v[102:103], s[18:19]
	v_ashrrev_i32_e32 v101, 31, v100
	v_mad_i64_i32 v[102:103], s[4:5], v2, s91, v[102:103]
	v_bfe_u32 v2, v20, 16, 1
	v_lshl_add_u64 v[104:105], v[100:101], 1, v[102:103]
	v_add3_u32 v2, v20, v2, s80
	v_bfe_u32 v100, v12, 16, 1
	v_lshrrev_b32_e32 v2, 16, v2
	v_add3_u32 v100, v12, v100, s80
	v_and_or_b32 v100, v100, s85, v2
	v_bfe_u32 v2, v48, 16, 1
	v_add3_u32 v2, v48, v2, s80
	v_bfe_u32 v101, v44, 16, 1
	v_lshrrev_b32_e32 v2, 16, v2
	v_add3_u32 v101, v44, v101, s80
	v_and_or_b32 v101, v101, s85, v2
	v_bfe_u32 v2, v68, 16, 1
	v_add3_u32 v2, v68, v2, s80
	v_bfe_u32 v102, v40, 16, 1
	v_lshrrev_b32_e32 v2, 16, v2
	v_add3_u32 v102, v40, v102, s80
	v_and_or_b32 v102, v102, s85, v2
	v_bfe_u32 v2, v84, 16, 1
	v_add3_u32 v2, v84, v2, s80
	v_bfe_u32 v103, v88, 16, 1
	v_lshrrev_b32_e32 v2, 16, v2
	v_add3_u32 v103, v88, v103, s80
	v_and_or_b32 v103, v103, s85, v2
	v_bfe_u32 v2, v21, 16, 1
	global_store_dwordx4 v[104:105], v[100:103], off nt
	v_add3_u32 v2, v21, v2, s80
	v_lshrrev_b32_e32 v2, 16, v2
	v_bfe_u32 v100, v13, 16, 1
	v_add3_u32 v100, v13, v100, s80
	v_and_or_b32 v100, v100, s85, v2
	v_bfe_u32 v2, v49, 16, 1
	v_add3_u32 v2, v49, v2, s80
	v_bfe_u32 v101, v45, 16, 1
	v_lshrrev_b32_e32 v2, 16, v2
	v_add3_u32 v101, v45, v101, s80
	v_and_or_b32 v101, v101, s85, v2
	v_bfe_u32 v2, v69, 16, 1
	v_add3_u32 v2, v69, v2, s80
	v_bfe_u32 v102, v41, 16, 1
	v_lshrrev_b32_e32 v2, 16, v2
	v_add3_u32 v102, v41, v102, s80
	v_and_or_b32 v102, v102, s85, v2
	v_bfe_u32 v2, v85, 16, 1
	v_add3_u32 v2, v85, v2, s80
	v_bfe_u32 v103, v89, 16, 1
	v_lshrrev_b32_e32 v2, 16, v2
	v_add3_u32 v103, v89, v103, s80
	v_add_co_u32_e32 v106, vcc, s91, v104
	v_and_or_b32 v103, v103, s85, v2
	s_nop 0
	v_addc_co_u32_e32 v107, vcc, 0, v105, vcc
	v_bfe_u32 v2, v22, 16, 1
	global_store_dwordx4 v[106:107], v[100:103], off nt
	v_add3_u32 v2, v22, v2, s80
	v_lshrrev_b32_e32 v2, 16, v2
	v_bfe_u32 v100, v14, 16, 1
	v_add3_u32 v100, v14, v100, s80
	v_and_or_b32 v100, v100, s85, v2
	v_bfe_u32 v2, v50, 16, 1
	v_add3_u32 v2, v50, v2, s80
	v_bfe_u32 v101, v46, 16, 1
	v_lshrrev_b32_e32 v2, 16, v2
	v_add3_u32 v101, v46, v101, s80
	v_and_or_b32 v101, v101, s85, v2
	v_bfe_u32 v2, v70, 16, 1
	v_add3_u32 v2, v70, v2, s80
	v_bfe_u32 v102, v42, 16, 1
	v_lshrrev_b32_e32 v2, 16, v2
	v_add3_u32 v102, v42, v102, s80
	v_and_or_b32 v102, v102, s85, v2
	v_bfe_u32 v2, v86, 16, 1
	v_add3_u32 v2, v86, v2, s80
	v_bfe_u32 v103, v90, 16, 1
	v_lshrrev_b32_e32 v2, 16, v2
	v_add3_u32 v103, v90, v103, s80
	v_add_co_u32_e32 v106, vcc, s87, v104
	v_and_or_b32 v103, v103, s85, v2
	s_nop 0
	v_addc_co_u32_e32 v107, vcc, 0, v105, vcc
	v_bfe_u32 v2, v23, 16, 1
	global_store_dwordx4 v[106:107], v[100:103], off nt
	v_add3_u32 v2, v23, v2, s80
	v_lshrrev_b32_e32 v2, 16, v2
	v_bfe_u32 v100, v15, 16, 1
	v_add3_u32 v100, v15, v100, s80
	v_and_or_b32 v100, v100, s85, v2
	v_bfe_u32 v2, v51, 16, 1
	v_add3_u32 v2, v51, v2, s80
	v_bfe_u32 v101, v47, 16, 1
	v_lshrrev_b32_e32 v2, 16, v2
	v_add3_u32 v101, v47, v101, s80
	v_and_or_b32 v101, v101, s85, v2
	v_bfe_u32 v2, v71, 16, 1
	v_add3_u32 v2, v71, v2, s80
	v_bfe_u32 v102, v43, 16, 1
	v_lshrrev_b32_e32 v2, 16, v2
	v_add3_u32 v102, v43, v102, s80
	v_and_or_b32 v102, v102, s85, v2
	v_bfe_u32 v2, v87, 16, 1
	v_add3_u32 v2, v87, v2, s80
	v_bfe_u32 v103, v91, 16, 1
	v_lshrrev_b32_e32 v2, 16, v2
	v_add3_u32 v103, v91, v103, s80
	v_add_co_u32_e32 v104, vcc, 0x9000, v104
	v_and_or_b32 v103, v103, s85, v2
	s_nop 0
	v_addc_co_u32_e32 v105, vcc, 0, v105, vcc
	global_store_dwordx4 v[104:105], v[100:103], off nt
	s_andn2_b64 vcc, exec, s[24:25]
	s_cbranch_vccnz .LBB0_2455
.LBB0_2504:
	s_ashr_i32 s4, s14, 31
	s_lshr_b32 s4, s4, 25
	s_add_i32 s14, s14, s4
	s_ashr_i32 s4, s14, 7
	v_lshl_or_b32 v100, s4, 6, v231
	v_add_u32_e32 v2, s0, v135
	s_lshl_b32 s4, s4, 12
	v_subrev_u32_e32 v2, s4, v2
	v_mov_b64_e32 v[102:103], s[18:19]
	v_ashrrev_i32_e32 v101, 31, v100
	v_mad_i64_i32 v[102:103], s[4:5], v2, s91, v[102:103]
	v_bfe_u32 v2, v8, 16, 1
	v_lshl_add_u64 v[104:105], v[100:101], 1, v[102:103]
	v_add3_u32 v2, v8, v2, s80
	v_bfe_u32 v100, v4, 16, 1
	v_lshrrev_b32_e32 v2, 16, v2
	v_add3_u32 v100, v4, v100, s80
	v_and_or_b32 v100, v100, s85, v2
	v_bfe_u32 v2, v28, 16, 1
	v_add3_u32 v2, v28, v2, s80
	v_bfe_u32 v101, v24, 16, 1
	v_lshrrev_b32_e32 v2, 16, v2
	v_add3_u32 v101, v24, v101, s80
	v_and_or_b32 v101, v101, s85, v2
	v_bfe_u32 v2, v52, 16, 1
	v_add3_u32 v2, v52, v2, s80
	v_bfe_u32 v102, v16, 16, 1
	v_lshrrev_b32_e32 v2, 16, v2
	v_add3_u32 v102, v16, v102, s80
	v_and_or_b32 v102, v102, s85, v2
	v_bfe_u32 v2, v72, 16, 1
	v_add3_u32 v2, v72, v2, s80
	v_bfe_u32 v103, v76, 16, 1
	v_lshrrev_b32_e32 v2, 16, v2
	v_add3_u32 v103, v76, v103, s80
	v_and_or_b32 v103, v103, s85, v2
	v_bfe_u32 v2, v9, 16, 1
	global_store_dwordx4 v[104:105], v[100:103], off nt
	v_add3_u32 v2, v9, v2, s80
	v_lshrrev_b32_e32 v2, 16, v2
	v_bfe_u32 v100, v5, 16, 1
	v_add3_u32 v100, v5, v100, s80
	v_and_or_b32 v100, v100, s85, v2
	v_bfe_u32 v2, v29, 16, 1
	v_add3_u32 v2, v29, v2, s80
	v_bfe_u32 v101, v25, 16, 1
	v_lshrrev_b32_e32 v2, 16, v2
	v_add3_u32 v101, v25, v101, s80
	v_and_or_b32 v101, v101, s85, v2
	v_bfe_u32 v2, v53, 16, 1
	v_add3_u32 v2, v53, v2, s80
	v_bfe_u32 v102, v17, 16, 1
	v_lshrrev_b32_e32 v2, 16, v2
	v_add3_u32 v102, v17, v102, s80
	v_and_or_b32 v102, v102, s85, v2
	v_bfe_u32 v2, v73, 16, 1
	v_add3_u32 v2, v73, v2, s80
	v_bfe_u32 v103, v77, 16, 1
	v_lshrrev_b32_e32 v2, 16, v2
	v_add3_u32 v103, v77, v103, s80
	v_add_co_u32_e32 v106, vcc, s91, v104
	v_and_or_b32 v103, v103, s85, v2
	s_nop 0
	v_addc_co_u32_e32 v107, vcc, 0, v105, vcc
	v_bfe_u32 v2, v10, 16, 1
	global_store_dwordx4 v[106:107], v[100:103], off nt
	v_add3_u32 v2, v10, v2, s80
	v_lshrrev_b32_e32 v2, 16, v2
	v_bfe_u32 v100, v6, 16, 1
	v_add3_u32 v100, v6, v100, s80
	v_and_or_b32 v100, v100, s85, v2
	v_bfe_u32 v2, v30, 16, 1
	v_add3_u32 v2, v30, v2, s80
	v_bfe_u32 v101, v26, 16, 1
	v_lshrrev_b32_e32 v2, 16, v2
	v_add3_u32 v101, v26, v101, s80
	v_and_or_b32 v101, v101, s85, v2
	v_bfe_u32 v2, v54, 16, 1
	v_add3_u32 v2, v54, v2, s80
	v_bfe_u32 v102, v18, 16, 1
	v_lshrrev_b32_e32 v2, 16, v2
	v_add3_u32 v102, v18, v102, s80
	v_and_or_b32 v102, v102, s85, v2
	v_bfe_u32 v2, v74, 16, 1
	v_add3_u32 v2, v74, v2, s80
	v_bfe_u32 v103, v78, 16, 1
	v_lshrrev_b32_e32 v2, 16, v2
	v_add3_u32 v103, v78, v103, s80
	v_add_co_u32_e32 v106, vcc, s87, v104
	v_and_or_b32 v103, v103, s85, v2
	s_nop 0
	v_addc_co_u32_e32 v107, vcc, 0, v105, vcc
	v_bfe_u32 v2, v11, 16, 1
	global_store_dwordx4 v[106:107], v[100:103], off nt
	v_add3_u32 v2, v11, v2, s80
	v_lshrrev_b32_e32 v2, 16, v2
	v_bfe_u32 v100, v7, 16, 1
	v_add3_u32 v100, v7, v100, s80
	v_and_or_b32 v100, v100, s85, v2
	v_bfe_u32 v2, v31, 16, 1
	v_add3_u32 v2, v31, v2, s80
	v_bfe_u32 v101, v27, 16, 1
	v_lshrrev_b32_e32 v2, 16, v2
	v_add3_u32 v101, v27, v101, s80
	v_and_or_b32 v101, v101, s85, v2
	v_bfe_u32 v2, v55, 16, 1
	v_add3_u32 v2, v55, v2, s80
	v_bfe_u32 v102, v19, 16, 1
	v_lshrrev_b32_e32 v2, 16, v2
	v_add3_u32 v102, v19, v102, s80
	v_and_or_b32 v102, v102, s85, v2
	v_bfe_u32 v2, v75, 16, 1
	v_add3_u32 v2, v75, v2, s80
	v_bfe_u32 v103, v79, 16, 1
	v_lshrrev_b32_e32 v2, 16, v2
	v_add3_u32 v103, v79, v103, s80
	v_add_co_u32_e32 v104, vcc, 0x9000, v104
	v_and_or_b32 v103, v103, s85, v2
	s_nop 0
	v_addc_co_u32_e32 v105, vcc, 0, v105, vcc
	global_store_dwordx4 v[104:105], v[100:103], off nt
	s_branch .LBB0_2455

.LBB0_2551:
	s_waitcnt vmcnt(1)
	v_bfe_u32 v2, v104, 16, 1
	v_mov_b64_e32 v[138:139], s[18:19]
	v_add3_u32 v2, v104, v2, s80
	s_waitcnt vmcnt(0)
	v_bfe_u32 v104, v100, 16, 1
	v_mad_i64_i32 v[138:139], s[8:9], v137, s91, v[138:139]
	v_lshrrev_b32_e32 v2, 16, v2
	v_add3_u32 v100, v100, v104, s80
	v_lshl_add_u64 v[132:133], v[132:133], 1, v[138:139]
	v_and_or_b32 v138, v100, s85, v2
	v_bfe_u32 v2, v116, 16, 1
	v_add3_u32 v2, v116, v2, s80
	v_bfe_u32 v100, v112, 16, 1
	v_lshrrev_b32_e32 v2, 16, v2
	v_add3_u32 v100, v112, v100, s80
	v_and_or_b32 v139, v100, s85, v2
	v_bfe_u32 v2, v120, 16, 1
	v_add3_u32 v2, v120, v2, s80
	v_bfe_u32 v100, v108, 16, 1
	v_lshrrev_b32_e32 v2, 16, v2
	v_add3_u32 v100, v108, v100, s80
	v_and_or_b32 v140, v100, s85, v2
	v_bfe_u32 v2, v128, 16, 1
	v_add3_u32 v2, v128, v2, s80
	v_bfe_u32 v100, v124, 16, 1
	v_lshrrev_b32_e32 v2, 16, v2
	v_add3_u32 v100, v124, v100, s80
	v_and_or_b32 v141, v100, s85, v2
	v_bfe_u32 v2, v105, 16, 1
	v_add3_u32 v2, v105, v2, s80
	v_bfe_u32 v100, v101, 16, 1
	v_lshrrev_b32_e32 v2, 16, v2
	v_add3_u32 v100, v101, v100, s80
	global_store_dwordx4 v[132:133], v[138:141], off nt
	s_nop 1
	v_and_or_b32 v138, v100, s85, v2
	v_bfe_u32 v2, v117, 16, 1
	v_add3_u32 v2, v117, v2, s80
	v_bfe_u32 v100, v113, 16, 1
	v_lshrrev_b32_e32 v2, 16, v2
	v_add3_u32 v100, v113, v100, s80
	v_and_or_b32 v139, v100, s85, v2
	v_bfe_u32 v2, v121, 16, 1
	v_add3_u32 v2, v121, v2, s80
	v_bfe_u32 v100, v109, 16, 1
	v_lshrrev_b32_e32 v2, 16, v2
	v_add3_u32 v100, v109, v100, s80
	v_and_or_b32 v140, v100, s85, v2
	v_bfe_u32 v2, v129, 16, 1
	v_add3_u32 v2, v129, v2, s80
	v_bfe_u32 v100, v125, 16, 1
	v_lshrrev_b32_e32 v2, 16, v2
	v_add3_u32 v100, v125, v100, s80
	v_and_or_b32 v141, v100, s85, v2
	v_add_co_u32_e32 v100, vcc, s91, v132
	v_bfe_u32 v2, v106, 16, 1
	s_nop 0
	v_addc_co_u32_e32 v101, vcc, 0, v133, vcc
	global_store_dwordx4 v[100:101], v[138:141], off nt
	v_add3_u32 v2, v106, v2, s80
	v_bfe_u32 v100, v102, 16, 1
	v_lshrrev_b32_e32 v2, 16, v2
	v_add3_u32 v100, v102, v100, s80
	v_and_or_b32 v138, v100, s85, v2
	v_bfe_u32 v2, v118, 16, 1
	v_add3_u32 v2, v118, v2, s80
	v_bfe_u32 v100, v114, 16, 1
	v_lshrrev_b32_e32 v2, 16, v2
	v_add3_u32 v100, v114, v100, s80
	v_and_or_b32 v139, v100, s85, v2
	v_bfe_u32 v2, v122, 16, 1
	v_add3_u32 v2, v122, v2, s80
	v_bfe_u32 v100, v110, 16, 1
	v_lshrrev_b32_e32 v2, 16, v2
	v_add3_u32 v100, v110, v100, s80
	v_and_or_b32 v140, v100, s85, v2
	v_bfe_u32 v2, v130, 16, 1
	v_add3_u32 v2, v130, v2, s80
	v_bfe_u32 v100, v126, 16, 1
	v_lshrrev_b32_e32 v2, 16, v2
	v_add3_u32 v100, v126, v100, s80
	v_and_or_b32 v141, v100, s85, v2
	v_add_co_u32_e32 v100, vcc, s87, v132
	v_bfe_u32 v2, v107, 16, 1
	s_nop 0
	v_addc_co_u32_e32 v101, vcc, 0, v133, vcc
	global_store_dwordx4 v[100:101], v[138:141], off nt
	v_add3_u32 v2, v107, v2, s80
	v_bfe_u32 v100, v103, 16, 1
	v_lshrrev_b32_e32 v2, 16, v2
	v_add3_u32 v100, v103, v100, s80
	v_and_or_b32 v100, v100, s85, v2
	v_bfe_u32 v2, v119, 16, 1
	v_add3_u32 v2, v119, v2, s80
	v_bfe_u32 v101, v115, 16, 1
	v_lshrrev_b32_e32 v2, 16, v2
	v_add3_u32 v101, v115, v101, s80
	v_and_or_b32 v101, v101, s85, v2
	v_bfe_u32 v2, v123, 16, 1
	v_add3_u32 v2, v123, v2, s80
	v_bfe_u32 v102, v111, 16, 1
	v_lshrrev_b32_e32 v2, 16, v2
	v_add3_u32 v102, v111, v102, s80
	v_and_or_b32 v102, v102, s85, v2
	v_bfe_u32 v2, v131, 16, 1
	v_add3_u32 v2, v131, v2, s80
	v_bfe_u32 v103, v127, 16, 1
	v_add_co_u32_e32 v104, vcc, 0x9000, v132
	v_lshrrev_b32_e32 v2, 16, v2
	v_add3_u32 v103, v127, v103, s80
	v_addc_co_u32_e32 v105, vcc, 0, v133, vcc
	v_and_or_b32 v103, v103, s85, v2
	s_andn2_b64 vcc, exec, s[20:21]
	global_store_dwordx4 v[104:105], v[100:103], off nt
	s_cbranch_vccnz .LBB0_2554
	s_ashr_i32 s8, s4, 31
	s_lshr_b32 s8, s8, 25
	s_add_i32 s4, s4, s8
	s_ashr_i32 s4, s4, 7
	v_lshl_or_b32 v100, s4, 6, v231
	v_add_u32_e32 v2, s0, v136
	s_lshl_b32 s4, s4, 12
	v_subrev_u32_e32 v2, s4, v2
	v_mov_b64_e32 v[102:103], s[18:19]
	v_ashrrev_i32_e32 v101, 31, v100
	v_mad_i64_i32 v[102:103], s[8:9], v2, s91, v[102:103]
	v_bfe_u32 v2, v36, 16, 1
	v_lshl_add_u64 v[104:105], v[100:101], 1, v[102:103]
	v_add3_u32 v2, v36, v2, s80
	v_bfe_u32 v100, v32, 16, 1
	v_lshrrev_b32_e32 v2, 16, v2
	v_add3_u32 v100, v32, v100, s80
	v_and_or_b32 v100, v100, s85, v2
	v_bfe_u32 v2, v64, 16, 1
	v_add3_u32 v2, v64, v2, s80
	v_bfe_u32 v101, v60, 16, 1
	v_lshrrev_b32_e32 v2, 16, v2
	v_add3_u32 v101, v60, v101, s80
	v_and_or_b32 v101, v101, s85, v2
	v_bfe_u32 v2, v80, 16, 1
	v_add3_u32 v2, v80, v2, s80
	v_bfe_u32 v102, v56, 16, 1
	v_lshrrev_b32_e32 v2, 16, v2
	v_add3_u32 v102, v56, v102, s80
	v_and_or_b32 v102, v102, s85, v2
	v_bfe_u32 v2, v92, 16, 1
	v_add3_u32 v2, v92, v2, s80
	v_bfe_u32 v103, v96, 16, 1
	v_lshrrev_b32_e32 v2, 16, v2
	v_add3_u32 v103, v96, v103, s80
	v_and_or_b32 v103, v103, s85, v2
	v_bfe_u32 v2, v37, 16, 1
	global_store_dwordx4 v[104:105], v[100:103], off nt
	v_add3_u32 v2, v37, v2, s80
	v_lshrrev_b32_e32 v2, 16, v2
	v_bfe_u32 v100, v33, 16, 1
	v_add3_u32 v100, v33, v100, s80
	v_and_or_b32 v100, v100, s85, v2
	v_bfe_u32 v2, v65, 16, 1
	v_add3_u32 v2, v65, v2, s80
	v_bfe_u32 v101, v61, 16, 1
	v_lshrrev_b32_e32 v2, 16, v2
	v_add3_u32 v101, v61, v101, s80
	v_and_or_b32 v101, v101, s85, v2
	v_bfe_u32 v2, v81, 16, 1
	v_add3_u32 v2, v81, v2, s80
	v_bfe_u32 v102, v57, 16, 1
	v_lshrrev_b32_e32 v2, 16, v2
	v_add3_u32 v102, v57, v102, s80
	v_and_or_b32 v102, v102, s85, v2
	v_bfe_u32 v2, v93, 16, 1
	v_add3_u32 v2, v93, v2, s80
	v_bfe_u32 v103, v97, 16, 1
	v_lshrrev_b32_e32 v2, 16, v2
	v_add3_u32 v103, v97, v103, s80
	v_add_co_u32_e32 v106, vcc, s91, v104
	v_and_or_b32 v103, v103, s85, v2
	s_nop 0
	v_addc_co_u32_e32 v107, vcc, 0, v105, vcc
	v_bfe_u32 v2, v38, 16, 1
	global_store_dwordx4 v[106:107], v[100:103], off nt
	v_add3_u32 v2, v38, v2, s80
	v_lshrrev_b32_e32 v2, 16, v2
	v_bfe_u32 v100, v34, 16, 1
	v_add3_u32 v100, v34, v100, s80
	v_and_or_b32 v100, v100, s85, v2
	v_bfe_u32 v2, v66, 16, 1
	v_add3_u32 v2, v66, v2, s80
	v_bfe_u32 v101, v62, 16, 1
	v_lshrrev_b32_e32 v2, 16, v2
	v_add3_u32 v101, v62, v101, s80
	v_and_or_b32 v101, v101, s85, v2
	v_bfe_u32 v2, v82, 16, 1
	v_add3_u32 v2, v82, v2, s80
	v_bfe_u32 v102, v58, 16, 1
	v_lshrrev_b32_e32 v2, 16, v2
	v_add3_u32 v102, v58, v102, s80
	v_and_or_b32 v102, v102, s85, v2
	v_bfe_u32 v2, v94, 16, 1
	v_add3_u32 v2, v94, v2, s80
	v_bfe_u32 v103, v98, 16, 1
	v_lshrrev_b32_e32 v2, 16, v2
	v_add3_u32 v103, v98, v103, s80
	v_add_co_u32_e32 v106, vcc, s87, v104
	v_and_or_b32 v103, v103, s85, v2
	s_nop 0
	v_addc_co_u32_e32 v107, vcc, 0, v105, vcc
	v_bfe_u32 v2, v39, 16, 1
	global_store_dwordx4 v[106:107], v[100:103], off nt
	v_add3_u32 v2, v39, v2, s80
	v_lshrrev_b32_e32 v2, 16, v2
	v_bfe_u32 v100, v35, 16, 1
	v_add3_u32 v100, v35, v100, s80
	v_and_or_b32 v100, v100, s85, v2
	v_bfe_u32 v2, v67, 16, 1
	v_add3_u32 v2, v67, v2, s80
	v_bfe_u32 v101, v63, 16, 1
	v_lshrrev_b32_e32 v2, 16, v2
	v_add3_u32 v101, v63, v101, s80
	v_and_or_b32 v101, v101, s85, v2
	v_bfe_u32 v2, v83, 16, 1
	v_add3_u32 v2, v83, v2, s80
	v_bfe_u32 v102, v59, 16, 1
	v_lshrrev_b32_e32 v2, 16, v2
	v_add3_u32 v102, v59, v102, s80
	v_and_or_b32 v102, v102, s85, v2
	v_bfe_u32 v2, v95, 16, 1
	v_add3_u32 v2, v95, v2, s80
	v_bfe_u32 v103, v99, 16, 1
	v_lshrrev_b32_e32 v2, 16, v2
	v_add3_u32 v103, v99, v103, s80
	v_add_co_u32_e32 v104, vcc, 0x9000, v104
	v_and_or_b32 v103, v103, s85, v2
	s_nop 0
	v_addc_co_u32_e32 v105, vcc, 0, v105, vcc
	global_store_dwordx4 v[104:105], v[100:103], off nt
	s_andn2_b64 vcc, exec, s[22:23]
	s_cbranch_vccz .LBB0_2555

.LBB0_2603:
	s_waitcnt vmcnt(1)
	v_bfe_u32 v2, v104, 16, 1
	v_mov_b64_e32 v[138:139], s[16:17]
	v_add3_u32 v2, v104, v2, s80
	s_waitcnt vmcnt(0)
	v_bfe_u32 v104, v100, 16, 1
	v_mad_i64_i32 v[138:139], s[6:7], v137, s91, v[138:139]
	v_lshrrev_b32_e32 v2, 16, v2
	v_add3_u32 v100, v100, v104, s80
	v_lshl_add_u64 v[132:133], v[132:133], 1, v[138:139]
	v_and_or_b32 v138, v100, s85, v2
	v_bfe_u32 v2, v116, 16, 1
	v_add3_u32 v2, v116, v2, s80
	v_bfe_u32 v100, v112, 16, 1
	v_lshrrev_b32_e32 v2, 16, v2
	v_add3_u32 v100, v112, v100, s80
	v_and_or_b32 v139, v100, s85, v2
	v_bfe_u32 v2, v120, 16, 1
	v_add3_u32 v2, v120, v2, s80
	v_bfe_u32 v100, v108, 16, 1
	v_lshrrev_b32_e32 v2, 16, v2
	v_add3_u32 v100, v108, v100, s80
	v_and_or_b32 v140, v100, s85, v2
	v_bfe_u32 v2, v128, 16, 1
	v_add3_u32 v2, v128, v2, s80
	v_bfe_u32 v100, v124, 16, 1
	v_lshrrev_b32_e32 v2, 16, v2
	v_add3_u32 v100, v124, v100, s80
	v_and_or_b32 v141, v100, s85, v2
	v_bfe_u32 v2, v105, 16, 1
	v_add3_u32 v2, v105, v2, s80
	v_bfe_u32 v100, v101, 16, 1
	v_lshrrev_b32_e32 v2, 16, v2
	v_add3_u32 v100, v101, v100, s80
	global_store_dwordx4 v[132:133], v[138:141], off nt
	s_nop 1
	v_and_or_b32 v138, v100, s85, v2
	v_bfe_u32 v2, v117, 16, 1
	v_add3_u32 v2, v117, v2, s80
	v_bfe_u32 v100, v113, 16, 1
	v_lshrrev_b32_e32 v2, 16, v2
	v_add3_u32 v100, v113, v100, s80
	v_and_or_b32 v139, v100, s85, v2
	v_bfe_u32 v2, v121, 16, 1
	v_add3_u32 v2, v121, v2, s80
	v_bfe_u32 v100, v109, 16, 1
	v_lshrrev_b32_e32 v2, 16, v2
	v_add3_u32 v100, v109, v100, s80
	v_and_or_b32 v140, v100, s85, v2
	v_bfe_u32 v2, v129, 16, 1
	v_add3_u32 v2, v129, v2, s80
	v_bfe_u32 v100, v125, 16, 1
	v_lshrrev_b32_e32 v2, 16, v2
	v_add3_u32 v100, v125, v100, s80
	v_and_or_b32 v141, v100, s85, v2
	v_add_co_u32_e32 v100, vcc, s91, v132
	v_bfe_u32 v2, v106, 16, 1
	s_nop 0
	v_addc_co_u32_e32 v101, vcc, 0, v133, vcc
	global_store_dwordx4 v[100:101], v[138:141], off nt
	v_add3_u32 v2, v106, v2, s80
	v_bfe_u32 v100, v102, 16, 1
	v_lshrrev_b32_e32 v2, 16, v2
	v_add3_u32 v100, v102, v100, s80
	v_and_or_b32 v138, v100, s85, v2
	v_bfe_u32 v2, v118, 16, 1
	v_add3_u32 v2, v118, v2, s80
	v_bfe_u32 v100, v114, 16, 1
	v_lshrrev_b32_e32 v2, 16, v2
	v_add3_u32 v100, v114, v100, s80
	v_and_or_b32 v139, v100, s85, v2
	v_bfe_u32 v2, v122, 16, 1
	v_add3_u32 v2, v122, v2, s80
	v_bfe_u32 v100, v110, 16, 1
	v_lshrrev_b32_e32 v2, 16, v2
	v_add3_u32 v100, v110, v100, s80
	v_and_or_b32 v140, v100, s85, v2
	v_bfe_u32 v2, v130, 16, 1
	v_add3_u32 v2, v130, v2, s80
	v_bfe_u32 v100, v126, 16, 1
	v_lshrrev_b32_e32 v2, 16, v2
	v_add3_u32 v100, v126, v100, s80
	v_and_or_b32 v141, v100, s85, v2
	v_add_co_u32_e32 v100, vcc, s87, v132
	v_bfe_u32 v2, v107, 16, 1
	s_nop 0
	v_addc_co_u32_e32 v101, vcc, 0, v133, vcc
	global_store_dwordx4 v[100:101], v[138:141], off nt
	v_add3_u32 v2, v107, v2, s80
	v_bfe_u32 v100, v103, 16, 1
	v_lshrrev_b32_e32 v2, 16, v2
	v_add3_u32 v100, v103, v100, s80
	v_and_or_b32 v100, v100, s85, v2
	v_bfe_u32 v2, v119, 16, 1
	v_add3_u32 v2, v119, v2, s80
	v_bfe_u32 v101, v115, 16, 1
	v_lshrrev_b32_e32 v2, 16, v2
	v_add3_u32 v101, v115, v101, s80
	v_and_or_b32 v101, v101, s85, v2
	v_bfe_u32 v2, v123, 16, 1
	v_add3_u32 v2, v123, v2, s80
	v_bfe_u32 v102, v111, 16, 1
	v_lshrrev_b32_e32 v2, 16, v2
	v_add3_u32 v102, v111, v102, s80
	v_and_or_b32 v102, v102, s85, v2
	v_bfe_u32 v2, v131, 16, 1
	v_add3_u32 v2, v131, v2, s80
	v_bfe_u32 v103, v127, 16, 1
	v_add_co_u32_e32 v104, vcc, 0x9000, v132
	v_lshrrev_b32_e32 v2, 16, v2
	v_add3_u32 v103, v127, v103, s80
	v_addc_co_u32_e32 v105, vcc, 0, v133, vcc
	v_and_or_b32 v103, v103, s85, v2
	s_andn2_b64 vcc, exec, s[18:19]
	global_store_dwordx4 v[104:105], v[100:103], off nt
	s_cbranch_vccnz .LBB0_2606
	s_ashr_i32 s6, s4, 31
	s_lshr_b32 s6, s6, 25
	s_add_i32 s4, s4, s6
	s_ashr_i32 s4, s4, 7
	v_lshl_or_b32 v100, s4, 6, v231
	v_add_u32_e32 v2, s0, v136
	s_lshl_b32 s4, s4, 12
	v_subrev_u32_e32 v2, s4, v2
	v_mov_b64_e32 v[102:103], s[16:17]
	v_ashrrev_i32_e32 v101, 31, v100
	v_mad_i64_i32 v[102:103], s[6:7], v2, s91, v[102:103]
	v_bfe_u32 v2, v36, 16, 1
	v_lshl_add_u64 v[104:105], v[100:101], 1, v[102:103]
	v_add3_u32 v2, v36, v2, s80
	v_bfe_u32 v100, v32, 16, 1
	v_lshrrev_b32_e32 v2, 16, v2
	v_add3_u32 v100, v32, v100, s80
	v_and_or_b32 v100, v100, s85, v2
	v_bfe_u32 v2, v64, 16, 1
	v_add3_u32 v2, v64, v2, s80
	v_bfe_u32 v101, v60, 16, 1
	v_lshrrev_b32_e32 v2, 16, v2
	v_add3_u32 v101, v60, v101, s80
	v_and_or_b32 v101, v101, s85, v2
	v_bfe_u32 v2, v80, 16, 1
	v_add3_u32 v2, v80, v2, s80
	v_bfe_u32 v102, v56, 16, 1
	v_lshrrev_b32_e32 v2, 16, v2
	v_add3_u32 v102, v56, v102, s80
	v_and_or_b32 v102, v102, s85, v2
	v_bfe_u32 v2, v92, 16, 1
	v_add3_u32 v2, v92, v2, s80
	v_bfe_u32 v103, v96, 16, 1
	v_lshrrev_b32_e32 v2, 16, v2
	v_add3_u32 v103, v96, v103, s80
	v_and_or_b32 v103, v103, s85, v2
	v_bfe_u32 v2, v37, 16, 1
	global_store_dwordx4 v[104:105], v[100:103], off nt
	v_add3_u32 v2, v37, v2, s80
	v_lshrrev_b32_e32 v2, 16, v2
	v_bfe_u32 v100, v33, 16, 1
	v_add3_u32 v100, v33, v100, s80
	v_and_or_b32 v100, v100, s85, v2
	v_bfe_u32 v2, v65, 16, 1
	v_add3_u32 v2, v65, v2, s80
	v_bfe_u32 v101, v61, 16, 1
	v_lshrrev_b32_e32 v2, 16, v2
	v_add3_u32 v101, v61, v101, s80
	v_and_or_b32 v101, v101, s85, v2
	v_bfe_u32 v2, v81, 16, 1
	v_add3_u32 v2, v81, v2, s80
	v_bfe_u32 v102, v57, 16, 1
	v_lshrrev_b32_e32 v2, 16, v2
	v_add3_u32 v102, v57, v102, s80
	v_and_or_b32 v102, v102, s85, v2
	v_bfe_u32 v2, v93, 16, 1
	v_add3_u32 v2, v93, v2, s80
	v_bfe_u32 v103, v97, 16, 1
	v_lshrrev_b32_e32 v2, 16, v2
	v_add3_u32 v103, v97, v103, s80
	v_add_co_u32_e32 v106, vcc, s91, v104
	v_and_or_b32 v103, v103, s85, v2
	s_nop 0
	v_addc_co_u32_e32 v107, vcc, 0, v105, vcc
	v_bfe_u32 v2, v38, 16, 1
	global_store_dwordx4 v[106:107], v[100:103], off nt
	v_add3_u32 v2, v38, v2, s80
	v_lshrrev_b32_e32 v2, 16, v2
	v_bfe_u32 v100, v34, 16, 1
	v_add3_u32 v100, v34, v100, s80
	v_and_or_b32 v100, v100, s85, v2
	v_bfe_u32 v2, v66, 16, 1
	v_add3_u32 v2, v66, v2, s80
	v_bfe_u32 v101, v62, 16, 1
	v_lshrrev_b32_e32 v2, 16, v2
	v_add3_u32 v101, v62, v101, s80
	v_and_or_b32 v101, v101, s85, v2
	v_bfe_u32 v2, v82, 16, 1
	v_add3_u32 v2, v82, v2, s80
	v_bfe_u32 v102, v58, 16, 1
	v_lshrrev_b32_e32 v2, 16, v2
	v_add3_u32 v102, v58, v102, s80
	v_and_or_b32 v102, v102, s85, v2
	v_bfe_u32 v2, v94, 16, 1
	v_add3_u32 v2, v94, v2, s80
	v_bfe_u32 v103, v98, 16, 1
	v_lshrrev_b32_e32 v2, 16, v2
	v_add3_u32 v103, v98, v103, s80
	v_add_co_u32_e32 v106, vcc, s87, v104
	v_and_or_b32 v103, v103, s85, v2
	s_nop 0
	v_addc_co_u32_e32 v107, vcc, 0, v105, vcc
	v_bfe_u32 v2, v39, 16, 1
	global_store_dwordx4 v[106:107], v[100:103], off nt
	v_add3_u32 v2, v39, v2, s80
	v_lshrrev_b32_e32 v2, 16, v2
	v_bfe_u32 v100, v35, 16, 1
	v_add3_u32 v100, v35, v100, s80
	v_and_or_b32 v100, v100, s85, v2
	v_bfe_u32 v2, v67, 16, 1
	v_add3_u32 v2, v67, v2, s80
	v_bfe_u32 v101, v63, 16, 1
	v_lshrrev_b32_e32 v2, 16, v2
	v_add3_u32 v101, v63, v101, s80
	v_and_or_b32 v101, v101, s85, v2
	v_bfe_u32 v2, v83, 16, 1
	v_add3_u32 v2, v83, v2, s80
	v_bfe_u32 v102, v59, 16, 1
	v_lshrrev_b32_e32 v2, 16, v2
	v_add3_u32 v102, v59, v102, s80
	v_and_or_b32 v102, v102, s85, v2
	v_bfe_u32 v2, v95, 16, 1
	v_add3_u32 v2, v95, v2, s80
	v_bfe_u32 v103, v99, 16, 1
	v_lshrrev_b32_e32 v2, 16, v2
	v_add3_u32 v103, v99, v103, s80
	v_add_co_u32_e32 v104, vcc, 0x9000, v104
	v_and_or_b32 v103, v103, s85, v2
	s_nop 0
	v_addc_co_u32_e32 v105, vcc, 0, v105, vcc
	global_store_dwordx4 v[104:105], v[100:103], off nt
	s_andn2_b64 vcc, exec, s[20:21]
	s_cbranch_vccz .LBB0_2607

.LBB0_2607:
	s_ashr_i32 s4, s5, 31
	s_lshr_b32 s4, s4, 25
	s_add_i32 s5, s5, s4
	s_ashr_i32 s4, s5, 7
	v_lshl_or_b32 v100, s4, 6, v231
	v_add_u32_e32 v2, s0, v134
	s_lshl_b32 s4, s4, 12
	v_subrev_u32_e32 v2, s4, v2
	v_mov_b64_e32 v[102:103], s[16:17]
	v_ashrrev_i32_e32 v101, 31, v100
	v_mad_i64_i32 v[102:103], s[4:5], v2, s91, v[102:103]
	v_bfe_u32 v2, v20, 16, 1
	v_lshl_add_u64 v[104:105], v[100:101], 1, v[102:103]
	v_add3_u32 v2, v20, v2, s80
	v_bfe_u32 v100, v12, 16, 1
	v_lshrrev_b32_e32 v2, 16, v2
	v_add3_u32 v100, v12, v100, s80
	v_and_or_b32 v100, v100, s85, v2
	v_bfe_u32 v2, v48, 16, 1
	v_add3_u32 v2, v48, v2, s80
	v_bfe_u32 v101, v44, 16, 1
	v_lshrrev_b32_e32 v2, 16, v2
	v_add3_u32 v101, v44, v101, s80
	v_and_or_b32 v101, v101, s85, v2
	v_bfe_u32 v2, v68, 16, 1
	v_add3_u32 v2, v68, v2, s80
	v_bfe_u32 v102, v40, 16, 1
	v_lshrrev_b32_e32 v2, 16, v2
	v_add3_u32 v102, v40, v102, s80
	v_and_or_b32 v102, v102, s85, v2
	v_bfe_u32 v2, v84, 16, 1
	v_add3_u32 v2, v84, v2, s80
	v_bfe_u32 v103, v88, 16, 1
	v_lshrrev_b32_e32 v2, 16, v2
	v_add3_u32 v103, v88, v103, s80
	v_and_or_b32 v103, v103, s85, v2
	v_bfe_u32 v2, v21, 16, 1
	global_store_dwordx4 v[104:105], v[100:103], off nt
	v_add3_u32 v2, v21, v2, s80
	v_lshrrev_b32_e32 v2, 16, v2
	v_bfe_u32 v100, v13, 16, 1
	v_add3_u32 v100, v13, v100, s80
	v_and_or_b32 v100, v100, s85, v2
	v_bfe_u32 v2, v49, 16, 1
	v_add3_u32 v2, v49, v2, s80
	v_bfe_u32 v101, v45, 16, 1
	v_lshrrev_b32_e32 v2, 16, v2
	v_add3_u32 v101, v45, v101, s80
	v_and_or_b32 v101, v101, s85, v2
	v_bfe_u32 v2, v69, 16, 1
	v_add3_u32 v2, v69, v2, s80
	v_bfe_u32 v102, v41, 16, 1
	v_lshrrev_b32_e32 v2, 16, v2
	v_add3_u32 v102, v41, v102, s80
	v_and_or_b32 v102, v102, s85, v2
	v_bfe_u32 v2, v85, 16, 1
	v_add3_u32 v2, v85, v2, s80
	v_bfe_u32 v103, v89, 16, 1
	v_lshrrev_b32_e32 v2, 16, v2
	v_add3_u32 v103, v89, v103, s80
	v_add_co_u32_e32 v106, vcc, s91, v104
	v_and_or_b32 v103, v103, s85, v2
	s_nop 0
	v_addc_co_u32_e32 v107, vcc, 0, v105, vcc
	v_bfe_u32 v2, v22, 16, 1
	global_store_dwordx4 v[106:107], v[100:103], off nt
	v_add3_u32 v2, v22, v2, s80
	v_lshrrev_b32_e32 v2, 16, v2
	v_bfe_u32 v100, v14, 16, 1
	v_add3_u32 v100, v14, v100, s80
	v_and_or_b32 v100, v100, s85, v2
	v_bfe_u32 v2, v50, 16, 1
	v_add3_u32 v2, v50, v2, s80
	v_bfe_u32 v101, v46, 16, 1
	v_lshrrev_b32_e32 v2, 16, v2
	v_add3_u32 v101, v46, v101, s80
	v_and_or_b32 v101, v101, s85, v2
	v_bfe_u32 v2, v70, 16, 1
	v_add3_u32 v2, v70, v2, s80
	v_bfe_u32 v102, v42, 16, 1
	v_lshrrev_b32_e32 v2, 16, v2
	v_add3_u32 v102, v42, v102, s80
	v_and_or_b32 v102, v102, s85, v2
	v_bfe_u32 v2, v86, 16, 1
	v_add3_u32 v2, v86, v2, s80
	v_bfe_u32 v103, v90, 16, 1
	v_lshrrev_b32_e32 v2, 16, v2
	v_add3_u32 v103, v90, v103, s80
	v_add_co_u32_e32 v106, vcc, s87, v104
	v_and_or_b32 v103, v103, s85, v2
	s_nop 0
	v_addc_co_u32_e32 v107, vcc, 0, v105, vcc
	v_bfe_u32 v2, v23, 16, 1
	global_store_dwordx4 v[106:107], v[100:103], off nt
	v_add3_u32 v2, v23, v2, s80
	v_lshrrev_b32_e32 v2, 16, v2
	v_bfe_u32 v100, v15, 16, 1
	v_add3_u32 v100, v15, v100, s80
	v_and_or_b32 v100, v100, s85, v2
	v_bfe_u32 v2, v51, 16, 1
	v_add3_u32 v2, v51, v2, s80
	v_bfe_u32 v101, v47, 16, 1
	v_lshrrev_b32_e32 v2, 16, v2
	v_add3_u32 v101, v47, v101, s80
	v_and_or_b32 v101, v101, s85, v2
	v_bfe_u32 v2, v71, 16, 1
	v_add3_u32 v2, v71, v2, s80
	v_bfe_u32 v102, v43, 16, 1
	v_lshrrev_b32_e32 v2, 16, v2
	v_add3_u32 v102, v43, v102, s80
	v_and_or_b32 v102, v102, s85, v2
	v_bfe_u32 v2, v87, 16, 1
	v_add3_u32 v2, v87, v2, s80
	v_bfe_u32 v103, v91, 16, 1
	v_lshrrev_b32_e32 v2, 16, v2
	v_add3_u32 v103, v91, v103, s80
	v_add_co_u32_e32 v104, vcc, 0x9000, v104
	v_and_or_b32 v103, v103, s85, v2
	s_nop 0
	v_addc_co_u32_e32 v105, vcc, 0, v105, vcc
	global_store_dwordx4 v[104:105], v[100:103], off nt
	s_andn2_b64 vcc, exec, s[22:23]
	s_cbranch_vccnz .LBB0_2559
.LBB0_2608:
	s_ashr_i32 s4, s14, 31
	s_lshr_b32 s4, s4, 25
	s_add_i32 s14, s14, s4
	s_ashr_i32 s4, s14, 7
	v_lshl_or_b32 v100, s4, 6, v231
	v_add_u32_e32 v2, s0, v135
	s_lshl_b32 s4, s4, 12
	v_subrev_u32_e32 v2, s4, v2
	v_mov_b64_e32 v[102:103], s[16:17]
	v_ashrrev_i32_e32 v101, 31, v100
	v_mad_i64_i32 v[102:103], s[4:5], v2, s91, v[102:103]
	v_bfe_u32 v2, v8, 16, 1
	v_lshl_add_u64 v[104:105], v[100:101], 1, v[102:103]
	v_add3_u32 v2, v8, v2, s80
	v_bfe_u32 v100, v4, 16, 1
	v_lshrrev_b32_e32 v2, 16, v2
	v_add3_u32 v100, v4, v100, s80
	v_and_or_b32 v100, v100, s85, v2
	v_bfe_u32 v2, v28, 16, 1
	v_add3_u32 v2, v28, v2, s80
	v_bfe_u32 v101, v24, 16, 1
	v_lshrrev_b32_e32 v2, 16, v2
	v_add3_u32 v101, v24, v101, s80
	v_and_or_b32 v101, v101, s85, v2
	v_bfe_u32 v2, v52, 16, 1
	v_add3_u32 v2, v52, v2, s80
	v_bfe_u32 v102, v16, 16, 1
	v_lshrrev_b32_e32 v2, 16, v2
	v_add3_u32 v102, v16, v102, s80
	v_and_or_b32 v102, v102, s85, v2
	v_bfe_u32 v2, v72, 16, 1
	v_add3_u32 v2, v72, v2, s80
	v_bfe_u32 v103, v76, 16, 1
	v_lshrrev_b32_e32 v2, 16, v2
	v_add3_u32 v103, v76, v103, s80
	v_and_or_b32 v103, v103, s85, v2
	v_bfe_u32 v2, v9, 16, 1
	global_store_dwordx4 v[104:105], v[100:103], off nt
	v_add3_u32 v2, v9, v2, s80
	v_lshrrev_b32_e32 v2, 16, v2
	v_bfe_u32 v100, v5, 16, 1
	v_add3_u32 v100, v5, v100, s80
	v_and_or_b32 v100, v100, s85, v2
	v_bfe_u32 v2, v29, 16, 1
	v_add3_u32 v2, v29, v2, s80
	v_bfe_u32 v101, v25, 16, 1
	v_lshrrev_b32_e32 v2, 16, v2
	v_add3_u32 v101, v25, v101, s80
	v_and_or_b32 v101, v101, s85, v2
	v_bfe_u32 v2, v53, 16, 1
	v_add3_u32 v2, v53, v2, s80
	v_bfe_u32 v102, v17, 16, 1
	v_lshrrev_b32_e32 v2, 16, v2
	v_add3_u32 v102, v17, v102, s80
	v_and_or_b32 v102, v102, s85, v2
	v_bfe_u32 v2, v73, 16, 1
	v_add3_u32 v2, v73, v2, s80
	v_bfe_u32 v103, v77, 16, 1
	v_lshrrev_b32_e32 v2, 16, v2
	v_add3_u32 v103, v77, v103, s80
	v_add_co_u32_e32 v106, vcc, s91, v104
	v_and_or_b32 v103, v103, s85, v2
	s_nop 0
	v_addc_co_u32_e32 v107, vcc, 0, v105, vcc
	v_bfe_u32 v2, v10, 16, 1
	global_store_dwordx4 v[106:107], v[100:103], off nt
	v_add3_u32 v2, v10, v2, s80
	v_lshrrev_b32_e32 v2, 16, v2
	v_bfe_u32 v100, v6, 16, 1
	v_add3_u32 v100, v6, v100, s80
	v_and_or_b32 v100, v100, s85, v2
	v_bfe_u32 v2, v30, 16, 1
	v_add3_u32 v2, v30, v2, s80
	v_bfe_u32 v101, v26, 16, 1
	v_lshrrev_b32_e32 v2, 16, v2
	v_add3_u32 v101, v26, v101, s80
	v_and_or_b32 v101, v101, s85, v2
	v_bfe_u32 v2, v54, 16, 1
	v_add3_u32 v2, v54, v2, s80
	v_bfe_u32 v102, v18, 16, 1
	v_lshrrev_b32_e32 v2, 16, v2
	v_add3_u32 v102, v18, v102, s80
	v_and_or_b32 v102, v102, s85, v2
	v_bfe_u32 v2, v74, 16, 1
	v_add3_u32 v2, v74, v2, s80
	v_bfe_u32 v103, v78, 16, 1
	v_lshrrev_b32_e32 v2, 16, v2
	v_add3_u32 v103, v78, v103, s80
	v_add_co_u32_e32 v106, vcc, s87, v104
	v_and_or_b32 v103, v103, s85, v2
	s_nop 0
	v_addc_co_u32_e32 v107, vcc, 0, v105, vcc
	v_bfe_u32 v2, v11, 16, 1
	global_store_dwordx4 v[106:107], v[100:103], off nt
	v_add3_u32 v2, v11, v2, s80
	v_lshrrev_b32_e32 v2, 16, v2
	v_bfe_u32 v100, v7, 16, 1
	v_add3_u32 v100, v7, v100, s80
	v_and_or_b32 v100, v100, s85, v2
	v_bfe_u32 v2, v31, 16, 1
	v_add3_u32 v2, v31, v2, s80
	v_bfe_u32 v101, v27, 16, 1
	v_lshrrev_b32_e32 v2, 16, v2
	v_add3_u32 v101, v27, v101, s80
	v_and_or_b32 v101, v101, s85, v2
	v_bfe_u32 v2, v55, 16, 1
	v_add3_u32 v2, v55, v2, s80
	v_bfe_u32 v102, v19, 16, 1
	v_lshrrev_b32_e32 v2, 16, v2
	v_add3_u32 v102, v19, v102, s80
	v_and_or_b32 v102, v102, s85, v2
	v_bfe_u32 v2, v75, 16, 1
	v_add3_u32 v2, v75, v2, s80
	v_bfe_u32 v103, v79, 16, 1
	v_lshrrev_b32_e32 v2, 16, v2
	v_add3_u32 v103, v79, v103, s80
	v_add_co_u32_e32 v104, vcc, 0x9000, v104
	v_and_or_b32 v103, v103, s85, v2
	s_nop 0
	v_addc_co_u32_e32 v105, vcc, 0, v105, vcc
	global_store_dwordx4 v[104:105], v[100:103], off nt
	s_branch .LBB0_2559

.LBB0_2655:
	v_ashrrev_i32_e32 v135, 31, v134
	s_waitcnt vmcnt(1)
	v_bfe_u32 v2, v104, 16, 1
	v_lshlrev_b64 v[134:135], 13, v[134:135]
	v_add3_u32 v2, v104, v2, s80
	s_waitcnt vmcnt(0)
	v_bfe_u32 v104, v100, 16, 1
	v_lshl_add_u64 v[134:135], s[12:13], 0, v[134:135]
	v_lshrrev_b32_e32 v2, 16, v2
	v_add3_u32 v100, v100, v104, s80
	v_lshl_add_u64 v[140:141], v[132:133], 1, v[134:135]
	v_and_or_b32 v132, v100, s85, v2
	v_bfe_u32 v2, v116, 16, 1
	v_add3_u32 v2, v116, v2, s80
	v_bfe_u32 v100, v112, 16, 1
	v_lshrrev_b32_e32 v2, 16, v2
	v_add3_u32 v100, v112, v100, s80
	v_and_or_b32 v133, v100, s85, v2
	v_bfe_u32 v2, v120, 16, 1
	v_add3_u32 v2, v120, v2, s80
	v_bfe_u32 v100, v108, 16, 1
	v_lshrrev_b32_e32 v2, 16, v2
	v_add3_u32 v100, v108, v100, s80
	v_and_or_b32 v134, v100, s85, v2
	v_bfe_u32 v2, v128, 16, 1
	v_add3_u32 v2, v128, v2, s80
	v_bfe_u32 v100, v124, 16, 1
	v_lshrrev_b32_e32 v2, 16, v2
	v_add3_u32 v100, v124, v100, s80
	v_and_or_b32 v135, v100, s85, v2
	v_bfe_u32 v2, v105, 16, 1
	v_add3_u32 v2, v105, v2, s80
	v_bfe_u32 v100, v101, 16, 1
	v_lshrrev_b32_e32 v2, 16, v2
	v_add3_u32 v100, v101, v100, s80
	global_store_dwordx4 v[140:141], v[132:135], off nt
	s_nop 1
	v_and_or_b32 v132, v100, s85, v2
	v_bfe_u32 v2, v117, 16, 1
	v_add3_u32 v2, v117, v2, s80
	v_bfe_u32 v100, v113, 16, 1
	v_lshrrev_b32_e32 v2, 16, v2
	v_add3_u32 v100, v113, v100, s80
	v_and_or_b32 v133, v100, s85, v2
	v_bfe_u32 v2, v121, 16, 1
	v_add3_u32 v2, v121, v2, s80
	v_bfe_u32 v100, v109, 16, 1
	v_lshrrev_b32_e32 v2, 16, v2
	v_add3_u32 v100, v109, v100, s80
	v_and_or_b32 v134, v100, s85, v2
	v_bfe_u32 v2, v129, 16, 1
	v_add3_u32 v2, v129, v2, s80
	v_bfe_u32 v100, v125, 16, 1
	v_lshrrev_b32_e32 v2, 16, v2
	v_add3_u32 v100, v125, v100, s80
	v_and_or_b32 v135, v100, s85, v2
	v_add_co_u32_e32 v100, vcc, s84, v140
	v_bfe_u32 v2, v106, 16, 1
	s_nop 0
	v_addc_co_u32_e32 v101, vcc, 0, v141, vcc
	global_store_dwordx4 v[100:101], v[132:135], off nt
	v_add3_u32 v2, v106, v2, s80
	v_bfe_u32 v100, v102, 16, 1
	v_lshrrev_b32_e32 v2, 16, v2
	v_add3_u32 v100, v102, v100, s80
	v_and_or_b32 v132, v100, s85, v2
	v_bfe_u32 v2, v118, 16, 1
	v_add3_u32 v2, v118, v2, s80
	v_bfe_u32 v100, v114, 16, 1
	v_lshrrev_b32_e32 v2, 16, v2
	v_add3_u32 v100, v114, v100, s80
	v_and_or_b32 v133, v100, s85, v2
	v_bfe_u32 v2, v122, 16, 1
	v_add3_u32 v2, v122, v2, s80
	v_bfe_u32 v100, v110, 16, 1
	v_lshrrev_b32_e32 v2, 16, v2
	v_add3_u32 v100, v110, v100, s80
	v_and_or_b32 v134, v100, s85, v2
	v_bfe_u32 v2, v130, 16, 1
	v_add3_u32 v2, v130, v2, s80
	v_bfe_u32 v100, v126, 16, 1
	v_lshrrev_b32_e32 v2, 16, v2
	v_add3_u32 v100, v126, v100, s80
	v_and_or_b32 v135, v100, s85, v2
	v_add_co_u32_e32 v100, vcc, s81, v140
	v_bfe_u32 v2, v107, 16, 1
	s_nop 0
	v_addc_co_u32_e32 v101, vcc, 0, v141, vcc
	global_store_dwordx4 v[100:101], v[132:135], off nt
	v_add3_u32 v2, v107, v2, s80
	v_bfe_u32 v100, v103, 16, 1
	v_lshrrev_b32_e32 v2, 16, v2
	v_add3_u32 v100, v103, v100, s80
	v_and_or_b32 v100, v100, s85, v2
	v_bfe_u32 v2, v119, 16, 1
	v_add3_u32 v2, v119, v2, s80
	v_bfe_u32 v101, v115, 16, 1
	v_lshrrev_b32_e32 v2, 16, v2
	v_add3_u32 v101, v115, v101, s80
	v_and_or_b32 v101, v101, s85, v2
	v_bfe_u32 v2, v123, 16, 1
	v_add3_u32 v2, v123, v2, s80
	v_bfe_u32 v102, v111, 16, 1
	v_lshrrev_b32_e32 v2, 16, v2
	v_add3_u32 v102, v111, v102, s80
	v_and_or_b32 v102, v102, s85, v2
	v_bfe_u32 v2, v131, 16, 1
	v_add3_u32 v2, v131, v2, s80
	v_bfe_u32 v103, v127, 16, 1
	v_add_co_u32_e32 v104, vcc, 0x6000, v140
	v_lshrrev_b32_e32 v2, 16, v2
	v_add3_u32 v103, v127, v103, s80
	v_addc_co_u32_e32 v105, vcc, 0, v141, vcc
	v_and_or_b32 v103, v103, s85, v2
	s_andn2_b64 vcc, exec, s[16:17]
	global_store_dwordx4 v[104:105], v[100:103], off nt
	s_cbranch_vccnz .LBB0_2658
	s_ashr_i32 s6, s1, 31
	s_lshr_b32 s6, s6, 25
	s_add_i32 s1, s1, s6
	s_ashr_i32 s1, s1, 7
	v_lshl_or_b32 v100, s1, 6, v231
	v_add_u32_e32 v2, s0, v138
	s_lshl_b32 s1, s1, 12
	v_subrev_u32_e32 v102, s1, v2
	v_ashrrev_i32_e32 v103, 31, v102
	v_lshlrev_b64 v[102:103], 13, v[102:103]
	v_ashrrev_i32_e32 v101, 31, v100
	v_lshl_add_u64 v[102:103], s[12:13], 0, v[102:103]
	v_bfe_u32 v2, v36, 16, 1
	v_lshl_add_u64 v[104:105], v[100:101], 1, v[102:103]
	v_add3_u32 v2, v36, v2, s80
	v_bfe_u32 v100, v32, 16, 1
	v_lshrrev_b32_e32 v2, 16, v2
	v_add3_u32 v100, v32, v100, s80
	v_and_or_b32 v100, v100, s85, v2
	v_bfe_u32 v2, v64, 16, 1
	v_add3_u32 v2, v64, v2, s80
	v_bfe_u32 v101, v60, 16, 1
	v_lshrrev_b32_e32 v2, 16, v2
	v_add3_u32 v101, v60, v101, s80
	v_and_or_b32 v101, v101, s85, v2
	v_bfe_u32 v2, v80, 16, 1
	v_add3_u32 v2, v80, v2, s80
	v_bfe_u32 v102, v56, 16, 1
	v_lshrrev_b32_e32 v2, 16, v2
	v_add3_u32 v102, v56, v102, s80
	v_and_or_b32 v102, v102, s85, v2
	v_bfe_u32 v2, v92, 16, 1
	v_add3_u32 v2, v92, v2, s80
	v_bfe_u32 v103, v96, 16, 1
	v_lshrrev_b32_e32 v2, 16, v2
	v_add3_u32 v103, v96, v103, s80
	v_and_or_b32 v103, v103, s85, v2
	v_bfe_u32 v2, v37, 16, 1
	global_store_dwordx4 v[104:105], v[100:103], off nt
	v_add3_u32 v2, v37, v2, s80
	v_lshrrev_b32_e32 v2, 16, v2
	v_bfe_u32 v100, v33, 16, 1
	v_add3_u32 v100, v33, v100, s80
	v_and_or_b32 v100, v100, s85, v2
	v_bfe_u32 v2, v65, 16, 1
	v_add3_u32 v2, v65, v2, s80
	v_bfe_u32 v101, v61, 16, 1
	v_lshrrev_b32_e32 v2, 16, v2
	v_add3_u32 v101, v61, v101, s80
	v_and_or_b32 v101, v101, s85, v2
	v_bfe_u32 v2, v81, 16, 1
	v_add3_u32 v2, v81, v2, s80
	v_bfe_u32 v102, v57, 16, 1
	v_lshrrev_b32_e32 v2, 16, v2
	v_add3_u32 v102, v57, v102, s80
	v_and_or_b32 v102, v102, s85, v2
	v_bfe_u32 v2, v93, 16, 1
	v_add3_u32 v2, v93, v2, s80
	v_bfe_u32 v103, v97, 16, 1
	v_lshrrev_b32_e32 v2, 16, v2
	v_add3_u32 v103, v97, v103, s80
	v_add_co_u32_e32 v106, vcc, s84, v104
	v_and_or_b32 v103, v103, s85, v2
	s_nop 0
	v_addc_co_u32_e32 v107, vcc, 0, v105, vcc
	v_bfe_u32 v2, v38, 16, 1
	global_store_dwordx4 v[106:107], v[100:103], off nt
	v_add3_u32 v2, v38, v2, s80
	v_lshrrev_b32_e32 v2, 16, v2
	v_bfe_u32 v100, v34, 16, 1
	v_add3_u32 v100, v34, v100, s80
	v_and_or_b32 v100, v100, s85, v2
	v_bfe_u32 v2, v66, 16, 1
	v_add3_u32 v2, v66, v2, s80
	v_bfe_u32 v101, v62, 16, 1
	v_lshrrev_b32_e32 v2, 16, v2
	v_add3_u32 v101, v62, v101, s80
	v_and_or_b32 v101, v101, s85, v2
	v_bfe_u32 v2, v82, 16, 1
	v_add3_u32 v2, v82, v2, s80
	v_bfe_u32 v102, v58, 16, 1
	v_lshrrev_b32_e32 v2, 16, v2
	v_add3_u32 v102, v58, v102, s80
	v_and_or_b32 v102, v102, s85, v2
	v_bfe_u32 v2, v94, 16, 1
	v_add3_u32 v2, v94, v2, s80
	v_bfe_u32 v103, v98, 16, 1
	v_lshrrev_b32_e32 v2, 16, v2
	v_add3_u32 v103, v98, v103, s80
	v_add_co_u32_e32 v106, vcc, s81, v104
	v_and_or_b32 v103, v103, s85, v2
	s_nop 0
	v_addc_co_u32_e32 v107, vcc, 0, v105, vcc
	v_bfe_u32 v2, v39, 16, 1
	global_store_dwordx4 v[106:107], v[100:103], off nt
	v_add3_u32 v2, v39, v2, s80
	v_lshrrev_b32_e32 v2, 16, v2
	v_bfe_u32 v100, v35, 16, 1
	v_add3_u32 v100, v35, v100, s80
	v_and_or_b32 v100, v100, s85, v2
	v_bfe_u32 v2, v67, 16, 1
	v_add3_u32 v2, v67, v2, s80
	v_bfe_u32 v101, v63, 16, 1
	v_lshrrev_b32_e32 v2, 16, v2
	v_add3_u32 v101, v63, v101, s80
	v_and_or_b32 v101, v101, s85, v2
	v_bfe_u32 v2, v83, 16, 1
	v_add3_u32 v2, v83, v2, s80
	v_bfe_u32 v102, v59, 16, 1
	v_lshrrev_b32_e32 v2, 16, v2
	v_add3_u32 v102, v59, v102, s80
	v_and_or_b32 v102, v102, s85, v2
	v_bfe_u32 v2, v95, 16, 1
	v_add3_u32 v2, v95, v2, s80
	v_bfe_u32 v103, v99, 16, 1
	v_lshrrev_b32_e32 v2, 16, v2
	v_add3_u32 v103, v99, v103, s80
	v_add_co_u32_e32 v104, vcc, 0x6000, v104
	v_and_or_b32 v103, v103, s85, v2
	s_nop 0
	v_addc_co_u32_e32 v105, vcc, 0, v105, vcc
	global_store_dwordx4 v[104:105], v[100:103], off nt
	s_andn2_b64 vcc, exec, s[18:19]
	s_cbranch_vccz .LBB0_2659

.LBB0_2659:
	s_ashr_i32 s1, s4, 31
	s_lshr_b32 s1, s1, 25
	s_add_i32 s4, s4, s1
	s_ashr_i32 s1, s4, 7
	v_lshl_or_b32 v100, s1, 6, v231
	v_add_u32_e32 v2, s0, v136
	s_lshl_b32 s1, s1, 12
	v_subrev_u32_e32 v102, s1, v2
	v_ashrrev_i32_e32 v103, 31, v102
	v_lshlrev_b64 v[102:103], 13, v[102:103]
	v_ashrrev_i32_e32 v101, 31, v100
	v_lshl_add_u64 v[102:103], s[12:13], 0, v[102:103]
	v_bfe_u32 v2, v20, 16, 1
	v_lshl_add_u64 v[104:105], v[100:101], 1, v[102:103]
	v_add3_u32 v2, v20, v2, s80
	v_bfe_u32 v100, v12, 16, 1
	v_lshrrev_b32_e32 v2, 16, v2
	v_add3_u32 v100, v12, v100, s80
	v_and_or_b32 v100, v100, s85, v2
	v_bfe_u32 v2, v48, 16, 1
	v_add3_u32 v2, v48, v2, s80
	v_bfe_u32 v101, v44, 16, 1
	v_lshrrev_b32_e32 v2, 16, v2
	v_add3_u32 v101, v44, v101, s80
	v_and_or_b32 v101, v101, s85, v2
	v_bfe_u32 v2, v68, 16, 1
	v_add3_u32 v2, v68, v2, s80
	v_bfe_u32 v102, v40, 16, 1
	v_lshrrev_b32_e32 v2, 16, v2
	v_add3_u32 v102, v40, v102, s80
	v_and_or_b32 v102, v102, s85, v2
	v_bfe_u32 v2, v84, 16, 1
	v_add3_u32 v2, v84, v2, s80
	v_bfe_u32 v103, v88, 16, 1
	v_lshrrev_b32_e32 v2, 16, v2
	v_add3_u32 v103, v88, v103, s80
	v_and_or_b32 v103, v103, s85, v2
	v_bfe_u32 v2, v21, 16, 1
	global_store_dwordx4 v[104:105], v[100:103], off nt
	v_add3_u32 v2, v21, v2, s80
	v_lshrrev_b32_e32 v2, 16, v2
	v_bfe_u32 v100, v13, 16, 1
	v_add3_u32 v100, v13, v100, s80
	v_and_or_b32 v100, v100, s85, v2
	v_bfe_u32 v2, v49, 16, 1
	v_add3_u32 v2, v49, v2, s80
	v_bfe_u32 v101, v45, 16, 1
	v_lshrrev_b32_e32 v2, 16, v2
	v_add3_u32 v101, v45, v101, s80
	v_and_or_b32 v101, v101, s85, v2
	v_bfe_u32 v2, v69, 16, 1
	v_add3_u32 v2, v69, v2, s80
	v_bfe_u32 v102, v41, 16, 1
	v_lshrrev_b32_e32 v2, 16, v2
	v_add3_u32 v102, v41, v102, s80
	v_and_or_b32 v102, v102, s85, v2
	v_bfe_u32 v2, v85, 16, 1
	v_add3_u32 v2, v85, v2, s80
	v_bfe_u32 v103, v89, 16, 1
	v_lshrrev_b32_e32 v2, 16, v2
	v_add3_u32 v103, v89, v103, s80
	v_add_co_u32_e32 v106, vcc, s84, v104
	v_and_or_b32 v103, v103, s85, v2
	s_nop 0
	v_addc_co_u32_e32 v107, vcc, 0, v105, vcc
	v_bfe_u32 v2, v22, 16, 1
	global_store_dwordx4 v[106:107], v[100:103], off nt
	v_add3_u32 v2, v22, v2, s80
	v_lshrrev_b32_e32 v2, 16, v2
	v_bfe_u32 v100, v14, 16, 1
	v_add3_u32 v100, v14, v100, s80
	v_and_or_b32 v100, v100, s85, v2
	v_bfe_u32 v2, v50, 16, 1
	v_add3_u32 v2, v50, v2, s80
	v_bfe_u32 v101, v46, 16, 1
	v_lshrrev_b32_e32 v2, 16, v2
	v_add3_u32 v101, v46, v101, s80
	v_and_or_b32 v101, v101, s85, v2
	v_bfe_u32 v2, v70, 16, 1
	v_add3_u32 v2, v70, v2, s80
	v_bfe_u32 v102, v42, 16, 1
	v_lshrrev_b32_e32 v2, 16, v2
	v_add3_u32 v102, v42, v102, s80
	v_and_or_b32 v102, v102, s85, v2
	v_bfe_u32 v2, v86, 16, 1
	v_add3_u32 v2, v86, v2, s80
	v_bfe_u32 v103, v90, 16, 1
	v_lshrrev_b32_e32 v2, 16, v2
	v_add3_u32 v103, v90, v103, s80
	v_add_co_u32_e32 v106, vcc, s81, v104
	v_and_or_b32 v103, v103, s85, v2
	s_nop 0
	v_addc_co_u32_e32 v107, vcc, 0, v105, vcc
	v_bfe_u32 v2, v23, 16, 1
	global_store_dwordx4 v[106:107], v[100:103], off nt
	v_add3_u32 v2, v23, v2, s80
	v_lshrrev_b32_e32 v2, 16, v2
	v_bfe_u32 v100, v15, 16, 1
	v_add3_u32 v100, v15, v100, s80
	v_and_or_b32 v100, v100, s85, v2
	v_bfe_u32 v2, v51, 16, 1
	v_add3_u32 v2, v51, v2, s80
	v_bfe_u32 v101, v47, 16, 1
	v_lshrrev_b32_e32 v2, 16, v2
	v_add3_u32 v101, v47, v101, s80
	v_and_or_b32 v101, v101, s85, v2
	v_bfe_u32 v2, v71, 16, 1
	v_add3_u32 v2, v71, v2, s80
	v_bfe_u32 v102, v43, 16, 1
	v_lshrrev_b32_e32 v2, 16, v2
	v_add3_u32 v102, v43, v102, s80
	v_and_or_b32 v102, v102, s85, v2
	v_bfe_u32 v2, v87, 16, 1
	v_add3_u32 v2, v87, v2, s80
	v_bfe_u32 v103, v91, 16, 1
	v_lshrrev_b32_e32 v2, 16, v2
	v_add3_u32 v103, v91, v103, s80
	v_add_co_u32_e32 v104, vcc, 0x6000, v104
	v_and_or_b32 v103, v103, s85, v2
	s_nop 0
	v_addc_co_u32_e32 v105, vcc, 0, v105, vcc
	global_store_dwordx4 v[104:105], v[100:103], off nt
	s_andn2_b64 vcc, exec, s[20:21]
	s_cbranch_vccnz .LBB0_2611
.LBB0_2660:
	s_ashr_i32 s1, s5, 31
	s_lshr_b32 s1, s1, 25
	s_add_i32 s5, s5, s1
	s_ashr_i32 s1, s5, 7
	v_lshl_or_b32 v100, s1, 6, v231
	v_add_u32_e32 v2, s0, v137
	s_lshl_b32 s1, s1, 12
	v_subrev_u32_e32 v102, s1, v2
	v_ashrrev_i32_e32 v103, 31, v102
	v_lshlrev_b64 v[102:103], 13, v[102:103]
	v_ashrrev_i32_e32 v101, 31, v100
	v_lshl_add_u64 v[102:103], s[12:13], 0, v[102:103]
	v_bfe_u32 v2, v8, 16, 1
	v_lshl_add_u64 v[104:105], v[100:101], 1, v[102:103]
	v_add3_u32 v2, v8, v2, s80
	v_bfe_u32 v100, v4, 16, 1
	v_lshrrev_b32_e32 v2, 16, v2
	v_add3_u32 v100, v4, v100, s80
	v_and_or_b32 v100, v100, s85, v2
	v_bfe_u32 v2, v28, 16, 1
	v_add3_u32 v2, v28, v2, s80
	v_bfe_u32 v101, v24, 16, 1
	v_lshrrev_b32_e32 v2, 16, v2
	v_add3_u32 v101, v24, v101, s80
	v_and_or_b32 v101, v101, s85, v2
	v_bfe_u32 v2, v52, 16, 1
	v_add3_u32 v2, v52, v2, s80
	v_bfe_u32 v102, v16, 16, 1
	v_lshrrev_b32_e32 v2, 16, v2
	v_add3_u32 v102, v16, v102, s80
	v_and_or_b32 v102, v102, s85, v2
	v_bfe_u32 v2, v72, 16, 1
	v_add3_u32 v2, v72, v2, s80
	v_bfe_u32 v103, v76, 16, 1
	v_lshrrev_b32_e32 v2, 16, v2
	v_add3_u32 v103, v76, v103, s80
	v_and_or_b32 v103, v103, s85, v2
	v_bfe_u32 v2, v9, 16, 1
	global_store_dwordx4 v[104:105], v[100:103], off nt
	v_add3_u32 v2, v9, v2, s80
	v_lshrrev_b32_e32 v2, 16, v2
	v_bfe_u32 v100, v5, 16, 1
	v_add3_u32 v100, v5, v100, s80
	v_and_or_b32 v100, v100, s85, v2
	v_bfe_u32 v2, v29, 16, 1
	v_add3_u32 v2, v29, v2, s80
	v_bfe_u32 v101, v25, 16, 1
	v_lshrrev_b32_e32 v2, 16, v2
	v_add3_u32 v101, v25, v101, s80
	v_and_or_b32 v101, v101, s85, v2
	v_bfe_u32 v2, v53, 16, 1
	v_add3_u32 v2, v53, v2, s80
	v_bfe_u32 v102, v17, 16, 1
	v_lshrrev_b32_e32 v2, 16, v2
	v_add3_u32 v102, v17, v102, s80
	v_and_or_b32 v102, v102, s85, v2
	v_bfe_u32 v2, v73, 16, 1
	v_add3_u32 v2, v73, v2, s80
	v_bfe_u32 v103, v77, 16, 1
	v_lshrrev_b32_e32 v2, 16, v2
	v_add3_u32 v103, v77, v103, s80
	v_add_co_u32_e32 v106, vcc, s84, v104
	v_and_or_b32 v103, v103, s85, v2
	s_nop 0
	v_addc_co_u32_e32 v107, vcc, 0, v105, vcc
	v_bfe_u32 v2, v10, 16, 1
	global_store_dwordx4 v[106:107], v[100:103], off nt
	v_add3_u32 v2, v10, v2, s80
	v_lshrrev_b32_e32 v2, 16, v2
	v_bfe_u32 v100, v6, 16, 1
	v_add3_u32 v100, v6, v100, s80
	v_and_or_b32 v100, v100, s85, v2
	v_bfe_u32 v2, v30, 16, 1
	v_add3_u32 v2, v30, v2, s80
	v_bfe_u32 v101, v26, 16, 1
	v_lshrrev_b32_e32 v2, 16, v2
	v_add3_u32 v101, v26, v101, s80
	v_and_or_b32 v101, v101, s85, v2
	v_bfe_u32 v2, v54, 16, 1
	v_add3_u32 v2, v54, v2, s80
	v_bfe_u32 v102, v18, 16, 1
	v_lshrrev_b32_e32 v2, 16, v2
	v_add3_u32 v102, v18, v102, s80
	v_and_or_b32 v102, v102, s85, v2
	v_bfe_u32 v2, v74, 16, 1
	v_add3_u32 v2, v74, v2, s80
	v_bfe_u32 v103, v78, 16, 1
	v_lshrrev_b32_e32 v2, 16, v2
	v_add3_u32 v103, v78, v103, s80
	v_add_co_u32_e32 v106, vcc, s81, v104
	v_and_or_b32 v103, v103, s85, v2
	s_nop 0
	v_addc_co_u32_e32 v107, vcc, 0, v105, vcc
	v_bfe_u32 v2, v11, 16, 1
	global_store_dwordx4 v[106:107], v[100:103], off nt
	v_add3_u32 v2, v11, v2, s80
	v_lshrrev_b32_e32 v2, 16, v2
	v_bfe_u32 v100, v7, 16, 1
	v_add3_u32 v100, v7, v100, s80
	v_and_or_b32 v100, v100, s85, v2
	v_bfe_u32 v2, v31, 16, 1
	v_add3_u32 v2, v31, v2, s80
	v_bfe_u32 v101, v27, 16, 1
	v_lshrrev_b32_e32 v2, 16, v2
	v_add3_u32 v101, v27, v101, s80
	v_and_or_b32 v101, v101, s85, v2
	v_bfe_u32 v2, v55, 16, 1
	v_add3_u32 v2, v55, v2, s80
	v_bfe_u32 v102, v19, 16, 1
	v_lshrrev_b32_e32 v2, 16, v2
	v_add3_u32 v102, v19, v102, s80
	v_and_or_b32 v102, v102, s85, v2
	v_bfe_u32 v2, v75, 16, 1
	v_add3_u32 v2, v75, v2, s80
	v_bfe_u32 v103, v79, 16, 1
	v_lshrrev_b32_e32 v2, 16, v2
	v_add3_u32 v103, v79, v103, s80
	v_add_co_u32_e32 v104, vcc, 0x6000, v104
	v_and_or_b32 v103, v103, s85, v2
	s_nop 0
	v_addc_co_u32_e32 v105, vcc, 0, v105, vcc
	global_store_dwordx4 v[104:105], v[100:103], off nt
	s_branch .LBB0_2611

.LBB0_3030:
	s_or_b64 exec, exec, s[16:17]
	s_waitcnt lgkmcnt(0)
	v_max_f32_e32 v2, v132, v132
	v_max_f32_e32 v2, 0xda24260, v2
	v_div_scale_f32 v132, s[16:17], v2, v2, s88
	v_rcp_f32_e32 v136, v132
	v_div_scale_f32 v137, vcc, s88, v2, s88
	v_max_f32_e32 v133, v133, v133
	v_fma_f32 v139, -v132, v136, 1.0
	v_fmac_f32_e32 v136, v139, v136
	v_mul_f32_e32 v139, v137, v136
	v_fma_f32 v140, -v132, v139, v137
	v_fmac_f32_e32 v139, v140, v136
	v_max_f32_e32 v133, 0xda24260, v133
	v_fma_f32 v132, -v132, v139, v137
	v_div_scale_f32 v137, s[16:17], v133, v133, s88
	v_rcp_f32_e32 v140, v137
	v_div_fmas_f32 v132, v132, v136, v139
	v_div_fixup_f32 v2, v132, v2, s88
	v_max_f32_e32 v134, v134, v134
	v_fma_f32 v132, -v137, v140, 1.0
	v_fmac_f32_e32 v140, v132, v140
	v_div_scale_f32 v132, vcc, s88, v133, s88
	v_mul_f32_e32 v136, v132, v140
	v_fma_f32 v139, -v137, v136, v132
	v_fmac_f32_e32 v136, v139, v140
	v_max_f32_e32 v134, 0xda24260, v134
	v_fma_f32 v132, -v137, v136, v132
	v_div_scale_f32 v137, s[16:17], v134, v134, s88
	v_rcp_f32_e32 v139, v137
	v_div_fmas_f32 v132, v132, v140, v136
	v_div_fixup_f32 v132, v132, v133, s88
	v_max_f32_e32 v135, v135, v135
	v_fma_f32 v133, -v137, v139, 1.0
	v_fmac_f32_e32 v139, v133, v139
	v_div_scale_f32 v133, vcc, s88, v134, s88
	v_mul_f32_e32 v136, v133, v139
	v_fma_f32 v140, -v137, v136, v133
	v_fmac_f32_e32 v136, v140, v139
	v_max_f32_e32 v135, 0xda24260, v135
	v_fma_f32 v133, -v137, v136, v133
	v_div_scale_f32 v137, s[16:17], v135, v135, s88
	v_rcp_f32_e32 v140, v137
	v_div_fmas_f32 v133, v133, v139, v136
	v_div_fixup_f32 v133, v133, v134, s88
	v_bfe_u32 v176, v126, 16, 1
	v_fma_f32 v134, -v137, v140, 1.0
	v_fmac_f32_e32 v140, v134, v140
	v_div_scale_f32 v134, vcc, s88, v135, s88
	v_mul_f32_e32 v136, v134, v140
	v_fma_f32 v139, -v137, v136, v134
	v_fmac_f32_e32 v136, v139, v140
	v_fma_f32 v134, -v137, v136, v134
	v_div_fmas_f32 v134, v134, v140, v136
	v_bfe_u32 v136, v79, 16, 1
	v_add3_u32 v169, v79, v136, s80
	v_bfe_u32 v79, v72, 16, 1
	v_add3_u32 v136, v72, v79, s80
	v_add3_u32 v79, v126, v176, s80
	v_bfe_u32 v126, v12, 16, 1
	v_add3_u32 v12, v12, v126, s80
	v_bfe_u32 v126, v13, 16, 1
	v_add3_u32 v13, v13, v126, s80
	v_bfe_u32 v126, v14, 16, 1
	v_add3_u32 v14, v14, v126, s80
	v_bfe_u32 v126, v15, 16, 1
	v_add3_u32 v15, v15, v126, s80
	v_bfe_u32 v126, v8, 16, 1
	v_add3_u32 v8, v8, v126, s80
	v_bfe_u32 v126, v9, 16, 1
	v_bfe_u32 v147, v91, 16, 1
	v_add3_u32 v9, v9, v126, s80
	v_bfe_u32 v160, v125, 16, 1
	v_add3_u32 v147, v91, v147, s80
	v_bfe_u32 v91, v96, 16, 1
	v_bfe_u32 v179, v128, 16, 1
	v_and_b32_e32 v126, 0xffff0000, v9
	v_bfe_u32 v9, v10, 16, 1
	v_div_fixup_f32 v134, v134, v135, s88
	v_bfe_u32 v135, v77, 16, 1
	v_bfe_u32 v139, v75, 16, 1
	v_add3_u32 v160, v125, v160, s80
	v_add3_u32 v125, v96, v91, s80
	v_add3_u32 v91, v128, v179, s80
	v_add3_u32 v128, v10, v9, s80
	v_bfe_u32 v9, v11, 16, 1
	v_bfe_u32 v162, v121, 16, 1
	v_add3_u32 v77, v77, v135, s80
	v_bfe_u32 v135, v78, 16, 1
	v_add3_u32 v139, v75, v139, s80
	v_bfe_u32 v75, v80, 16, 1
	v_bfe_u32 v180, v130, 16, 1
	v_add3_u32 v9, v11, v9, s80
	v_add3_u32 v162, v121, v162, s80
	v_add3_u32 v121, v78, v135, s80
	v_add3_u32 v135, v80, v75, s80
	v_add3_u32 v75, v130, v180, s80
	v_and_b32_e32 v130, 0xffff0000, v9
	v_bfe_u32 v9, v20, 16, 1
	v_bfe_u32 v11, v22, 16, 1
	v_add3_u32 v9, v20, v9, s80
	v_add3_u32 v20, v22, v11, s80
	v_bfe_u32 v11, v23, 16, 1
	v_bfe_u32 v10, v21, 16, 1
	v_add3_u32 v11, v23, v11, s80
	v_add3_u32 v10, v21, v10, s80
	v_and_b32_e32 v21, 0xffff0000, v11
	v_bfe_u32 v11, v4, 16, 1
	v_add3_u32 v11, v4, v11, s80
	v_bfe_u32 v4, v5, 16, 1
	v_add3_u32 v4, v5, v4, s80
	v_and_b32_e32 v22, 0xffff0000, v4
	v_bfe_u32 v4, v6, 16, 1
	v_bfe_u32 v149, v99, 16, 1
	v_bfe_u32 v151, v87, 16, 1
	v_add3_u32 v23, v6, v4, s80
	v_bfe_u32 v4, v7, 16, 1
	v_bfe_u32 v163, v123, 16, 1
	v_add3_u32 v149, v99, v149, s80
	v_bfe_u32 v99, v84, 16, 1
	v_add3_u32 v87, v87, v151, s80
	v_bfe_u32 v151, v108, 16, 1
	v_add3_u32 v4, v7, v4, s80
	v_add3_u32 v163, v123, v163, s80
	v_add3_u32 v123, v84, v99, s80
	v_add3_u32 v99, v108, v151, s80
	v_and_b32_e32 v108, 0xffff0000, v139
	v_and_b32_e32 v139, 0xffff0000, v4
	v_bfe_u32 v4, v28, 16, 1
	v_add3_u32 v28, v28, v4, s80
	v_bfe_u32 v4, v29, 16, 1
	v_add3_u32 v4, v29, v4, s80
	v_and_b32_e32 v29, 0xffff0000, v4
	v_bfe_u32 v4, v30, 16, 1
	v_add3_u32 v30, v30, v4, s80
	v_bfe_u32 v4, v31, 16, 1
	v_add3_u32 v4, v31, v4, s80
	v_and_b32_e32 v31, 0xffff0000, v4
	v_bfe_u32 v4, v24, 16, 1
	v_add3_u32 v24, v24, v4, s80
	v_bfe_u32 v4, v25, 16, 1
	v_add3_u32 v4, v25, v4, s80
	v_and_b32_e32 v25, 0xffff0000, v4
	v_bfe_u32 v4, v26, 16, 1
	v_add3_u32 v26, v26, v4, s80
	v_bfe_u32 v4, v27, 16, 1
	v_and_b32_e32 v8, 0xffff0000, v8
	v_add3_u32 v4, v27, v4, s80
	v_and_b32_e32 v12, 0xffff0000, v12
	v_mul_f32_e32 v8, v2, v8
	v_and_b32_e32 v9, 0xffff0000, v9
	v_and_b32_e32 v11, 0xffff0000, v11
	v_and_b32_e32 v27, 0xffff0000, v4
	v_bfe_u32 v4, v32, 16, 1
	v_mul_f32_e32 v12, v2, v12
	v_rndne_f32_e32 v8, v8
	v_mul_f32_e32 v9, v2, v9
	v_mul_f32_e32 v11, v2, v11
	v_add3_u32 v32, v32, v4, s80
	v_bfe_u32 v4, v33, 16, 1
	v_rndne_f32_e32 v12, v12
	v_cvt_i32_f32_e32 v8, v8
	v_rndne_f32_e32 v9, v9
	v_rndne_f32_e32 v11, v11
	v_add3_u32 v4, v33, v4, s80
	v_cvt_i32_f32_e32 v12, v12
	v_cvt_i32_f32_sdwa v9, v9 dst_sel:WORD_1 dst_unused:UNUSED_PAD src0_sel:DWORD
	v_cvt_i32_f32_e32 v11, v11
	v_and_b32_e32 v33, 0xffff0000, v4
	v_bfe_u32 v4, v34, 16, 1
	v_add3_u32 v34, v34, v4, s80
	v_bfe_u32 v4, v35, 16, 1
	v_add3_u32 v4, v35, v4, s80
	v_lshlrev_b32_e32 v8, 8, v8
	v_and_b32_e32 v35, 0xffff0000, v4
	v_bfe_u32 v4, v16, 16, 1
	v_and_b32_e32 v8, 0xff00, v8
	v_and_b32_e32 v9, 0xff0000, v9
	v_perm_b32 v11, v11, v12, s89
	v_add3_u32 v16, v16, v4, s80
	v_or3_b32 v8, v11, v8, v9
	v_and_b32_e32 v11, 0xffff0000, v24
	v_and_b32_e32 v9, 0xffff0000, v28
	v_mul_f32_e32 v11, v2, v11
	v_and_b32_e32 v12, 0xffff0000, v32
	v_and_b32_e32 v16, 0xffff0000, v16
	v_mul_f32_e32 v9, v2, v9
	v_rndne_f32_e32 v11, v11
	v_mul_f32_e32 v12, v2, v12
	v_mul_f32_e32 v16, v2, v16
	v_rndne_f32_e32 v9, v9
	v_cvt_i32_f32_e32 v11, v11
	v_rndne_f32_e32 v12, v12
	v_rndne_f32_e32 v16, v16
	v_cvt_i32_f32_e32 v9, v9
	v_cvt_i32_f32_sdwa v12, v12 dst_sel:WORD_1 dst_unused:UNUSED_PAD src0_sel:DWORD
	v_cvt_i32_f32_e32 v16, v16
	v_or_b32_e32 v6, v138, v230
	v_ashrrev_i32_e32 v7, 31, v6
	v_lshlrev_b32_e32 v11, 8, v11
	v_lshlrev_b64 v[6:7], 12, v[6:7]
	v_and_b32_e32 v11, 0xff00, v11
	v_and_b32_e32 v12, 0xff0000, v12
	v_perm_b32 v9, v16, v9, s89
	v_lshl_add_u64 v[6:7], v[206:207], 0, v[6:7]
	v_or3_b32 v9, v9, v11, v12
	v_and_b32_e32 v13, 0xffff0000, v13
	v_and_b32_e32 v10, 0xffff0000, v10
	global_store_dwordx2 v[6:7], v[8:9], off nt
	v_mul_f32_e32 v9, v132, v126
	v_mul_f32_e32 v8, v132, v13
	v_rndne_f32_e32 v9, v9
	v_mul_f32_e32 v10, v132, v10
	v_mul_f32_e32 v11, v132, v22
	v_rndne_f32_e32 v8, v8
	v_cvt_i32_f32_e32 v9, v9
	v_rndne_f32_e32 v10, v10
	v_rndne_f32_e32 v11, v11
	v_cvt_i32_f32_e32 v8, v8
	v_cvt_i32_f32_sdwa v10, v10 dst_sel:WORD_1 dst_unused:UNUSED_PAD src0_sel:DWORD
	v_cvt_i32_f32_e32 v11, v11
	v_bfe_u32 v4, v17, 16, 1
	v_lshlrev_b32_e32 v9, 8, v9
	v_add3_u32 v4, v17, v4, s80
	v_and_b32_e32 v9, 0xff00, v9
	v_and_b32_e32 v10, 0xff0000, v10
	v_perm_b32 v8, v11, v8, s89
	v_and_b32_e32 v17, 0xffff0000, v4
	v_or3_b32 v12, v8, v9, v10
	v_mul_f32_e32 v9, v132, v25
	v_mul_f32_e32 v8, v132, v29
	v_rndne_f32_e32 v9, v9
	v_mul_f32_e32 v10, v132, v33
	v_mul_f32_e32 v11, v132, v17
	v_rndne_f32_e32 v8, v8
	v_cvt_i32_f32_e32 v9, v9
	v_rndne_f32_e32 v10, v10
	v_rndne_f32_e32 v11, v11
	v_cvt_i32_f32_e32 v8, v8
	v_cvt_i32_f32_sdwa v10, v10 dst_sel:WORD_1 dst_unused:UNUSED_PAD src0_sel:DWORD
	v_cvt_i32_f32_e32 v11, v11
	v_lshlrev_b32_e32 v9, 8, v9
	v_and_b32_e32 v9, 0xff00, v9
	v_and_b32_e32 v10, 0xff0000, v10
	v_perm_b32 v8, v11, v8, s89
	s_movk_i32 s15, 0x1000
	v_or3_b32 v13, v8, v9, v10
	v_add_co_u32_e32 v10, vcc, s15, v6
	v_bfe_u32 v4, v18, 16, 1
	s_nop 0
	v_addc_co_u32_e32 v11, vcc, 0, v7, vcc
	v_add_co_u32_e32 v8, vcc, s84, v6
	v_add3_u32 v18, v18, v4, s80
	s_nop 0
	v_addc_co_u32_e32 v9, vcc, 0, v7, vcc
	global_store_dwordx2 v[8:9], v[12:13], off offset:-4096 nt
	v_and_b32_e32 v13, 0xffff0000, v128
	v_bfe_u32 v4, v19, 16, 1
	v_and_b32_e32 v12, 0xffff0000, v14
	v_mul_f32_e32 v13, v133, v13
	v_and_b32_e32 v14, 0xffff0000, v20
	v_and_b32_e32 v16, 0xffff0000, v23
	v_add3_u32 v4, v19, v4, s80
	v_mul_f32_e32 v12, v133, v12
	v_rndne_f32_e32 v13, v13
	v_mul_f32_e32 v14, v133, v14
	v_mul_f32_e32 v16, v133, v16
	v_and_b32_e32 v19, 0xffff0000, v4
	v_bfe_u32 v4, v44, 16, 1
	v_rndne_f32_e32 v12, v12
	v_cvt_i32_f32_e32 v13, v13
	v_rndne_f32_e32 v14, v14
	v_rndne_f32_e32 v16, v16
	v_add3_u32 v44, v44, v4, s80
	v_bfe_u32 v4, v45, 16, 1
	v_cvt_i32_f32_e32 v12, v12
	v_cvt_i32_f32_sdwa v14, v14 dst_sel:WORD_1 dst_unused:UNUSED_PAD src0_sel:DWORD
	v_cvt_i32_f32_e32 v16, v16
	v_add3_u32 v4, v45, v4, s80
	v_and_b32_e32 v45, 0xffff0000, v4
	v_bfe_u32 v4, v46, 16, 1
	v_add3_u32 v46, v46, v4, s80
	v_bfe_u32 v4, v47, 16, 1
	v_lshlrev_b32_e32 v13, 8, v13
	v_add3_u32 v4, v47, v4, s80
	v_and_b32_e32 v13, 0xff00, v13
	v_and_b32_e32 v14, 0xff0000, v14
	v_perm_b32 v12, v16, v12, s89
	v_and_b32_e32 v47, 0xffff0000, v4
	v_bfe_u32 v4, v40, 16, 1
	v_or3_b32 v12, v12, v13, v14
	v_and_b32_e32 v14, 0xffff0000, v26
	v_add3_u32 v40, v40, v4, s80
	v_bfe_u32 v4, v41, 16, 1
	v_and_b32_e32 v13, 0xffff0000, v30
	v_mul_f32_e32 v14, v133, v14
	v_and_b32_e32 v16, 0xffff0000, v34
	v_and_b32_e32 v17, 0xffff0000, v18
	v_add3_u32 v4, v41, v4, s80
	v_mul_f32_e32 v13, v133, v13
	v_rndne_f32_e32 v14, v14
	v_mul_f32_e32 v16, v133, v16
	v_mul_f32_e32 v17, v133, v17
	v_and_b32_e32 v41, 0xffff0000, v4
	v_bfe_u32 v4, v42, 16, 1
	v_rndne_f32_e32 v13, v13
	v_cvt_i32_f32_e32 v14, v14
	v_rndne_f32_e32 v16, v16
	v_rndne_f32_e32 v17, v17
	v_add3_u32 v42, v42, v4, s80
	v_bfe_u32 v4, v43, 16, 1
	v_cvt_i32_f32_e32 v13, v13
	v_cvt_i32_f32_sdwa v16, v16 dst_sel:WORD_1 dst_unused:UNUSED_PAD src0_sel:DWORD
	v_cvt_i32_f32_e32 v17, v17
	v_add3_u32 v4, v43, v4, s80
	v_and_b32_e32 v43, 0xffff0000, v4
	v_bfe_u32 v4, v52, 16, 1
	v_add3_u32 v52, v52, v4, s80
	v_bfe_u32 v4, v53, 16, 1
	v_lshlrev_b32_e32 v14, 8, v14
	v_add3_u32 v4, v53, v4, s80
	v_and_b32_e32 v14, 0xff00, v14
	v_and_b32_e32 v16, 0xff0000, v16
	v_perm_b32 v13, v17, v13, s89
	v_and_b32_e32 v53, 0xffff0000, v4
	v_bfe_u32 v4, v54, 16, 1
	v_or3_b32 v13, v13, v14, v16
	v_and_b32_e32 v15, 0xffff0000, v15
	v_add3_u32 v54, v54, v4, s80
	v_bfe_u32 v4, v55, 16, 1
	global_store_dwordx2 v[8:9], v[12:13], off nt
	v_mul_f32_e32 v13, v134, v130
	v_add3_u32 v4, v55, v4, s80
	v_mul_f32_e32 v12, v134, v15
	v_rndne_f32_e32 v13, v13
	v_mul_f32_e32 v14, v134, v21
	v_mul_f32_e32 v15, v134, v139
	v_and_b32_e32 v55, 0xffff0000, v4
	v_bfe_u32 v4, v36, 16, 1
	v_rndne_f32_e32 v12, v12
	v_cvt_i32_f32_e32 v13, v13
	v_rndne_f32_e32 v14, v14
	v_rndne_f32_e32 v15, v15
	v_add3_u32 v36, v36, v4, s80
	v_bfe_u32 v4, v37, 16, 1
	v_cvt_i32_f32_e32 v12, v12
	v_cvt_i32_f32_sdwa v14, v14 dst_sel:WORD_1 dst_unused:UNUSED_PAD src0_sel:DWORD
	v_cvt_i32_f32_e32 v15, v15
	v_add3_u32 v4, v37, v4, s80
	v_and_b32_e32 v37, 0xffff0000, v4
	v_bfe_u32 v4, v38, 16, 1
	v_add3_u32 v38, v38, v4, s80
	v_bfe_u32 v4, v39, 16, 1
	v_lshlrev_b32_e32 v13, 8, v13
	v_add3_u32 v4, v39, v4, s80
	v_and_b32_e32 v13, 0xff00, v13
	v_and_b32_e32 v14, 0xff0000, v14
	v_perm_b32 v12, v15, v12, s89
	v_and_b32_e32 v39, 0xffff0000, v4
	v_bfe_u32 v4, v60, 16, 1
	v_or3_b32 v14, v12, v13, v14
	v_mul_f32_e32 v13, v134, v27
	v_add3_u32 v60, v60, v4, s80
	v_bfe_u32 v4, v61, 16, 1
	v_mul_f32_e32 v12, v134, v31
	v_rndne_f32_e32 v13, v13
	v_mul_f32_e32 v15, v134, v35
	v_mul_f32_e32 v16, v134, v19
	v_add3_u32 v4, v61, v4, s80
	v_rndne_f32_e32 v12, v12
	v_cvt_i32_f32_e32 v13, v13
	v_rndne_f32_e32 v15, v15
	v_rndne_f32_e32 v16, v16
	v_and_b32_e32 v61, 0xffff0000, v4
	v_bfe_u32 v4, v62, 16, 1
	v_cvt_i32_f32_e32 v12, v12
	v_cvt_i32_f32_sdwa v15, v15 dst_sel:WORD_1 dst_unused:UNUSED_PAD src0_sel:DWORD
	v_cvt_i32_f32_e32 v16, v16
	v_add3_u32 v62, v62, v4, s80
	v_bfe_u32 v4, v63, 16, 1
	v_add3_u32 v4, v63, v4, s80
	v_and_b32_e32 v63, 0xffff0000, v4
	v_bfe_u32 v4, v56, 16, 1
	v_lshlrev_b32_e32 v13, 8, v13
	v_add3_u32 v56, v56, v4, s80
	v_bfe_u32 v4, v57, 16, 1
	v_and_b32_e32 v13, 0xff00, v13
	v_and_b32_e32 v15, 0xff0000, v15
	v_perm_b32 v12, v16, v12, s89
	v_add3_u32 v4, v57, v4, s80
	v_or3_b32 v15, v12, v13, v15
	v_add_co_u32_e32 v12, vcc, s91, v6
	v_and_b32_e32 v57, 0xffff0000, v4
	v_bfe_u32 v4, v58, 16, 1
	v_addc_co_u32_e32 v13, vcc, 0, v7, vcc
	v_add3_u32 v58, v58, v4, s80
	v_bfe_u32 v4, v59, 16, 1
	global_store_dwordx2 v[12:13], v[14:15], off nt
	v_and_b32_e32 v15, 0xffff0000, v40
	v_add3_u32 v4, v59, v4, s80
	v_and_b32_e32 v14, 0xffff0000, v44
	v_mul_f32_e32 v15, v2, v15
	v_and_b32_e32 v16, 0xffff0000, v52
	v_and_b32_e32 v17, 0xffff0000, v36
	v_and_b32_e32 v59, 0xffff0000, v4
	v_bfe_u32 v4, v64, 16, 1
	v_mul_f32_e32 v14, v2, v14
	v_rndne_f32_e32 v15, v15
	v_mul_f32_e32 v16, v2, v16
	v_mul_f32_e32 v17, v2, v17
	v_add3_u32 v64, v64, v4, s80
	v_bfe_u32 v4, v65, 16, 1
	v_rndne_f32_e32 v14, v14
	v_cvt_i32_f32_e32 v15, v15
	v_rndne_f32_e32 v16, v16
	v_rndne_f32_e32 v17, v17
	v_add3_u32 v4, v65, v4, s80
	v_cvt_i32_f32_e32 v14, v14
	v_cvt_i32_f32_sdwa v16, v16 dst_sel:WORD_1 dst_unused:UNUSED_PAD src0_sel:DWORD
	v_cvt_i32_f32_e32 v17, v17
	v_and_b32_e32 v65, 0xffff0000, v4
	v_bfe_u32 v4, v66, 16, 1
	v_add3_u32 v66, v66, v4, s80
	v_bfe_u32 v4, v67, 16, 1
	v_add3_u32 v4, v67, v4, s80
	v_lshlrev_b32_e32 v15, 8, v15
	v_and_b32_e32 v67, 0xffff0000, v4
	v_bfe_u32 v4, v48, 16, 1
	v_and_b32_e32 v15, 0xff00, v15
	v_and_b32_e32 v16, 0xff0000, v16
	v_perm_b32 v14, v17, v14, s89
	v_add3_u32 v48, v48, v4, s80
	v_or3_b32 v14, v14, v15, v16
	v_and_b32_e32 v16, 0xffff0000, v56
	v_and_b32_e32 v15, 0xffff0000, v60
	v_mul_f32_e32 v16, v2, v16
	v_and_b32_e32 v17, 0xffff0000, v64
	v_and_b32_e32 v18, 0xffff0000, v48
	v_mul_f32_e32 v15, v2, v15
	v_rndne_f32_e32 v16, v16
	v_mul_f32_e32 v17, v2, v17
	v_mul_f32_e32 v18, v2, v18
	v_rndne_f32_e32 v15, v15
	v_cvt_i32_f32_e32 v16, v16
	v_rndne_f32_e32 v17, v17
	v_rndne_f32_e32 v18, v18
	v_cvt_i32_f32_e32 v15, v15
	v_cvt_i32_f32_sdwa v17, v17 dst_sel:WORD_1 dst_unused:UNUSED_PAD src0_sel:DWORD
	v_cvt_i32_f32_e32 v18, v18
	v_lshlrev_b32_e32 v16, 8, v16
	v_and_b32_e32 v16, 0xff00, v16
	v_and_b32_e32 v17, 0xff0000, v17
	v_perm_b32 v15, v18, v15, s89
	v_or3_b32 v15, v15, v16, v17
	global_store_dwordx2 v[6:7], v[14:15], off offset:512 nt
	v_mul_f32_e32 v15, v132, v41
	v_mul_f32_e32 v14, v132, v45
	v_rndne_f32_e32 v15, v15
	v_mul_f32_e32 v16, v132, v53
	v_mul_f32_e32 v17, v132, v37
	v_rndne_f32_e32 v14, v14
	v_cvt_i32_f32_e32 v15, v15
	v_rndne_f32_e32 v16, v16
	v_rndne_f32_e32 v17, v17
	v_cvt_i32_f32_e32 v14, v14
	v_cvt_i32_f32_sdwa v16, v16 dst_sel:WORD_1 dst_unused:UNUSED_PAD src0_sel:DWORD
	v_cvt_i32_f32_e32 v17, v17
	v_bfe_u32 v4, v49, 16, 1
	v_lshlrev_b32_e32 v15, 8, v15
	v_add3_u32 v4, v49, v4, s80
	v_and_b32_e32 v15, 0xff00, v15
	v_and_b32_e32 v16, 0xff0000, v16
	v_perm_b32 v14, v17, v14, s89
	v_and_b32_e32 v49, 0xffff0000, v4
	v_or3_b32 v14, v14, v15, v16
	v_mul_f32_e32 v16, v132, v57
	v_mul_f32_e32 v15, v132, v61
	v_rndne_f32_e32 v16, v16
	v_mul_f32_e32 v17, v132, v65
	v_mul_f32_e32 v18, v132, v49
	v_rndne_f32_e32 v15, v15
	v_cvt_i32_f32_e32 v16, v16
	v_rndne_f32_e32 v17, v17
	v_rndne_f32_e32 v18, v18
	v_cvt_i32_f32_e32 v15, v15
	v_cvt_i32_f32_sdwa v17, v17 dst_sel:WORD_1 dst_unused:UNUSED_PAD src0_sel:DWORD
	v_cvt_i32_f32_e32 v18, v18
	v_lshlrev_b32_e32 v16, 8, v16
	v_and_b32_e32 v16, 0xff00, v16
	v_and_b32_e32 v17, 0xff0000, v17
	v_perm_b32 v15, v18, v15, s89
	v_or3_b32 v15, v15, v16, v17
	global_store_dwordx2 v[10:11], v[14:15], off offset:512 nt
	v_and_b32_e32 v15, 0xffff0000, v42
	v_and_b32_e32 v14, 0xffff0000, v46
	v_mul_f32_e32 v15, v133, v15
	v_and_b32_e32 v16, 0xffff0000, v54
	v_and_b32_e32 v17, 0xffff0000, v38
	v_mul_f32_e32 v14, v133, v14
	v_rndne_f32_e32 v15, v15
	v_mul_f32_e32 v16, v133, v16
	v_mul_f32_e32 v17, v133, v17
	v_rndne_f32_e32 v14, v14
	v_cvt_i32_f32_e32 v15, v15
	v_rndne_f32_e32 v16, v16
	v_rndne_f32_e32 v17, v17
	v_cvt_i32_f32_e32 v14, v14
	v_cvt_i32_f32_sdwa v16, v16 dst_sel:WORD_1 dst_unused:UNUSED_PAD src0_sel:DWORD
	v_cvt_i32_f32_e32 v17, v17
	v_lshlrev_b32_e32 v15, 8, v15
	v_bfe_u32 v4, v50, 16, 1
	v_and_b32_e32 v15, 0xff00, v15
	v_and_b32_e32 v16, 0xff0000, v16
	v_perm_b32 v14, v17, v14, s89
	v_add3_u32 v50, v50, v4, s80
	v_or3_b32 v14, v14, v15, v16
	v_and_b32_e32 v16, 0xffff0000, v58
	v_and_b32_e32 v15, 0xffff0000, v62
	v_mul_f32_e32 v16, v133, v16
	v_and_b32_e32 v17, 0xffff0000, v66
	v_and_b32_e32 v18, 0xffff0000, v50
	v_mul_f32_e32 v15, v133, v15
	v_rndne_f32_e32 v16, v16
	v_mul_f32_e32 v17, v133, v17
	v_mul_f32_e32 v18, v133, v18
	v_rndne_f32_e32 v15, v15
	v_cvt_i32_f32_e32 v16, v16
	v_rndne_f32_e32 v17, v17
	v_rndne_f32_e32 v18, v18
	v_cvt_i32_f32_e32 v15, v15
	v_cvt_i32_f32_sdwa v17, v17 dst_sel:WORD_1 dst_unused:UNUSED_PAD src0_sel:DWORD
	v_cvt_i32_f32_e32 v18, v18
	v_lshlrev_b32_e32 v16, 8, v16
	v_and_b32_e32 v16, 0xff00, v16
	v_and_b32_e32 v17, 0xff0000, v17
	v_perm_b32 v15, v18, v15, s89
	v_or3_b32 v15, v15, v16, v17
	global_store_dwordx2 v[8:9], v[14:15], off offset:512 nt
	v_mul_f32_e32 v15, v134, v43
	v_mul_f32_e32 v14, v134, v47
	v_rndne_f32_e32 v15, v15
	v_mul_f32_e32 v16, v134, v55
	v_mul_f32_e32 v17, v134, v39
	v_rndne_f32_e32 v14, v14
	v_cvt_i32_f32_e32 v15, v15
	v_rndne_f32_e32 v16, v16
	v_rndne_f32_e32 v17, v17
	v_cvt_i32_f32_e32 v14, v14
	v_cvt_i32_f32_sdwa v16, v16 dst_sel:WORD_1 dst_unused:UNUSED_PAD src0_sel:DWORD
	v_cvt_i32_f32_e32 v17, v17
	v_bfe_u32 v4, v51, 16, 1
	v_lshlrev_b32_e32 v15, 8, v15
	v_add3_u32 v4, v51, v4, s80
	v_and_b32_e32 v15, 0xff00, v15
	v_and_b32_e32 v16, 0xff0000, v16
	v_perm_b32 v14, v17, v14, s89
	v_and_b32_e32 v51, 0xffff0000, v4
	v_or3_b32 v14, v14, v15, v16
	v_mul_f32_e32 v16, v134, v59
	v_mul_f32_e32 v15, v134, v63
	v_rndne_f32_e32 v16, v16
	v_mul_f32_e32 v17, v134, v67
	v_mul_f32_e32 v18, v134, v51
	v_rndne_f32_e32 v15, v15
	v_cvt_i32_f32_e32 v16, v16
	v_rndne_f32_e32 v17, v17
	v_rndne_f32_e32 v18, v18
	v_cvt_i32_f32_e32 v15, v15
	v_cvt_i32_f32_sdwa v17, v17 dst_sel:WORD_1 dst_unused:UNUSED_PAD src0_sel:DWORD
	v_cvt_i32_f32_e32 v18, v18
	v_lshlrev_b32_e32 v16, 8, v16
	v_bfe_u32 v141, v83, 16, 1
	v_and_b32_e32 v16, 0xff00, v16
	v_and_b32_e32 v17, 0xff0000, v17
	v_perm_b32 v15, v18, v15, s89
	v_bfe_u32 v137, v73, 16, 1
	v_bfe_u32 v165, v131, 16, 1
	v_bfe_u32 v168, v76, 16, 1
	v_add3_u32 v141, v83, v141, s80
	v_bfe_u32 v83, v68, 16, 1
	v_or3_b32 v15, v15, v16, v17
	v_add3_u32 v73, v73, v137, s80
	v_add3_u32 v165, v131, v165, s80
	v_add3_u32 v137, v76, v168, s80
	v_add3_u32 v131, v68, v83, s80
	global_store_dwordx2 v[12:13], v[14:15], off offset:512 nt
	v_and_b32_e32 v15, 0xffff0000, v136
	v_and_b32_e32 v14, 0xffff0000, v137
	v_mul_f32_e32 v15, v2, v15
	v_and_b32_e32 v16, 0xffff0000, v135
	v_and_b32_e32 v17, 0xffff0000, v131
	v_mul_f32_e32 v14, v2, v14
	v_rndne_f32_e32 v15, v15
	v_mul_f32_e32 v16, v2, v16
	v_mul_f32_e32 v17, v2, v17
	v_rndne_f32_e32 v14, v14
	v_cvt_i32_f32_e32 v15, v15
	v_rndne_f32_e32 v16, v16
	v_rndne_f32_e32 v17, v17
	v_cvt_i32_f32_e32 v14, v14
	v_cvt_i32_f32_sdwa v16, v16 dst_sel:WORD_1 dst_unused:UNUSED_PAD src0_sel:DWORD
	v_cvt_i32_f32_e32 v17, v17
	v_bfe_u32 v145, v95, 16, 1
	v_bfe_u32 v143, v71, 16, 1
	v_bfe_u32 v161, v127, 16, 1
	v_add3_u32 v145, v95, v145, s80
	v_bfe_u32 v95, v88, 16, 1
	v_lshlrev_b32_e32 v15, 8, v15
	v_bfe_u32 v164, v129, 16, 1
	v_add3_u32 v71, v71, v143, s80
	v_bfe_u32 v143, v92, 16, 1
	v_add3_u32 v161, v127, v161, s80
	v_add3_u32 v127, v88, v95, s80
	v_and_b32_e32 v15, 0xff00, v15
	v_and_b32_e32 v16, 0xff0000, v16
	v_perm_b32 v14, v17, v14, s89
	v_add3_u32 v164, v129, v164, s80
	v_add3_u32 v129, v92, v143, s80
	v_or3_b32 v14, v14, v15, v16
	v_and_b32_e32 v16, 0xffff0000, v127
	v_and_b32_e32 v15, 0xffff0000, v129
	v_mul_f32_e32 v16, v2, v16
	v_and_b32_e32 v17, 0xffff0000, v125
	v_and_b32_e32 v18, 0xffff0000, v123
	v_mul_f32_e32 v15, v2, v15
	v_rndne_f32_e32 v16, v16
	v_mul_f32_e32 v17, v2, v17
	v_mul_f32_e32 v18, v2, v18
	v_rndne_f32_e32 v15, v15
	v_cvt_i32_f32_e32 v16, v16
	v_rndne_f32_e32 v17, v17
	v_rndne_f32_e32 v18, v18
	v_cvt_i32_f32_e32 v15, v15
	v_cvt_i32_f32_sdwa v17, v17 dst_sel:WORD_1 dst_unused:UNUSED_PAD src0_sel:DWORD
	v_cvt_i32_f32_e32 v18, v18
	v_lshlrev_b32_e32 v16, 8, v16
	v_bfe_u32 v140, v81, 16, 1
	v_bfe_u32 v142, v69, 16, 1
	v_bfe_u32 v144, v93, 16, 1
	v_bfe_u32 v159, v103, 16, 1
	v_bfe_u32 v178, v122, 16, 1
	v_and_b32_e32 v16, 0xff00, v16
	v_and_b32_e32 v17, 0xff0000, v17
	v_perm_b32 v15, v18, v15, s89
	v_bfe_u32 v156, v113, 16, 1
	v_add3_u32 v140, v81, v140, s80
	v_add3_u32 v69, v69, v142, s80
	v_add3_u32 v93, v93, v144, s80
	v_bfe_u32 v144, v94, 16, 1
	v_add3_u32 v159, v103, v159, s80
	v_bfe_u32 v103, v124, 16, 1
	v_bfe_u32 v177, v120, 16, 1
	v_bfe_u32 v182, v118, 16, 1
	v_add3_u32 v78, v122, v178, s80
	v_and_b32_e32 v122, 0xffff0000, v73
	v_or3_b32 v15, v15, v16, v17
	v_add3_u32 v156, v113, v156, s80
	v_add3_u32 v113, v94, v144, s80
	v_add3_u32 v95, v124, v103, s80
	v_add3_u32 v94, v120, v177, s80
	v_add3_u32 v72, v118, v182, s80
	v_and_b32_e32 v124, 0xffff0000, v77
	v_and_b32_e32 v120, 0xffff0000, v140
	v_and_b32_e32 v118, 0xffff0000, v69
	global_store_dwordx2 v[6:7], v[14:15], off offset:1024 nt
	v_mul_f32_e32 v15, v132, v122
	v_mul_f32_e32 v14, v132, v124
	v_rndne_f32_e32 v15, v15
	v_mul_f32_e32 v16, v132, v120
	v_mul_f32_e32 v17, v132, v118
	v_rndne_f32_e32 v14, v14
	v_cvt_i32_f32_e32 v15, v15
	v_rndne_f32_e32 v16, v16
	v_rndne_f32_e32 v17, v17
	v_cvt_i32_f32_e32 v14, v14
	v_cvt_i32_f32_sdwa v16, v16 dst_sel:WORD_1 dst_unused:UNUSED_PAD src0_sel:DWORD
	v_cvt_i32_f32_e32 v17, v17
	v_bfe_u32 v146, v89, 16, 1
	v_bfe_u32 v148, v97, 16, 1
	v_bfe_u32 v150, v85, 16, 1
	v_bfe_u32 v152, v109, 16, 1
	v_bfe_u32 v166, v117, 16, 1
	v_bfe_u32 v81, v82, 16, 1
	v_add3_u32 v89, v89, v146, s80
	v_bfe_u32 v174, v114, 16, 1
	v_lshlrev_b32_e32 v15, 8, v15
	v_bfe_u32 v155, v107, 16, 1
	v_add3_u32 v148, v97, v148, s80
	v_bfe_u32 v97, v98, 16, 1
	v_add3_u32 v85, v85, v150, s80
	v_add3_u32 v152, v109, v152, s80
	v_bfe_u32 v109, v110, 16, 1
	v_bfe_u32 v173, v112, 16, 1
	v_bfe_u32 v181, v116, 16, 1
	v_add3_u32 v166, v117, v166, s80
	v_add3_u32 v117, v82, v81, s80
	v_add3_u32 v81, v114, v174, s80
	v_and_b32_e32 v114, 0xffff0000, v89
	v_and_b32_e32 v15, 0xff00, v15
	v_and_b32_e32 v16, 0xff0000, v16
	v_perm_b32 v14, v17, v14, s89
	v_add3_u32 v155, v107, v155, s80
	v_add3_u32 v107, v98, v97, s80
	v_add3_u32 v83, v110, v109, s80
	v_add3_u32 v97, v112, v173, s80
	v_add3_u32 v88, v116, v181, s80
	v_and_b32_e32 v116, 0xffff0000, v93
	v_and_b32_e32 v112, 0xffff0000, v148
	v_and_b32_e32 v110, 0xffff0000, v85
	v_or3_b32 v14, v14, v15, v16
	v_mul_f32_e32 v16, v132, v114
	v_mul_f32_e32 v15, v132, v116
	v_rndne_f32_e32 v16, v16
	v_mul_f32_e32 v17, v132, v112
	v_mul_f32_e32 v18, v132, v110
	v_rndne_f32_e32 v15, v15
	v_cvt_i32_f32_e32 v16, v16
	v_rndne_f32_e32 v17, v17
	v_rndne_f32_e32 v18, v18
	v_cvt_i32_f32_e32 v15, v15
	v_cvt_i32_f32_sdwa v17, v17 dst_sel:WORD_1 dst_unused:UNUSED_PAD src0_sel:DWORD
	v_cvt_i32_f32_e32 v18, v18
	v_lshlrev_b32_e32 v16, 8, v16
	v_bfe_u32 v167, v119, 16, 1
	v_bfe_u32 v170, v74, 16, 1
	v_and_b32_e32 v16, 0xff00, v16
	v_and_b32_e32 v17, 0xff0000, v17
	v_perm_b32 v15, v18, v15, s89
	v_bfe_u32 v157, v115, 16, 1
	v_bfe_u32 v142, v70, 16, 1
	v_add3_u32 v167, v119, v167, s80
	v_add3_u32 v119, v74, v170, s80
	v_or3_b32 v15, v15, v16, v17
	v_add3_u32 v157, v115, v157, s80
	v_add3_u32 v115, v70, v142, s80
	global_store_dwordx2 v[10:11], v[14:15], off offset:1024 nt
	v_and_b32_e32 v15, 0xffff0000, v119
	v_and_b32_e32 v14, 0xffff0000, v121
	v_mul_f32_e32 v15, v133, v15
	v_and_b32_e32 v16, 0xffff0000, v117
	v_and_b32_e32 v17, 0xffff0000, v115
	v_mul_f32_e32 v14, v133, v14
	v_rndne_f32_e32 v15, v15
	v_mul_f32_e32 v16, v133, v16
	v_mul_f32_e32 v17, v133, v17
	v_rndne_f32_e32 v14, v14
	v_cvt_i32_f32_e32 v15, v15
	v_rndne_f32_e32 v16, v16
	v_rndne_f32_e32 v17, v17
	v_cvt_i32_f32_e32 v14, v14
	v_cvt_i32_f32_sdwa v16, v16 dst_sel:WORD_1 dst_unused:UNUSED_PAD src0_sel:DWORD
	v_cvt_i32_f32_e32 v17, v17
	v_bfe_u32 v153, v111, 16, 1
	v_bfe_u32 v146, v90, 16, 1
	v_lshlrev_b32_e32 v15, 8, v15
	v_bfe_u32 v154, v105, 16, 1
	v_bfe_u32 v150, v86, 16, 1
	v_add3_u32 v153, v111, v153, s80
	v_add3_u32 v111, v90, v146, s80
	v_and_b32_e32 v15, 0xff00, v15
	v_and_b32_e32 v16, 0xff0000, v16
	v_perm_b32 v14, v17, v14, s89
	v_add3_u32 v154, v105, v154, s80
	v_add3_u32 v105, v86, v150, s80
	v_or3_b32 v14, v14, v15, v16
	v_and_b32_e32 v16, 0xffff0000, v111
	v_and_b32_e32 v15, 0xffff0000, v113
	v_mul_f32_e32 v16, v133, v16
	v_and_b32_e32 v17, 0xffff0000, v107
	v_and_b32_e32 v18, 0xffff0000, v105
	v_mul_f32_e32 v15, v133, v15
	v_rndne_f32_e32 v16, v16
	v_mul_f32_e32 v17, v133, v17
	v_mul_f32_e32 v18, v133, v18
	v_rndne_f32_e32 v15, v15
	v_cvt_i32_f32_e32 v16, v16
	v_rndne_f32_e32 v17, v17
	v_rndne_f32_e32 v18, v18
	v_cvt_i32_f32_e32 v15, v15
	v_cvt_i32_f32_sdwa v17, v17 dst_sel:WORD_1 dst_unused:UNUSED_PAD src0_sel:DWORD
	v_cvt_i32_f32_e32 v18, v18
	v_lshlrev_b32_e32 v16, 8, v16
	v_and_b32_e32 v16, 0xff00, v16
	v_and_b32_e32 v17, 0xff0000, v17
	v_perm_b32 v15, v18, v15, s89
	v_bfe_u32 v171, v104, 16, 1
	v_bfe_u32 v172, v106, 16, 1
	v_or3_b32 v15, v15, v16, v17
	v_add3_u32 v98, v104, v171, s80
	v_add3_u32 v82, v106, v172, s80
	v_and_b32_e32 v109, 0xffff0000, v169
	v_and_b32_e32 v106, 0xffff0000, v141
	v_and_b32_e32 v104, 0xffff0000, v71
	global_store_dwordx2 v[8:9], v[14:15], off offset:1024 nt
	v_mul_f32_e32 v15, v134, v108
	v_mul_f32_e32 v14, v134, v109
	v_rndne_f32_e32 v15, v15
	v_mul_f32_e32 v16, v134, v106
	v_mul_f32_e32 v17, v134, v104
	v_rndne_f32_e32 v14, v14
	v_cvt_i32_f32_e32 v15, v15
	v_rndne_f32_e32 v16, v16
	v_rndne_f32_e32 v17, v17
	v_cvt_i32_f32_e32 v14, v14
	v_cvt_i32_f32_sdwa v16, v16 dst_sel:WORD_1 dst_unused:UNUSED_PAD src0_sel:DWORD
	v_cvt_i32_f32_e32 v17, v17
	v_bfe_u32 v158, v101, 16, 1
	v_add3_u32 v158, v101, v158, s80
	v_bfe_u32 v101, v102, 16, 1
	v_lshlrev_b32_e32 v15, 8, v15
	v_bfe_u32 v175, v100, 16, 1
	v_add3_u32 v80, v102, v101, s80
	v_and_b32_e32 v102, 0xffff0000, v147
	v_and_b32_e32 v15, 0xff00, v15
	v_and_b32_e32 v16, 0xff0000, v16
	v_perm_b32 v14, v17, v14, s89
	v_add3_u32 v96, v100, v175, s80
	v_and_b32_e32 v103, 0xffff0000, v145
	v_and_b32_e32 v101, 0xffff0000, v149
	v_and_b32_e32 v100, 0xffff0000, v87
	v_or3_b32 v14, v14, v15, v16
	v_mul_f32_e32 v16, v134, v102
	v_mul_f32_e32 v15, v134, v103
	v_rndne_f32_e32 v16, v16
	v_mul_f32_e32 v17, v134, v101
	v_mul_f32_e32 v18, v134, v100
	v_rndne_f32_e32 v15, v15
	v_cvt_i32_f32_e32 v16, v16
	v_rndne_f32_e32 v17, v17
	v_rndne_f32_e32 v18, v18
	v_cvt_i32_f32_e32 v15, v15
	v_cvt_i32_f32_sdwa v17, v17 dst_sel:WORD_1 dst_unused:UNUSED_PAD src0_sel:DWORD
	v_cvt_i32_f32_e32 v18, v18
	v_lshlrev_b32_e32 v16, 8, v16
	v_and_b32_e32 v16, 0xff00, v16
	v_and_b32_e32 v17, 0xff0000, v17
	v_perm_b32 v15, v18, v15, s89
	v_or3_b32 v15, v15, v16, v17
	global_store_dwordx2 v[12:13], v[14:15], off offset:1024 nt
	v_and_b32_e32 v15, 0xffff0000, v98
	v_and_b32_e32 v14, 0xffff0000, v99
	v_mul_f32_e32 v15, v2, v15
	v_and_b32_e32 v16, 0xffff0000, v97
	v_and_b32_e32 v17, 0xffff0000, v96
	v_mul_f32_e32 v14, v2, v14
	v_rndne_f32_e32 v15, v15
	v_mul_f32_e32 v16, v2, v16
	v_mul_f32_e32 v17, v2, v17
	v_rndne_f32_e32 v14, v14
	v_cvt_i32_f32_e32 v15, v15
	v_rndne_f32_e32 v16, v16
	v_rndne_f32_e32 v17, v17
	v_cvt_i32_f32_e32 v14, v14
	v_cvt_i32_f32_sdwa v16, v16 dst_sel:WORD_1 dst_unused:UNUSED_PAD src0_sel:DWORD
	v_cvt_i32_f32_e32 v17, v17
	v_lshlrev_b32_e32 v15, 8, v15
	v_and_b32_e32 v15, 0xff00, v15
	v_and_b32_e32 v16, 0xff0000, v16
	v_perm_b32 v14, v17, v14, s89
	v_or3_b32 v14, v14, v15, v16
	v_and_b32_e32 v16, 0xffff0000, v94
	v_and_b32_e32 v15, 0xffff0000, v95
	v_mul_f32_e32 v16, v2, v16
	v_and_b32_e32 v17, 0xffff0000, v91
	v_and_b32_e32 v18, 0xffff0000, v88
	v_mul_f32_e32 v15, v2, v15
	v_rndne_f32_e32 v16, v16
	v_mul_f32_e32 v17, v2, v17
	v_mul_f32_e32 v18, v2, v18
	v_rndne_f32_e32 v15, v15
	v_cvt_i32_f32_e32 v16, v16
	v_rndne_f32_e32 v17, v17
	v_rndne_f32_e32 v18, v18
	v_cvt_i32_f32_e32 v15, v15
	v_cvt_i32_f32_sdwa v17, v17 dst_sel:WORD_1 dst_unused:UNUSED_PAD src0_sel:DWORD
	v_cvt_i32_f32_e32 v18, v18
	v_lshlrev_b32_e32 v16, 8, v16
	v_and_b32_e32 v16, 0xff00, v16
	v_and_b32_e32 v17, 0xff0000, v17
	v_perm_b32 v15, v18, v15, s89
	v_and_b32_e32 v92, 0xffff0000, v154
	v_or3_b32 v15, v15, v16, v17
	v_and_b32_e32 v93, 0xffff0000, v152
	v_and_b32_e32 v90, 0xffff0000, v156
	v_and_b32_e32 v89, 0xffff0000, v158
	global_store_dwordx2 v[6:7], v[14:15], off offset:1536 nt
	v_mul_f32_e32 v7, v132, v92
	v_mul_f32_e32 v6, v132, v93
	v_rndne_f32_e32 v7, v7
	v_mul_f32_e32 v14, v132, v90
	v_mul_f32_e32 v15, v132, v89
	v_rndne_f32_e32 v6, v6
	v_cvt_i32_f32_e32 v7, v7
	v_rndne_f32_e32 v14, v14
	v_rndne_f32_e32 v15, v15
	v_cvt_i32_f32_e32 v6, v6
	v_cvt_i32_f32_sdwa v14, v14 dst_sel:WORD_1 dst_unused:UNUSED_PAD src0_sel:DWORD
	v_cvt_i32_f32_e32 v15, v15
	v_lshlrev_b32_e32 v7, 8, v7
	v_and_b32_e32 v86, 0xffff0000, v162
	v_and_b32_e32 v7, 0xff00, v7
	v_and_b32_e32 v14, 0xff0000, v14
	v_perm_b32 v6, v15, v6, s89
	v_and_b32_e32 v87, 0xffff0000, v160
	v_and_b32_e32 v85, 0xffff0000, v164
	v_and_b32_e32 v84, 0xffff0000, v166
	v_or3_b32 v6, v6, v7, v14
	v_mul_f32_e32 v14, v132, v86
	v_mul_f32_e32 v7, v132, v87
	v_rndne_f32_e32 v14, v14
	v_mul_f32_e32 v15, v132, v85
	v_mul_f32_e32 v16, v132, v84
	v_rndne_f32_e32 v7, v7
	v_cvt_i32_f32_e32 v14, v14
	v_rndne_f32_e32 v15, v15
	v_rndne_f32_e32 v16, v16
	v_cvt_i32_f32_e32 v7, v7
	v_cvt_i32_f32_sdwa v15, v15 dst_sel:WORD_1 dst_unused:UNUSED_PAD src0_sel:DWORD
	v_cvt_i32_f32_e32 v16, v16
	v_lshlrev_b32_e32 v14, 8, v14
	v_and_b32_e32 v14, 0xff00, v14
	v_and_b32_e32 v15, 0xff0000, v15
	v_perm_b32 v7, v16, v7, s89
	v_or3_b32 v7, v7, v14, v15
	global_store_dwordx2 v[10:11], v[6:7], off offset:1536 nt
	v_and_b32_e32 v7, 0xffff0000, v82
	v_and_b32_e32 v6, 0xffff0000, v83
	v_mul_f32_e32 v7, v133, v7
	v_and_b32_e32 v10, 0xffff0000, v81
	v_and_b32_e32 v11, 0xffff0000, v80
	v_mul_f32_e32 v6, v133, v6
	v_rndne_f32_e32 v7, v7
	v_mul_f32_e32 v10, v133, v10
	v_mul_f32_e32 v11, v133, v11
	v_rndne_f32_e32 v6, v6
	v_cvt_i32_f32_e32 v7, v7
	v_rndne_f32_e32 v10, v10
	v_rndne_f32_e32 v11, v11
	v_cvt_i32_f32_e32 v6, v6
	v_cvt_i32_f32_sdwa v10, v10 dst_sel:WORD_1 dst_unused:UNUSED_PAD src0_sel:DWORD
	v_cvt_i32_f32_e32 v11, v11
	v_lshlrev_b32_e32 v7, 8, v7
	v_and_b32_e32 v7, 0xff00, v7
	v_and_b32_e32 v10, 0xff0000, v10
	v_perm_b32 v6, v11, v6, s89
	v_or3_b32 v6, v6, v7, v10
	v_and_b32_e32 v10, 0xffff0000, v78
	v_and_b32_e32 v7, 0xffff0000, v79
	v_mul_f32_e32 v10, v133, v10
	v_and_b32_e32 v11, 0xffff0000, v75
	v_and_b32_e32 v14, 0xffff0000, v72
	v_mul_f32_e32 v7, v133, v7
	v_rndne_f32_e32 v10, v10
	v_mul_f32_e32 v11, v133, v11
	v_mul_f32_e32 v14, v133, v14
	v_rndne_f32_e32 v7, v7
	v_cvt_i32_f32_e32 v10, v10
	v_rndne_f32_e32 v11, v11
	v_rndne_f32_e32 v14, v14
	v_cvt_i32_f32_e32 v7, v7
	v_cvt_i32_f32_sdwa v11, v11 dst_sel:WORD_1 dst_unused:UNUSED_PAD src0_sel:DWORD
	v_cvt_i32_f32_e32 v14, v14
	v_lshlrev_b32_e32 v10, 8, v10
	v_and_b32_e32 v10, 0xff00, v10
	v_and_b32_e32 v11, 0xff0000, v11
	v_perm_b32 v7, v14, v7, s89
	v_and_b32_e32 v76, 0xffff0000, v155
	v_or3_b32 v7, v7, v10, v11
	v_and_b32_e32 v77, 0xffff0000, v153
	v_and_b32_e32 v74, 0xffff0000, v157
	v_and_b32_e32 v73, 0xffff0000, v159
	global_store_dwordx2 v[8:9], v[6:7], off offset:1536 nt
	v_mul_f32_e32 v7, v134, v76
	v_mul_f32_e32 v6, v134, v77
	v_rndne_f32_e32 v7, v7
	v_mul_f32_e32 v8, v134, v74
	v_mul_f32_e32 v9, v134, v73
	v_rndne_f32_e32 v6, v6
	v_cvt_i32_f32_e32 v7, v7
	v_rndne_f32_e32 v8, v8
	v_rndne_f32_e32 v9, v9
	v_cvt_i32_f32_e32 v6, v6
	v_cvt_i32_f32_sdwa v8, v8 dst_sel:WORD_1 dst_unused:UNUSED_PAD src0_sel:DWORD
	v_cvt_i32_f32_e32 v9, v9
	v_lshlrev_b32_e32 v7, 8, v7
	v_and_b32_e32 v70, 0xffff0000, v163
	v_and_b32_e32 v7, 0xff00, v7
	v_and_b32_e32 v8, 0xff0000, v8
	v_perm_b32 v6, v9, v6, s89
	v_and_b32_e32 v71, 0xffff0000, v161
	v_and_b32_e32 v69, 0xffff0000, v165
	v_and_b32_e32 v68, 0xffff0000, v167
	v_or3_b32 v6, v6, v7, v8
	v_mul_f32_e32 v8, v134, v70
	v_mul_f32_e32 v7, v134, v71
	v_rndne_f32_e32 v8, v8
	v_mul_f32_e32 v9, v134, v69
	v_mul_f32_e32 v10, v134, v68
	v_rndne_f32_e32 v7, v7
	v_cvt_i32_f32_e32 v8, v8
	v_rndne_f32_e32 v9, v9
	v_rndne_f32_e32 v10, v10
	v_cvt_i32_f32_e32 v7, v7
	v_cvt_i32_f32_sdwa v9, v9 dst_sel:WORD_1 dst_unused:UNUSED_PAD src0_sel:DWORD
	v_cvt_i32_f32_e32 v10, v10
	v_lshlrev_b32_e32 v8, 8, v8
	v_ashrrev_i32_e32 v209, 31, v208
	v_and_b32_e32 v8, 0xff00, v8
	v_and_b32_e32 v9, 0xff0000, v9
	v_perm_b32 v7, v10, v7, s89
	v_lshlrev_b64 v[4:5], 12, v[208:209]
	v_or3_b32 v7, v7, v8, v9
	v_lshl_add_u64 v[4:5], v[204:205], 0, v[4:5]
	global_store_dwordx2 v[12:13], v[6:7], off offset:1536 nt
	s_mov_b64 s[16:17], 0
	v_mov_b32_e32 v6, v235

.LBB0_3138:
	v_ashrrev_i32_e32 v133, 31, v132
	s_waitcnt vmcnt(1)
	v_bfe_u32 v2, v108, 16, 1
	v_lshlrev_b64 v[132:133], 13, v[132:133]
	v_add3_u32 v2, v108, v2, s80
	s_waitcnt vmcnt(0)
	v_bfe_u32 v108, v104, 16, 1
	v_lshl_add_u64 v[132:133], s[8:9], 0, v[132:133]
	v_lshrrev_b32_e32 v2, 16, v2
	v_add3_u32 v104, v104, v108, s80
	v_lshl_add_u64 v[136:137], v[134:135], 1, v[132:133]
	v_and_or_b32 v132, v104, s85, v2
	v_bfe_u32 v2, v112, 16, 1
	v_add3_u32 v2, v112, v2, s80
	v_bfe_u32 v104, v100, 16, 1
	v_lshrrev_b32_e32 v2, 16, v2
	v_add3_u32 v100, v100, v104, s80
	v_and_or_b32 v133, v100, s85, v2
	v_bfe_u32 v2, v124, 16, 1
	v_add3_u32 v2, v124, v2, s80
	v_bfe_u32 v100, v120, 16, 1
	v_lshrrev_b32_e32 v2, 16, v2
	v_add3_u32 v100, v120, v100, s80
	v_and_or_b32 v134, v100, s85, v2
	v_bfe_u32 v2, v128, 16, 1
	v_add3_u32 v2, v128, v2, s80
	v_bfe_u32 v100, v116, 16, 1
	v_lshrrev_b32_e32 v2, 16, v2
	v_add3_u32 v100, v116, v100, s80
	v_and_or_b32 v135, v100, s85, v2
	v_bfe_u32 v2, v109, 16, 1
	v_add3_u32 v2, v109, v2, s80
	v_bfe_u32 v100, v105, 16, 1
	v_lshrrev_b32_e32 v2, 16, v2
	v_add3_u32 v100, v105, v100, s80
	global_store_dwordx4 v[136:137], v[132:135], off nt
	s_nop 1
	v_and_or_b32 v132, v100, s85, v2
	v_bfe_u32 v2, v113, 16, 1
	v_add3_u32 v2, v113, v2, s80
	v_bfe_u32 v100, v101, 16, 1
	v_lshrrev_b32_e32 v2, 16, v2
	v_add3_u32 v100, v101, v100, s80
	v_and_or_b32 v133, v100, s85, v2
	v_bfe_u32 v2, v125, 16, 1
	v_add3_u32 v2, v125, v2, s80
	v_bfe_u32 v100, v121, 16, 1
	v_lshrrev_b32_e32 v2, 16, v2
	v_add3_u32 v100, v121, v100, s80
	v_and_or_b32 v134, v100, s85, v2
	v_bfe_u32 v2, v129, 16, 1
	v_add3_u32 v2, v129, v2, s80
	v_bfe_u32 v100, v117, 16, 1
	v_lshrrev_b32_e32 v2, 16, v2
	v_add3_u32 v100, v117, v100, s80
	v_and_or_b32 v135, v100, s85, v2
	v_add_co_u32_e32 v100, vcc, s84, v136
	v_bfe_u32 v2, v110, 16, 1
	s_nop 0
	v_addc_co_u32_e32 v101, vcc, 0, v137, vcc
	global_store_dwordx4 v[100:101], v[132:135], off nt
	v_add3_u32 v2, v110, v2, s80
	v_bfe_u32 v100, v106, 16, 1
	v_lshrrev_b32_e32 v2, 16, v2
	v_add3_u32 v100, v106, v100, s80
	v_and_or_b32 v132, v100, s85, v2
	v_bfe_u32 v2, v114, 16, 1
	v_add3_u32 v2, v114, v2, s80
	v_bfe_u32 v100, v102, 16, 1
	v_lshrrev_b32_e32 v2, 16, v2
	v_add3_u32 v100, v102, v100, s80
	v_and_or_b32 v133, v100, s85, v2
	v_bfe_u32 v2, v126, 16, 1
	v_add3_u32 v2, v126, v2, s80
	v_bfe_u32 v100, v122, 16, 1
	v_lshrrev_b32_e32 v2, 16, v2
	v_add3_u32 v100, v122, v100, s80
	v_and_or_b32 v134, v100, s85, v2
	v_bfe_u32 v2, v130, 16, 1
	v_add3_u32 v2, v130, v2, s80
	v_bfe_u32 v100, v118, 16, 1
	v_lshrrev_b32_e32 v2, 16, v2
	v_add3_u32 v100, v118, v100, s80
	v_and_or_b32 v135, v100, s85, v2
	v_add_co_u32_e32 v100, vcc, s81, v136
	v_bfe_u32 v2, v111, 16, 1
	s_nop 0
	v_addc_co_u32_e32 v101, vcc, 0, v137, vcc
	global_store_dwordx4 v[100:101], v[132:135], off nt
	v_add3_u32 v2, v111, v2, s80
	v_bfe_u32 v100, v107, 16, 1
	v_lshrrev_b32_e32 v2, 16, v2
	v_add3_u32 v100, v107, v100, s80
	v_and_or_b32 v100, v100, s85, v2
	v_bfe_u32 v2, v115, 16, 1
	v_add3_u32 v2, v115, v2, s80
	v_bfe_u32 v101, v103, 16, 1
	v_lshrrev_b32_e32 v2, 16, v2
	v_add3_u32 v101, v103, v101, s80
	v_and_or_b32 v101, v101, s85, v2
	v_bfe_u32 v2, v127, 16, 1
	v_add3_u32 v2, v127, v2, s80
	v_bfe_u32 v102, v123, 16, 1
	v_lshrrev_b32_e32 v2, 16, v2
	v_add3_u32 v102, v123, v102, s80
	v_and_or_b32 v102, v102, s85, v2
	v_bfe_u32 v2, v131, 16, 1
	v_add3_u32 v2, v131, v2, s80
	v_bfe_u32 v103, v119, 16, 1
	v_add_co_u32_e32 v104, vcc, 0x6000, v136
	v_lshrrev_b32_e32 v2, 16, v2
	v_add3_u32 v103, v119, v103, s80
	v_addc_co_u32_e32 v105, vcc, 0, v137, vcc
	v_and_or_b32 v103, v103, s85, v2
	s_andn2_b64 vcc, exec, s[12:13]
	global_store_dwordx4 v[104:105], v[100:103], off nt
	s_cbranch_vccnz .LBB0_3141
	s_lshr_b32 s4, s14, 31
	s_ashr_i32 s5, s14, 4
	s_add_i32 s4, s5, s4
	v_lshl_or_b32 v100, s4, 6, v231
	s_mulk_i32 s4, 0xf400
	s_add_i32 s4, s4, s0
	v_add_u32_e32 v102, s4, v142
	v_ashrrev_i32_e32 v103, 31, v102
	v_lshlrev_b64 v[102:103], 13, v[102:103]
	v_ashrrev_i32_e32 v101, 31, v100
	v_lshl_add_u64 v[102:103], s[8:9], 0, v[102:103]
	v_bfe_u32 v2, v40, 16, 1
	v_lshl_add_u64 v[104:105], v[100:101], 1, v[102:103]
	v_add3_u32 v2, v40, v2, s80
	v_bfe_u32 v100, v36, 16, 1
	v_lshrrev_b32_e32 v2, 16, v2
	v_add3_u32 v100, v36, v100, s80
	v_and_or_b32 v100, v100, s85, v2
	v_bfe_u32 v2, v60, 16, 1
	v_add3_u32 v2, v60, v2, s80
	v_bfe_u32 v101, v28, 16, 1
	v_lshrrev_b32_e32 v2, 16, v2
	v_add3_u32 v101, v28, v101, s80
	v_and_or_b32 v101, v101, s85, v2
	v_bfe_u32 v2, v88, 16, 1
	v_add3_u32 v2, v88, v2, s80
	v_bfe_u32 v102, v84, 16, 1
	v_lshrrev_b32_e32 v2, 16, v2
	v_add3_u32 v102, v84, v102, s80
	v_and_or_b32 v102, v102, s85, v2
	v_bfe_u32 v2, v80, 16, 1
	v_add3_u32 v2, v80, v2, s80
	v_bfe_u32 v103, v96, 16, 1
	v_lshrrev_b32_e32 v2, 16, v2
	v_add3_u32 v103, v96, v103, s80
	v_and_or_b32 v103, v103, s85, v2
	v_bfe_u32 v2, v41, 16, 1
	global_store_dwordx4 v[104:105], v[100:103], off nt
	v_add3_u32 v2, v41, v2, s80
	v_lshrrev_b32_e32 v2, 16, v2
	v_bfe_u32 v100, v37, 16, 1
	v_add3_u32 v100, v37, v100, s80
	v_and_or_b32 v100, v100, s85, v2
	v_bfe_u32 v2, v61, 16, 1
	v_add3_u32 v2, v61, v2, s80
	v_bfe_u32 v101, v29, 16, 1
	v_lshrrev_b32_e32 v2, 16, v2
	v_add3_u32 v101, v29, v101, s80
	v_and_or_b32 v101, v101, s85, v2
	v_bfe_u32 v2, v89, 16, 1
	v_add3_u32 v2, v89, v2, s80
	v_bfe_u32 v102, v85, 16, 1
	v_lshrrev_b32_e32 v2, 16, v2
	v_add3_u32 v102, v85, v102, s80
	v_and_or_b32 v102, v102, s85, v2
	v_bfe_u32 v2, v81, 16, 1
	v_add3_u32 v2, v81, v2, s80
	v_bfe_u32 v103, v97, 16, 1
	v_lshrrev_b32_e32 v2, 16, v2
	v_add3_u32 v103, v97, v103, s80
	v_add_co_u32_e32 v106, vcc, s84, v104
	v_and_or_b32 v103, v103, s85, v2
	s_nop 0
	v_addc_co_u32_e32 v107, vcc, 0, v105, vcc
	v_bfe_u32 v2, v42, 16, 1
	global_store_dwordx4 v[106:107], v[100:103], off nt
	v_add3_u32 v2, v42, v2, s80
	v_lshrrev_b32_e32 v2, 16, v2
	v_bfe_u32 v100, v38, 16, 1
	v_add3_u32 v100, v38, v100, s80
	v_and_or_b32 v100, v100, s85, v2
	v_bfe_u32 v2, v62, 16, 1
	v_add3_u32 v2, v62, v2, s80
	v_bfe_u32 v101, v30, 16, 1
	v_lshrrev_b32_e32 v2, 16, v2
	v_add3_u32 v101, v30, v101, s80
	v_and_or_b32 v101, v101, s85, v2
	v_bfe_u32 v2, v90, 16, 1
	v_add3_u32 v2, v90, v2, s80
	v_bfe_u32 v102, v86, 16, 1
	v_lshrrev_b32_e32 v2, 16, v2
	v_add3_u32 v102, v86, v102, s80
	v_and_or_b32 v102, v102, s85, v2
	v_bfe_u32 v2, v82, 16, 1
	v_add3_u32 v2, v82, v2, s80
	v_bfe_u32 v103, v98, 16, 1
	v_lshrrev_b32_e32 v2, 16, v2
	v_add3_u32 v103, v98, v103, s80
	v_add_co_u32_e32 v106, vcc, s81, v104
	v_and_or_b32 v103, v103, s85, v2
	s_nop 0
	v_addc_co_u32_e32 v107, vcc, 0, v105, vcc
	v_bfe_u32 v2, v43, 16, 1
	global_store_dwordx4 v[106:107], v[100:103], off nt
	v_add3_u32 v2, v43, v2, s80
	v_lshrrev_b32_e32 v2, 16, v2
	v_bfe_u32 v100, v39, 16, 1
	v_add3_u32 v100, v39, v100, s80
	v_and_or_b32 v100, v100, s85, v2
	v_bfe_u32 v2, v63, 16, 1
	v_add3_u32 v2, v63, v2, s80
	v_bfe_u32 v101, v31, 16, 1
	v_lshrrev_b32_e32 v2, 16, v2
	v_add3_u32 v101, v31, v101, s80
	v_and_or_b32 v101, v101, s85, v2
	v_bfe_u32 v2, v91, 16, 1
	v_add3_u32 v2, v91, v2, s80
	v_bfe_u32 v102, v87, 16, 1
	v_lshrrev_b32_e32 v2, 16, v2
	v_add3_u32 v102, v87, v102, s80
	v_and_or_b32 v102, v102, s85, v2
	v_bfe_u32 v2, v83, 16, 1
	v_add3_u32 v2, v83, v2, s80
	v_bfe_u32 v103, v99, 16, 1
	v_lshrrev_b32_e32 v2, 16, v2
	v_add3_u32 v103, v99, v103, s80
	v_add_co_u32_e32 v104, vcc, 0x6000, v104
	v_and_or_b32 v103, v103, s85, v2
	s_nop 0
	v_addc_co_u32_e32 v105, vcc, 0, v105, vcc
	global_store_dwordx4 v[104:105], v[100:103], off nt
	s_andn2_b64 vcc, exec, s[16:17]
	s_cbranch_vccz .LBB0_3142

.LBB0_3142:
	s_lshr_b32 s4, s15, 31
	s_ashr_i32 s5, s15, 4
	s_add_i32 s4, s5, s4
	v_lshl_or_b32 v100, s4, 6, v231
	s_mulk_i32 s4, 0xf400
	s_add_i32 s4, s4, s0
	v_add_u32_e32 v102, s4, v140
	v_ashrrev_i32_e32 v103, 31, v102
	v_lshlrev_b64 v[102:103], 13, v[102:103]
	v_ashrrev_i32_e32 v101, 31, v100
	v_lshl_add_u64 v[102:103], s[8:9], 0, v[102:103]
	v_bfe_u32 v2, v24, 16, 1
	v_lshl_add_u64 v[104:105], v[100:101], 1, v[102:103]
	v_add3_u32 v2, v24, v2, s80
	v_bfe_u32 v100, v20, 16, 1
	v_lshrrev_b32_e32 v2, 16, v2
	v_add3_u32 v100, v20, v100, s80
	v_and_or_b32 v100, v100, s85, v2
	v_bfe_u32 v2, v44, 16, 1
	v_add3_u32 v2, v44, v2, s80
	v_bfe_u32 v101, v16, 16, 1
	v_lshrrev_b32_e32 v2, 16, v2
	v_add3_u32 v101, v16, v101, s80
	v_and_or_b32 v101, v101, s85, v2
	v_bfe_u32 v2, v72, 16, 1
	v_add3_u32 v2, v72, v2, s80
	v_bfe_u32 v102, v68, 16, 1
	v_lshrrev_b32_e32 v2, 16, v2
	v_add3_u32 v102, v68, v102, s80
	v_and_or_b32 v102, v102, s85, v2
	v_bfe_u32 v2, v64, 16, 1
	v_add3_u32 v2, v64, v2, s80
	v_bfe_u32 v103, v92, 16, 1
	v_lshrrev_b32_e32 v2, 16, v2
	v_add3_u32 v103, v92, v103, s80
	v_and_or_b32 v103, v103, s85, v2
	v_bfe_u32 v2, v25, 16, 1
	global_store_dwordx4 v[104:105], v[100:103], off nt
	v_add3_u32 v2, v25, v2, s80
	v_lshrrev_b32_e32 v2, 16, v2
	v_bfe_u32 v100, v21, 16, 1
	v_add3_u32 v100, v21, v100, s80
	v_and_or_b32 v100, v100, s85, v2
	v_bfe_u32 v2, v45, 16, 1
	v_add3_u32 v2, v45, v2, s80
	v_bfe_u32 v101, v17, 16, 1
	v_lshrrev_b32_e32 v2, 16, v2
	v_add3_u32 v101, v17, v101, s80
	v_and_or_b32 v101, v101, s85, v2
	v_bfe_u32 v2, v73, 16, 1
	v_add3_u32 v2, v73, v2, s80
	v_bfe_u32 v102, v69, 16, 1
	v_lshrrev_b32_e32 v2, 16, v2
	v_add3_u32 v102, v69, v102, s80
	v_and_or_b32 v102, v102, s85, v2
	v_bfe_u32 v2, v65, 16, 1
	v_add3_u32 v2, v65, v2, s80
	v_bfe_u32 v103, v93, 16, 1
	v_lshrrev_b32_e32 v2, 16, v2
	v_add3_u32 v103, v93, v103, s80
	v_add_co_u32_e32 v106, vcc, s84, v104
	v_and_or_b32 v103, v103, s85, v2
	s_nop 0
	v_addc_co_u32_e32 v107, vcc, 0, v105, vcc
	v_bfe_u32 v2, v26, 16, 1
	global_store_dwordx4 v[106:107], v[100:103], off nt
	v_add3_u32 v2, v26, v2, s80
	v_lshrrev_b32_e32 v2, 16, v2
	v_bfe_u32 v100, v22, 16, 1
	v_add3_u32 v100, v22, v100, s80
	v_and_or_b32 v100, v100, s85, v2
	v_bfe_u32 v2, v46, 16, 1
	v_add3_u32 v2, v46, v2, s80
	v_bfe_u32 v101, v18, 16, 1
	v_lshrrev_b32_e32 v2, 16, v2
	v_add3_u32 v101, v18, v101, s80
	v_and_or_b32 v101, v101, s85, v2
	v_bfe_u32 v2, v74, 16, 1
	v_add3_u32 v2, v74, v2, s80
	v_bfe_u32 v102, v70, 16, 1
	v_lshrrev_b32_e32 v2, 16, v2
	v_add3_u32 v102, v70, v102, s80
	v_and_or_b32 v102, v102, s85, v2
	v_bfe_u32 v2, v66, 16, 1
	v_add3_u32 v2, v66, v2, s80
	v_bfe_u32 v103, v94, 16, 1
	v_lshrrev_b32_e32 v2, 16, v2
	v_add3_u32 v103, v94, v103, s80
	v_add_co_u32_e32 v106, vcc, s81, v104
	v_and_or_b32 v103, v103, s85, v2
	s_nop 0
	v_addc_co_u32_e32 v107, vcc, 0, v105, vcc
	v_bfe_u32 v2, v27, 16, 1
	global_store_dwordx4 v[106:107], v[100:103], off nt
	v_add3_u32 v2, v27, v2, s80
	v_lshrrev_b32_e32 v2, 16, v2
	v_bfe_u32 v100, v23, 16, 1
	v_add3_u32 v100, v23, v100, s80
	v_and_or_b32 v100, v100, s85, v2
	v_bfe_u32 v2, v47, 16, 1
	v_add3_u32 v2, v47, v2, s80
	v_bfe_u32 v101, v19, 16, 1
	v_lshrrev_b32_e32 v2, 16, v2
	v_add3_u32 v101, v19, v101, s80
	v_and_or_b32 v101, v101, s85, v2
	v_bfe_u32 v2, v75, 16, 1
	v_add3_u32 v2, v75, v2, s80
	v_bfe_u32 v102, v71, 16, 1
	v_lshrrev_b32_e32 v2, 16, v2
	v_add3_u32 v102, v71, v102, s80
	v_and_or_b32 v102, v102, s85, v2
	v_bfe_u32 v2, v67, 16, 1
	v_add3_u32 v2, v67, v2, s80
	v_bfe_u32 v103, v95, 16, 1
	v_lshrrev_b32_e32 v2, 16, v2
	v_add3_u32 v103, v95, v103, s80
	v_add_co_u32_e32 v104, vcc, 0x6000, v104
	v_and_or_b32 v103, v103, s85, v2
	s_nop 0
	v_addc_co_u32_e32 v105, vcc, 0, v105, vcc
	global_store_dwordx4 v[104:105], v[100:103], off nt
	s_andn2_b64 vcc, exec, s[18:19]
	s_cbranch_vccnz .LBB0_3035
.LBB0_3143:
	s_lshr_b32 s4, s22, 31
	s_ashr_i32 s5, s22, 4
	s_add_i32 s4, s5, s4
	v_lshl_or_b32 v100, s4, 6, v231
	s_mulk_i32 s4, 0xf400
	s_add_i32 s4, s4, s0
	v_add_u32_e32 v102, s4, v141
	v_ashrrev_i32_e32 v103, 31, v102
	v_lshlrev_b64 v[102:103], 13, v[102:103]
	v_ashrrev_i32_e32 v101, 31, v100
	v_lshl_add_u64 v[102:103], s[8:9], 0, v[102:103]
	v_bfe_u32 v2, v12, 16, 1
	v_lshl_add_u64 v[104:105], v[100:101], 1, v[102:103]
	v_add3_u32 v2, v12, v2, s80
	v_bfe_u32 v100, v8, 16, 1
	v_lshrrev_b32_e32 v2, 16, v2
	v_add3_u32 v100, v8, v100, s80
	v_and_or_b32 v100, v100, s85, v2
	v_bfe_u32 v2, v32, 16, 1
	v_add3_u32 v2, v32, v2, s80
	v_bfe_u32 v101, v4, 16, 1
	v_lshrrev_b32_e32 v2, 16, v2
	v_add3_u32 v101, v4, v101, s80
	v_and_or_b32 v101, v101, s85, v2
	v_bfe_u32 v2, v56, 16, 1
	v_add3_u32 v2, v56, v2, s80
	v_bfe_u32 v102, v52, 16, 1
	v_lshrrev_b32_e32 v2, 16, v2
	v_add3_u32 v102, v52, v102, s80
	v_and_or_b32 v102, v102, s85, v2
	v_bfe_u32 v2, v48, 16, 1
	v_add3_u32 v2, v48, v2, s80
	v_bfe_u32 v103, v76, 16, 1
	v_lshrrev_b32_e32 v2, 16, v2
	v_add3_u32 v103, v76, v103, s80
	v_and_or_b32 v103, v103, s85, v2
	v_bfe_u32 v2, v13, 16, 1
	global_store_dwordx4 v[104:105], v[100:103], off nt
	v_add3_u32 v2, v13, v2, s80
	v_lshrrev_b32_e32 v2, 16, v2
	v_bfe_u32 v100, v9, 16, 1
	v_add3_u32 v100, v9, v100, s80
	v_and_or_b32 v100, v100, s85, v2
	v_bfe_u32 v2, v33, 16, 1
	v_add3_u32 v2, v33, v2, s80
	v_bfe_u32 v101, v5, 16, 1
	v_lshrrev_b32_e32 v2, 16, v2
	v_add3_u32 v101, v5, v101, s80
	v_and_or_b32 v101, v101, s85, v2
	v_bfe_u32 v2, v57, 16, 1
	v_add3_u32 v2, v57, v2, s80
	v_bfe_u32 v102, v53, 16, 1
	v_lshrrev_b32_e32 v2, 16, v2
	v_add3_u32 v102, v53, v102, s80
	v_and_or_b32 v102, v102, s85, v2
	v_bfe_u32 v2, v49, 16, 1
	v_add3_u32 v2, v49, v2, s80
	v_bfe_u32 v103, v77, 16, 1
	v_lshrrev_b32_e32 v2, 16, v2
	v_add3_u32 v103, v77, v103, s80
	v_add_co_u32_e32 v106, vcc, s84, v104
	v_and_or_b32 v103, v103, s85, v2
	s_nop 0
	v_addc_co_u32_e32 v107, vcc, 0, v105, vcc
	v_bfe_u32 v2, v14, 16, 1
	global_store_dwordx4 v[106:107], v[100:103], off nt
	v_add3_u32 v2, v14, v2, s80
	v_lshrrev_b32_e32 v2, 16, v2
	v_bfe_u32 v100, v10, 16, 1
	v_add3_u32 v100, v10, v100, s80
	v_and_or_b32 v100, v100, s85, v2
	v_bfe_u32 v2, v34, 16, 1
	v_add3_u32 v2, v34, v2, s80
	v_bfe_u32 v101, v6, 16, 1
	v_lshrrev_b32_e32 v2, 16, v2
	v_add3_u32 v101, v6, v101, s80
	v_and_or_b32 v101, v101, s85, v2
	v_bfe_u32 v2, v58, 16, 1
	v_add3_u32 v2, v58, v2, s80
	v_bfe_u32 v102, v54, 16, 1
	v_lshrrev_b32_e32 v2, 16, v2
	v_add3_u32 v102, v54, v102, s80
	v_and_or_b32 v102, v102, s85, v2
	v_bfe_u32 v2, v50, 16, 1
	v_add3_u32 v2, v50, v2, s80
	v_bfe_u32 v103, v78, 16, 1
	v_lshrrev_b32_e32 v2, 16, v2
	v_add3_u32 v103, v78, v103, s80
	v_add_co_u32_e32 v106, vcc, s81, v104
	v_and_or_b32 v103, v103, s85, v2
	s_nop 0
	v_addc_co_u32_e32 v107, vcc, 0, v105, vcc
	v_bfe_u32 v2, v15, 16, 1
	global_store_dwordx4 v[106:107], v[100:103], off nt
	v_add3_u32 v2, v15, v2, s80
	v_lshrrev_b32_e32 v2, 16, v2
	v_bfe_u32 v100, v11, 16, 1
	v_add3_u32 v100, v11, v100, s80
	v_and_or_b32 v100, v100, s85, v2
	v_bfe_u32 v2, v35, 16, 1
	v_add3_u32 v2, v35, v2, s80
	v_bfe_u32 v101, v7, 16, 1
	v_lshrrev_b32_e32 v2, 16, v2
	v_add3_u32 v101, v7, v101, s80
	v_and_or_b32 v101, v101, s85, v2
	v_bfe_u32 v2, v59, 16, 1
	v_add3_u32 v2, v59, v2, s80
	v_bfe_u32 v102, v55, 16, 1
	v_lshrrev_b32_e32 v2, 16, v2
	v_add3_u32 v102, v55, v102, s80
	v_and_or_b32 v102, v102, s85, v2
	v_bfe_u32 v2, v51, 16, 1
	v_add3_u32 v2, v51, v2, s80
	v_bfe_u32 v103, v79, 16, 1
	v_lshrrev_b32_e32 v2, 16, v2
	v_add3_u32 v103, v79, v103, s80
	v_add_co_u32_e32 v104, vcc, 0x6000, v104
	v_and_or_b32 v103, v103, s85, v2
	s_nop 0
	v_addc_co_u32_e32 v105, vcc, 0, v105, vcc
	global_store_dwordx4 v[104:105], v[100:103], off nt
	s_branch .LBB0_3035

.LBB0_3185:
	v_lshl_add_u64 v[4:5], v[134:135], 2, s[8:9]
	global_load_dwordx4 v[150:153], v[4:5], off offset:16
	global_load_dwordx4 v[138:141], v[4:5], off
	s_waitcnt vmcnt(1)
	v_pk_mul_f32 v[126:127], v[126:127], v[150:151] op_sel_hi:[1,0]
	s_waitcnt vmcnt(0)
	v_mov_b32_e32 v2, v141
	v_pk_mul_f32 v[136:137], v[112:113], v[138:139] op_sel_hi:[1,0]
	v_pk_mul_f32 v[144:145], v[110:111], v[138:139] op_sel_hi:[1,0]
	v_pk_mul_f32 v[112:113], v[108:109], v[138:139] op_sel:[0,1]
	v_pk_mul_f32 v[142:143], v[106:107], v[138:139] op_sel:[0,1]
	v_pk_mul_f32 v[108:109], v[116:117], v[140:141] op_sel_hi:[1,0]
	v_pk_mul_f32 v[138:139], v[114:115], v[140:141] op_sel_hi:[1,0]
	v_pk_mul_f32 v[110:111], v[104:105], v[2:3] op_sel_hi:[1,0]
	v_pk_mul_f32 v[140:141], v[102:103], v[2:3] op_sel_hi:[1,0]
	v_mov_b32_e32 v2, v153
	v_pk_mul_f32 v[102:103], v[120:121], v[2:3] op_sel_hi:[1,0]
	v_pk_mul_f32 v[118:119], v[118:119], v[2:3] op_sel_hi:[1,0]
	v_bfe_u32 v2, v144, 16, 1
	v_add3_u32 v2, v144, v2, s80
	v_bfe_u32 v120, v142, 16, 1
	v_lshrrev_b32_e32 v2, 16, v2
	v_add3_u32 v120, v142, v120, s80
	v_pk_mul_f32 v[106:107], v[128:129], v[150:151] op_sel_hi:[1,0]
	v_and_or_b32 v128, v120, s85, v2
	v_bfe_u32 v2, v138, 16, 1
	v_add3_u32 v2, v138, v2, s80
	v_bfe_u32 v120, v140, 16, 1
	v_lshrrev_b32_e32 v2, 16, v2
	v_add3_u32 v120, v140, v120, s80
	v_pk_mul_f32 v[122:123], v[122:123], v[150:151] op_sel:[0,1]
	v_and_or_b32 v129, v120, s85, v2
	v_bfe_u32 v2, v126, 16, 1
	v_add3_u32 v2, v126, v2, s80
	v_bfe_u32 v120, v122, 16, 1
	v_pk_mul_f32 v[116:117], v[130:131], v[152:153] op_sel_hi:[1,0]
	v_lshrrev_b32_e32 v2, 16, v2
	v_add3_u32 v120, v122, v120, s80
	v_and_or_b32 v130, v120, s85, v2
	v_bfe_u32 v2, v116, 16, 1
	v_add3_u32 v2, v116, v2, s80
	v_bfe_u32 v116, v118, 16, 1
	v_lshrrev_b32_e32 v2, 16, v2
	v_add3_u32 v116, v118, v116, s80
	v_and_or_b32 v131, v116, s85, v2
	v_bfe_u32 v2, v145, 16, 1
	v_add3_u32 v2, v145, v2, s80
	v_bfe_u32 v116, v143, 16, 1
	v_lshrrev_b32_e32 v2, 16, v2
	v_add3_u32 v116, v143, v116, s80
	v_and_or_b32 v120, v116, s85, v2
	v_bfe_u32 v2, v139, 16, 1
	v_add3_u32 v2, v139, v2, s80
	v_bfe_u32 v116, v141, 16, 1
	v_lshrrev_b32_e32 v2, 16, v2
	v_add3_u32 v116, v141, v116, s80
	v_and_or_b32 v121, v116, s85, v2
	v_bfe_u32 v2, v127, 16, 1
	v_add3_u32 v2, v127, v2, s80
	v_bfe_u32 v116, v123, 16, 1
	v_lshrrev_b32_e32 v2, 16, v2
	v_add3_u32 v116, v123, v116, s80
	v_and_or_b32 v122, v116, s85, v2
	v_bfe_u32 v2, v117, 16, 1
	v_add3_u32 v2, v117, v2, s80
	v_bfe_u32 v116, v119, 16, 1
	v_lshrrev_b32_e32 v2, 16, v2
	v_add3_u32 v116, v119, v116, s80
	v_and_or_b32 v123, v116, s85, v2
	v_bfe_u32 v2, v136, 16, 1
	v_add3_u32 v2, v136, v2, s80
	v_bfe_u32 v116, v112, 16, 1
	v_lshrrev_b32_e32 v2, 16, v2
	v_add3_u32 v112, v112, v116, s80
	v_and_or_b32 v116, v112, s85, v2
	v_bfe_u32 v2, v108, 16, 1
	v_add3_u32 v2, v108, v2, s80
	v_bfe_u32 v108, v110, 16, 1
	v_lshrrev_b32_e32 v2, 16, v2
	v_add3_u32 v108, v110, v108, s80
	v_pk_mul_f32 v[104:105], v[124:125], v[150:151] op_sel:[0,1]
	v_and_or_b32 v117, v108, s85, v2
	v_bfe_u32 v2, v106, 16, 1
	v_add3_u32 v2, v106, v2, s80
	v_bfe_u32 v106, v104, 16, 1
	v_pk_mul_f32 v[4:5], v[132:133], v[152:153] op_sel_hi:[1,0]
	v_lshrrev_b32_e32 v2, 16, v2
	v_add3_u32 v104, v104, v106, s80
	v_and_or_b32 v118, v104, s85, v2
	v_bfe_u32 v2, v4, 16, 1
	v_add3_u32 v2, v4, v2, s80
	v_bfe_u32 v4, v102, 16, 1
	v_lshrrev_b32_e32 v2, 16, v2
	v_add3_u32 v4, v102, v4, s80
	v_and_or_b32 v119, v4, s85, v2
	v_bfe_u32 v2, v137, 16, 1
	v_add3_u32 v2, v137, v2, s80
	v_bfe_u32 v4, v113, 16, 1
	v_lshrrev_b32_e32 v2, 16, v2
	v_add3_u32 v4, v113, v4, s80
	v_and_or_b32 v108, v4, s85, v2
	v_bfe_u32 v2, v109, 16, 1
	v_add3_u32 v2, v109, v2, s80
	v_bfe_u32 v4, v111, 16, 1
	v_lshrrev_b32_e32 v2, 16, v2
	v_add3_u32 v4, v111, v4, s80
	v_and_or_b32 v109, v4, s85, v2
	v_bfe_u32 v2, v107, 16, 1
	v_mov_b64_e32 v[114:115], s[12:13]
	v_add3_u32 v2, v107, v2, s80
	v_bfe_u32 v4, v105, 16, 1
	v_mad_i64_i32 v[114:115], s[4:5], v149, s68, v[114:115]
	v_lshrrev_b32_e32 v2, 16, v2
	v_add3_u32 v4, v105, v4, s80
	v_lshl_add_u64 v[114:115], v[134:135], 1, v[114:115]
	s_movk_i32 s4, 0x1000
	v_and_or_b32 v110, v4, s85, v2
	v_bfe_u32 v2, v5, 16, 1
	global_store_dwordx4 v[114:115], v[120:123], off offset:3072 nt
	v_add3_u32 v2, v5, v2, s80
	v_bfe_u32 v4, v103, 16, 1
	v_add_co_u32_e32 v120, vcc, s4, v114
	v_lshrrev_b32_e32 v2, 16, v2
	s_nop 0
	v_addc_co_u32_e32 v121, vcc, 0, v115, vcc
	v_add3_u32 v4, v103, v4, s80
	v_and_or_b32 v111, v4, s85, v2
	v_add_co_u32_e32 v4, vcc, 0x2000, v114
	global_store_dwordx4 v[114:115], v[128:131], off nt
	s_nop 0
	v_addc_co_u32_e32 v5, vcc, 0, v115, vcc
	s_andn2_b64 vcc, exec, s[20:21]
	global_store_dwordx4 v[120:121], v[116:119], off offset:2048 nt
	global_store_dwordx4 v[4:5], v[108:111], off offset:1024 nt
	s_cbranch_vccnz .LBB0_3188
	s_lshr_b32 s4, s25, 31
	s_ashr_i32 s5, s25, 4
	s_add_i32 s4, s5, s4
	v_lshl_or_b32 v4, s4, 6, v231
	v_ashrrev_i32_e32 v5, 31, v4
	v_lshl_add_u64 v[106:107], v[4:5], 2, s[8:9]
	global_load_dwordx4 v[102:105], v[106:107], off offset:16
	s_nop 0
	global_load_dwordx4 v[106:109], v[106:107], off
	s_mulk_i32 s4, 0xf400
	s_add_i32 s4, s4, s0
	s_waitcnt vmcnt(1)
	v_pk_mul_f32 v[72:73], v[72:73], v[102:103] op_sel_hi:[1,0]
	s_waitcnt vmcnt(0)
	v_mov_b32_e32 v2, v109
	v_pk_mul_f32 v[36:37], v[36:37], v[2:3] op_sel_hi:[1,0]
	v_pk_mul_f32 v[34:35], v[34:35], v[2:3] op_sel_hi:[1,0]
	v_mov_b32_e32 v2, v105
	v_pk_mul_f32 v[30:31], v[30:31], v[106:107] op_sel_hi:[1,0]
	v_pk_mul_f32 v[70:71], v[70:71], v[102:103] op_sel_hi:[1,0]
	v_pk_mul_f32 v[76:77], v[76:77], v[102:103] op_sel:[0,1]
	v_pk_mul_f32 v[74:75], v[74:75], v[102:103] op_sel:[0,1]
	v_pk_mul_f32 v[100:101], v[100:101], v[2:3] op_sel_hi:[1,0]
	v_pk_mul_f32 v[98:99], v[98:99], v[2:3] op_sel_hi:[1,0]
	v_add_u32_e32 v2, s4, v148
	v_mov_b64_e32 v[102:103], s[12:13]
	v_pk_mul_f32 v[38:39], v[38:39], v[106:107] op_sel:[0,1]
	v_mad_i64_i32 v[102:103], s[4:5], v2, s68, v[102:103]
	v_bfe_u32 v2, v30, 16, 1
	v_lshl_add_u64 v[4:5], v[4:5], 1, v[102:103]
	v_add3_u32 v2, v30, v2, s80
	v_bfe_u32 v102, v38, 16, 1
	v_pk_mul_f32 v[50:51], v[50:51], v[108:109] op_sel_hi:[1,0]
	v_lshrrev_b32_e32 v2, 16, v2
	v_add3_u32 v102, v38, v102, s80
	v_and_or_b32 v102, v102, s85, v2
	v_bfe_u32 v2, v50, 16, 1
	v_add3_u32 v2, v50, v2, s80
	v_bfe_u32 v103, v34, 16, 1
	v_lshrrev_b32_e32 v2, 16, v2
	v_add3_u32 v103, v34, v103, s80
	v_and_or_b32 v103, v103, s85, v2
	v_bfe_u32 v2, v70, 16, 1
	v_pk_mul_f32 v[96:97], v[96:97], v[104:105] op_sel_hi:[1,0]
	v_pk_mul_f32 v[94:95], v[94:95], v[104:105] op_sel_hi:[1,0]
	v_add3_u32 v2, v70, v2, s80
	v_bfe_u32 v104, v74, 16, 1
	v_lshrrev_b32_e32 v2, 16, v2
	v_add3_u32 v104, v74, v104, s80
	v_and_or_b32 v104, v104, s85, v2
	v_bfe_u32 v2, v94, 16, 1
	v_add3_u32 v2, v94, v2, s80
	v_bfe_u32 v105, v98, 16, 1
	v_lshrrev_b32_e32 v2, 16, v2
	v_add3_u32 v105, v98, v105, s80
	v_and_or_b32 v105, v105, s85, v2
	v_bfe_u32 v2, v31, 16, 1
	global_store_dwordx4 v[4:5], v[102:105], off nt
	v_add3_u32 v2, v31, v2, s80
	v_lshrrev_b32_e32 v2, 16, v2
	v_bfe_u32 v102, v39, 16, 1
	v_add3_u32 v102, v39, v102, s80
	v_and_or_b32 v102, v102, s85, v2
	v_bfe_u32 v2, v51, 16, 1
	v_add3_u32 v2, v51, v2, s80
	v_bfe_u32 v103, v35, 16, 1
	v_lshrrev_b32_e32 v2, 16, v2
	v_add3_u32 v103, v35, v103, s80
	v_and_or_b32 v103, v103, s85, v2
	v_bfe_u32 v2, v71, 16, 1
	v_add3_u32 v2, v71, v2, s80
	v_bfe_u32 v104, v75, 16, 1
	v_lshrrev_b32_e32 v2, 16, v2
	v_add3_u32 v104, v75, v104, s80
	v_and_or_b32 v104, v104, s85, v2
	v_bfe_u32 v2, v95, 16, 1
	v_add3_u32 v2, v95, v2, s80
	v_bfe_u32 v105, v99, 16, 1
	v_pk_mul_f32 v[32:33], v[32:33], v[106:107] op_sel_hi:[1,0]
	v_lshrrev_b32_e32 v2, 16, v2
	v_add3_u32 v105, v99, v105, s80
	v_pk_mul_f32 v[40:41], v[40:41], v[106:107] op_sel:[0,1]
	v_and_or_b32 v105, v105, s85, v2
	v_bfe_u32 v2, v32, 16, 1
	global_store_dwordx4 v[4:5], v[102:105], off offset:3072 nt
	v_add3_u32 v2, v32, v2, s80
	v_pk_mul_f32 v[52:53], v[52:53], v[108:109] op_sel_hi:[1,0]
	v_bfe_u32 v102, v40, 16, 1
	v_lshrrev_b32_e32 v2, 16, v2
	v_add3_u32 v102, v40, v102, s80
	v_and_or_b32 v102, v102, s85, v2
	v_bfe_u32 v2, v52, 16, 1
	v_add3_u32 v2, v52, v2, s80
	v_bfe_u32 v103, v36, 16, 1
	v_lshrrev_b32_e32 v2, 16, v2
	v_add3_u32 v103, v36, v103, s80
	v_and_or_b32 v103, v103, s85, v2
	v_bfe_u32 v2, v72, 16, 1
	v_add3_u32 v2, v72, v2, s80
	v_bfe_u32 v104, v76, 16, 1
	v_lshrrev_b32_e32 v2, 16, v2
	v_add3_u32 v104, v76, v104, s80
	v_and_or_b32 v104, v104, s85, v2
	v_bfe_u32 v2, v96, 16, 1
	s_movk_i32 s4, 0x1000
	v_add3_u32 v2, v96, v2, s80
	v_bfe_u32 v105, v100, 16, 1
	v_lshrrev_b32_e32 v2, 16, v2
	v_add3_u32 v105, v100, v105, s80
	v_add_co_u32_e32 v106, vcc, s4, v4
	v_and_or_b32 v105, v105, s85, v2
	s_nop 0
	v_addc_co_u32_e32 v107, vcc, 0, v5, vcc
	v_bfe_u32 v2, v33, 16, 1
	global_store_dwordx4 v[106:107], v[102:105], off offset:2048 nt
	v_add3_u32 v2, v33, v2, s80
	v_lshrrev_b32_e32 v2, 16, v2
	v_bfe_u32 v102, v41, 16, 1
	v_add3_u32 v102, v41, v102, s80
	v_and_or_b32 v102, v102, s85, v2
	v_bfe_u32 v2, v53, 16, 1
	v_add3_u32 v2, v53, v2, s80
	v_bfe_u32 v103, v37, 16, 1
	v_lshrrev_b32_e32 v2, 16, v2
	v_add3_u32 v103, v37, v103, s80
	v_and_or_b32 v103, v103, s85, v2
	v_bfe_u32 v2, v73, 16, 1
	v_add3_u32 v2, v73, v2, s80
	v_bfe_u32 v104, v77, 16, 1
	v_lshrrev_b32_e32 v2, 16, v2
	v_add3_u32 v104, v77, v104, s80
	v_and_or_b32 v104, v104, s85, v2
	v_bfe_u32 v2, v97, 16, 1
	v_add3_u32 v2, v97, v2, s80
	v_bfe_u32 v105, v101, 16, 1
	v_lshrrev_b32_e32 v2, 16, v2
	v_add3_u32 v105, v101, v105, s80
	v_add_co_u32_e32 v4, vcc, 0x2000, v4
	v_and_or_b32 v105, v105, s85, v2
	s_nop 0
	v_addc_co_u32_e32 v5, vcc, 0, v5, vcc
	global_store_dwordx4 v[4:5], v[102:105], off offset:1024 nt
	s_andn2_b64 vcc, exec, s[18:19]
	s_cbranch_vccz .LBB0_3189

.LBB0_3189:
	s_lshr_b32 s4, s15, 31
	s_ashr_i32 s5, s15, 4
	s_add_i32 s4, s5, s4
	v_lshl_or_b32 v4, s4, 6, v231
	v_ashrrev_i32_e32 v5, 31, v4
	v_lshl_add_u64 v[106:107], v[4:5], 2, s[8:9]
	global_load_dwordx4 v[102:105], v[106:107], off offset:16
	s_nop 0
	global_load_dwordx4 v[106:109], v[106:107], off
	s_mulk_i32 s4, 0xf400
	s_add_i32 s4, s4, s0
	s_waitcnt vmcnt(1)
	v_pk_mul_f32 v[64:65], v[64:65], v[102:103] op_sel_hi:[1,0]
	s_waitcnt vmcnt(0)
	v_mov_b32_e32 v2, v109
	v_pk_mul_f32 v[20:21], v[20:21], v[2:3] op_sel_hi:[1,0]
	v_pk_mul_f32 v[18:19], v[18:19], v[2:3] op_sel_hi:[1,0]
	v_mov_b32_e32 v2, v105
	v_pk_mul_f32 v[22:23], v[22:23], v[106:107] op_sel_hi:[1,0]
	v_pk_mul_f32 v[62:63], v[62:63], v[102:103] op_sel_hi:[1,0]
	v_pk_mul_f32 v[68:69], v[68:69], v[102:103] op_sel:[0,1]
	v_pk_mul_f32 v[66:67], v[66:67], v[102:103] op_sel:[0,1]
	v_pk_mul_f32 v[92:93], v[92:93], v[2:3] op_sel_hi:[1,0]
	v_pk_mul_f32 v[90:91], v[90:91], v[2:3] op_sel_hi:[1,0]
	v_add_u32_e32 v2, s4, v146
	v_mov_b64_e32 v[102:103], s[12:13]
	v_pk_mul_f32 v[26:27], v[26:27], v[106:107] op_sel:[0,1]
	v_mad_i64_i32 v[102:103], s[4:5], v2, s68, v[102:103]
	v_bfe_u32 v2, v22, 16, 1
	v_lshl_add_u64 v[4:5], v[4:5], 1, v[102:103]
	v_add3_u32 v2, v22, v2, s80
	v_bfe_u32 v102, v26, 16, 1
	v_pk_mul_f32 v[46:47], v[46:47], v[108:109] op_sel_hi:[1,0]
	v_lshrrev_b32_e32 v2, 16, v2
	v_add3_u32 v102, v26, v102, s80
	v_and_or_b32 v102, v102, s85, v2
	v_bfe_u32 v2, v46, 16, 1
	v_add3_u32 v2, v46, v2, s80
	v_bfe_u32 v103, v18, 16, 1
	v_lshrrev_b32_e32 v2, 16, v2
	v_add3_u32 v103, v18, v103, s80
	v_and_or_b32 v103, v103, s85, v2
	v_bfe_u32 v2, v62, 16, 1
	v_pk_mul_f32 v[88:89], v[88:89], v[104:105] op_sel_hi:[1,0]
	v_pk_mul_f32 v[86:87], v[86:87], v[104:105] op_sel_hi:[1,0]
	v_add3_u32 v2, v62, v2, s80
	v_bfe_u32 v104, v66, 16, 1
	v_lshrrev_b32_e32 v2, 16, v2
	v_add3_u32 v104, v66, v104, s80
	v_and_or_b32 v104, v104, s85, v2
	v_bfe_u32 v2, v86, 16, 1
	v_add3_u32 v2, v86, v2, s80
	v_bfe_u32 v105, v90, 16, 1
	v_lshrrev_b32_e32 v2, 16, v2
	v_add3_u32 v105, v90, v105, s80
	v_and_or_b32 v105, v105, s85, v2
	v_bfe_u32 v2, v23, 16, 1
	global_store_dwordx4 v[4:5], v[102:105], off nt
	v_add3_u32 v2, v23, v2, s80
	v_lshrrev_b32_e32 v2, 16, v2
	v_bfe_u32 v102, v27, 16, 1
	v_add3_u32 v102, v27, v102, s80
	v_and_or_b32 v102, v102, s85, v2
	v_bfe_u32 v2, v47, 16, 1
	v_add3_u32 v2, v47, v2, s80
	v_bfe_u32 v103, v19, 16, 1
	v_lshrrev_b32_e32 v2, 16, v2
	v_add3_u32 v103, v19, v103, s80
	v_and_or_b32 v103, v103, s85, v2
	v_bfe_u32 v2, v63, 16, 1
	v_add3_u32 v2, v63, v2, s80
	v_bfe_u32 v104, v67, 16, 1
	v_lshrrev_b32_e32 v2, 16, v2
	v_add3_u32 v104, v67, v104, s80
	v_and_or_b32 v104, v104, s85, v2
	v_bfe_u32 v2, v87, 16, 1
	v_add3_u32 v2, v87, v2, s80
	v_bfe_u32 v105, v91, 16, 1
	v_pk_mul_f32 v[24:25], v[24:25], v[106:107] op_sel_hi:[1,0]
	v_lshrrev_b32_e32 v2, 16, v2
	v_add3_u32 v105, v91, v105, s80
	v_pk_mul_f32 v[28:29], v[28:29], v[106:107] op_sel:[0,1]
	v_and_or_b32 v105, v105, s85, v2
	v_bfe_u32 v2, v24, 16, 1
	global_store_dwordx4 v[4:5], v[102:105], off offset:3072 nt
	v_add3_u32 v2, v24, v2, s80
	v_pk_mul_f32 v[48:49], v[48:49], v[108:109] op_sel_hi:[1,0]
	v_bfe_u32 v102, v28, 16, 1
	v_lshrrev_b32_e32 v2, 16, v2
	v_add3_u32 v102, v28, v102, s80
	v_and_or_b32 v102, v102, s85, v2
	v_bfe_u32 v2, v48, 16, 1
	v_add3_u32 v2, v48, v2, s80
	v_bfe_u32 v103, v20, 16, 1
	v_lshrrev_b32_e32 v2, 16, v2
	v_add3_u32 v103, v20, v103, s80
	v_and_or_b32 v103, v103, s85, v2
	v_bfe_u32 v2, v64, 16, 1
	v_add3_u32 v2, v64, v2, s80
	v_bfe_u32 v104, v68, 16, 1
	v_lshrrev_b32_e32 v2, 16, v2
	v_add3_u32 v104, v68, v104, s80
	v_and_or_b32 v104, v104, s85, v2
	v_bfe_u32 v2, v88, 16, 1
	s_movk_i32 s4, 0x1000
	v_add3_u32 v2, v88, v2, s80
	v_bfe_u32 v105, v92, 16, 1
	v_lshrrev_b32_e32 v2, 16, v2
	v_add3_u32 v105, v92, v105, s80
	v_add_co_u32_e32 v106, vcc, s4, v4
	v_and_or_b32 v105, v105, s85, v2
	s_nop 0
	v_addc_co_u32_e32 v107, vcc, 0, v5, vcc
	v_bfe_u32 v2, v25, 16, 1
	global_store_dwordx4 v[106:107], v[102:105], off offset:2048 nt
	v_add3_u32 v2, v25, v2, s80
	v_lshrrev_b32_e32 v2, 16, v2
	v_bfe_u32 v102, v29, 16, 1
	v_add3_u32 v102, v29, v102, s80
	v_and_or_b32 v102, v102, s85, v2
	v_bfe_u32 v2, v49, 16, 1
	v_add3_u32 v2, v49, v2, s80
	v_bfe_u32 v103, v21, 16, 1
	v_lshrrev_b32_e32 v2, 16, v2
	v_add3_u32 v103, v21, v103, s80
	v_and_or_b32 v103, v103, s85, v2
	v_bfe_u32 v2, v65, 16, 1
	v_add3_u32 v2, v65, v2, s80
	v_bfe_u32 v104, v69, 16, 1
	v_lshrrev_b32_e32 v2, 16, v2
	v_add3_u32 v104, v69, v104, s80
	v_and_or_b32 v104, v104, s85, v2
	v_bfe_u32 v2, v89, 16, 1
	v_add3_u32 v2, v89, v2, s80
	v_bfe_u32 v105, v93, 16, 1
	v_lshrrev_b32_e32 v2, 16, v2
	v_add3_u32 v105, v93, v105, s80
	v_add_co_u32_e32 v4, vcc, 0x2000, v4
	v_and_or_b32 v105, v105, s85, v2
	s_nop 0
	v_addc_co_u32_e32 v5, vcc, 0, v5, vcc
	global_store_dwordx4 v[4:5], v[102:105], off offset:1024 nt
	s_andn2_b64 vcc, exec, s[16:17]
	s_cbranch_vccnz .LBB0_3146
.LBB0_3190:
	s_lshr_b32 s4, s14, 31
	s_ashr_i32 s5, s14, 4
	s_add_i32 s4, s5, s4
	v_lshl_or_b32 v4, s4, 6, v231
	v_ashrrev_i32_e32 v5, 31, v4
	v_lshl_add_u64 v[106:107], v[4:5], 2, s[8:9]
	global_load_dwordx4 v[102:105], v[106:107], off offset:16
	s_nop 0
	global_load_dwordx4 v[106:109], v[106:107], off
	s_mulk_i32 s4, 0xf400
	s_add_i32 s4, s4, s0
	s_movk_i32 s15, 0x1000
	s_waitcnt vmcnt(1)
	v_pk_mul_f32 v[56:57], v[56:57], v[102:103] op_sel_hi:[1,0]
	s_waitcnt vmcnt(0)
	v_mov_b32_e32 v2, v109
	v_pk_mul_f32 v[12:13], v[12:13], v[2:3] op_sel_hi:[1,0]
	v_pk_mul_f32 v[10:11], v[10:11], v[2:3] op_sel_hi:[1,0]
	v_mov_b32_e32 v2, v105
	v_pk_mul_f32 v[6:7], v[6:7], v[106:107] op_sel_hi:[1,0]
	v_pk_mul_f32 v[54:55], v[54:55], v[102:103] op_sel_hi:[1,0]
	v_pk_mul_f32 v[60:61], v[60:61], v[102:103] op_sel:[0,1]
	v_pk_mul_f32 v[58:59], v[58:59], v[102:103] op_sel:[0,1]
	v_pk_mul_f32 v[84:85], v[84:85], v[2:3] op_sel_hi:[1,0]
	v_pk_mul_f32 v[82:83], v[82:83], v[2:3] op_sel_hi:[1,0]
	v_add_u32_e32 v2, s4, v147
	v_mov_b64_e32 v[102:103], s[12:13]
	v_pk_mul_f32 v[14:15], v[14:15], v[106:107] op_sel:[0,1]
	v_mad_i64_i32 v[102:103], s[4:5], v2, s68, v[102:103]
	v_bfe_u32 v2, v6, 16, 1
	v_lshl_add_u64 v[4:5], v[4:5], 1, v[102:103]
	v_add3_u32 v2, v6, v2, s80
	v_bfe_u32 v102, v14, 16, 1
	v_pk_mul_f32 v[42:43], v[42:43], v[108:109] op_sel_hi:[1,0]
	v_lshrrev_b32_e32 v2, 16, v2
	v_add3_u32 v102, v14, v102, s80
	v_and_or_b32 v102, v102, s85, v2
	v_bfe_u32 v2, v42, 16, 1
	v_add3_u32 v2, v42, v2, s80
	v_bfe_u32 v103, v10, 16, 1
	v_lshrrev_b32_e32 v2, 16, v2
	v_add3_u32 v103, v10, v103, s80
	v_and_or_b32 v103, v103, s85, v2
	v_bfe_u32 v2, v54, 16, 1
	v_pk_mul_f32 v[80:81], v[80:81], v[104:105] op_sel_hi:[1,0]
	v_pk_mul_f32 v[78:79], v[78:79], v[104:105] op_sel_hi:[1,0]
	v_add3_u32 v2, v54, v2, s80
	v_bfe_u32 v104, v58, 16, 1
	v_lshrrev_b32_e32 v2, 16, v2
	v_add3_u32 v104, v58, v104, s80
	v_and_or_b32 v104, v104, s85, v2
	v_bfe_u32 v2, v78, 16, 1
	v_add3_u32 v2, v78, v2, s80
	v_bfe_u32 v105, v82, 16, 1
	v_lshrrev_b32_e32 v2, 16, v2
	v_add3_u32 v105, v82, v105, s80
	v_and_or_b32 v105, v105, s85, v2
	v_bfe_u32 v2, v7, 16, 1
	global_store_dwordx4 v[4:5], v[102:105], off nt
	v_add3_u32 v2, v7, v2, s80
	v_lshrrev_b32_e32 v2, 16, v2
	v_bfe_u32 v102, v15, 16, 1
	v_add3_u32 v102, v15, v102, s80
	v_and_or_b32 v102, v102, s85, v2
	v_bfe_u32 v2, v43, 16, 1
	v_add3_u32 v2, v43, v2, s80
	v_bfe_u32 v103, v11, 16, 1
	v_lshrrev_b32_e32 v2, 16, v2
	v_add3_u32 v103, v11, v103, s80
	v_and_or_b32 v103, v103, s85, v2
	v_bfe_u32 v2, v55, 16, 1
	v_add3_u32 v2, v55, v2, s80
	v_bfe_u32 v104, v59, 16, 1
	v_lshrrev_b32_e32 v2, 16, v2
	v_add3_u32 v104, v59, v104, s80
	v_and_or_b32 v104, v104, s85, v2
	v_bfe_u32 v2, v79, 16, 1
	v_add3_u32 v2, v79, v2, s80
	v_bfe_u32 v105, v83, 16, 1
	v_pk_mul_f32 v[8:9], v[8:9], v[106:107] op_sel_hi:[1,0]
	v_lshrrev_b32_e32 v2, 16, v2
	v_add3_u32 v105, v83, v105, s80
	v_pk_mul_f32 v[16:17], v[16:17], v[106:107] op_sel:[0,1]
	v_and_or_b32 v105, v105, s85, v2
	v_bfe_u32 v2, v8, 16, 1
	global_store_dwordx4 v[4:5], v[102:105], off offset:3072 nt
	v_add3_u32 v2, v8, v2, s80
	v_pk_mul_f32 v[44:45], v[44:45], v[108:109] op_sel_hi:[1,0]
	v_bfe_u32 v102, v16, 16, 1
	v_lshrrev_b32_e32 v2, 16, v2
	v_add3_u32 v102, v16, v102, s80
	v_and_or_b32 v102, v102, s85, v2
	v_bfe_u32 v2, v44, 16, 1
	v_add3_u32 v2, v44, v2, s80
	v_bfe_u32 v103, v12, 16, 1
	v_lshrrev_b32_e32 v2, 16, v2
	v_add3_u32 v103, v12, v103, s80
	v_and_or_b32 v103, v103, s85, v2
	v_bfe_u32 v2, v56, 16, 1
	v_add3_u32 v2, v56, v2, s80
	v_bfe_u32 v104, v60, 16, 1
	v_lshrrev_b32_e32 v2, 16, v2
	v_add3_u32 v104, v60, v104, s80
	v_and_or_b32 v104, v104, s85, v2
	v_bfe_u32 v2, v80, 16, 1
	v_add3_u32 v2, v80, v2, s80
	v_bfe_u32 v105, v84, 16, 1
	v_lshrrev_b32_e32 v2, 16, v2
	v_add3_u32 v105, v84, v105, s80
	v_add_co_u32_e32 v106, vcc, s15, v4
	v_and_or_b32 v105, v105, s85, v2
	s_nop 0
	v_addc_co_u32_e32 v107, vcc, 0, v5, vcc
	v_bfe_u32 v2, v9, 16, 1
	global_store_dwordx4 v[106:107], v[102:105], off offset:2048 nt
	v_add3_u32 v2, v9, v2, s80
	v_lshrrev_b32_e32 v2, 16, v2
	v_bfe_u32 v102, v17, 16, 1
	v_add3_u32 v102, v17, v102, s80
	v_and_or_b32 v102, v102, s85, v2
	v_bfe_u32 v2, v45, 16, 1
	v_add3_u32 v2, v45, v2, s80
	v_bfe_u32 v103, v13, 16, 1
	v_lshrrev_b32_e32 v2, 16, v2
	v_add3_u32 v103, v13, v103, s80
	v_and_or_b32 v103, v103, s85, v2
	v_bfe_u32 v2, v57, 16, 1
	v_add3_u32 v2, v57, v2, s80
	v_bfe_u32 v104, v61, 16, 1
	v_lshrrev_b32_e32 v2, 16, v2
	v_add3_u32 v104, v61, v104, s80
	v_and_or_b32 v104, v104, s85, v2
	v_bfe_u32 v2, v81, 16, 1
	v_add3_u32 v2, v81, v2, s80
	v_bfe_u32 v105, v85, 16, 1
	v_lshrrev_b32_e32 v2, 16, v2
	v_add3_u32 v105, v85, v105, s80
	v_add_co_u32_e32 v4, vcc, 0x2000, v4
	v_and_or_b32 v105, v105, s85, v2
	s_nop 0
	v_addc_co_u32_e32 v5, vcc, 0, v5, vcc
	global_store_dwordx4 v[4:5], v[102:105], off offset:1024 nt
	s_branch .LBB0_3146

.LBB0_3232:
	v_lshl_add_u64 v[4:5], v[134:135], 2, s[6:7]
	global_load_dwordx4 v[146:149], v[4:5], off offset:2048
	global_load_dwordx4 v[150:153], v[4:5], off offset:2064
	v_ashrrev_i32_e32 v137, 31, v136
	v_lshlrev_b64 v[4:5], 10, v[136:137]
	v_lshl_add_u64 v[4:5], s[8:9], 0, v[4:5]
	v_lshl_add_u64 v[4:5], v[134:135], 1, v[4:5]
	s_andn2_b64 vcc, exec, s[18:19]
	s_waitcnt vmcnt(1)
	v_pk_mul_f32 v[134:135], v[112:113], v[146:147] op_sel_hi:[1,0]
	v_pk_mul_f32 v[110:111], v[110:111], v[146:147] op_sel_hi:[1,0]
	v_pk_mul_f32 v[136:137], v[108:109], v[146:147] op_sel:[0,1]
	v_pk_mul_f32 v[106:107], v[106:107], v[146:147] op_sel:[0,1]
	v_pk_mul_f32 v[108:109], v[114:115], v[148:149] op_sel_hi:[1,0]
	v_mov_b32_e32 v2, v149
	s_waitcnt vmcnt(0)
	v_pk_mul_f32 v[114:115], v[128:129], v[150:151] op_sel_hi:[1,0]
	v_pk_mul_f32 v[112:113], v[126:127], v[150:151] op_sel_hi:[1,0]
	v_pk_mul_f32 v[122:123], v[122:123], v[150:151] op_sel:[0,1]
	v_pk_mul_f32 v[128:129], v[130:131], v[152:153] op_sel_hi:[1,0]
	v_mov_b32_e32 v130, v153
	v_pk_mul_f32 v[126:127], v[132:133], v[152:153] op_sel_hi:[1,0]
	v_pk_mul_f32 v[132:133], v[104:105], v[2:3] op_sel_hi:[1,0]
	v_pk_mul_f32 v[102:103], v[102:103], v[2:3] op_sel_hi:[1,0]
	v_pk_mul_f32 v[120:121], v[120:121], v[130:131] op_sel_hi:[1,0]
	v_pk_mul_f32 v[104:105], v[118:119], v[130:131] op_sel_hi:[1,0]
	v_bfe_u32 v2, v110, 16, 1
	v_bfe_u32 v118, v106, 16, 1
	v_bfe_u32 v119, v108, 16, 1
	v_bfe_u32 v130, v112, 16, 1
	v_bfe_u32 v131, v122, 16, 1
	v_bfe_u32 v138, v128, 16, 1
	v_pk_mul_f32 v[116:117], v[116:117], v[148:149] op_sel_hi:[1,0]
	v_pk_mul_f32 v[124:125], v[124:125], v[150:151] op_sel:[0,1]
	v_bfe_u32 v139, v111, 16, 1
	v_bfe_u32 v147, v109, 16, 1
	v_bfe_u32 v148, v113, 16, 1
	v_bfe_u32 v150, v129, 16, 1
	v_add3_u32 v2, v110, v2, s80
	v_add3_u32 v106, v106, v118, s80
	v_add3_u32 v108, v108, v119, s80
	v_bfe_u32 v110, v102, 16, 1
	v_add3_u32 v112, v112, v130, s80
	v_add3_u32 v118, v122, v131, s80
	v_add3_u32 v119, v128, v138, s80
	v_bfe_u32 v122, v104, 16, 1
	v_bfe_u32 v146, v107, 16, 1
	v_bfe_u32 v149, v123, 16, 1
	v_add3_u32 v111, v111, v139, s80
	v_add3_u32 v109, v109, v147, s80
	v_bfe_u32 v128, v103, 16, 1
	v_add3_u32 v113, v113, v148, s80
	v_add3_u32 v129, v129, v150, s80
	v_bfe_u32 v130, v105, 16, 1
	v_lshrrev_b32_e32 v2, 16, v2
	v_lshrrev_b32_e32 v108, 16, v108
	v_add3_u32 v110, v102, v110, s80
	v_lshrrev_b32_e32 v112, 16, v112
	v_lshrrev_b32_e32 v119, 16, v119
	v_add3_u32 v122, v104, v122, s80
	v_add3_u32 v107, v107, v146, s80
	v_add3_u32 v123, v123, v149, s80
	v_lshrrev_b32_e32 v111, 16, v111
	v_lshrrev_b32_e32 v109, 16, v109
	v_add3_u32 v128, v103, v128, s80
	v_lshrrev_b32_e32 v113, 16, v113
	v_lshrrev_b32_e32 v129, 16, v129
	v_add3_u32 v130, v105, v130, s80
	v_and_or_b32 v102, v106, s85, v2
	v_and_or_b32 v103, v110, s85, v108
	v_and_or_b32 v104, v118, s85, v112
	v_and_or_b32 v105, v122, s85, v119
	v_bfe_u32 v2, v114, 16, 1
	v_and_or_b32 v106, v107, s85, v111
	v_and_or_b32 v107, v128, s85, v109
	v_and_or_b32 v108, v123, s85, v113
	v_and_or_b32 v109, v130, s85, v129
	global_store_dwordx4 v[4:5], v[102:105], off nt
	global_store_dwordx4 v[4:5], v[106:109], off offset:1024 nt
	v_add3_u32 v2, v114, v2, s80
	v_bfe_u32 v102, v124, 16, 1
	v_lshrrev_b32_e32 v2, 16, v2
	v_add3_u32 v102, v124, v102, s80
	v_and_or_b32 v112, v102, s85, v2
	v_bfe_u32 v2, v126, 16, 1
	v_add3_u32 v2, v126, v2, s80
	v_bfe_u32 v102, v120, 16, 1
	v_lshrrev_b32_e32 v2, 16, v2
	v_add3_u32 v102, v120, v102, s80
	v_and_or_b32 v113, v102, s85, v2
	v_bfe_u32 v2, v135, 16, 1
	v_add3_u32 v2, v135, v2, s80
	v_bfe_u32 v102, v137, 16, 1
	v_lshrrev_b32_e32 v2, 16, v2
	v_add3_u32 v102, v137, v102, s80
	v_and_or_b32 v102, v102, s85, v2
	v_bfe_u32 v2, v117, 16, 1
	v_add3_u32 v2, v117, v2, s80
	v_bfe_u32 v103, v133, 16, 1
	v_lshrrev_b32_e32 v2, 16, v2
	v_add3_u32 v103, v133, v103, s80
	v_and_or_b32 v103, v103, s85, v2
	v_bfe_u32 v2, v115, 16, 1
	v_add3_u32 v2, v115, v2, s80
	v_bfe_u32 v104, v125, 16, 1
	v_lshrrev_b32_e32 v2, 16, v2
	v_add3_u32 v104, v125, v104, s80
	v_bfe_u32 v151, v134, 16, 1
	v_bfe_u32 v152, v136, 16, 1
	v_bfe_u32 v153, v116, 16, 1
	v_and_or_b32 v104, v104, s85, v2
	v_bfe_u32 v2, v127, 16, 1
	v_add3_u32 v131, v134, v151, s80
	v_add3_u32 v134, v136, v152, s80
	v_add3_u32 v116, v116, v153, s80
	v_bfe_u32 v136, v132, 16, 1
	v_add3_u32 v2, v127, v2, s80
	v_bfe_u32 v105, v121, 16, 1
	v_lshrrev_b32_e32 v131, 16, v131
	v_lshrrev_b32_e32 v116, 16, v116
	v_add3_u32 v132, v132, v136, s80
	v_lshrrev_b32_e32 v2, 16, v2
	v_add3_u32 v105, v121, v105, s80
	v_and_or_b32 v110, v134, s85, v131
	v_and_or_b32 v111, v132, s85, v116
	v_and_or_b32 v105, v105, s85, v2
	global_store_dwordx4 v[4:5], v[110:113], off offset:2048 nt
	global_store_dwordx4 v[4:5], v[102:105], off offset:3072 nt
	s_cbranch_vccnz .LBB0_3235
	s_ashr_i32 s4, s27, 31
	s_lshr_b32 s4, s4, 25
	s_add_i32 s27, s27, s4
	s_ashr_i32 s4, s27, 7
	v_lshl_or_b32 v4, s4, 6, v231
	v_ashrrev_i32_e32 v5, 31, v4
	v_lshl_add_u64 v[106:107], v[4:5], 2, s[6:7]
	global_load_dwordx4 v[102:105], v[106:107], off offset:2064
	s_nop 0
	global_load_dwordx4 v[106:109], v[106:107], off offset:2048
	s_lshl_b32 s4, s4, 12
	s_waitcnt vmcnt(1)
	v_pk_mul_f32 v[72:73], v[72:73], v[102:103] op_sel_hi:[1,0]
	v_pk_mul_f32 v[70:71], v[70:71], v[102:103] op_sel_hi:[1,0]
	v_pk_mul_f32 v[76:77], v[76:77], v[102:103] op_sel:[0,1]
	v_pk_mul_f32 v[74:75], v[74:75], v[102:103] op_sel:[0,1]
	v_subrev_u32_e32 v102, s4, v145
	s_waitcnt vmcnt(0)
	v_mov_b32_e32 v2, v109
	v_ashrrev_i32_e32 v103, 31, v102
	v_pk_mul_f32 v[30:31], v[30:31], v[106:107] op_sel_hi:[1,0]
	v_pk_mul_f32 v[36:37], v[36:37], v[2:3] op_sel_hi:[1,0]
	v_pk_mul_f32 v[34:35], v[34:35], v[2:3] op_sel_hi:[1,0]
	v_mov_b32_e32 v2, v105
	v_lshlrev_b64 v[102:103], 10, v[102:103]
	v_pk_mul_f32 v[38:39], v[38:39], v[106:107] op_sel:[0,1]
	v_pk_mul_f32 v[100:101], v[100:101], v[2:3] op_sel_hi:[1,0]
	v_pk_mul_f32 v[98:99], v[98:99], v[2:3] op_sel_hi:[1,0]
	v_lshl_add_u64 v[102:103], s[8:9], 0, v[102:103]
	v_bfe_u32 v2, v30, 16, 1
	v_lshl_add_u64 v[4:5], v[4:5], 1, v[102:103]
	v_add3_u32 v2, v30, v2, s80
	v_bfe_u32 v102, v38, 16, 1
	v_pk_mul_f32 v[50:51], v[50:51], v[108:109] op_sel_hi:[1,0]
	v_lshrrev_b32_e32 v2, 16, v2
	v_add3_u32 v102, v38, v102, s80
	v_and_or_b32 v102, v102, s85, v2
	v_bfe_u32 v2, v50, 16, 1
	v_add3_u32 v2, v50, v2, s80
	v_bfe_u32 v103, v34, 16, 1
	v_lshrrev_b32_e32 v2, 16, v2
	v_add3_u32 v103, v34, v103, s80
	v_and_or_b32 v103, v103, s85, v2
	v_bfe_u32 v2, v70, 16, 1
	v_pk_mul_f32 v[96:97], v[96:97], v[104:105] op_sel_hi:[1,0]
	v_pk_mul_f32 v[94:95], v[94:95], v[104:105] op_sel_hi:[1,0]
	v_add3_u32 v2, v70, v2, s80
	v_bfe_u32 v104, v74, 16, 1
	v_lshrrev_b32_e32 v2, 16, v2
	v_add3_u32 v104, v74, v104, s80
	v_and_or_b32 v104, v104, s85, v2
	v_bfe_u32 v2, v94, 16, 1
	v_add3_u32 v2, v94, v2, s80
	v_bfe_u32 v105, v98, 16, 1
	v_lshrrev_b32_e32 v2, 16, v2
	v_add3_u32 v105, v98, v105, s80
	v_and_or_b32 v105, v105, s85, v2
	v_bfe_u32 v2, v31, 16, 1
	global_store_dwordx4 v[4:5], v[102:105], off nt
	v_add3_u32 v2, v31, v2, s80
	v_lshrrev_b32_e32 v2, 16, v2
	v_bfe_u32 v102, v39, 16, 1
	v_add3_u32 v102, v39, v102, s80
	v_and_or_b32 v102, v102, s85, v2
	v_bfe_u32 v2, v51, 16, 1
	v_add3_u32 v2, v51, v2, s80
	v_bfe_u32 v103, v35, 16, 1
	v_lshrrev_b32_e32 v2, 16, v2
	v_add3_u32 v103, v35, v103, s80
	v_and_or_b32 v103, v103, s85, v2
	v_bfe_u32 v2, v71, 16, 1
	v_add3_u32 v2, v71, v2, s80
	v_bfe_u32 v104, v75, 16, 1
	v_lshrrev_b32_e32 v2, 16, v2
	v_add3_u32 v104, v75, v104, s80
	v_and_or_b32 v104, v104, s85, v2
	v_bfe_u32 v2, v95, 16, 1
	v_add3_u32 v2, v95, v2, s80
	v_bfe_u32 v105, v99, 16, 1
	v_pk_mul_f32 v[32:33], v[32:33], v[106:107] op_sel_hi:[1,0]
	v_lshrrev_b32_e32 v2, 16, v2
	v_add3_u32 v105, v99, v105, s80
	v_pk_mul_f32 v[40:41], v[40:41], v[106:107] op_sel:[0,1]
	v_and_or_b32 v105, v105, s85, v2
	v_bfe_u32 v2, v32, 16, 1
	global_store_dwordx4 v[4:5], v[102:105], off offset:1024 nt
	v_add3_u32 v2, v32, v2, s80
	v_pk_mul_f32 v[52:53], v[52:53], v[108:109] op_sel_hi:[1,0]
	v_bfe_u32 v102, v40, 16, 1
	v_lshrrev_b32_e32 v2, 16, v2
	v_add3_u32 v102, v40, v102, s80
	v_and_or_b32 v102, v102, s85, v2
	v_bfe_u32 v2, v52, 16, 1
	v_add3_u32 v2, v52, v2, s80
	v_bfe_u32 v103, v36, 16, 1
	v_lshrrev_b32_e32 v2, 16, v2
	v_add3_u32 v103, v36, v103, s80
	v_and_or_b32 v103, v103, s85, v2
	v_bfe_u32 v2, v72, 16, 1
	v_add3_u32 v2, v72, v2, s80
	v_bfe_u32 v104, v76, 16, 1
	v_lshrrev_b32_e32 v2, 16, v2
	v_add3_u32 v104, v76, v104, s80
	v_and_or_b32 v104, v104, s85, v2
	v_bfe_u32 v2, v96, 16, 1
	v_add3_u32 v2, v96, v2, s80
	v_bfe_u32 v105, v100, 16, 1
	v_lshrrev_b32_e32 v2, 16, v2
	v_add3_u32 v105, v100, v105, s80
	v_and_or_b32 v105, v105, s85, v2
	v_bfe_u32 v2, v33, 16, 1
	global_store_dwordx4 v[4:5], v[102:105], off offset:2048 nt
	v_add3_u32 v2, v33, v2, s80
	v_lshrrev_b32_e32 v2, 16, v2
	v_bfe_u32 v102, v41, 16, 1
	v_add3_u32 v102, v41, v102, s80
	v_and_or_b32 v102, v102, s85, v2
	v_bfe_u32 v2, v53, 16, 1
	v_add3_u32 v2, v53, v2, s80
	v_bfe_u32 v103, v37, 16, 1
	v_lshrrev_b32_e32 v2, 16, v2
	v_add3_u32 v103, v37, v103, s80
	v_and_or_b32 v103, v103, s85, v2
	v_bfe_u32 v2, v73, 16, 1
	v_add3_u32 v2, v73, v2, s80
	v_bfe_u32 v104, v77, 16, 1
	v_lshrrev_b32_e32 v2, 16, v2
	v_add3_u32 v104, v77, v104, s80
	v_and_or_b32 v104, v104, s85, v2
	v_bfe_u32 v2, v97, 16, 1
	v_add3_u32 v2, v97, v2, s80
	v_bfe_u32 v105, v101, 16, 1
	v_lshrrev_b32_e32 v2, 16, v2
	v_add3_u32 v105, v101, v105, s80
	v_and_or_b32 v105, v105, s85, v2
	global_store_dwordx4 v[4:5], v[102:105], off offset:3072 nt
	s_andn2_b64 vcc, exec, s[16:17]
	s_cbranch_vccz .LBB0_3236

.LBB0_3236:
	s_ashr_i32 s4, s26, 31
	s_lshr_b32 s4, s4, 25
	s_add_i32 s26, s26, s4
	s_ashr_i32 s4, s26, 7
	v_lshl_or_b32 v4, s4, 6, v231
	v_ashrrev_i32_e32 v5, 31, v4
	v_lshl_add_u64 v[106:107], v[4:5], 2, s[6:7]
	global_load_dwordx4 v[102:105], v[106:107], off offset:2064
	s_nop 0
	global_load_dwordx4 v[106:109], v[106:107], off offset:2048
	s_lshl_b32 s4, s4, 12
	s_waitcnt vmcnt(1)
	v_pk_mul_f32 v[64:65], v[64:65], v[102:103] op_sel_hi:[1,0]
	v_pk_mul_f32 v[62:63], v[62:63], v[102:103] op_sel_hi:[1,0]
	v_pk_mul_f32 v[68:69], v[68:69], v[102:103] op_sel:[0,1]
	v_pk_mul_f32 v[66:67], v[66:67], v[102:103] op_sel:[0,1]
	v_subrev_u32_e32 v102, s4, v144
	s_waitcnt vmcnt(0)
	v_mov_b32_e32 v2, v109
	v_ashrrev_i32_e32 v103, 31, v102
	v_pk_mul_f32 v[22:23], v[22:23], v[106:107] op_sel_hi:[1,0]
	v_pk_mul_f32 v[20:21], v[20:21], v[2:3] op_sel_hi:[1,0]
	v_pk_mul_f32 v[18:19], v[18:19], v[2:3] op_sel_hi:[1,0]
	v_mov_b32_e32 v2, v105
	v_lshlrev_b64 v[102:103], 10, v[102:103]
	v_pk_mul_f32 v[26:27], v[26:27], v[106:107] op_sel:[0,1]
	v_pk_mul_f32 v[92:93], v[92:93], v[2:3] op_sel_hi:[1,0]
	v_pk_mul_f32 v[90:91], v[90:91], v[2:3] op_sel_hi:[1,0]
	v_lshl_add_u64 v[102:103], s[8:9], 0, v[102:103]
	v_bfe_u32 v2, v22, 16, 1
	v_lshl_add_u64 v[4:5], v[4:5], 1, v[102:103]
	v_add3_u32 v2, v22, v2, s80
	v_bfe_u32 v102, v26, 16, 1
	v_pk_mul_f32 v[46:47], v[46:47], v[108:109] op_sel_hi:[1,0]
	v_lshrrev_b32_e32 v2, 16, v2
	v_add3_u32 v102, v26, v102, s80
	v_and_or_b32 v102, v102, s85, v2
	v_bfe_u32 v2, v46, 16, 1
	v_add3_u32 v2, v46, v2, s80
	v_bfe_u32 v103, v18, 16, 1
	v_lshrrev_b32_e32 v2, 16, v2
	v_add3_u32 v103, v18, v103, s80
	v_and_or_b32 v103, v103, s85, v2
	v_bfe_u32 v2, v62, 16, 1
	v_pk_mul_f32 v[88:89], v[88:89], v[104:105] op_sel_hi:[1,0]
	v_pk_mul_f32 v[86:87], v[86:87], v[104:105] op_sel_hi:[1,0]
	v_add3_u32 v2, v62, v2, s80
	v_bfe_u32 v104, v66, 16, 1
	v_lshrrev_b32_e32 v2, 16, v2
	v_add3_u32 v104, v66, v104, s80
	v_and_or_b32 v104, v104, s85, v2
	v_bfe_u32 v2, v86, 16, 1
	v_add3_u32 v2, v86, v2, s80
	v_bfe_u32 v105, v90, 16, 1
	v_lshrrev_b32_e32 v2, 16, v2
	v_add3_u32 v105, v90, v105, s80
	v_and_or_b32 v105, v105, s85, v2
	v_bfe_u32 v2, v23, 16, 1
	global_store_dwordx4 v[4:5], v[102:105], off nt
	v_add3_u32 v2, v23, v2, s80
	v_lshrrev_b32_e32 v2, 16, v2
	v_bfe_u32 v102, v27, 16, 1
	v_add3_u32 v102, v27, v102, s80
	v_and_or_b32 v102, v102, s85, v2
	v_bfe_u32 v2, v47, 16, 1
	v_add3_u32 v2, v47, v2, s80
	v_bfe_u32 v103, v19, 16, 1
	v_lshrrev_b32_e32 v2, 16, v2
	v_add3_u32 v103, v19, v103, s80
	v_and_or_b32 v103, v103, s85, v2
	v_bfe_u32 v2, v63, 16, 1
	v_add3_u32 v2, v63, v2, s80
	v_bfe_u32 v104, v67, 16, 1
	v_lshrrev_b32_e32 v2, 16, v2
	v_add3_u32 v104, v67, v104, s80
	v_and_or_b32 v104, v104, s85, v2
	v_bfe_u32 v2, v87, 16, 1
	v_add3_u32 v2, v87, v2, s80
	v_bfe_u32 v105, v91, 16, 1
	v_pk_mul_f32 v[24:25], v[24:25], v[106:107] op_sel_hi:[1,0]
	v_lshrrev_b32_e32 v2, 16, v2
	v_add3_u32 v105, v91, v105, s80
	v_pk_mul_f32 v[28:29], v[28:29], v[106:107] op_sel:[0,1]
	v_and_or_b32 v105, v105, s85, v2
	v_bfe_u32 v2, v24, 16, 1
	global_store_dwordx4 v[4:5], v[102:105], off offset:1024 nt
	v_add3_u32 v2, v24, v2, s80
	v_pk_mul_f32 v[48:49], v[48:49], v[108:109] op_sel_hi:[1,0]
	v_bfe_u32 v102, v28, 16, 1
	v_lshrrev_b32_e32 v2, 16, v2
	v_add3_u32 v102, v28, v102, s80
	v_and_or_b32 v102, v102, s85, v2
	v_bfe_u32 v2, v48, 16, 1
	v_add3_u32 v2, v48, v2, s80
	v_bfe_u32 v103, v20, 16, 1
	v_lshrrev_b32_e32 v2, 16, v2
	v_add3_u32 v103, v20, v103, s80
	v_and_or_b32 v103, v103, s85, v2
	v_bfe_u32 v2, v64, 16, 1
	v_add3_u32 v2, v64, v2, s80
	v_bfe_u32 v104, v68, 16, 1
	v_lshrrev_b32_e32 v2, 16, v2
	v_add3_u32 v104, v68, v104, s80
	v_and_or_b32 v104, v104, s85, v2
	v_bfe_u32 v2, v88, 16, 1
	v_add3_u32 v2, v88, v2, s80
	v_bfe_u32 v105, v92, 16, 1
	v_lshrrev_b32_e32 v2, 16, v2
	v_add3_u32 v105, v92, v105, s80
	v_and_or_b32 v105, v105, s85, v2
	v_bfe_u32 v2, v25, 16, 1
	global_store_dwordx4 v[4:5], v[102:105], off offset:2048 nt
	v_add3_u32 v2, v25, v2, s80
	v_lshrrev_b32_e32 v2, 16, v2
	v_bfe_u32 v102, v29, 16, 1
	v_add3_u32 v102, v29, v102, s80
	v_and_or_b32 v102, v102, s85, v2
	v_bfe_u32 v2, v49, 16, 1
	v_add3_u32 v2, v49, v2, s80
	v_bfe_u32 v103, v21, 16, 1
	v_lshrrev_b32_e32 v2, 16, v2
	v_add3_u32 v103, v21, v103, s80
	v_and_or_b32 v103, v103, s85, v2
	v_bfe_u32 v2, v65, 16, 1
	v_add3_u32 v2, v65, v2, s80
	v_bfe_u32 v104, v69, 16, 1
	v_lshrrev_b32_e32 v2, 16, v2
	v_add3_u32 v104, v69, v104, s80
	v_and_or_b32 v104, v104, s85, v2
	v_bfe_u32 v2, v89, 16, 1
	v_add3_u32 v2, v89, v2, s80
	v_bfe_u32 v105, v93, 16, 1
	v_lshrrev_b32_e32 v2, 16, v2
	v_add3_u32 v105, v93, v105, s80
	v_and_or_b32 v105, v105, s85, v2
	global_store_dwordx4 v[4:5], v[102:105], off offset:3072 nt
	s_andn2_b64 vcc, exec, s[12:13]
	s_cbranch_vccnz .LBB0_3193
.LBB0_3237:
	s_ashr_i32 s4, s15, 31
	s_lshr_b32 s4, s4, 25
	s_add_i32 s15, s15, s4
	s_ashr_i32 s4, s15, 7
	v_lshl_or_b32 v4, s4, 6, v231
	v_ashrrev_i32_e32 v5, 31, v4
	v_lshl_add_u64 v[106:107], v[4:5], 2, s[6:7]
	global_load_dwordx4 v[102:105], v[106:107], off offset:2064
	s_nop 0
	global_load_dwordx4 v[106:109], v[106:107], off offset:2048
	s_lshl_b32 s4, s4, 12
	s_waitcnt vmcnt(1)
	v_pk_mul_f32 v[56:57], v[56:57], v[102:103] op_sel_hi:[1,0]
	v_pk_mul_f32 v[54:55], v[54:55], v[102:103] op_sel_hi:[1,0]
	v_pk_mul_f32 v[60:61], v[60:61], v[102:103] op_sel:[0,1]
	v_pk_mul_f32 v[58:59], v[58:59], v[102:103] op_sel:[0,1]
	v_subrev_u32_e32 v102, s4, v143
	s_waitcnt vmcnt(0)
	v_mov_b32_e32 v2, v109
	v_ashrrev_i32_e32 v103, 31, v102
	v_pk_mul_f32 v[6:7], v[6:7], v[106:107] op_sel_hi:[1,0]
	v_pk_mul_f32 v[12:13], v[12:13], v[2:3] op_sel_hi:[1,0]
	v_pk_mul_f32 v[10:11], v[10:11], v[2:3] op_sel_hi:[1,0]
	v_mov_b32_e32 v2, v105
	v_lshlrev_b64 v[102:103], 10, v[102:103]
	v_pk_mul_f32 v[14:15], v[14:15], v[106:107] op_sel:[0,1]
	v_pk_mul_f32 v[84:85], v[84:85], v[2:3] op_sel_hi:[1,0]
	v_pk_mul_f32 v[82:83], v[82:83], v[2:3] op_sel_hi:[1,0]
	v_lshl_add_u64 v[102:103], s[8:9], 0, v[102:103]
	v_bfe_u32 v2, v6, 16, 1
	v_lshl_add_u64 v[4:5], v[4:5], 1, v[102:103]
	v_add3_u32 v2, v6, v2, s80
	v_bfe_u32 v102, v14, 16, 1
	v_pk_mul_f32 v[42:43], v[42:43], v[108:109] op_sel_hi:[1,0]
	v_lshrrev_b32_e32 v2, 16, v2
	v_add3_u32 v102, v14, v102, s80
	v_and_or_b32 v102, v102, s85, v2
	v_bfe_u32 v2, v42, 16, 1
	v_add3_u32 v2, v42, v2, s80
	v_bfe_u32 v103, v10, 16, 1
	v_lshrrev_b32_e32 v2, 16, v2
	v_add3_u32 v103, v10, v103, s80
	v_and_or_b32 v103, v103, s85, v2
	v_bfe_u32 v2, v54, 16, 1
	v_pk_mul_f32 v[80:81], v[80:81], v[104:105] op_sel_hi:[1,0]
	v_pk_mul_f32 v[78:79], v[78:79], v[104:105] op_sel_hi:[1,0]
	v_add3_u32 v2, v54, v2, s80
	v_bfe_u32 v104, v58, 16, 1
	v_lshrrev_b32_e32 v2, 16, v2
	v_add3_u32 v104, v58, v104, s80
	v_and_or_b32 v104, v104, s85, v2
	v_bfe_u32 v2, v78, 16, 1
	v_add3_u32 v2, v78, v2, s80
	v_bfe_u32 v105, v82, 16, 1
	v_lshrrev_b32_e32 v2, 16, v2
	v_add3_u32 v105, v82, v105, s80
	v_and_or_b32 v105, v105, s85, v2
	v_bfe_u32 v2, v7, 16, 1
	global_store_dwordx4 v[4:5], v[102:105], off nt
	v_add3_u32 v2, v7, v2, s80
	v_lshrrev_b32_e32 v2, 16, v2
	v_bfe_u32 v102, v15, 16, 1
	v_add3_u32 v102, v15, v102, s80
	v_and_or_b32 v102, v102, s85, v2
	v_bfe_u32 v2, v43, 16, 1
	v_add3_u32 v2, v43, v2, s80
	v_bfe_u32 v103, v11, 16, 1
	v_lshrrev_b32_e32 v2, 16, v2
	v_add3_u32 v103, v11, v103, s80
	v_and_or_b32 v103, v103, s85, v2
	v_bfe_u32 v2, v55, 16, 1
	v_add3_u32 v2, v55, v2, s80
	v_bfe_u32 v104, v59, 16, 1
	v_lshrrev_b32_e32 v2, 16, v2
	v_add3_u32 v104, v59, v104, s80
	v_and_or_b32 v104, v104, s85, v2
	v_bfe_u32 v2, v79, 16, 1
	v_add3_u32 v2, v79, v2, s80
	v_bfe_u32 v105, v83, 16, 1
	v_pk_mul_f32 v[8:9], v[8:9], v[106:107] op_sel_hi:[1,0]
	v_lshrrev_b32_e32 v2, 16, v2
	v_add3_u32 v105, v83, v105, s80
	v_pk_mul_f32 v[16:17], v[16:17], v[106:107] op_sel:[0,1]
	v_and_or_b32 v105, v105, s85, v2
	v_bfe_u32 v2, v8, 16, 1
	global_store_dwordx4 v[4:5], v[102:105], off offset:1024 nt
	v_add3_u32 v2, v8, v2, s80
	v_pk_mul_f32 v[44:45], v[44:45], v[108:109] op_sel_hi:[1,0]
	v_bfe_u32 v102, v16, 16, 1
	v_lshrrev_b32_e32 v2, 16, v2
	v_add3_u32 v102, v16, v102, s80
	v_and_or_b32 v102, v102, s85, v2
	v_bfe_u32 v2, v44, 16, 1
	v_add3_u32 v2, v44, v2, s80
	v_bfe_u32 v103, v12, 16, 1
	v_lshrrev_b32_e32 v2, 16, v2
	v_add3_u32 v103, v12, v103, s80
	v_and_or_b32 v103, v103, s85, v2
	v_bfe_u32 v2, v56, 16, 1
	v_add3_u32 v2, v56, v2, s80
	v_bfe_u32 v104, v60, 16, 1
	v_lshrrev_b32_e32 v2, 16, v2
	v_add3_u32 v104, v60, v104, s80
	v_and_or_b32 v104, v104, s85, v2
	v_bfe_u32 v2, v80, 16, 1
	v_add3_u32 v2, v80, v2, s80
	v_bfe_u32 v105, v84, 16, 1
	v_lshrrev_b32_e32 v2, 16, v2
	v_add3_u32 v105, v84, v105, s80
	v_and_or_b32 v105, v105, s85, v2
	v_bfe_u32 v2, v9, 16, 1
	global_store_dwordx4 v[4:5], v[102:105], off offset:2048 nt
	v_add3_u32 v2, v9, v2, s80
	v_lshrrev_b32_e32 v2, 16, v2
	v_bfe_u32 v102, v17, 16, 1
	v_add3_u32 v102, v17, v102, s80
	v_and_or_b32 v102, v102, s85, v2
	v_bfe_u32 v2, v45, 16, 1
	v_add3_u32 v2, v45, v2, s80
	v_bfe_u32 v103, v13, 16, 1
	v_lshrrev_b32_e32 v2, 16, v2
	v_add3_u32 v103, v13, v103, s80
	v_and_or_b32 v103, v103, s85, v2
	v_bfe_u32 v2, v57, 16, 1
	v_add3_u32 v2, v57, v2, s80
	v_bfe_u32 v104, v61, 16, 1
	v_lshrrev_b32_e32 v2, 16, v2
	v_add3_u32 v104, v61, v104, s80
	v_and_or_b32 v104, v104, s85, v2
	v_bfe_u32 v2, v81, 16, 1
	v_add3_u32 v2, v81, v2, s80
	v_bfe_u32 v105, v85, 16, 1
	v_lshrrev_b32_e32 v2, 16, v2
	v_add3_u32 v105, v85, v105, s80
	v_and_or_b32 v105, v105, s85, v2
	global_store_dwordx4 v[4:5], v[102:105], off offset:3072 nt
	s_branch .LBB0_3193

.LBB0_3284:
	s_waitcnt vmcnt(1)
	v_bfe_u32 v2, v104, 16, 1
	v_mov_b64_e32 v[138:139], s[16:17]
	v_add3_u32 v2, v104, v2, s80
	s_waitcnt vmcnt(0)
	v_bfe_u32 v104, v100, 16, 1
	v_mad_i64_i32 v[138:139], s[4:5], v137, s91, v[138:139]
	v_lshrrev_b32_e32 v2, 16, v2
	v_add3_u32 v100, v100, v104, s80
	v_lshl_add_u64 v[132:133], v[132:133], 1, v[138:139]
	v_and_or_b32 v138, v100, s85, v2
	v_bfe_u32 v2, v116, 16, 1
	v_add3_u32 v2, v116, v2, s80
	v_bfe_u32 v100, v112, 16, 1
	v_lshrrev_b32_e32 v2, 16, v2
	v_add3_u32 v100, v112, v100, s80
	v_and_or_b32 v139, v100, s85, v2
	v_bfe_u32 v2, v120, 16, 1
	v_add3_u32 v2, v120, v2, s80
	v_bfe_u32 v100, v108, 16, 1
	v_lshrrev_b32_e32 v2, 16, v2
	v_add3_u32 v100, v108, v100, s80
	v_and_or_b32 v140, v100, s85, v2
	v_bfe_u32 v2, v128, 16, 1
	v_add3_u32 v2, v128, v2, s80
	v_bfe_u32 v100, v124, 16, 1
	v_lshrrev_b32_e32 v2, 16, v2
	v_add3_u32 v100, v124, v100, s80
	v_and_or_b32 v141, v100, s85, v2
	v_bfe_u32 v2, v105, 16, 1
	v_add3_u32 v2, v105, v2, s80
	v_bfe_u32 v100, v101, 16, 1
	v_lshrrev_b32_e32 v2, 16, v2
	v_add3_u32 v100, v101, v100, s80
	global_store_dwordx4 v[132:133], v[138:141], off nt
	s_nop 1
	v_and_or_b32 v138, v100, s85, v2
	v_bfe_u32 v2, v117, 16, 1
	v_add3_u32 v2, v117, v2, s80
	v_bfe_u32 v100, v113, 16, 1
	v_lshrrev_b32_e32 v2, 16, v2
	v_add3_u32 v100, v113, v100, s80
	v_and_or_b32 v139, v100, s85, v2
	v_bfe_u32 v2, v121, 16, 1
	v_add3_u32 v2, v121, v2, s80
	v_bfe_u32 v100, v109, 16, 1
	v_lshrrev_b32_e32 v2, 16, v2
	v_add3_u32 v100, v109, v100, s80
	v_and_or_b32 v140, v100, s85, v2
	v_bfe_u32 v2, v129, 16, 1
	v_add3_u32 v2, v129, v2, s80
	v_bfe_u32 v100, v125, 16, 1
	v_lshrrev_b32_e32 v2, 16, v2
	v_add3_u32 v100, v125, v100, s80
	v_and_or_b32 v141, v100, s85, v2
	v_add_co_u32_e32 v100, vcc, s91, v132
	v_bfe_u32 v2, v106, 16, 1
	s_nop 0
	v_addc_co_u32_e32 v101, vcc, 0, v133, vcc
	global_store_dwordx4 v[100:101], v[138:141], off nt
	v_add3_u32 v2, v106, v2, s80
	v_bfe_u32 v100, v102, 16, 1
	v_lshrrev_b32_e32 v2, 16, v2
	v_add3_u32 v100, v102, v100, s80
	v_and_or_b32 v138, v100, s85, v2
	v_bfe_u32 v2, v118, 16, 1
	v_add3_u32 v2, v118, v2, s80
	v_bfe_u32 v100, v114, 16, 1
	v_lshrrev_b32_e32 v2, 16, v2
	v_add3_u32 v100, v114, v100, s80
	v_and_or_b32 v139, v100, s85, v2
	v_bfe_u32 v2, v122, 16, 1
	v_add3_u32 v2, v122, v2, s80
	v_bfe_u32 v100, v110, 16, 1
	v_lshrrev_b32_e32 v2, 16, v2
	v_add3_u32 v100, v110, v100, s80
	v_and_or_b32 v140, v100, s85, v2
	v_bfe_u32 v2, v130, 16, 1
	v_add3_u32 v2, v130, v2, s80
	v_bfe_u32 v100, v126, 16, 1
	v_lshrrev_b32_e32 v2, 16, v2
	v_add3_u32 v100, v126, v100, s80
	v_and_or_b32 v141, v100, s85, v2
	v_add_co_u32_e32 v100, vcc, s87, v132
	v_bfe_u32 v2, v107, 16, 1
	s_nop 0
	v_addc_co_u32_e32 v101, vcc, 0, v133, vcc
	global_store_dwordx4 v[100:101], v[138:141], off nt
	v_add3_u32 v2, v107, v2, s80
	v_bfe_u32 v100, v103, 16, 1
	v_lshrrev_b32_e32 v2, 16, v2
	v_add3_u32 v100, v103, v100, s80
	v_and_or_b32 v100, v100, s85, v2
	v_bfe_u32 v2, v119, 16, 1
	v_add3_u32 v2, v119, v2, s80
	v_bfe_u32 v101, v115, 16, 1
	v_lshrrev_b32_e32 v2, 16, v2
	v_add3_u32 v101, v115, v101, s80
	v_and_or_b32 v101, v101, s85, v2
	v_bfe_u32 v2, v123, 16, 1
	v_add3_u32 v2, v123, v2, s80
	v_bfe_u32 v102, v111, 16, 1
	v_lshrrev_b32_e32 v2, 16, v2
	v_add3_u32 v102, v111, v102, s80
	v_and_or_b32 v102, v102, s85, v2
	v_bfe_u32 v2, v131, 16, 1
	v_add3_u32 v2, v131, v2, s80
	v_bfe_u32 v103, v127, 16, 1
	v_add_co_u32_e32 v104, vcc, 0x9000, v132
	v_lshrrev_b32_e32 v2, 16, v2
	v_add3_u32 v103, v127, v103, s80
	v_addc_co_u32_e32 v105, vcc, 0, v133, vcc
	v_and_or_b32 v103, v103, s85, v2
	s_andn2_b64 vcc, exec, s[18:19]
	global_store_dwordx4 v[104:105], v[100:103], off nt
	s_cbranch_vccnz .LBB0_3287
	s_ashr_i32 s4, s14, 31
	s_lshr_b32 s4, s4, 25
	s_add_i32 s14, s14, s4
	s_ashr_i32 s4, s14, 7
	v_lshl_or_b32 v100, s4, 6, v231
	v_add_u32_e32 v2, s0, v136
	s_lshl_b32 s4, s4, 12
	v_subrev_u32_e32 v2, s4, v2
	v_mov_b64_e32 v[102:103], s[16:17]
	v_ashrrev_i32_e32 v101, 31, v100
	v_mad_i64_i32 v[102:103], s[4:5], v2, s91, v[102:103]
	v_bfe_u32 v2, v36, 16, 1
	v_lshl_add_u64 v[104:105], v[100:101], 1, v[102:103]
	v_add3_u32 v2, v36, v2, s80
	v_bfe_u32 v100, v32, 16, 1
	v_lshrrev_b32_e32 v2, 16, v2
	v_add3_u32 v100, v32, v100, s80
	v_and_or_b32 v100, v100, s85, v2
	v_bfe_u32 v2, v64, 16, 1
	v_add3_u32 v2, v64, v2, s80
	v_bfe_u32 v101, v60, 16, 1
	v_lshrrev_b32_e32 v2, 16, v2
	v_add3_u32 v101, v60, v101, s80
	v_and_or_b32 v101, v101, s85, v2
	v_bfe_u32 v2, v80, 16, 1
	v_add3_u32 v2, v80, v2, s80
	v_bfe_u32 v102, v56, 16, 1
	v_lshrrev_b32_e32 v2, 16, v2
	v_add3_u32 v102, v56, v102, s80
	v_and_or_b32 v102, v102, s85, v2
	v_bfe_u32 v2, v92, 16, 1
	v_add3_u32 v2, v92, v2, s80
	v_bfe_u32 v103, v96, 16, 1
	v_lshrrev_b32_e32 v2, 16, v2
	v_add3_u32 v103, v96, v103, s80
	v_and_or_b32 v103, v103, s85, v2
	v_bfe_u32 v2, v37, 16, 1
	global_store_dwordx4 v[104:105], v[100:103], off nt
	v_add3_u32 v2, v37, v2, s80
	v_lshrrev_b32_e32 v2, 16, v2
	v_bfe_u32 v100, v33, 16, 1
	v_add3_u32 v100, v33, v100, s80
	v_and_or_b32 v100, v100, s85, v2
	v_bfe_u32 v2, v65, 16, 1
	v_add3_u32 v2, v65, v2, s80
	v_bfe_u32 v101, v61, 16, 1
	v_lshrrev_b32_e32 v2, 16, v2
	v_add3_u32 v101, v61, v101, s80
	v_and_or_b32 v101, v101, s85, v2
	v_bfe_u32 v2, v81, 16, 1
	v_add3_u32 v2, v81, v2, s80
	v_bfe_u32 v102, v57, 16, 1
	v_lshrrev_b32_e32 v2, 16, v2
	v_add3_u32 v102, v57, v102, s80
	v_and_or_b32 v102, v102, s85, v2
	v_bfe_u32 v2, v93, 16, 1
	v_add3_u32 v2, v93, v2, s80
	v_bfe_u32 v103, v97, 16, 1
	v_lshrrev_b32_e32 v2, 16, v2
	v_add3_u32 v103, v97, v103, s80
	v_add_co_u32_e32 v106, vcc, s91, v104
	v_and_or_b32 v103, v103, s85, v2
	s_nop 0
	v_addc_co_u32_e32 v107, vcc, 0, v105, vcc
	v_bfe_u32 v2, v38, 16, 1
	global_store_dwordx4 v[106:107], v[100:103], off nt
	v_add3_u32 v2, v38, v2, s80
	v_lshrrev_b32_e32 v2, 16, v2
	v_bfe_u32 v100, v34, 16, 1
	v_add3_u32 v100, v34, v100, s80
	v_and_or_b32 v100, v100, s85, v2
	v_bfe_u32 v2, v66, 16, 1
	v_add3_u32 v2, v66, v2, s80
	v_bfe_u32 v101, v62, 16, 1
	v_lshrrev_b32_e32 v2, 16, v2
	v_add3_u32 v101, v62, v101, s80
	v_and_or_b32 v101, v101, s85, v2
	v_bfe_u32 v2, v82, 16, 1
	v_add3_u32 v2, v82, v2, s80
	v_bfe_u32 v102, v58, 16, 1
	v_lshrrev_b32_e32 v2, 16, v2
	v_add3_u32 v102, v58, v102, s80
	v_and_or_b32 v102, v102, s85, v2
	v_bfe_u32 v2, v94, 16, 1
	v_add3_u32 v2, v94, v2, s80
	v_bfe_u32 v103, v98, 16, 1
	v_lshrrev_b32_e32 v2, 16, v2
	v_add3_u32 v103, v98, v103, s80
	v_add_co_u32_e32 v106, vcc, s87, v104
	v_and_or_b32 v103, v103, s85, v2
	s_nop 0
	v_addc_co_u32_e32 v107, vcc, 0, v105, vcc
	v_bfe_u32 v2, v39, 16, 1
	global_store_dwordx4 v[106:107], v[100:103], off nt
	v_add3_u32 v2, v39, v2, s80
	v_lshrrev_b32_e32 v2, 16, v2
	v_bfe_u32 v100, v35, 16, 1
	v_add3_u32 v100, v35, v100, s80
	v_and_or_b32 v100, v100, s85, v2
	v_bfe_u32 v2, v67, 16, 1
	v_add3_u32 v2, v67, v2, s80
	v_bfe_u32 v101, v63, 16, 1
	v_lshrrev_b32_e32 v2, 16, v2
	v_add3_u32 v101, v63, v101, s80
	v_and_or_b32 v101, v101, s85, v2
	v_bfe_u32 v2, v83, 16, 1
	v_add3_u32 v2, v83, v2, s80
	v_bfe_u32 v102, v59, 16, 1
	v_lshrrev_b32_e32 v2, 16, v2
	v_add3_u32 v102, v59, v102, s80
	v_and_or_b32 v102, v102, s85, v2
	v_bfe_u32 v2, v95, 16, 1
	v_add3_u32 v2, v95, v2, s80
	v_bfe_u32 v103, v99, 16, 1
	v_lshrrev_b32_e32 v2, 16, v2
	v_add3_u32 v103, v99, v103, s80
	v_add_co_u32_e32 v104, vcc, 0x9000, v104
	v_and_or_b32 v103, v103, s85, v2
	s_nop 0
	v_addc_co_u32_e32 v105, vcc, 0, v105, vcc
	global_store_dwordx4 v[104:105], v[100:103], off nt
	s_andn2_b64 vcc, exec, s[20:21]
	s_cbranch_vccz .LBB0_3288

.LBB0_3288:
	s_ashr_i32 s4, s15, 31
	s_lshr_b32 s4, s4, 25
	s_add_i32 s15, s15, s4
	s_ashr_i32 s4, s15, 7
	v_lshl_or_b32 v100, s4, 6, v231
	v_add_u32_e32 v2, s0, v134
	s_lshl_b32 s4, s4, 12
	v_subrev_u32_e32 v2, s4, v2
	v_mov_b64_e32 v[102:103], s[16:17]
	v_ashrrev_i32_e32 v101, 31, v100
	v_mad_i64_i32 v[102:103], s[4:5], v2, s91, v[102:103]
	v_bfe_u32 v2, v20, 16, 1
	v_lshl_add_u64 v[104:105], v[100:101], 1, v[102:103]
	v_add3_u32 v2, v20, v2, s80
	v_bfe_u32 v100, v12, 16, 1
	v_lshrrev_b32_e32 v2, 16, v2
	v_add3_u32 v100, v12, v100, s80
	v_and_or_b32 v100, v100, s85, v2
	v_bfe_u32 v2, v48, 16, 1
	v_add3_u32 v2, v48, v2, s80
	v_bfe_u32 v101, v44, 16, 1
	v_lshrrev_b32_e32 v2, 16, v2
	v_add3_u32 v101, v44, v101, s80
	v_and_or_b32 v101, v101, s85, v2
	v_bfe_u32 v2, v68, 16, 1
	v_add3_u32 v2, v68, v2, s80
	v_bfe_u32 v102, v40, 16, 1
	v_lshrrev_b32_e32 v2, 16, v2
	v_add3_u32 v102, v40, v102, s80
	v_and_or_b32 v102, v102, s85, v2
	v_bfe_u32 v2, v84, 16, 1
	v_add3_u32 v2, v84, v2, s80
	v_bfe_u32 v103, v88, 16, 1
	v_lshrrev_b32_e32 v2, 16, v2
	v_add3_u32 v103, v88, v103, s80
	v_and_or_b32 v103, v103, s85, v2
	v_bfe_u32 v2, v21, 16, 1
	global_store_dwordx4 v[104:105], v[100:103], off nt
	v_add3_u32 v2, v21, v2, s80
	v_lshrrev_b32_e32 v2, 16, v2
	v_bfe_u32 v100, v13, 16, 1
	v_add3_u32 v100, v13, v100, s80
	v_and_or_b32 v100, v100, s85, v2
	v_bfe_u32 v2, v49, 16, 1
	v_add3_u32 v2, v49, v2, s80
	v_bfe_u32 v101, v45, 16, 1
	v_lshrrev_b32_e32 v2, 16, v2
	v_add3_u32 v101, v45, v101, s80
	v_and_or_b32 v101, v101, s85, v2
	v_bfe_u32 v2, v69, 16, 1
	v_add3_u32 v2, v69, v2, s80
	v_bfe_u32 v102, v41, 16, 1
	v_lshrrev_b32_e32 v2, 16, v2
	v_add3_u32 v102, v41, v102, s80
	v_and_or_b32 v102, v102, s85, v2
	v_bfe_u32 v2, v85, 16, 1
	v_add3_u32 v2, v85, v2, s80
	v_bfe_u32 v103, v89, 16, 1
	v_lshrrev_b32_e32 v2, 16, v2
	v_add3_u32 v103, v89, v103, s80
	v_add_co_u32_e32 v106, vcc, s91, v104
	v_and_or_b32 v103, v103, s85, v2
	s_nop 0
	v_addc_co_u32_e32 v107, vcc, 0, v105, vcc
	v_bfe_u32 v2, v22, 16, 1
	global_store_dwordx4 v[106:107], v[100:103], off nt
	v_add3_u32 v2, v22, v2, s80
	v_lshrrev_b32_e32 v2, 16, v2
	v_bfe_u32 v100, v14, 16, 1
	v_add3_u32 v100, v14, v100, s80
	v_and_or_b32 v100, v100, s85, v2
	v_bfe_u32 v2, v50, 16, 1
	v_add3_u32 v2, v50, v2, s80
	v_bfe_u32 v101, v46, 16, 1
	v_lshrrev_b32_e32 v2, 16, v2
	v_add3_u32 v101, v46, v101, s80
	v_and_or_b32 v101, v101, s85, v2
	v_bfe_u32 v2, v70, 16, 1
	v_add3_u32 v2, v70, v2, s80
	v_bfe_u32 v102, v42, 16, 1
	v_lshrrev_b32_e32 v2, 16, v2
	v_add3_u32 v102, v42, v102, s80
	v_and_or_b32 v102, v102, s85, v2
	v_bfe_u32 v2, v86, 16, 1
	v_add3_u32 v2, v86, v2, s80
	v_bfe_u32 v103, v90, 16, 1
	v_lshrrev_b32_e32 v2, 16, v2
	v_add3_u32 v103, v90, v103, s80
	v_add_co_u32_e32 v106, vcc, s87, v104
	v_and_or_b32 v103, v103, s85, v2
	s_nop 0
	v_addc_co_u32_e32 v107, vcc, 0, v105, vcc
	v_bfe_u32 v2, v23, 16, 1
	global_store_dwordx4 v[106:107], v[100:103], off nt
	v_add3_u32 v2, v23, v2, s80
	v_lshrrev_b32_e32 v2, 16, v2
	v_bfe_u32 v100, v15, 16, 1
	v_add3_u32 v100, v15, v100, s80
	v_and_or_b32 v100, v100, s85, v2
	v_bfe_u32 v2, v51, 16, 1
	v_add3_u32 v2, v51, v2, s80
	v_bfe_u32 v101, v47, 16, 1
	v_lshrrev_b32_e32 v2, 16, v2
	v_add3_u32 v101, v47, v101, s80
	v_and_or_b32 v101, v101, s85, v2
	v_bfe_u32 v2, v71, 16, 1
	v_add3_u32 v2, v71, v2, s80
	v_bfe_u32 v102, v43, 16, 1
	v_lshrrev_b32_e32 v2, 16, v2
	v_add3_u32 v102, v43, v102, s80
	v_and_or_b32 v102, v102, s85, v2
	v_bfe_u32 v2, v87, 16, 1
	v_add3_u32 v2, v87, v2, s80
	v_bfe_u32 v103, v91, 16, 1
	v_lshrrev_b32_e32 v2, 16, v2
	v_add3_u32 v103, v91, v103, s80
	v_add_co_u32_e32 v104, vcc, 0x9000, v104
	v_and_or_b32 v103, v103, s85, v2
	s_nop 0
	v_addc_co_u32_e32 v105, vcc, 0, v105, vcc
	global_store_dwordx4 v[104:105], v[100:103], off nt
	s_andn2_b64 vcc, exec, s[22:23]
	s_cbranch_vccnz .LBB0_3240
.LBB0_3289:
	s_ashr_i32 s4, s25, 31
	s_lshr_b32 s4, s4, 25
	s_add_i32 s25, s25, s4
	s_ashr_i32 s4, s25, 7
	v_lshl_or_b32 v100, s4, 6, v231
	v_add_u32_e32 v2, s0, v135
	s_lshl_b32 s4, s4, 12
	v_subrev_u32_e32 v2, s4, v2
	v_mov_b64_e32 v[102:103], s[16:17]
	v_ashrrev_i32_e32 v101, 31, v100
	v_mad_i64_i32 v[102:103], s[4:5], v2, s91, v[102:103]
	v_bfe_u32 v2, v8, 16, 1
	v_lshl_add_u64 v[104:105], v[100:101], 1, v[102:103]
	v_add3_u32 v2, v8, v2, s80
	v_bfe_u32 v100, v4, 16, 1
	v_lshrrev_b32_e32 v2, 16, v2
	v_add3_u32 v100, v4, v100, s80
	v_and_or_b32 v100, v100, s85, v2
	v_bfe_u32 v2, v28, 16, 1
	v_add3_u32 v2, v28, v2, s80
	v_bfe_u32 v101, v24, 16, 1
	v_lshrrev_b32_e32 v2, 16, v2
	v_add3_u32 v101, v24, v101, s80
	v_and_or_b32 v101, v101, s85, v2
	v_bfe_u32 v2, v52, 16, 1
	v_add3_u32 v2, v52, v2, s80
	v_bfe_u32 v102, v16, 16, 1
	v_lshrrev_b32_e32 v2, 16, v2
	v_add3_u32 v102, v16, v102, s80
	v_and_or_b32 v102, v102, s85, v2
	v_bfe_u32 v2, v72, 16, 1
	v_add3_u32 v2, v72, v2, s80
	v_bfe_u32 v103, v76, 16, 1
	v_lshrrev_b32_e32 v2, 16, v2
	v_add3_u32 v103, v76, v103, s80
	v_and_or_b32 v103, v103, s85, v2
	v_bfe_u32 v2, v9, 16, 1
	global_store_dwordx4 v[104:105], v[100:103], off nt
	v_add3_u32 v2, v9, v2, s80
	v_lshrrev_b32_e32 v2, 16, v2
	v_bfe_u32 v100, v5, 16, 1
	v_add3_u32 v100, v5, v100, s80
	v_and_or_b32 v100, v100, s85, v2
	v_bfe_u32 v2, v29, 16, 1
	v_add3_u32 v2, v29, v2, s80
	v_bfe_u32 v101, v25, 16, 1
	v_lshrrev_b32_e32 v2, 16, v2
	v_add3_u32 v101, v25, v101, s80
	v_and_or_b32 v101, v101, s85, v2
	v_bfe_u32 v2, v53, 16, 1
	v_add3_u32 v2, v53, v2, s80
	v_bfe_u32 v102, v17, 16, 1
	v_lshrrev_b32_e32 v2, 16, v2
	v_add3_u32 v102, v17, v102, s80
	v_and_or_b32 v102, v102, s85, v2
	v_bfe_u32 v2, v73, 16, 1
	v_add3_u32 v2, v73, v2, s80
	v_bfe_u32 v103, v77, 16, 1
	v_lshrrev_b32_e32 v2, 16, v2
	v_add3_u32 v103, v77, v103, s80
	v_add_co_u32_e32 v106, vcc, s91, v104
	v_and_or_b32 v103, v103, s85, v2
	s_nop 0
	v_addc_co_u32_e32 v107, vcc, 0, v105, vcc
	v_bfe_u32 v2, v10, 16, 1
	global_store_dwordx4 v[106:107], v[100:103], off nt
	v_add3_u32 v2, v10, v2, s80
	v_lshrrev_b32_e32 v2, 16, v2
	v_bfe_u32 v100, v6, 16, 1
	v_add3_u32 v100, v6, v100, s80
	v_and_or_b32 v100, v100, s85, v2
	v_bfe_u32 v2, v30, 16, 1
	v_add3_u32 v2, v30, v2, s80
	v_bfe_u32 v101, v26, 16, 1
	v_lshrrev_b32_e32 v2, 16, v2
	v_add3_u32 v101, v26, v101, s80
	v_and_or_b32 v101, v101, s85, v2
	v_bfe_u32 v2, v54, 16, 1
	v_add3_u32 v2, v54, v2, s80
	v_bfe_u32 v102, v18, 16, 1
	v_lshrrev_b32_e32 v2, 16, v2
	v_add3_u32 v102, v18, v102, s80
	v_and_or_b32 v102, v102, s85, v2
	v_bfe_u32 v2, v74, 16, 1
	v_add3_u32 v2, v74, v2, s80
	v_bfe_u32 v103, v78, 16, 1
	v_lshrrev_b32_e32 v2, 16, v2
	v_add3_u32 v103, v78, v103, s80
	v_add_co_u32_e32 v106, vcc, s87, v104
	v_and_or_b32 v103, v103, s85, v2
	s_nop 0
	v_addc_co_u32_e32 v107, vcc, 0, v105, vcc
	v_bfe_u32 v2, v11, 16, 1
	global_store_dwordx4 v[106:107], v[100:103], off nt
	v_add3_u32 v2, v11, v2, s80
	v_lshrrev_b32_e32 v2, 16, v2
	v_bfe_u32 v100, v7, 16, 1
	v_add3_u32 v100, v7, v100, s80
	v_and_or_b32 v100, v100, s85, v2
	v_bfe_u32 v2, v31, 16, 1
	v_add3_u32 v2, v31, v2, s80
	v_bfe_u32 v101, v27, 16, 1
	v_lshrrev_b32_e32 v2, 16, v2
	v_add3_u32 v101, v27, v101, s80
	v_and_or_b32 v101, v101, s85, v2
	v_bfe_u32 v2, v55, 16, 1
	v_add3_u32 v2, v55, v2, s80
	v_bfe_u32 v102, v19, 16, 1
	v_lshrrev_b32_e32 v2, 16, v2
	v_add3_u32 v102, v19, v102, s80
	v_and_or_b32 v102, v102, s85, v2
	v_bfe_u32 v2, v75, 16, 1
	v_add3_u32 v2, v75, v2, s80
	v_bfe_u32 v103, v79, 16, 1
	v_lshrrev_b32_e32 v2, 16, v2
	v_add3_u32 v103, v79, v103, s80
	v_add_co_u32_e32 v104, vcc, 0x9000, v104
	v_and_or_b32 v103, v103, s85, v2
	s_nop 0
	v_addc_co_u32_e32 v105, vcc, 0, v105, vcc
	global_store_dwordx4 v[104:105], v[100:103], off nt
	s_branch .LBB0_3240

.LBB0_3336:
	s_waitcnt vmcnt(1)
	v_bfe_u32 v2, v104, 16, 1
	v_mov_b64_e32 v[138:139], s[16:17]
	v_add3_u32 v2, v104, v2, s80
	s_waitcnt vmcnt(0)
	v_bfe_u32 v104, v100, 16, 1
	v_mad_i64_i32 v[138:139], s[6:7], v137, s91, v[138:139]
	v_lshrrev_b32_e32 v2, 16, v2
	v_add3_u32 v100, v100, v104, s80
	v_lshl_add_u64 v[132:133], v[132:133], 1, v[138:139]
	v_and_or_b32 v138, v100, s85, v2
	v_bfe_u32 v2, v116, 16, 1
	v_add3_u32 v2, v116, v2, s80
	v_bfe_u32 v100, v112, 16, 1
	v_lshrrev_b32_e32 v2, 16, v2
	v_add3_u32 v100, v112, v100, s80
	v_and_or_b32 v139, v100, s85, v2
	v_bfe_u32 v2, v120, 16, 1
	v_add3_u32 v2, v120, v2, s80
	v_bfe_u32 v100, v108, 16, 1
	v_lshrrev_b32_e32 v2, 16, v2
	v_add3_u32 v100, v108, v100, s80
	v_and_or_b32 v140, v100, s85, v2
	v_bfe_u32 v2, v128, 16, 1
	v_add3_u32 v2, v128, v2, s80
	v_bfe_u32 v100, v124, 16, 1
	v_lshrrev_b32_e32 v2, 16, v2
	v_add3_u32 v100, v124, v100, s80
	v_and_or_b32 v141, v100, s85, v2
	v_bfe_u32 v2, v105, 16, 1
	v_add3_u32 v2, v105, v2, s80
	v_bfe_u32 v100, v101, 16, 1
	v_lshrrev_b32_e32 v2, 16, v2
	v_add3_u32 v100, v101, v100, s80
	global_store_dwordx4 v[132:133], v[138:141], off nt
	s_nop 1
	v_and_or_b32 v138, v100, s85, v2
	v_bfe_u32 v2, v117, 16, 1
	v_add3_u32 v2, v117, v2, s80
	v_bfe_u32 v100, v113, 16, 1
	v_lshrrev_b32_e32 v2, 16, v2
	v_add3_u32 v100, v113, v100, s80
	v_and_or_b32 v139, v100, s85, v2
	v_bfe_u32 v2, v121, 16, 1
	v_add3_u32 v2, v121, v2, s80
	v_bfe_u32 v100, v109, 16, 1
	v_lshrrev_b32_e32 v2, 16, v2
	v_add3_u32 v100, v109, v100, s80
	v_and_or_b32 v140, v100, s85, v2
	v_bfe_u32 v2, v129, 16, 1
	v_add3_u32 v2, v129, v2, s80
	v_bfe_u32 v100, v125, 16, 1
	v_lshrrev_b32_e32 v2, 16, v2
	v_add3_u32 v100, v125, v100, s80
	v_and_or_b32 v141, v100, s85, v2
	v_add_co_u32_e32 v100, vcc, s91, v132
	v_bfe_u32 v2, v106, 16, 1
	s_nop 0
	v_addc_co_u32_e32 v101, vcc, 0, v133, vcc
	global_store_dwordx4 v[100:101], v[138:141], off nt
	v_add3_u32 v2, v106, v2, s80
	v_bfe_u32 v100, v102, 16, 1
	v_lshrrev_b32_e32 v2, 16, v2
	v_add3_u32 v100, v102, v100, s80
	v_and_or_b32 v138, v100, s85, v2
	v_bfe_u32 v2, v118, 16, 1
	v_add3_u32 v2, v118, v2, s80
	v_bfe_u32 v100, v114, 16, 1
	v_lshrrev_b32_e32 v2, 16, v2
	v_add3_u32 v100, v114, v100, s80
	v_and_or_b32 v139, v100, s85, v2
	v_bfe_u32 v2, v122, 16, 1
	v_add3_u32 v2, v122, v2, s80
	v_bfe_u32 v100, v110, 16, 1
	v_lshrrev_b32_e32 v2, 16, v2
	v_add3_u32 v100, v110, v100, s80
	v_and_or_b32 v140, v100, s85, v2
	v_bfe_u32 v2, v130, 16, 1
	v_add3_u32 v2, v130, v2, s80
	v_bfe_u32 v100, v126, 16, 1
	v_lshrrev_b32_e32 v2, 16, v2
	v_add3_u32 v100, v126, v100, s80
	v_and_or_b32 v141, v100, s85, v2
	v_add_co_u32_e32 v100, vcc, s87, v132
	v_bfe_u32 v2, v107, 16, 1
	s_nop 0
	v_addc_co_u32_e32 v101, vcc, 0, v133, vcc
	global_store_dwordx4 v[100:101], v[138:141], off nt
	v_add3_u32 v2, v107, v2, s80
	v_bfe_u32 v100, v103, 16, 1
	v_lshrrev_b32_e32 v2, 16, v2
	v_add3_u32 v100, v103, v100, s80
	v_and_or_b32 v100, v100, s85, v2
	v_bfe_u32 v2, v119, 16, 1
	v_add3_u32 v2, v119, v2, s80
	v_bfe_u32 v101, v115, 16, 1
	v_lshrrev_b32_e32 v2, 16, v2
	v_add3_u32 v101, v115, v101, s80
	v_and_or_b32 v101, v101, s85, v2
	v_bfe_u32 v2, v123, 16, 1
	v_add3_u32 v2, v123, v2, s80
	v_bfe_u32 v102, v111, 16, 1
	v_lshrrev_b32_e32 v2, 16, v2
	v_add3_u32 v102, v111, v102, s80
	v_and_or_b32 v102, v102, s85, v2
	v_bfe_u32 v2, v131, 16, 1
	v_add3_u32 v2, v131, v2, s80
	v_bfe_u32 v103, v127, 16, 1
	v_add_co_u32_e32 v104, vcc, 0x9000, v132
	v_lshrrev_b32_e32 v2, 16, v2
	v_add3_u32 v103, v127, v103, s80
	v_addc_co_u32_e32 v105, vcc, 0, v133, vcc
	v_and_or_b32 v103, v103, s85, v2
	s_andn2_b64 vcc, exec, s[18:19]
	global_store_dwordx4 v[104:105], v[100:103], off nt
	s_cbranch_vccnz .LBB0_3339
	s_ashr_i32 s6, s14, 31
	s_lshr_b32 s6, s6, 25
	s_add_i32 s14, s14, s6
	s_ashr_i32 s6, s14, 7
	v_lshl_or_b32 v100, s6, 6, v231
	v_add_u32_e32 v2, s0, v136
	s_lshl_b32 s6, s6, 12
	v_subrev_u32_e32 v2, s6, v2
	v_mov_b64_e32 v[102:103], s[16:17]
	v_ashrrev_i32_e32 v101, 31, v100
	v_mad_i64_i32 v[102:103], s[6:7], v2, s91, v[102:103]
	v_bfe_u32 v2, v36, 16, 1
	v_lshl_add_u64 v[104:105], v[100:101], 1, v[102:103]
	v_add3_u32 v2, v36, v2, s80
	v_bfe_u32 v100, v32, 16, 1
	v_lshrrev_b32_e32 v2, 16, v2
	v_add3_u32 v100, v32, v100, s80
	v_and_or_b32 v100, v100, s85, v2
	v_bfe_u32 v2, v64, 16, 1
	v_add3_u32 v2, v64, v2, s80
	v_bfe_u32 v101, v60, 16, 1
	v_lshrrev_b32_e32 v2, 16, v2
	v_add3_u32 v101, v60, v101, s80
	v_and_or_b32 v101, v101, s85, v2
	v_bfe_u32 v2, v80, 16, 1
	v_add3_u32 v2, v80, v2, s80
	v_bfe_u32 v102, v56, 16, 1
	v_lshrrev_b32_e32 v2, 16, v2
	v_add3_u32 v102, v56, v102, s80
	v_and_or_b32 v102, v102, s85, v2
	v_bfe_u32 v2, v92, 16, 1
	v_add3_u32 v2, v92, v2, s80
	v_bfe_u32 v103, v96, 16, 1
	v_lshrrev_b32_e32 v2, 16, v2
	v_add3_u32 v103, v96, v103, s80
	v_and_or_b32 v103, v103, s85, v2
	v_bfe_u32 v2, v37, 16, 1
	global_store_dwordx4 v[104:105], v[100:103], off nt
	v_add3_u32 v2, v37, v2, s80
	v_lshrrev_b32_e32 v2, 16, v2
	v_bfe_u32 v100, v33, 16, 1
	v_add3_u32 v100, v33, v100, s80
	v_and_or_b32 v100, v100, s85, v2
	v_bfe_u32 v2, v65, 16, 1
	v_add3_u32 v2, v65, v2, s80
	v_bfe_u32 v101, v61, 16, 1
	v_lshrrev_b32_e32 v2, 16, v2
	v_add3_u32 v101, v61, v101, s80
	v_and_or_b32 v101, v101, s85, v2
	v_bfe_u32 v2, v81, 16, 1
	v_add3_u32 v2, v81, v2, s80
	v_bfe_u32 v102, v57, 16, 1
	v_lshrrev_b32_e32 v2, 16, v2
	v_add3_u32 v102, v57, v102, s80
	v_and_or_b32 v102, v102, s85, v2
	v_bfe_u32 v2, v93, 16, 1
	v_add3_u32 v2, v93, v2, s80
	v_bfe_u32 v103, v97, 16, 1
	v_lshrrev_b32_e32 v2, 16, v2
	v_add3_u32 v103, v97, v103, s80
	v_add_co_u32_e32 v106, vcc, s91, v104
	v_and_or_b32 v103, v103, s85, v2
	s_nop 0
	v_addc_co_u32_e32 v107, vcc, 0, v105, vcc
	v_bfe_u32 v2, v38, 16, 1
	global_store_dwordx4 v[106:107], v[100:103], off nt
	v_add3_u32 v2, v38, v2, s80
	v_lshrrev_b32_e32 v2, 16, v2
	v_bfe_u32 v100, v34, 16, 1
	v_add3_u32 v100, v34, v100, s80
	v_and_or_b32 v100, v100, s85, v2
	v_bfe_u32 v2, v66, 16, 1
	v_add3_u32 v2, v66, v2, s80
	v_bfe_u32 v101, v62, 16, 1
	v_lshrrev_b32_e32 v2, 16, v2
	v_add3_u32 v101, v62, v101, s80
	v_and_or_b32 v101, v101, s85, v2
	v_bfe_u32 v2, v82, 16, 1
	v_add3_u32 v2, v82, v2, s80
	v_bfe_u32 v102, v58, 16, 1
	v_lshrrev_b32_e32 v2, 16, v2
	v_add3_u32 v102, v58, v102, s80
	v_and_or_b32 v102, v102, s85, v2
	v_bfe_u32 v2, v94, 16, 1
	v_add3_u32 v2, v94, v2, s80
	v_bfe_u32 v103, v98, 16, 1
	v_lshrrev_b32_e32 v2, 16, v2
	v_add3_u32 v103, v98, v103, s80
	v_add_co_u32_e32 v106, vcc, s87, v104
	v_and_or_b32 v103, v103, s85, v2
	s_nop 0
	v_addc_co_u32_e32 v107, vcc, 0, v105, vcc
	v_bfe_u32 v2, v39, 16, 1
	global_store_dwordx4 v[106:107], v[100:103], off nt
	v_add3_u32 v2, v39, v2, s80
	v_lshrrev_b32_e32 v2, 16, v2
	v_bfe_u32 v100, v35, 16, 1
	v_add3_u32 v100, v35, v100, s80
	v_and_or_b32 v100, v100, s85, v2
	v_bfe_u32 v2, v67, 16, 1
	v_add3_u32 v2, v67, v2, s80
	v_bfe_u32 v101, v63, 16, 1
	v_lshrrev_b32_e32 v2, 16, v2
	v_add3_u32 v101, v63, v101, s80
	v_and_or_b32 v101, v101, s85, v2
	v_bfe_u32 v2, v83, 16, 1
	v_add3_u32 v2, v83, v2, s80
	v_bfe_u32 v102, v59, 16, 1
	v_lshrrev_b32_e32 v2, 16, v2
	v_add3_u32 v102, v59, v102, s80
	v_and_or_b32 v102, v102, s85, v2
	v_bfe_u32 v2, v95, 16, 1
	v_add3_u32 v2, v95, v2, s80
	v_bfe_u32 v103, v99, 16, 1
	v_lshrrev_b32_e32 v2, 16, v2
	v_add3_u32 v103, v99, v103, s80
	v_add_co_u32_e32 v104, vcc, 0x9000, v104
	v_and_or_b32 v103, v103, s85, v2
	s_nop 0
	v_addc_co_u32_e32 v105, vcc, 0, v105, vcc
	global_store_dwordx4 v[104:105], v[100:103], off nt
	s_andn2_b64 vcc, exec, s[20:21]
	s_cbranch_vccz .LBB0_3340

.LBB0_3340:
	s_ashr_i32 s6, s15, 31
	s_lshr_b32 s6, s6, 25
	s_add_i32 s15, s15, s6
	s_ashr_i32 s6, s15, 7
	v_lshl_or_b32 v100, s6, 6, v231
	v_add_u32_e32 v2, s0, v134
	s_lshl_b32 s6, s6, 12
	v_subrev_u32_e32 v2, s6, v2
	v_mov_b64_e32 v[102:103], s[16:17]
	v_ashrrev_i32_e32 v101, 31, v100
	v_mad_i64_i32 v[102:103], s[6:7], v2, s91, v[102:103]
	v_bfe_u32 v2, v20, 16, 1
	v_lshl_add_u64 v[104:105], v[100:101], 1, v[102:103]
	v_add3_u32 v2, v20, v2, s80
	v_bfe_u32 v100, v12, 16, 1
	v_lshrrev_b32_e32 v2, 16, v2
	v_add3_u32 v100, v12, v100, s80
	v_and_or_b32 v100, v100, s85, v2
	v_bfe_u32 v2, v48, 16, 1
	v_add3_u32 v2, v48, v2, s80
	v_bfe_u32 v101, v44, 16, 1
	v_lshrrev_b32_e32 v2, 16, v2
	v_add3_u32 v101, v44, v101, s80
	v_and_or_b32 v101, v101, s85, v2
	v_bfe_u32 v2, v68, 16, 1
	v_add3_u32 v2, v68, v2, s80
	v_bfe_u32 v102, v40, 16, 1
	v_lshrrev_b32_e32 v2, 16, v2
	v_add3_u32 v102, v40, v102, s80
	v_and_or_b32 v102, v102, s85, v2
	v_bfe_u32 v2, v84, 16, 1
	v_add3_u32 v2, v84, v2, s80
	v_bfe_u32 v103, v88, 16, 1
	v_lshrrev_b32_e32 v2, 16, v2
	v_add3_u32 v103, v88, v103, s80
	v_and_or_b32 v103, v103, s85, v2
	v_bfe_u32 v2, v21, 16, 1
	global_store_dwordx4 v[104:105], v[100:103], off nt
	v_add3_u32 v2, v21, v2, s80
	v_lshrrev_b32_e32 v2, 16, v2
	v_bfe_u32 v100, v13, 16, 1
	v_add3_u32 v100, v13, v100, s80
	v_and_or_b32 v100, v100, s85, v2
	v_bfe_u32 v2, v49, 16, 1
	v_add3_u32 v2, v49, v2, s80
	v_bfe_u32 v101, v45, 16, 1
	v_lshrrev_b32_e32 v2, 16, v2
	v_add3_u32 v101, v45, v101, s80
	v_and_or_b32 v101, v101, s85, v2
	v_bfe_u32 v2, v69, 16, 1
	v_add3_u32 v2, v69, v2, s80
	v_bfe_u32 v102, v41, 16, 1
	v_lshrrev_b32_e32 v2, 16, v2
	v_add3_u32 v102, v41, v102, s80
	v_and_or_b32 v102, v102, s85, v2
	v_bfe_u32 v2, v85, 16, 1
	v_add3_u32 v2, v85, v2, s80
	v_bfe_u32 v103, v89, 16, 1
	v_lshrrev_b32_e32 v2, 16, v2
	v_add3_u32 v103, v89, v103, s80
	v_add_co_u32_e32 v106, vcc, s91, v104
	v_and_or_b32 v103, v103, s85, v2
	s_nop 0
	v_addc_co_u32_e32 v107, vcc, 0, v105, vcc
	v_bfe_u32 v2, v22, 16, 1
	global_store_dwordx4 v[106:107], v[100:103], off nt
	v_add3_u32 v2, v22, v2, s80
	v_lshrrev_b32_e32 v2, 16, v2
	v_bfe_u32 v100, v14, 16, 1
	v_add3_u32 v100, v14, v100, s80
	v_and_or_b32 v100, v100, s85, v2
	v_bfe_u32 v2, v50, 16, 1
	v_add3_u32 v2, v50, v2, s80
	v_bfe_u32 v101, v46, 16, 1
	v_lshrrev_b32_e32 v2, 16, v2
	v_add3_u32 v101, v46, v101, s80
	v_and_or_b32 v101, v101, s85, v2
	v_bfe_u32 v2, v70, 16, 1
	v_add3_u32 v2, v70, v2, s80
	v_bfe_u32 v102, v42, 16, 1
	v_lshrrev_b32_e32 v2, 16, v2
	v_add3_u32 v102, v42, v102, s80
	v_and_or_b32 v102, v102, s85, v2
	v_bfe_u32 v2, v86, 16, 1
	v_add3_u32 v2, v86, v2, s80
	v_bfe_u32 v103, v90, 16, 1
	v_lshrrev_b32_e32 v2, 16, v2
	v_add3_u32 v103, v90, v103, s80
	v_add_co_u32_e32 v106, vcc, s87, v104
	v_and_or_b32 v103, v103, s85, v2
	s_nop 0
	v_addc_co_u32_e32 v107, vcc, 0, v105, vcc
	v_bfe_u32 v2, v23, 16, 1
	global_store_dwordx4 v[106:107], v[100:103], off nt
	v_add3_u32 v2, v23, v2, s80
	v_lshrrev_b32_e32 v2, 16, v2
	v_bfe_u32 v100, v15, 16, 1
	v_add3_u32 v100, v15, v100, s80
	v_and_or_b32 v100, v100, s85, v2
	v_bfe_u32 v2, v51, 16, 1
	v_add3_u32 v2, v51, v2, s80
	v_bfe_u32 v101, v47, 16, 1
	v_lshrrev_b32_e32 v2, 16, v2
	v_add3_u32 v101, v47, v101, s80
	v_and_or_b32 v101, v101, s85, v2
	v_bfe_u32 v2, v71, 16, 1
	v_add3_u32 v2, v71, v2, s80
	v_bfe_u32 v102, v43, 16, 1
	v_lshrrev_b32_e32 v2, 16, v2
	v_add3_u32 v102, v43, v102, s80
	v_and_or_b32 v102, v102, s85, v2
	v_bfe_u32 v2, v87, 16, 1
	v_add3_u32 v2, v87, v2, s80
	v_bfe_u32 v103, v91, 16, 1
	v_lshrrev_b32_e32 v2, 16, v2
	v_add3_u32 v103, v91, v103, s80
	v_add_co_u32_e32 v104, vcc, 0x9000, v104
	v_and_or_b32 v103, v103, s85, v2
	s_nop 0
	v_addc_co_u32_e32 v105, vcc, 0, v105, vcc
	global_store_dwordx4 v[104:105], v[100:103], off nt
	s_andn2_b64 vcc, exec, s[22:23]
	s_cbranch_vccnz .LBB0_3292
.LBB0_3341:
	s_ashr_i32 s6, s25, 31
	s_lshr_b32 s6, s6, 25
	s_add_i32 s25, s25, s6
	s_ashr_i32 s6, s25, 7
	v_lshl_or_b32 v100, s6, 6, v231
	v_add_u32_e32 v2, s0, v135
	s_lshl_b32 s6, s6, 12
	v_subrev_u32_e32 v2, s6, v2
	v_mov_b64_e32 v[102:103], s[16:17]
	v_ashrrev_i32_e32 v101, 31, v100
	v_mad_i64_i32 v[102:103], s[6:7], v2, s91, v[102:103]
	v_bfe_u32 v2, v8, 16, 1
	v_lshl_add_u64 v[104:105], v[100:101], 1, v[102:103]
	v_add3_u32 v2, v8, v2, s80
	v_bfe_u32 v100, v4, 16, 1
	v_lshrrev_b32_e32 v2, 16, v2
	v_add3_u32 v100, v4, v100, s80
	v_and_or_b32 v100, v100, s85, v2
	v_bfe_u32 v2, v28, 16, 1
	v_add3_u32 v2, v28, v2, s80
	v_bfe_u32 v101, v24, 16, 1
	v_lshrrev_b32_e32 v2, 16, v2
	v_add3_u32 v101, v24, v101, s80
	v_and_or_b32 v101, v101, s85, v2
	v_bfe_u32 v2, v52, 16, 1
	v_add3_u32 v2, v52, v2, s80
	v_bfe_u32 v102, v16, 16, 1
	v_lshrrev_b32_e32 v2, 16, v2
	v_add3_u32 v102, v16, v102, s80
	v_and_or_b32 v102, v102, s85, v2
	v_bfe_u32 v2, v72, 16, 1
	v_add3_u32 v2, v72, v2, s80
	v_bfe_u32 v103, v76, 16, 1
	v_lshrrev_b32_e32 v2, 16, v2
	v_add3_u32 v103, v76, v103, s80
	v_and_or_b32 v103, v103, s85, v2
	v_bfe_u32 v2, v9, 16, 1
	global_store_dwordx4 v[104:105], v[100:103], off nt
	v_add3_u32 v2, v9, v2, s80
	v_lshrrev_b32_e32 v2, 16, v2
	v_bfe_u32 v100, v5, 16, 1
	v_add3_u32 v100, v5, v100, s80
	v_and_or_b32 v100, v100, s85, v2
	v_bfe_u32 v2, v29, 16, 1
	v_add3_u32 v2, v29, v2, s80
	v_bfe_u32 v101, v25, 16, 1
	v_lshrrev_b32_e32 v2, 16, v2
	v_add3_u32 v101, v25, v101, s80
	v_and_or_b32 v101, v101, s85, v2
	v_bfe_u32 v2, v53, 16, 1
	v_add3_u32 v2, v53, v2, s80
	v_bfe_u32 v102, v17, 16, 1
	v_lshrrev_b32_e32 v2, 16, v2
	v_add3_u32 v102, v17, v102, s80
	v_and_or_b32 v102, v102, s85, v2
	v_bfe_u32 v2, v73, 16, 1
	v_add3_u32 v2, v73, v2, s80
	v_bfe_u32 v103, v77, 16, 1
	v_lshrrev_b32_e32 v2, 16, v2
	v_add3_u32 v103, v77, v103, s80
	v_add_co_u32_e32 v106, vcc, s91, v104
	v_and_or_b32 v103, v103, s85, v2
	s_nop 0
	v_addc_co_u32_e32 v107, vcc, 0, v105, vcc
	v_bfe_u32 v2, v10, 16, 1
	global_store_dwordx4 v[106:107], v[100:103], off nt
	v_add3_u32 v2, v10, v2, s80
	v_lshrrev_b32_e32 v2, 16, v2
	v_bfe_u32 v100, v6, 16, 1
	v_add3_u32 v100, v6, v100, s80
	v_and_or_b32 v100, v100, s85, v2
	v_bfe_u32 v2, v30, 16, 1
	v_add3_u32 v2, v30, v2, s80
	v_bfe_u32 v101, v26, 16, 1
	v_lshrrev_b32_e32 v2, 16, v2
	v_add3_u32 v101, v26, v101, s80
	v_and_or_b32 v101, v101, s85, v2
	v_bfe_u32 v2, v54, 16, 1
	v_add3_u32 v2, v54, v2, s80
	v_bfe_u32 v102, v18, 16, 1
	v_lshrrev_b32_e32 v2, 16, v2
	v_add3_u32 v102, v18, v102, s80
	v_and_or_b32 v102, v102, s85, v2
	v_bfe_u32 v2, v74, 16, 1
	v_add3_u32 v2, v74, v2, s80
	v_bfe_u32 v103, v78, 16, 1
	v_lshrrev_b32_e32 v2, 16, v2
	v_add3_u32 v103, v78, v103, s80
	v_add_co_u32_e32 v106, vcc, s87, v104
	v_and_or_b32 v103, v103, s85, v2
	s_nop 0
	v_addc_co_u32_e32 v107, vcc, 0, v105, vcc
	v_bfe_u32 v2, v11, 16, 1
	global_store_dwordx4 v[106:107], v[100:103], off nt
	v_add3_u32 v2, v11, v2, s80
	v_lshrrev_b32_e32 v2, 16, v2
	v_bfe_u32 v100, v7, 16, 1
	v_add3_u32 v100, v7, v100, s80
	v_and_or_b32 v100, v100, s85, v2
	v_bfe_u32 v2, v31, 16, 1
	v_add3_u32 v2, v31, v2, s80
	v_bfe_u32 v101, v27, 16, 1
	v_lshrrev_b32_e32 v2, 16, v2
	v_add3_u32 v101, v27, v101, s80
	v_and_or_b32 v101, v101, s85, v2
	v_bfe_u32 v2, v55, 16, 1
	v_add3_u32 v2, v55, v2, s80
	v_bfe_u32 v102, v19, 16, 1
	v_lshrrev_b32_e32 v2, 16, v2
	v_add3_u32 v102, v19, v102, s80
	v_and_or_b32 v102, v102, s85, v2
	v_bfe_u32 v2, v75, 16, 1
	v_add3_u32 v2, v75, v2, s80
	v_bfe_u32 v103, v79, 16, 1
	v_lshrrev_b32_e32 v2, 16, v2
	v_add3_u32 v103, v79, v103, s80
	v_add_co_u32_e32 v104, vcc, 0x9000, v104
	v_and_or_b32 v103, v103, s85, v2
	s_nop 0
	v_addc_co_u32_e32 v105, vcc, 0, v105, vcc
	global_store_dwordx4 v[104:105], v[100:103], off nt
	s_branch .LBB0_3292

.LBB0_3388:
	s_waitcnt vmcnt(1)
	v_bfe_u32 v2, v104, 16, 1
	v_mov_b64_e32 v[138:139], s[12:13]
	v_add3_u32 v2, v104, v2, s80
	s_waitcnt vmcnt(0)
	v_bfe_u32 v104, v100, 16, 1
	v_mad_i64_i32 v[138:139], s[4:5], v137, s91, v[138:139]
	v_lshrrev_b32_e32 v2, 16, v2
	v_add3_u32 v100, v100, v104, s80
	v_lshl_add_u64 v[132:133], v[132:133], 1, v[138:139]
	v_and_or_b32 v138, v100, s85, v2
	v_bfe_u32 v2, v116, 16, 1
	v_add3_u32 v2, v116, v2, s80
	v_bfe_u32 v100, v112, 16, 1
	v_lshrrev_b32_e32 v2, 16, v2
	v_add3_u32 v100, v112, v100, s80
	v_and_or_b32 v139, v100, s85, v2
	v_bfe_u32 v2, v120, 16, 1
	v_add3_u32 v2, v120, v2, s80
	v_bfe_u32 v100, v108, 16, 1
	v_lshrrev_b32_e32 v2, 16, v2
	v_add3_u32 v100, v108, v100, s80
	v_and_or_b32 v140, v100, s85, v2
	v_bfe_u32 v2, v128, 16, 1
	v_add3_u32 v2, v128, v2, s80
	v_bfe_u32 v100, v124, 16, 1
	v_lshrrev_b32_e32 v2, 16, v2
	v_add3_u32 v100, v124, v100, s80
	v_and_or_b32 v141, v100, s85, v2
	v_bfe_u32 v2, v105, 16, 1
	v_add3_u32 v2, v105, v2, s80
	v_bfe_u32 v100, v101, 16, 1
	v_lshrrev_b32_e32 v2, 16, v2
	v_add3_u32 v100, v101, v100, s80
	global_store_dwordx4 v[132:133], v[138:141], off nt
	s_nop 1
	v_and_or_b32 v138, v100, s85, v2
	v_bfe_u32 v2, v117, 16, 1
	v_add3_u32 v2, v117, v2, s80
	v_bfe_u32 v100, v113, 16, 1
	v_lshrrev_b32_e32 v2, 16, v2
	v_add3_u32 v100, v113, v100, s80
	v_and_or_b32 v139, v100, s85, v2
	v_bfe_u32 v2, v121, 16, 1
	v_add3_u32 v2, v121, v2, s80
	v_bfe_u32 v100, v109, 16, 1
	v_lshrrev_b32_e32 v2, 16, v2
	v_add3_u32 v100, v109, v100, s80
	v_and_or_b32 v140, v100, s85, v2
	v_bfe_u32 v2, v129, 16, 1
	v_add3_u32 v2, v129, v2, s80
	v_bfe_u32 v100, v125, 16, 1
	v_lshrrev_b32_e32 v2, 16, v2
	v_add3_u32 v100, v125, v100, s80
	v_and_or_b32 v141, v100, s85, v2
	v_add_co_u32_e32 v100, vcc, s91, v132
	v_bfe_u32 v2, v106, 16, 1
	s_nop 0
	v_addc_co_u32_e32 v101, vcc, 0, v133, vcc
	global_store_dwordx4 v[100:101], v[138:141], off nt
	v_add3_u32 v2, v106, v2, s80
	v_bfe_u32 v100, v102, 16, 1
	v_lshrrev_b32_e32 v2, 16, v2
	v_add3_u32 v100, v102, v100, s80
	v_and_or_b32 v138, v100, s85, v2
	v_bfe_u32 v2, v118, 16, 1
	v_add3_u32 v2, v118, v2, s80
	v_bfe_u32 v100, v114, 16, 1
	v_lshrrev_b32_e32 v2, 16, v2
	v_add3_u32 v100, v114, v100, s80
	v_and_or_b32 v139, v100, s85, v2
	v_bfe_u32 v2, v122, 16, 1
	v_add3_u32 v2, v122, v2, s80
	v_bfe_u32 v100, v110, 16, 1
	v_lshrrev_b32_e32 v2, 16, v2
	v_add3_u32 v100, v110, v100, s80
	v_and_or_b32 v140, v100, s85, v2
	v_bfe_u32 v2, v130, 16, 1
	v_add3_u32 v2, v130, v2, s80
	v_bfe_u32 v100, v126, 16, 1
	v_lshrrev_b32_e32 v2, 16, v2
	v_add3_u32 v100, v126, v100, s80
	v_and_or_b32 v141, v100, s85, v2
	v_add_co_u32_e32 v100, vcc, s87, v132
	v_bfe_u32 v2, v107, 16, 1
	s_nop 0
	v_addc_co_u32_e32 v101, vcc, 0, v133, vcc
	global_store_dwordx4 v[100:101], v[138:141], off nt
	v_add3_u32 v2, v107, v2, s80
	v_bfe_u32 v100, v103, 16, 1
	v_lshrrev_b32_e32 v2, 16, v2
	v_add3_u32 v100, v103, v100, s80
	v_and_or_b32 v100, v100, s85, v2
	v_bfe_u32 v2, v119, 16, 1
	v_add3_u32 v2, v119, v2, s80
	v_bfe_u32 v101, v115, 16, 1
	v_lshrrev_b32_e32 v2, 16, v2
	v_add3_u32 v101, v115, v101, s80
	v_and_or_b32 v101, v101, s85, v2
	v_bfe_u32 v2, v123, 16, 1
	v_add3_u32 v2, v123, v2, s80
	v_bfe_u32 v102, v111, 16, 1
	v_lshrrev_b32_e32 v2, 16, v2
	v_add3_u32 v102, v111, v102, s80
	v_and_or_b32 v102, v102, s85, v2
	v_bfe_u32 v2, v131, 16, 1
	v_add3_u32 v2, v131, v2, s80
	v_bfe_u32 v103, v127, 16, 1
	v_add_co_u32_e32 v104, vcc, 0x9000, v132
	v_lshrrev_b32_e32 v2, 16, v2
	v_add3_u32 v103, v127, v103, s80
	v_addc_co_u32_e32 v105, vcc, 0, v133, vcc
	v_and_or_b32 v103, v103, s85, v2
	s_andn2_b64 vcc, exec, s[16:17]
	global_store_dwordx4 v[104:105], v[100:103], off nt
	s_cbranch_vccnz .LBB0_3391
	s_ashr_i32 s4, s14, 31
	s_lshr_b32 s4, s4, 25
	s_add_i32 s14, s14, s4
	s_ashr_i32 s4, s14, 7
	v_lshl_or_b32 v100, s4, 6, v231
	v_add_u32_e32 v2, s0, v136
	s_lshl_b32 s4, s4, 12
	v_subrev_u32_e32 v2, s4, v2
	v_mov_b64_e32 v[102:103], s[12:13]
	v_ashrrev_i32_e32 v101, 31, v100
	v_mad_i64_i32 v[102:103], s[4:5], v2, s91, v[102:103]
	v_bfe_u32 v2, v36, 16, 1
	v_lshl_add_u64 v[104:105], v[100:101], 1, v[102:103]
	v_add3_u32 v2, v36, v2, s80
	v_bfe_u32 v100, v32, 16, 1
	v_lshrrev_b32_e32 v2, 16, v2
	v_add3_u32 v100, v32, v100, s80
	v_and_or_b32 v100, v100, s85, v2
	v_bfe_u32 v2, v64, 16, 1
	v_add3_u32 v2, v64, v2, s80
	v_bfe_u32 v101, v60, 16, 1
	v_lshrrev_b32_e32 v2, 16, v2
	v_add3_u32 v101, v60, v101, s80
	v_and_or_b32 v101, v101, s85, v2
	v_bfe_u32 v2, v80, 16, 1
	v_add3_u32 v2, v80, v2, s80
	v_bfe_u32 v102, v56, 16, 1
	v_lshrrev_b32_e32 v2, 16, v2
	v_add3_u32 v102, v56, v102, s80
	v_and_or_b32 v102, v102, s85, v2
	v_bfe_u32 v2, v92, 16, 1
	v_add3_u32 v2, v92, v2, s80
	v_bfe_u32 v103, v96, 16, 1
	v_lshrrev_b32_e32 v2, 16, v2
	v_add3_u32 v103, v96, v103, s80
	v_and_or_b32 v103, v103, s85, v2
	v_bfe_u32 v2, v37, 16, 1
	global_store_dwordx4 v[104:105], v[100:103], off nt
	v_add3_u32 v2, v37, v2, s80
	v_lshrrev_b32_e32 v2, 16, v2
	v_bfe_u32 v100, v33, 16, 1
	v_add3_u32 v100, v33, v100, s80
	v_and_or_b32 v100, v100, s85, v2
	v_bfe_u32 v2, v65, 16, 1
	v_add3_u32 v2, v65, v2, s80
	v_bfe_u32 v101, v61, 16, 1
	v_lshrrev_b32_e32 v2, 16, v2
	v_add3_u32 v101, v61, v101, s80
	v_and_or_b32 v101, v101, s85, v2
	v_bfe_u32 v2, v81, 16, 1
	v_add3_u32 v2, v81, v2, s80
	v_bfe_u32 v102, v57, 16, 1
	v_lshrrev_b32_e32 v2, 16, v2
	v_add3_u32 v102, v57, v102, s80
	v_and_or_b32 v102, v102, s85, v2
	v_bfe_u32 v2, v93, 16, 1
	v_add3_u32 v2, v93, v2, s80
	v_bfe_u32 v103, v97, 16, 1
	v_lshrrev_b32_e32 v2, 16, v2
	v_add3_u32 v103, v97, v103, s80
	v_add_co_u32_e32 v106, vcc, s91, v104
	v_and_or_b32 v103, v103, s85, v2
	s_nop 0
	v_addc_co_u32_e32 v107, vcc, 0, v105, vcc
	v_bfe_u32 v2, v38, 16, 1
	global_store_dwordx4 v[106:107], v[100:103], off nt
	v_add3_u32 v2, v38, v2, s80
	v_lshrrev_b32_e32 v2, 16, v2
	v_bfe_u32 v100, v34, 16, 1
	v_add3_u32 v100, v34, v100, s80
	v_and_or_b32 v100, v100, s85, v2
	v_bfe_u32 v2, v66, 16, 1
	v_add3_u32 v2, v66, v2, s80
	v_bfe_u32 v101, v62, 16, 1
	v_lshrrev_b32_e32 v2, 16, v2
	v_add3_u32 v101, v62, v101, s80
	v_and_or_b32 v101, v101, s85, v2
	v_bfe_u32 v2, v82, 16, 1
	v_add3_u32 v2, v82, v2, s80
	v_bfe_u32 v102, v58, 16, 1
	v_lshrrev_b32_e32 v2, 16, v2
	v_add3_u32 v102, v58, v102, s80
	v_and_or_b32 v102, v102, s85, v2
	v_bfe_u32 v2, v94, 16, 1
	v_add3_u32 v2, v94, v2, s80
	v_bfe_u32 v103, v98, 16, 1
	v_lshrrev_b32_e32 v2, 16, v2
	v_add3_u32 v103, v98, v103, s80
	v_add_co_u32_e32 v106, vcc, s87, v104
	v_and_or_b32 v103, v103, s85, v2
	s_nop 0
	v_addc_co_u32_e32 v107, vcc, 0, v105, vcc
	v_bfe_u32 v2, v39, 16, 1
	global_store_dwordx4 v[106:107], v[100:103], off nt
	v_add3_u32 v2, v39, v2, s80
	v_lshrrev_b32_e32 v2, 16, v2
	v_bfe_u32 v100, v35, 16, 1
	v_add3_u32 v100, v35, v100, s80
	v_and_or_b32 v100, v100, s85, v2
	v_bfe_u32 v2, v67, 16, 1
	v_add3_u32 v2, v67, v2, s80
	v_bfe_u32 v101, v63, 16, 1
	v_lshrrev_b32_e32 v2, 16, v2
	v_add3_u32 v101, v63, v101, s80
	v_and_or_b32 v101, v101, s85, v2
	v_bfe_u32 v2, v83, 16, 1
	v_add3_u32 v2, v83, v2, s80
	v_bfe_u32 v102, v59, 16, 1
	v_lshrrev_b32_e32 v2, 16, v2
	v_add3_u32 v102, v59, v102, s80
	v_and_or_b32 v102, v102, s85, v2
	v_bfe_u32 v2, v95, 16, 1
	v_add3_u32 v2, v95, v2, s80
	v_bfe_u32 v103, v99, 16, 1
	v_lshrrev_b32_e32 v2, 16, v2
	v_add3_u32 v103, v99, v103, s80
	v_add_co_u32_e32 v104, vcc, 0x9000, v104
	v_and_or_b32 v103, v103, s85, v2
	s_nop 0
	v_addc_co_u32_e32 v105, vcc, 0, v105, vcc
	global_store_dwordx4 v[104:105], v[100:103], off nt
	s_andn2_b64 vcc, exec, s[18:19]
	s_cbranch_vccz .LBB0_3392

.LBB0_3392:
	s_ashr_i32 s4, s15, 31
	s_lshr_b32 s4, s4, 25
	s_add_i32 s15, s15, s4
	s_ashr_i32 s4, s15, 7
	v_lshl_or_b32 v100, s4, 6, v231
	v_add_u32_e32 v2, s0, v134
	s_lshl_b32 s4, s4, 12
	v_subrev_u32_e32 v2, s4, v2
	v_mov_b64_e32 v[102:103], s[12:13]
	v_ashrrev_i32_e32 v101, 31, v100
	v_mad_i64_i32 v[102:103], s[4:5], v2, s91, v[102:103]
	v_bfe_u32 v2, v20, 16, 1
	v_lshl_add_u64 v[104:105], v[100:101], 1, v[102:103]
	v_add3_u32 v2, v20, v2, s80
	v_bfe_u32 v100, v12, 16, 1
	v_lshrrev_b32_e32 v2, 16, v2
	v_add3_u32 v100, v12, v100, s80
	v_and_or_b32 v100, v100, s85, v2
	v_bfe_u32 v2, v48, 16, 1
	v_add3_u32 v2, v48, v2, s80
	v_bfe_u32 v101, v44, 16, 1
	v_lshrrev_b32_e32 v2, 16, v2
	v_add3_u32 v101, v44, v101, s80
	v_and_or_b32 v101, v101, s85, v2
	v_bfe_u32 v2, v68, 16, 1
	v_add3_u32 v2, v68, v2, s80
	v_bfe_u32 v102, v40, 16, 1
	v_lshrrev_b32_e32 v2, 16, v2
	v_add3_u32 v102, v40, v102, s80
	v_and_or_b32 v102, v102, s85, v2
	v_bfe_u32 v2, v84, 16, 1
	v_add3_u32 v2, v84, v2, s80
	v_bfe_u32 v103, v88, 16, 1
	v_lshrrev_b32_e32 v2, 16, v2
	v_add3_u32 v103, v88, v103, s80
	v_and_or_b32 v103, v103, s85, v2
	v_bfe_u32 v2, v21, 16, 1
	global_store_dwordx4 v[104:105], v[100:103], off nt
	v_add3_u32 v2, v21, v2, s80
	v_lshrrev_b32_e32 v2, 16, v2
	v_bfe_u32 v100, v13, 16, 1
	v_add3_u32 v100, v13, v100, s80
	v_and_or_b32 v100, v100, s85, v2
	v_bfe_u32 v2, v49, 16, 1
	v_add3_u32 v2, v49, v2, s80
	v_bfe_u32 v101, v45, 16, 1
	v_lshrrev_b32_e32 v2, 16, v2
	v_add3_u32 v101, v45, v101, s80
	v_and_or_b32 v101, v101, s85, v2
	v_bfe_u32 v2, v69, 16, 1
	v_add3_u32 v2, v69, v2, s80
	v_bfe_u32 v102, v41, 16, 1
	v_lshrrev_b32_e32 v2, 16, v2
	v_add3_u32 v102, v41, v102, s80
	v_and_or_b32 v102, v102, s85, v2
	v_bfe_u32 v2, v85, 16, 1
	v_add3_u32 v2, v85, v2, s80
	v_bfe_u32 v103, v89, 16, 1
	v_lshrrev_b32_e32 v2, 16, v2
	v_add3_u32 v103, v89, v103, s80
	v_add_co_u32_e32 v106, vcc, s91, v104
	v_and_or_b32 v103, v103, s85, v2
	s_nop 0
	v_addc_co_u32_e32 v107, vcc, 0, v105, vcc
	v_bfe_u32 v2, v22, 16, 1
	global_store_dwordx4 v[106:107], v[100:103], off nt
	v_add3_u32 v2, v22, v2, s80
	v_lshrrev_b32_e32 v2, 16, v2
	v_bfe_u32 v100, v14, 16, 1
	v_add3_u32 v100, v14, v100, s80
	v_and_or_b32 v100, v100, s85, v2
	v_bfe_u32 v2, v50, 16, 1
	v_add3_u32 v2, v50, v2, s80
	v_bfe_u32 v101, v46, 16, 1
	v_lshrrev_b32_e32 v2, 16, v2
	v_add3_u32 v101, v46, v101, s80
	v_and_or_b32 v101, v101, s85, v2
	v_bfe_u32 v2, v70, 16, 1
	v_add3_u32 v2, v70, v2, s80
	v_bfe_u32 v102, v42, 16, 1
	v_lshrrev_b32_e32 v2, 16, v2
	v_add3_u32 v102, v42, v102, s80
	v_and_or_b32 v102, v102, s85, v2
	v_bfe_u32 v2, v86, 16, 1
	v_add3_u32 v2, v86, v2, s80
	v_bfe_u32 v103, v90, 16, 1
	v_lshrrev_b32_e32 v2, 16, v2
	v_add3_u32 v103, v90, v103, s80
	v_add_co_u32_e32 v106, vcc, s87, v104
	v_and_or_b32 v103, v103, s85, v2
	s_nop 0
	v_addc_co_u32_e32 v107, vcc, 0, v105, vcc
	v_bfe_u32 v2, v23, 16, 1
	global_store_dwordx4 v[106:107], v[100:103], off nt
	v_add3_u32 v2, v23, v2, s80
	v_lshrrev_b32_e32 v2, 16, v2
	v_bfe_u32 v100, v15, 16, 1
	v_add3_u32 v100, v15, v100, s80
	v_and_or_b32 v100, v100, s85, v2
	v_bfe_u32 v2, v51, 16, 1
	v_add3_u32 v2, v51, v2, s80
	v_bfe_u32 v101, v47, 16, 1
	v_lshrrev_b32_e32 v2, 16, v2
	v_add3_u32 v101, v47, v101, s80
	v_and_or_b32 v101, v101, s85, v2
	v_bfe_u32 v2, v71, 16, 1
	v_add3_u32 v2, v71, v2, s80
	v_bfe_u32 v102, v43, 16, 1
	v_lshrrev_b32_e32 v2, 16, v2
	v_add3_u32 v102, v43, v102, s80
	v_and_or_b32 v102, v102, s85, v2
	v_bfe_u32 v2, v87, 16, 1
	v_add3_u32 v2, v87, v2, s80
	v_bfe_u32 v103, v91, 16, 1
	v_lshrrev_b32_e32 v2, 16, v2
	v_add3_u32 v103, v91, v103, s80
	v_add_co_u32_e32 v104, vcc, 0x9000, v104
	v_and_or_b32 v103, v103, s85, v2
	s_nop 0
	v_addc_co_u32_e32 v105, vcc, 0, v105, vcc
	global_store_dwordx4 v[104:105], v[100:103], off nt
	s_andn2_b64 vcc, exec, s[20:21]
	s_cbranch_vccnz .LBB0_3344
.LBB0_3393:
	s_ashr_i32 s4, s22, 31
	s_lshr_b32 s4, s4, 25
	s_add_i32 s22, s22, s4
	s_ashr_i32 s4, s22, 7
	v_lshl_or_b32 v100, s4, 6, v231
	v_add_u32_e32 v2, s0, v135
	s_lshl_b32 s4, s4, 12
	v_subrev_u32_e32 v2, s4, v2
	v_mov_b64_e32 v[102:103], s[12:13]
	v_ashrrev_i32_e32 v101, 31, v100
	v_mad_i64_i32 v[102:103], s[4:5], v2, s91, v[102:103]
	v_bfe_u32 v2, v8, 16, 1
	v_lshl_add_u64 v[104:105], v[100:101], 1, v[102:103]
	v_add3_u32 v2, v8, v2, s80
	v_bfe_u32 v100, v4, 16, 1
	v_lshrrev_b32_e32 v2, 16, v2
	v_add3_u32 v100, v4, v100, s80
	v_and_or_b32 v100, v100, s85, v2
	v_bfe_u32 v2, v28, 16, 1
	v_add3_u32 v2, v28, v2, s80
	v_bfe_u32 v101, v24, 16, 1
	v_lshrrev_b32_e32 v2, 16, v2
	v_add3_u32 v101, v24, v101, s80
	v_and_or_b32 v101, v101, s85, v2
	v_bfe_u32 v2, v52, 16, 1
	v_add3_u32 v2, v52, v2, s80
	v_bfe_u32 v102, v16, 16, 1
	v_lshrrev_b32_e32 v2, 16, v2
	v_add3_u32 v102, v16, v102, s80
	v_and_or_b32 v102, v102, s85, v2
	v_bfe_u32 v2, v72, 16, 1
	v_add3_u32 v2, v72, v2, s80
	v_bfe_u32 v103, v76, 16, 1
	v_lshrrev_b32_e32 v2, 16, v2
	v_add3_u32 v103, v76, v103, s80
	v_and_or_b32 v103, v103, s85, v2
	v_bfe_u32 v2, v9, 16, 1
	global_store_dwordx4 v[104:105], v[100:103], off nt
	v_add3_u32 v2, v9, v2, s80
	v_lshrrev_b32_e32 v2, 16, v2
	v_bfe_u32 v100, v5, 16, 1
	v_add3_u32 v100, v5, v100, s80
	v_and_or_b32 v100, v100, s85, v2
	v_bfe_u32 v2, v29, 16, 1
	v_add3_u32 v2, v29, v2, s80
	v_bfe_u32 v101, v25, 16, 1
	v_lshrrev_b32_e32 v2, 16, v2
	v_add3_u32 v101, v25, v101, s80
	v_and_or_b32 v101, v101, s85, v2
	v_bfe_u32 v2, v53, 16, 1
	v_add3_u32 v2, v53, v2, s80
	v_bfe_u32 v102, v17, 16, 1
	v_lshrrev_b32_e32 v2, 16, v2
	v_add3_u32 v102, v17, v102, s80
	v_and_or_b32 v102, v102, s85, v2
	v_bfe_u32 v2, v73, 16, 1
	v_add3_u32 v2, v73, v2, s80
	v_bfe_u32 v103, v77, 16, 1
	v_lshrrev_b32_e32 v2, 16, v2
	v_add3_u32 v103, v77, v103, s80
	v_add_co_u32_e32 v106, vcc, s91, v104
	v_and_or_b32 v103, v103, s85, v2
	s_nop 0
	v_addc_co_u32_e32 v107, vcc, 0, v105, vcc
	v_bfe_u32 v2, v10, 16, 1
	global_store_dwordx4 v[106:107], v[100:103], off nt
	v_add3_u32 v2, v10, v2, s80
	v_lshrrev_b32_e32 v2, 16, v2
	v_bfe_u32 v100, v6, 16, 1
	v_add3_u32 v100, v6, v100, s80
	v_and_or_b32 v100, v100, s85, v2
	v_bfe_u32 v2, v30, 16, 1
	v_add3_u32 v2, v30, v2, s80
	v_bfe_u32 v101, v26, 16, 1
	v_lshrrev_b32_e32 v2, 16, v2
	v_add3_u32 v101, v26, v101, s80
	v_and_or_b32 v101, v101, s85, v2
	v_bfe_u32 v2, v54, 16, 1
	v_add3_u32 v2, v54, v2, s80
	v_bfe_u32 v102, v18, 16, 1
	v_lshrrev_b32_e32 v2, 16, v2
	v_add3_u32 v102, v18, v102, s80
	v_and_or_b32 v102, v102, s85, v2
	v_bfe_u32 v2, v74, 16, 1
	v_add3_u32 v2, v74, v2, s80
	v_bfe_u32 v103, v78, 16, 1
	v_lshrrev_b32_e32 v2, 16, v2
	v_add3_u32 v103, v78, v103, s80
	v_add_co_u32_e32 v106, vcc, s87, v104
	v_and_or_b32 v103, v103, s85, v2
	s_nop 0
	v_addc_co_u32_e32 v107, vcc, 0, v105, vcc
	v_bfe_u32 v2, v11, 16, 1
	global_store_dwordx4 v[106:107], v[100:103], off nt
	v_add3_u32 v2, v11, v2, s80
	v_lshrrev_b32_e32 v2, 16, v2
	v_bfe_u32 v100, v7, 16, 1
	v_add3_u32 v100, v7, v100, s80
	v_and_or_b32 v100, v100, s85, v2
	v_bfe_u32 v2, v31, 16, 1
	v_add3_u32 v2, v31, v2, s80
	v_bfe_u32 v101, v27, 16, 1
	v_lshrrev_b32_e32 v2, 16, v2
	v_add3_u32 v101, v27, v101, s80
	v_and_or_b32 v101, v101, s85, v2
	v_bfe_u32 v2, v55, 16, 1
	v_add3_u32 v2, v55, v2, s80
	v_bfe_u32 v102, v19, 16, 1
	v_lshrrev_b32_e32 v2, 16, v2
	v_add3_u32 v102, v19, v102, s80
	v_and_or_b32 v102, v102, s85, v2
	v_bfe_u32 v2, v75, 16, 1
	v_add3_u32 v2, v75, v2, s80
	v_bfe_u32 v103, v79, 16, 1
	v_lshrrev_b32_e32 v2, 16, v2
	v_add3_u32 v103, v79, v103, s80
	v_add_co_u32_e32 v104, vcc, 0x9000, v104
	v_and_or_b32 v103, v103, s85, v2
	s_nop 0
	v_addc_co_u32_e32 v105, vcc, 0, v105, vcc
	global_store_dwordx4 v[104:105], v[100:103], off nt
	s_branch .LBB0_3344

.LBB0_3440:
	v_ashrrev_i32_e32 v135, 31, v134
	s_waitcnt vmcnt(1)
	v_bfe_u32 v2, v104, 16, 1
	v_lshlrev_b64 v[134:135], 13, v[134:135]
	v_add3_u32 v2, v104, v2, s80
	s_waitcnt vmcnt(0)
	v_bfe_u32 v104, v100, 16, 1
	v_lshl_add_u64 v[134:135], s[10:11], 0, v[134:135]
	v_lshrrev_b32_e32 v2, 16, v2
	v_add3_u32 v100, v100, v104, s80
	v_lshl_add_u64 v[140:141], v[132:133], 1, v[134:135]
	v_and_or_b32 v132, v100, s85, v2
	v_bfe_u32 v2, v116, 16, 1
	v_add3_u32 v2, v116, v2, s80
	v_bfe_u32 v100, v112, 16, 1
	v_lshrrev_b32_e32 v2, 16, v2
	v_add3_u32 v100, v112, v100, s80
	v_and_or_b32 v133, v100, s85, v2
	v_bfe_u32 v2, v120, 16, 1
	v_add3_u32 v2, v120, v2, s80
	v_bfe_u32 v100, v108, 16, 1
	v_lshrrev_b32_e32 v2, 16, v2
	v_add3_u32 v100, v108, v100, s80
	v_and_or_b32 v134, v100, s85, v2
	v_bfe_u32 v2, v128, 16, 1
	v_add3_u32 v2, v128, v2, s80
	v_bfe_u32 v100, v124, 16, 1
	v_lshrrev_b32_e32 v2, 16, v2
	v_add3_u32 v100, v124, v100, s80
	v_and_or_b32 v135, v100, s85, v2
	v_bfe_u32 v2, v105, 16, 1
	v_add3_u32 v2, v105, v2, s80
	v_bfe_u32 v100, v101, 16, 1
	v_lshrrev_b32_e32 v2, 16, v2
	v_add3_u32 v100, v101, v100, s80
	global_store_dwordx4 v[140:141], v[132:135], off nt
	s_nop 1
	v_and_or_b32 v132, v100, s85, v2
	v_bfe_u32 v2, v117, 16, 1
	v_add3_u32 v2, v117, v2, s80
	v_bfe_u32 v100, v113, 16, 1
	v_lshrrev_b32_e32 v2, 16, v2
	v_add3_u32 v100, v113, v100, s80
	v_and_or_b32 v133, v100, s85, v2
	v_bfe_u32 v2, v121, 16, 1
	v_add3_u32 v2, v121, v2, s80
	v_bfe_u32 v100, v109, 16, 1
	v_lshrrev_b32_e32 v2, 16, v2
	v_add3_u32 v100, v109, v100, s80
	v_and_or_b32 v134, v100, s85, v2
	v_bfe_u32 v2, v129, 16, 1
	v_add3_u32 v2, v129, v2, s80
	v_bfe_u32 v100, v125, 16, 1
	v_lshrrev_b32_e32 v2, 16, v2
	v_add3_u32 v100, v125, v100, s80
	v_and_or_b32 v135, v100, s85, v2
	v_add_co_u32_e32 v100, vcc, s84, v140
	v_bfe_u32 v2, v106, 16, 1
	s_nop 0
	v_addc_co_u32_e32 v101, vcc, 0, v141, vcc
	global_store_dwordx4 v[100:101], v[132:135], off nt
	v_add3_u32 v2, v106, v2, s80
	v_bfe_u32 v100, v102, 16, 1
	v_lshrrev_b32_e32 v2, 16, v2
	v_add3_u32 v100, v102, v100, s80
	v_and_or_b32 v132, v100, s85, v2
	v_bfe_u32 v2, v118, 16, 1
	v_add3_u32 v2, v118, v2, s80
	v_bfe_u32 v100, v114, 16, 1
	v_lshrrev_b32_e32 v2, 16, v2
	v_add3_u32 v100, v114, v100, s80
	v_and_or_b32 v133, v100, s85, v2
	v_bfe_u32 v2, v122, 16, 1
	v_add3_u32 v2, v122, v2, s80
	v_bfe_u32 v100, v110, 16, 1
	v_lshrrev_b32_e32 v2, 16, v2
	v_add3_u32 v100, v110, v100, s80
	v_and_or_b32 v134, v100, s85, v2
	v_bfe_u32 v2, v130, 16, 1
	v_add3_u32 v2, v130, v2, s80
	v_bfe_u32 v100, v126, 16, 1
	v_lshrrev_b32_e32 v2, 16, v2
	v_add3_u32 v100, v126, v100, s80
	v_and_or_b32 v135, v100, s85, v2
	v_add_co_u32_e32 v100, vcc, s81, v140
	v_bfe_u32 v2, v107, 16, 1
	s_nop 0
	v_addc_co_u32_e32 v101, vcc, 0, v141, vcc
	global_store_dwordx4 v[100:101], v[132:135], off nt
	v_add3_u32 v2, v107, v2, s80
	v_bfe_u32 v100, v103, 16, 1
	v_lshrrev_b32_e32 v2, 16, v2
	v_add3_u32 v100, v103, v100, s80
	v_and_or_b32 v100, v100, s85, v2
	v_bfe_u32 v2, v119, 16, 1
	v_add3_u32 v2, v119, v2, s80
	v_bfe_u32 v101, v115, 16, 1
	v_lshrrev_b32_e32 v2, 16, v2
	v_add3_u32 v101, v115, v101, s80
	v_and_or_b32 v101, v101, s85, v2
	v_bfe_u32 v2, v123, 16, 1
	v_add3_u32 v2, v123, v2, s80
	v_bfe_u32 v102, v111, 16, 1
	v_lshrrev_b32_e32 v2, 16, v2
	v_add3_u32 v102, v111, v102, s80
	v_and_or_b32 v102, v102, s85, v2
	v_bfe_u32 v2, v131, 16, 1
	v_add3_u32 v2, v131, v2, s80
	v_bfe_u32 v103, v127, 16, 1
	v_add_co_u32_e32 v104, vcc, 0x6000, v140
	v_lshrrev_b32_e32 v2, 16, v2
	v_add3_u32 v103, v127, v103, s80
	v_addc_co_u32_e32 v105, vcc, 0, v141, vcc
	v_and_or_b32 v103, v103, s85, v2
	s_andn2_b64 vcc, exec, s[12:13]
	global_store_dwordx4 v[104:105], v[100:103], off nt
	s_cbranch_vccnz .LBB0_3443
	s_ashr_i32 s4, s1, 31
	s_lshr_b32 s4, s4, 25
	s_add_i32 s1, s1, s4
	s_ashr_i32 s1, s1, 7
	v_lshl_or_b32 v100, s1, 6, v231
	v_add_u32_e32 v2, s0, v138
	s_lshl_b32 s1, s1, 12
	v_subrev_u32_e32 v102, s1, v2
	v_ashrrev_i32_e32 v103, 31, v102
	v_lshlrev_b64 v[102:103], 13, v[102:103]
	v_ashrrev_i32_e32 v101, 31, v100
	v_lshl_add_u64 v[102:103], s[10:11], 0, v[102:103]
	v_bfe_u32 v2, v36, 16, 1
	v_lshl_add_u64 v[104:105], v[100:101], 1, v[102:103]
	v_add3_u32 v2, v36, v2, s80
	v_bfe_u32 v100, v32, 16, 1
	v_lshrrev_b32_e32 v2, 16, v2
	v_add3_u32 v100, v32, v100, s80
	v_and_or_b32 v100, v100, s85, v2
	v_bfe_u32 v2, v64, 16, 1
	v_add3_u32 v2, v64, v2, s80
	v_bfe_u32 v101, v60, 16, 1
	v_lshrrev_b32_e32 v2, 16, v2
	v_add3_u32 v101, v60, v101, s80
	v_and_or_b32 v101, v101, s85, v2
	v_bfe_u32 v2, v80, 16, 1
	v_add3_u32 v2, v80, v2, s80
	v_bfe_u32 v102, v56, 16, 1
	v_lshrrev_b32_e32 v2, 16, v2
	v_add3_u32 v102, v56, v102, s80
	v_and_or_b32 v102, v102, s85, v2
	v_bfe_u32 v2, v92, 16, 1
	v_add3_u32 v2, v92, v2, s80
	v_bfe_u32 v103, v96, 16, 1
	v_lshrrev_b32_e32 v2, 16, v2
	v_add3_u32 v103, v96, v103, s80
	v_and_or_b32 v103, v103, s85, v2
	v_bfe_u32 v2, v37, 16, 1
	global_store_dwordx4 v[104:105], v[100:103], off nt
	v_add3_u32 v2, v37, v2, s80
	v_lshrrev_b32_e32 v2, 16, v2
	v_bfe_u32 v100, v33, 16, 1
	v_add3_u32 v100, v33, v100, s80
	v_and_or_b32 v100, v100, s85, v2
	v_bfe_u32 v2, v65, 16, 1
	v_add3_u32 v2, v65, v2, s80
	v_bfe_u32 v101, v61, 16, 1
	v_lshrrev_b32_e32 v2, 16, v2
	v_add3_u32 v101, v61, v101, s80
	v_and_or_b32 v101, v101, s85, v2
	v_bfe_u32 v2, v81, 16, 1
	v_add3_u32 v2, v81, v2, s80
	v_bfe_u32 v102, v57, 16, 1
	v_lshrrev_b32_e32 v2, 16, v2
	v_add3_u32 v102, v57, v102, s80
	v_and_or_b32 v102, v102, s85, v2
	v_bfe_u32 v2, v93, 16, 1
	v_add3_u32 v2, v93, v2, s80
	v_bfe_u32 v103, v97, 16, 1
	v_lshrrev_b32_e32 v2, 16, v2
	v_add3_u32 v103, v97, v103, s80
	v_add_co_u32_e32 v106, vcc, s84, v104
	v_and_or_b32 v103, v103, s85, v2
	s_nop 0
	v_addc_co_u32_e32 v107, vcc, 0, v105, vcc
	v_bfe_u32 v2, v38, 16, 1
	global_store_dwordx4 v[106:107], v[100:103], off nt
	v_add3_u32 v2, v38, v2, s80
	v_lshrrev_b32_e32 v2, 16, v2
	v_bfe_u32 v100, v34, 16, 1
	v_add3_u32 v100, v34, v100, s80
	v_and_or_b32 v100, v100, s85, v2
	v_bfe_u32 v2, v66, 16, 1
	v_add3_u32 v2, v66, v2, s80
	v_bfe_u32 v101, v62, 16, 1
	v_lshrrev_b32_e32 v2, 16, v2
	v_add3_u32 v101, v62, v101, s80
	v_and_or_b32 v101, v101, s85, v2
	v_bfe_u32 v2, v82, 16, 1
	v_add3_u32 v2, v82, v2, s80
	v_bfe_u32 v102, v58, 16, 1
	v_lshrrev_b32_e32 v2, 16, v2
	v_add3_u32 v102, v58, v102, s80
	v_and_or_b32 v102, v102, s85, v2
	v_bfe_u32 v2, v94, 16, 1
	v_add3_u32 v2, v94, v2, s80
	v_bfe_u32 v103, v98, 16, 1
	v_lshrrev_b32_e32 v2, 16, v2
	v_add3_u32 v103, v98, v103, s80
	v_add_co_u32_e32 v106, vcc, s81, v104
	v_and_or_b32 v103, v103, s85, v2
	s_nop 0
	v_addc_co_u32_e32 v107, vcc, 0, v105, vcc
	v_bfe_u32 v2, v39, 16, 1
	global_store_dwordx4 v[106:107], v[100:103], off nt
	v_add3_u32 v2, v39, v2, s80
	v_lshrrev_b32_e32 v2, 16, v2
	v_bfe_u32 v100, v35, 16, 1
	v_add3_u32 v100, v35, v100, s80
	v_and_or_b32 v100, v100, s85, v2
	v_bfe_u32 v2, v67, 16, 1
	v_add3_u32 v2, v67, v2, s80
	v_bfe_u32 v101, v63, 16, 1
	v_lshrrev_b32_e32 v2, 16, v2
	v_add3_u32 v101, v63, v101, s80
	v_and_or_b32 v101, v101, s85, v2
	v_bfe_u32 v2, v83, 16, 1
	v_add3_u32 v2, v83, v2, s80
	v_bfe_u32 v102, v59, 16, 1
	v_lshrrev_b32_e32 v2, 16, v2
	v_add3_u32 v102, v59, v102, s80
	v_and_or_b32 v102, v102, s85, v2
	v_bfe_u32 v2, v95, 16, 1
	v_add3_u32 v2, v95, v2, s80
	v_bfe_u32 v103, v99, 16, 1
	v_lshrrev_b32_e32 v2, 16, v2
	v_add3_u32 v103, v99, v103, s80
	v_add_co_u32_e32 v104, vcc, 0x6000, v104
	v_and_or_b32 v103, v103, s85, v2
	s_nop 0
	v_addc_co_u32_e32 v105, vcc, 0, v105, vcc
	global_store_dwordx4 v[104:105], v[100:103], off nt
	s_andn2_b64 vcc, exec, s[16:17]
	s_cbranch_vccz .LBB0_3444

.LBB0_3444:
	s_ashr_i32 s1, s14, 31
	s_lshr_b32 s1, s1, 25
	s_add_i32 s14, s14, s1
	s_ashr_i32 s1, s14, 7
	v_lshl_or_b32 v100, s1, 6, v231
	v_add_u32_e32 v2, s0, v136
	s_lshl_b32 s1, s1, 12
	v_subrev_u32_e32 v102, s1, v2
	v_ashrrev_i32_e32 v103, 31, v102
	v_lshlrev_b64 v[102:103], 13, v[102:103]
	v_ashrrev_i32_e32 v101, 31, v100
	v_lshl_add_u64 v[102:103], s[10:11], 0, v[102:103]
	v_bfe_u32 v2, v20, 16, 1
	v_lshl_add_u64 v[104:105], v[100:101], 1, v[102:103]
	v_add3_u32 v2, v20, v2, s80
	v_bfe_u32 v100, v12, 16, 1
	v_lshrrev_b32_e32 v2, 16, v2
	v_add3_u32 v100, v12, v100, s80
	v_and_or_b32 v100, v100, s85, v2
	v_bfe_u32 v2, v48, 16, 1
	v_add3_u32 v2, v48, v2, s80
	v_bfe_u32 v101, v44, 16, 1
	v_lshrrev_b32_e32 v2, 16, v2
	v_add3_u32 v101, v44, v101, s80
	v_and_or_b32 v101, v101, s85, v2
	v_bfe_u32 v2, v68, 16, 1
	v_add3_u32 v2, v68, v2, s80
	v_bfe_u32 v102, v40, 16, 1
	v_lshrrev_b32_e32 v2, 16, v2
	v_add3_u32 v102, v40, v102, s80
	v_and_or_b32 v102, v102, s85, v2
	v_bfe_u32 v2, v84, 16, 1
	v_add3_u32 v2, v84, v2, s80
	v_bfe_u32 v103, v88, 16, 1
	v_lshrrev_b32_e32 v2, 16, v2
	v_add3_u32 v103, v88, v103, s80
	v_and_or_b32 v103, v103, s85, v2
	v_bfe_u32 v2, v21, 16, 1
	global_store_dwordx4 v[104:105], v[100:103], off nt
	v_add3_u32 v2, v21, v2, s80
	v_lshrrev_b32_e32 v2, 16, v2
	v_bfe_u32 v100, v13, 16, 1
	v_add3_u32 v100, v13, v100, s80
	v_and_or_b32 v100, v100, s85, v2
	v_bfe_u32 v2, v49, 16, 1
	v_add3_u32 v2, v49, v2, s80
	v_bfe_u32 v101, v45, 16, 1
	v_lshrrev_b32_e32 v2, 16, v2
	v_add3_u32 v101, v45, v101, s80
	v_and_or_b32 v101, v101, s85, v2
	v_bfe_u32 v2, v69, 16, 1
	v_add3_u32 v2, v69, v2, s80
	v_bfe_u32 v102, v41, 16, 1
	v_lshrrev_b32_e32 v2, 16, v2
	v_add3_u32 v102, v41, v102, s80
	v_and_or_b32 v102, v102, s85, v2
	v_bfe_u32 v2, v85, 16, 1
	v_add3_u32 v2, v85, v2, s80
	v_bfe_u32 v103, v89, 16, 1
	v_lshrrev_b32_e32 v2, 16, v2
	v_add3_u32 v103, v89, v103, s80
	v_add_co_u32_e32 v106, vcc, s84, v104
	v_and_or_b32 v103, v103, s85, v2
	s_nop 0
	v_addc_co_u32_e32 v107, vcc, 0, v105, vcc
	v_bfe_u32 v2, v22, 16, 1
	global_store_dwordx4 v[106:107], v[100:103], off nt
	v_add3_u32 v2, v22, v2, s80
	v_lshrrev_b32_e32 v2, 16, v2
	v_bfe_u32 v100, v14, 16, 1
	v_add3_u32 v100, v14, v100, s80
	v_and_or_b32 v100, v100, s85, v2
	v_bfe_u32 v2, v50, 16, 1
	v_add3_u32 v2, v50, v2, s80
	v_bfe_u32 v101, v46, 16, 1
	v_lshrrev_b32_e32 v2, 16, v2
	v_add3_u32 v101, v46, v101, s80
	v_and_or_b32 v101, v101, s85, v2
	v_bfe_u32 v2, v70, 16, 1
	v_add3_u32 v2, v70, v2, s80
	v_bfe_u32 v102, v42, 16, 1
	v_lshrrev_b32_e32 v2, 16, v2
	v_add3_u32 v102, v42, v102, s80
	v_and_or_b32 v102, v102, s85, v2
	v_bfe_u32 v2, v86, 16, 1
	v_add3_u32 v2, v86, v2, s80
	v_bfe_u32 v103, v90, 16, 1
	v_lshrrev_b32_e32 v2, 16, v2
	v_add3_u32 v103, v90, v103, s80
	v_add_co_u32_e32 v106, vcc, s81, v104
	v_and_or_b32 v103, v103, s85, v2
	s_nop 0
	v_addc_co_u32_e32 v107, vcc, 0, v105, vcc
	v_bfe_u32 v2, v23, 16, 1
	global_store_dwordx4 v[106:107], v[100:103], off nt
	v_add3_u32 v2, v23, v2, s80
	v_lshrrev_b32_e32 v2, 16, v2
	v_bfe_u32 v100, v15, 16, 1
	v_add3_u32 v100, v15, v100, s80
	v_and_or_b32 v100, v100, s85, v2
	v_bfe_u32 v2, v51, 16, 1
	v_add3_u32 v2, v51, v2, s80
	v_bfe_u32 v101, v47, 16, 1
	v_lshrrev_b32_e32 v2, 16, v2
	v_add3_u32 v101, v47, v101, s80
	v_and_or_b32 v101, v101, s85, v2
	v_bfe_u32 v2, v71, 16, 1
	v_add3_u32 v2, v71, v2, s80
	v_bfe_u32 v102, v43, 16, 1
	v_lshrrev_b32_e32 v2, 16, v2
	v_add3_u32 v102, v43, v102, s80
	v_and_or_b32 v102, v102, s85, v2
	v_bfe_u32 v2, v87, 16, 1
	v_add3_u32 v2, v87, v2, s80
	v_bfe_u32 v103, v91, 16, 1
	v_lshrrev_b32_e32 v2, 16, v2
	v_add3_u32 v103, v91, v103, s80
	v_add_co_u32_e32 v104, vcc, 0x6000, v104
	v_and_or_b32 v103, v103, s85, v2
	s_nop 0
	v_addc_co_u32_e32 v105, vcc, 0, v105, vcc
	global_store_dwordx4 v[104:105], v[100:103], off nt
	s_andn2_b64 vcc, exec, s[18:19]
	s_cbranch_vccnz .LBB0_3396
.LBB0_3445:
	s_ashr_i32 s1, s15, 31
	s_lshr_b32 s1, s1, 25
	s_add_i32 s15, s15, s1
	s_ashr_i32 s1, s15, 7
	v_lshl_or_b32 v100, s1, 6, v231
	v_add_u32_e32 v2, s0, v137
	s_lshl_b32 s1, s1, 12
	v_subrev_u32_e32 v102, s1, v2
	v_ashrrev_i32_e32 v103, 31, v102
	v_lshlrev_b64 v[102:103], 13, v[102:103]
	v_ashrrev_i32_e32 v101, 31, v100
	v_lshl_add_u64 v[102:103], s[10:11], 0, v[102:103]
	v_bfe_u32 v2, v8, 16, 1
	v_lshl_add_u64 v[104:105], v[100:101], 1, v[102:103]
	v_add3_u32 v2, v8, v2, s80
	v_bfe_u32 v100, v4, 16, 1
	v_lshrrev_b32_e32 v2, 16, v2
	v_add3_u32 v100, v4, v100, s80
	v_and_or_b32 v100, v100, s85, v2
	v_bfe_u32 v2, v28, 16, 1
	v_add3_u32 v2, v28, v2, s80
	v_bfe_u32 v101, v24, 16, 1
	v_lshrrev_b32_e32 v2, 16, v2
	v_add3_u32 v101, v24, v101, s80
	v_and_or_b32 v101, v101, s85, v2
	v_bfe_u32 v2, v52, 16, 1
	v_add3_u32 v2, v52, v2, s80
	v_bfe_u32 v102, v16, 16, 1
	v_lshrrev_b32_e32 v2, 16, v2
	v_add3_u32 v102, v16, v102, s80
	v_and_or_b32 v102, v102, s85, v2
	v_bfe_u32 v2, v72, 16, 1
	v_add3_u32 v2, v72, v2, s80
	v_bfe_u32 v103, v76, 16, 1
	v_lshrrev_b32_e32 v2, 16, v2
	v_add3_u32 v103, v76, v103, s80
	v_and_or_b32 v103, v103, s85, v2
	v_bfe_u32 v2, v9, 16, 1
	global_store_dwordx4 v[104:105], v[100:103], off nt
	v_add3_u32 v2, v9, v2, s80
	v_lshrrev_b32_e32 v2, 16, v2
	v_bfe_u32 v100, v5, 16, 1
	v_add3_u32 v100, v5, v100, s80
	v_and_or_b32 v100, v100, s85, v2
	v_bfe_u32 v2, v29, 16, 1
	v_add3_u32 v2, v29, v2, s80
	v_bfe_u32 v101, v25, 16, 1
	v_lshrrev_b32_e32 v2, 16, v2
	v_add3_u32 v101, v25, v101, s80
	v_and_or_b32 v101, v101, s85, v2
	v_bfe_u32 v2, v53, 16, 1
	v_add3_u32 v2, v53, v2, s80
	v_bfe_u32 v102, v17, 16, 1
	v_lshrrev_b32_e32 v2, 16, v2
	v_add3_u32 v102, v17, v102, s80
	v_and_or_b32 v102, v102, s85, v2
	v_bfe_u32 v2, v73, 16, 1
	v_add3_u32 v2, v73, v2, s80
	v_bfe_u32 v103, v77, 16, 1
	v_lshrrev_b32_e32 v2, 16, v2
	v_add3_u32 v103, v77, v103, s80
	v_add_co_u32_e32 v106, vcc, s84, v104
	v_and_or_b32 v103, v103, s85, v2
	s_nop 0
	v_addc_co_u32_e32 v107, vcc, 0, v105, vcc
	v_bfe_u32 v2, v10, 16, 1
	global_store_dwordx4 v[106:107], v[100:103], off nt
	v_add3_u32 v2, v10, v2, s80
	v_lshrrev_b32_e32 v2, 16, v2
	v_bfe_u32 v100, v6, 16, 1
	v_add3_u32 v100, v6, v100, s80
	v_and_or_b32 v100, v100, s85, v2
	v_bfe_u32 v2, v30, 16, 1
	v_add3_u32 v2, v30, v2, s80
	v_bfe_u32 v101, v26, 16, 1
	v_lshrrev_b32_e32 v2, 16, v2
	v_add3_u32 v101, v26, v101, s80
	v_and_or_b32 v101, v101, s85, v2
	v_bfe_u32 v2, v54, 16, 1
	v_add3_u32 v2, v54, v2, s80
	v_bfe_u32 v102, v18, 16, 1
	v_lshrrev_b32_e32 v2, 16, v2
	v_add3_u32 v102, v18, v102, s80
	v_and_or_b32 v102, v102, s85, v2
	v_bfe_u32 v2, v74, 16, 1
	v_add3_u32 v2, v74, v2, s80
	v_bfe_u32 v103, v78, 16, 1
	v_lshrrev_b32_e32 v2, 16, v2
	v_add3_u32 v103, v78, v103, s80
	v_add_co_u32_e32 v106, vcc, s81, v104
	v_and_or_b32 v103, v103, s85, v2
	s_nop 0
	v_addc_co_u32_e32 v107, vcc, 0, v105, vcc
	v_bfe_u32 v2, v11, 16, 1
	global_store_dwordx4 v[106:107], v[100:103], off nt
	v_add3_u32 v2, v11, v2, s80
	v_lshrrev_b32_e32 v2, 16, v2
	v_bfe_u32 v100, v7, 16, 1
	v_add3_u32 v100, v7, v100, s80
	v_and_or_b32 v100, v100, s85, v2
	v_bfe_u32 v2, v31, 16, 1
	v_add3_u32 v2, v31, v2, s80
	v_bfe_u32 v101, v27, 16, 1
	v_lshrrev_b32_e32 v2, 16, v2
	v_add3_u32 v101, v27, v101, s80
	v_and_or_b32 v101, v101, s85, v2
	v_bfe_u32 v2, v55, 16, 1
	v_add3_u32 v2, v55, v2, s80
	v_bfe_u32 v102, v19, 16, 1
	v_lshrrev_b32_e32 v2, 16, v2
	v_add3_u32 v102, v19, v102, s80
	v_and_or_b32 v102, v102, s85, v2
	v_bfe_u32 v2, v75, 16, 1
	v_add3_u32 v2, v75, v2, s80
	v_bfe_u32 v103, v79, 16, 1
	v_lshrrev_b32_e32 v2, 16, v2
	v_add3_u32 v103, v79, v103, s80
	v_add_co_u32_e32 v104, vcc, 0x6000, v104
	v_and_or_b32 v103, v103, s85, v2
	s_nop 0
	v_addc_co_u32_e32 v105, vcc, 0, v105, vcc
	global_store_dwordx4 v[104:105], v[100:103], off nt
	s_branch .LBB0_3396
